# flat_load/store/atomic converted to global_* (off) so lgkmcnt waits no longer cover global memory ops
# speedup vs baseline: 1.0140x; 1.0140x over previous
; __device__ __forceinline__ float silu_f(float x) { return x / (1.f + __expf(-x)); }
; __device__ __forceinline__ void ada_item(const Params& p, int it, unsigned char* smem) {
;     ...
; #pragma unroll
;   for (int i = 0; i < 12; ++i) {
;     const int idx = t + 256 * i, r = idx >> 10, k = idx & 1023;
;     const float cv = r < 2 ? p.c[r * 1024 + k] : p.c_ctx[k];
;     sc[idx] = silu_f(cv);
;   }
.LBB0_8:
	v_mov_b32_e32 v6, v187
	global_load_dwordx2 v[10:11], v[2:3], off offset:8
	global_load_dwordx2 v[8:9], v[2:3], off offset:24
	v_and_b32_e32 v4, 0x3ff, v6
	v_ashrrev_i32_e32 v7, 31, v6
	v_lshlrev_b32_e32 v4, 2, v4
	v_cmp_gt_i32_e32 vcc, s34, v6
	s_mov_b64 s[30:31], 0
	s_waitcnt vmcnt(0) lgkmcnt(0)
	v_lshl_add_u64 v[10:11], v[6:7], 2, v[10:11]
	v_lshl_add_u64 v[12:13], v[8:9], 0, v[4:5]
	v_cndmask_b32_e32 v15, v13, v11, vcc
	v_cndmask_b32_e32 v14, v12, v10, vcc
	global_load_dword v18, v[14:15], off
	v_add_u32_e32 v4, 0x100, v6
	v_and_b32_e32 v4, 0x3ff, v4
	v_lshlrev_b32_e32 v4, 2, v4
	v_lshl_add_u64 v[14:15], v[10:11], 0, s[0:1]
	v_cmp_gt_i32_e32 vcc, s36, v6
	v_lshlrev_b32_e32 v7, 2, v6
	s_waitcnt vmcnt(0) lgkmcnt(0)
	v_mul_f32_e32 v16, 0xbfb8aa3b, v18
	v_exp_f32_e32 v19, v16
	v_lshl_add_u64 v[16:17], v[8:9], 0, v[4:5]
	v_cndmask_b32_e32 v15, v17, v15, vcc
	v_cndmask_b32_e32 v14, v16, v14, vcc
	v_add_f32_e32 v4, 1.0, v19
	v_div_scale_f32 v17, s[28:29], v4, v4, v18
	v_rcp_f32_e32 v19, v17
	v_div_scale_f32 v16, vcc, v18, v4, v18
	v_fma_f32 v20, -v17, v19, 1.0
	v_fmac_f32_e32 v19, v20, v19
	v_mul_f32_e32 v20, v16, v19
	v_fma_f32 v21, -v17, v20, v16
	v_fmac_f32_e32 v20, v21, v19
	v_fma_f32 v16, -v17, v20, v16
	v_div_fmas_f32 v16, v16, v19, v20
	v_div_fixup_f32 v4, v16, v4, v18
	ds_write_b32 v7, v4
	global_load_dword v18, v[14:15], off
	v_add_u32_e32 v4, 0x200, v6
	v_and_b32_e32 v4, 0x3ff, v4
	v_lshlrev_b32_e32 v4, 2, v4
	v_lshl_add_u64 v[14:15], v[10:11], 0, s[4:5]
	v_cmp_gt_i32_e32 vcc, s38, v6
	s_waitcnt vmcnt(0) lgkmcnt(0)
	v_mul_f32_e32 v16, 0xbfb8aa3b, v18
	v_exp_f32_e32 v19, v16
	v_lshl_add_u64 v[16:17], v[8:9], 0, v[4:5]
	v_cndmask_b32_e32 v15, v17, v15, vcc
	v_cndmask_b32_e32 v14, v16, v14, vcc
	v_add_f32_e32 v4, 1.0, v19
	v_div_scale_f32 v17, s[28:29], v4, v4, v18
	v_rcp_f32_e32 v19, v17
	v_div_scale_f32 v16, vcc, v18, v4, v18
	v_fma_f32 v20, -v17, v19, 1.0
	v_fmac_f32_e32 v19, v20, v19
	v_mul_f32_e32 v20, v16, v19
	v_fma_f32 v21, -v17, v20, v16
	v_fmac_f32_e32 v20, v21, v19
	v_fma_f32 v16, -v17, v20, v16
	v_div_fmas_f32 v16, v16, v19, v20
	v_div_fixup_f32 v4, v16, v4, v18
	ds_write_b32 v7, v4 offset:1024
	global_load_dword v18, v[14:15], off
	v_add_u32_e32 v4, 0x300, v6
	v_and_b32_e32 v4, 0x3ff, v4
	v_lshlrev_b32_e32 v4, 2, v4
	v_lshl_add_u64 v[14:15], v[10:11], 0, s[6:7]
	v_cmp_gt_i32_e32 vcc, s40, v6
	s_waitcnt vmcnt(0) lgkmcnt(0)
	v_mul_f32_e32 v16, 0xbfb8aa3b, v18
	v_exp_f32_e32 v19, v16
	v_lshl_add_u64 v[16:17], v[8:9], 0, v[4:5]
	v_cndmask_b32_e32 v15, v17, v15, vcc
	v_cndmask_b32_e32 v14, v16, v14, vcc
	v_add_f32_e32 v4, 1.0, v19
	v_div_scale_f32 v17, s[28:29], v4, v4, v18
	v_rcp_f32_e32 v19, v17
	v_div_scale_f32 v16, vcc, v18, v4, v18
	v_fma_f32 v20, -v17, v19, 1.0
	v_fmac_f32_e32 v19, v20, v19
	v_mul_f32_e32 v20, v16, v19
	v_fma_f32 v21, -v17, v20, v16
	v_fmac_f32_e32 v20, v21, v19
	v_fma_f32 v16, -v17, v20, v16
	v_div_fmas_f32 v16, v16, v19, v20
	v_div_fixup_f32 v4, v16, v4, v18
	ds_write_b32 v7, v4 offset:2048
	global_load_dword v4, v[14:15], off
	v_cmp_gt_i32_e32 vcc, s41, v6
	s_waitcnt vmcnt(0) lgkmcnt(0)
	v_mul_f32_e32 v14, 0xbfb8aa3b, v4
	v_exp_f32_e32 v16, v14
	v_lshl_add_u64 v[14:15], v[10:11], 0, s[12:13]
	v_cndmask_b32_e32 v15, v13, v15, vcc
	v_cndmask_b32_e32 v14, v12, v14, vcc
	v_add_f32_e32 v16, 1.0, v16
	v_div_scale_f32 v17, s[28:29], v16, v16, v4
	v_rcp_f32_e32 v18, v17
	v_div_scale_f32 v19, vcc, v4, v16, v4
	v_fma_f32 v20, -v17, v18, 1.0
	v_fmac_f32_e32 v18, v20, v18
	v_mul_f32_e32 v20, v19, v18
	v_fma_f32 v21, -v17, v20, v19
	v_fmac_f32_e32 v20, v21, v18
	v_fma_f32 v17, -v17, v20, v19
	v_div_fmas_f32 v17, v17, v18, v20
	v_div_fixup_f32 v4, v17, v16, v4
	ds_write_b32 v7, v4 offset:3072
	global_load_dword v18, v[14:15], off
	v_add_u32_e32 v4, 0x500, v6
	v_and_b32_e32 v4, 0x3ff, v4
	v_lshlrev_b32_e32 v4, 2, v4
	v_lshl_add_u64 v[14:15], v[10:11], 0, s[14:15]
	v_cmp_gt_i32_e32 vcc, s39, v6
	s_waitcnt vmcnt(0) lgkmcnt(0)
	v_mul_f32_e32 v16, 0xbfb8aa3b, v18
	v_exp_f32_e32 v19, v16
	v_lshl_add_u64 v[16:17], v[8:9], 0, v[4:5]
	v_cndmask_b32_e32 v15, v17, v15, vcc
	v_cndmask_b32_e32 v14, v16, v14, vcc
	v_add_f32_e32 v4, 1.0, v19
	v_div_scale_f32 v17, s[28:29], v4, v4, v18
	v_rcp_f32_e32 v19, v17
	v_div_scale_f32 v16, vcc, v18, v4, v18
	v_fma_f32 v20, -v17, v19, 1.0
	v_fmac_f32_e32 v19, v20, v19
	v_mul_f32_e32 v20, v16, v19
	v_fma_f32 v21, -v17, v20, v16
	v_fmac_f32_e32 v20, v21, v19
	v_fma_f32 v16, -v17, v20, v16
	v_div_fmas_f32 v16, v16, v19, v20
	v_div_fixup_f32 v4, v16, v4, v18
	ds_write_b32 v7, v4 offset:4096
	global_load_dword v18, v[14:15], off
	v_add_u32_e32 v4, 0x600, v6
	v_and_b32_e32 v4, 0x3ff, v4
	v_lshlrev_b32_e32 v4, 2, v4
	v_lshl_add_u64 v[14:15], v[10:11], 0, s[16:17]
	v_cmp_gt_i32_e32 vcc, s37, v6
	s_waitcnt vmcnt(0) lgkmcnt(0)
	v_mul_f32_e32 v16, 0xbfb8aa3b, v18
	v_exp_f32_e32 v19, v16
	v_lshl_add_u64 v[16:17], v[8:9], 0, v[4:5]
	v_cndmask_b32_e32 v15, v17, v15, vcc
	v_cndmask_b32_e32 v14, v16, v14, vcc
	v_add_f32_e32 v4, 1.0, v19
	v_div_scale_f32 v17, s[28:29], v4, v4, v18
	v_rcp_f32_e32 v19, v17
	v_div_scale_f32 v16, vcc, v18, v4, v18
	v_fma_f32 v20, -v17, v19, 1.0
	v_fmac_f32_e32 v19, v20, v19
	v_mul_f32_e32 v20, v16, v19
	v_fma_f32 v21, -v17, v20, v16
	v_fmac_f32_e32 v20, v21, v19
	v_fma_f32 v16, -v17, v20, v16
	v_div_fmas_f32 v16, v16, v19, v20
	v_div_fixup_f32 v4, v16, v4, v18
	ds_write_b32 v7, v4 offset:5120
	global_load_dword v18, v[14:15], off
	v_add_u32_e32 v4, 0x700, v6
	v_and_b32_e32 v4, 0x3ff, v4
	v_lshlrev_b32_e32 v4, 2, v4
	v_lshl_add_u64 v[14:15], v[10:11], 0, s[18:19]
	v_cmp_gt_i32_e32 vcc, s35, v6
	s_waitcnt vmcnt(0) lgkmcnt(0)
; __device__ __forceinline__ float silu_f(float x) { return x / (1.f + __expf(-x)); }
; __device__ __forceinline__ void ada_item(const Params& p, int it, unsigned char* smem) {
;     ...
; #pragma unroll
;   for (int i = 0; i < 12; ++i) {
;     const int idx = t + 256 * i, r = idx >> 10, k = idx & 1023;
;     const float cv = r < 2 ? p.c[r * 1024 + k] : p.c_ctx[k];
;     sc[idx] = silu_f(cv);
;   }
;   __syncthreads();
;   const float* w = p.w_ada + (size_t)l * 1024 * 6144 + jc * 64 + lane;
;   float a0 = 0.f, a1 = 0.f, a2 = 0.f;
;   const int kb = wid * 256;
	v_mul_f32_e32 v16, 0xbfb8aa3b, v18
	v_exp_f32_e32 v19, v16
	v_lshl_add_u64 v[16:17], v[8:9], 0, v[4:5]
	v_cndmask_b32_e32 v15, v17, v15, vcc
	v_cndmask_b32_e32 v14, v16, v14, vcc
	v_add_f32_e32 v4, 1.0, v19
	v_div_scale_f32 v17, s[28:29], v4, v4, v18
	v_rcp_f32_e32 v19, v17
	v_div_scale_f32 v16, vcc, v18, v4, v18
	v_fma_f32 v20, -v17, v19, 1.0
	v_fmac_f32_e32 v19, v20, v19
	v_mul_f32_e32 v20, v16, v19
	v_fma_f32 v21, -v17, v20, v16
	v_fmac_f32_e32 v20, v21, v19
	v_fma_f32 v16, -v17, v20, v16
	v_div_fmas_f32 v16, v16, v19, v20
	v_div_fixup_f32 v4, v16, v4, v18
	ds_write_b32 v7, v4 offset:6144
	global_load_dword v4, v[14:15], off
	v_cmp_gt_i32_e32 vcc, 0, v6
	s_waitcnt vmcnt(0) lgkmcnt(0)
	v_mul_f32_e32 v14, 0xbfb8aa3b, v4
	v_exp_f32_e32 v16, v14
	v_lshl_add_u64 v[14:15], v[10:11], 0, s[20:21]
	v_cndmask_b32_e32 v13, v13, v15, vcc
	v_cndmask_b32_e32 v12, v12, v14, vcc
	v_add_f32_e32 v15, 1.0, v16
	v_div_scale_f32 v16, s[28:29], v15, v15, v4
	v_rcp_f32_e32 v17, v16
	v_div_scale_f32 v14, vcc, v4, v15, v4
	v_fma_f32 v18, -v16, v17, 1.0
	v_fmac_f32_e32 v17, v18, v17
	v_mul_f32_e32 v18, v14, v17
	v_fma_f32 v19, -v16, v18, v14
	v_fmac_f32_e32 v18, v19, v17
	v_fma_f32 v14, -v16, v18, v14
	v_div_fmas_f32 v14, v14, v17, v18
	v_div_fixup_f32 v4, v14, v15, v4
	ds_write_b32 v7, v4 offset:7168
	global_load_dword v16, v[12:13], off
	v_add_u32_e32 v4, 0x900, v6
	v_and_b32_e32 v4, 0x3ff, v4
	v_lshlrev_b32_e32 v4, 2, v4
	v_lshl_add_u64 v[12:13], v[10:11], 0, s[22:23]
	v_cmp_gt_i32_e32 vcc, s42, v6
	s_waitcnt vmcnt(0) lgkmcnt(0)
	v_mul_f32_e32 v14, 0xbfb8aa3b, v16
	v_exp_f32_e32 v17, v14
	v_lshl_add_u64 v[14:15], v[8:9], 0, v[4:5]
	v_cndmask_b32_e32 v13, v15, v13, vcc
	v_cndmask_b32_e32 v12, v14, v12, vcc
	v_add_f32_e32 v4, 1.0, v17
	v_div_scale_f32 v15, s[28:29], v4, v4, v16
	v_rcp_f32_e32 v17, v15
	v_div_scale_f32 v14, vcc, v16, v4, v16
	v_fma_f32 v18, -v15, v17, 1.0
	v_fmac_f32_e32 v17, v18, v17
	v_mul_f32_e32 v18, v14, v17
	v_fma_f32 v19, -v15, v18, v14
	v_fmac_f32_e32 v18, v19, v17
	v_fma_f32 v14, -v15, v18, v14
	v_div_fmas_f32 v14, v14, v17, v18
	v_div_fixup_f32 v4, v14, v4, v16
	ds_write_b32 v7, v4 offset:8192
	global_load_dword v16, v[12:13], off
	v_add_u32_e32 v4, 0xa00, v6
	v_and_b32_e32 v4, 0x3ff, v4
	v_lshlrev_b32_e32 v4, 2, v4
	v_lshl_add_u64 v[12:13], v[10:11], 0, s[24:25]
	v_cmp_gt_i32_e32 vcc, s43, v6
	v_lshl_add_u64 v[10:11], v[10:11], 0, s[26:27]
	s_waitcnt vmcnt(0) lgkmcnt(0)
	v_mul_f32_e32 v14, 0xbfb8aa3b, v16
	v_exp_f32_e32 v17, v14
	v_lshl_add_u64 v[14:15], v[8:9], 0, v[4:5]
	v_cndmask_b32_e32 v13, v15, v13, vcc
	v_cndmask_b32_e32 v12, v14, v12, vcc
	v_add_f32_e32 v4, 1.0, v17
	v_div_scale_f32 v15, s[28:29], v4, v4, v16
	v_rcp_f32_e32 v17, v15
	v_div_scale_f32 v14, vcc, v16, v4, v16
	v_fma_f32 v18, -v15, v17, 1.0
	v_fmac_f32_e32 v17, v18, v17
	v_mul_f32_e32 v18, v14, v17
	v_fma_f32 v19, -v15, v18, v14
	v_fmac_f32_e32 v18, v19, v17
	v_fma_f32 v14, -v15, v18, v14
	v_div_fmas_f32 v14, v14, v17, v18
	v_div_fixup_f32 v4, v14, v4, v16
	ds_write_b32 v7, v4 offset:9216
	global_load_dword v12, v[12:13], off
	v_add_u32_e32 v4, 0xb00, v6
	v_and_b32_e32 v4, 0x3ff, v4
	v_lshlrev_b32_e32 v4, 2, v4
	v_lshl_add_u64 v[8:9], v[8:9], 0, v[4:5]
	v_cmp_gt_i32_e32 vcc, s44, v6
	s_waitcnt vmcnt(0) lgkmcnt(0)
	v_mul_f32_e32 v13, 0xbfb8aa3b, v12
	v_exp_f32_e32 v13, v13
	v_cndmask_b32_e32 v9, v9, v11, vcc
	v_cndmask_b32_e32 v8, v8, v10, vcc
	v_add_f32_e32 v4, 1.0, v13
	v_div_scale_f32 v11, s[28:29], v4, v4, v12
	v_rcp_f32_e32 v13, v11
	v_div_scale_f32 v10, vcc, v12, v4, v12
	v_fma_f32 v14, -v11, v13, 1.0
	v_fmac_f32_e32 v13, v14, v13
	v_mul_f32_e32 v14, v10, v13
	v_fma_f32 v15, -v11, v14, v10
	v_fmac_f32_e32 v14, v15, v13
	v_fma_f32 v10, -v11, v14, v10
	v_div_fmas_f32 v10, v10, v13, v14
	v_div_fixup_f32 v4, v10, v4, v12
	ds_write_b32 v7, v4 offset:10240
	global_load_dword v4, v[8:9], off
	s_waitcnt vmcnt(0) lgkmcnt(0)
	v_mul_f32_e32 v8, 0xbfb8aa3b, v4
	v_exp_f32_e32 v8, v8
	s_nop 0
	v_add_f32_e32 v8, 1.0, v8
	v_div_scale_f32 v9, s[28:29], v8, v8, v4
	v_rcp_f32_e32 v10, v9
	v_div_scale_f32 v11, vcc, v4, v8, v4
	s_mul_hi_i32 s28, s33, 0x2aaaaaab
	v_fma_f32 v12, -v9, v10, 1.0
	v_fmac_f32_e32 v10, v12, v10
	v_mul_f32_e32 v12, v11, v10
	v_fma_f32 v13, -v9, v12, v11
	v_fmac_f32_e32 v12, v13, v10
	v_fma_f32 v9, -v9, v12, v11
	v_div_fmas_f32 v9, v9, v10, v12
	v_div_fixup_f32 v4, v9, v8, v4
	ds_write_b32 v7, v4 offset:11264
	s_waitcnt lgkmcnt(0)
	s_barrier
	global_load_dwordx2 v[10:11], v[2:3], off offset:32
	s_lshr_b32 s29, s28, 31
	s_ashr_i32 s54, s28, 4
	s_add_i32 s54, s54, s29
	s_mul_i32 s28, s54, 0x60
	s_sub_i32 s28, s33, s28
	s_lshl_b32 s28, s28, 6
	s_ashr_i32 s29, s28, 31
	s_mul_i32 s58, s54, 0x1800000
	s_lshl_b64 s[56:57], s[28:29], 2
	s_mul_hi_i32 s55, s54, 0x1800000
	s_add_u32 s56, s56, s58
	v_ashrrev_i32_e32 v4, 6, v6
	s_addc_u32 s57, s57, s55
	v_lshlrev_b32_e32 v12, 8, v4
	v_mov_b64_e32 v[16:17], s[56:57]
	v_and_b32_e32 v7, 63, v6
	v_mad_i64_i32 v[16:17], s[56:57], v12, s45, v[16:17]
	v_lshl_or_b32 v16, v7, 2, v16
	v_mov_b32_e32 v13, 0
	v_mov_b32_e32 v8, 0
	v_lshlrev_b32_e32 v14, 10, v4
	v_mov_b32_e32 v9, v5
	s_waitcnt vmcnt(0) lgkmcnt(0)
	v_lshl_add_u64 v[10:11], v[10:11], 0, v[16:17]
; __device__ __forceinline__ unsigned xb_add(unsigned* p, unsigned v) { return __hip_atomic_fetch_add(p, v, __ATOMIC_RELAXED, __HIP_MEMORY_SCOPE_AGENT); }
; __device__ __forceinline__ void ada_item(const Params& p, int it, unsigned char* smem) {
;     ...
;   const float* w = p.w_ada + (size_t)l * 1024 * 6144 + jc * 64 + lane;
;   float a0 = 0.f, a1 = 0.f, a2 = 0.f;
;   const int kb = wid * 256;
; #pragma unroll 8
;   for (int k = 0; k < 256; ++k) {
;     const float wv = __builtin_nontemporal_load(w + (size_t)(kb + k) * 6144);
;     a0 += sc[kb + k] * wv;
;     a1 += sc[1024 + kb + k] * wv;
;     a2 += sc[2048 + kb + k] * wv;
;   }
;   red[(wid * 3 + 0) * 64 + lane] = a0;
;   red[(wid * 3 + 1) * 64 + lane] = a1;
;   red[(wid * 3 + 2) * 64 + lane] = a2;
;   __syncthreads();
;   if (t < 192) {
;     const int r = t >> 6, ln = t & 63;
;     float s = 0.f;
; #pragma unroll
;     for (int w4 = 0; w4 < 4; ++w4) s += red[(w4 * 3 + r) * 64 + ln];
;     s += p.b_ada[l * 6144 + jc * 64 + ln];
;     p.mada[(l * 3 + r) * 6144 + jc * 64 + ln] = s;
;   }
;   asm volatile("s_waitcnt vmcnt(0)" ::: "memory");
;   __syncthreads();
;   if (t == 0) {
;     __builtin_amdgcn_fence(__ATOMIC_RELEASE, "agent");
;     asm volatile("s_waitcnt vmcnt(0)" ::: "memory");
;     (void)xb_add(&p.bar[64], 1u);
;   }
.LBB0_9:
	v_lshl_add_u64 v[16:17], v[10:11], 0, s[30:31]
	v_add_co_u32_e32 v18, vcc, s45, v16
	global_load_dword v40, v[16:17], off nt
	s_nop 0
	v_addc_co_u32_e32 v19, vcc, 0, v17, vcc
	v_add_co_u32_e32 v20, vcc, s46, v16
	s_add_u32 s30, s30, 0x30000
	s_nop 0
	v_addc_co_u32_e32 v21, vcc, 0, v17, vcc
	v_add_co_u32_e32 v22, vcc, s47, v16
	s_addc_u32 s31, s31, 0
	s_nop 0
	v_addc_co_u32_e32 v23, vcc, 0, v17, vcc
	v_add_co_u32_e32 v24, vcc, s48, v16
	s_cmp_eq_u32 s30, 0x600000
	s_nop 0
	v_addc_co_u32_e32 v25, vcc, 0, v17, vcc
	v_add_co_u32_e32 v26, vcc, s49, v16
	s_nop 1
	v_addc_co_u32_e32 v27, vcc, 0, v17, vcc
	v_add_co_u32_e32 v28, vcc, s50, v16
	s_nop 1
	v_addc_co_u32_e32 v29, vcc, 0, v17, vcc
	v_add_co_u32_e32 v16, vcc, s51, v16
	s_nop 1
	v_addc_co_u32_e32 v17, vcc, 0, v17, vcc
	global_load_dword v42, v[18:19], off nt
	global_load_dword v44, v[20:21], off nt
	global_load_dword v46, v[22:23], off nt
	global_load_dword v48, v[24:25], off nt
	global_load_dword v50, v[26:27], off nt
	global_load_dword v52, v[28:29], off nt
	global_load_dword v54, v[16:17], off nt
	ds_read_b128 v[16:19], v14
	ds_read_b128 v[20:23], v14 offset:16
	ds_read_b128 v[24:27], v14 offset:4096
	ds_read_b128 v[28:31], v14 offset:4112
	ds_read_b128 v[32:35], v14 offset:8192
	ds_read_b128 v[36:39], v14 offset:8208
	s_waitcnt lgkmcnt(0)
	v_mov_b32_e32 v56, v16
	v_mov_b32_e32 v57, v24
	v_mov_b32_e32 v24, v17
	v_mov_b32_e32 v16, v18
	v_mov_b32_e32 v17, v26
	v_mov_b32_e32 v26, v19
	v_mov_b32_e32 v18, v20
	v_mov_b32_e32 v19, v28
	v_mov_b32_e32 v28, v21
	v_mov_b32_e32 v20, v22
	v_mov_b32_e32 v21, v30
	v_mov_b32_e32 v30, v23
	v_add_u32_e32 v14, 32, v14
	s_waitcnt vmcnt(0)
	v_pk_fma_f32 v[8:9], v[40:41], v[56:57], v[8:9] op_sel_hi:[0,1,1]
	v_fmac_f32_e32 v13, v40, v32
	v_pk_fma_f32 v[8:9], v[42:43], v[24:25], v[8:9] op_sel_hi:[0,1,1]
	v_fmac_f32_e32 v13, v42, v33
	v_pk_fma_f32 v[8:9], v[44:45], v[16:17], v[8:9] op_sel_hi:[0,1,1]
	v_fmac_f32_e32 v13, v44, v34
	v_pk_fma_f32 v[8:9], v[46:47], v[26:27], v[8:9] op_sel_hi:[0,1,1]
	v_fmac_f32_e32 v13, v46, v35
	v_pk_fma_f32 v[8:9], v[48:49], v[18:19], v[8:9] op_sel_hi:[0,1,1]
	v_fmac_f32_e32 v13, v48, v36
	v_pk_fma_f32 v[8:9], v[50:51], v[28:29], v[8:9] op_sel_hi:[0,1,1]
	v_fmac_f32_e32 v13, v50, v37
	v_pk_fma_f32 v[8:9], v[52:53], v[20:21], v[8:9] op_sel_hi:[0,1,1]
	v_fmac_f32_e32 v13, v52, v38
	v_pk_fma_f32 v[8:9], v[54:55], v[30:31], v[8:9] op_sel_hi:[0,1,1]
	v_fmac_f32_e32 v13, v54, v39
	s_cbranch_scc0 .LBB0_9
	v_mul_lo_u32 v10, v4, s39
	v_lshl_or_b32 v10, v7, 2, v10
	v_cmp_gt_i32_e32 vcc, s52, v6
	ds_write2st64_b32 v10, v8, v9 offset0:48 offset1:49
	ds_write_b32 v10, v13 offset:12800
	s_waitcnt lgkmcnt(0)
	s_barrier
	s_and_saveexec_b64 s[30:31], vcc
	s_cbranch_execz .LBB0_12
	global_load_dwordx2 v[8:9], v[2:3], off offset:40
	global_load_dwordx2 v[10:11], v[2:3], off offset:184
	s_mul_i32 s29, s54, 0x1800
	s_add_i32 s29, s29, s28
	v_or_b32_e32 v14, s29, v7
	v_ashrrev_i32_e32 v15, 31, v14
	s_waitcnt vmcnt(0) lgkmcnt(0)
	v_lshl_add_u64 v[8:9], v[14:15], 2, v[8:9]
	global_load_dword v16, v[8:9], off
	v_lshl_add_u32 v14, v7, 2, v12
	ds_read2st64_b32 v[12:13], v14 offset0:48 offset1:51
	ds_read2st64_b32 v[14:15], v14 offset0:54 offset1:57
	v_mad_u64_u32 v[8:9], s[54:55], s54, 3, v[4:5]
	v_mul_lo_u32 v4, v8, s53
	v_add_u32_e32 v4, s28, v4
	v_or_b32_e32 v8, v4, v7
	s_waitcnt lgkmcnt(0)
	v_add_f32_e32 v4, 0, v12
	v_add_f32_e32 v4, v4, v13
	v_add_f32_e32 v4, v4, v14
	v_ashrrev_i32_e32 v9, 31, v8
	v_add_f32_e32 v4, v4, v15
	v_lshl_add_u64 v[8:9], v[8:9], 2, v[10:11]
	s_waitcnt vmcnt(0)
	v_add_f32_e32 v4, v4, v16
	global_store_dword v[8:9], v4, off
.LBB0_12:
	s_or_b64 exec, exec, s[30:31]
	s_waitcnt vmcnt(0)
	v_cmp_eq_u32_e32 vcc, 0, v6
	s_waitcnt lgkmcnt(0)
	s_barrier
	s_and_saveexec_b64 s[28:29], vcc
	s_cbranch_execz .LBB0_7
	buffer_wbl2 sc1
	s_waitcnt vmcnt(0)
	s_waitcnt vmcnt(0)
	global_load_dwordx2 v[6:7], v[2:3], off offset:176
	s_waitcnt vmcnt(0) lgkmcnt(0)
	global_atomic_add v[6:7], v1, off offset:256
	s_branch .LBB0_7

; __device__ __forceinline__ int tid_() { int t = threadIdx.x; asm volatile("" : "+v"(t)); return t; }
; __device__ __forceinline__ void fold_item(const Params& p, int it, unsigned char* smem) {
;   float* tile = (float*)smem;
;   float* ct = tile + 64 * 65;
;   const int t = tid_();
;   const int l = it >> 6, rem = it & 63, g = rem >> 4, k0 = (rem & 15) * 64;
; #pragma unroll
;   for (int i = 0; i < 16; ++i) {
;     const int kk = i * 4 + (t >> 6), d = t & 63;
;     tile[kk * 65 + d] = __builtin_nontemporal_load(p.w_in + (size_t)(l * 1024 + k0 + kk) * 1216 + 512 + g * 64 + d);
;   }
;   if (t < 64) ct[t] = cospif((float)t / 32.f);
;   __syncthreads();
;   const int k = t & 63, jg = t >> 6;
;   u16* dst = p.WinT + (size_t)l * 1536 * 1024;
.LBB0_16:
	v_mov_b32_e32 v6, v187
	global_load_dwordx2 v[8:9], v[2:3], off offset:48
	s_ashr_i32 s16, s6, 6
	s_lshl_b32 s0, s6, 6
	s_lshl_b32 s4, s6, 2
	s_and_b32 s17, s0, 0x3c0
	s_lshl_b32 s0, s16, 10
	s_and_b32 s15, s4, 0xc0
	v_ashrrev_i32_e32 v13, 6, v6
	s_or_b32 s4, s0, s17
	v_add_u32_e32 v18, s4, v13
	v_and_b32_e32 v7, 63, v6
	s_lshl_b32 s0, s15, 2
	v_lshlrev_b32_e32 v4, 2, v7
	v_cmp_gt_i32_e32 vcc, 64, v6
	s_waitcnt vmcnt(0) lgkmcnt(0)
	v_mad_i64_i32 v[14:15], s[4:5], v18, s7, v[8:9]
	v_lshl_add_u64 v[14:15], v[14:15], 0, s[0:1]
	v_lshl_add_u64 v[14:15], v[14:15], 0, v[4:5]
	global_load_dword v19, v[14:15], off offset:2048 nt
	v_mad_u64_u32 v[14:15], s[4:5], v13, s12, v[4:5]
	v_add_u32_e32 v15, 4, v18
	v_mad_i64_i32 v[16:17], s[4:5], v15, s7, v[8:9]
	v_lshl_add_u64 v[16:17], v[16:17], 0, s[0:1]
	v_lshl_add_u64 v[16:17], v[16:17], 0, v[4:5]
	s_waitcnt vmcnt(0) lgkmcnt(0)
	ds_write_b32 v14, v19
	global_load_dword v15, v[16:17], off offset:2048 nt
	v_add_u32_e32 v16, 8, v18
	v_mad_i64_i32 v[16:17], s[4:5], v16, s7, v[8:9]
	v_lshl_add_u64 v[16:17], v[16:17], 0, s[0:1]
	v_lshl_add_u64 v[16:17], v[16:17], 0, v[4:5]
	s_waitcnt vmcnt(0) lgkmcnt(0)
	ds_write_b32 v14, v15 offset:1040
	global_load_dword v15, v[16:17], off offset:2048 nt
	v_add_u32_e32 v16, 12, v18
	v_mad_i64_i32 v[16:17], s[4:5], v16, s7, v[8:9]
	v_lshl_add_u64 v[16:17], v[16:17], 0, s[0:1]
	v_lshl_add_u64 v[16:17], v[16:17], 0, v[4:5]
	s_waitcnt vmcnt(0) lgkmcnt(0)
	ds_write_b32 v14, v15 offset:2080
	global_load_dword v15, v[16:17], off offset:2048 nt
	v_add_u32_e32 v16, 16, v18
	v_mad_i64_i32 v[16:17], s[4:5], v16, s7, v[8:9]
	v_lshl_add_u64 v[16:17], v[16:17], 0, s[0:1]
	v_lshl_add_u64 v[16:17], v[16:17], 0, v[4:5]
	s_waitcnt vmcnt(0) lgkmcnt(0)
	ds_write_b32 v14, v15 offset:3120
	global_load_dword v15, v[16:17], off offset:2048 nt
	v_add_u32_e32 v16, 20, v18
	v_mad_i64_i32 v[16:17], s[4:5], v16, s7, v[8:9]
	v_lshl_add_u64 v[16:17], v[16:17], 0, s[0:1]
	v_lshl_add_u64 v[16:17], v[16:17], 0, v[4:5]
	s_waitcnt vmcnt(0) lgkmcnt(0)
	ds_write_b32 v14, v15 offset:4160
	global_load_dword v15, v[16:17], off offset:2048 nt
	v_add_u32_e32 v16, 24, v18
	v_mad_i64_i32 v[16:17], s[4:5], v16, s7, v[8:9]
	v_lshl_add_u64 v[16:17], v[16:17], 0, s[0:1]
	v_lshl_add_u64 v[16:17], v[16:17], 0, v[4:5]
	s_waitcnt vmcnt(0) lgkmcnt(0)
	ds_write_b32 v14, v15 offset:5200
	global_load_dword v15, v[16:17], off offset:2048 nt
	v_add_u32_e32 v16, 28, v18
	v_mad_i64_i32 v[16:17], s[4:5], v16, s7, v[8:9]
	v_lshl_add_u64 v[16:17], v[16:17], 0, s[0:1]
	v_lshl_add_u64 v[16:17], v[16:17], 0, v[4:5]
	s_waitcnt vmcnt(0) lgkmcnt(0)
	ds_write_b32 v14, v15 offset:6240
	global_load_dword v15, v[16:17], off offset:2048 nt
	v_add_u32_e32 v16, 32, v18
	v_mad_i64_i32 v[16:17], s[4:5], v16, s7, v[8:9]
	v_lshl_add_u64 v[16:17], v[16:17], 0, s[0:1]
	v_lshl_add_u64 v[16:17], v[16:17], 0, v[4:5]
	s_waitcnt vmcnt(0) lgkmcnt(0)
	ds_write_b32 v14, v15 offset:7280
	global_load_dword v15, v[16:17], off offset:2048 nt
	v_add_u32_e32 v16, 36, v18
	v_mad_i64_i32 v[16:17], s[4:5], v16, s7, v[8:9]
	v_lshl_add_u64 v[16:17], v[16:17], 0, s[0:1]
	v_lshl_add_u64 v[16:17], v[16:17], 0, v[4:5]
	s_waitcnt vmcnt(0) lgkmcnt(0)
	ds_write_b32 v14, v15 offset:8320
	global_load_dword v15, v[16:17], off offset:2048 nt
	v_add_u32_e32 v16, 40, v18
	v_mad_i64_i32 v[16:17], s[4:5], v16, s7, v[8:9]
	v_lshl_add_u64 v[16:17], v[16:17], 0, s[0:1]
	v_lshl_add_u64 v[16:17], v[16:17], 0, v[4:5]
	s_waitcnt vmcnt(0) lgkmcnt(0)
	ds_write_b32 v14, v15 offset:9360
	global_load_dword v15, v[16:17], off offset:2048 nt
	v_add_u32_e32 v16, 44, v18
	v_mad_i64_i32 v[16:17], s[4:5], v16, s7, v[8:9]
	v_lshl_add_u64 v[16:17], v[16:17], 0, s[0:1]
	v_lshl_add_u64 v[16:17], v[16:17], 0, v[4:5]
	s_waitcnt vmcnt(0) lgkmcnt(0)
	ds_write_b32 v14, v15 offset:10400
	global_load_dword v15, v[16:17], off offset:2048 nt
	v_add_u32_e32 v16, 48, v18
	v_mad_i64_i32 v[16:17], s[4:5], v16, s7, v[8:9]
	v_lshl_add_u64 v[16:17], v[16:17], 0, s[0:1]
	v_lshl_add_u64 v[16:17], v[16:17], 0, v[4:5]
	s_waitcnt vmcnt(0) lgkmcnt(0)
	ds_write_b32 v14, v15 offset:11440
	global_load_dword v15, v[16:17], off offset:2048 nt
	v_add_u32_e32 v16, 52, v18
	v_mad_i64_i32 v[16:17], s[4:5], v16, s7, v[8:9]
	v_lshl_add_u64 v[16:17], v[16:17], 0, s[0:1]
	v_lshl_add_u64 v[16:17], v[16:17], 0, v[4:5]
	s_waitcnt vmcnt(0) lgkmcnt(0)
	ds_write_b32 v14, v15 offset:12480
	global_load_dword v15, v[16:17], off offset:2048 nt
	v_add_u32_e32 v16, 56, v18
	v_mad_i64_i32 v[16:17], s[4:5], v16, s7, v[8:9]
	v_lshl_add_u64 v[16:17], v[16:17], 0, s[0:1]
	v_lshl_add_u64 v[16:17], v[16:17], 0, v[4:5]
	s_waitcnt vmcnt(0) lgkmcnt(0)
	ds_write_b32 v14, v15 offset:13520
	global_load_dword v15, v[16:17], off offset:2048 nt
	v_add_u32_e32 v16, 60, v18
	v_mad_i64_i32 v[8:9], s[4:5], v16, s7, v[8:9]
	v_lshl_add_u64 v[8:9], v[8:9], 0, s[0:1]
	v_lshl_add_u64 v[8:9], v[8:9], 0, v[4:5]
	s_waitcnt vmcnt(0) lgkmcnt(0)
	ds_write_b32 v14, v15 offset:14560
	global_load_dword v4, v[8:9], off offset:2048 nt
	s_waitcnt vmcnt(0) lgkmcnt(0)
	ds_write_b32 v14, v4 offset:15600
	s_and_saveexec_b64 s[4:5], vcc
	s_cbranch_execz .LBB0_18
	v_cvt_f32_i32_e32 v4, v6
	v_lshlrev_b32_e32 v6, 2, v6
	v_mul_f32_e32 v4, 0x3d000000, v4
	v_mul_f32_e64 v8, |v4|, 0.5
	v_fract_f32_e32 v9, v8
	v_add_f32_e32 v9, v9, v9
	v_cmp_neq_f32_e32 vcc, s13, v8
	v_cmp_gt_f32_e64 s[18:19], |v4|, 1.0
	s_nop 0
	v_cndmask_b32_e32 v8, 0, v9, vcc
	v_cndmask_b32_e64 v8, |v4|, v8, s[18:19]
	v_add_f32_e32 v9, v8, v8
	v_rndne_f32_e32 v9, v9
	v_fmac_f32_e32 v8, -0.5, v9
	v_mul_f32_e32 v14, v8, v8
	v_fmamk_f32 v15, v14, 0x3e75aa41, v1
	v_fmaak_f32 v15, v14, v15, 0x40234736
	v_fmaak_f32 v15, v14, v15, 0xc0a55e0e
	v_mul_f32_e32 v17, v8, v14
	v_cvt_i32_f32_e32 v9, v9
	v_mul_f32_e32 v15, v17, v15
	v_fmac_f32_e32 v15, 0x40490fdb, v8
	v_fmamk_f32 v8, v14, 0x3d4be544, v10
	v_fmaak_f32 v8, v14, v8, 0xbfaad1da
	v_fmaak_f32 v8, v14, v8, 0x4081e0d3
	v_and_b32_e32 v16, 2, v9
	v_fmaak_f32 v8, v14, v8, 0xc09de9e6
	v_and_b32_e32 v9, 1, v9
	v_fma_f32 v8, v14, v8, 1.0
	v_cmp_eq_u32_e32 vcc, 0, v9
	s_nop 1
	v_cndmask_b32_e64 v8, -v15, v8, vcc
	v_cmp_eq_u32_e32 vcc, 0, v16
	s_nop 1
	v_cndmask_b32_e64 v8, -v8, v8, vcc
	v_cmp_class_f32_e64 vcc, v4, s14
	s_nop 1
	v_cndmask_b32_e32 v4, v12, v8, vcc
	ds_write_b32 v6, v4 offset:16640
.LBB0_18:
	s_or_b64 exec, exec, s[4:5]
	s_waitcnt lgkmcnt(0)
	s_barrier
	global_load_dwordx2 v[8:9], v[2:3], off offset:192
	v_mul_u32_u24_e32 v14, 0x104, v7
	s_lshl_b32 s0, s17, 1
	v_lshlrev_b32_e32 v4, 1, v7
	s_or_b32 s4, s15, 0x200
	s_or_b32 s5, s15, 0x300
	v_lshlrev_b32_e32 v15, 3, v13
	v_lshlrev_b32_e32 v16, 1, v13
	v_lshl_add_u32 v17, v13, 1, v13
	v_lshlrev_b32_e32 v18, 2, v13
	v_lshl_add_u32 v19, v13, 2, v13
	v_mul_lo_u32 v20, v13, 6
	v_mul_lo_u32 v21, v13, 7
	s_mov_b32 s15, 0
	s_waitcnt vmcnt(0) lgkmcnt(0)
	v_mad_i64_i32 v[6:7], s[16:17], s16, v11, v[8:9]
	v_lshl_add_u64 v[6:7], v[6:7], 0, s[0:1]
	v_lshl_add_u64 v[6:7], v[6:7], 0, v[4:5]
	v_mov_b32_e32 v4, v13

; __device__ __forceinline__ u16 f2bf(float f) { return (u16)(pack2(f, 0.f) & 0xffffu); }
; __device__ __forceinline__ void fold_item(const Params& p, int it, unsigned char* smem) {
;     ...
;   const int k = t & 63, jg = t >> 6;
;   u16* dst = p.WinT + (size_t)l * 1536 * 1024;
;   for (int jj = 0; jj < 16; ++jj) {
;     const int j = jg + 4 * jj;
;     float sr = 0.f, si = 0.f;
; #pragma unroll 8
;     for (int d = 0; d < 64; ++d) {
;       const float v = tile[k * 65 + d];
;       const int m = (j * d) & 63;
;       sr += v * ct[m];
;       si += v * ct[(m - 16) & 63];
;     }
;     dst[(size_t)(512 + g * 64 + j) * 1024 + k0 + k] = f2bf(sr);
;     dst[(size_t)(768 + g * 64 + j) * 1024 + k0 + k] = f2bf(-si);
;   }
;   __syncthreads();
; }
.LBB0_20:
	v_and_b32_e32 v24, 56, v22
	v_add_u32_e32 v23, s0, v14
	v_add_u32_e32 v25, 48, v22
	v_add_u32_e32 v26, v4, v22
	v_add_u32_e32 v27, v16, v22
	v_add_u32_e32 v28, v17, v22
	v_add_u32_e32 v29, v18, v22
	v_add_u32_e32 v30, v19, v22
	v_add_u32_e32 v33, v21, v22
	v_lshlrev_b32_e32 v34, 2, v24
	v_and_b32_e32 v35, 56, v25
	v_and_b32_e32 v36, 63, v26
	v_add_u32_e32 v37, 48, v26
	v_and_b32_e32 v38, 62, v27
	v_add_u32_e32 v39, 48, v27
	v_and_b32_e32 v40, 63, v28
	v_add_u32_e32 v41, 48, v28
	v_and_b32_e32 v42, 60, v29
	v_add_u32_e32 v43, 48, v29
	v_and_b32_e32 v44, 63, v30
	v_add_u32_e32 v45, 48, v30
	ds_read2_b32 v[24:25], v23 offset1:1
	ds_read2_b32 v[26:27], v23 offset0:2 offset1:3
	ds_read2_b32 v[28:29], v23 offset0:4 offset1:5
	ds_read2_b32 v[30:31], v23 offset0:6 offset1:7
	v_and_b32_e32 v46, 63, v33
	v_add_u32_e32 v47, 48, v33
	ds_read_b32 v33, v34 offset:16640
	v_add_u32_e32 v32, v20, v22
	v_and_b32_e32 v23, 62, v32
	v_add_u32_e32 v32, 48, v32
	v_lshlrev_b32_e32 v34, 2, v35
	v_and_b32_e32 v35, 63, v37
	v_and_b32_e32 v37, 62, v39
	v_and_b32_e32 v39, 63, v41
	v_lshlrev_b32_e32 v41, 2, v42
	v_and_b32_e32 v42, 60, v43
	v_lshlrev_b32_e32 v43, 2, v44
	v_and_b32_e32 v44, 63, v45
	v_lshlrev_b32_e32 v36, 2, v36
	v_lshlrev_b32_e32 v38, 2, v38
	v_lshlrev_b32_e32 v40, 2, v40
	v_and_b32_e32 v32, 62, v32
	v_lshlrev_b32_e32 v46, 2, v46
	v_and_b32_e32 v45, 63, v47
	v_lshlrev_b32_e32 v47, 2, v35
	ds_read_b32 v35, v41 offset:16640
	v_lshlrev_b32_e32 v42, 2, v42
	v_lshlrev_b32_e32 v44, 2, v44
	v_lshlrev_b32_e32 v23, 2, v23
	v_lshlrev_b32_e32 v48, 2, v37
	v_lshlrev_b32_e32 v49, 2, v39
	v_lshlrev_b32_e32 v50, 2, v32
	v_lshlrev_b32_e32 v51, 2, v45
	ds_read_b32 v32, v34 offset:16640
	ds_read_b32 v37, v36 offset:16640
	ds_read_b32 v36, v47 offset:16640
	ds_read_b32 v39, v38 offset:16640
	ds_read_b32 v38, v48 offset:16640
	ds_read_b32 v41, v40 offset:16640
	ds_read_b32 v40, v49 offset:16640
	ds_read_b32 v34, v42 offset:16640
	ds_read_b32 v43, v43 offset:16640
	ds_read_b32 v42, v44 offset:16640
	ds_read_b32 v45, v23 offset:16640
	ds_read_b32 v44, v50 offset:16640
	ds_read_b32 v47, v46 offset:16640
	ds_read_b32 v46, v51 offset:16640
	s_waitcnt lgkmcnt(0)
	v_pk_fma_f32 v[8:9], v[24:25], v[32:33], v[8:9] op_sel_hi:[0,1,1]
	s_waitcnt lgkmcnt(11)
	v_pk_fma_f32 v[8:9], v[24:25], v[36:37], v[8:9] op_sel:[1,0,0]
	s_add_i32 s0, s0, 32
	s_waitcnt lgkmcnt(9)
	v_pk_fma_f32 v[8:9], v[26:27], v[38:39], v[8:9] op_sel_hi:[0,1,1]
	s_waitcnt lgkmcnt(7)
	v_pk_fma_f32 v[8:9], v[26:27], v[40:41], v[8:9] op_sel:[1,0,0]
	v_add_u32_e32 v22, v22, v15
	s_waitcnt lgkmcnt(6)
	v_pk_fma_f32 v[8:9], v[28:29], v[34:35], v[8:9] op_sel_hi:[0,1,1]
	s_waitcnt lgkmcnt(4)
	v_pk_fma_f32 v[8:9], v[28:29], v[42:43], v[8:9] op_sel:[1,0,0]
	s_cmpk_eq_i32 s0, 0x100
	s_waitcnt lgkmcnt(2)
	v_pk_fma_f32 v[8:9], v[30:31], v[44:45], v[8:9] op_sel_hi:[0,1,1]
	s_waitcnt lgkmcnt(0)
	v_pk_fma_f32 v[8:9], v[30:31], v[46:47], v[8:9] op_sel:[1,0,0]
	s_cbranch_scc0 .LBB0_20
	v_lshl_add_u32 v24, s15, 2, v13
	v_add_u32_e32 v22, s4, v24
	v_ashrrev_i32_e32 v23, 31, v22
	v_lshlrev_b64 v[22:23], 11, v[22:23]
	v_cvt_pk_bf16_f32 v9, v9, s0
	v_lshl_add_u64 v[22:23], v[6:7], 0, v[22:23]
	global_store_short v[22:23], v9, off
	v_cvt_pk_bf16_f32 v22, -v8, s0
	v_add_u32_e32 v8, s5, v24
	v_ashrrev_i32_e32 v9, 31, v8
	v_lshlrev_b64 v[8:9], 11, v[8:9]
	s_add_i32 s15, s15, 1
	v_lshl_add_u64 v[8:9], v[6:7], 0, v[8:9]
	v_add_u32_e32 v4, 4, v4
	v_add_u32_e32 v15, 32, v15
	v_add_u32_e32 v16, 8, v16
	v_add_u32_e32 v17, 12, v17
	v_add_u32_e32 v18, 16, v18
	v_add_u32_e32 v19, 20, v19
	v_add_u32_e32 v20, 24, v20
	s_cmp_eq_u32 s15, 16
	v_add_u32_e32 v21, 28, v21
	global_store_short v[8:9], v22, off
	s_cbranch_scc0 .LBB0_19
	s_waitcnt lgkmcnt(0)
	s_barrier
	s_load_dwordx2 s[4:5], s[64:65], 0x1b0
	s_waitcnt lgkmcnt(0)
	s_add_i32 s6, s6, s4
	s_cmpk_lt_i32 s6, 0x80
	s_cbranch_scc1 .LBB0_16

; __device__ __forceinline__ u16 f2bf(float f) { return (u16)(pack2(f, 0.f) & 0xffffu); }
; __device__ __forceinline__ int tid_() { int t = threadIdx.x; asm volatile("" : "+v"(t)); return t; }
; __device__ __forceinline__ void convT_tile(const float* __restrict__ src, int lds, int k0, int c0, u16* __restrict__ dst, int Kd,
;                                            int rbase, int mode, int which, unsigned char* smem, const float* __restrict__ kscale = nullptr) {
;   float* tile = (float*)smem;
;   const int t = tid_();
;   float4 v4[4];
; #pragma unroll
;   for (int i = 0; i < 4; ++i) {
;     const f32x4 w_ = __builtin_nontemporal_load((const f32x4*)(src + (size_t)(k0 + i * 16 + (t >> 4)) * lds + c0 + (t & 15) * 4));
;     v4[i] = make_float4(w_[0], w_[1], w_[2], w_[3]);
;   }
; #pragma unroll
;   for (int i = 0; i < 4; ++i) {
;     const int kk = i * 16 + (t >> 4), cc = (t & 15) * 4;
;     const float sc = kscale ? kscale[k0 + kk] : 1.f;
;     tile[kk * 65 + cc + 0] = v4[i].x * sc; tile[kk * 65 + cc + 1] = v4[i].y * sc;
;     tile[kk * 65 + cc + 2] = v4[i].z * sc; tile[kk * 65 + cc + 3] = v4[i].w * sc;
;   }
;   __syncthreads();
; #pragma unroll
;   for (int i = 0; i < 16; ++i) {
;     const int cc = i * 4 + (t >> 6), kk = t & 63;
;     int row;
;     if (mode == 0) row = rbase + cc;
;     else { const int f = c0 + cc; row = (((f >> 4) * 2 + which) << 4) + (f & 15); }
;     dst[(size_t)row * Kd + k0 + kk] = f2bf(tile[kk * 65 + cc]);
;   }
;   __syncthreads();
; }
; __device__ __forceinline__ void conv_item(const Params& p, int it, unsigned char* smem) {
;     ...
;   {
;     const int e = r >> 7, r3 = r & 127, ct = r3 >> 3, kt = r3 & 7;
;     convT_tile(p.w_down + (size_t)(l * 16 + e) * 512 * 1024, 1024, kt * 64, ct * 64, p.WdT + (size_t)(l * 16 + e) * 1024 * 512, 512, ct * 64, 0, 0, smem);
;   }
.LBB0_26:
	s_mul_hi_i32 s0, s14, 0x9c09c09d
	s_add_i32 s0, s0, s14
	s_lshr_b32 s1, s0, 31
	s_ashr_i32 s0, s0, 12
	s_add_i32 s6, s0, s1
	s_mul_i32 s0, s6, 0xffffe5c0
	s_add_i32 s35, s14, s0
	s_cmpk_gt_i32 s35, 0xef
	s_mov_b64 s[0:1], -1
	s_cbranch_scc0 .LBB0_60
	s_cmpk_gt_u32 s35, 0x11f
	s_cbranch_scc0 .LBB0_49
	s_cmpk_gt_u32 s35, 0x13f
	s_cbranch_scc0 .LBB0_38
	s_cmpk_gt_u32 s35, 0x23f
	s_cbranch_scc0 .LBB0_35
	s_cmpk_gt_u32 s35, 0x123f
	s_cbranch_scc0 .LBB0_32
	v_mov_b64_e32 v[2:3], s[10:11]
	global_load_dwordx2 v[4:5], v[2:3], off offset:160
	s_add_i32 s0, s35, 0xffffedc0
	s_lshl_b32 s1, s6, 4
	s_lshl_b32 s4, s6, 9
	s_lshr_b32 s0, s0, 7
	v_mov_b32_e32 v6, v187
	s_sub_i32 s4, s23, s4
	s_add_i32 s0, s0, s1
	global_load_dwordx2 v[2:3], v[2:3], off offset:232
	s_and_b32 s12, s4, 0x3c0
	v_ashrrev_i32_e32 v9, 6, v6
	s_ashr_i32 s1, s0, 31
	s_and_b32 s7, s15, 0x1c0
	v_ashrrev_i32_e32 v8, 4, v6
	s_lshl_b32 s4, s12, 2
	v_add_u32_e32 v16, s12, v9
	s_lshl_b64 s[12:13], s[0:1], 21
	v_lshlrev_b32_e32 v7, 4, v6
	v_and_b32_e32 v24, 63, v6
	v_add_u32_e32 v6, s7, v8
	v_and_b32_e32 v18, 0xf0, v7
	v_ashrrev_i32_e32 v7, 31, v6
	v_lshlrev_b64 v[6:7], 12, v[6:7]
	v_lshlrev_b32_e32 v9, 2, v9
	v_mad_u64_u32 v[30:31], s[36:37], v8, s28, v[18:19]
	v_mad_u32_u24 v26, v24, s28, v9
	v_add_u32_e32 v29, 0x1040, v30
	v_add_u32_e32 v31, 0x1048, v30
	v_add_u32_e32 v62, 0x2080, v30
	v_add_u32_e32 v63, 0x2088, v30
	v_add_u32_e32 v64, 0x30c0, v30
	v_add_u32_e32 v65, 0x30c8, v30
	s_lshl_b64 s[0:1], s[0:1], 20
	v_add_u32_e32 v34, 8, v16
	v_add_u32_e32 v36, 12, v16
	v_add_u32_e32 v38, 16, v16
	v_add_u32_e32 v40, 20, v16
	v_add_u32_e32 v42, 24, v16
	v_add_u32_e32 v44, 28, v16
	v_add_u32_e32 v46, 32, v16
	v_add_u32_e32 v48, 36, v16
	v_add_u32_e32 v50, 40, v16
	v_add_u32_e32 v52, 44, v16
	v_add_u32_e32 v54, 48, v16
	v_add_u32_e32 v56, 52, v16
	v_add_u32_e32 v58, 56, v16
	v_add_u32_e32 v60, 60, v16
	v_ashrrev_i32_e32 v17, 31, v16
	v_ashrrev_i32_e32 v35, 31, v34
	v_ashrrev_i32_e32 v37, 31, v36
	v_ashrrev_i32_e32 v39, 31, v38
	v_ashrrev_i32_e32 v41, 31, v40
	v_ashrrev_i32_e32 v43, 31, v42
	v_ashrrev_i32_e32 v45, 31, v44
	v_ashrrev_i32_e32 v47, 31, v46
	v_ashrrev_i32_e32 v49, 31, v48
	v_ashrrev_i32_e32 v51, 31, v50
	v_ashrrev_i32_e32 v53, 31, v52
	v_ashrrev_i32_e32 v55, 31, v54
	v_ashrrev_i32_e32 v57, 31, v56
	v_ashrrev_i32_e32 v59, 31, v58
	v_ashrrev_i32_e32 v61, 31, v60
	v_lshlrev_b64 v[34:35], 10, v[34:35]
	v_lshlrev_b64 v[36:37], 10, v[36:37]
	v_lshlrev_b64 v[38:39], 10, v[38:39]
	v_lshlrev_b64 v[40:41], 10, v[40:41]
	v_lshlrev_b64 v[42:43], 10, v[42:43]
	v_lshlrev_b64 v[44:45], 10, v[44:45]
	v_lshlrev_b64 v[46:47], 10, v[46:47]
	v_lshlrev_b64 v[48:49], 10, v[48:49]
	v_lshlrev_b64 v[50:51], 10, v[50:51]
	v_lshlrev_b64 v[52:53], 10, v[52:53]
	v_lshlrev_b64 v[54:55], 10, v[54:55]
	v_lshlrev_b64 v[56:57], 10, v[56:57]
	v_lshlrev_b64 v[58:59], 10, v[58:59]
	v_lshlrev_b64 v[60:61], 10, v[60:61]
	s_waitcnt vmcnt(0) lgkmcnt(0)
	v_lshl_add_u64 v[4:5], v[4:5], 0, s[12:13]
	v_lshl_add_u64 v[4:5], v[4:5], 0, s[4:5]
	v_lshl_add_u64 v[4:5], v[4:5], 0, v[18:19]
	v_lshl_add_u64 v[20:21], v[4:5], 0, v[6:7]
	v_add_co_u32_e32 v22, vcc, s25, v20
	s_lshl_b32 s4, s7, 1
	s_nop 0
	v_addc_co_u32_e32 v23, vcc, 0, v21, vcc
	v_add_co_u32_e32 v32, vcc, s26, v20
	v_lshl_add_u64 v[2:3], v[2:3], 0, s[0:1]
	s_nop 0
	v_addc_co_u32_e32 v33, vcc, 0, v21, vcc
	global_load_dwordx4 v[4:7], v[20:21], off nt
	global_load_dwordx4 v[8:11], v[22:23], off nt
	global_load_dwordx4 v[12:15], v[32:33], off nt
	v_add_co_u32_e32 v20, vcc, s27, v20
	v_add_u32_e32 v32, 4, v16
	s_nop 0
	v_addc_co_u32_e32 v21, vcc, 0, v21, vcc
	global_load_dwordx4 v[20:23], v[20:21], off nt
	v_ashrrev_i32_e32 v33, 31, v32
	v_lshl_add_u64 v[2:3], v[2:3], 0, s[4:5]
	v_lshlrev_b32_e32 v18, 1, v24
	v_lshlrev_b64 v[16:17], 10, v[16:17]
	v_lshlrev_b64 v[32:33], 10, v[32:33]
	v_lshl_add_u64 v[2:3], v[2:3], 0, v[18:19]
	v_lshl_add_u64 v[16:17], v[2:3], 0, v[16:17]
	v_lshl_add_u64 v[32:33], v[2:3], 0, v[32:33]
	v_lshl_add_u64 v[34:35], v[2:3], 0, v[34:35]
	v_lshl_add_u64 v[36:37], v[2:3], 0, v[36:37]
	v_lshl_add_u64 v[38:39], v[2:3], 0, v[38:39]
	v_lshl_add_u64 v[40:41], v[2:3], 0, v[40:41]
	v_lshl_add_u64 v[42:43], v[2:3], 0, v[42:43]
	v_lshl_add_u64 v[44:45], v[2:3], 0, v[44:45]
	v_lshl_add_u64 v[46:47], v[2:3], 0, v[46:47]
	v_lshl_add_u64 v[48:49], v[2:3], 0, v[48:49]
	v_lshl_add_u64 v[50:51], v[2:3], 0, v[50:51]
	v_lshl_add_u64 v[52:53], v[2:3], 0, v[52:53]
	v_lshl_add_u64 v[54:55], v[2:3], 0, v[54:55]
	v_lshl_add_u64 v[56:57], v[2:3], 0, v[56:57]
	v_lshl_add_u64 v[58:59], v[2:3], 0, v[58:59]
	v_lshl_add_u64 v[2:3], v[2:3], 0, v[60:61]
	s_waitcnt vmcnt(0) lgkmcnt(0)
	ds_write2_b32 v30, v4, v5 offset1:1
	ds_write2_b32 v30, v6, v7 offset0:2 offset1:3
	ds_write2_b32 v29, v8, v9 offset1:1
	ds_write2_b32 v31, v10, v11 offset1:1
	ds_write2_b32 v62, v12, v13 offset1:1
	ds_write2_b32 v63, v14, v15 offset1:1
	ds_write2_b32 v64, v20, v21 offset1:1
	ds_write2_b32 v65, v22, v23 offset1:1
	s_waitcnt lgkmcnt(0)
	s_barrier
	ds_read2_b32 v[4:5], v26 offset1:4
	ds_read2_b32 v[6:7], v26 offset0:8 offset1:12
	ds_read2_b32 v[8:9], v26 offset0:16 offset1:20
	ds_read2_b32 v[10:11], v26 offset0:24 offset1:28
	ds_read2_b32 v[12:13], v26 offset0:32 offset1:36
	ds_read2_b32 v[14:15], v26 offset0:40 offset1:44
	ds_read2_b32 v[20:21], v26 offset0:48 offset1:52
	ds_read2_b32 v[22:23], v26 offset0:56 offset1:60
	s_waitcnt lgkmcnt(7)
	v_cvt_pk_bf16_f32 v4, v4, s0
	v_cvt_pk_bf16_f32 v5, v5, s0
	s_waitcnt lgkmcnt(6)
	v_cvt_pk_bf16_f32 v6, v6, s0
	s_waitcnt lgkmcnt(1)
	v_cvt_pk_bf16_f32 v18, v20, s0
	v_cvt_pk_bf16_f32 v20, v21, s0
	s_waitcnt lgkmcnt(0)
	v_cvt_pk_bf16_f32 v21, v22, s0
	v_cvt_pk_bf16_f32 v22, v23, s0
	v_cvt_pk_bf16_f32 v7, v7, s0
	v_cvt_pk_bf16_f32 v8, v8, s0
	v_cvt_pk_bf16_f32 v9, v9, s0
	v_cvt_pk_bf16_f32 v10, v10, s0
	v_cvt_pk_bf16_f32 v11, v11, s0
	v_cvt_pk_bf16_f32 v12, v12, s0
	v_cvt_pk_bf16_f32 v13, v13, s0
	v_cvt_pk_bf16_f32 v14, v14, s0
	v_cvt_pk_bf16_f32 v15, v15, s0
	global_store_short v[16:17], v4, off
	global_store_short v[32:33], v5, off
	global_store_short v[34:35], v6, off
	global_store_short v[36:37], v7, off
	global_store_short v[38:39], v8, off
	global_store_short v[40:41], v9, off
	global_store_short v[42:43], v10, off
	global_store_short v[44:45], v11, off
	global_store_short v[46:47], v12, off
	global_store_short v[48:49], v13, off
	global_store_short v[50:51], v14, off
	global_store_short v[52:53], v15, off
	global_store_short v[54:55], v18, off
	global_store_short v[56:57], v20, off
	global_store_short v[58:59], v21, off
	global_store_short v[2:3], v22, off
	s_waitcnt lgkmcnt(0)
	s_barrier
	s_mov_b64 s[0:1], 0
; __device__ __forceinline__ u16 f2bf(float f) { return (u16)(pack2(f, 0.f) & 0xffffu); }
; __device__ __forceinline__ int tid_() { int t = threadIdx.x; asm volatile("" : "+v"(t)); return t; }
; __device__ __forceinline__ void convT_tile(const float* __restrict__ src, int lds, int k0, int c0, u16* __restrict__ dst, int Kd,
;                                            int rbase, int mode, int which, unsigned char* smem, const float* __restrict__ kscale = nullptr) {
;   float* tile = (float*)smem;
;   const int t = tid_();
;   float4 v4[4];
; #pragma unroll
;   for (int i = 0; i < 4; ++i) {
;     const f32x4 w_ = __builtin_nontemporal_load((const f32x4*)(src + (size_t)(k0 + i * 16 + (t >> 4)) * lds + c0 + (t & 15) * 4));
;     v4[i] = make_float4(w_[0], w_[1], w_[2], w_[3]);
;   }
; #pragma unroll
;   for (int i = 0; i < 4; ++i) {
;     const int kk = i * 16 + (t >> 4), cc = (t & 15) * 4;
;     const float sc = kscale ? kscale[k0 + kk] : 1.f;
;     tile[kk * 65 + cc + 0] = v4[i].x * sc; tile[kk * 65 + cc + 1] = v4[i].y * sc;
;     tile[kk * 65 + cc + 2] = v4[i].z * sc; tile[kk * 65 + cc + 3] = v4[i].w * sc;
;   }
;   __syncthreads();
; #pragma unroll
;   for (int i = 0; i < 16; ++i) {
;     const int cc = i * 4 + (t >> 6), kk = t & 63;
;     int row;
;     if (mode == 0) row = rbase + cc;
;     else { const int f = c0 + cc; row = (((f >> 4) * 2 + which) << 4) + (f & 15); }
;     dst[(size_t)row * Kd + k0 + kk] = f2bf(tile[kk * 65 + cc]);
; __device__ __forceinline__ void conv_item(const Params& p, int it, unsigned char* smem) {
;     ...
;   if (r < 4096) {
;     const int which = r >> 11, r2 = r & 2047, e = r2 >> 7, r3 = r2 & 127, ct = r3 >> 4, kt = r3 & 15;
;     const float* src = (which ? p.w_up : p.w_gate) + (size_t)(l * 16 + e) * 1024 * 512;
;     convT_tile(src, 512, kt * 64, ct * 64, p.WguT + (size_t)(l * 16 + e) * 1024 * 1024, 1024, 0, 1, which, smem);
;     return;
.LBB0_32:
	s_andn2_b64 vcc, exec, s[0:1]
	s_cbranch_vccnz .LBB0_34
	s_add_i32 s0, s35, 0xfffffdc0
	s_lshr_b32 s7, s0, 11
	s_bfe_u32 s4, s0, 0x40007
	s_cmpk_lt_u32 s0, 0x800
	s_cselect_b32 s0, s29, 0x98
	s_add_u32 s0, s10, s0
	s_addc_u32 s1, s11, 0
	v_mov_b64_e32 v[2:3], s[0:1]
	global_load_dwordx2 v[4:5], v[2:3], off
	s_lshl_b32 s0, s6, 4
	s_lshl_b32 s1, s6, 8
	s_or_b32 s0, s4, s0
	s_sub_i32 s4, s21, s1
	v_mov_b64_e32 v[2:3], s[10:11]
	v_mov_b32_e32 v6, v187
	s_ashr_i32 s1, s0, 31
	s_addk_i32 s4, 0xf700
	s_and_b32 s13, s15, 0x3c0
	global_load_dwordx2 v[2:3], v[2:3], off offset:224
	s_lshl_b64 s[0:1], s[0:1], 21
	s_and_b32 s12, s4, 0x1c0
	v_ashrrev_i32_e32 v8, 4, v6
	v_lshlrev_b32_e32 v7, 4, v6
	v_ashrrev_i32_e32 v24, 6, v6
	v_and_b32_e32 v26, 63, v6
	v_add_u32_e32 v6, s13, v8
	s_lshl_b32 s4, s12, 2
	v_and_b32_e32 v18, 0xf0, v7
	v_ashrrev_i32_e32 v7, 31, v6
	v_lshlrev_b64 v[6:7], 11, v[6:7]
	v_lshlrev_b32_e32 v9, 2, v24
	v_add_u32_e32 v10, 4, v24
	v_add_u32_e32 v11, 8, v24
	v_add_u32_e32 v12, 12, v24
	v_add_u32_e32 v13, 20, v24
	v_mad_u64_u32 v[16:17], s[36:37], v8, s28, v[18:19]
	v_mad_u32_u24 v47, v26, s28, v9
	v_add_u32_e32 v34, s12, v10
	v_and_b32_e32 v35, 15, v10
	v_add_u32_e32 v36, s12, v11
	v_and_b32_e32 v37, 15, v11
	v_add_u32_e32 v38, s12, v12
	v_and_b32_e32 v39, 15, v12
	v_add_u32_e32 v41, s12, v13
	v_and_b32_e32 v42, 15, v13
	v_add_u32_e32 v29, s12, v24
	v_add_u32_e32 v32, 24, v24
	v_add_u32_e32 v33, 28, v24
	v_lshrrev_b32_e32 v17, 3, v29
	v_add_u32_e32 v40, 16, v29
	v_add_u32_e32 v43, s12, v32
	v_and_b32_e32 v17, 0xffffffe, v17
	v_and_b32_e32 v46, 15, v24
	v_add_u32_e32 v17, s7, v17
	v_add_u32_e32 v48, 0x1040, v16
	v_add_u32_e32 v49, 0x1048, v16
	v_add_u32_e32 v50, 0x2080, v16
	v_add_u32_e32 v51, 0x2088, v16
	v_add_u32_e32 v52, 0x30c0, v16
	v_add_u32_e32 v53, 0x30c8, v16
	s_waitcnt vmcnt(0) lgkmcnt(0)
	v_lshl_add_u64 v[4:5], v[4:5], 0, s[0:1]
	v_lshl_add_u64 v[4:5], v[4:5], 0, s[4:5]
	v_lshl_add_u64 v[4:5], v[4:5], 0, v[18:19]
	v_lshl_add_u64 v[20:21], v[4:5], 0, v[6:7]
	v_add_co_u32_e32 v22, vcc, s30, v20
	v_and_b32_e32 v18, 15, v32
	s_nop 0
	v_addc_co_u32_e32 v23, vcc, 0, v21, vcc
	v_add_co_u32_e32 v30, vcc, s25, v20
	v_lshrrev_b32_e32 v32, 3, v34
	s_nop 0
	v_addc_co_u32_e32 v31, vcc, 0, v21, vcc
	global_load_dwordx4 v[4:7], v[20:21], off nt
	global_load_dwordx4 v[8:11], v[22:23], off nt
	global_load_dwordx4 v[12:15], v[30:31], off nt
	v_add_co_u32_e32 v20, vcc, s31, v20
	v_add_u32_e32 v30, s12, v33
	s_nop 0
	v_addc_co_u32_e32 v21, vcc, 0, v21, vcc
	global_load_dwordx4 v[20:23], v[20:21], off nt
	v_add_u32_e32 v31, 32, v29
	v_lshrrev_b32_e32 v34, 3, v36
	v_lshrrev_b32_e32 v36, 3, v38
	v_lshrrev_b32_e32 v38, 3, v40
	v_lshrrev_b32_e32 v40, 3, v41
	v_lshrrev_b32_e32 v41, 3, v43
	v_lshrrev_b32_e32 v30, 3, v30
	v_lshrrev_b32_e32 v31, 3, v31
	v_and_b32_e32 v32, 0xffffffe, v32
	v_and_b32_e32 v34, 0xffffffe, v34
	v_and_b32_e32 v36, 0xffffffe, v36
	v_and_b32_e32 v38, 0xffffffe, v38
	v_and_b32_e32 v40, 0xffffffe, v40
	v_and_b32_e32 v41, 0xffffffe, v41
	v_and_b32_e32 v43, 0xffffffe, v30
	v_and_b32_e32 v33, 15, v33
	v_and_b32_e32 v31, 0xffffffe, v31
	v_lshl_or_b32 v30, v17, 4, v46
	v_add_u32_e32 v17, s7, v32
	v_add_u32_e32 v34, s7, v34
	v_add_u32_e32 v36, s7, v36
	v_add_u32_e32 v38, s7, v38
	v_add_u32_e32 v40, s7, v40
	v_add_u32_e32 v41, s7, v41
	v_add_u32_e32 v43, s7, v43
	v_lshl_add_u64 v[2:3], v[2:3], 0, s[0:1]
	s_lshl_b32 s4, s13, 1
	v_add_u32_e32 v54, s7, v31
	v_ashrrev_i32_e32 v31, 31, v30
	v_lshl_or_b32 v32, v17, 4, v35
	v_lshl_or_b32 v34, v34, 4, v37
	v_lshl_or_b32 v36, v36, 4, v39
	v_lshl_or_b32 v38, v38, 4, v46
	v_lshl_or_b32 v40, v40, 4, v42
	v_lshl_or_b32 v42, v41, 4, v18
	v_lshl_or_b32 v44, v43, 4, v33
	v_lshl_add_u64 v[2:3], v[2:3], 0, s[4:5]
	v_lshlrev_b32_e32 v18, 1, v26
	v_lshlrev_b64 v[30:31], 11, v[30:31]
	v_ashrrev_i32_e32 v33, 31, v32
	v_ashrrev_i32_e32 v35, 31, v34
	v_ashrrev_i32_e32 v37, 31, v36
	v_ashrrev_i32_e32 v39, 31, v38
	v_ashrrev_i32_e32 v41, 31, v40
	v_ashrrev_i32_e32 v43, 31, v42
	v_ashrrev_i32_e32 v45, 31, v44
	v_lshl_add_u64 v[2:3], v[2:3], 0, v[18:19]
	v_lshlrev_b64 v[32:33], 11, v[32:33]
	v_lshlrev_b64 v[34:35], 11, v[34:35]
	v_lshlrev_b64 v[36:37], 11, v[36:37]
	v_lshlrev_b64 v[38:39], 11, v[38:39]
	v_lshlrev_b64 v[40:41], 11, v[40:41]
	v_lshlrev_b64 v[42:43], 11, v[42:43]
	v_lshlrev_b64 v[44:45], 11, v[44:45]
	v_lshl_add_u64 v[30:31], v[2:3], 0, v[30:31]
	v_lshl_add_u64 v[32:33], v[2:3], 0, v[32:33]
	v_lshl_add_u64 v[34:35], v[2:3], 0, v[34:35]
	v_lshl_add_u64 v[36:37], v[2:3], 0, v[36:37]
	v_lshl_add_u64 v[38:39], v[2:3], 0, v[38:39]
	v_lshl_add_u64 v[40:41], v[2:3], 0, v[40:41]
	v_lshl_add_u64 v[42:43], v[2:3], 0, v[42:43]
	v_lshl_add_u64 v[44:45], v[2:3], 0, v[44:45]
	s_waitcnt vmcnt(0) lgkmcnt(0)
	ds_write2_b32 v16, v4, v5 offset1:1
	ds_write2_b32 v16, v6, v7 offset0:2 offset1:3
	ds_write2_b32 v48, v8, v9 offset1:1
	ds_write2_b32 v49, v10, v11 offset1:1
	ds_write2_b32 v50, v12, v13 offset1:1
	ds_write2_b32 v51, v14, v15 offset1:1
	ds_write2_b32 v52, v20, v21 offset1:1
	ds_write2_b32 v53, v22, v23 offset1:1
	s_waitcnt lgkmcnt(0)
	s_barrier
; __device__ __forceinline__ u16 f2bf(float f) { return (u16)(pack2(f, 0.f) & 0xffffu); }
; __device__ __forceinline__ void convT_tile(const float* __restrict__ src, int lds, int k0, int c0, u16* __restrict__ dst, int Kd,
;                                            int rbase, int mode, int which, unsigned char* smem, const float* __restrict__ kscale = nullptr) {
;     ...
; #pragma unroll
;   for (int i = 0; i < 16; ++i) {
;     const int cc = i * 4 + (t >> 6), kk = t & 63;
;     int row;
;     if (mode == 0) row = rbase + cc;
;     else { const int f = c0 + cc; row = (((f >> 4) * 2 + which) << 4) + (f & 15); }
;     dst[(size_t)row * Kd + k0 + kk] = f2bf(tile[kk * 65 + cc]);
;   }
;   __syncthreads();
	ds_read2_b32 v[4:5], v47 offset1:4
	ds_read2_b32 v[6:7], v47 offset0:8 offset1:12
	ds_read2_b32 v[8:9], v47 offset0:16 offset1:20
	ds_read2_b32 v[10:11], v47 offset0:24 offset1:28
	ds_read2_b32 v[12:13], v47 offset0:32 offset1:36
	s_waitcnt lgkmcnt(4)
	v_cvt_pk_bf16_f32 v4, v4, s0
	v_cvt_pk_bf16_f32 v5, v5, s0
	s_waitcnt lgkmcnt(3)
	v_cvt_pk_bf16_f32 v6, v6, s0
	v_cvt_pk_bf16_f32 v7, v7, s0
	s_waitcnt lgkmcnt(2)
	v_cvt_pk_bf16_f32 v8, v8, s0
	v_cvt_pk_bf16_f32 v9, v9, s0
	s_waitcnt lgkmcnt(1)
	v_cvt_pk_bf16_f32 v10, v10, s0
	v_cvt_pk_bf16_f32 v11, v11, s0
	global_store_short v[30:31], v4, off
	global_store_short v[32:33], v5, off
	global_store_short v[34:35], v6, off
	global_store_short v[36:37], v7, off
	global_store_short v[38:39], v8, off
	global_store_short v[40:41], v9, off
	global_store_short v[42:43], v10, off
	global_store_short v[44:45], v11, off
	v_lshl_or_b32 v4, v54, 4, v46
	v_ashrrev_i32_e32 v5, 31, v4
	v_lshlrev_b64 v[4:5], 11, v[4:5]
	s_waitcnt lgkmcnt(0)
	v_cvt_pk_bf16_f32 v6, v12, s0
	v_lshl_add_u64 v[4:5], v[2:3], 0, v[4:5]
	global_store_short v[4:5], v6, off
	v_add_u32_e32 v4, 36, v24
	v_add_u32_e32 v5, s12, v4
	v_lshrrev_b32_e32 v5, 3, v5
	v_and_b32_e32 v5, 0xffffffe, v5
	v_add_u32_e32 v5, s7, v5
	v_and_b32_e32 v4, 15, v4
	v_lshl_or_b32 v4, v5, 4, v4
	v_ashrrev_i32_e32 v5, 31, v4
	v_lshlrev_b64 v[4:5], 11, v[4:5]
	v_cvt_pk_bf16_f32 v6, v13, s0
	v_lshl_add_u64 v[4:5], v[2:3], 0, v[4:5]
	global_store_short v[4:5], v6, off
	v_add_u32_e32 v6, 40, v24
	v_add_u32_e32 v4, s12, v6
	v_lshrrev_b32_e32 v7, 3, v4
	ds_read2_b32 v[4:5], v47 offset0:40 offset1:44
	v_and_b32_e32 v7, 0xffffffe, v7
	v_add_u32_e32 v7, s7, v7
	v_and_b32_e32 v6, 15, v6
	v_lshl_or_b32 v6, v7, 4, v6
	v_ashrrev_i32_e32 v7, 31, v6
	v_lshlrev_b64 v[6:7], 11, v[6:7]
	s_waitcnt lgkmcnt(0)
	v_cvt_pk_bf16_f32 v4, v4, s0
	v_lshl_add_u64 v[6:7], v[2:3], 0, v[6:7]
	global_store_short v[6:7], v4, off
	v_add_u32_e32 v4, 44, v24
	v_add_u32_e32 v6, s12, v4
	v_lshrrev_b32_e32 v6, 3, v6
	v_and_b32_e32 v6, 0xffffffe, v6
	v_add_u32_e32 v6, s7, v6
	v_and_b32_e32 v4, 15, v4
	v_lshl_or_b32 v4, v6, 4, v4
	v_cvt_pk_bf16_f32 v6, v5, s0
	v_ashrrev_i32_e32 v5, 31, v4
	v_lshlrev_b64 v[4:5], 11, v[4:5]
	v_lshl_add_u64 v[4:5], v[2:3], 0, v[4:5]
	global_store_short v[4:5], v6, off
	v_add_u32_e32 v6, 48, v29
	v_lshrrev_b32_e32 v6, 3, v6
	ds_read2_b32 v[4:5], v47 offset0:48 offset1:52
	v_and_b32_e32 v6, 0xffffffe, v6
	v_add_u32_e32 v6, s7, v6
	v_lshl_or_b32 v6, v6, 4, v46
	v_ashrrev_i32_e32 v7, 31, v6
	v_lshlrev_b64 v[6:7], 11, v[6:7]
	s_waitcnt lgkmcnt(0)
	v_cvt_pk_bf16_f32 v4, v4, s0
	v_lshl_add_u64 v[6:7], v[2:3], 0, v[6:7]
	global_store_short v[6:7], v4, off
	v_add_u32_e32 v4, 52, v24
	v_add_u32_e32 v6, s12, v4
	v_lshrrev_b32_e32 v6, 3, v6
	v_and_b32_e32 v6, 0xffffffe, v6
	v_add_u32_e32 v6, s7, v6
	v_and_b32_e32 v4, 15, v4
	v_lshl_or_b32 v4, v6, 4, v4
	v_cvt_pk_bf16_f32 v6, v5, s0
	v_ashrrev_i32_e32 v5, 31, v4
	v_lshlrev_b64 v[4:5], 11, v[4:5]
	v_lshl_add_u64 v[4:5], v[2:3], 0, v[4:5]
	global_store_short v[4:5], v6, off
	v_add_u32_e32 v6, 56, v24
	v_add_u32_e32 v4, s12, v6
	v_lshrrev_b32_e32 v7, 3, v4
	ds_read2_b32 v[4:5], v47 offset0:56 offset1:60
	v_and_b32_e32 v7, 0xffffffe, v7
	v_add_u32_e32 v7, s7, v7
	v_and_b32_e32 v6, 15, v6
	v_lshl_or_b32 v6, v7, 4, v6
	v_ashrrev_i32_e32 v7, 31, v6
	v_lshlrev_b64 v[6:7], 11, v[6:7]
	s_waitcnt lgkmcnt(0)
	v_cvt_pk_bf16_f32 v4, v4, s0
	v_lshl_add_u64 v[6:7], v[2:3], 0, v[6:7]
	global_store_short v[6:7], v4, off
	v_add_u32_e32 v4, 60, v24
	v_add_u32_e32 v6, s12, v4
	v_lshrrev_b32_e32 v6, 3, v6
	v_and_b32_e32 v6, 0xffffffe, v6
	v_add_u32_e32 v6, s7, v6
	v_and_b32_e32 v4, 15, v4
	v_lshl_or_b32 v4, v6, 4, v4
	v_cvt_pk_bf16_f32 v6, v5, s0
	v_ashrrev_i32_e32 v5, 31, v4
	v_lshlrev_b64 v[4:5], 11, v[4:5]
	v_lshl_add_u64 v[2:3], v[2:3], 0, v[4:5]
	global_store_short v[2:3], v6, off
	s_waitcnt lgkmcnt(0)
	s_barrier

; __device__ __forceinline__ u16 f2bf(float f) { return (u16)(pack2(f, 0.f) & 0xffffu); }
; __device__ __forceinline__ int tid_() { int t = threadIdx.x; asm volatile("" : "+v"(t)); return t; }
; __device__ __forceinline__ void convT_tile(const float* __restrict__ src, int lds, int k0, int c0, u16* __restrict__ dst, int Kd,
;                                            int rbase, int mode, int which, unsigned char* smem, const float* __restrict__ kscale = nullptr) {
;   float* tile = (float*)smem;
;   const int t = tid_();
;   float4 v4[4];
; #pragma unroll
;   for (int i = 0; i < 4; ++i) {
;     const f32x4 w_ = __builtin_nontemporal_load((const f32x4*)(src + (size_t)(k0 + i * 16 + (t >> 4)) * lds + c0 + (t & 15) * 4));
;     v4[i] = make_float4(w_[0], w_[1], w_[2], w_[3]);
;   }
; #pragma unroll
;   for (int i = 0; i < 4; ++i) {
;     const int kk = i * 16 + (t >> 4), cc = (t & 15) * 4;
;     const float sc = kscale ? kscale[k0 + kk] : 1.f;
;     tile[kk * 65 + cc + 0] = v4[i].x * sc; tile[kk * 65 + cc + 1] = v4[i].y * sc;
;     tile[kk * 65 + cc + 2] = v4[i].z * sc; tile[kk * 65 + cc + 3] = v4[i].w * sc;
;   }
;   __syncthreads();
; #pragma unroll
;   for (int i = 0; i < 16; ++i) {
;     const int cc = i * 4 + (t >> 6), kk = t & 63;
;     int row;
;     if (mode == 0) row = rbase + cc;
;     else { const int f = c0 + cc; row = (((f >> 4) * 2 + which) << 4) + (f & 15); }
;     dst[(size_t)row * Kd + k0 + kk] = f2bf(tile[kk * 65 + cc]);
;   }
;   __syncthreads();
; }
; __device__ __forceinline__ void conv_item(const Params& p, int it, unsigned char* smem) {
;     ...
;   if (r < 256) {
;     const int ct = r >> 4, kt = r & 15;
;     convT_tile(p.w_out + (size_t)l * 1024 * 1024, 1024, kt * 64, ct * 64, p.WoutT + (size_t)l * 1024 * 1024, 1024, ct * 64, 0, 0, smem);
;     return;
;   }
.LBB0_35:
	s_andn2_b64 vcc, exec, s[0:1]
	s_cbranch_vccnz .LBB0_37
	v_mov_b64_e32 v[2:3], s[10:11]
	global_load_dwordx2 v[4:5], v[2:3], off offset:128
	global_load_dwordx2 v[20:21], v[2:3], off offset:216
	s_mul_i32 s0, s6, 0xffff9700
	s_ashr_i32 s7, s6, 31
	v_mov_b32_e32 v6, v187
	s_add_i32 s4, s21, s0
	s_and_b32 s38, s15, 0x3c0
	s_lshl_b64 s[36:37], s[6:7], 22
	s_and_b32 s4, s4, 0xfc0
	v_ashrrev_i32_e32 v7, 4, v6
	v_lshlrev_b32_e32 v3, 4, v6
	s_addk_i32 s4, 0xfb00
	v_add_u32_e32 v2, s38, v7
	v_and_b32_e32 v18, 0xf0, v3
	v_ashrrev_i32_e32 v3, 31, v2
	v_lshlrev_b64 v[2:3], 12, v[2:3]
	v_ashrrev_i32_e32 v8, 6, v6
	s_lshl_b32 s0, s38, 1
	v_and_b32_e32 v24, 63, v6
	v_lshlrev_b32_e32 v6, 2, v8
	v_mad_u64_u32 v[22:23], s[38:39], v7, s28, v[18:19]
	v_add_u32_e32 v30, s4, v8
	v_mad_u32_u24 v23, v24, s28, v6
	s_lshl_b64 s[12:13], s[6:7], 21
	v_add_u32_e32 v26, 0x1040, v22
	v_add_u32_e32 v29, 0x1048, v22
	v_add_u32_e32 v62, 0x2080, v22
	v_add_u32_e32 v63, 0x2088, v22
	v_add_u32_e32 v64, 0x30c0, v22
	v_add_u32_e32 v65, 0x30c8, v22
	s_mov_b32 s1, s5
	v_ashrrev_i32_e32 v31, 31, v30
	v_add_u32_e32 v34, 8, v30
	v_add_u32_e32 v36, 12, v30
	v_add_u32_e32 v38, 16, v30
	v_add_u32_e32 v40, 20, v30
	v_add_u32_e32 v42, 24, v30
	v_add_u32_e32 v44, 28, v30
	v_add_u32_e32 v46, 32, v30
	v_add_u32_e32 v48, 36, v30
	v_add_u32_e32 v50, 40, v30
	v_add_u32_e32 v52, 44, v30
	v_add_u32_e32 v54, 48, v30
	v_add_u32_e32 v56, 52, v30
	v_add_u32_e32 v58, 56, v30
	v_add_u32_e32 v60, 60, v30
	v_ashrrev_i32_e32 v35, 31, v34
	v_ashrrev_i32_e32 v37, 31, v36
	v_ashrrev_i32_e32 v39, 31, v38
	v_ashrrev_i32_e32 v41, 31, v40
	v_ashrrev_i32_e32 v43, 31, v42
	v_ashrrev_i32_e32 v45, 31, v44
	v_ashrrev_i32_e32 v47, 31, v46
	v_ashrrev_i32_e32 v49, 31, v48
	v_ashrrev_i32_e32 v51, 31, v50
	v_ashrrev_i32_e32 v53, 31, v52
	v_ashrrev_i32_e32 v55, 31, v54
	v_ashrrev_i32_e32 v57, 31, v56
	v_ashrrev_i32_e32 v59, 31, v58
	v_ashrrev_i32_e32 v61, 31, v60
	v_lshlrev_b64 v[34:35], 11, v[34:35]
	v_lshlrev_b64 v[36:37], 11, v[36:37]
	v_lshlrev_b64 v[38:39], 11, v[38:39]
	v_lshlrev_b64 v[40:41], 11, v[40:41]
	v_lshlrev_b64 v[42:43], 11, v[42:43]
	v_lshlrev_b64 v[44:45], 11, v[44:45]
	v_lshlrev_b64 v[46:47], 11, v[46:47]
	v_lshlrev_b64 v[48:49], 11, v[48:49]
	v_lshlrev_b64 v[50:51], 11, v[50:51]
	v_lshlrev_b64 v[52:53], 11, v[52:53]
	v_lshlrev_b64 v[54:55], 11, v[54:55]
	v_lshlrev_b64 v[56:57], 11, v[56:57]
	v_lshlrev_b64 v[58:59], 11, v[58:59]
	v_lshlrev_b64 v[60:61], 11, v[60:61]
	s_waitcnt vmcnt(0) lgkmcnt(0)
	v_lshl_add_u64 v[4:5], v[4:5], 0, s[36:37]
	v_lshl_add_u64 v[4:5], s[4:5], 2, v[4:5]
	v_lshl_add_u64 v[4:5], v[4:5], 0, v[18:19]
	v_lshl_add_u64 v[14:15], v[4:5], 0, v[2:3]
	v_add_co_u32_e32 v16, vcc, s25, v14
	v_lshl_add_u64 v[20:21], v[20:21], 0, s[12:13]
	s_nop 0
	v_addc_co_u32_e32 v17, vcc, 0, v15, vcc
	v_add_co_u32_e32 v32, vcc, s26, v14
	v_lshl_add_u64 v[20:21], v[20:21], 0, s[0:1]
	s_nop 0
	v_addc_co_u32_e32 v33, vcc, 0, v15, vcc
	global_load_dwordx4 v[2:5], v[14:15], off nt
	global_load_dwordx4 v[6:9], v[16:17], off nt
	global_load_dwordx4 v[10:13], v[32:33], off nt
	v_add_co_u32_e32 v14, vcc, s27, v14
	v_add_u32_e32 v32, 4, v30
	s_nop 0
	v_addc_co_u32_e32 v15, vcc, 0, v15, vcc
	global_load_dwordx4 v[14:17], v[14:15], off nt
	v_lshlrev_b32_e32 v18, 1, v24
	v_lshlrev_b64 v[30:31], 11, v[30:31]
	v_ashrrev_i32_e32 v33, 31, v32
	v_lshl_add_u64 v[20:21], v[20:21], 0, v[18:19]
	v_lshlrev_b64 v[32:33], 11, v[32:33]
	v_lshl_add_u64 v[30:31], v[20:21], 0, v[30:31]
	v_lshl_add_u64 v[32:33], v[20:21], 0, v[32:33]
	v_lshl_add_u64 v[34:35], v[20:21], 0, v[34:35]
	v_lshl_add_u64 v[36:37], v[20:21], 0, v[36:37]
	v_lshl_add_u64 v[38:39], v[20:21], 0, v[38:39]
	v_lshl_add_u64 v[40:41], v[20:21], 0, v[40:41]
	v_lshl_add_u64 v[42:43], v[20:21], 0, v[42:43]
	v_lshl_add_u64 v[44:45], v[20:21], 0, v[44:45]
	v_lshl_add_u64 v[46:47], v[20:21], 0, v[46:47]
	v_lshl_add_u64 v[48:49], v[20:21], 0, v[48:49]
	v_lshl_add_u64 v[50:51], v[20:21], 0, v[50:51]
	v_lshl_add_u64 v[52:53], v[20:21], 0, v[52:53]
	v_lshl_add_u64 v[54:55], v[20:21], 0, v[54:55]
	v_lshl_add_u64 v[56:57], v[20:21], 0, v[56:57]
	v_lshl_add_u64 v[58:59], v[20:21], 0, v[58:59]
	v_lshl_add_u64 v[20:21], v[20:21], 0, v[60:61]
	s_waitcnt vmcnt(0) lgkmcnt(0)
	ds_write2_b32 v22, v2, v3 offset1:1
	ds_write2_b32 v22, v4, v5 offset0:2 offset1:3
	ds_write2_b32 v26, v6, v7 offset1:1
	ds_write2_b32 v29, v8, v9 offset1:1
	ds_write2_b32 v62, v10, v11 offset1:1
	ds_write2_b32 v63, v12, v13 offset1:1
	ds_write2_b32 v64, v14, v15 offset1:1
	ds_write2_b32 v65, v16, v17 offset1:1
	s_waitcnt lgkmcnt(0)
	s_barrier
	ds_read2_b32 v[2:3], v23 offset1:4
	ds_read2_b32 v[4:5], v23 offset0:8 offset1:12
	ds_read2_b32 v[6:7], v23 offset0:16 offset1:20
	ds_read2_b32 v[8:9], v23 offset0:24 offset1:28
	ds_read2_b32 v[10:11], v23 offset0:32 offset1:36
	ds_read2_b32 v[12:13], v23 offset0:40 offset1:44
	ds_read2_b32 v[14:15], v23 offset0:48 offset1:52
	ds_read2_b32 v[16:17], v23 offset0:56 offset1:60
	s_waitcnt lgkmcnt(7)
	v_cvt_pk_bf16_f32 v2, v2, s0
	v_cvt_pk_bf16_f32 v3, v3, s0
	s_waitcnt lgkmcnt(6)
	v_cvt_pk_bf16_f32 v4, v4, s0
	v_cvt_pk_bf16_f32 v5, v5, s0
	s_waitcnt lgkmcnt(5)
	v_cvt_pk_bf16_f32 v6, v6, s0
	v_cvt_pk_bf16_f32 v7, v7, s0
	s_waitcnt lgkmcnt(4)
	v_cvt_pk_bf16_f32 v8, v8, s0
	v_cvt_pk_bf16_f32 v9, v9, s0
	s_waitcnt lgkmcnt(3)
	v_cvt_pk_bf16_f32 v10, v10, s0
	v_cvt_pk_bf16_f32 v11, v11, s0
	s_waitcnt lgkmcnt(2)
	v_cvt_pk_bf16_f32 v12, v12, s0
	v_cvt_pk_bf16_f32 v13, v13, s0
	s_waitcnt lgkmcnt(1)
	v_cvt_pk_bf16_f32 v14, v14, s0
	v_cvt_pk_bf16_f32 v15, v15, s0
	s_waitcnt lgkmcnt(0)
	v_cvt_pk_bf16_f32 v16, v16, s0
	v_cvt_pk_bf16_f32 v17, v17, s0
	global_store_short v[30:31], v2, off
	global_store_short v[32:33], v3, off
	global_store_short v[34:35], v4, off
	global_store_short v[36:37], v5, off
	global_store_short v[38:39], v6, off
	global_store_short v[40:41], v7, off
	global_store_short v[42:43], v8, off
	global_store_short v[44:45], v9, off
	global_store_short v[46:47], v10, off
	global_store_short v[48:49], v11, off
	global_store_short v[50:51], v12, off
	global_store_short v[52:53], v13, off
	global_store_short v[54:55], v14, off
	global_store_short v[56:57], v15, off
	global_store_short v[58:59], v16, off
	global_store_short v[20:21], v17, off
	s_waitcnt lgkmcnt(0)
	s_barrier

; __device__ __forceinline__ int tid_() { int t = threadIdx.x; asm volatile("" : "+v"(t)); return t; }
; __device__ __forceinline__ void convT_tile(const float* __restrict__ src, int lds, int k0, int c0, u16* __restrict__ dst, int Kd,
;                                            int rbase, int mode, int which, unsigned char* smem, const float* __restrict__ kscale = nullptr) {
;   float* tile = (float*)smem;
;   const int t = tid_();
;   float4 v4[4];
; #pragma unroll
;   for (int i = 0; i < 4; ++i) {
;     const f32x4 w_ = __builtin_nontemporal_load((const f32x4*)(src + (size_t)(k0 + i * 16 + (t >> 4)) * lds + c0 + (t & 15) * 4));
;     v4[i] = make_float4(w_[0], w_[1], w_[2], w_[3]);
;   }
; #pragma unroll
;   for (int i = 0; i < 4; ++i) {
;     const int kk = i * 16 + (t >> 4), cc = (t & 15) * 4;
;     const float sc = kscale ? kscale[k0 + kk] : 1.f;
;     tile[kk * 65 + cc + 0] = v4[i].x * sc; tile[kk * 65 + cc + 1] = v4[i].y * sc;
;     tile[kk * 65 + cc + 2] = v4[i].z * sc; tile[kk * 65 + cc + 3] = v4[i].w * sc;
;   }
; __device__ __forceinline__ void conv_item(const Params& p, int it, unsigned char* smem) {
;     ...
;   if (r < 32) {
;     const int ct = r >> 1, kt = r & 1;
;     convT_tile(p.w_ukv + (size_t)l * 128 * 1024, 1024, kt * 64, ct * 64, p.WukvT + (size_t)l * 1024 * 128, 128, ct * 64, 0, 0, smem, p.kv_lora_norm + l * 128);
;     return;
;   }
.LBB0_38:
	s_andn2_b64 vcc, exec, s[0:1]
	s_cbranch_vccnz .LBB0_48
	v_mov_b64_e32 v[2:3], s[10:11]
	global_load_dwordx4 v[32:35], v[2:3], off offset:96
	global_load_dwordx2 v[20:21], v[2:3], off offset:208
	s_lshl_b32 s0, s6, 7
	s_lshl_b32 s1, s6, 11
	s_ashr_i32 s7, s6, 31
	v_mov_b32_e32 v29, v187
	s_sub_i32 s4, s15, s0
	s_sub_i32 s1, s19, s1
	s_lshl_b64 s[36:37], s[6:7], 19
	s_and_b32 s12, s4, 64
	s_and_b32 s1, s1, 0x3fc0
	v_ashrrev_i32_e32 v30, 4, v29
	v_lshlrev_b32_e32 v2, 2, v29
	s_add_i32 s4, s1, 0xffffdc00
	v_add_u32_e32 v22, s12, v30
	v_and_b32_e32 v2, 60, v2
	v_lshlrev_b32_e32 v18, 2, v2
	v_ashrrev_i32_e32 v23, 31, v22
	v_lshlrev_b64 v[2:3], 12, v[22:23]
	s_ashr_i32 s1, s0, 31
	v_mov_b32_e32 v24, 1.0
	v_mov_b32_e32 v26, 1.0
	s_waitcnt vmcnt(0) lgkmcnt(0)
	v_lshl_add_u64 v[4:5], v[34:35], 0, s[36:37]
	v_lshl_add_u64 v[4:5], s[4:5], 2, v[4:5]
	v_lshl_add_u64 v[4:5], v[4:5], 0, v[18:19]
	v_lshl_add_u64 v[2:3], v[4:5], 0, v[2:3]
	v_add_co_u32_e32 v4, vcc, s25, v2
	s_nop 1
	v_addc_co_u32_e32 v5, vcc, 0, v3, vcc
	v_add_co_u32_e32 v34, vcc, 0x20000, v2
	global_load_dwordx4 v[14:17], v[2:3], off nt
	global_load_dwordx4 v[10:13], v[4:5], off nt
	v_addc_co_u32_e32 v35, vcc, 0, v3, vcc
	v_add_co_u32_e32 v36, vcc, 0x30000, v2
	s_nop 1
	v_addc_co_u32_e32 v37, vcc, 0, v3, vcc
	global_load_dwordx4 v[6:9], v[34:35], off nt
	global_load_dwordx4 v[2:5], v[36:37], off nt
	v_lshl_add_u64 v[34:35], s[0:1], 2, v[32:33]
	v_cmp_ne_u64_e32 vcc, 0, v[32:33]
	v_lshl_add_u64 v[22:23], v[22:23], 2, v[34:35]
	s_and_saveexec_b64 s[0:1], vcc
	s_cbranch_execz .LBB0_41
	global_load_dword v26, v[22:23], off
.LBB0_41:
	s_or_b64 exec, exec, s[0:1]
	s_waitcnt vmcnt(0) lgkmcnt(0)
	v_pk_mul_f32 v[32:33], v[14:15], v[26:27] op_sel_hi:[1,0]
	v_mul_lo_u32 v14, v30, s28
	v_add_u32_e32 v14, v18, v14
	v_pk_mul_f32 v[16:17], v[16:17], v[26:27] op_sel_hi:[1,0]
	ds_write2_b32 v14, v32, v33 offset1:1
	ds_write2_b32 v14, v16, v17 offset0:2 offset1:3
	s_and_saveexec_b64 s[0:1], vcc
	s_cbranch_execz .LBB0_43
	global_load_dword v24, v[22:23], off offset:64
.LBB0_43:
	s_or_b64 exec, exec, s[0:1]
	s_waitcnt vmcnt(0) lgkmcnt(0)
	v_pk_mul_f32 v[10:11], v[10:11], v[24:25] op_sel_hi:[1,0]
	v_add_u32_e32 v15, 0x1040, v14
	ds_write2_b32 v15, v10, v11 offset1:1
	v_pk_mul_f32 v[10:11], v[12:13], v[24:25] op_sel_hi:[1,0]
	v_add_u32_e32 v12, 0x1048, v14
	ds_write2_b32 v12, v10, v11 offset1:1
	v_mov_b32_e32 v10, 1.0
	v_mov_b32_e32 v12, 1.0
	s_and_saveexec_b64 s[0:1], vcc
	s_cbranch_execz .LBB0_45
	global_load_dword v12, v[22:23], off offset:128
.LBB0_45:
	s_or_b64 exec, exec, s[0:1]
	s_waitcnt vmcnt(0) lgkmcnt(0)
	v_pk_mul_f32 v[6:7], v[6:7], v[12:13] op_sel_hi:[1,0]
	v_add_u32_e32 v11, 0x2080, v14
	ds_write2_b32 v11, v6, v7 offset1:1
	v_pk_mul_f32 v[6:7], v[8:9], v[12:13] op_sel_hi:[1,0]
	v_add_u32_e32 v8, 0x2088, v14
	ds_write2_b32 v8, v6, v7 offset1:1
	s_and_saveexec_b64 s[0:1], vcc
	s_cbranch_execz .LBB0_47
	global_load_dword v10, v[22:23], off offset:192
; __device__ __forceinline__ u16 f2bf(float f) { return (u16)(pack2(f, 0.f) & 0xffffu); }
; __device__ __forceinline__ void convT_tile(const float* __restrict__ src, int lds, int k0, int c0, u16* __restrict__ dst, int Kd,
;                                            int rbase, int mode, int which, unsigned char* smem, const float* __restrict__ kscale = nullptr) {
;     ...
;   __syncthreads();
; #pragma unroll
;   for (int i = 0; i < 16; ++i) {
;     const int cc = i * 4 + (t >> 6), kk = t & 63;
;     int row;
;     if (mode == 0) row = rbase + cc;
;     else { const int f = c0 + cc; row = (((f >> 4) * 2 + which) << 4) + (f & 15); }
;     dst[(size_t)row * Kd + k0 + kk] = f2bf(tile[kk * 65 + cc]);
;   }
;   __syncthreads();
; }
.LBB0_47:
	s_or_b64 exec, exec, s[0:1]
	s_waitcnt vmcnt(0) lgkmcnt(0)
	v_pk_mul_f32 v[2:3], v[2:3], v[10:11] op_sel_hi:[1,0]
	v_add_u32_e32 v8, 0x30c0, v14
	ds_write2_b32 v8, v2, v3 offset1:1
	v_pk_mul_f32 v[2:3], v[4:5], v[10:11] op_sel_hi:[1,0]
	v_add_u32_e32 v4, 0x30c8, v14
	v_ashrrev_i32_e32 v8, 6, v29
	ds_write2_b32 v4, v2, v3 offset1:1
	v_and_b32_e32 v9, 63, v29
	v_lshlrev_b32_e32 v4, 2, v8
	v_mad_u32_u24 v14, v9, s28, v4
	s_lshl_b64 s[0:1], s[6:7], 18
	s_waitcnt lgkmcnt(0)
	s_barrier
	ds_read2_b32 v[4:5], v14 offset1:4
	v_lshl_add_u64 v[6:7], v[20:21], 0, s[0:1]
	s_lshl_b32 s0, s12, 1
	s_mov_b32 s1, s5
	v_lshl_add_u64 v[2:3], v[6:7], 0, s[0:1]
	v_add_u32_e32 v6, s4, v8
	v_lshlrev_b32_e32 v18, 1, v9
	v_ashrrev_i32_e32 v7, 31, v6
	v_lshl_add_u64 v[2:3], v[2:3], 0, v[18:19]
	v_lshlrev_b64 v[10:11], 8, v[6:7]
	s_waitcnt lgkmcnt(0)
	v_cvt_pk_bf16_f32 v4, v4, s0
	v_lshl_add_u64 v[10:11], v[2:3], 0, v[10:11]
	global_store_short v[10:11], v4, off
	v_add_u32_e32 v4, 4, v6
	v_cvt_pk_bf16_f32 v7, v5, s0
	v_ashrrev_i32_e32 v5, 31, v4
	ds_read2_b32 v[8:9], v14 offset0:8 offset1:12
	v_lshlrev_b64 v[4:5], 8, v[4:5]
	v_lshl_add_u64 v[4:5], v[2:3], 0, v[4:5]
	global_store_short v[4:5], v7, off
	v_add_u32_e32 v4, 8, v6
	v_ashrrev_i32_e32 v5, 31, v4
	v_lshlrev_b64 v[4:5], 8, v[4:5]
	s_waitcnt lgkmcnt(0)
	v_cvt_pk_bf16_f32 v7, v8, s0
	v_lshl_add_u64 v[4:5], v[2:3], 0, v[4:5]
	global_store_short v[4:5], v7, off
	v_add_u32_e32 v4, 12, v6
	v_ashrrev_i32_e32 v5, 31, v4
	v_cvt_pk_bf16_f32 v7, v9, s0
	ds_read2_b32 v[8:9], v14 offset0:16 offset1:20
	v_lshlrev_b64 v[4:5], 8, v[4:5]
	v_lshl_add_u64 v[4:5], v[2:3], 0, v[4:5]
	global_store_short v[4:5], v7, off
	v_add_u32_e32 v4, 16, v6
	v_ashrrev_i32_e32 v5, 31, v4
	v_lshlrev_b64 v[4:5], 8, v[4:5]
	s_waitcnt lgkmcnt(0)
	v_cvt_pk_bf16_f32 v7, v8, s0
	v_lshl_add_u64 v[4:5], v[2:3], 0, v[4:5]
	global_store_short v[4:5], v7, off
	v_add_u32_e32 v4, 20, v6
	v_ashrrev_i32_e32 v5, 31, v4
	v_cvt_pk_bf16_f32 v7, v9, s0
	ds_read2_b32 v[8:9], v14 offset0:24 offset1:28
	v_lshlrev_b64 v[4:5], 8, v[4:5]
	v_lshl_add_u64 v[4:5], v[2:3], 0, v[4:5]
	global_store_short v[4:5], v7, off
	v_add_u32_e32 v4, 24, v6
	v_ashrrev_i32_e32 v5, 31, v4
	v_lshlrev_b64 v[4:5], 8, v[4:5]
	s_waitcnt lgkmcnt(0)
	v_cvt_pk_bf16_f32 v7, v8, s0
	v_lshl_add_u64 v[4:5], v[2:3], 0, v[4:5]
	global_store_short v[4:5], v7, off
	v_add_u32_e32 v4, 28, v6
	v_ashrrev_i32_e32 v5, 31, v4
	v_cvt_pk_bf16_f32 v7, v9, s0
	ds_read2_b32 v[8:9], v14 offset0:32 offset1:36
	v_lshlrev_b64 v[4:5], 8, v[4:5]
	v_lshl_add_u64 v[4:5], v[2:3], 0, v[4:5]
	global_store_short v[4:5], v7, off
	v_add_u32_e32 v4, 32, v6
	v_ashrrev_i32_e32 v5, 31, v4
	v_lshlrev_b64 v[4:5], 8, v[4:5]
	s_waitcnt lgkmcnt(0)
	v_cvt_pk_bf16_f32 v7, v8, s0
	v_lshl_add_u64 v[4:5], v[2:3], 0, v[4:5]
	global_store_short v[4:5], v7, off
	v_add_u32_e32 v4, 36, v6
	v_ashrrev_i32_e32 v5, 31, v4
	v_lshlrev_b64 v[4:5], 8, v[4:5]
	ds_read2_b32 v[10:11], v14 offset0:40 offset1:44
	ds_read2_b32 v[12:13], v14 offset0:48 offset1:52
	v_cvt_pk_bf16_f32 v7, v9, s0
	v_lshl_add_u64 v[4:5], v[2:3], 0, v[4:5]
	global_store_short v[4:5], v7, off
	v_add_u32_e32 v4, 40, v6
	v_ashrrev_i32_e32 v5, 31, v4
	v_lshlrev_b64 v[4:5], 8, v[4:5]
	s_waitcnt lgkmcnt(0)
	v_cvt_pk_bf16_f32 v7, v10, s0
	v_lshl_add_u64 v[4:5], v[2:3], 0, v[4:5]
	global_store_short v[4:5], v7, off
	v_add_u32_e32 v4, 44, v6
	v_ashrrev_i32_e32 v5, 31, v4
	v_lshlrev_b64 v[4:5], 8, v[4:5]
	v_cvt_pk_bf16_f32 v7, v11, s0
	v_lshl_add_u64 v[4:5], v[2:3], 0, v[4:5]
	global_store_short v[4:5], v7, off
	v_add_u32_e32 v4, 48, v6
	v_ashrrev_i32_e32 v5, 31, v4
	v_lshlrev_b64 v[4:5], 8, v[4:5]
	v_cvt_pk_bf16_f32 v7, v12, s0
	v_lshl_add_u64 v[4:5], v[2:3], 0, v[4:5]
	global_store_short v[4:5], v7, off
	v_add_u32_e32 v4, 52, v6
	v_ashrrev_i32_e32 v5, 31, v4
	ds_read2_b32 v[8:9], v14 offset0:56 offset1:60
	v_lshlrev_b64 v[4:5], 8, v[4:5]
	v_cvt_pk_bf16_f32 v7, v13, s0
	v_lshl_add_u64 v[4:5], v[2:3], 0, v[4:5]
	global_store_short v[4:5], v7, off
	v_add_u32_e32 v4, 56, v6
	v_ashrrev_i32_e32 v5, 31, v4
	v_lshlrev_b64 v[4:5], 8, v[4:5]
	s_waitcnt lgkmcnt(0)
	v_cvt_pk_bf16_f32 v7, v8, s0
	v_lshl_add_u64 v[4:5], v[2:3], 0, v[4:5]
	global_store_short v[4:5], v7, off
	v_add_u32_e32 v4, 60, v6
	v_ashrrev_i32_e32 v5, 31, v4
	v_lshlrev_b64 v[4:5], 8, v[4:5]
	v_cvt_pk_bf16_f32 v6, v9, s0
	v_lshl_add_u64 v[2:3], v[2:3], 0, v[4:5]
	global_store_short v[2:3], v6, off
	s_waitcnt lgkmcnt(0)
	s_barrier

; __device__ __forceinline__ int tid_() { int t = threadIdx.x; asm volatile("" : "+v"(t)); return t; }
; __device__ __forceinline__ void convT_tile(const float* __restrict__ src, int lds, int k0, int c0, u16* __restrict__ dst, int Kd,
;                                            int rbase, int mode, int which, unsigned char* smem, const float* __restrict__ kscale = nullptr) {
;   float* tile = (float*)smem;
;   const int t = tid_();
;   float4 v4[4];
; #pragma unroll
;   for (int i = 0; i < 4; ++i) {
;     const f32x4 w_ = __builtin_nontemporal_load((const f32x4*)(src + (size_t)(k0 + i * 16 + (t >> 4)) * lds + c0 + (t & 15) * 4));
;     v4[i] = make_float4(w_[0], w_[1], w_[2], w_[3]);
;   }
; #pragma unroll
;   for (int i = 0; i < 4; ++i) {
;     const int kk = i * 16 + (t >> 4), cc = (t & 15) * 4;
;     const float sc = kscale ? kscale[k0 + kk] : 1.f;
; __device__ __forceinline__ void conv_item(const Params& p, int it, unsigned char* smem) {
;     ...
;   if (r < 48) {
;     const int ct = r >> 2, kt = r & 3;
;     convT_tile(p.w_uq + (size_t)l * 256 * 768, 768, kt * 64, ct * 64, p.WuqT + (size_t)l * 768 * 256, 256, ct * 64, 0, 0, smem, p.q_lora_norm + l * 256);
;     return;
;   }
.LBB0_49:
	s_andn2_b64 vcc, exec, s[0:1]
	s_cbranch_vccnz .LBB0_59
	v_mov_b64_e32 v[2:3], s[10:11]
	global_load_dwordx4 v[32:35], v[2:3], off offset:80
	global_load_dwordx2 v[20:21], v[2:3], off offset:200
	s_lshl_b32 s0, s6, 10
	v_mov_b32_e32 v29, v187
	s_sub_i32 s0, s17, s0
	s_and_b32 s0, s0, 0x1fc0
	v_lshlrev_b32_e32 v2, 2, v29
	v_and_b32_e32 v2, 60, v2
	s_add_i32 s4, s0, 0xfffff100
	v_lshlrev_b32_e32 v18, 2, v2
	s_and_b32 s7, s15, 0xc0
	v_ashrrev_i32_e32 v30, 4, v29
	v_add_u32_e32 v22, s7, v30
	v_add_u32_e32 v4, 16, v22
	v_add_u32_e32 v5, 32, v22
	v_add_u32_e32 v6, 48, v22
	v_ashrrev_i32_e32 v23, 31, v22
	v_mov_b32_e32 v24, 1.0
	v_mov_b32_e32 v26, 1.0
	s_waitcnt vmcnt(0) lgkmcnt(0)
	v_mad_i64_i32 v[2:3], s[0:1], s6, v1, v[34:35]
	v_lshl_add_u64 v[2:3], s[4:5], 2, v[2:3]
	v_lshl_add_u64 v[2:3], v[2:3], 0, v[18:19]
	v_mad_i64_i32 v[34:35], s[0:1], v22, s33, v[2:3]
	v_mad_i64_i32 v[36:37], s[0:1], v4, s33, v[2:3]
	v_mad_i64_i32 v[38:39], s[0:1], v5, s33, v[2:3]
	v_mad_i64_i32 v[40:41], s[0:1], v6, s33, v[2:3]
	global_load_dwordx4 v[14:17], v[34:35], off nt
	global_load_dwordx4 v[10:13], v[36:37], off nt
	global_load_dwordx4 v[6:9], v[38:39], off nt
	global_load_dwordx4 v[2:5], v[40:41], off nt
	s_lshl_b32 s0, s6, 8
	s_ashr_i32 s1, s0, 31
	v_lshl_add_u64 v[34:35], s[0:1], 2, v[32:33]
	v_cmp_ne_u64_e32 vcc, 0, v[32:33]
	v_lshl_add_u64 v[22:23], v[22:23], 2, v[34:35]
	s_and_saveexec_b64 s[0:1], vcc
	s_cbranch_execz .LBB0_52
	global_load_dword v26, v[22:23], off

; __device__ __forceinline__ u16 f2bf(float f) { return (u16)(pack2(f, 0.f) & 0xffffu); }
; __device__ __forceinline__ void convT_tile(const float* __restrict__ src, int lds, int k0, int c0, u16* __restrict__ dst, int Kd,
;                                            int rbase, int mode, int which, unsigned char* smem, const float* __restrict__ kscale = nullptr) {
;     ...
;   for (int i = 0; i < 4; ++i) {
;     const int kk = i * 16 + (t >> 4), cc = (t & 15) * 4;
;     const float sc = kscale ? kscale[k0 + kk] : 1.f;
;     tile[kk * 65 + cc + 0] = v4[i].x * sc; tile[kk * 65 + cc + 1] = v4[i].y * sc;
;     tile[kk * 65 + cc + 2] = v4[i].z * sc; tile[kk * 65 + cc + 3] = v4[i].w * sc;
;   }
;   __syncthreads();
; #pragma unroll
;   for (int i = 0; i < 16; ++i) {
;     const int cc = i * 4 + (t >> 6), kk = t & 63;
;     int row;
;     if (mode == 0) row = rbase + cc;
;     else { const int f = c0 + cc; row = (((f >> 4) * 2 + which) << 4) + (f & 15); }
;     dst[(size_t)row * Kd + k0 + kk] = f2bf(tile[kk * 65 + cc]);
;   }
;   __syncthreads();
; }
.LBB0_58:
	s_or_b64 exec, exec, s[0:1]
	s_waitcnt vmcnt(0) lgkmcnt(0)
	v_pk_mul_f32 v[2:3], v[2:3], v[10:11] op_sel_hi:[1,0]
	v_add_u32_e32 v8, 0x30c0, v14
	ds_write2_b32 v8, v2, v3 offset1:1
	v_pk_mul_f32 v[2:3], v[4:5], v[10:11] op_sel_hi:[1,0]
	v_add_u32_e32 v4, 0x30c8, v14
	v_ashrrev_i32_e32 v8, 6, v29
	ds_write2_b32 v4, v2, v3 offset1:1
	v_and_b32_e32 v9, 63, v29
	v_lshlrev_b32_e32 v4, 2, v8
	v_mad_u32_u24 v14, v9, s28, v4
	v_mad_i64_i32 v[6:7], s[0:1], s6, v25, v[20:21]
	s_waitcnt lgkmcnt(0)
	s_barrier
	ds_read2_b32 v[4:5], v14 offset1:4
	s_lshl_b32 s0, s7, 1
	s_mov_b32 s1, s5
	v_lshl_add_u64 v[2:3], v[6:7], 0, s[0:1]
	v_add_u32_e32 v6, s4, v8
	v_lshlrev_b32_e32 v18, 1, v9
	v_ashrrev_i32_e32 v7, 31, v6
	v_lshl_add_u64 v[2:3], v[2:3], 0, v[18:19]
	v_lshlrev_b64 v[10:11], 9, v[6:7]
	s_waitcnt lgkmcnt(0)
	v_cvt_pk_bf16_f32 v4, v4, s0
	v_lshl_add_u64 v[10:11], v[2:3], 0, v[10:11]
	global_store_short v[10:11], v4, off
	v_add_u32_e32 v4, 4, v6
	v_cvt_pk_bf16_f32 v7, v5, s0
	v_ashrrev_i32_e32 v5, 31, v4
	ds_read2_b32 v[8:9], v14 offset0:8 offset1:12
	v_lshlrev_b64 v[4:5], 9, v[4:5]
	v_lshl_add_u64 v[4:5], v[2:3], 0, v[4:5]
	global_store_short v[4:5], v7, off
	v_add_u32_e32 v4, 8, v6
	v_ashrrev_i32_e32 v5, 31, v4
	v_lshlrev_b64 v[4:5], 9, v[4:5]
	s_waitcnt lgkmcnt(0)
	v_cvt_pk_bf16_f32 v7, v8, s0
	v_lshl_add_u64 v[4:5], v[2:3], 0, v[4:5]
	global_store_short v[4:5], v7, off
	v_add_u32_e32 v4, 12, v6
	v_ashrrev_i32_e32 v5, 31, v4
	v_cvt_pk_bf16_f32 v7, v9, s0
	ds_read2_b32 v[8:9], v14 offset0:16 offset1:20
	v_lshlrev_b64 v[4:5], 9, v[4:5]
	v_lshl_add_u64 v[4:5], v[2:3], 0, v[4:5]
	global_store_short v[4:5], v7, off
	v_add_u32_e32 v4, 16, v6
	v_ashrrev_i32_e32 v5, 31, v4
	v_lshlrev_b64 v[4:5], 9, v[4:5]
	s_waitcnt lgkmcnt(0)
	v_cvt_pk_bf16_f32 v7, v8, s0
	v_lshl_add_u64 v[4:5], v[2:3], 0, v[4:5]
	global_store_short v[4:5], v7, off
	v_add_u32_e32 v4, 20, v6
	v_ashrrev_i32_e32 v5, 31, v4
	v_cvt_pk_bf16_f32 v7, v9, s0
	ds_read2_b32 v[8:9], v14 offset0:24 offset1:28
	v_lshlrev_b64 v[4:5], 9, v[4:5]
	v_lshl_add_u64 v[4:5], v[2:3], 0, v[4:5]
	global_store_short v[4:5], v7, off
	v_add_u32_e32 v4, 24, v6
	v_ashrrev_i32_e32 v5, 31, v4
	v_lshlrev_b64 v[4:5], 9, v[4:5]
	s_waitcnt lgkmcnt(0)
	v_cvt_pk_bf16_f32 v7, v8, s0
	v_lshl_add_u64 v[4:5], v[2:3], 0, v[4:5]
	global_store_short v[4:5], v7, off
	v_add_u32_e32 v4, 28, v6
	v_ashrrev_i32_e32 v5, 31, v4
	v_cvt_pk_bf16_f32 v7, v9, s0
	ds_read2_b32 v[8:9], v14 offset0:32 offset1:36
	v_lshlrev_b64 v[4:5], 9, v[4:5]
	v_lshl_add_u64 v[4:5], v[2:3], 0, v[4:5]
	global_store_short v[4:5], v7, off
	v_add_u32_e32 v4, 32, v6
	v_ashrrev_i32_e32 v5, 31, v4
	v_lshlrev_b64 v[4:5], 9, v[4:5]
	s_waitcnt lgkmcnt(0)
	v_cvt_pk_bf16_f32 v7, v8, s0
	v_lshl_add_u64 v[4:5], v[2:3], 0, v[4:5]
	global_store_short v[4:5], v7, off
	v_add_u32_e32 v4, 36, v6
	v_ashrrev_i32_e32 v5, 31, v4
	v_lshlrev_b64 v[4:5], 9, v[4:5]
	ds_read2_b32 v[10:11], v14 offset0:40 offset1:44
	ds_read2_b32 v[12:13], v14 offset0:48 offset1:52
	v_cvt_pk_bf16_f32 v7, v9, s0
	v_lshl_add_u64 v[4:5], v[2:3], 0, v[4:5]
	global_store_short v[4:5], v7, off
	v_add_u32_e32 v4, 40, v6
	v_ashrrev_i32_e32 v5, 31, v4
	v_lshlrev_b64 v[4:5], 9, v[4:5]
	s_waitcnt lgkmcnt(0)
	v_cvt_pk_bf16_f32 v7, v10, s0
	v_lshl_add_u64 v[4:5], v[2:3], 0, v[4:5]
	global_store_short v[4:5], v7, off
	v_add_u32_e32 v4, 44, v6
	v_ashrrev_i32_e32 v5, 31, v4
	v_lshlrev_b64 v[4:5], 9, v[4:5]
	v_cvt_pk_bf16_f32 v7, v11, s0
	v_lshl_add_u64 v[4:5], v[2:3], 0, v[4:5]
	global_store_short v[4:5], v7, off
	v_add_u32_e32 v4, 48, v6
	v_ashrrev_i32_e32 v5, 31, v4
	v_lshlrev_b64 v[4:5], 9, v[4:5]
	v_cvt_pk_bf16_f32 v7, v12, s0
	v_lshl_add_u64 v[4:5], v[2:3], 0, v[4:5]
	global_store_short v[4:5], v7, off
	v_add_u32_e32 v4, 52, v6
	v_ashrrev_i32_e32 v5, 31, v4
	ds_read2_b32 v[8:9], v14 offset0:56 offset1:60
	v_lshlrev_b64 v[4:5], 9, v[4:5]
	v_cvt_pk_bf16_f32 v7, v13, s0
	v_lshl_add_u64 v[4:5], v[2:3], 0, v[4:5]
	global_store_short v[4:5], v7, off
	v_add_u32_e32 v4, 56, v6
	v_ashrrev_i32_e32 v5, 31, v4
	v_lshlrev_b64 v[4:5], 9, v[4:5]
	s_waitcnt lgkmcnt(0)
	v_cvt_pk_bf16_f32 v7, v8, s0
	v_lshl_add_u64 v[4:5], v[2:3], 0, v[4:5]
	global_store_short v[4:5], v7, off
	v_add_u32_e32 v4, 60, v6
	v_ashrrev_i32_e32 v5, 31, v4
	v_lshlrev_b64 v[4:5], 9, v[4:5]
	v_cvt_pk_bf16_f32 v6, v9, s0
	v_lshl_add_u64 v[2:3], v[2:3], 0, v[4:5]
	global_store_short v[2:3], v6, off
	s_waitcnt lgkmcnt(0)
	s_barrier

; __device__ __forceinline__ u16 f2bf(float f) { return (u16)(pack2(f, 0.f) & 0xffffu); }
; __device__ __forceinline__ int tid_() { int t = threadIdx.x; asm volatile("" : "+v"(t)); return t; }
; __device__ __forceinline__ void convT_tile(const float* __restrict__ src, int lds, int k0, int c0, u16* __restrict__ dst, int Kd,
;                                            int rbase, int mode, int which, unsigned char* smem, const float* __restrict__ kscale = nullptr) {
;   float* tile = (float*)smem;
;   const int t = tid_();
;   float4 v4[4];
; #pragma unroll
;   for (int i = 0; i < 4; ++i) {
;     const f32x4 w_ = __builtin_nontemporal_load((const f32x4*)(src + (size_t)(k0 + i * 16 + (t >> 4)) * lds + c0 + (t & 15) * 4));
;     v4[i] = make_float4(w_[0], w_[1], w_[2], w_[3]);
;   }
; #pragma unroll
;   for (int i = 0; i < 4; ++i) {
;     const int kk = i * 16 + (t >> 4), cc = (t & 15) * 4;
;     const float sc = kscale ? kscale[k0 + kk] : 1.f;
;     tile[kk * 65 + cc + 0] = v4[i].x * sc; tile[kk * 65 + cc + 1] = v4[i].y * sc;
;     tile[kk * 65 + cc + 2] = v4[i].z * sc; tile[kk * 65 + cc + 3] = v4[i].w * sc;
;   }
;   __syncthreads();
; #pragma unroll
;   for (int i = 0; i < 16; ++i) {
;     const int cc = i * 4 + (t >> 6), kk = t & 63;
;     int row;
;     if (mode == 0) row = rbase + cc;
;     else { const int f = c0 + cc; row = (((f >> 4) * 2 + which) << 4) + (f & 15); }
;     dst[(size_t)row * Kd + k0 + kk] = f2bf(tile[kk * 65 + cc]);
;   }
;   __syncthreads();
; }
; __device__ __forceinline__ void conv_item(const Params& p, int it, unsigned char* smem) {
;     ...
;   if (r < 240) {
;     const int ct = r >> 4, kt = r & 15;
;     const int c0 = (ct < 8 ? ct : ct + 4) * 64;
;     const int n0 = c0 + (c0 >= 768 ? 256 : 0);
;     convT_tile(p.w_in + (size_t)l * 1024 * 1216, 1216, kt * 64, c0, p.WinT + (size_t)l * 1536 * 1024, 1024, n0, 0, 0, smem);
;     return;
.LBB0_60:
	s_andn2_b64 vcc, exec, s[0:1]
	s_cbranch_vccnz .LBB0_25
	v_mov_b64_e32 v[2:3], s[10:11]
	global_load_dwordx2 v[4:5], v[2:3], off offset:48
	global_load_dwordx2 v[20:21], v[2:3], off offset:192
	s_ashr_i32 s0, s35, 4
	s_lshl_b32 s1, s0, 6
	s_add_i32 s4, s1, 0x100
	v_mov_b32_e32 v6, v187
	s_cmp_lt_i32 s0, 8
	s_cselect_b32 s0, s1, s4
	v_lshlrev_b32_e32 v3, 4, v6
	v_ashrrev_i32_e32 v2, 4, v6
	v_ashrrev_i32_e32 v24, 6, v6
	v_and_b32_e32 v18, 0xf0, v3
	s_cmpk_gt_i32 s0, 0x2ff
	v_and_b32_e32 v26, 63, v6
	v_lshlrev_b32_e32 v3, 2, v24
	v_mad_u64_u32 v[22:23], s[12:13], v2, s28, v[18:19]
	s_cselect_b32 s4, 0x100, 0
	s_and_b32 s7, s15, 0x3c0
	v_mad_u32_u24 v23, v26, s28, v3
	s_ashr_i32 s1, s0, 31
	v_add_u32_e32 v6, s7, v2
	v_add_u32_e32 v7, 16, v6
	v_add_u32_e32 v8, 32, v6
	v_add_u32_e32 v32, 48, v6
	v_add_u32_e32 v29, 0x1040, v22
	v_add_u32_e32 v62, 0x1048, v22
	v_add_u32_e32 v63, 0x2080, v22
	v_add_u32_e32 v64, 0x2088, v22
	v_add_u32_e32 v65, 0x30c0, v22
	v_add_u32_e32 v66, 0x30c8, v22
	s_waitcnt vmcnt(0) lgkmcnt(0)
	v_mad_i64_i32 v[2:3], s[12:13], s6, v27, v[4:5]
	v_lshl_add_u64 v[2:3], s[0:1], 2, v[2:3]
	v_lshl_add_u64 v[14:15], v[2:3], 0, v[18:19]
	v_mad_i64_i32 v[2:3], s[12:13], v6, s34, v[14:15]
	v_mad_i64_i32 v[16:17], s[12:13], v7, s34, v[14:15]
	global_load_dwordx4 v[2:5], v[2:3], off nt
	v_mad_i64_i32 v[30:31], s[12:13], v8, s34, v[14:15]
	global_load_dwordx4 v[6:9], v[16:17], off nt
	global_load_dwordx4 v[10:13], v[30:31], off nt
	v_mad_i64_i32 v[14:15], s[12:13], v32, s34, v[14:15]
	global_load_dwordx4 v[14:17], v[14:15], off nt
	s_add_i32 s0, s4, s0
	s_lshl_b32 s4, s7, 1
	v_add_u32_e32 v30, s0, v24
	v_mad_i64_i32 v[20:21], s[0:1], s6, v28, v[20:21]
	v_ashrrev_i32_e32 v31, 31, v30
	v_add_u32_e32 v32, 4, v30
	v_add_u32_e32 v34, 8, v30
	v_add_u32_e32 v36, 12, v30
	v_add_u32_e32 v38, 16, v30
	v_add_u32_e32 v40, 20, v30
	v_add_u32_e32 v42, 24, v30
	v_add_u32_e32 v44, 28, v30
	v_add_u32_e32 v46, 32, v30
	v_add_u32_e32 v48, 36, v30
	v_add_u32_e32 v50, 40, v30
	v_add_u32_e32 v52, 44, v30
	v_add_u32_e32 v54, 48, v30
	v_add_u32_e32 v56, 52, v30
	v_add_u32_e32 v58, 56, v30
	v_add_u32_e32 v60, 60, v30
	v_lshl_add_u64 v[20:21], v[20:21], 0, s[4:5]
	v_lshlrev_b32_e32 v18, 1, v26
	v_lshlrev_b64 v[30:31], 11, v[30:31]
	v_ashrrev_i32_e32 v33, 31, v32
	v_ashrrev_i32_e32 v35, 31, v34
	v_ashrrev_i32_e32 v37, 31, v36
	v_ashrrev_i32_e32 v39, 31, v38
	v_ashrrev_i32_e32 v41, 31, v40
	v_ashrrev_i32_e32 v43, 31, v42
	v_ashrrev_i32_e32 v45, 31, v44
	v_ashrrev_i32_e32 v47, 31, v46
	v_ashrrev_i32_e32 v49, 31, v48
	v_ashrrev_i32_e32 v51, 31, v50
	v_ashrrev_i32_e32 v53, 31, v52
	v_ashrrev_i32_e32 v55, 31, v54
	v_ashrrev_i32_e32 v57, 31, v56
	v_ashrrev_i32_e32 v59, 31, v58
	v_ashrrev_i32_e32 v61, 31, v60
	v_lshl_add_u64 v[20:21], v[20:21], 0, v[18:19]
	v_lshlrev_b64 v[32:33], 11, v[32:33]
	v_lshlrev_b64 v[34:35], 11, v[34:35]
	v_lshlrev_b64 v[36:37], 11, v[36:37]
	v_lshlrev_b64 v[38:39], 11, v[38:39]
	v_lshlrev_b64 v[40:41], 11, v[40:41]
	v_lshlrev_b64 v[42:43], 11, v[42:43]
	v_lshlrev_b64 v[44:45], 11, v[44:45]
	v_lshlrev_b64 v[46:47], 11, v[46:47]
	v_lshlrev_b64 v[48:49], 11, v[48:49]
	v_lshlrev_b64 v[50:51], 11, v[50:51]
	v_lshlrev_b64 v[52:53], 11, v[52:53]
	v_lshlrev_b64 v[54:55], 11, v[54:55]
	v_lshlrev_b64 v[56:57], 11, v[56:57]
	v_lshlrev_b64 v[58:59], 11, v[58:59]
	v_lshlrev_b64 v[60:61], 11, v[60:61]
	v_lshl_add_u64 v[30:31], v[20:21], 0, v[30:31]
	v_lshl_add_u64 v[32:33], v[20:21], 0, v[32:33]
	v_lshl_add_u64 v[34:35], v[20:21], 0, v[34:35]
	v_lshl_add_u64 v[36:37], v[20:21], 0, v[36:37]
	v_lshl_add_u64 v[38:39], v[20:21], 0, v[38:39]
	v_lshl_add_u64 v[40:41], v[20:21], 0, v[40:41]
	v_lshl_add_u64 v[42:43], v[20:21], 0, v[42:43]
	v_lshl_add_u64 v[44:45], v[20:21], 0, v[44:45]
	v_lshl_add_u64 v[46:47], v[20:21], 0, v[46:47]
	v_lshl_add_u64 v[48:49], v[20:21], 0, v[48:49]
	v_lshl_add_u64 v[50:51], v[20:21], 0, v[50:51]
	v_lshl_add_u64 v[52:53], v[20:21], 0, v[52:53]
	v_lshl_add_u64 v[54:55], v[20:21], 0, v[54:55]
	v_lshl_add_u64 v[56:57], v[20:21], 0, v[56:57]
	s_waitcnt vmcnt(0) lgkmcnt(0)
	ds_write2_b32 v22, v2, v3 offset1:1
	ds_write2_b32 v22, v4, v5 offset0:2 offset1:3
	ds_write2_b32 v29, v6, v7 offset1:1
	ds_write2_b32 v62, v8, v9 offset1:1
	ds_write2_b32 v63, v10, v11 offset1:1
	ds_write2_b32 v64, v12, v13 offset1:1
	ds_write2_b32 v65, v14, v15 offset1:1
	ds_write2_b32 v66, v16, v17 offset1:1
	s_waitcnt lgkmcnt(0)
	s_barrier
	ds_read2_b32 v[2:3], v23 offset1:4
	ds_read2_b32 v[4:5], v23 offset0:8 offset1:12
	ds_read2_b32 v[6:7], v23 offset0:16 offset1:20
	ds_read2_b32 v[8:9], v23 offset0:24 offset1:28
	ds_read2_b32 v[10:11], v23 offset0:32 offset1:36
	ds_read2_b32 v[12:13], v23 offset0:40 offset1:44
	ds_read2_b32 v[14:15], v23 offset0:48 offset1:52
	ds_read2_b32 v[16:17], v23 offset0:56 offset1:60
	s_waitcnt lgkmcnt(7)
	v_cvt_pk_bf16_f32 v2, v2, s0
	v_lshl_add_u64 v[58:59], v[20:21], 0, v[58:59]
	v_lshl_add_u64 v[20:21], v[20:21], 0, v[60:61]
	v_cvt_pk_bf16_f32 v3, v3, s0
	s_waitcnt lgkmcnt(6)
	v_cvt_pk_bf16_f32 v4, v4, s0
	v_cvt_pk_bf16_f32 v5, v5, s0
	s_waitcnt lgkmcnt(5)
	v_cvt_pk_bf16_f32 v6, v6, s0
	v_cvt_pk_bf16_f32 v7, v7, s0
	s_waitcnt lgkmcnt(4)
	v_cvt_pk_bf16_f32 v8, v8, s0
	v_cvt_pk_bf16_f32 v9, v9, s0
	s_waitcnt lgkmcnt(3)
	v_cvt_pk_bf16_f32 v10, v10, s0
	v_cvt_pk_bf16_f32 v11, v11, s0
	s_waitcnt lgkmcnt(2)
	v_cvt_pk_bf16_f32 v12, v12, s0
	v_cvt_pk_bf16_f32 v13, v13, s0
	s_waitcnt lgkmcnt(1)
	v_cvt_pk_bf16_f32 v14, v14, s0
	v_cvt_pk_bf16_f32 v15, v15, s0
	s_waitcnt lgkmcnt(0)
	v_cvt_pk_bf16_f32 v16, v16, s0
	v_cvt_pk_bf16_f32 v17, v17, s0
	global_store_short v[30:31], v2, off
	global_store_short v[32:33], v3, off
	global_store_short v[34:35], v4, off
	global_store_short v[36:37], v5, off
	global_store_short v[38:39], v6, off
	global_store_short v[40:41], v7, off
	global_store_short v[42:43], v8, off
	global_store_short v[44:45], v9, off
	global_store_short v[46:47], v10, off
	global_store_short v[48:49], v11, off
	global_store_short v[50:51], v12, off
	global_store_short v[52:53], v13, off
	global_store_short v[54:55], v14, off
	global_store_short v[56:57], v15, off
	global_store_short v[58:59], v16, off
	global_store_short v[20:21], v17, off
	s_waitcnt lgkmcnt(0)
	s_barrier
	s_branch .LBB0_25

; __device__ __forceinline__ u16 f2bf(float f) { return (u16)(pack2(f, 0.f) & 0xffffu); }
; __device__ __forceinline__ void elem_item(const Params& p, int it) {
;     ...
;   {
; #pragma unroll
;     for (int i = 0; i < 4; ++i) {
;       const int idx = it * 1024 + i * 256 + t;
;       const int k = idx >> 9, kk = idx & 511, ri = kk >> 8, n = kk & 255;
;       const int ph = (k * n) & 255;
;       const float xx = (float)ph / 128.f;
;       p.Mc[idx] = f2bf(ri ? sinpif(xx) : cospif(xx));
;     }
;   }
.LBB0_65:
	v_mov_b32_e32 v8, v187
	s_cmpk_gt_i32 s1, 0x7f
	s_mov_b64 s[4:5], -1
	s_cbranch_scc0 .LBB0_107
	s_cmpk_gt_u32 s1, 0x87f
	s_cbranch_scc0 .LBB0_104
	s_cmpk_lt_u32 s1, 0x8a0
	s_cbranch_scc1 .LBB0_85
	v_mov_b64_e32 v[2:3], s[10:11]
	global_load_dwordx2 v[4:5], v[2:3], off offset:264
	v_add_u32_e32 v2, s12, v8
	v_lshrrev_b32_e32 v3, 9, v2
	v_mul_lo_u32 v3, v3, v8
	v_cvt_f32_ubyte0_e32 v3, v3
	v_mul_f32_e32 v3, 0x3c000000, v3
	v_mul_f32_e32 v10, 0.5, v3
	v_fract_f32_e32 v11, v10
	v_add_f32_e32 v11, v11, v11
	v_cmp_neq_f32_e32 vcc, s14, v10
	v_and_b32_e32 v9, 0x100, v8
	s_nop 0
	v_cndmask_b32_e32 v10, 0, v11, vcc
	v_cmp_lt_f32_e32 vcc, 1.0, v3
	s_nop 1
	v_cndmask_b32_e32 v11, v3, v10, vcc
	v_add_f32_e32 v10, v11, v11
	v_rndne_f32_e32 v12, v10
	v_cvt_i32_f32_e32 v10, v12
	v_fmac_f32_e32 v11, -0.5, v12
	v_cmp_ne_u32_e32 vcc, 0, v9
	v_mul_f32_e32 v9, v11, v11
	v_and_b32_e32 v12, 1, v10
	v_fmamk_f32 v16, v9, 0x3e75aa41, v1
	v_mul_f32_e32 v15, v11, v9
	v_fmamk_f32 v13, v9, 0x3d4be544, v6
	s_and_saveexec_b64 s[4:5], vcc
	s_xor_b64 s[6:7], exec, s[4:5]
	s_cbranch_execz .LBB0_70
	v_fmaak_f32 v14, v9, v16, 0x40234736
	v_fmaak_f32 v14, v9, v14, 0xc0a55e0e
	v_mul_f32_e32 v14, v15, v14
	v_fmac_f32_e32 v14, 0x40490fdb, v11
	v_fmaak_f32 v11, v9, v13, 0xbfaad1da
	v_fmaak_f32 v11, v9, v11, 0x4081e0d3
	v_fmaak_f32 v11, v9, v11, 0xc09de9e6
	v_fma_f32 v9, v9, v11, 1.0
	v_cmp_eq_u32_e64 s[4:5], 0, v12
	v_lshlrev_b32_e32 v10, 30, v10
	s_nop 0
	v_cndmask_b32_e64 v9, v9, v14, s[4:5]
	v_bitop3_b32 v14, v10, v9, s15 bitop3:0x6c

; __device__ __forceinline__ u16 f2bf(float f) { return (u16)(pack2(f, 0.f) & 0xffffu); }
; __device__ __forceinline__ void elem_item(const Params& p, int it) {
;     ...
;   {
; #pragma unroll
;     for (int i = 0; i < 4; ++i) {
;       const int idx = it * 1024 + i * 256 + t;
;       const int k = idx >> 9, kk = idx & 511, ri = kk >> 8, n = kk & 255;
;       const int ph = (k * n) & 255;
;       const float xx = (float)ph / 128.f;
;       p.Mc[idx] = f2bf(ri ? sinpif(xx) : cospif(xx));
;     }
.LBB0_72:
	s_or_b64 exec, exec, s[6:7]
	v_cmp_lg_f32_e64 s[4:5], s14, v3
	s_nop 1
	v_cndmask_b32_e64 v3, v7, v14, s[4:5]
	v_cvt_pk_bf16_f32 v9, v3, s0
	v_ashrrev_i32_e32 v3, 31, v2
	s_waitcnt vmcnt(0) lgkmcnt(0)
	v_lshl_add_u64 v[4:5], v[2:3], 1, v[4:5]
	v_add_u32_e32 v3, 0x100, v2
	v_lshrrev_b32_e32 v3, 9, v3
	v_mul_lo_u32 v3, v3, v8
	v_cvt_f32_ubyte0_e32 v3, v3
	v_mul_f32_e32 v3, 0x3c000000, v3
	v_mul_f32_e32 v10, 0.5, v3
	v_fract_f32_e32 v11, v10
	v_add_f32_e32 v11, v11, v11
	v_cmp_neq_f32_e64 s[4:5], s14, v10
	global_store_short v[4:5], v9, off
	s_nop 0
	v_cndmask_b32_e64 v10, 0, v11, s[4:5]
	v_cmp_lt_f32_e64 s[4:5], 1.0, v3
	s_nop 1
	v_cndmask_b32_e64 v10, v3, v10, s[4:5]
	v_add_f32_e32 v11, v10, v10
	v_rndne_f32_e32 v11, v11
	v_cvt_i32_f32_e32 v12, v11
	v_fmac_f32_e32 v10, -0.5, v11
	v_mul_f32_e32 v9, v10, v10
	v_fmamk_f32 v16, v9, 0x3e75aa41, v1
	v_and_b32_e32 v11, 1, v12
	v_mul_f32_e32 v15, v10, v9
	v_fmamk_f32 v13, v9, 0x3d4be544, v6
	s_and_saveexec_b64 s[4:5], vcc
	s_xor_b64 s[6:7], exec, s[4:5]
	s_cbranch_execz .LBB0_74
	v_fmaak_f32 v14, v9, v16, 0x40234736
	v_fmaak_f32 v14, v9, v14, 0xc0a55e0e
	v_mul_f32_e32 v14, v15, v14
	v_fmac_f32_e32 v14, 0x40490fdb, v10
	v_fmaak_f32 v10, v9, v13, 0xbfaad1da
	v_fmaak_f32 v10, v9, v10, 0x4081e0d3
	v_fmaak_f32 v10, v9, v10, 0xc09de9e6
	v_and_b32_e32 v12, 2, v12
	v_fma_f32 v9, v9, v10, 1.0
	v_cmp_eq_u32_e64 s[4:5], 0, v11
	s_nop 1
	v_cndmask_b32_e64 v9, -v14, v9, s[4:5]
	v_cmp_eq_u32_e64 s[4:5], 0, v12
	s_nop 1
	v_cndmask_b32_e64 v14, -v9, v9, s[4:5]

; __device__ __forceinline__ u16 f2bf(float f) { return (u16)(pack2(f, 0.f) & 0xffffu); }
; __device__ __forceinline__ void elem_item(const Params& p, int it) {
;     ...
;   {
; #pragma unroll
;     for (int i = 0; i < 4; ++i) {
;       const int idx = it * 1024 + i * 256 + t;
;       const int k = idx >> 9, kk = idx & 511, ri = kk >> 8, n = kk & 255;
;       const int ph = (k * n) & 255;
;       const float xx = (float)ph / 128.f;
;       p.Mc[idx] = f2bf(ri ? sinpif(xx) : cospif(xx));
;     }
.LBB0_76:
	s_or_b64 exec, exec, s[6:7]
	v_cmp_lg_f32_e64 s[4:5], s14, v3
	s_nop 1
	v_cndmask_b32_e64 v3, v7, v14, s[4:5]
	v_cvt_pk_bf16_f32 v9, v3, s0
	v_add_u32_e32 v3, 0x200, v2
	v_lshrrev_b32_e32 v3, 9, v3
	v_mul_lo_u32 v3, v3, v8
	v_cvt_f32_ubyte0_e32 v3, v3
	v_mul_f32_e32 v3, 0x3c000000, v3
	v_mul_f32_e32 v10, 0.5, v3
	v_fract_f32_e32 v11, v10
	v_add_f32_e32 v11, v11, v11
	v_cmp_neq_f32_e64 s[4:5], s14, v10
	global_store_short v[4:5], v9, off offset:512
	s_nop 0
	v_cndmask_b32_e64 v10, 0, v11, s[4:5]
	v_cmp_lt_f32_e64 s[4:5], 1.0, v3
	s_nop 1
	v_cndmask_b32_e64 v11, v3, v10, s[4:5]
	v_add_f32_e32 v10, v11, v11
	v_rndne_f32_e32 v12, v10
	v_cvt_i32_f32_e32 v10, v12
	v_fmac_f32_e32 v11, -0.5, v12
	v_mul_f32_e32 v9, v11, v11
	v_fmamk_f32 v16, v9, 0x3e75aa41, v1
	v_and_b32_e32 v12, 1, v10
	v_mul_f32_e32 v15, v11, v9
	v_fmamk_f32 v13, v9, 0x3d4be544, v6
	s_and_saveexec_b64 s[4:5], vcc
	s_xor_b64 s[4:5], exec, s[4:5]
	s_cbranch_execz .LBB0_78
	v_fmaak_f32 v14, v9, v16, 0x40234736
	v_fmaak_f32 v14, v9, v14, 0xc0a55e0e
	v_mul_f32_e32 v14, v15, v14
	v_fmac_f32_e32 v14, 0x40490fdb, v11
	v_fmaak_f32 v11, v9, v13, 0xbfaad1da
	v_fmaak_f32 v11, v9, v11, 0x4081e0d3
	v_fmaak_f32 v11, v9, v11, 0xc09de9e6
	v_fma_f32 v9, v9, v11, 1.0
	v_cmp_eq_u32_e32 vcc, 0, v12
	v_lshlrev_b32_e32 v10, 30, v10
	s_nop 0
	v_cndmask_b32_e32 v9, v9, v14, vcc
	v_bitop3_b32 v14, v10, v9, s15 bitop3:0x6c

; __device__ __forceinline__ u16 f2bf(float f) { return (u16)(pack2(f, 0.f) & 0xffffu); }
; __device__ __forceinline__ void elem_item(const Params& p, int it) {
;     ...
;   {
; #pragma unroll
;     for (int i = 0; i < 4; ++i) {
;       const int idx = it * 1024 + i * 256 + t;
;       const int k = idx >> 9, kk = idx & 511, ri = kk >> 8, n = kk & 255;
;       const int ph = (k * n) & 255;
;       const float xx = (float)ph / 128.f;
;       p.Mc[idx] = f2bf(ri ? sinpif(xx) : cospif(xx));
;     }
.LBB0_80:
	s_or_b64 exec, exec, s[4:5]
	v_cmp_lg_f32_e32 vcc, s14, v3
	s_nop 1
	v_cndmask_b32_e32 v3, v7, v14, vcc
	v_cvt_pk_bf16_f32 v3, v3, s0
	global_store_short v[4:5], v3, off offset:1024
	v_add_u32_e32 v3, 0x300, v2
	v_lshrrev_b32_e32 v2, 9, v3
	v_mul_lo_u32 v2, v2, v8
	v_cvt_f32_ubyte0_e32 v2, v2
	v_mul_f32_e32 v2, 0x3c000000, v2
	v_mul_f32_e32 v9, 0.5, v2
	v_fract_f32_e32 v10, v9
	v_add_f32_e32 v10, v10, v10
	v_cmp_neq_f32_e32 vcc, s14, v9
	v_and_b32_e32 v3, 0x100, v3
	s_nop 0
	v_cndmask_b32_e32 v9, 0, v10, vcc
	v_cmp_lt_f32_e32 vcc, 1.0, v2
	s_nop 1
	v_cndmask_b32_e32 v10, v2, v9, vcc
	v_add_f32_e32 v9, v10, v10
	v_rndne_f32_e32 v11, v9
	v_cvt_i32_f32_e32 v9, v11
	v_fmac_f32_e32 v10, -0.5, v11
	v_cmp_ne_u32_e32 vcc, 0, v3
	v_mul_f32_e32 v3, v10, v10
	v_and_b32_e32 v11, 1, v9
	v_fmamk_f32 v15, v3, 0x3e75aa41, v1
	v_mul_f32_e32 v14, v10, v3
	v_fmamk_f32 v12, v3, 0x3d4be544, v6
	s_and_saveexec_b64 s[4:5], vcc
	s_xor_b64 s[4:5], exec, s[4:5]
	s_cbranch_execz .LBB0_82
	v_fmaak_f32 v13, v3, v15, 0x40234736
	v_fmaak_f32 v13, v3, v13, 0xc0a55e0e
	v_mul_f32_e32 v13, v14, v13
	v_fmac_f32_e32 v13, 0x40490fdb, v10
	v_fmaak_f32 v10, v3, v12, 0xbfaad1da
	v_fmaak_f32 v10, v3, v10, 0x4081e0d3
	v_fmaak_f32 v10, v3, v10, 0xc09de9e6
	v_fma_f32 v3, v3, v10, 1.0
	v_cmp_eq_u32_e32 vcc, 0, v11
	v_lshlrev_b32_e32 v9, 30, v9
	s_nop 0
	v_cndmask_b32_e32 v3, v3, v13, vcc
	v_bitop3_b32 v13, v9, v3, s15 bitop3:0x6c

; __device__ __forceinline__ u16 f2bf(float f) { return (u16)(pack2(f, 0.f) & 0xffffu); }
; __device__ __forceinline__ void elem_item(const Params& p, int it) {
;     ...
;   if (it < 32) {
; #pragma unroll
;     for (int i = 0; i < 4; ++i) {
;       const int idx = it * 1024 + i * 256 + t;
;       const int k1 = idx >> 8, kk = idx & 255, ri = kk >> 7, n1 = kk & 127;
;       const int ph = (k1 * n1) & 127;
;       const float xx = (float)ph / 64.f;
;       p.M2[idx] = f2bf(ri ? sinpif(xx) : cospif(xx));
;     }
;     return;
;   }
.LBB0_84:
	s_or_b64 exec, exec, s[4:5]
	v_cmp_lg_f32_e32 vcc, s14, v2
	s_mov_b64 s[4:5], 0
	s_nop 0
	v_cndmask_b32_e32 v2, v7, v13, vcc
	v_cvt_pk_bf16_f32 v2, v2, s0
	global_store_short v[4:5], v2, off offset:1536
.LBB0_85:
	s_and_b64 vcc, exec, s[4:5]
	s_cbranch_vccz .LBB0_103
	v_mov_b64_e32 v[2:3], s[10:11]
	global_load_dwordx2 v[2:3], v[2:3], off offset:256
	v_add_u32_e32 v9, s12, v8
	v_add_u32_e32 v4, 0x8000, v9
	v_lshrrev_b32_e32 v5, 8, v4
	v_mul_lo_u32 v5, v5, v8
	v_and_b32_e32 v5, 0x7f, v5
	v_cvt_f32_ubyte0_e32 v5, v5
	v_mul_f32_e32 v5, 0x3c800000, v5
	v_mul_f32_e32 v11, 0.5, v5
	v_fract_f32_e32 v12, v11
	v_add_f32_e32 v12, v12, v12
	v_cmp_neq_f32_e32 vcc, s14, v11
	v_and_b32_e32 v10, 0x80, v8
	s_nop 0
	v_cndmask_b32_e32 v11, 0, v12, vcc
	v_cmp_lt_f32_e32 vcc, 1.0, v5
	s_nop 1
	v_cndmask_b32_e32 v12, v5, v11, vcc
	v_add_f32_e32 v11, v12, v12
	v_rndne_f32_e32 v13, v11
	v_cvt_i32_f32_e32 v11, v13
	v_fmac_f32_e32 v12, -0.5, v13
	v_cmp_ne_u32_e32 vcc, 0, v10
	v_mul_f32_e32 v10, v12, v12
	v_and_b32_e32 v13, 1, v11
	v_fmamk_f32 v17, v10, 0x3e75aa41, v1
	v_mul_f32_e32 v16, v12, v10
	v_fmamk_f32 v14, v10, 0x3d4be544, v6
	s_and_saveexec_b64 s[4:5], vcc
	s_xor_b64 s[6:7], exec, s[4:5]
	s_cbranch_execz .LBB0_88
	v_fmaak_f32 v15, v10, v17, 0x40234736
	v_fmaak_f32 v15, v10, v15, 0xc0a55e0e
	v_mul_f32_e32 v15, v16, v15
	v_fmac_f32_e32 v15, 0x40490fdb, v12
	v_fmaak_f32 v12, v10, v14, 0xbfaad1da
	v_fmaak_f32 v12, v10, v12, 0x4081e0d3
	v_fmaak_f32 v12, v10, v12, 0xc09de9e6
	v_fma_f32 v10, v10, v12, 1.0
	v_cmp_eq_u32_e64 s[4:5], 0, v13
	v_lshlrev_b32_e32 v11, 30, v11
	s_nop 0
	v_cndmask_b32_e64 v10, v10, v15, s[4:5]
	v_bitop3_b32 v15, v11, v10, s15 bitop3:0x6c

; __device__ __forceinline__ u16 f2bf(float f) { return (u16)(pack2(f, 0.f) & 0xffffu); }
; __device__ __forceinline__ void elem_item(const Params& p, int it) {
;     ...
;   if (it < 32) {
; #pragma unroll
;     for (int i = 0; i < 4; ++i) {
;       const int idx = it * 1024 + i * 256 + t;
;       const int k1 = idx >> 8, kk = idx & 255, ri = kk >> 7, n1 = kk & 127;
;       const int ph = (k1 * n1) & 127;
;       const float xx = (float)ph / 64.f;
;       p.M2[idx] = f2bf(ri ? sinpif(xx) : cospif(xx));
;     }
;     return;
.LBB0_90:
	s_or_b64 exec, exec, s[6:7]
	v_cmp_lg_f32_e64 s[4:5], s14, v5
	s_nop 1
	v_cndmask_b32_e64 v5, v7, v15, s[4:5]
	v_cvt_pk_bf16_f32 v12, v5, s0
	v_ashrrev_i32_e32 v5, 31, v4
	s_waitcnt vmcnt(0) lgkmcnt(0)
	v_lshl_add_u64 v[2:3], v[4:5], 1, v[2:3]
	v_add_u32_e32 v4, 0x8100, v9
	v_lshrrev_b32_e32 v4, 8, v4
	v_mul_lo_u32 v4, v4, v8
	v_and_b32_e32 v4, 0x7f, v4
	v_cvt_f32_ubyte0_e32 v4, v4
	v_mul_f32_e32 v4, 0x3c800000, v4
	v_mul_f32_e32 v5, 0.5, v4
	v_fract_f32_e32 v10, v5
	v_add_f32_e32 v10, v10, v10
	v_cmp_neq_f32_e64 s[4:5], s14, v5
	global_store_short v[2:3], v12, off
	s_nop 0
	v_cndmask_b32_e64 v5, 0, v10, s[4:5]
	v_cmp_lt_f32_e64 s[4:5], 1.0, v4
	s_nop 1
	v_cndmask_b32_e64 v11, v4, v5, s[4:5]
	v_add_f32_e32 v5, v11, v11
	v_rndne_f32_e32 v5, v5
	v_cvt_i32_f32_e32 v10, v5
	v_fmac_f32_e32 v11, -0.5, v5
	v_mul_f32_e32 v5, v11, v11
	v_fmamk_f32 v16, v5, 0x3e75aa41, v1
	v_and_b32_e32 v12, 1, v10
	v_mul_f32_e32 v15, v11, v5
	v_fmamk_f32 v13, v5, 0x3d4be544, v6
	s_and_saveexec_b64 s[4:5], vcc
	s_xor_b64 s[6:7], exec, s[4:5]
	s_cbranch_execz .LBB0_92
	v_fmaak_f32 v14, v5, v16, 0x40234736
	v_fmaak_f32 v14, v5, v14, 0xc0a55e0e
	v_mul_f32_e32 v14, v15, v14
	v_fmac_f32_e32 v14, 0x40490fdb, v11
	v_fmaak_f32 v11, v5, v13, 0xbfaad1da
	v_fmaak_f32 v11, v5, v11, 0x4081e0d3
	v_fmaak_f32 v11, v5, v11, 0xc09de9e6
	v_fma_f32 v5, v5, v11, 1.0
	v_cmp_eq_u32_e64 s[4:5], 0, v12
	v_lshlrev_b32_e32 v10, 30, v10
	s_nop 0
	v_cndmask_b32_e64 v5, v5, v14, s[4:5]
	v_bitop3_b32 v14, v10, v5, s15 bitop3:0x6c

; __device__ __forceinline__ u16 f2bf(float f) { return (u16)(pack2(f, 0.f) & 0xffffu); }
; __device__ __forceinline__ void elem_item(const Params& p, int it) {
;     ...
;   if (it < 32) {
; #pragma unroll
;     for (int i = 0; i < 4; ++i) {
;       const int idx = it * 1024 + i * 256 + t;
;       const int k1 = idx >> 8, kk = idx & 255, ri = kk >> 7, n1 = kk & 127;
;       const int ph = (k1 * n1) & 127;
;       const float xx = (float)ph / 64.f;
;       p.M2[idx] = f2bf(ri ? sinpif(xx) : cospif(xx));
;     }
;     return;
.LBB0_94:
	s_or_b64 exec, exec, s[6:7]
	v_cmp_lg_f32_e64 s[4:5], s14, v4
	s_nop 1
	v_cndmask_b32_e64 v4, v7, v14, s[4:5]
	v_cvt_pk_bf16_f32 v5, v4, s0
	v_add_u32_e32 v4, 0x8200, v9
	v_lshrrev_b32_e32 v4, 8, v4
	v_mul_lo_u32 v4, v4, v8
	v_and_b32_e32 v4, 0x7f, v4
	v_cvt_f32_ubyte0_e32 v4, v4
	v_mul_f32_e32 v4, 0x3c800000, v4
	v_mul_f32_e32 v10, 0.5, v4
	v_fract_f32_e32 v11, v10
	v_add_f32_e32 v11, v11, v11
	v_cmp_neq_f32_e64 s[4:5], s14, v10
	global_store_short v[2:3], v5, off offset:512
	s_nop 0
	v_cndmask_b32_e64 v10, 0, v11, s[4:5]
	v_cmp_lt_f32_e64 s[4:5], 1.0, v4
	s_nop 1
	v_cndmask_b32_e64 v11, v4, v10, s[4:5]
	v_add_f32_e32 v10, v11, v11
	v_rndne_f32_e32 v12, v10
	v_cvt_i32_f32_e32 v10, v12
	v_fmac_f32_e32 v11, -0.5, v12
	v_mul_f32_e32 v5, v11, v11
	v_fmamk_f32 v16, v5, 0x3e75aa41, v1
	v_and_b32_e32 v12, 1, v10
	v_mul_f32_e32 v15, v11, v5
	v_fmamk_f32 v13, v5, 0x3d4be544, v6
	s_and_saveexec_b64 s[4:5], vcc
	s_xor_b64 s[6:7], exec, s[4:5]
	s_cbranch_execz .LBB0_96
	v_fmaak_f32 v14, v5, v16, 0x40234736
	v_fmaak_f32 v14, v5, v14, 0xc0a55e0e
	v_mul_f32_e32 v14, v15, v14
	v_fmac_f32_e32 v14, 0x40490fdb, v11
	v_fmaak_f32 v11, v5, v13, 0xbfaad1da
	v_fmaak_f32 v11, v5, v11, 0x4081e0d3
	v_fmaak_f32 v11, v5, v11, 0xc09de9e6
	v_fma_f32 v5, v5, v11, 1.0
	v_cmp_eq_u32_e64 s[4:5], 0, v12
	v_lshlrev_b32_e32 v10, 30, v10
	s_nop 0
	v_cndmask_b32_e64 v5, v5, v14, s[4:5]
	v_bitop3_b32 v14, v10, v5, s15 bitop3:0x6c

; __device__ __forceinline__ u16 f2bf(float f) { return (u16)(pack2(f, 0.f) & 0xffffu); }
; __device__ __forceinline__ void elem_item(const Params& p, int it) {
;     ...
;   if (it < 32) {
; #pragma unroll
;     for (int i = 0; i < 4; ++i) {
;       const int idx = it * 1024 + i * 256 + t;
;       const int k1 = idx >> 8, kk = idx & 255, ri = kk >> 7, n1 = kk & 127;
;       const int ph = (k1 * n1) & 127;
;       const float xx = (float)ph / 64.f;
;       p.M2[idx] = f2bf(ri ? sinpif(xx) : cospif(xx));
;     }
;     return;
.LBB0_98:
	s_or_b64 exec, exec, s[6:7]
	v_cmp_lg_f32_e64 s[4:5], s14, v4
	s_nop 1
	v_cndmask_b32_e64 v4, v7, v14, s[4:5]
	v_cvt_pk_bf16_f32 v5, v4, s0
	v_add_u32_e32 v4, 0x8300, v9
	v_lshrrev_b32_e32 v4, 8, v4
	v_mul_lo_u32 v4, v4, v8
	v_and_b32_e32 v4, 0x7f, v4
	v_cvt_f32_ubyte0_e32 v4, v4
	v_mul_f32_e32 v4, 0x3c800000, v4
	v_mul_f32_e32 v9, 0.5, v4
	v_fract_f32_e32 v10, v9
	v_add_f32_e32 v10, v10, v10
	v_cmp_neq_f32_e64 s[4:5], s14, v9
	global_store_short v[2:3], v5, off offset:1024
	s_nop 0
	v_cndmask_b32_e64 v9, 0, v10, s[4:5]
	v_cmp_lt_f32_e64 s[4:5], 1.0, v4
	s_nop 1
	v_cndmask_b32_e64 v10, v4, v9, s[4:5]
	v_add_f32_e32 v9, v10, v10
	v_rndne_f32_e32 v11, v9
	v_cvt_i32_f32_e32 v9, v11
	v_fmac_f32_e32 v10, -0.5, v11
	v_mul_f32_e32 v5, v10, v10
	v_fmamk_f32 v15, v5, 0x3e75aa41, v1
	v_and_b32_e32 v11, 1, v9
	v_mul_f32_e32 v14, v10, v5
	v_fmamk_f32 v12, v5, 0x3d4be544, v6
	s_and_saveexec_b64 s[4:5], vcc
	s_xor_b64 s[4:5], exec, s[4:5]
	s_cbranch_execz .LBB0_100
	v_fmaak_f32 v13, v5, v15, 0x40234736
	v_fmaak_f32 v13, v5, v13, 0xc0a55e0e
	v_mul_f32_e32 v13, v14, v13
	v_fmac_f32_e32 v13, 0x40490fdb, v10
	v_fmaak_f32 v10, v5, v12, 0xbfaad1da
	v_fmaak_f32 v10, v5, v10, 0x4081e0d3
	v_fmaak_f32 v10, v5, v10, 0xc09de9e6
	v_fma_f32 v5, v5, v10, 1.0
	v_cmp_eq_u32_e32 vcc, 0, v11
	v_lshlrev_b32_e32 v9, 30, v9
	s_nop 0
	v_cndmask_b32_e32 v5, v5, v13, vcc
	v_bitop3_b32 v13, v9, v5, s15 bitop3:0x6c

; __device__ __forceinline__ u16 f2bf(float f) { return (u16)(pack2(f, 0.f) & 0xffffu); }
; __device__ __forceinline__ void elem_item(const Params& p, int it) {
;     ...
;       p.M2[idx] = f2bf(ri ? sinpif(xx) : cospif(xx));
;     }
;     return;
.LBB0_102:
	s_or_b64 exec, exec, s[4:5]
	v_cmp_lg_f32_e32 vcc, s14, v4
	s_nop 1
	v_cndmask_b32_e32 v4, v7, v13, vcc
	v_cvt_pk_bf16_f32 v4, v4, s0
	global_store_short v[2:3], v4, off offset:1536

; __device__ __forceinline__ u16 f2bf(float f) { return (u16)(pack2(f, 0.f) & 0xffffu); }
; __device__ __forceinline__ void elem_item(const Params& p, int it) {
;     ...
;   if (it < 2048) {
; #pragma unroll
;     for (int i = 0; i < 4; ++i) {
;       const int idx = it * 1024 + i * 256 + t;
;       const int n1 = idx >> 14, m = (idx >> 7) & 127, kk = idx & 127;
;       const int rip = m >> 6, k2 = m & 63, ri = kk >> 6, n2 = kk & 63;
;       const int n = n1 + 128 * n2;
;       const int ph = (k2 * n) & 8191;
;       const float xx = (float)ph / 4096.f;
;       const float cs = cospif(xx), sn = sinpif(xx);
;       const float v = rip == 0 ? (ri == 0 ? cs : sn) : (ri == 0 ? -sn : cs);
;       p.M1[idx] = f2bf(v);
;     }
;     return;
;   }
.LBB0_104:
	s_andn2_b64 vcc, exec, s[4:5]
	s_cbranch_vccnz .LBB0_106
	v_mov_b64_e32 v[2:3], s[10:11]
	global_load_dwordx2 v[2:3], v[2:3], off offset:248
	v_add_u32_e32 v14, s12, v8
	v_add_u32_e32 v4, 0x208000, v14
	v_add_u32_e32 v15, 0x208100, v14
	v_lshlrev_b32_e32 v9, 7, v8
	v_lshrrev_b32_e32 v5, 14, v4
	v_lshrrev_b32_e32 v10, 14, v15
	v_lshrrev_b32_e32 v11, 7, v4
	v_lshrrev_b32_e32 v12, 7, v15
	v_and_b32_e32 v11, 63, v11
	v_and_b32_e32 v12, 63, v12
	v_add_u32_e32 v10, v10, v9
	v_add_u32_e32 v5, v5, v9
	v_mul_lo_u32 v5, v11, v5
	v_mul_lo_u32 v10, v12, v10
	v_and_b32_e32 v5, 0x1fff, v5
	v_and_b32_e32 v10, 0x1fff, v10
	v_cvt_f32_u32_e32 v11, v5
	v_cvt_f32_u32_e32 v10, v10
	v_and_b32_e32 v16, 64, v8
	v_and_b32_e32 v17, 0x2000, v4
	v_cmp_eq_u32_e64 s[4:5], 0, v17
	v_pk_mul_f32 v[10:11], v[10:11], s[0:1] op_sel_hi:[1,0]
	v_ashrrev_i32_e32 v5, 31, v4
	v_pk_mul_f32 v[12:13], v[10:11], 0.5 op_sel_hi:[1,0]
	s_waitcnt vmcnt(0) lgkmcnt(0)
; __device__ __forceinline__ u16 f2bf(float f) { return (u16)(pack2(f, 0.f) & 0xffffu); }
; __device__ __forceinline__ void elem_item(const Params& p, int it) {
;     ...
;     for (int i = 0; i < 4; ++i) {
;       const int idx = it * 1024 + i * 256 + t;
;       const int n1 = idx >> 14, m = (idx >> 7) & 127, kk = idx & 127;
;       const int rip = m >> 6, k2 = m & 63, ri = kk >> 6, n2 = kk & 63;
;       const int n = n1 + 128 * n2;
;       const int ph = (k2 * n) & 8191;
;       const float xx = (float)ph / 4096.f;
;       const float cs = cospif(xx), sn = sinpif(xx);
;       const float v = rip == 0 ? (ri == 0 ? cs : sn) : (ri == 0 ? -sn : cs);
;       p.M1[idx] = f2bf(v);
;     }
	v_lshl_add_u64 v[4:5], v[4:5], 1, v[2:3]
	v_fract_f32_e32 v18, v13
	v_fract_f32_e32 v19, v12
	v_add_f32_e32 v18, v18, v18
	v_cmp_neq_f32_e32 vcc, s14, v13
	v_add_f32_e32 v19, v19, v19
	s_nop 0
	v_cndmask_b32_e32 v13, 0, v18, vcc
	v_cmp_neq_f32_e32 vcc, s14, v12
	s_nop 1
	v_cndmask_b32_e32 v12, 0, v19, vcc
	v_cmp_lt_f32_e32 vcc, 1.0, v11
	s_nop 1
	v_cndmask_b32_e32 v13, v11, v13, vcc
	v_add_f32_e32 v18, v13, v13
	v_rndne_f32_e32 v18, v18
	v_fmac_f32_e32 v13, -0.5, v18
	v_cvt_i32_f32_e32 v18, v18
	v_mul_f32_e32 v20, v13, v13
	v_fmamk_f32 v22, v20, 0x3e75aa41, v1
	v_fmamk_f32 v24, v20, 0x3d4be544, v6
	v_fmaak_f32 v22, v20, v22, 0x40234736
	v_fmaak_f32 v24, v20, v24, 0xbfaad1da
	v_cmp_lt_f32_e32 vcc, 1.0, v10
	v_mul_f32_e32 v23, v13, v20
	v_fmaak_f32 v22, v20, v22, 0xc0a55e0e
	v_fmaak_f32 v24, v20, v24, 0x4081e0d3
	v_cndmask_b32_e32 v12, v10, v12, vcc
	v_and_b32_e32 v28, 1, v18
	v_mul_f32_e32 v22, v23, v22
	v_fmaak_f32 v23, v20, v24, 0xc09de9e6
	v_add_f32_e32 v19, v12, v12
	v_and_b32_e32 v27, 2, v18
	v_fmac_f32_e32 v22, 0x40490fdb, v13
	v_fma_f32 v13, v20, v23, 1.0
	v_cmp_eq_u32_e32 vcc, 0, v28
	v_rndne_f32_e32 v19, v19
	v_lshlrev_b32_e32 v18, 30, v18
	v_cndmask_b32_e64 v20, -v22, v13, vcc
	v_cndmask_b32_e32 v13, v13, v22, vcc
	v_cmp_eq_u32_e32 vcc, 0, v27
	v_fmac_f32_e32 v12, -0.5, v19
	v_bitop3_b32 v13, v18, v13, s15 bitop3:0x6c
	v_cndmask_b32_e64 v20, -v20, v20, vcc
	v_cmp_lg_f32_e32 vcc, s14, v11
	v_mul_f32_e32 v21, v12, v12
	v_fmamk_f32 v25, v21, 0x3e75aa41, v1
	v_cndmask_b32_e32 v11, v7, v20, vcc
	v_cndmask_b32_e32 v13, v7, v13, vcc
	v_cmp_eq_u32_e32 vcc, 0, v16
	v_fmaak_f32 v25, v21, v25, 0x40234736
	v_mul_f32_e32 v26, v12, v21
	v_cndmask_b32_e32 v16, v13, v11, vcc
	v_cndmask_b32_e64 v11, v11, -v13, vcc
	v_cndmask_b32_e64 v11, v11, v16, s[4:5]
	v_fmaak_f32 v25, v21, v25, 0xc0a55e0e
	v_cvt_pk_bf16_f32 v11, v11, s0
	v_cvt_i32_f32_e32 v19, v19
	global_store_short v[4:5], v11, off
	v_mul_f32_e32 v11, v26, v25
	v_fmac_f32_e32 v11, 0x40490fdb, v12
	v_fmamk_f32 v12, v21, 0x3d4be544, v6
	v_fmaak_f32 v12, v21, v12, 0xbfaad1da
	v_fmaak_f32 v12, v21, v12, 0x4081e0d3
	v_fmaak_f32 v12, v21, v12, 0xc09de9e6
	v_and_b32_e32 v13, 1, v19
	v_and_b32_e32 v29, 2, v19
	v_fma_f32 v12, v21, v12, 1.0
	v_cmp_eq_u32_e64 s[4:5], 0, v13
	v_cmp_eq_u32_e64 s[6:7], 0, v29
	v_and_b32_e32 v16, 0x2000, v15
	v_cndmask_b32_e64 v13, -v11, v12, s[4:5]
	v_cndmask_b32_e64 v13, -v13, v13, s[6:7]
	v_cmp_lg_f32_e64 s[6:7], s14, v10
	v_cndmask_b32_e64 v10, v12, v11, s[4:5]
	v_lshlrev_b32_e32 v11, 30, v19
	v_bitop3_b32 v10, v11, v10, s15 bitop3:0x6c
	v_cndmask_b32_e64 v11, v7, v10, s[6:7]
	v_add_u32_e32 v10, 0x208300, v14
	v_add_u32_e32 v12, 0x208200, v14
	v_lshrrev_b32_e32 v14, 14, v12
	v_lshrrev_b32_e32 v15, 14, v10
	v_lshrrev_b32_e32 v18, 7, v12
	v_lshrrev_b32_e32 v19, 7, v10
	v_and_b32_e32 v18, 63, v18
	v_and_b32_e32 v19, 63, v19
	v_add_u32_e32 v15, v15, v9
	v_add_u32_e32 v9, v14, v9
	v_mul_lo_u32 v9, v18, v9
	v_mul_lo_u32 v14, v19, v15
	v_and_b32_e32 v9, 0x1fff, v9
	v_and_b32_e32 v14, 0x1fff, v14
	v_cvt_f32_u32_e32 v15, v9
	v_cvt_f32_u32_e32 v14, v14
	v_cndmask_b32_e64 v13, v7, v13, s[6:7]
	v_cndmask_b32_e32 v17, v11, v13, vcc
	v_cndmask_b32_e64 v9, v13, -v11, vcc
	v_cmp_eq_u32_e64 s[4:5], 0, v16
	v_pk_mul_f32 v[14:15], v[14:15], s[0:1] op_sel_hi:[1,0]
	s_nop 0
	v_cndmask_b32_e64 v9, v9, v17, s[4:5]
	v_pk_mul_f32 v[16:17], v[14:15], 0.5 op_sel_hi:[1,0]
	v_cvt_pk_bf16_f32 v9, v9, s0
	v_fract_f32_e32 v11, v17
	v_add_f32_e32 v11, v11, v11
	v_cmp_neq_f32_e64 s[4:5], s14, v17
	global_store_short v[4:5], v9, off offset:512
	s_nop 0
	v_cndmask_b32_e64 v11, 0, v11, s[4:5]
	v_cmp_lt_f32_e64 s[4:5], 1.0, v15
	s_nop 1
	v_cndmask_b32_e64 v11, v15, v11, s[4:5]
	v_add_f32_e32 v13, v11, v11
	v_rndne_f32_e32 v13, v13
	v_fmac_f32_e32 v11, -0.5, v13
	v_mul_f32_e32 v5, v11, v11
	v_fmamk_f32 v9, v5, 0x3e75aa41, v1
	v_fmaak_f32 v9, v5, v9, 0x40234736
	v_cvt_i32_f32_e32 v17, v13
	v_fmaak_f32 v9, v5, v9, 0xc0a55e0e
	v_mul_f32_e32 v13, v11, v5
	v_mul_f32_e32 v9, v13, v9
	v_fmac_f32_e32 v9, 0x40490fdb, v11
	v_fmamk_f32 v11, v5, 0x3d4be544, v6
	v_fmaak_f32 v11, v5, v11, 0xbfaad1da
	v_fmaak_f32 v11, v5, v11, 0x4081e0d3
	v_fmaak_f32 v11, v5, v11, 0xc09de9e6
	v_fma_f32 v5, v5, v11, 1.0
	v_and_b32_e32 v11, 1, v17
	v_and_b32_e32 v4, 2, v17
	v_cmp_eq_u32_e64 s[4:5], 0, v11
	v_cmp_eq_u32_e64 s[6:7], 0, v4
	v_ashrrev_i32_e32 v13, 31, v12
	v_cndmask_b32_e64 v11, -v9, v5, s[4:5]
	v_cndmask_b32_e64 v5, v5, v9, s[4:5]
	v_lshlrev_b32_e32 v9, 30, v17
	v_cndmask_b32_e64 v4, -v11, v11, s[6:7]
	v_cmp_lg_f32_e64 s[6:7], s14, v15
	v_bitop3_b32 v5, v9, v5, s15 bitop3:0x6c
	v_and_b32_e32 v9, 0x2000, v12
	v_cndmask_b32_e64 v4, v7, v4, s[6:7]
	v_cndmask_b32_e64 v5, v7, v5, s[6:7]
	v_cndmask_b32_e32 v11, v5, v4, vcc
	v_cndmask_b32_e64 v4, v4, -v5, vcc
	v_cmp_eq_u32_e64 s[4:5], 0, v9
	s_nop 1
	v_cndmask_b32_e64 v4, v4, v11, s[4:5]
	v_cvt_pk_bf16_f32 v9, v4, s0
	v_fract_f32_e32 v4, v16
	v_add_f32_e32 v4, v4, v4
	v_cmp_neq_f32_e64 s[4:5], s14, v16
	s_nop 1
	v_cndmask_b32_e64 v4, 0, v4, s[4:5]
	v_cmp_lt_f32_e64 s[4:5], 1.0, v14
	s_nop 1
	v_cndmask_b32_e64 v11, v14, v4, s[4:5]
	v_add_f32_e32 v4, v11, v11
	v_rndne_f32_e32 v15, v4
	v_lshl_add_u64 v[4:5], v[12:13], 1, v[2:3]
	v_fmac_f32_e32 v11, -0.5, v15
	global_store_short v[4:5], v9, off
	v_mul_f32_e32 v5, v11, v11
	v_fmamk_f32 v9, v5, 0x3e75aa41, v1
	v_fmaak_f32 v9, v5, v9, 0x40234736
	v_fmaak_f32 v9, v5, v9, 0xc0a55e0e
	v_mul_f32_e32 v12, v11, v5
	v_mul_f32_e32 v9, v12, v9
	v_cvt_i32_f32_e32 v16, v15
	v_fmac_f32_e32 v9, 0x40490fdb, v11
	v_fmamk_f32 v11, v5, 0x3d4be544, v6
	v_fmaak_f32 v11, v5, v11, 0xbfaad1da
	v_fmaak_f32 v11, v5, v11, 0x4081e0d3
	v_fmaak_f32 v11, v5, v11, 0xc09de9e6
	v_fma_f32 v5, v5, v11, 1.0
	v_and_b32_e32 v11, 1, v16
	v_and_b32_e32 v4, 2, v16
	v_cmp_eq_u32_e64 s[4:5], 0, v11
	v_cmp_eq_u32_e64 s[6:7], 0, v4
	s_nop 0
	v_cndmask_b32_e64 v11, -v9, v5, s[4:5]
	v_cndmask_b32_e64 v5, v5, v9, s[4:5]
	v_lshlrev_b32_e32 v9, 30, v16
	v_cndmask_b32_e64 v4, -v11, v11, s[6:7]
	v_cmp_lg_f32_e64 s[6:7], s14, v14
	v_bitop3_b32 v5, v9, v5, s15 bitop3:0x6c
	v_and_b32_e32 v9, 0x2000, v10
	v_cndmask_b32_e64 v4, v7, v4, s[6:7]
	v_cndmask_b32_e64 v5, v7, v5, s[6:7]
	v_cndmask_b32_e32 v11, v5, v4, vcc
	v_cndmask_b32_e64 v4, v4, -v5, vcc
	v_cmp_eq_u32_e32 vcc, 0, v9
	s_nop 1
	v_cndmask_b32_e32 v4, v4, v11, vcc
	v_ashrrev_i32_e32 v11, 31, v10
	v_cvt_pk_bf16_f32 v4, v4, s0
	v_lshl_add_u64 v[2:3], v[10:11], 1, v[2:3]
	global_store_short v[2:3], v4, off

; __device__ __forceinline__ u16 f2bf(float f) { return (u16)(pack2(f, 0.f) & 0xffffu); }
; __device__ __forceinline__ int tid_() { int t = threadIdx.x; asm volatile("" : "+v"(t)); return t; }
; __device__ __forceinline__ void elem_item(const Params& p, int it) {
;   const int t = tid_();
;   if (it < 128) {
; #pragma unroll
;     for (int i = 0; i < 4; ++i) { const int idx = it * 1024 + i * 256 + t; p.Wsgu[idx] = f2bf(p.w_sgu[idx]); }
;     return;
;   }
.LBB0_107:
	s_andn2_b64 vcc, exec, s[4:5]
	s_cbranch_vccnz .LBB0_64
	v_mov_b64_e32 v[2:3], s[10:11]
	global_load_dwordx2 v[4:5], v[2:3], off offset:64
	v_add_u32_e32 v8, s12, v8
	v_add_u32_e32 v8, 0x228000, v8
	v_ashrrev_i32_e32 v9, 31, v8
	global_load_dwordx2 v[2:3], v[2:3], off offset:240
	s_waitcnt vmcnt(0) lgkmcnt(0)
	v_lshl_add_u64 v[4:5], v[8:9], 2, v[4:5]
	global_load_dword v10, v[4:5], off
	global_load_dword v11, v[4:5], off offset:1024
	global_load_dword v12, v[4:5], off offset:2048
	global_load_dword v13, v[4:5], off offset:3072
	v_lshl_add_u64 v[2:3], v[8:9], 1, v[2:3]
	s_waitcnt vmcnt(0) lgkmcnt(0)
	v_cvt_pk_bf16_f32 v4, v10, s0
	v_cvt_pk_bf16_f32 v5, v11, s0
	v_cvt_pk_bf16_f32 v8, v12, s0
	v_cvt_pk_bf16_f32 v9, v13, s0
	global_store_short v[2:3], v4, off
	global_store_short v[2:3], v5, off offset:512
	global_store_short v[2:3], v8, off offset:1024
	global_store_short v[2:3], v9, off offset:1536
	s_branch .LBB0_64

; __device__ __forceinline__ int tid_() { int t = threadIdx.x; asm volatile("" : "+v"(t)); return t; }
; __device__ __forceinline__ int bid_() { int b = blockIdx.x; asm volatile("" : "+s"(b)); return b; }
; __device__ __forceinline__ void phase_router_prep(const Params& p) {
;   const int t = tid_(), lane = t & 63, wid = t >> 6;
;   for (int i = bid_() * 256 + t; i < 2 * 3 * 16384; i += gridDim.x * 256) {
;     const int lc = i >> 14, k = (i >> 4) & 1023, e = i & 15, l = lc / 3;
;     p.WR2[i] = (1.f + p.mada[(size_t)lc * 6144 + 4 * 1024 + k]) * p.w_router[(size_t)l * 16384 + k * 16 + e];
;   }
;   for (int o = bid_() * 4 + wid; o < 96; o += gridDim.x * 4) {
;     const int lc = o >> 4, e = o & 15, l = lc / 3;
;     float s = 0.f;
;     for (int k = lane; k < 1024; k += 64) s += p.mada[(size_t)lc * 6144 + 3 * 1024 + k] * p.w_router[(size_t)l * 16384 + k * 16 + e];
;     s = wave_sum(s);
;     if (lane == 0) p.CE[o] = s;
;   }
.LBB0_139:
	s_and_b64 vcc, exec, s[86:87]
	s_mov_b64 s[0:1], -1
	s_cbranch_vccnz .LBB0_156
	s_mov_b64 s[0:1], s[64:65]
	v_mov_b32_e32 v12, v187
	s_mov_b32 s8, s2
	s_nop 0
	v_lshl_add_u32 v2, s8, 8, v12
	v_cmp_gt_i32_e32 vcc, s55, v2
	s_and_saveexec_b64 s[38:39], vcc
	s_cbranch_execz .LBB0_143
	v_mov_b64_e32 v[8:9], s[0:1]
	global_load_dwordx2 v[4:5], v[8:9], off offset:184
	global_load_dwordx2 v[6:7], v[8:9], off offset:392
	s_nop 0
	global_load_dwordx2 v[8:9], v[8:9], off offset:136
	v_and_b32_e32 v0, 15, v12
	s_mov_b64 s[40:41], 0
	v_lshlrev_b32_e32 v10, 2, v0
	v_mov_b32_e32 v11, v1
.LBB0_142:
	v_ashrrev_i32_e32 v0, 14, v2
	v_mul_i32_i24_e32 v16, 0x1800, v0
	v_bfe_u32 v3, v2, 4, 10
	v_ashrrev_i32_e32 v17, 31, v16
	v_mul_hi_i32 v13, v0, s61
	s_waitcnt vmcnt(0) lgkmcnt(0)
	v_lshl_add_u64 v[16:17], v[16:17], 2, v[4:5]
	v_lshlrev_b32_e32 v0, 2, v3
	v_lshl_add_u64 v[16:17], v[16:17], 0, v[0:1]
	v_add_co_u32_e32 v16, vcc, 0x4000, v16
	v_lshrrev_b32_e32 v14, 31, v13
	s_nop 0
	v_addc_co_u32_e32 v17, vcc, 0, v17, vcc
	global_load_dword v0, v[16:17], off
	v_add_u32_e32 v14, v13, v14
	v_ashrrev_i32_e32 v15, 31, v14
	v_lshlrev_b64 v[14:15], 16, v[14:15]
	v_lshl_add_u64 v[14:15], v[8:9], 0, v[14:15]
	s_mov_b32 s8, 0x17fff
	s_waitcnt vmcnt(0) lgkmcnt(0)
	v_add_f32_e32 v13, 1.0, v0
	v_lshlrev_b32_e32 v0, 6, v3
	v_lshl_add_u64 v[14:15], v[14:15], 0, v[0:1]
	v_lshl_add_u64 v[14:15], v[14:15], 0, v[10:11]
	global_load_dword v0, v[14:15], off
	v_ashrrev_i32_e32 v3, 31, v2
	v_lshl_add_u64 v[14:15], v[2:3], 2, v[6:7]
	v_add_u32_e32 v2, s90, v2
	v_cmp_lt_i32_e32 vcc, s8, v2
	s_or_b64 s[40:41], vcc, s[40:41]
	s_waitcnt vmcnt(0) lgkmcnt(0)
	v_mul_f32_e32 v0, v13, v0
	global_store_dword v[14:15], v0, off
	s_andn2_b64 exec, exec, s[40:41]
	s_cbranch_execnz .LBB0_142
.LBB0_143:
	s_or_b64 exec, exec, s[38:39]
	v_ashrrev_i32_e32 v0, 6, v12
	s_mov_b32 s8, s2
	s_movk_i32 s9, 0x60
	v_lshl_add_u32 v2, s8, 2, v0
	v_cmp_gt_i32_e32 vcc, s9, v2
	s_and_saveexec_b64 s[40:41], vcc
	s_cbranch_execz .LBB0_150
	v_mov_b64_e32 v[4:5], s[0:1]
	global_load_dwordx2 v[6:7], v[4:5], off offset:136
	global_load_dwordx2 v[8:9], v[4:5], off offset:184
	s_nop 0
	global_load_dwordx2 v[4:5], v[4:5], off offset:400
	v_cmp_lt_i32_e32 vcc, v249, v227
	v_and_b32_e32 v3, 63, v12
	v_lshrrev_b32_e32 v10, 6, v12
	v_cndmask_b32_e32 v0, v186, v249, vcc
	v_cmp_lt_i32_e32 vcc, v250, v227
	v_lshlrev_b32_e32 v14, 2, v0
	v_lshlrev_b32_e32 v0, 6, v3
	v_cndmask_b32_e32 v11, v186, v250, vcc
	v_cmp_lt_i32_e32 vcc, v251, v227
	s_lshl_b32 s0, s8, 2
	v_add_u16_e32 v21, s0, v10
	v_cndmask_b32_e32 v12, v186, v251, vcc
	v_cmp_lt_i32_e32 vcc, v252, v227
	s_mov_b64 s[0:1], 0x3000
	v_lshlrev_b32_e32 v15, 2, v11
	v_cndmask_b32_e32 v13, v186, v252, vcc
	v_cmp_lt_i32_e32 vcc, v253, v227
	v_lshlrev_b32_e32 v16, 2, v12
	v_lshlrev_b32_e32 v17, 2, v13
	v_cndmask_b32_e32 v18, v186, v253, vcc
	v_cmp_lt_i32_e32 vcc, v212, v227
	v_lshlrev_b32_e32 v18, 2, v18
	v_or_b32_e32 v20, 0xffffffc0, v3
	v_cndmask_b32_e32 v19, v186, v212, vcc
	v_lshlrev_b32_e32 v19, 2, v19
	v_cmp_eq_u32_e32 vcc, 0, v3
	s_waitcnt vmcnt(0) lgkmcnt(0)
	v_lshl_add_u64 v[6:7], v[6:7], 0, v[0:1]
	v_lshlrev_b32_e32 v0, 2, v3
	v_lshl_add_u64 v[8:9], v[8:9], 0, v[0:1]
	v_lshl_add_u64 v[8:9], v[8:9], 0, s[0:1]
	s_mov_b64 s[0:1], 0
	s_branch .LBB0_146

; __device__ __forceinline__ int bid_() { int b = blockIdx.x; asm volatile("" : "+s"(b)); return b; }
; __device__ __forceinline__ void phase_router_prep(const Params& p) {
;     ...
;   for (int o = bid_() * 4 + wid; o < 96; o += gridDim.x * 4) {
;     const int lc = o >> 4, e = o & 15, l = lc / 3;
;     float s = 0.f;
;     for (int k = lane; k < 1024; k += 64) s += p.mada[(size_t)lc * 6144 + 3 * 1024 + k] * p.w_router[(size_t)l * 16384 + k * 16 + e];
;     s = wave_sum(s);
;     if (lane == 0) p.CE[o] = s;
;   }
.LBB0_147:
	global_load_dword v22, v[12:13], off
	global_load_dword v23, v[10:11], off
	v_add_u32_e32 v3, 64, v3
	s_movk_i32 s18, 0x3bf
	v_cmp_lt_u32_e64 s[38:39], s18, v3
	v_lshl_add_u64 v[10:11], v[10:11], 0, s[92:93]
	v_lshl_add_u64 v[12:13], v[12:13], 0, s[6:7]
	s_or_b64 s[8:9], s[38:39], s[8:9]
	s_waitcnt vmcnt(0) lgkmcnt(0)
	v_fmac_f32_e32 v0, v22, v23
	s_andn2_b64 exec, exec, s[8:9]
	s_cbranch_execnz .LBB0_147
	s_or_b64 exec, exec, s[8:9]
	ds_bpermute_b32 v3, v14, v0
	s_waitcnt lgkmcnt(0)
	v_add_f32_e32 v0, v0, v3
	ds_bpermute_b32 v3, v15, v0
	s_waitcnt lgkmcnt(0)
	v_add_f32_e32 v0, v0, v3
	ds_bpermute_b32 v3, v16, v0
	s_waitcnt lgkmcnt(0)
	v_add_f32_e32 v0, v0, v3
	ds_bpermute_b32 v3, v17, v0
	s_waitcnt lgkmcnt(0)
	v_add_f32_e32 v0, v0, v3
	ds_bpermute_b32 v3, v18, v0
	s_waitcnt lgkmcnt(0)
	v_add_f32_e32 v0, v0, v3
	ds_bpermute_b32 v10, v19, v0
	s_and_saveexec_b64 s[8:9], vcc
	s_cbranch_execz .LBB0_145
	v_ashrrev_i32_e32 v3, 31, v2
	v_lshl_add_u64 v[12:13], v[2:3], 2, v[4:5]
	s_waitcnt lgkmcnt(0)
	v_add_f32_e32 v0, v0, v10
	global_store_dword v[12:13], v0, off
	s_branch .LBB0_145

; template <bool COMBINE, bool MOD>
; __device__ __forceinline__ void phase_combine_modulate(const Params& p, int lprev, int lnext, const float* xlat, const float* xctx,
;                                                        float* olat, float* octx, int nrows) {
;     ...
;     const bool lat = row0 < T_LAT;
;     const float* xr = lat ? xlat + (size_t)row0 * DM : xctx + (size_t)(row0 - T_LAT) * DM;
;     const int cond = row_cond(row0);
;     float4 v[R][4];
; #pragma unroll
;     for (int r = 0; r < R; ++r)
; #pragma unroll
;       for (int i = 0; i < 4; ++i) v[r][i] = *(const float4*)(xr + (size_t)r * DM + i * 256 + lane * 4);
;     ...
;       const float* sh = p.mada + (size_t)(lnext * 3 + cond) * 6144;
;       const float* sc = sh + 1024;
;       float rstd[R];
; #pragma unroll
;       for (int r = 0; r < R; ++r) {
;         float ss = 0.f;
; #pragma unroll
;         for (int i = 0; i < 4; ++i) ss += v[r][i].x * v[r][i].x + v[r][i].y * v[r][i].y + v[r][i].z * v[r][i].z + v[r][i].w * v[r][i].w;
;         rstd[r] = rsqrtf(wave_sum(ss) * (1.f / 1024.f) + 1e-6f);
;       }
.LBB0_152:
	s_or_b64 exec, exec, s[0:1]
	global_load_dwordx2 v[6:7], v[46:47], off offset:184
	v_min_i32_e32 v0, 0x4000, v38
	v_ashrrev_i32_e32 v0, 13, v0
	v_mul_hi_i32_i24_e32 v9, 0x6000, v0
	v_mul_i32_i24_e32 v8, 0x6000, v0
	v_lshl_add_u64 v[4:5], v[4:5], 0, v[44:45]
	v_lshlrev_b64 v[56:57], 11, v[2:3]
	s_mov_b32 s0, 0x3a800000
	s_waitcnt vmcnt(0) lgkmcnt(0)
	v_lshl_add_u64 v[6:7], v[6:7], 0, v[8:9]
	v_lshl_add_u64 v[34:35], v[6:7], 0, s[92:93]
	v_lshl_add_u64 v[8:9], v[34:35], 0, v[44:45]
	v_lshl_add_u64 v[58:59], v[6:7], 0, v[44:45]
	global_load_dwordx4 v[14:17], v[4:5], off
	global_load_dwordx4 v[10:13], v[8:9], off
	s_nop 0
	global_load_dwordx4 v[6:9], v[58:59], off
	global_load_dwordx4 v[22:25], v[4:5], off offset:1024
	v_lshl_add_u64 v[64:65], v[34:35], 0, v[50:51]
	v_lshl_add_u64 v[62:63], v[34:35], 0, v[52:53]
	v_lshl_add_u64 v[60:61], v[34:35], 0, v[54:55]
	s_waitcnt vmcnt(0)
	v_mov_b32_e32 v28, v15
	s_waitcnt lgkmcnt(0)
	v_pk_add_f32 v[70:71], v[10:11], 1.0 op_sel_hi:[1,0]
	global_load_dwordx2 v[10:11], v[46:47], off offset:280
	v_mov_b32_e32 v29, v23
	v_mov_b32_e32 v26, v14
	v_mov_b32_e32 v27, v22
	v_pk_mul_f32 v[28:29], v[28:29], v[28:29]
	v_mov_b32_e32 v18, v16
	v_mov_b32_e32 v19, v24
	v_pk_fma_f32 v[26:27], v[26:27], v[26:27], v[28:29]
	v_mov_b32_e32 v20, v17
	v_mov_b32_e32 v21, v25
	v_pk_fma_f32 v[18:19], v[18:19], v[18:19], v[26:27]
	v_pk_add_f32 v[68:69], v[12:13], 1.0 op_sel_hi:[1,0]
	v_pk_fma_f32 v[72:73], v[20:21], v[20:21], v[18:19]
	s_waitcnt vmcnt(0) lgkmcnt(0)
	v_lshl_add_u64 v[2:3], v[10:11], 0, v[56:57]
	v_lshl_add_u64 v[66:67], v[2:3], 0, v[48:49]
	v_add_co_u32_e32 v2, vcc, s84, v4
	s_nop 1
	v_addc_co_u32_e32 v3, vcc, 0, v5, vcc
	global_load_dwordx4 v[10:13], v[2:3], off
	global_load_dwordx4 v[18:21], v[2:3], off offset:1024
	s_waitcnt vmcnt(1)
	v_mov_b32_e32 v32, v11
	s_waitcnt vmcnt(0)
	v_mov_b32_e32 v33, v19
	v_mov_b32_e32 v30, v10
	v_mov_b32_e32 v31, v18
	v_pk_mul_f32 v[32:33], v[32:33], v[32:33]
	v_mov_b32_e32 v26, v12
	v_mov_b32_e32 v27, v20
	v_pk_fma_f32 v[30:31], v[30:31], v[30:31], v[32:33]
	v_mov_b32_e32 v28, v13
	v_mov_b32_e32 v29, v21
	v_pk_fma_f32 v[26:27], v[26:27], v[26:27], v[30:31]
	s_nop 0
	v_pk_fma_f32 v[74:75], v[28:29], v[28:29], v[26:27]
	global_load_dwordx4 v[30:33], v[4:5], off offset:2048
	global_load_dwordx4 v[26:29], v[2:3], off offset:2048
	global_load_dwordx4 v[34:37], v[4:5], off offset:3072
	s_waitcnt vmcnt(2)
	v_mov_b32_e32 v86, v31
	v_mov_b32_e32 v84, v30
	s_waitcnt vmcnt(0)
	v_mov_b32_e32 v87, v35
	v_mov_b32_e32 v85, v34
	v_pk_mul_f32 v[86:87], v[86:87], v[86:87]
	v_mov_b32_e32 v4, v32
	v_mov_b32_e32 v5, v36
	v_pk_fma_f32 v[84:85], v[84:85], v[84:85], v[86:87]
	v_mov_b32_e32 v76, v33
	v_mov_b32_e32 v77, v37
	v_pk_fma_f32 v[4:5], v[4:5], v[4:5], v[84:85]
	v_mov_b32_e32 v90, v27
	v_pk_fma_f32 v[76:77], v[76:77], v[76:77], v[4:5]
	global_load_dwordx4 v[2:5], v[2:3], off offset:3072
	v_mov_b32_e32 v88, v26
	v_mov_b32_e32 v84, v28
	v_mov_b32_e32 v86, v29
	s_waitcnt vmcnt(0)
	v_mov_b32_e32 v91, v3
	v_mov_b32_e32 v89, v2
	v_pk_mul_f32 v[90:91], v[90:91], v[90:91]
	v_mov_b32_e32 v85, v4
	v_pk_fma_f32 v[88:89], v[88:89], v[88:89], v[90:91]
	v_mov_b32_e32 v87, v5
	v_pk_fma_f32 v[84:85], v[84:85], v[84:85], v[88:89]
	s_nop 0
	v_pk_fma_f32 v[84:85], v[86:87], v[86:87], v[84:85]
	v_mov_b32_e32 v86, v74
	v_mov_b32_e32 v87, v72
	v_mov_b32_e32 v72, v75
	v_pk_add_f32 v[72:73], v[86:87], v[72:73]
	v_mov_b32_e32 v74, v84
	v_mov_b32_e32 v75, v76
	v_pk_add_f32 v[72:73], v[72:73], v[74:75]
	v_mov_b32_e32 v76, v85
	v_pk_add_f32 v[72:73], v[72:73], v[76:77]
	ds_bpermute_b32 v75, v78, v73
	ds_bpermute_b32 v74, v78, v72
	s_waitcnt lgkmcnt(0)
	v_pk_add_f32 v[72:73], v[72:73], v[74:75]
	ds_bpermute_b32 v75, v79, v73
	ds_bpermute_b32 v74, v79, v72
	s_waitcnt lgkmcnt(0)
	v_pk_add_f32 v[72:73], v[72:73], v[74:75]
	ds_bpermute_b32 v75, v80, v73
	ds_bpermute_b32 v74, v80, v72
	s_waitcnt lgkmcnt(0)
	v_pk_add_f32 v[72:73], v[72:73], v[74:75]
	ds_bpermute_b32 v75, v81, v73
	ds_bpermute_b32 v74, v81, v72
	s_waitcnt lgkmcnt(0)
	v_pk_add_f32 v[72:73], v[72:73], v[74:75]
	ds_bpermute_b32 v75, v82, v73
	ds_bpermute_b32 v74, v82, v72
	s_waitcnt lgkmcnt(0)
	v_pk_add_f32 v[72:73], v[72:73], v[74:75]
	ds_bpermute_b32 v75, v83, v73
	ds_bpermute_b32 v74, v83, v72
	s_waitcnt lgkmcnt(0)
; template <bool COMBINE, bool MOD>
; __device__ __forceinline__ void phase_combine_modulate(const Params& p, int lprev, int lnext, const float* xlat, const float* xctx,
;                                                        float* olat, float* octx, int nrows) {
;     ...
;       float rstd[R];
; #pragma unroll
;       for (int r = 0; r < R; ++r) {
;         float ss = 0.f;
; #pragma unroll
;         for (int i = 0; i < 4; ++i) ss += v[r][i].x * v[r][i].x + v[r][i].y * v[r][i].y + v[r][i].z * v[r][i].z + v[r][i].w * v[r][i].w;
;         rstd[r] = rsqrtf(wave_sum(ss) * (1.f / 1024.f) + 1e-6f);
;       }
; #pragma unroll
;       for (int i = 0; i < 4; ++i) {
;         const int col = i * 256 + lane * 4;
;         const float4 s4 = *(const float4*)(sc + col);
;         const float4 h4 = *(const float4*)(sh + col);
; #pragma unroll
;         for (int r = 0; r < R; ++r) {
;           u32x2 pk;
;           pk.x = pack2(v[r][i].x * rstd[r] * (1.f + s4.x) + h4.x, v[r][i].y * rstd[r] * (1.f + s4.y) + h4.y);
;           pk.y = pack2(v[r][i].z * rstd[r] * (1.f + s4.z) + h4.z, v[r][i].w * rstd[r] * (1.f + s4.w) + h4.w);
;           *(u32x2*)(p.H + (size_t)(row0 + r) * DM + col) = pk;
;         }
;       }
	v_pk_add_f32 v[72:73], v[72:73], v[74:75]
	s_nop 0
	v_pk_fma_f32 v[72:73], v[72:73], s[0:1], v[224:225] op_sel_hi:[1,0,0]
	v_readlane_b32 s0, v254, 54
	v_mul_f32_e32 v0, 0x4b800000, v73
	v_cmp_gt_f32_e64 s[38:39], s85, v73
	v_cmp_gt_f32_e32 vcc, s85, v72
	v_readlane_b32 s1, v254, 55
	v_cndmask_b32_e64 v0, v73, v0, s[38:39]
	v_rsq_f32_e32 v0, v0
	v_lshl_add_u64 v[38:39], v[38:39], 0, s[0:1]
	v_readlane_b32 s0, v254, 52
	v_readlane_b32 s1, v254, 53
	v_mul_f32_e32 v73, 0x45800000, v0
	v_cndmask_b32_e64 v0, v0, v73, s[38:39]
	v_pk_mul_f32 v[14:15], v[14:15], v[0:1] op_sel_hi:[1,0]
	v_pk_mul_f32 v[76:77], v[22:23], v[0:1] op_sel_hi:[1,0]
	v_pk_fma_f32 v[14:15], v[70:71], v[14:15], v[6:7]
	v_pk_mul_f32 v[84:85], v[24:25], v[0:1] op_sel_hi:[1,0]
	v_cvt_pk_bf16_f32 v74, v14, v15
	v_pk_mul_f32 v[14:15], v[16:17], v[0:1] op_sel_hi:[1,0]
	v_pk_mul_f32 v[24:25], v[30:31], v[0:1] op_sel_hi:[1,0]
	v_pk_fma_f32 v[14:15], v[68:69], v[14:15], v[8:9]
	v_pk_mul_f32 v[22:23], v[32:33], v[0:1] op_sel_hi:[1,0]
	v_cvt_pk_bf16_f32 v75, v14, v15
	v_pk_mul_f32 v[16:17], v[34:35], v[0:1] op_sel_hi:[1,0]
	v_pk_mul_f32 v[14:15], v[36:37], v[0:1] op_sel_hi:[1,0]
	v_mul_f32_e32 v0, 0x4b800000, v72
	v_cndmask_b32_e32 v0, v72, v0, vcc
	v_rsq_f32_e32 v0, v0
	global_store_dwordx2 v[66:67], v[74:75], off
	v_lshl_add_u64 v[40:41], v[40:41], 0, s[0:1]
	v_readlane_b32 s0, v254, 56
	v_mul_f32_e32 v30, 0x45800000, v0
	v_cndmask_b32_e32 v0, v0, v30, vcc
	v_pk_mul_f32 v[10:11], v[10:11], v[0:1] op_sel_hi:[1,0]
	v_pk_mul_f32 v[30:31], v[18:19], v[0:1] op_sel_hi:[1,0]
	v_pk_fma_f32 v[6:7], v[70:71], v[10:11], v[6:7]
	v_pk_mul_f32 v[32:33], v[20:21], v[0:1] op_sel_hi:[1,0]
	v_cvt_pk_bf16_f32 v10, v6, v7
	v_pk_mul_f32 v[6:7], v[12:13], v[0:1] op_sel_hi:[1,0]
	global_load_dwordx2 v[12:13], v[46:47], off offset:280
	v_pk_fma_f32 v[6:7], v[68:69], v[6:7], v[8:9]
	v_pk_mul_f32 v[8:9], v[26:27], v[0:1] op_sel_hi:[1,0]
	v_cvt_pk_bf16_f32 v11, v6, v7
	v_pk_mul_f32 v[6:7], v[28:29], v[0:1] op_sel_hi:[1,0]
	v_pk_mul_f32 v[2:3], v[2:3], v[0:1] op_sel_hi:[1,0]
	v_pk_mul_f32 v[4:5], v[4:5], v[0:1] op_sel_hi:[1,0]
	v_readlane_b32 s1, v254, 57
	s_waitcnt vmcnt(0) lgkmcnt(0)
	v_lshl_add_u64 v[12:13], v[12:13], 0, v[42:43]
	global_store_dwordx2 v[12:13], v[10:11], off offset:2048
	global_load_dwordx4 v[10:13], v[64:65], off
	s_nop 0
	global_load_dwordx4 v[18:21], v[58:59], off offset:1024
	s_waitcnt vmcnt(0) lgkmcnt(0)
	v_pk_add_f32 v[10:11], v[10:11], 1.0 op_sel_hi:[1,0]
	v_pk_add_f32 v[12:13], v[12:13], 1.0 op_sel_hi:[1,0]
	v_pk_fma_f32 v[26:27], v[76:77], v[10:11], v[18:19]
	v_pk_fma_f32 v[28:29], v[84:85], v[12:13], v[20:21]
	v_cvt_pk_bf16_f32 v26, v26, v27
	v_cvt_pk_bf16_f32 v27, v28, v29
	global_load_dwordx2 v[28:29], v[46:47], off offset:280
	v_pk_fma_f32 v[10:11], v[30:31], v[10:11], v[18:19]
	v_pk_fma_f32 v[12:13], v[32:33], v[12:13], v[20:21]
	v_cvt_pk_bf16_f32 v10, v10, v11
	v_cvt_pk_bf16_f32 v11, v12, v13
	s_waitcnt vmcnt(0) lgkmcnt(0)
	v_lshl_add_u64 v[28:29], v[28:29], 0, v[56:57]
	v_lshl_add_u64 v[28:29], v[28:29], 0, v[48:49]
	global_store_dwordx2 v[28:29], v[26:27], off offset:512
	global_load_dwordx2 v[12:13], v[46:47], off offset:280
	s_waitcnt vmcnt(0) lgkmcnt(0)
	v_lshl_add_u64 v[12:13], v[12:13], 0, v[42:43]
	global_store_dwordx2 v[12:13], v[10:11], off offset:2560
	global_load_dwordx4 v[10:13], v[62:63], off
	s_nop 0
	global_load_dwordx4 v[18:21], v[58:59], off offset:2048
	s_waitcnt vmcnt(0) lgkmcnt(0)
	v_pk_add_f32 v[10:11], v[10:11], 1.0 op_sel_hi:[1,0]
	v_pk_add_f32 v[12:13], v[12:13], 1.0 op_sel_hi:[1,0]
	v_pk_fma_f32 v[24:25], v[24:25], v[10:11], v[18:19]
	v_pk_fma_f32 v[22:23], v[22:23], v[12:13], v[20:21]
	v_cvt_pk_bf16_f32 v24, v24, v25
	v_cvt_pk_bf16_f32 v25, v22, v23
	global_load_dwordx2 v[22:23], v[46:47], off offset:280
	v_pk_fma_f32 v[8:9], v[8:9], v[10:11], v[18:19]
	v_pk_fma_f32 v[6:7], v[6:7], v[12:13], v[20:21]
	v_cvt_pk_bf16_f32 v8, v8, v9
	v_cvt_pk_bf16_f32 v9, v6, v7
	s_waitcnt vmcnt(0) lgkmcnt(0)
	v_lshl_add_u64 v[22:23], v[22:23], 0, v[56:57]
	v_lshl_add_u64 v[22:23], v[22:23], 0, v[48:49]
	global_store_dwordx2 v[22:23], v[24:25], off offset:1024
	global_load_dwordx2 v[6:7], v[46:47], off offset:280
	s_waitcnt vmcnt(0) lgkmcnt(0)
	v_lshl_add_u64 v[6:7], v[6:7], 0, v[42:43]
	global_store_dwordx2 v[6:7], v[8:9], off offset:3072
	global_load_dwordx4 v[6:9], v[60:61], off
	s_nop 0
	global_load_dwordx4 v[10:13], v[58:59], off offset:3072
	s_waitcnt vmcnt(0) lgkmcnt(0)
	v_pk_add_f32 v[6:7], v[6:7], 1.0 op_sel_hi:[1,0]
	v_pk_add_f32 v[8:9], v[8:9], 1.0 op_sel_hi:[1,0]
	v_pk_fma_f32 v[16:17], v[16:17], v[6:7], v[10:11]
	v_pk_fma_f32 v[14:15], v[14:15], v[8:9], v[12:13]
	v_cvt_pk_bf16_f32 v16, v16, v17
	v_cvt_pk_bf16_f32 v17, v14, v15
	global_load_dwordx2 v[14:15], v[46:47], off offset:280
	v_pk_fma_f32 v[2:3], v[2:3], v[6:7], v[10:11]
	v_pk_fma_f32 v[4:5], v[4:5], v[8:9], v[12:13]
	v_cvt_pk_bf16_f32 v2, v2, v3
	v_cvt_pk_bf16_f32 v3, v4, v5
	s_waitcnt vmcnt(0) lgkmcnt(0)
	v_lshl_add_u64 v[14:15], v[14:15], 0, v[56:57]
	v_lshl_add_u64 v[14:15], v[14:15], 0, v[48:49]
	global_store_dwordx2 v[14:15], v[16:17], off offset:1536
	global_load_dwordx2 v[4:5], v[46:47], off offset:280
	s_waitcnt vmcnt(0) lgkmcnt(0)
	v_lshl_add_u64 v[4:5], v[4:5], 0, v[42:43]
	v_lshl_add_u64 v[42:43], v[42:43], 0, s[0:1]
	s_movk_i32 s0, 0x41ff
	v_cmp_lt_i32_e32 vcc, s0, v38
	s_or_b64 s[42:43], vcc, s[42:43]
	global_store_dwordx2 v[4:5], v[2:3], off offset:3584
	s_andn2_b64 exec, exec, s[42:43]
	s_cbranch_execz .LBB0_155

; template <bool COMBINE, bool MOD>
; __device__ __forceinline__ void phase_combine_modulate(const Params& p, int lprev, int lnext, const float* xlat, const float* xctx,
;                                                        float* olat, float* octx, int nrows) {
;     ...
; #pragma unroll
;         for (int i = 0; i < 4; ++i) {
;           const int col = i * 256 + lane * 4;
;           const float4 g4 = *(const float4*)(g2 + col);
;           v[r][i].x += g4.x * s[i].x; v[r][i].y += g4.y * s[i].y; v[r][i].z += g4.z * s[i].z; v[r][i].w += g4.w * s[i].w;
;           *(float4*)(orow + (size_t)r * DM + col) = v[r][i];
;         }
;       }
;     }
;     if (MOD) {
;       const float* sh = p.mada + (size_t)(lnext * 3 + cond) * 6144;
;       const float* sc = sh + 1024;
;       float rstd[R];
; #pragma unroll
;       for (int r = 0; r < R; ++r) {
;         float ss = 0.f;
; #pragma unroll
;         for (int i = 0; i < 4; ++i) ss += v[r][i].x * v[r][i].x + v[r][i].y * v[r][i].y + v[r][i].z * v[r][i].z + v[r][i].w * v[r][i].w;
;         rstd[r] = rsqrtf(wave_sum(ss) * (1.f / 1024.f) + 1e-6f);
;       }
.LBB0_159:
	global_load_dwordx4 v[76:79], v[52:53], off
	v_lshl_add_u64 v[80:81], v[50:51], 0, s[92:93]
	v_mov_b32_e32 v49, v1
	v_lshl_add_u64 v[50:51], v[80:81], 0, v[48:49]
	v_mov_b32_e32 v41, v1
	v_mov_b32_e32 v43, v1
	v_mov_b32_e32 v45, v1
	v_add_u32_e32 v0, 3, v94
	s_mov_b32 s0, 0x3a800000
	v_mov_b32_e32 v47, v1
	s_waitcnt vmcnt(0) lgkmcnt(0)
	v_pk_fma_f32 v[14:15], v[72:73], v[76:77], v[14:15]
	v_pk_fma_f32 v[16:17], v[74:75], v[78:79], v[16:17]
	global_store_dwordx4 v[50:51], v[14:17], off
	global_load_dwordx4 v[50:53], v[54:55], off
	v_lshl_add_u64 v[54:55], v[80:81], 0, v[40:41]
	v_mov_b32_e32 v72, v17
	s_waitcnt vmcnt(0) lgkmcnt(0)
	v_pk_fma_f32 v[10:11], v[70:71], v[50:51], v[10:11]
	v_pk_fma_f32 v[12:13], v[68:69], v[52:53], v[12:13]
	global_store_dwordx4 v[54:55], v[10:13], off
	global_load_dwordx4 v[50:53], v[56:57], off
	v_lshl_add_u64 v[54:55], v[80:81], 0, v[42:43]
	v_lshl_add_u64 v[56:57], v[80:81], 0, v[44:45]
	v_mov_b32_e32 v68, v25
	v_mov_b32_e32 v69, v21
	v_mul_hi_i32_i24_e32 v71, 0x6000, v0
	v_mul_i32_i24_e32 v70, 0x6000, v0
	v_mov_b32_e32 v73, v13
	s_waitcnt vmcnt(0) lgkmcnt(0)
	v_pk_fma_f32 v[6:7], v[66:67], v[50:51], v[6:7]
	v_pk_fma_f32 v[8:9], v[64:65], v[52:53], v[8:9]
	global_store_dwordx4 v[54:55], v[6:9], off
	global_load_dwordx4 v[52:55], v[62:63], off
	v_mov_b64_e32 v[50:51], s[42:43]
	v_mov_b32_e32 v64, v23
	v_mov_b32_e32 v65, v19
	v_mov_b32_e32 v62, v22
	v_mov_b32_e32 v63, v18
	v_pk_mul_f32 v[64:65], v[64:65], v[64:65]
	v_mov_b32_e32 v66, v24
	v_mov_b32_e32 v67, v20
	s_waitcnt vmcnt(0) lgkmcnt(0)
	v_pk_fma_f32 v[2:3], v[60:61], v[52:53], v[2:3]
	v_pk_fma_f32 v[4:5], v[58:59], v[54:55], v[4:5]
	global_store_dwordx4 v[56:57], v[2:5], off
	global_load_dwordx2 v[52:53], v[50:51], off offset:184
	global_load_dwordx2 v[76:77], v[50:51], off offset:280
	v_mov_b32_e32 v56, v31
	v_mov_b32_e32 v57, v27
	v_mov_b32_e32 v54, v30
	v_mov_b32_e32 v55, v26
	v_pk_mul_f32 v[56:57], v[56:57], v[56:57]
	v_mov_b32_e32 v58, v32
	v_pk_fma_f32 v[54:55], v[54:55], v[54:55], v[56:57]
	v_pk_fma_f32 v[56:57], v[62:63], v[62:63], v[64:65]
	v_mov_b32_e32 v59, v28
	v_pk_fma_f32 v[56:57], v[66:67], v[66:67], v[56:57]
	v_mov_b32_e32 v60, v33
	v_mov_b32_e32 v61, v29
	v_pk_fma_f32 v[54:55], v[58:59], v[58:59], v[54:55]
	v_pk_fma_f32 v[62:63], v[68:69], v[68:69], v[56:57]
	v_mov_b32_e32 v56, v15
	v_mov_b32_e32 v57, v11
	v_pk_fma_f32 v[60:61], v[60:61], v[60:61], v[54:55]
	v_mov_b32_e32 v54, v14
	v_mov_b32_e32 v55, v10
	v_pk_mul_f32 v[56:57], v[56:57], v[56:57]
	v_mov_b32_e32 v68, v16
	v_pk_fma_f32 v[74:75], v[54:55], v[54:55], v[56:57]
	v_mov_b32_e32 v69, v12
	v_pk_fma_f32 v[68:69], v[68:69], v[68:69], v[74:75]
	v_mov_b32_e32 v65, v60
	v_pk_fma_f32 v[68:69], v[72:73], v[72:73], v[68:69]
	v_mov_b32_e32 v72, v8
	v_mov_b32_e32 v64, v68
	v_mov_b32_e32 v60, v69
	v_mov_b32_e32 v68, v7
	v_mov_b32_e32 v69, v3
	v_pk_add_f32 v[60:61], v[64:65], v[60:61]
	v_mov_b32_e32 v64, v6
	v_mov_b32_e32 v65, v2
	v_pk_mul_f32 v[68:69], v[68:69], v[68:69]
	v_mov_b32_e32 v73, v4
	v_pk_fma_f32 v[64:65], v[64:65], v[64:65], v[68:69]
	v_mov_b32_e32 v74, v9
	v_mov_b32_e32 v75, v5
	v_pk_fma_f32 v[64:65], v[72:73], v[72:73], v[64:65]
	v_mov_b32_e32 v67, v62
	v_pk_fma_f32 v[64:65], v[74:75], v[74:75], v[64:65]
	s_waitcnt vmcnt(0) lgkmcnt(0)
	v_lshl_add_u64 v[56:57], v[52:53], 0, v[70:71]
	v_lshl_add_u64 v[70:71], v[56:57], 0, s[92:93]
	v_lshl_add_u64 v[52:53], v[70:71], 0, v[48:49]
	global_load_dwordx4 v[52:55], v[52:53], off
	v_lshl_add_u64 v[48:49], v[56:57], 0, v[48:49]
	global_load_dwordx4 v[56:59], v[48:49], off
	v_mov_b32_e32 v66, v64
	v_mov_b32_e32 v62, v65
	v_pk_add_f32 v[60:61], v[60:61], v[66:67]
	s_waitcnt vmcnt(0) lgkmcnt(0)
	v_pk_add_f32 v[52:53], v[52:53], 1.0 op_sel_hi:[1,0]
	v_pk_add_f32 v[60:61], v[60:61], v[62:63]
	ds_bpermute_b32 v63, v37, v61
	ds_bpermute_b32 v62, v37, v60
	v_pk_add_f32 v[54:55], v[54:55], 1.0 op_sel_hi:[1,0]
	s_waitcnt lgkmcnt(0)
	v_pk_add_f32 v[60:61], v[60:61], v[62:63]
	ds_bpermute_b32 v63, v86, v61
	ds_bpermute_b32 v62, v86, v60
	s_waitcnt lgkmcnt(0)
	v_pk_add_f32 v[60:61], v[60:61], v[62:63]
	ds_bpermute_b32 v63, v87, v61
	ds_bpermute_b32 v62, v87, v60
	s_waitcnt lgkmcnt(0)
	v_pk_add_f32 v[60:61], v[60:61], v[62:63]
	ds_bpermute_b32 v63, v88, v61
	ds_bpermute_b32 v62, v88, v60
	s_waitcnt lgkmcnt(0)
	v_pk_add_f32 v[60:61], v[60:61], v[62:63]
	ds_bpermute_b32 v63, v89, v61
	ds_bpermute_b32 v62, v89, v60
	s_waitcnt lgkmcnt(0)
	v_pk_add_f32 v[60:61], v[60:61], v[62:63]
	ds_bpermute_b32 v63, v90, v61
	ds_bpermute_b32 v62, v90, v60
	s_waitcnt lgkmcnt(0)
; template <bool COMBINE, bool MOD>
; __device__ __forceinline__ void phase_combine_modulate(const Params& p, int lprev, int lnext, const float* xlat, const float* xctx,
;                                                        float* olat, float* octx, int nrows) {
;     ...
; #pragma unroll
;       for (int i = 0; i < 4; ++i) {
;         const int col = i * 256 + lane * 4;
;         const float4 s4 = *(const float4*)(sc + col);
;         const float4 h4 = *(const float4*)(sh + col);
; #pragma unroll
;         for (int r = 0; r < R; ++r) {
;           u32x2 pk;
;           pk.x = pack2(v[r][i].x * rstd[r] * (1.f + s4.x) + h4.x, v[r][i].y * rstd[r] * (1.f + s4.y) + h4.y);
;           pk.y = pack2(v[r][i].z * rstd[r] * (1.f + s4.z) + h4.z, v[r][i].w * rstd[r] * (1.f + s4.w) + h4.w);
;           *(u32x2*)(p.H + (size_t)(row0 + r) * DM + col) = pk;
;         }
;       }
	v_pk_add_f32 v[60:61], v[60:61], v[62:63]
	s_nop 0
	v_pk_fma_f32 v[60:61], v[60:61], s[0:1], v[224:225] op_sel_hi:[1,0,0]
	v_lshlrev_b64 v[62:63], 11, v[34:35]
	v_mul_f32_e32 v0, 0x4b800000, v61
	v_cmp_gt_f32_e32 vcc, s85, v61
	v_lshl_add_u64 v[64:65], v[76:77], 0, v[62:63]
	v_lshl_add_u64 v[64:65], v[64:65], 0, v[46:47]
	v_cndmask_b32_e32 v0, v61, v0, vcc
	v_rsq_f32_e32 v0, v0
	v_readlane_b32 s0, v254, 54
	v_readlane_b32 s1, v254, 55
	v_mul_f32_e32 v35, 0x45800000, v0
	v_cndmask_b32_e32 v0, v0, v35, vcc
	v_pk_mul_f32 v[30:31], v[30:31], v[0:1] op_sel_hi:[1,0]
	v_pk_mul_f32 v[32:33], v[32:33], v[0:1] op_sel_hi:[1,0]
	v_pk_fma_f32 v[30:31], v[52:53], v[30:31], v[56:57]
	v_pk_fma_f32 v[32:33], v[54:55], v[32:33], v[58:59]
	v_cvt_pk_bf16_f32 v30, v30, v31
	v_cvt_pk_bf16_f32 v31, v32, v33
	global_store_dwordx2 v[64:65], v[30:31], off
	global_load_dwordx2 v[30:31], v[50:51], off offset:280
	v_mul_f32_e32 v32, 0x4b800000, v60
	v_cmp_gt_f32_e32 vcc, s85, v60
	v_pk_mul_f32 v[26:27], v[26:27], v[0:1] op_sel_hi:[1,0]
	v_pk_mul_f32 v[28:29], v[28:29], v[0:1] op_sel_hi:[1,0]
	v_cndmask_b32_e32 v32, v60, v32, vcc
	v_rsq_f32_e32 v35, v32
	v_or_b32_e32 v32, 1, v34
	v_ashrrev_i32_e32 v33, 31, v32
	v_lshlrev_b64 v[60:61], 11, v[32:33]
	v_mul_f32_e32 v32, 0x45800000, v35
	v_cndmask_b32_e32 v64, v35, v32, vcc
	v_pk_mul_f32 v[14:15], v[14:15], v[64:65] op_sel_hi:[1,0]
	v_pk_mul_f32 v[16:17], v[16:17], v[64:65] op_sel_hi:[1,0]
	v_pk_fma_f32 v[14:15], v[52:53], v[14:15], v[56:57]
	v_pk_fma_f32 v[16:17], v[54:55], v[16:17], v[58:59]
	v_cvt_pk_bf16_f32 v14, v14, v15
	v_cvt_pk_bf16_f32 v15, v16, v17
	v_lshl_add_u64 v[32:33], v[70:71], 0, v[40:41]
	v_pk_mul_f32 v[10:11], v[10:11], v[64:65] op_sel_hi:[1,0]
	v_pk_mul_f32 v[12:13], v[12:13], v[64:65] op_sel_hi:[1,0]
	v_pk_mul_f32 v[22:23], v[22:23], v[0:1] op_sel_hi:[1,0]
	v_pk_mul_f32 v[24:25], v[24:25], v[0:1] op_sel_hi:[1,0]
	v_pk_mul_f32 v[6:7], v[6:7], v[64:65] op_sel_hi:[1,0]
	v_pk_mul_f32 v[8:9], v[8:9], v[64:65] op_sel_hi:[1,0]
	v_pk_mul_f32 v[2:3], v[2:3], v[64:65] op_sel_hi:[1,0]
	v_pk_mul_f32 v[4:5], v[4:5], v[64:65] op_sel_hi:[1,0]
	v_add_u32_e32 v34, s0, v34
	s_movk_i32 s0, 0x41ff
	v_cmp_lt_i32_e32 vcc, s0, v34
	s_or_b64 s[50:51], vcc, s[50:51]
	s_waitcnt vmcnt(0) lgkmcnt(0)
	v_lshl_add_u64 v[16:17], v[30:31], 0, v[60:61]
	v_lshl_add_u64 v[16:17], v[16:17], 0, v[46:47]
	global_store_dwordx2 v[16:17], v[14:15], off
	global_load_dwordx4 v[14:17], v[32:33], off
	s_nop 0
	global_load_dwordx2 v[52:53], v[50:51], off offset:280
	global_load_dwordx4 v[30:33], v[48:49], off offset:1024
	s_waitcnt vmcnt(0) lgkmcnt(0)
	v_pk_add_f32 v[14:15], v[14:15], 1.0 op_sel_hi:[1,0]
	v_pk_add_f32 v[16:17], v[16:17], 1.0 op_sel_hi:[1,0]
	v_lshl_add_u64 v[52:53], v[52:53], 0, v[62:63]
	v_pk_fma_f32 v[26:27], v[26:27], v[14:15], v[30:31]
	v_pk_fma_f32 v[28:29], v[28:29], v[16:17], v[32:33]
	v_lshl_add_u64 v[52:53], v[52:53], 0, v[46:47]
	v_cvt_pk_bf16_f32 v26, v26, v27
	v_cvt_pk_bf16_f32 v27, v28, v29
	global_store_dwordx2 v[52:53], v[26:27], off offset:512
	global_load_dwordx2 v[26:27], v[50:51], off offset:280
	v_pk_fma_f32 v[10:11], v[10:11], v[14:15], v[30:31]
	v_pk_fma_f32 v[12:13], v[12:13], v[16:17], v[32:33]
	v_cvt_pk_bf16_f32 v10, v10, v11
	v_cvt_pk_bf16_f32 v11, v12, v13
	v_lshl_add_u64 v[28:29], v[70:71], 0, v[42:43]
	s_waitcnt vmcnt(0) lgkmcnt(0)
	v_lshl_add_u64 v[12:13], v[26:27], 0, v[60:61]
	v_lshl_add_u64 v[12:13], v[12:13], 0, v[46:47]
	global_store_dwordx2 v[12:13], v[10:11], off offset:512
	global_load_dwordx4 v[10:13], v[28:29], off
	s_nop 0
	global_load_dwordx2 v[26:27], v[50:51], off offset:280
	global_load_dwordx4 v[14:17], v[48:49], off offset:2048
	s_waitcnt vmcnt(0) lgkmcnt(0)
	v_pk_add_f32 v[10:11], v[10:11], 1.0 op_sel_hi:[1,0]
	v_pk_add_f32 v[12:13], v[12:13], 1.0 op_sel_hi:[1,0]
	v_lshl_add_u64 v[26:27], v[26:27], 0, v[62:63]
	v_pk_fma_f32 v[22:23], v[22:23], v[10:11], v[14:15]
	v_pk_fma_f32 v[24:25], v[24:25], v[12:13], v[16:17]
	v_lshl_add_u64 v[26:27], v[26:27], 0, v[46:47]
	v_cvt_pk_bf16_f32 v22, v22, v23
	v_cvt_pk_bf16_f32 v23, v24, v25
	global_store_dwordx2 v[26:27], v[22:23], off offset:1024
	global_load_dwordx2 v[22:23], v[50:51], off offset:280
	v_pk_fma_f32 v[6:7], v[6:7], v[10:11], v[14:15]
	v_pk_fma_f32 v[8:9], v[8:9], v[12:13], v[16:17]
	v_cvt_pk_bf16_f32 v6, v6, v7
	v_cvt_pk_bf16_f32 v7, v8, v9
	v_lshl_add_u64 v[24:25], v[70:71], 0, v[44:45]
	v_pk_mul_f32 v[16:17], v[18:19], v[0:1] op_sel_hi:[1,0]
	v_pk_mul_f32 v[18:19], v[20:21], v[0:1] op_sel_hi:[1,0]
	s_waitcnt vmcnt(0) lgkmcnt(0)
	v_lshl_add_u64 v[8:9], v[22:23], 0, v[60:61]
	v_lshl_add_u64 v[8:9], v[8:9], 0, v[46:47]
	global_store_dwordx2 v[8:9], v[6:7], off offset:1024
	global_load_dwordx4 v[6:9], v[24:25], off
	s_nop 0
	global_load_dwordx2 v[14:15], v[50:51], off offset:280
	global_load_dwordx4 v[10:13], v[48:49], off offset:3072
	s_waitcnt vmcnt(0) lgkmcnt(0)
	v_pk_add_f32 v[6:7], v[6:7], 1.0 op_sel_hi:[1,0]
	v_pk_add_f32 v[8:9], v[8:9], 1.0 op_sel_hi:[1,0]
	v_lshl_add_u64 v[14:15], v[14:15], 0, v[62:63]
	v_pk_fma_f32 v[16:17], v[16:17], v[6:7], v[10:11]
	v_pk_fma_f32 v[18:19], v[18:19], v[8:9], v[12:13]
	v_lshl_add_u64 v[14:15], v[14:15], 0, v[46:47]
	v_cvt_pk_bf16_f32 v16, v16, v17
	v_cvt_pk_bf16_f32 v17, v18, v19
	global_store_dwordx2 v[14:15], v[16:17], off offset:1536
	global_load_dwordx2 v[14:15], v[50:51], off offset:280
	v_pk_fma_f32 v[2:3], v[2:3], v[6:7], v[10:11]
	v_pk_fma_f32 v[4:5], v[4:5], v[8:9], v[12:13]
	v_cvt_pk_bf16_f32 v2, v2, v3
	v_cvt_pk_bf16_f32 v3, v4, v5
	s_waitcnt vmcnt(0) lgkmcnt(0)
	v_lshl_add_u64 v[4:5], v[14:15], 0, v[60:61]
	v_lshl_add_u64 v[4:5], v[4:5], 0, v[46:47]
	global_store_dwordx2 v[4:5], v[2:3], off offset:1536
	s_andn2_b64 exec, exec, s[50:51]
	s_cbranch_execz .LBB0_187

; template <bool COMBINE, bool MOD>
; __device__ __forceinline__ void phase_combine_modulate(const Params& p, int lprev, int lnext, const float* xlat, const float* xctx,
;                                                        float* olat, float* octx, int nrows) {
;     ...
;   for (int row0 = gw * R; row0 < nrows; row0 += nw * R) {
;     const bool lat = row0 < T_LAT;
;     const float* xr = lat ? xlat + (size_t)row0 * DM : xctx + (size_t)(row0 - T_LAT) * DM;
;     const int cond = row_cond(row0);
;     float4 v[R][4];
; #pragma unroll
;     for (int r = 0; r < R; ++r)
; #pragma unroll
;       for (int i = 0; i < 4; ++i) v[r][i] = *(const float4*)(xr + (size_t)r * DM + i * 256 + lane * 4);
;     if (COMBINE) {
;       const int b = row_batch(row0);
;       const int myinv = p.INV[(size_t)row0 * 16 + (lane & 31)];
;       const float* g2 = p.mada + (size_t)(lprev * 3 + cond) * 6144 + 5 * 1024;
;       float* orow = lat ? olat + (size_t)row0 * DM : octx + (size_t)(row0 - T_LAT) * DM;
; #pragma unroll
;       for (int r = 0; r < R; ++r) {
;         float4 s[4];
; #pragma unroll
;         for (int i = 0; i < 4; ++i) s[i] = make_float4(0.f, 0.f, 0.f, 0.f);
;         unsigned mask = (unsigned)((__ballot(myinv >= 0) >> (16 * r)) & 0xFFFFull);
;         while (mask) {
;           const int e0 = __builtin_ctz(mask);
;           mask &= mask - 1;
;           const bool two = mask != 0u;
;           const int e1 = two ? __builtin_ctz(mask) : e0;
;           mask &= mask - 1;
;           const int s0 = __shfl(myinv, 16 * r + e0), s1 = __shfl(myinv, 16 * r + e1);
;           const size_t y0 = lat ? (size_t)(b * 16 + e0) * 1024 + s0 : (size_t)32768 + (size_t)(b * 16 + e0) * 128 + s0;
;           const size_t y1 = lat ? (size_t)(b * 16 + e1) * 1024 + s1 : (size_t)32768 + (size_t)(b * 16 + e1) * 128 + s1;
;           u32x2 a0[4], a1[4];
; #pragma unroll
;           for (int i = 0; i < 4; ++i) { a0[i] = *(const u32x2*)(p.YB + y0 * 1024 + lane * 4 + i * 256); a1[i] = *(const u32x2*)(p.YB + y1 * 1024 + lane * 4 + i * 256); }
;           const float w1 = two ? 1.f : 0.f;
; #pragma unroll
;           for (int i = 0; i < 4; ++i) {
;             s[i].x += bf2f((u16)(a0[i].x & 0xffffu)); s[i].y += bf2f((u16)(a0[i].x >> 16));
;             s[i].z += bf2f((u16)(a0[i].y & 0xffffu)); s[i].w += bf2f((u16)(a0[i].y >> 16));
.LBB0_164:
	s_or_b64 exec, exec, s[0:1]
	v_mov_b64_e32 v[4:5], s[42:43]
	global_load_dwordx2 v[6:7], v[4:5], off offset:416
	v_lshlrev_b32_e32 v48, 2, v36
	v_mov_b32_e32 v49, v1
	v_lshlrev_b64 v[8:9], 6, v[34:35]
	v_mov_b32_e32 v39, v1
	v_lshl_add_u64 v[2:3], v[2:3], 0, v[48:49]
	global_load_dwordx2 v[54:55], v[4:5], off offset:184
	global_load_dwordx4 v[30:33], v[2:3], off
	global_load_dwordx4 v[26:29], v[2:3], off offset:1024
	global_load_dwordx4 v[22:25], v[2:3], off offset:2048
	global_load_dwordx4 v[18:21], v[2:3], off offset:3072
	v_add_co_u32_e32 v2, vcc, 0x1000, v2
	v_lshrrev_b32_e32 v0, 4, v0
	s_nop 0
	v_addc_co_u32_e32 v3, vcc, 0, v3, vcc
	v_ashrrev_i32_e32 v41, 9, v34
	v_and_b32_e32 v92, 0xffffff0, v0
	v_and_b32_e32 v93, -16, v41
	v_lshlrev_b32_e32 v46, 1, v36
	s_waitcnt vmcnt(0) lgkmcnt(0)
	v_lshl_add_u64 v[4:5], v[6:7], 0, v[8:9]
	v_lshl_add_u64 v[4:5], v[4:5], 0, v[38:39]
	global_load_dword v39, v[4:5], off
	global_load_dwordx4 v[14:17], v[2:3], off
	global_load_dwordx4 v[10:13], v[2:3], off offset:1024
	global_load_dwordx4 v[6:9], v[2:3], off offset:2048
	s_nop 0
	global_load_dwordx4 v[2:5], v[2:3], off offset:3072
	s_waitcnt vmcnt(0) lgkmcnt(0)
	v_cmp_lt_i32_e32 vcc, -1, v39
	s_and_b32 s8, vcc_lo, 0xffff
	s_cmp_eq_u32 s8, 0
	s_cbranch_scc1 .LBB0_175
	v_mov_b64_e32 v[56:57], s[42:43]
	global_load_dwordx2 v[56:57], v[56:57], off offset:424
	v_mov_b32_e32 v47, v1
	v_mov_b32_e32 v68, 0
	v_mov_b32_e32 v69, v68
	v_mov_b32_e32 v70, v68
	v_mov_b32_e32 v71, v68
	v_mov_b32_e32 v66, v68
	v_mov_b32_e32 v67, v68
	v_mov_b32_e32 v62, v68
	v_mov_b32_e32 v63, v68
	v_mov_b32_e32 v64, v68
	v_mov_b32_e32 v65, v68
	v_mov_b32_e32 v58, v68
	v_mov_b32_e32 v59, v68
	v_mov_b32_e32 v60, v68
	v_mov_b32_e32 v61, v68
	s_waitcnt vmcnt(0) lgkmcnt(0)
	v_lshl_add_u64 v[72:73], v[56:57], 0, v[46:47]
	v_mov_b32_e32 v56, v68
	v_mov_b32_e32 v57, v68
	s_branch .LBB0_167
.LBB0_166:
	s_or_b64 exec, exec, s[8:9]
	s_waitcnt lgkmcnt(1)
	v_ashrrev_i32_e32 v77, 31, v76
	s_waitcnt lgkmcnt(0)
	v_ashrrev_i32_e32 v75, 31, v74
	v_lshl_add_u64 v[76:77], v[78:79], 0, v[76:77]
	v_lshl_add_u64 v[74:75], v[80:81], 0, v[74:75]
	v_lshlrev_b64 v[76:77], 11, v[76:77]
	v_lshlrev_b64 v[74:75], 11, v[74:75]
	v_lshl_add_u64 v[76:77], v[72:73], 0, v[76:77]
	v_lshl_add_u64 v[74:75], v[72:73], 0, v[74:75]
	global_load_dwordx2 v[78:79], v[76:77], off
	global_load_dwordx2 v[80:81], v[74:75], off
	global_load_dwordx2 v[82:83], v[76:77], off offset:512
	global_load_dwordx2 v[84:85], v[74:75], off offset:512
	global_load_dwordx2 v[94:95], v[76:77], off offset:1024
	global_load_dwordx2 v[96:97], v[74:75], off offset:1024
	s_nop 0
	global_load_dwordx2 v[76:77], v[76:77], off offset:1536
	s_nop 0
	global_load_dwordx2 v[74:75], v[74:75], off offset:1536
	v_cndmask_b32_e64 v0, 1.0, 0, s[0:1]
	s_and_b32 s8, s19, s18
	s_cmp_eq_u32 s8, 0
	s_waitcnt vmcnt(0) lgkmcnt(0)
	v_and_b32_e32 v99, 0xffff0000, v78
	v_lshlrev_b32_e32 v98, 16, v78
	v_pk_add_f32 v[70:71], v[70:71], v[98:99]
	v_and_b32_e32 v99, 0xffff0000, v80
	v_lshlrev_b32_e32 v98, 16, v80
	v_pk_fma_f32 v[70:71], v[0:1], v[98:99], v[70:71] op_sel_hi:[0,1,1]
	v_and_b32_e32 v99, 0xffff0000, v79
	v_lshlrev_b32_e32 v98, 16, v79
	v_pk_add_f32 v[68:69], v[68:69], v[98:99]
	v_and_b32_e32 v79, 0xffff0000, v81
	v_lshlrev_b32_e32 v78, 16, v81
	v_pk_fma_f32 v[68:69], v[0:1], v[78:79], v[68:69] op_sel_hi:[0,1,1]
	v_and_b32_e32 v79, 0xffff0000, v82
	v_lshlrev_b32_e32 v78, 16, v82
	v_pk_add_f32 v[66:67], v[66:67], v[78:79]
	v_and_b32_e32 v79, 0xffff0000, v84
	v_lshlrev_b32_e32 v78, 16, v84
	v_pk_fma_f32 v[66:67], v[0:1], v[78:79], v[66:67] op_sel_hi:[0,1,1]
	v_and_b32_e32 v79, 0xffff0000, v83
	v_lshlrev_b32_e32 v78, 16, v83
	v_pk_add_f32 v[56:57], v[56:57], v[78:79]
	v_and_b32_e32 v79, 0xffff0000, v85
	v_lshlrev_b32_e32 v78, 16, v85
	v_pk_fma_f32 v[56:57], v[0:1], v[78:79], v[56:57] op_sel_hi:[0,1,1]
	v_and_b32_e32 v79, 0xffff0000, v94
	v_lshlrev_b32_e32 v78, 16, v94
	v_pk_add_f32 v[64:65], v[64:65], v[78:79]
	v_and_b32_e32 v79, 0xffff0000, v96
	v_lshlrev_b32_e32 v78, 16, v96
	v_pk_fma_f32 v[64:65], v[0:1], v[78:79], v[64:65] op_sel_hi:[0,1,1]
	v_and_b32_e32 v79, 0xffff0000, v95
	v_lshlrev_b32_e32 v78, 16, v95
	v_pk_add_f32 v[62:63], v[62:63], v[78:79]
	v_and_b32_e32 v79, 0xffff0000, v97
	v_lshlrev_b32_e32 v78, 16, v97
	v_pk_fma_f32 v[62:63], v[0:1], v[78:79], v[62:63] op_sel_hi:[0,1,1]
	v_and_b32_e32 v79, 0xffff0000, v76
	v_lshlrev_b32_e32 v78, 16, v76
	v_pk_add_f32 v[60:61], v[60:61], v[78:79]
	v_and_b32_e32 v79, 0xffff0000, v74
	v_lshlrev_b32_e32 v78, 16, v74
	v_pk_fma_f32 v[60:61], v[0:1], v[78:79], v[60:61] op_sel_hi:[0,1,1]
	v_and_b32_e32 v79, 0xffff0000, v77
	v_lshlrev_b32_e32 v78, 16, v77
	v_pk_add_f32 v[58:59], v[58:59], v[78:79]
	v_and_b32_e32 v77, 0xffff0000, v75
	v_lshlrev_b32_e32 v76, 16, v75
	v_pk_fma_f32 v[58:59], v[0:1], v[76:77], v[58:59] op_sel_hi:[0,1,1]
	s_cbranch_scc1 .LBB0_176

; __device__ __forceinline__ float bf2f(u16 b) { return __uint_as_float(((unsigned)b) << 16); }
; template <bool COMBINE, bool MOD>
; __device__ __forceinline__ void phase_combine_modulate(const Params& p, int lprev, int lnext, const float* xlat, const float* xctx,
;                                                        float* olat, float* octx, int nrows) {
;     ...
;         unsigned mask = (unsigned)((__ballot(myinv >= 0) >> (16 * r)) & 0xFFFFull);
;         while (mask) {
;           const int e0 = __builtin_ctz(mask);
;           mask &= mask - 1;
;           const bool two = mask != 0u;
;           const int e1 = two ? __builtin_ctz(mask) : e0;
;           mask &= mask - 1;
;           const int s0 = __shfl(myinv, 16 * r + e0), s1 = __shfl(myinv, 16 * r + e1);
;           const size_t y0 = lat ? (size_t)(b * 16 + e0) * 1024 + s0 : (size_t)32768 + (size_t)(b * 16 + e0) * 128 + s0;
;           const size_t y1 = lat ? (size_t)(b * 16 + e1) * 1024 + s1 : (size_t)32768 + (size_t)(b * 16 + e1) * 128 + s1;
;           u32x2 a0[4], a1[4];
; #pragma unroll
;           for (int i = 0; i < 4; ++i) { a0[i] = *(const u32x2*)(p.YB + y0 * 1024 + lane * 4 + i * 256); a1[i] = *(const u32x2*)(p.YB + y1 * 1024 + lane * 4 + i * 256); }
;           const float w1 = two ? 1.f : 0.f;
; #pragma unroll
;           for (int i = 0; i < 4; ++i) {
;             s[i].x += bf2f((u16)(a0[i].x & 0xffffu)); s[i].y += bf2f((u16)(a0[i].x >> 16));
;             s[i].z += bf2f((u16)(a0[i].y & 0xffffu)); s[i].w += bf2f((u16)(a0[i].y >> 16));
;             s[i].x += w1 * bf2f((u16)(a1[i].x & 0xffffu)); s[i].y += w1 * bf2f((u16)(a1[i].x >> 16));
;             s[i].z += w1 * bf2f((u16)(a1[i].y & 0xffffu)); s[i].w += w1 * bf2f((u16)(a1[i].y >> 16));
;           }
;         }
; #pragma unroll
;         for (int i = 0; i < 4; ++i) {
;           const int col = i * 256 + lane * 4;
;           const float4 g4 = *(const float4*)(g2 + col);
;           v[r][i].x += g4.x * s[i].x; v[r][i].y += g4.y * s[i].y; v[r][i].z += g4.z * s[i].z; v[r][i].w += g4.w * s[i].w;
;           *(float4*)(orow + (size_t)r * DM + col) = v[r][i];
;         }
.LBB0_176:
	v_min_i32_e32 v0, 0x4000, v34
	v_ashrrev_i32_e32 v94, 13, v0
	v_mul_hi_i32_i24_e32 v73, 0x6000, v94
	v_mul_i32_i24_e32 v72, 0x6000, v94
	v_lshl_add_u64 v[54:55], v[54:55], 0, v[72:73]
	s_mov_b64 s[0:1], 0x5000
	v_lshl_add_u64 v[76:77], v[54:55], 0, s[0:1]
	v_lshl_add_u64 v[52:53], s[46:47], 0, v[52:53]
	v_lshl_add_u64 v[50:51], s[48:49], 0, v[50:51]
	v_mov_b32_e32 v49, v1
	v_cndmask_b32_e64 v51, v51, v53, s[40:41]
	v_cndmask_b32_e64 v50, v50, v52, s[40:41]
	v_lshl_add_u64 v[52:53], v[76:77], 0, v[48:49]
	global_load_dwordx4 v[72:75], v[52:53], off
	v_mov_b32_e32 v41, v1
	v_lshl_add_u64 v[54:55], v[76:77], 0, v[40:41]
	v_mov_b32_e32 v43, v1
	v_mov_b32_e32 v45, v1
	v_cndmask_b32_e64 v0, 0, 1, vcc
	v_cmp_ne_u32_e32 vcc, 0, v0
	s_cmpk_gt_u32 vcc_lo, 0xffff
	s_waitcnt vmcnt(0) lgkmcnt(0)
	v_pk_fma_f32 v[30:31], v[70:71], v[72:73], v[30:31]
	v_pk_fma_f32 v[32:33], v[68:69], v[74:75], v[32:33]
	v_lshl_add_u64 v[72:73], v[50:51], 0, v[48:49]
	global_store_dwordx4 v[72:73], v[30:33], off
	global_load_dwordx4 v[68:71], v[54:55], off
	s_waitcnt vmcnt(0) lgkmcnt(0)
	v_pk_fma_f32 v[26:27], v[66:67], v[68:69], v[26:27]
	v_pk_fma_f32 v[28:29], v[56:57], v[70:71], v[28:29]
	global_store_dwordx4 v[72:73], v[26:29], off offset:1024
	v_lshl_add_u64 v[56:57], v[76:77], 0, v[42:43]
	global_load_dwordx4 v[66:69], v[56:57], off
	s_waitcnt vmcnt(0) lgkmcnt(0)
	v_pk_fma_f32 v[22:23], v[64:65], v[66:67], v[22:23]
	v_pk_fma_f32 v[24:25], v[62:63], v[68:69], v[24:25]
	global_store_dwordx4 v[72:73], v[22:25], off offset:2048
	v_lshl_add_u64 v[62:63], v[76:77], 0, v[44:45]
	global_load_dwordx4 v[64:67], v[62:63], off
	s_waitcnt vmcnt(0) lgkmcnt(0)
	v_pk_fma_f32 v[18:19], v[60:61], v[64:65], v[18:19]
	v_pk_fma_f32 v[20:21], v[58:59], v[66:67], v[20:21]
	v_mov_b32_e32 v59, 0
	global_store_dwordx4 v[72:73], v[18:21], off offset:3072
	v_mov_b32_e32 v58, v59
	v_mov_b32_e32 v61, v59
	v_mov_b32_e32 v60, v59
	v_mov_b32_e32 v65, v59
	v_mov_b32_e32 v64, v59
	v_mov_b32_e32 v67, v59
	v_mov_b32_e32 v66, v59
	v_mov_b32_e32 v69, v59
	v_mov_b32_e32 v68, v59
	v_mov_b32_e32 v71, v59
	v_mov_b32_e32 v70, v59
	v_mov_b32_e32 v75, v59
	v_mov_b32_e32 v74, v59
	v_mov_b32_e32 v73, v59
	v_mov_b32_e32 v72, v59
	s_cbranch_scc0 .LBB0_159
	v_mov_b64_e32 v[58:59], s[42:43]
	global_load_dwordx2 v[58:59], v[58:59], off offset:424
	v_mov_b32_e32 v47, v1
	v_mov_b32_e32 v72, 0
	s_lshr_b32 s8, vcc_lo, 16
	v_mov_b32_e32 v73, v72
	v_mov_b32_e32 v74, v72
	v_mov_b32_e32 v75, v72
	v_mov_b32_e32 v70, v72
	v_mov_b32_e32 v71, v72
	v_mov_b32_e32 v68, v72
	v_mov_b32_e32 v69, v72
	v_mov_b32_e32 v66, v72
	v_mov_b32_e32 v67, v72
	v_mov_b32_e32 v64, v72
	v_mov_b32_e32 v65, v72
	v_mov_b32_e32 v60, v72
	v_mov_b32_e32 v61, v72
	s_waitcnt vmcnt(0) lgkmcnt(0)
	v_lshl_add_u64 v[76:77], v[58:59], 0, v[46:47]
	v_mov_b32_e32 v58, v72
	v_mov_b32_e32 v59, v72
	s_branch .LBB0_179
.LBB0_178:
	s_or_b64 exec, exec, s[8:9]
	s_waitcnt lgkmcnt(1)
	v_ashrrev_i32_e32 v81, 31, v80
	s_waitcnt lgkmcnt(0)
	v_ashrrev_i32_e32 v79, 31, v78
	v_lshl_add_u64 v[80:81], v[82:83], 0, v[80:81]
	v_lshl_add_u64 v[78:79], v[84:85], 0, v[78:79]
	v_lshlrev_b64 v[80:81], 11, v[80:81]
	v_lshlrev_b64 v[78:79], 11, v[78:79]
	v_lshl_add_u64 v[80:81], v[76:77], 0, v[80:81]
	v_lshl_add_u64 v[78:79], v[76:77], 0, v[78:79]
	global_load_dwordx2 v[82:83], v[80:81], off
	global_load_dwordx2 v[84:85], v[78:79], off
	global_load_dwordx2 v[96:97], v[80:81], off offset:512
	global_load_dwordx2 v[98:99], v[78:79], off offset:512
	global_load_dwordx2 v[100:101], v[80:81], off offset:1024
	global_load_dwordx2 v[102:103], v[78:79], off offset:1024
	s_nop 0
	global_load_dwordx2 v[80:81], v[80:81], off offset:1536
	s_nop 0
	global_load_dwordx2 v[78:79], v[78:79], off offset:1536
	v_cndmask_b32_e64 v0, 1.0, 0, s[0:1]
	s_and_b32 s8, s19, s18
	s_cmp_lg_u32 s8, 0
	s_waitcnt vmcnt(0) lgkmcnt(0)
	v_and_b32_e32 v105, 0xffff0000, v82
	v_lshlrev_b32_e32 v104, 16, v82
	v_pk_add_f32 v[72:73], v[72:73], v[104:105]
	v_and_b32_e32 v105, 0xffff0000, v84
	v_lshlrev_b32_e32 v104, 16, v84
	v_pk_fma_f32 v[72:73], v[0:1], v[104:105], v[72:73] op_sel_hi:[0,1,1]
	v_and_b32_e32 v105, 0xffff0000, v83
	v_lshlrev_b32_e32 v104, 16, v83
	v_pk_add_f32 v[74:75], v[74:75], v[104:105]
	v_and_b32_e32 v83, 0xffff0000, v85
	v_lshlrev_b32_e32 v82, 16, v85
	v_pk_fma_f32 v[74:75], v[0:1], v[82:83], v[74:75] op_sel_hi:[0,1,1]
	v_and_b32_e32 v83, 0xffff0000, v96
	v_lshlrev_b32_e32 v82, 16, v96
	v_pk_add_f32 v[70:71], v[70:71], v[82:83]
	v_and_b32_e32 v83, 0xffff0000, v98
	v_lshlrev_b32_e32 v82, 16, v98
	v_pk_fma_f32 v[70:71], v[0:1], v[82:83], v[70:71] op_sel_hi:[0,1,1]
	v_and_b32_e32 v83, 0xffff0000, v97
	v_lshlrev_b32_e32 v82, 16, v97
	v_pk_add_f32 v[68:69], v[68:69], v[82:83]
	v_and_b32_e32 v83, 0xffff0000, v99
	v_lshlrev_b32_e32 v82, 16, v99
	v_pk_fma_f32 v[68:69], v[0:1], v[82:83], v[68:69] op_sel_hi:[0,1,1]
	v_and_b32_e32 v83, 0xffff0000, v100
	v_lshlrev_b32_e32 v82, 16, v100
	v_pk_add_f32 v[66:67], v[66:67], v[82:83]
	v_and_b32_e32 v83, 0xffff0000, v102
	v_lshlrev_b32_e32 v82, 16, v102
	v_pk_fma_f32 v[66:67], v[0:1], v[82:83], v[66:67] op_sel_hi:[0,1,1]
	v_and_b32_e32 v83, 0xffff0000, v101
	v_lshlrev_b32_e32 v82, 16, v101
	v_pk_add_f32 v[64:65], v[64:65], v[82:83]
	v_and_b32_e32 v83, 0xffff0000, v103
	v_lshlrev_b32_e32 v82, 16, v103
	v_pk_fma_f32 v[64:65], v[0:1], v[82:83], v[64:65] op_sel_hi:[0,1,1]
	v_and_b32_e32 v83, 0xffff0000, v80
	v_lshlrev_b32_e32 v82, 16, v80
	v_pk_add_f32 v[60:61], v[60:61], v[82:83]
	v_and_b32_e32 v83, 0xffff0000, v78
	v_lshlrev_b32_e32 v82, 16, v78
	v_pk_fma_f32 v[60:61], v[0:1], v[82:83], v[60:61] op_sel_hi:[0,1,1]
	v_and_b32_e32 v83, 0xffff0000, v81
	v_lshlrev_b32_e32 v82, 16, v81
	v_pk_add_f32 v[58:59], v[58:59], v[82:83]
	v_and_b32_e32 v81, 0xffff0000, v79
	v_lshlrev_b32_e32 v80, 16, v79
	v_pk_fma_f32 v[58:59], v[0:1], v[80:81], v[58:59] op_sel_hi:[0,1,1]
	s_cbranch_scc0 .LBB0_159

; #define XCD_FOR(u, T)                                                                                         \
;   for (int _x = bid_() & 7, _gb = gridDim.x >> 3, _hi = (int)(((long)(_x + 1) * (T)) >> 3),                    \
;            u = (int)(((long)_x * (T)) >> 3) + (bid_() >> 3);                                                  \
;        u < _hi; u += _gb)
; __device__ __forceinline__ void phase_in_gemm(const Params& p, int l, unsigned char* smem) {
;   const u16* W = p.WinT + (size_t)l * 1536 * 1024;
;   XCD_FOR(t, 132 * 11) {
.LBB0_240:
	s_or_b64 exec, exec, s[0:1]
	s_xor_b64 s[0:1], s[4:5], -1
	s_mov_b64 s[4:5], s[64:65]
	s_waitcnt lgkmcnt(0)
	s_barrier
	v_writelane_b32 v254, s0, 63
	v_mov_b64_e32 v[2:3], s[4:5]
	global_load_dwordx2 v[130:131], v[2:3], off offset:192
	v_writelane_b32 v255, s1, 0
	s_mov_b32 s0, s2
	s_and_b32 s0, s0, 7
	s_mulk_i32 s0, 0x5ac
	s_add_i32 s1, s0, 0x5ac
	s_lshr_b32 s8, s1, 3
	s_mov_b32 s1, s2
	s_lshr_b32 s0, s0, 3
	s_ashr_i32 s1, s1, 3
	s_xor_b64 s[44:45], s[86:87], -1
	s_mul_i32 s94, s36, 0x180000
	s_add_i32 s9, s0, s1
	s_cmp_ge_i32 s9, s8
	s_waitcnt vmcnt(0) lgkmcnt(0)
	v_lshl_add_u64 v[132:133], s[94:95], 1, v[130:131]
	s_cbranch_scc1 .LBB0_485
	v_mov_b32_e32 v0, 0x300000
	v_mad_u64_u32 v[134:135], s[0:1], s36, v0, v[130:131]
	s_branch .LBB0_243

; __device__ __forceinline__ int tid_() { int t = threadIdx.x; asm volatile("" : "+v"(t)); return t; }
; template <int NT, bool BKN, bool MASK = false, bool ROWSS = false, class Epi> ...
;     ...
;   const int t = tid_(), lane = t & 63, wid = t >> 6, wr = wid >> 1, wc = wid & 1, l16 = lane & 15, quad = lane >> 4;
;   const u16* ap[4];
;   const u16* bp[NT];
;   unsigned amask = 0u;
; #pragma unroll
;   for (int i = 0; i < 4; ++i) {
;     const int row = (t >> 3) + 32 * i;
;     const bool v = MASK ? (row < mvalid) : true;
;     amask |= v ? (1u << i) : 0u;
;     int r = v ? row : 0;
;     if (arows) r = arows[r];
;     ap[i] = A + (size_t)r * lda + (t & 7) * 8;
;   }
; #pragma unroll
;   for (int i = 0; i < NT; ++i) {
;     if (!BKN) bp[i] = B + (size_t)((t >> 3) + 32 * i) * ldb + (t & 7) * 8;
;     else { const int c = t + 256 * i; bp[i] = B + (size_t)(c / CPR) * ldb + (c % CPR) * 8; }
;   }
;   const size_t bstep = BKN ? (size_t)64 * ldb : (size_t)64;
;   int nmi = 4;
;   if (MASK) { nmi = (mvalid - wr * 64 + 15) >> 4; nmi = nmi < 0 ? 0 : (nmi > 4 ? 4 : nmi); nmi = __builtin_amdgcn_readfirstlane(nmi); }
;   u32x4 ra0[4], rb0[NT], ra1[4], rb1[NT];
;     ...
;   float ss_[4] = {0.f, 0.f, 0.f, 0.f};
;   int stk_ = 0;
;   f32x4 acc[4][NT];
; #pragma unroll
;   for (int i = 0; i < 4; ++i)
; #pragma unroll
;     for (int j = 0; j < NT; ++j) acc[i][j] = (f32x4){0.f, 0.f, 0.f, 0.f};
;   const int nk = K >> 6;
;   const int nkm1 = nk - 1;
;   __syncthreads();
;   GEMM_LOAD(ra0, rb0, 0);
;   GEMM_LOAD(ra1, rb1, 1);
;   GEMM_STORE(ra0, rb0, 0);
;   GEMM_LOAD(ra0, rb0, (2 < nkm1 ? 2 : nkm1));
;   __syncthreads();
.LBB0_243:
	v_mov_b64_e32 v[2:3], s[4:5]
	global_load_dwordx2 v[66:67], v[2:3], off offset:280
	s_mul_hi_i32 s0, s9, 0x2e8ba2e9
	s_lshr_b32 s1, s0, 31
	s_ashr_i32 s0, s0, 1
	s_add_i32 s0, s0, s1
	v_mov_b32_e32 v70, v187
	s_mul_i32 s1, s0, 11
	s_lshl_b32 s42, s0, 7
	s_sub_i32 s40, s9, s1
	v_ashrrev_i32_e32 v6, 3, v70
	s_ashr_i32 s43, s42, 31
	v_ashrrev_i32_e32 v7, 31, v6
	s_lshl_b64 s[0:1], s[42:43], 11
	s_ashr_i32 s41, s40, 31
	v_lshlrev_b32_e32 v72, 4, v70
	v_lshlrev_b64 v[68:69], 11, v[6:7]
	s_mov_b64 s[18:19], 0x20000
	s_lshl_b64 s[38:39], s[40:41], 18
	v_and_b32_e32 v0, 0x70, v72
	v_lshl_add_u64 v[8:9], v[68:69], 0, s[18:19]
	s_mov_b64 s[18:19], 0x30000
	v_lshl_add_u64 v[4:5], v[132:133], 0, s[38:39]
	v_lshl_add_u64 v[6:7], v[68:69], 0, s[12:13]
	v_lshl_add_u64 v[10:11], v[68:69], 0, s[18:19]
	s_waitcnt lgkmcnt(0)
	s_barrier
	v_lshrrev_b32_e32 v71, 4, v70
	v_and_b32_e32 v72, 0xffffff80, v72
	v_and_b32_e32 v157, 15, v70
	v_bfe_u32 v159, v70, 4, 2
	v_bfe_u32 v156, v70, 6, 1
	v_ashrrev_i32_e32 v158, 7, v70
	v_mov_b32_e32 v78, 0
	v_mov_b32_e32 v79, v78
	v_mov_b32_e32 v80, v78
	v_mov_b32_e32 v81, v78
	v_mov_b32_e32 v74, v78
	v_mov_b32_e32 v75, v78
	v_mov_b32_e32 v76, v78
	v_mov_b32_e32 v77, v78
	v_mov_b32_e32 v82, v78
	v_mov_b32_e32 v83, v78
	v_mov_b32_e32 v84, v78
	v_mov_b32_e32 v85, v78
	v_mov_b32_e32 v86, v78
	v_mov_b32_e32 v87, v78
	v_mov_b32_e32 v88, v78
	v_mov_b32_e32 v89, v78
	v_mov_b32_e32 v126, v78
	v_mov_b32_e32 v127, v78
	v_mov_b32_e32 v128, v78
	v_mov_b32_e32 v129, v78
	v_mov_b32_e32 v122, v78
	v_mov_b32_e32 v123, v78
	v_mov_b32_e32 v124, v78
	v_mov_b32_e32 v125, v78
	v_mov_b32_e32 v102, v78
	v_mov_b32_e32 v103, v78
	v_mov_b32_e32 v104, v78
	v_mov_b32_e32 v105, v78
	v_mov_b32_e32 v110, v78
	v_mov_b32_e32 v111, v78
	v_mov_b32_e32 v112, v78
	v_mov_b32_e32 v113, v78
	v_mov_b32_e32 v114, v78
	v_mov_b32_e32 v115, v78
	v_mov_b32_e32 v116, v78
	v_mov_b32_e32 v117, v78
	v_mov_b32_e32 v94, v78
	v_mov_b32_e32 v95, v78
	v_mov_b32_e32 v96, v78
	v_mov_b32_e32 v97, v78
	v_mov_b32_e32 v90, v78
	v_mov_b32_e32 v91, v78
	v_mov_b32_e32 v92, v78
	v_mov_b32_e32 v93, v78
	v_mov_b32_e32 v98, v78
	v_mov_b32_e32 v99, v78
	s_waitcnt vmcnt(0)
	v_lshl_add_u64 v[2:3], v[66:67], 0, s[0:1]
	v_lshl_add_u64 v[2:3], v[2:3], 0, v[0:1]
	v_lshl_add_u64 v[136:137], v[2:3], 0, v[68:69]
	v_lshl_add_u64 v[138:139], v[2:3], 0, v[6:7]
	v_lshl_add_u64 v[140:141], v[2:3], 0, v[8:9]
	v_lshl_add_u64 v[142:143], v[2:3], 0, v[10:11]
	v_lshl_add_u64 v[2:3], v[4:5], 0, v[0:1]
	v_lshl_add_u64 v[144:145], v[2:3], 0, v[68:69]
	v_lshl_add_u64 v[146:147], v[2:3], 0, v[6:7]
	v_lshl_add_u64 v[148:149], v[2:3], 0, v[8:9]
	v_lshl_add_u64 v[150:151], v[2:3], 0, v[10:11]
	global_load_dwordx4 v[34:37], v[136:137], off
	global_load_dwordx4 v[38:41], v[138:139], off
	global_load_dwordx4 v[42:45], v[140:141], off
	global_load_dwordx4 v[46:49], v[142:143], off
	global_load_dwordx4 v[50:53], v[144:145], off
	global_load_dwordx4 v[54:57], v[146:147], off
	global_load_dwordx4 v[58:61], v[148:149], off
	global_load_dwordx4 v[62:65], v[150:151], off
	global_load_dwordx4 v[2:5], v[136:137], off offset:128
	global_load_dwordx4 v[26:29], v[138:139], off offset:128
	global_load_dwordx4 v[22:25], v[140:141], off offset:128
	global_load_dwordx4 v[18:21], v[142:143], off offset:128
	global_load_dwordx4 v[6:9], v[144:145], off offset:128
	global_load_dwordx4 v[14:17], v[146:147], off offset:128
	global_load_dwordx4 v[10:13], v[148:149], off offset:128
	global_load_dwordx4 v[30:33], v[150:151], off offset:128
	v_xor_b32_e32 v0, v71, v70
	v_lshlrev_b32_e32 v0, 4, v0
	v_and_or_b32 v163, v0, s14, v72
	v_bfe_u32 v0, v70, 1, 3
	v_bitop3_b32 v71, v71, v0, 3 bitop3:0x6c
	v_lshlrev_b32_e32 v72, 7, v157
	v_bitop3_b32 v0, v159, v0, 4 bitop3:0x36
	v_lshlrev_b32_e32 v71, 4, v71
	v_lshl_or_b32 v73, v158, 13, v72
	v_lshl_or_b32 v72, v156, 13, v72
	v_lshlrev_b32_e32 v0, 4, v0
	v_or_b32_e32 v162, v71, v73
	v_or_b32_e32 v164, v71, v72
	v_or_b32_e32 v160, v0, v73
	v_or_b32_e32 v161, v0, v72
	v_and_b32_e32 v0, 7, v70
	v_lshl_add_u64 v[70:71], s[38:39], 0, v[68:69]
	v_lshl_add_u64 v[68:69], v[68:69], 0, s[0:1]
	v_lshlrev_b32_e32 v0, 4, v0
	v_lshl_add_u64 v[152:153], v[134:135], 0, v[70:71]
	v_lshl_add_u64 v[154:155], v[66:67], 0, v[68:69]
	s_mov_b32 s0, -2
	v_mov_b32_e32 v66, v78
	v_mov_b32_e32 v67, v78
	v_mov_b32_e32 v68, v78
	v_mov_b32_e32 v69, v78
	v_mov_b32_e32 v70, v78
	v_mov_b32_e32 v71, v78
	v_mov_b32_e32 v72, v78
	v_mov_b32_e32 v73, v78
	v_mov_b32_e32 v100, v78
	v_mov_b32_e32 v101, v78
	v_mov_b32_e32 v106, v78
	v_mov_b32_e32 v107, v78
	v_mov_b32_e32 v108, v78
	v_mov_b32_e32 v109, v78
	v_mov_b32_e32 v118, v78
	v_mov_b32_e32 v119, v78
	v_mov_b32_e32 v120, v78
	v_mov_b32_e32 v121, v78
	s_waitcnt vmcnt(0) lgkmcnt(0)
	ds_write_b128 v163, v[34:37]
	ds_write_b128 v163, v[38:41] offset:4096
	ds_write_b128 v163, v[42:45] offset:8192
	ds_write_b128 v163, v[46:49] offset:12288
	ds_write_b128 v163, v[50:53] offset:16384
	ds_write_b128 v163, v[54:57] offset:20480
	ds_write_b128 v163, v[58:61] offset:24576
	ds_write_b128 v163, v[62:65] offset:28672
	global_load_dwordx4 v[34:37], v[136:137], off offset:256
	global_load_dwordx4 v[38:41], v[138:139], off offset:256
	global_load_dwordx4 v[46:49], v[140:141], off offset:256
	global_load_dwordx4 v[42:45], v[142:143], off offset:256
	global_load_dwordx4 v[50:53], v[144:145], off offset:256
	global_load_dwordx4 v[58:61], v[146:147], off offset:256
	global_load_dwordx4 v[54:57], v[148:149], off offset:256
	global_load_dwordx4 v[62:65], v[150:151], off offset:256
	s_waitcnt lgkmcnt(0)
	s_barrier
; template <int NT, bool BKN, bool MASK = false, bool ROWSS = false, class Epi> ...
;     ...
;   for (int kt = 0; kt < nk - 2; kt += 2) {
;     GEMM_COMPUTE(0);
;     GEMM_STORE(ra1, rb1, 1);
;     GEMM_LOAD(ra1, rb1, kt + 3);
;     __syncthreads();
.LBB0_244:
	ds_read_b128 v[166:169], v162
	ds_read_b128 v[170:173], v164 offset:16384
	ds_read_b128 v[174:177], v162 offset:2048
	ds_read_b128 v[178:181], v164 offset:18432
	ds_read_b128 v[182:185], v164 offset:20480
	ds_read_b128 v[188:191], v164 offset:22528
	s_add_i32 s0, s0, 2
	s_waitcnt lgkmcnt(0)
	v_mfma_f32_16x16x32_bf16 v[118:121], v[166:169], v[170:173], v[118:121]
	s_min_u32 s1, s0, 11
	s_lshl_b32 s94, s1, 7
	s_cmp_lt_u32 s0, 12
	v_mfma_f32_16x16x32_bf16 v[106:109], v[166:169], v[178:181], v[106:109]
	v_mfma_f32_16x16x32_bf16 v[98:101], v[166:169], v[182:185], v[98:101]
	v_mfma_f32_16x16x32_bf16 v[90:93], v[166:169], v[188:191], v[90:93]
	v_mfma_f32_16x16x32_bf16 v[94:97], v[174:177], v[170:173], v[94:97]
	v_mfma_f32_16x16x32_bf16 v[114:117], v[174:177], v[178:181], v[114:117]
	v_mfma_f32_16x16x32_bf16 v[110:113], v[174:177], v[182:185], v[110:113]
	v_mfma_f32_16x16x32_bf16 v[102:105], v[174:177], v[188:191], v[102:105]
	ds_read_b128 v[166:169], v162 offset:4096
	ds_read_b128 v[174:177], v162 offset:6144
	s_waitcnt lgkmcnt(0)
	v_mfma_f32_16x16x32_bf16 v[122:125], v[166:169], v[170:173], v[122:125]
	v_mfma_f32_16x16x32_bf16 v[126:129], v[166:169], v[178:181], v[126:129]
	v_mfma_f32_16x16x32_bf16 v[86:89], v[166:169], v[182:185], v[86:89]
	v_mfma_f32_16x16x32_bf16 v[82:85], v[166:169], v[188:191], v[82:85]
	v_mfma_f32_16x16x32_bf16 v[74:77], v[174:177], v[170:173], v[74:77]
	v_mfma_f32_16x16x32_bf16 v[70:73], v[174:177], v[178:181], v[70:73]
	ds_read_b128 v[166:169], v160
	ds_read_b128 v[170:173], v160 offset:2048
	ds_read_b128 v[178:181], v161 offset:16384
	v_mfma_f32_16x16x32_bf16 v[66:69], v[174:177], v[182:185], v[66:69]
	v_mfma_f32_16x16x32_bf16 v[78:81], v[174:177], v[188:191], v[78:81]
	ds_read_b128 v[174:177], v160 offset:4096
	ds_read_b128 v[182:185], v160 offset:6144
	ds_read_b128 v[188:191], v161 offset:18432
	ds_read_b128 v[192:195], v161 offset:20480
	ds_read_b128 v[196:199], v161 offset:22528
	ds_write_b128 v163, v[2:5] offset:32768
	ds_write_b128 v163, v[26:29] offset:36864
	ds_write_b128 v163, v[22:25] offset:40960
	ds_write_b128 v163, v[18:21] offset:45056
	ds_write_b128 v163, v[6:9] offset:49152
	ds_write_b128 v163, v[14:17] offset:53248
	ds_write_b128 v163, v[10:13] offset:57344
	v_lshl_add_u64 v[6:7], v[154:155], 0, v[0:1]
	v_add_co_u32_e32 v12, vcc, s15, v6
	v_lshl_add_u64 v[10:11], v[152:153], 0, v[0:1]
	s_nop 0
	v_addc_co_u32_e32 v13, vcc, 0, v7, vcc
	v_add_co_u32_e32 v14, vcc, s16, v6
	ds_write_b128 v163, v[30:33] offset:61440
	s_nop 0
	v_addc_co_u32_e32 v15, vcc, 0, v7, vcc
	v_add_co_u32_e32 v16, vcc, s17, v6
	s_waitcnt lgkmcnt(0)
	v_mfma_f32_16x16x32_bf16 v[118:121], v[166:169], v[178:181], v[118:121]
	v_addc_co_u32_e32 v17, vcc, 0, v7, vcc
	v_add_co_u32_e32 v30, vcc, s15, v10
	v_mfma_f32_16x16x32_bf16 v[106:109], v[166:169], v[188:191], v[106:109]
	s_nop 0
	v_addc_co_u32_e32 v31, vcc, 0, v11, vcc
	v_add_co_u32_e32 v32, vcc, s16, v10
	v_mfma_f32_16x16x32_bf16 v[98:101], v[166:169], v[192:195], v[98:101]
	s_nop 0
	v_addc_co_u32_e32 v33, vcc, 0, v11, vcc
	global_load_dwordx4 v[2:5], v[6:7], off offset:384
	v_mfma_f32_16x16x32_bf16 v[90:93], v[166:169], v[196:199], v[90:93]
	v_add_co_u32_e32 v166, vcc, s17, v10
	global_load_dwordx4 v[6:9], v[10:11], off offset:384
	s_nop 0
	v_addc_co_u32_e32 v167, vcc, 0, v11, vcc
	global_load_dwordx4 v[26:29], v[12:13], off offset:384
	global_load_dwordx4 v[22:25], v[14:15], off offset:384
	global_load_dwordx4 v[18:21], v[16:17], off offset:384
	s_nop 0
	global_load_dwordx4 v[14:17], v[30:31], off offset:384
	global_load_dwordx4 v[10:13], v[32:33], off offset:384
	s_nop 0
	global_load_dwordx4 v[30:33], v[166:167], off offset:384
	s_waitcnt lgkmcnt(0)
	s_barrier
	ds_read_b128 v[166:169], v162 offset:32768
	v_mfma_f32_16x16x32_bf16 v[94:97], v[170:173], v[178:181], v[94:97]
	v_lshl_add_u64 v[152:153], v[152:153], 0, s[6:7]
	v_lshl_add_u64 v[154:155], v[154:155], 0, s[6:7]
	v_mfma_f32_16x16x32_bf16 v[114:117], v[170:173], v[188:191], v[114:117]
	v_mfma_f32_16x16x32_bf16 v[110:113], v[170:173], v[192:195], v[110:113]
	v_mfma_f32_16x16x32_bf16 v[102:105], v[170:173], v[196:199], v[102:105]
	v_mfma_f32_16x16x32_bf16 v[122:125], v[174:177], v[178:181], v[122:125]
	v_mfma_f32_16x16x32_bf16 v[126:129], v[174:177], v[188:191], v[126:129]
	v_mfma_f32_16x16x32_bf16 v[86:89], v[174:177], v[192:195], v[86:89]
	v_mfma_f32_16x16x32_bf16 v[82:85], v[174:177], v[196:199], v[82:85]
	v_mfma_f32_16x16x32_bf16 v[74:77], v[182:185], v[178:181], v[74:77]
	ds_read_b128 v[170:173], v164 offset:49152
	ds_read_b128 v[174:177], v162 offset:34816
	ds_read_b128 v[178:181], v164 offset:51200
	v_mfma_f32_16x16x32_bf16 v[70:73], v[182:185], v[188:191], v[70:73]
	v_mfma_f32_16x16x32_bf16 v[66:69], v[182:185], v[192:195], v[66:69]
	v_mfma_f32_16x16x32_bf16 v[78:81], v[182:185], v[196:199], v[78:81]
	ds_read_b128 v[182:185], v164 offset:53248
	ds_read_b128 v[188:191], v164 offset:55296
	s_waitcnt lgkmcnt(0)
	v_mfma_f32_16x16x32_bf16 v[118:121], v[166:169], v[170:173], v[118:121]
	v_mfma_f32_16x16x32_bf16 v[106:109], v[166:169], v[178:181], v[106:109]
	v_mfma_f32_16x16x32_bf16 v[98:101], v[166:169], v[182:185], v[98:101]
	v_mfma_f32_16x16x32_bf16 v[90:93], v[166:169], v[188:191], v[90:93]
	v_mfma_f32_16x16x32_bf16 v[94:97], v[174:177], v[170:173], v[94:97]
	v_mfma_f32_16x16x32_bf16 v[114:117], v[174:177], v[178:181], v[114:117]
	v_mfma_f32_16x16x32_bf16 v[110:113], v[174:177], v[182:185], v[110:113]
	v_mfma_f32_16x16x32_bf16 v[102:105], v[174:177], v[188:191], v[102:105]
	ds_read_b128 v[166:169], v162 offset:36864
	ds_read_b128 v[174:177], v162 offset:38912
	s_waitcnt lgkmcnt(0)
; template <int NT, bool BKN, bool MASK = false, bool ROWSS = false, class Epi> ...
;     ...
;   for (int kt = 0; kt < nk - 2; kt += 2) {
;     GEMM_COMPUTE(0);
;     GEMM_STORE(ra1, rb1, 1);
;     GEMM_LOAD(ra1, rb1, kt + 3);
;     __syncthreads();
;     GEMM_COMPUTE(1);
;     GEMM_STORE(ra0, rb0, 0);
;     GEMM_LOAD(ra0, rb0, (kt + 4 < nkm1 ? kt + 4 : nkm1));
;     __syncthreads();
;   }
;   GEMM_COMPUTE(0);
;   GEMM_STORE(ra1, rb1, 1);
;   __syncthreads();
;   GEMM_COMPUTE(1);
	v_mfma_f32_16x16x32_bf16 v[122:125], v[166:169], v[170:173], v[122:125]
	v_mfma_f32_16x16x32_bf16 v[126:129], v[166:169], v[178:181], v[126:129]
	v_mfma_f32_16x16x32_bf16 v[86:89], v[166:169], v[182:185], v[86:89]
	v_mfma_f32_16x16x32_bf16 v[82:85], v[166:169], v[188:191], v[82:85]
	ds_read_b128 v[166:169], v160 offset:32768
	v_mfma_f32_16x16x32_bf16 v[74:77], v[174:177], v[170:173], v[74:77]
	v_mfma_f32_16x16x32_bf16 v[70:73], v[174:177], v[178:181], v[70:73]
	v_mfma_f32_16x16x32_bf16 v[66:69], v[174:177], v[182:185], v[66:69]
	v_mfma_f32_16x16x32_bf16 v[78:81], v[174:177], v[188:191], v[78:81]
	ds_read_b128 v[170:173], v161 offset:49152
	ds_read_b128 v[174:177], v160 offset:34816
	ds_read_b128 v[178:181], v161 offset:51200
	ds_read_b128 v[182:185], v161 offset:53248
	ds_read_b128 v[188:191], v161 offset:55296
	s_waitcnt lgkmcnt(0)
	v_mfma_f32_16x16x32_bf16 v[118:121], v[166:169], v[170:173], v[118:121]
	v_mfma_f32_16x16x32_bf16 v[106:109], v[166:169], v[178:181], v[106:109]
	v_mfma_f32_16x16x32_bf16 v[98:101], v[166:169], v[182:185], v[98:101]
	v_mfma_f32_16x16x32_bf16 v[90:93], v[166:169], v[188:191], v[90:93]
	ds_read_b128 v[166:169], v160 offset:36864
	ds_read_b128 v[192:195], v160 offset:38912
	s_waitcnt vmcnt(0)
	ds_write_b128 v163, v[34:37]
	ds_write_b128 v163, v[38:41] offset:4096
	ds_write_b128 v163, v[46:49] offset:8192
	ds_write_b128 v163, v[42:45] offset:12288
	ds_write_b128 v163, v[50:53] offset:16384
	ds_write_b128 v163, v[58:61] offset:20480
	ds_write_b128 v163, v[54:57] offset:24576
	ds_write_b128 v163, v[62:65] offset:28672
	v_lshl_add_u64 v[34:35], v[136:137], 0, s[94:95]
	v_lshl_add_u64 v[38:39], v[138:139], 0, s[94:95]
	v_lshl_add_u64 v[42:43], v[140:141], 0, s[94:95]
	v_lshl_add_u64 v[44:45], v[142:143], 0, s[94:95]
	v_lshl_add_u64 v[50:51], v[144:145], 0, s[94:95]
	v_lshl_add_u64 v[54:55], v[146:147], 0, s[94:95]
	v_lshl_add_u64 v[56:57], v[148:149], 0, s[94:95]
	v_lshl_add_u64 v[62:63], v[150:151], 0, s[94:95]
	global_load_dwordx4 v[34:37], v[34:35], off offset:512
	s_nop 0
	global_load_dwordx4 v[38:41], v[38:39], off offset:512
	s_nop 0
	global_load_dwordx4 v[46:49], v[42:43], off offset:512
	s_nop 0
	global_load_dwordx4 v[42:45], v[44:45], off offset:512
	s_nop 0
	global_load_dwordx4 v[50:53], v[50:51], off offset:512
	s_nop 0
	global_load_dwordx4 v[58:61], v[54:55], off offset:512
	s_nop 0
	global_load_dwordx4 v[54:57], v[56:57], off offset:512
	v_mfma_f32_16x16x32_bf16 v[94:97], v[174:177], v[170:173], v[94:97]
	global_load_dwordx4 v[62:65], v[62:63], off offset:512
	s_waitcnt lgkmcnt(0)
	s_barrier
	v_mfma_f32_16x16x32_bf16 v[114:117], v[174:177], v[178:181], v[114:117]
	v_mfma_f32_16x16x32_bf16 v[110:113], v[174:177], v[182:185], v[110:113]
	v_mfma_f32_16x16x32_bf16 v[102:105], v[174:177], v[188:191], v[102:105]
	v_mfma_f32_16x16x32_bf16 v[122:125], v[166:169], v[170:173], v[122:125]
	v_mfma_f32_16x16x32_bf16 v[126:129], v[166:169], v[178:181], v[126:129]
	v_mfma_f32_16x16x32_bf16 v[86:89], v[166:169], v[182:185], v[86:89]
	v_mfma_f32_16x16x32_bf16 v[82:85], v[166:169], v[188:191], v[82:85]
	v_mfma_f32_16x16x32_bf16 v[74:77], v[192:195], v[170:173], v[74:77]
	v_mfma_f32_16x16x32_bf16 v[70:73], v[192:195], v[178:181], v[70:73]
	v_mfma_f32_16x16x32_bf16 v[66:69], v[192:195], v[182:185], v[66:69]
	v_mfma_f32_16x16x32_bf16 v[78:81], v[192:195], v[188:191], v[78:81]
	s_cbranch_scc1 .LBB0_244
	s_waitcnt vmcnt(0)
	ds_read_b128 v[34:37], v162
	ds_read_b128 v[38:41], v164 offset:16384
	ds_read_b128 v[46:49], v164 offset:18432
	ds_read_b128 v[54:57], v164 offset:20480
	ds_read_b128 v[62:65], v164 offset:22528
	s_cmp_lt_i32 s40, 4
	s_waitcnt lgkmcnt(3)
	v_mfma_f32_16x16x32_bf16 v[42:45], v[34:37], v[38:41], v[118:121]
	s_cselect_b64 s[0:1], -1, 0
	s_cmp_gt_i32 s40, 3
	s_cselect_b64 s[46:47], -1, 0
	s_waitcnt lgkmcnt(2)
	v_mfma_f32_16x16x32_bf16 v[50:53], v[34:37], v[46:49], v[106:109]
	s_and_b64 vcc, exec, s[46:47]
	s_waitcnt lgkmcnt(1)
	v_mfma_f32_16x16x32_bf16 v[58:61], v[34:37], v[54:57], v[98:101]
	s_waitcnt lgkmcnt(0)
	v_mfma_f32_16x16x32_bf16 v[34:37], v[34:37], v[62:65], v[90:93]
	s_nop 2
	ds_read_b128 v[90:93], v162 offset:2048
	s_waitcnt lgkmcnt(0)
	v_mfma_f32_16x16x32_bf16 v[94:97], v[90:93], v[38:41], v[94:97]
	v_mfma_f32_16x16x32_bf16 v[98:101], v[90:93], v[46:49], v[114:117]
	v_mfma_f32_16x16x32_bf16 v[106:109], v[90:93], v[54:57], v[110:113]
	v_mfma_f32_16x16x32_bf16 v[90:93], v[90:93], v[62:65], v[102:105]
	s_nop 2
	ds_read_b128 v[102:105], v162 offset:4096
	s_waitcnt lgkmcnt(0)
	v_mfma_f32_16x16x32_bf16 v[110:113], v[102:105], v[38:41], v[122:125]
	v_mfma_f32_16x16x32_bf16 v[114:117], v[102:105], v[46:49], v[126:129]
	v_mfma_f32_16x16x32_bf16 v[86:89], v[102:105], v[54:57], v[86:89]
	v_mfma_f32_16x16x32_bf16 v[82:85], v[102:105], v[62:65], v[82:85]
	ds_read_b128 v[102:105], v162 offset:6144
	s_waitcnt lgkmcnt(0)
	v_mfma_f32_16x16x32_bf16 v[54:57], v[102:105], v[54:57], v[66:69]
	s_nop 2
	ds_read_b128 v[66:69], v160
	v_mfma_f32_16x16x32_bf16 v[38:41], v[102:105], v[38:41], v[74:77]
	v_mfma_f32_16x16x32_bf16 v[46:49], v[102:105], v[46:49], v[70:73]
	s_nop 1
	ds_read_b128 v[74:77], v161 offset:18432
	v_mfma_f32_16x16x32_bf16 v[62:65], v[102:105], v[62:65], v[78:81]
	ds_read_b128 v[70:73], v161 offset:16384
	ds_read_b128 v[102:105], v161 offset:22528
	s_nop 0
	ds_read_b128 v[78:81], v161 offset:20480
	s_waitcnt lgkmcnt(2)
	v_mfma_f32_16x16x32_bf16 v[42:45], v[66:69], v[70:73], v[42:45]
	v_mfma_f32_16x16x32_bf16 v[50:53], v[66:69], v[74:77], v[50:53]
	s_waitcnt lgkmcnt(0)
	v_mfma_f32_16x16x32_bf16 v[58:61], v[66:69], v[78:81], v[58:61]
	v_mfma_f32_16x16x32_bf16 v[34:37], v[66:69], v[102:105], v[34:37]
	ds_read_b128 v[66:69], v160 offset:2048
	s_waitcnt lgkmcnt(0)
	v_mfma_f32_16x16x32_bf16 v[94:97], v[66:69], v[70:73], v[94:97]
	v_mfma_f32_16x16x32_bf16 v[98:101], v[66:69], v[74:77], v[98:101]
	v_mfma_f32_16x16x32_bf16 v[106:109], v[66:69], v[78:81], v[106:109]
	v_mfma_f32_16x16x32_bf16 v[66:69], v[66:69], v[102:105], v[90:93]
	s_nop 2
	ds_read_b128 v[90:93], v160 offset:4096
	s_waitcnt lgkmcnt(0)
	v_mfma_f32_16x16x32_bf16 v[110:113], v[90:93], v[70:73], v[110:113]
	v_mfma_f32_16x16x32_bf16 v[114:117], v[90:93], v[74:77], v[114:117]
	v_mfma_f32_16x16x32_bf16 v[86:89], v[90:93], v[78:81], v[86:89]
	v_mfma_f32_16x16x32_bf16 v[82:85], v[90:93], v[102:105], v[82:85]
	ds_read_b128 v[90:93], v160 offset:6144
	ds_write_b128 v163, v[2:5] offset:32768
	ds_write_b128 v163, v[26:29] offset:36864
	ds_write_b128 v163, v[22:25] offset:40960
	ds_write_b128 v163, v[18:21] offset:45056
	ds_write_b128 v163, v[6:9] offset:49152
	ds_write_b128 v163, v[14:17] offset:53248
	ds_write_b128 v163, v[10:13] offset:57344
	ds_write_b128 v163, v[30:33] offset:61440
	s_waitcnt lgkmcnt(0)
	s_barrier
; __device__ __forceinline__ float gelu_tanh(float x) {
;   float y = 0.7978845608028654f * (x + 0.044715f * x * x * x);
;   return x / (1.f + __expf(-2.f * y));
; }
; template <int NT, bool BKN, bool MASK = false, bool ROWSS = false, class Epi> ...
;     ...
;   GEMM_COMPUTE(0);
;   GEMM_STORE(ra1, rb1, 1);
;   __syncthreads();
;   GEMM_COMPUTE(1);
	ds_read_b128 v[2:5], v162 offset:32768
	ds_read_b128 v[10:13], v164 offset:49152
	s_waitcnt lgkmcnt(0)
	v_mfma_f32_16x16x32_bf16 v[14:17], v[2:5], v[10:13], v[42:45]
	ds_read_b128 v[18:21], v164 offset:51200
	ds_read_b128 v[26:29], v164 offset:53248
	s_nop 0
	ds_read_b128 v[42:45], v164 offset:55296
	s_waitcnt lgkmcnt(2)
	v_mfma_f32_16x16x32_bf16 v[22:25], v[2:5], v[18:21], v[50:53]
	s_nop 2
	ds_read_b128 v[50:53], v162 offset:36864
	s_waitcnt lgkmcnt(2)
	v_mfma_f32_16x16x32_bf16 v[30:33], v[2:5], v[26:29], v[58:61]
	s_waitcnt lgkmcnt(1)
	v_mfma_f32_16x16x32_bf16 v[2:5], v[2:5], v[42:45], v[34:37]
	s_nop 2
	ds_read_b128 v[34:37], v162 offset:34816
	v_mfma_f32_16x16x32_bf16 v[38:41], v[90:93], v[70:73], v[38:41]
	v_mfma_f32_16x16x32_bf16 v[46:49], v[90:93], v[74:77], v[46:49]
	v_mfma_f32_16x16x32_bf16 v[54:57], v[90:93], v[78:81], v[54:57]
	v_mfma_f32_16x16x32_bf16 v[6:9], v[90:93], v[102:105], v[62:65]
	s_waitcnt lgkmcnt(0)
	v_mfma_f32_16x16x32_bf16 v[70:73], v[34:37], v[10:13], v[94:97]
	v_mfma_f32_16x16x32_bf16 v[74:77], v[34:37], v[18:21], v[98:101]
	v_mfma_f32_16x16x32_bf16 v[78:81], v[34:37], v[26:29], v[106:109]
	v_mfma_f32_16x16x32_bf16 v[34:37], v[34:37], v[42:45], v[66:69]
	s_nop 1
	ds_read_b128 v[106:109], v161 offset:51200
	v_mfma_f32_16x16x32_bf16 v[66:69], v[50:53], v[10:13], v[110:113]
	v_mfma_f32_16x16x32_bf16 v[90:93], v[50:53], v[18:21], v[114:117]
	s_nop 1
	ds_read_b128 v[110:113], v161 offset:53248
	ds_read_b128 v[114:117], v161 offset:55296
	v_mfma_f32_16x16x32_bf16 v[86:89], v[50:53], v[26:29], v[86:89]
	v_mfma_f32_16x16x32_bf16 v[82:85], v[50:53], v[42:45], v[82:85]
	ds_read_b128 v[50:53], v162 offset:38912
	s_waitcnt lgkmcnt(0)
	v_mfma_f32_16x16x32_bf16 v[94:97], v[50:53], v[18:21], v[46:49]
	ds_read_b128 v[18:21], v160 offset:32768
	v_mfma_f32_16x16x32_bf16 v[10:13], v[50:53], v[10:13], v[38:41]
	v_mfma_f32_16x16x32_bf16 v[98:101], v[50:53], v[26:29], v[54:57]
	v_mfma_f32_16x16x32_bf16 v[102:105], v[50:53], v[42:45], v[6:9]
	s_nop 2
	ds_read_b128 v[6:9], v161 offset:49152
	s_waitcnt lgkmcnt(1)
	v_mfma_f32_16x16x32_bf16 v[50:53], v[18:21], v[114:117], v[2:5]
	s_nop 2
	ds_read_b128 v[2:5], v160 offset:34816
	s_waitcnt lgkmcnt(0)
	v_mfma_f32_16x16x32_bf16 v[46:49], v[2:5], v[6:9], v[70:73]
	v_mfma_f32_16x16x32_bf16 v[42:45], v[2:5], v[106:109], v[74:77]
	v_mfma_f32_16x16x32_bf16 v[38:41], v[2:5], v[110:113], v[78:81]
	v_mfma_f32_16x16x32_bf16 v[34:37], v[2:5], v[114:117], v[34:37]
	ds_read_b128 v[2:5], v160 offset:36864
	v_mfma_f32_16x16x32_bf16 v[62:65], v[18:21], v[6:9], v[14:17]
	v_mfma_f32_16x16x32_bf16 v[58:61], v[18:21], v[106:109], v[22:25]
	v_mfma_f32_16x16x32_bf16 v[54:57], v[18:21], v[110:113], v[30:33]
	s_waitcnt lgkmcnt(0)
	v_mfma_f32_16x16x32_bf16 v[30:33], v[2:5], v[6:9], v[66:69]
	v_mfma_f32_16x16x32_bf16 v[26:29], v[2:5], v[106:109], v[90:93]
	s_nop 1
	v_mov_b32_e32 v66, v187
	v_mfma_f32_16x16x32_bf16 v[22:25], v[2:5], v[110:113], v[86:89]
	v_mfma_f32_16x16x32_bf16 v[18:21], v[2:5], v[114:117], v[82:85]
	ds_read_b128 v[2:5], v160 offset:38912
	s_waitcnt lgkmcnt(0)
	v_mfma_f32_16x16x32_bf16 v[14:17], v[2:5], v[6:9], v[10:13]
	s_barrier
	v_mfma_f32_16x16x32_bf16 v[10:13], v[2:5], v[106:109], v[94:97]
	v_mfma_f32_16x16x32_bf16 v[6:9], v[2:5], v[110:113], v[98:101]
	v_mfma_f32_16x16x32_bf16 v[2:5], v[2:5], v[114:117], v[102:105]
	s_cbranch_vccnz .LBB0_247
	v_mul_f32_e32 v0, 0x3d372713, v62
	v_mul_f32_e32 v0, v62, v0
	v_fma_f32 v0, v62, v0, v62
	v_mul_f32_e32 v0, 0x3f4c422a, v0
	v_mul_f32_e32 v0, -2.0, v0
	v_mul_f32_e32 v0, 0x3fb8aa3b, v0
	v_exp_f32_e32 v0, v0
	s_nop 0
	v_add_f32_e32 v0, 1.0, v0
	v_div_scale_f32 v67, s[18:19], v0, v0, v62
	v_rcp_f32_e32 v68, v67
	v_div_scale_f32 v69, vcc, v62, v0, v62
	v_fma_f32 v70, -v67, v68, 1.0
	v_fmac_f32_e32 v68, v70, v68
	v_mul_f32_e32 v70, v69, v68
	v_fma_f32 v71, -v67, v70, v69
	v_fmac_f32_e32 v70, v71, v68
	v_fma_f32 v67, -v67, v70, v69
	v_div_fmas_f32 v67, v67, v68, v70
	v_div_fixup_f32 v62, v67, v0, v62

; template <int NT, class VF, class RP>
; __device__ __forceinline__ void epi_staged_bf16(f32x4 (&acc)[4][NT], int r0, int c0, unsigned char* smem, VF vf, RP rowptr) {
;     ...
;   __syncthreads();
; #pragma unroll
;   for (int i = 0; i < CPR / 2; ++i) {
;     const int c = t + 256 * i, row = c / CPR, ch = c % CPR;
;     u16* d = rowptr(row);
;     if (d) *(u32x4*)(d + ch * 8) = *(const u32x4*)(Ts + row * PITCH + ch * 8);
; __device__ __forceinline__ void phase_in_gemm(const Params& p, int l, unsigned char* smem) {
;     ...
;       auto rp = [&](int r) -> u16* {
;         const int row = row_base + r;
;         if (nt < 4) return p.PX + (size_t)row * 1024 + nt * 128;
;         if (nt >= 8) return p.PX + (size_t)row * 1024 + 512 + (nt - 8) * 128;
;         const int ri = (nt - 4) >> 1, jx = ((nt - 4) & 1) * 128;
;         if (row < T_LAT) return p.GD + ((size_t)((row >> 13) * 2 + ri) * SEQ + (row & (SEQ - 1))) * 256 + jx;
;         const int rc = row - T_LAT;
;         return p.GDc + ((size_t)((rc >> 8) * 2 + ri) * CTX + (rc & 255)) * 256 + jx;
;       };
.LBB0_315:
	v_cvt_pk_bf16_f32 v2, v5, s0
	ds_write_b16 v0, v2 offset:13968
	v_ashrrev_i32_e32 v0, 31, v66
	v_lshrrev_b32_e32 v0, 28, v0
	v_add_u32_e32 v0, v66, v0
	v_ashrrev_i32_e32 v6, 4, v0
	v_add_u32_e32 v2, s42, v6
	s_mov_b64 s[0:1], -1
	s_and_b64 vcc, exec, s[46:47]
	s_waitcnt lgkmcnt(0)
	s_barrier
	s_cbranch_vccz .LBB0_468
	s_cmp_lt_u32 s40, 8
	s_cbranch_scc0 .LBB0_322
	s_add_i32 s0, s40, -4
	s_lshr_b32 s19, s0, 1
	s_lshl_b32 s0, s40, 7
	s_and_b32 s18, s0, 0x80
	s_movk_i32 s0, 0x3fff
	v_cmp_lt_i32_e32 vcc, s0, v2
	v_lshlrev_b32_e32 v3, 9, v2
	s_and_saveexec_b64 s[0:1], vcc
	s_xor_b64 s[0:1], exec, s[0:1]
	s_cbranch_execz .LBB0_319
	v_mov_b64_e32 v[4:5], s[4:5]
	global_load_dwordx2 v[4:5], v[4:5], off offset:312
	v_add_u32_e32 v0, 0xffffc000, v2
	v_lshrrev_b32_e32 v0, 7, v0
	v_and_b32_e32 v0, 0x1fffffe, v0
	v_add_u32_e32 v0, s19, v0
	v_lshlrev_b64 v[8:9], 17, v[0:1]
	v_and_b32_e32 v0, 0x1fe00, v3
	s_lshl_b32 s94, s18, 1
	s_waitcnt vmcnt(0) lgkmcnt(0)
	v_lshl_add_u64 v[4:5], v[4:5], 0, v[8:9]
	v_lshl_add_u64 v[4:5], v[4:5], 0, v[0:1]
	v_lshl_add_u64 v[4:5], v[4:5], 0, s[94:95]
.LBB0_319:
	s_andn2_saveexec_b64 s[0:1], s[0:1]
	s_cbranch_execz .LBB0_321
	v_mov_b64_e32 v[4:5], s[4:5]
	global_load_dwordx2 v[4:5], v[4:5], off offset:304
	v_ashrrev_i32_e32 v7, 12, v2
	v_and_b32_e32 v0, 0x3ffe00, v3
	v_and_b32_e32 v3, -2, v7
	v_add_u32_e32 v8, s19, v3
	v_ashrrev_i32_e32 v9, 31, v8
	v_lshlrev_b64 v[8:9], 22, v[8:9]
	s_lshl_b32 s94, s18, 1
	s_waitcnt vmcnt(0) lgkmcnt(0)
	v_lshl_add_u64 v[4:5], v[4:5], 0, v[8:9]
	v_lshl_add_u64 v[4:5], v[4:5], 0, v[0:1]
	v_lshl_add_u64 v[4:5], v[4:5], 0, s[94:95]

; __device__ __forceinline__ void phase_in_gemm(const Params& p, int l, unsigned char* smem) {
;     ...
;       auto rp = [&](int r) -> u16* {
;         const int row = row_base + r;
;         if (nt < 4) return p.PX + (size_t)row * 1024 + nt * 128;
;         if (nt >= 8) return p.PX + (size_t)row * 1024 + 512 + (nt - 8) * 128;
.LBB0_322:
	s_andn2_b64 vcc, exec, s[0:1]
	s_cbranch_vccnz .LBB0_324
	v_mov_b64_e32 v[4:5], s[4:5]
	global_load_dwordx2 v[4:5], v[4:5], off offset:288
	v_ashrrev_i32_e32 v3, 31, v2
	v_lshlrev_b64 v[8:9], 11, v[2:3]
	s_lshl_b32 s94, s40, 8
	s_movk_i32 s0, 0xfc00
	s_mov_b32 s1, -1
	s_waitcnt vmcnt(0) lgkmcnt(0)
	v_lshl_add_u64 v[4:5], v[4:5], 0, v[8:9]
	v_lshl_add_u64 v[4:5], v[4:5], 0, s[94:95]
	v_lshl_add_u64 v[4:5], v[4:5], 0, s[0:1]

; template <int NT, class VF, class RP>
; __device__ __forceinline__ void epi_staged_bf16(f32x4 (&acc)[4][NT], int r0, int c0, unsigned char* smem, VF vf, RP rowptr) {
;     ...
;   for (int i = 0; i < CPR / 2; ++i) {
;     const int c = t + 256 * i, row = c / CPR, ch = c % CPR;
;     u16* d = rowptr(row);
;     if (d) *(u32x4*)(d + ch * 8) = *(const u32x4*)(Ts + row * PITCH + ch * 8);
; __device__ __forceinline__ void phase_in_gemm(const Params& p, int l, unsigned char* smem) {
;     ...
;       auto rp = [&](int r) -> u16* {
;         const int row = row_base + r;
;         if (nt < 4) return p.PX + (size_t)row * 1024 + nt * 128;
;         if (nt >= 8) return p.PX + (size_t)row * 1024 + 512 + (nt - 8) * 128;
;         const int ri = (nt - 4) >> 1, jx = ((nt - 4) & 1) * 128;
;         if (row < T_LAT) return p.GD + ((size_t)((row >> 13) * 2 + ri) * SEQ + (row & (SEQ - 1))) * 256 + jx;
;         const int rc = row - T_LAT;
;         return p.GDc + ((size_t)((rc >> 8) * 2 + ri) * CTX + (rc & 255)) * 256 + jx;
.LBB0_326:
	v_lshlrev_b32_e32 v0, 4, v6
	v_sub_u32_e32 v0, v66, v0
	v_mul_lo_u32 v2, v6, s23
	v_lshl_add_u32 v2, v0, 4, v2
	ds_read_b128 v[6:9], v2
	v_lshlrev_b32_e32 v2, 3, v0
	v_ashrrev_i32_e32 v3, 31, v2
	v_lshl_add_u64 v[2:3], v[2:3], 1, v[4:5]
	s_waitcnt lgkmcnt(0)
	global_store_dwordx4 v[2:3], v[6:9], off
.LBB0_327:
	s_or_b64 exec, exec, s[0:1]
	s_nop 0
	v_add_u32_e32 v6, 0x100, v66
	v_ashrrev_i32_e32 v0, 31, v6
	v_lshrrev_b32_e32 v0, 28, v0
	v_add_u32_e32 v0, v6, v0
	v_ashrrev_i32_e32 v7, 4, v0
	v_cndmask_b32_e64 v0, 0, 1, s[46:47]
	v_add_u32_e32 v2, s42, v7
	v_cmp_ne_u32_e64 s[38:39], 1, v0
	s_andn2_b64 vcc, exec, s[46:47]
	s_mov_b64 s[0:1], -1
	s_cbranch_vccnz .LBB0_470
	s_cmp_gt_u32 s40, 7
	s_cbranch_scc1 .LBB0_334
	s_add_i32 s0, s40, -4
	s_lshr_b32 s19, s0, 1
	s_lshl_b32 s0, s40, 7
	s_and_b32 s18, s0, 0x80
	s_movk_i32 s0, 0x3fff
	v_cmp_lt_i32_e32 vcc, s0, v2
	v_lshlrev_b32_e32 v3, 9, v2
	s_and_saveexec_b64 s[0:1], vcc
	s_xor_b64 s[0:1], exec, s[0:1]
	s_cbranch_execz .LBB0_331
	v_mov_b64_e32 v[4:5], s[4:5]
	global_load_dwordx2 v[4:5], v[4:5], off offset:312
	v_add_u32_e32 v0, 0xffffc000, v2
	v_lshrrev_b32_e32 v0, 7, v0
	v_and_b32_e32 v0, 0x1fffffe, v0
	v_add_u32_e32 v0, s19, v0
	v_lshlrev_b64 v[8:9], 17, v[0:1]
	v_and_b32_e32 v0, 0x1fe00, v3
	s_lshl_b32 s94, s18, 1
	s_waitcnt vmcnt(0) lgkmcnt(0)
	v_lshl_add_u64 v[4:5], v[4:5], 0, v[8:9]
	v_lshl_add_u64 v[4:5], v[4:5], 0, v[0:1]
	v_lshl_add_u64 v[4:5], v[4:5], 0, s[94:95]
.LBB0_331:
	s_andn2_saveexec_b64 s[0:1], s[0:1]
	s_cbranch_execz .LBB0_333
	v_mov_b64_e32 v[4:5], s[4:5]
	global_load_dwordx2 v[4:5], v[4:5], off offset:304
	v_ashrrev_i32_e32 v8, 12, v2
	v_and_b32_e32 v0, 0x3ffe00, v3
	v_and_b32_e32 v3, -2, v8
	v_add_u32_e32 v8, s19, v3
	v_ashrrev_i32_e32 v9, 31, v8
	v_lshlrev_b64 v[8:9], 22, v[8:9]
	s_lshl_b32 s94, s18, 1
	s_waitcnt vmcnt(0) lgkmcnt(0)
	v_lshl_add_u64 v[4:5], v[4:5], 0, v[8:9]
	v_lshl_add_u64 v[4:5], v[4:5], 0, v[0:1]
	v_lshl_add_u64 v[4:5], v[4:5], 0, s[94:95]

; template <int NT, class VF, class RP>
; __device__ __forceinline__ void epi_staged_bf16(f32x4 (&acc)[4][NT], int r0, int c0, unsigned char* smem, VF vf, RP rowptr) {
;     ...
;   for (int i = 0; i < CPR / 2; ++i) {
;     const int c = t + 256 * i, row = c / CPR, ch = c % CPR;
;     u16* d = rowptr(row);
;     if (d) *(u32x4*)(d + ch * 8) = *(const u32x4*)(Ts + row * PITCH + ch * 8);
; __device__ __forceinline__ void phase_in_gemm(const Params& p, int l, unsigned char* smem) {
;     ...
;       auto rp = [&](int r) -> u16* {
;         const int row = row_base + r;
;         if (nt < 4) return p.PX + (size_t)row * 1024 + nt * 128;
;         if (nt >= 8) return p.PX + (size_t)row * 1024 + 512 + (nt - 8) * 128;
;         const int ri = (nt - 4) >> 1, jx = ((nt - 4) & 1) * 128;
;         if (row < T_LAT) return p.GD + ((size_t)((row >> 13) * 2 + ri) * SEQ + (row & (SEQ - 1))) * 256 + jx;
;         const int rc = row - T_LAT;
;         return p.GDc + ((size_t)((rc >> 8) * 2 + ri) * CTX + (rc & 255)) * 256 + jx;
.LBB0_338:
	v_lshlrev_b32_e32 v0, 4, v7
	v_sub_u32_e32 v0, v6, v0
	v_mul_lo_u32 v2, v7, s23
	v_lshl_add_u32 v2, v0, 4, v2
	ds_read_b128 v[6:9], v2
	v_lshlrev_b32_e32 v2, 3, v0
	v_ashrrev_i32_e32 v3, 31, v2
	v_lshl_add_u64 v[2:3], v[2:3], 1, v[4:5]
	s_waitcnt lgkmcnt(0)
	global_store_dwordx4 v[2:3], v[6:9], off
.LBB0_339:
	s_or_b64 exec, exec, s[0:1]
	s_nop 0
	v_add_u32_e32 v6, 0x200, v66
	v_ashrrev_i32_e32 v0, 31, v6
	v_lshrrev_b32_e32 v0, 28, v0
	v_add_u32_e32 v0, v6, v0
	v_ashrrev_i32_e32 v7, 4, v0
	v_add_u32_e32 v2, s42, v7
	s_and_b64 vcc, exec, s[38:39]
	s_mov_b64 s[0:1], -1
	s_cbranch_vccnz .LBB0_472
	s_cmp_gt_u32 s40, 7
	s_cbranch_scc1 .LBB0_346
	s_add_i32 s0, s40, -4
	s_lshr_b32 s19, s0, 1
	s_lshl_b32 s0, s40, 7
	s_and_b32 s18, s0, 0x80
	s_movk_i32 s0, 0x3fff
	v_cmp_lt_i32_e32 vcc, s0, v2
	v_lshlrev_b32_e32 v3, 9, v2
	s_and_saveexec_b64 s[0:1], vcc
	s_xor_b64 s[0:1], exec, s[0:1]
	s_cbranch_execz .LBB0_343
	v_mov_b64_e32 v[4:5], s[4:5]
	global_load_dwordx2 v[4:5], v[4:5], off offset:312
	v_add_u32_e32 v0, 0xffffc000, v2
	v_lshrrev_b32_e32 v0, 7, v0
	v_and_b32_e32 v0, 0x1fffffe, v0
	v_add_u32_e32 v0, s19, v0
	v_lshlrev_b64 v[8:9], 17, v[0:1]
	v_and_b32_e32 v0, 0x1fe00, v3
	s_lshl_b32 s94, s18, 1
	s_waitcnt vmcnt(0) lgkmcnt(0)
	v_lshl_add_u64 v[4:5], v[4:5], 0, v[8:9]
	v_lshl_add_u64 v[4:5], v[4:5], 0, v[0:1]
	v_lshl_add_u64 v[4:5], v[4:5], 0, s[94:95]

; template <int NT, class VF, class RP>
; __device__ __forceinline__ void epi_staged_bf16(f32x4 (&acc)[4][NT], int r0, int c0, unsigned char* smem, VF vf, RP rowptr) {
;     ...
;   for (int i = 0; i < CPR / 2; ++i) {
;     const int c = t + 256 * i, row = c / CPR, ch = c % CPR;
;     u16* d = rowptr(row);
;     if (d) *(u32x4*)(d + ch * 8) = *(const u32x4*)(Ts + row * PITCH + ch * 8);
; __device__ __forceinline__ void phase_in_gemm(const Params& p, int l, unsigned char* smem) {
;     ...
;       auto rp = [&](int r) -> u16* {
;         const int row = row_base + r;
;         if (nt < 4) return p.PX + (size_t)row * 1024 + nt * 128;
;         if (nt >= 8) return p.PX + (size_t)row * 1024 + 512 + (nt - 8) * 128;
;         const int ri = (nt - 4) >> 1, jx = ((nt - 4) & 1) * 128;
;         if (row < T_LAT) return p.GD + ((size_t)((row >> 13) * 2 + ri) * SEQ + (row & (SEQ - 1))) * 256 + jx;
;         const int rc = row - T_LAT;
;         return p.GDc + ((size_t)((rc >> 8) * 2 + ri) * CTX + (rc & 255)) * 256 + jx;
.LBB0_351:
	s_or_b64 exec, exec, s[0:1]
	s_nop 0
	v_add_u32_e32 v6, 0x300, v66
	v_ashrrev_i32_e32 v0, 31, v6
	v_lshrrev_b32_e32 v0, 28, v0
	v_add_u32_e32 v0, v6, v0
	v_ashrrev_i32_e32 v7, 4, v0
	v_add_u32_e32 v2, s42, v7
	s_and_b64 vcc, exec, s[38:39]
	s_mov_b64 s[0:1], -1
	s_cbranch_vccnz .LBB0_474
	s_cmp_gt_u32 s40, 7
	s_cbranch_scc1 .LBB0_358
	s_add_i32 s0, s40, -4
	s_lshr_b32 s19, s0, 1
	s_lshl_b32 s0, s40, 7
	s_and_b32 s18, s0, 0x80
	s_movk_i32 s0, 0x3fff
	v_cmp_lt_i32_e32 vcc, s0, v2
	v_lshlrev_b32_e32 v3, 9, v2
	s_and_saveexec_b64 s[0:1], vcc
	s_xor_b64 s[0:1], exec, s[0:1]
	s_cbranch_execz .LBB0_355
	v_mov_b64_e32 v[4:5], s[4:5]
	global_load_dwordx2 v[4:5], v[4:5], off offset:312
	v_add_u32_e32 v0, 0xffffc000, v2
	v_lshrrev_b32_e32 v0, 7, v0
	v_and_b32_e32 v0, 0x1fffffe, v0
	v_add_u32_e32 v0, s19, v0
	v_lshlrev_b64 v[8:9], 17, v[0:1]
	v_and_b32_e32 v0, 0x1fe00, v3
	s_lshl_b32 s94, s18, 1
	s_waitcnt vmcnt(0) lgkmcnt(0)
	v_lshl_add_u64 v[4:5], v[4:5], 0, v[8:9]
	v_lshl_add_u64 v[4:5], v[4:5], 0, v[0:1]
	v_lshl_add_u64 v[4:5], v[4:5], 0, s[94:95]

; template <int NT, class VF, class RP>
; __device__ __forceinline__ void epi_staged_bf16(f32x4 (&acc)[4][NT], int r0, int c0, unsigned char* smem, VF vf, RP rowptr) {
;     ...
;   for (int i = 0; i < CPR / 2; ++i) {
;     const int c = t + 256 * i, row = c / CPR, ch = c % CPR;
;     u16* d = rowptr(row);
;     if (d) *(u32x4*)(d + ch * 8) = *(const u32x4*)(Ts + row * PITCH + ch * 8);
; __device__ __forceinline__ void phase_in_gemm(const Params& p, int l, unsigned char* smem) {
;     ...
;       auto rp = [&](int r) -> u16* {
;         const int row = row_base + r;
;         if (nt < 4) return p.PX + (size_t)row * 1024 + nt * 128;
;         if (nt >= 8) return p.PX + (size_t)row * 1024 + 512 + (nt - 8) * 128;
;         const int ri = (nt - 4) >> 1, jx = ((nt - 4) & 1) * 128;
;         if (row < T_LAT) return p.GD + ((size_t)((row >> 13) * 2 + ri) * SEQ + (row & (SEQ - 1))) * 256 + jx;
;         const int rc = row - T_LAT;
;         return p.GDc + ((size_t)((rc >> 8) * 2 + ri) * CTX + (rc & 255)) * 256 + jx;
.LBB0_363:
	s_or_b64 exec, exec, s[0:1]
	s_nop 0
	v_add_u32_e32 v6, 0x400, v66
	v_ashrrev_i32_e32 v0, 31, v6
	v_lshrrev_b32_e32 v0, 28, v0
	v_add_u32_e32 v0, v6, v0
	v_ashrrev_i32_e32 v7, 4, v0
	v_add_u32_e32 v2, s42, v7
	s_and_b64 vcc, exec, s[38:39]
	s_mov_b64 s[0:1], -1
	s_cbranch_vccnz .LBB0_476
	s_cmp_gt_u32 s40, 7
	s_cbranch_scc1 .LBB0_370
	s_add_i32 s0, s40, -4
	s_lshr_b32 s19, s0, 1
	s_lshl_b32 s0, s40, 7
	s_and_b32 s18, s0, 0x80
	s_movk_i32 s0, 0x3fff
	v_cmp_lt_i32_e32 vcc, s0, v2
	v_lshlrev_b32_e32 v3, 9, v2
	s_and_saveexec_b64 s[0:1], vcc
	s_xor_b64 s[0:1], exec, s[0:1]
	s_cbranch_execz .LBB0_367
	v_mov_b64_e32 v[4:5], s[4:5]
	global_load_dwordx2 v[4:5], v[4:5], off offset:312
	v_add_u32_e32 v0, 0xffffc000, v2
	v_lshrrev_b32_e32 v0, 7, v0
	v_and_b32_e32 v0, 0x1fffffe, v0
	v_add_u32_e32 v0, s19, v0
	v_lshlrev_b64 v[8:9], 17, v[0:1]
	v_and_b32_e32 v0, 0x1fe00, v3
	s_lshl_b32 s94, s18, 1
	s_waitcnt vmcnt(0) lgkmcnt(0)
	v_lshl_add_u64 v[4:5], v[4:5], 0, v[8:9]
	v_lshl_add_u64 v[4:5], v[4:5], 0, v[0:1]
	v_lshl_add_u64 v[4:5], v[4:5], 0, s[94:95]

; template <int NT, class VF, class RP>
; __device__ __forceinline__ void epi_staged_bf16(f32x4 (&acc)[4][NT], int r0, int c0, unsigned char* smem, VF vf, RP rowptr) {
;     ...
;   for (int i = 0; i < CPR / 2; ++i) {
;     const int c = t + 256 * i, row = c / CPR, ch = c % CPR;
;     u16* d = rowptr(row);
;     if (d) *(u32x4*)(d + ch * 8) = *(const u32x4*)(Ts + row * PITCH + ch * 8);
; __device__ __forceinline__ void phase_in_gemm(const Params& p, int l, unsigned char* smem) {
;     ...
;       auto rp = [&](int r) -> u16* {
;         const int row = row_base + r;
;         if (nt < 4) return p.PX + (size_t)row * 1024 + nt * 128;
;         if (nt >= 8) return p.PX + (size_t)row * 1024 + 512 + (nt - 8) * 128;
;         const int ri = (nt - 4) >> 1, jx = ((nt - 4) & 1) * 128;
;         if (row < T_LAT) return p.GD + ((size_t)((row >> 13) * 2 + ri) * SEQ + (row & (SEQ - 1))) * 256 + jx;
;         const int rc = row - T_LAT;
;         return p.GDc + ((size_t)((rc >> 8) * 2 + ri) * CTX + (rc & 255)) * 256 + jx;
.LBB0_375:
	s_or_b64 exec, exec, s[0:1]
	s_nop 0
	v_add_u32_e32 v6, 0x500, v66
	v_ashrrev_i32_e32 v0, 31, v6
	v_lshrrev_b32_e32 v0, 28, v0
	v_add_u32_e32 v0, v6, v0
	v_ashrrev_i32_e32 v7, 4, v0
	v_add_u32_e32 v2, s42, v7
	s_and_b64 vcc, exec, s[38:39]
	s_mov_b64 s[0:1], -1
	s_cbranch_vccnz .LBB0_478
	s_cmp_gt_u32 s40, 7
	s_cbranch_scc1 .LBB0_382
	s_add_i32 s0, s40, -4
	s_lshr_b32 s19, s0, 1
	s_lshl_b32 s0, s40, 7
	s_and_b32 s18, s0, 0x80
	s_movk_i32 s0, 0x3fff
	v_cmp_lt_i32_e32 vcc, s0, v2
	v_lshlrev_b32_e32 v3, 9, v2
	s_and_saveexec_b64 s[0:1], vcc
	s_xor_b64 s[0:1], exec, s[0:1]
	s_cbranch_execz .LBB0_379
	v_mov_b64_e32 v[4:5], s[4:5]
	global_load_dwordx2 v[4:5], v[4:5], off offset:312
	v_add_u32_e32 v0, 0xffffc000, v2
	v_lshrrev_b32_e32 v0, 7, v0
	v_and_b32_e32 v0, 0x1fffffe, v0
	v_add_u32_e32 v0, s19, v0
	v_lshlrev_b64 v[8:9], 17, v[0:1]
	v_and_b32_e32 v0, 0x1fe00, v3
	s_lshl_b32 s94, s18, 1
	s_waitcnt vmcnt(0) lgkmcnt(0)
	v_lshl_add_u64 v[4:5], v[4:5], 0, v[8:9]
	v_lshl_add_u64 v[4:5], v[4:5], 0, v[0:1]
	v_lshl_add_u64 v[4:5], v[4:5], 0, s[94:95]

; template <int NT, class VF, class RP>
; __device__ __forceinline__ void epi_staged_bf16(f32x4 (&acc)[4][NT], int r0, int c0, unsigned char* smem, VF vf, RP rowptr) {
;     ...
;   for (int i = 0; i < CPR / 2; ++i) {
;     const int c = t + 256 * i, row = c / CPR, ch = c % CPR;
;     u16* d = rowptr(row);
;     if (d) *(u32x4*)(d + ch * 8) = *(const u32x4*)(Ts + row * PITCH + ch * 8);
; __device__ __forceinline__ void phase_in_gemm(const Params& p, int l, unsigned char* smem) {
;     ...
;       auto rp = [&](int r) -> u16* {
;         const int row = row_base + r;
;         if (nt < 4) return p.PX + (size_t)row * 1024 + nt * 128;
;         if (nt >= 8) return p.PX + (size_t)row * 1024 + 512 + (nt - 8) * 128;
;         const int ri = (nt - 4) >> 1, jx = ((nt - 4) & 1) * 128;
;         if (row < T_LAT) return p.GD + ((size_t)((row >> 13) * 2 + ri) * SEQ + (row & (SEQ - 1))) * 256 + jx;
;         const int rc = row - T_LAT;
;         return p.GDc + ((size_t)((rc >> 8) * 2 + ri) * CTX + (rc & 255)) * 256 + jx;
.LBB0_387:
	s_or_b64 exec, exec, s[0:1]
	s_nop 0
	v_add_u32_e32 v6, 0x600, v66
	v_ashrrev_i32_e32 v0, 31, v6
	v_lshrrev_b32_e32 v0, 28, v0
	v_add_u32_e32 v0, v6, v0
	v_ashrrev_i32_e32 v7, 4, v0
	v_add_u32_e32 v2, s42, v7
	s_and_b64 vcc, exec, s[38:39]
	s_mov_b64 s[0:1], -1
	s_cbranch_vccnz .LBB0_480
	s_cmp_gt_u32 s40, 7
	s_cbranch_scc1 .LBB0_394
	s_add_i32 s0, s40, -4
	s_lshr_b32 s19, s0, 1
	s_lshl_b32 s0, s40, 7
	s_and_b32 s18, s0, 0x80
	s_movk_i32 s0, 0x3fff
	v_cmp_lt_i32_e32 vcc, s0, v2
	v_lshlrev_b32_e32 v3, 9, v2
	s_and_saveexec_b64 s[0:1], vcc
	s_xor_b64 s[0:1], exec, s[0:1]
	s_cbranch_execz .LBB0_391
	v_mov_b64_e32 v[4:5], s[4:5]
	global_load_dwordx2 v[4:5], v[4:5], off offset:312
	v_add_u32_e32 v0, 0xffffc000, v2
	v_lshrrev_b32_e32 v0, 7, v0
	v_and_b32_e32 v0, 0x1fffffe, v0
	v_add_u32_e32 v0, s19, v0
	v_lshlrev_b64 v[8:9], 17, v[0:1]
	v_and_b32_e32 v0, 0x1fe00, v3
	s_lshl_b32 s94, s18, 1
	s_waitcnt vmcnt(0) lgkmcnt(0)
	v_lshl_add_u64 v[4:5], v[4:5], 0, v[8:9]
	v_lshl_add_u64 v[4:5], v[4:5], 0, v[0:1]
	v_lshl_add_u64 v[4:5], v[4:5], 0, s[94:95]

; template <int NT, class VF, class RP>
; __device__ __forceinline__ void epi_staged_bf16(f32x4 (&acc)[4][NT], int r0, int c0, unsigned char* smem, VF vf, RP rowptr) {
;     ...
;   for (int i = 0; i < CPR / 2; ++i) {
;     const int c = t + 256 * i, row = c / CPR, ch = c % CPR;
;     u16* d = rowptr(row);
;     if (d) *(u32x4*)(d + ch * 8) = *(const u32x4*)(Ts + row * PITCH + ch * 8);
; __device__ __forceinline__ void phase_in_gemm(const Params& p, int l, unsigned char* smem) {
;     ...
;       auto rp = [&](int r) -> u16* {
;         const int row = row_base + r;
;         if (nt < 4) return p.PX + (size_t)row * 1024 + nt * 128;
;         if (nt >= 8) return p.PX + (size_t)row * 1024 + 512 + (nt - 8) * 128;
;         const int ri = (nt - 4) >> 1, jx = ((nt - 4) & 1) * 128;
;         if (row < T_LAT) return p.GD + ((size_t)((row >> 13) * 2 + ri) * SEQ + (row & (SEQ - 1))) * 256 + jx;
;         const int rc = row - T_LAT;
;         return p.GDc + ((size_t)((rc >> 8) * 2 + ri) * CTX + (rc & 255)) * 256 + jx;
.LBB0_399:
	s_or_b64 exec, exec, s[0:1]
	s_nop 0
	v_add_u32_e32 v6, 0x700, v66
	v_ashrrev_i32_e32 v0, 31, v6
	v_lshrrev_b32_e32 v0, 28, v0
	v_add_u32_e32 v0, v6, v0
	v_ashrrev_i32_e32 v7, 4, v0
	v_add_u32_e32 v2, s42, v7
	s_and_b64 vcc, exec, s[38:39]
	s_mov_b64 s[0:1], -1
	s_cbranch_vccnz .LBB0_482
	s_cmp_gt_u32 s40, 7
	s_cbranch_scc1 .LBB0_406
	s_add_i32 s0, s40, -4
	s_lshr_b32 s19, s0, 1
	s_lshl_b32 s0, s40, 7
	s_and_b32 s18, s0, 0x80
	s_movk_i32 s0, 0x3fff
	v_cmp_lt_i32_e32 vcc, s0, v2
	v_lshlrev_b32_e32 v3, 9, v2
	s_and_saveexec_b64 s[0:1], vcc
	s_xor_b64 s[0:1], exec, s[0:1]
	s_cbranch_execz .LBB0_403
	v_mov_b64_e32 v[4:5], s[4:5]
	global_load_dwordx2 v[4:5], v[4:5], off offset:312
	v_add_u32_e32 v0, 0xffffc000, v2
	v_lshrrev_b32_e32 v0, 7, v0
	v_and_b32_e32 v0, 0x1fffffe, v0
	v_add_u32_e32 v0, s19, v0
	v_lshlrev_b64 v[8:9], 17, v[0:1]
	v_and_b32_e32 v0, 0x1fe00, v3
	s_lshl_b32 s94, s18, 1
	s_waitcnt vmcnt(0) lgkmcnt(0)
	v_lshl_add_u64 v[4:5], v[4:5], 0, v[8:9]
	v_lshl_add_u64 v[4:5], v[4:5], 0, v[0:1]
	v_lshl_add_u64 v[4:5], v[4:5], 0, s[94:95]

; template <int NT, class VF, class RP>
; __device__ __forceinline__ void epi_staged_bf16(f32x4 (&acc)[4][NT], int r0, int c0, unsigned char* smem, VF vf, RP rowptr) {
;     ...
;   for (int i = 0; i < CPR / 2; ++i) {
;     const int c = t + 256 * i, row = c / CPR, ch = c % CPR;
;     u16* d = rowptr(row);
;     if (d) *(u32x4*)(d + ch * 8) = *(const u32x4*)(Ts + row * PITCH + ch * 8);
; __device__ __forceinline__ void phase_in_gemm(const Params& p, int l, unsigned char* smem) {
;     ...
;       auto rp = [&](int r) -> u16* {
;         const int row = row_base + r;
;         if (nt < 4) return p.PX + (size_t)row * 1024 + nt * 128;
.LBB0_469:
	v_mov_b64_e32 v[4:5], s[4:5]
	global_load_dwordx2 v[4:5], v[4:5], off offset:288
	v_ashrrev_i32_e32 v3, 31, v2
	s_lshl_b32 s0, s40, 7
	v_lshlrev_b64 v[2:3], 11, v[2:3]
	s_ashr_i32 s1, s0, 31
	s_waitcnt vmcnt(0) lgkmcnt(0)
	v_lshl_add_u64 v[2:3], v[4:5], 0, v[2:3]
	v_lshl_add_u64 v[4:5], s[0:1], 1, v[2:3]
	v_cmp_ne_u64_e32 vcc, 0, v[4:5]
	s_and_saveexec_b64 s[0:1], vcc
	s_cbranch_execnz .LBB0_326
	s_branch .LBB0_327

; template <int NT, class VF, class RP>
; __device__ __forceinline__ void epi_staged_bf16(f32x4 (&acc)[4][NT], int r0, int c0, unsigned char* smem, VF vf, RP rowptr) {
;     ...
;   for (int i = 0; i < CPR / 2; ++i) {
;     const int c = t + 256 * i, row = c / CPR, ch = c % CPR;
;     u16* d = rowptr(row);
;     if (d) *(u32x4*)(d + ch * 8) = *(const u32x4*)(Ts + row * PITCH + ch * 8);
; __device__ __forceinline__ void phase_in_gemm(const Params& p, int l, unsigned char* smem) {
;     ...
;       auto rp = [&](int r) -> u16* {
;         const int row = row_base + r;
;         if (nt < 4) return p.PX + (size_t)row * 1024 + nt * 128;
.LBB0_483:
	v_mov_b64_e32 v[4:5], s[4:5]
	global_load_dwordx2 v[4:5], v[4:5], off offset:288
	v_ashrrev_i32_e32 v3, 31, v2
	s_lshl_b32 s0, s40, 7
	v_lshlrev_b64 v[2:3], 11, v[2:3]
	s_ashr_i32 s1, s0, 31
	s_waitcnt vmcnt(0) lgkmcnt(0)
	v_lshl_add_u64 v[2:3], v[4:5], 0, v[2:3]
	v_lshl_add_u64 v[4:5], s[0:1], 1, v[2:3]
	v_cmp_ne_u64_e32 vcc, 0, v[4:5]
	s_and_saveexec_b64 s[0:1], vcc
	s_cbranch_execz .LBB0_242
.LBB0_484:
	v_lshlrev_b32_e32 v0, 4, v7
	v_sub_u32_e32 v0, v6, v0
	v_mul_lo_u32 v2, v7, s23
	v_lshl_add_u32 v2, v0, 4, v2
	ds_read_b128 v[6:9], v2
	v_lshlrev_b32_e32 v2, 3, v0
	v_ashrrev_i32_e32 v3, 31, v2
	v_lshl_add_u64 v[2:3], v[2:3], 1, v[4:5]
	s_waitcnt lgkmcnt(0)
	global_store_dwordx4 v[2:3], v[6:9], off
	s_branch .LBB0_242

; #define XCD_FOR(u, T)                                                                                         \
;   for (int _x = bid_() & 7, _gb = gridDim.x >> 3, _hi = (int)(((long)(_x + 1) * (T)) >> 3),                    \
;            u = (int)(((long)_x * (T)) >> 3) + (bid_() >> 3);                                                  \
;        u < _hi; u += _gb)
; template <int NT, bool BKN, bool MASK = false, bool ROWSS = false, class Epi> ...
;     ...
;   float ss_[4] = {0.f, 0.f, 0.f, 0.f};
;   int stk_ = 0;
;   f32x4 acc[4][NT];
; #pragma unroll
;   for (int i = 0; i < 4; ++i)
; #pragma unroll
;     for (int j = 0; j < NT; ++j) acc[i][j] = (f32x4){0.f, 0.f, 0.f, 0.f};
;   const int nk = K >> 6;
;   const int nkm1 = nk - 1;
;   __syncthreads();
;   GEMM_LOAD(ra0, rb0, 0);
;   GEMM_LOAD(ra1, rb1, 1);
;   GEMM_STORE(ra0, rb0, 0);
;   GEMM_LOAD(ra0, rb0, (2 < nkm1 ? 2 : nkm1));
;   __syncthreads();
;   for (int kt = 0; kt < nk - 2; kt += 2) {
;     GEMM_COMPUTE(0);
;     GEMM_STORE(ra1, rb1, 1);
;     GEMM_LOAD(ra1, rb1, kt + 3);
;     __syncthreads();
; __device__ __forceinline__ void phase_in_gemm(const Params& p, int l, unsigned char* smem) {
;     ...
;   XCD_FOR(t, 132) {
;     const int row_base = t * 128;
;     auto epi = [&](f32x4(&acc)[4][2], int r0, int c0) {
;       auto vf = [&](int, int, float v) { return v; };
;       auto rp = [&](int r) -> u16* { return p.PX + (size_t)(row_base + r) * 1024 + 896; };
;       epi_staged_bf16<2>(acc, r0, c0, smem, vf, rp);
;     };
;     gemm_tile<2, false>(p.H + (size_t)row_base * 1024, 1024, nullptr, 128, W + (size_t)11 * 128 * 1024, 1024, 1024, smem, epi);
.LBB0_487:
	s_nop 0
	v_mov_b64_e32 v[2:3], s[4:5]
	global_load_dwordx2 v[100:101], v[2:3], off offset:280
	v_mov_b32_e32 v81, v187
	s_lshl_b32 s40, s1, 7
	v_ashrrev_i32_e32 v2, 3, v81
	v_lshlrev_b32_e32 v98, 4, v81
	v_ashrrev_i32_e32 v3, 31, v2
	s_ashr_i32 s41, s40, 31
	v_and_b32_e32 v0, 0x70, v98
	v_lshlrev_b64 v[136:137], 11, v[2:3]
	s_lshl_b64 s[8:9], s[40:41], 11
	v_lshl_add_u64 v[2:3], v[82:83], 0, v[0:1]
	v_lshl_add_u64 v[4:5], v[136:137], 0, s[12:13]
	v_lshl_add_u64 v[86:87], v[2:3], 0, v[136:137]
	v_lshl_add_u64 v[88:89], v[2:3], 0, v[4:5]
	s_waitcnt lgkmcnt(0)
	s_barrier
	global_load_dwordx4 v[112:115], v[86:87], off
	global_load_dwordx4 v[6:9], v[86:87], off offset:128
	global_load_dwordx4 v[116:119], v[88:89], off
	global_load_dwordx4 v[30:33], v[86:87], off offset:256
	global_load_dwordx4 v[22:25], v[88:89], off offset:128
	global_load_dwordx4 v[46:49], v[88:89], off offset:256
	v_and_b32_e32 v103, 15, v81
	v_bfe_u32 v104, v81, 4, 2
	v_bfe_u32 v99, v81, 1, 3
	s_ashr_i32 s39, s38, 31
	v_bfe_u32 v102, v81, 6, 1
	v_ashrrev_i32_e32 v105, 7, v81
	v_and_b32_e32 v111, 7, v81
	v_lshlrev_b32_e32 v106, 7, v103
	s_lshl_b64 s[18:19], s[38:39], 11
	v_and_b32_e32 v98, 0xffffff80, v98
	v_lshl_or_b32 v107, v105, 13, v106
	v_lshl_or_b32 v106, v102, 12, v106
	v_mov_b32_e32 v50, 0
	v_mov_b32_e32 v51, v50
	v_mov_b32_e32 v52, v50
	v_mov_b32_e32 v53, v50
	v_mov_b32_e32 v54, v50
	v_mov_b32_e32 v55, v50
	v_mov_b32_e32 v56, v50
	v_mov_b32_e32 v57, v50
	v_mov_b32_e32 v58, v50
	v_mov_b32_e32 v59, v50
	v_mov_b32_e32 v60, v50
	v_mov_b32_e32 v61, v50
	v_mov_b32_e32 v62, v50
	v_mov_b32_e32 v63, v50
	v_mov_b32_e32 v64, v50
	v_mov_b32_e32 v65, v50
	v_mov_b32_e32 v66, v50
	v_mov_b32_e32 v67, v50
	v_mov_b32_e32 v68, v50
	v_mov_b32_e32 v69, v50
	v_mov_b32_e32 v70, v50
	v_mov_b32_e32 v71, v50
	v_mov_b32_e32 v72, v50
	v_mov_b32_e32 v73, v50
	v_mov_b32_e32 v74, v50
	v_mov_b32_e32 v75, v50
	v_mov_b32_e32 v76, v50
	v_mov_b32_e32 v77, v50
	v_mov_b32_e32 v78, v50
	v_mov_b32_e32 v79, v50
	v_mov_b32_e32 v80, v50
	s_waitcnt vmcnt(0)
	v_lshl_add_u64 v[2:3], v[100:101], 0, s[8:9]
	v_lshl_add_u64 v[2:3], v[2:3], 0, v[0:1]
	v_lshl_add_u64 v[90:91], v[2:3], 0, v[136:137]
	v_add_co_u32_e32 v10, vcc, s16, v90
	s_mov_b64 s[8:9], 0x20000
	s_nop 0
	v_addc_co_u32_e32 v11, vcc, 0, v91, vcc
	v_add_co_u32_e32 v12, vcc, s17, v90
	v_lshl_add_u64 v[94:95], v[90:91], 0, s[8:9]
	s_mov_b64 s[8:9], 0x30000
	v_addc_co_u32_e32 v13, vcc, 0, v91, vcc
	v_lshl_add_u64 v[92:93], v[2:3], 0, v[4:5]
	v_lshl_add_u64 v[96:97], v[90:91], 0, s[8:9]
	global_load_dwordx4 v[120:123], v[90:91], off
	global_load_dwordx4 v[2:5], v[90:91], off offset:128
	global_load_dwordx4 v[124:127], v[92:93], off
	global_load_dwordx4 v[26:29], v[90:91], off offset:256
	global_load_dwordx4 v[128:131], v[10:11], off
	global_load_dwordx4 v[132:135], v[12:13], off
	s_nop 0
	global_load_dwordx4 v[10:13], v[92:93], off offset:128
	global_load_dwordx4 v[34:37], v[92:93], off offset:256
	global_load_dwordx4 v[14:17], v[94:95], off offset:128
	global_load_dwordx4 v[38:41], v[94:95], off offset:256
	global_load_dwordx4 v[18:21], v[96:97], off offset:128
	global_load_dwordx4 v[42:45], v[96:97], off offset:256
	v_lshrrev_b32_e32 v0, 4, v81
	v_xor_b32_e32 v81, v0, v81
	v_bitop3_b32 v0, v0, v99, 3 bitop3:0x6c
	v_bitop3_b32 v99, v104, v99, 4 bitop3:0x36
	v_lshlrev_b32_e32 v81, 4, v81
	v_lshlrev_b32_e32 v0, 4, v0
	v_lshlrev_b32_e32 v99, 4, v99
	v_and_or_b32 v110, v81, s14, v98
	v_or_b32_e32 v109, v0, v107
	v_or_b32_e32 v108, v0, v106
	v_or_b32_e32 v107, v99, v107
	v_or_b32_e32 v106, v99, v106
	v_lshl_add_u64 v[98:99], v[84:85], 0, v[136:137]
	v_lshl_add_u64 v[136:137], v[136:137], 0, s[18:19]
	s_mov_b32 s8, -2
	v_lshl_add_u64 v[100:101], v[100:101], 0, v[136:137]
	v_lshlrev_b32_e32 v0, 4, v111
	v_mov_b32_e32 v81, v50
	s_waitcnt lgkmcnt(0)
	ds_write_b128 v110, v[112:115] offset:16384
	ds_write_b128 v110, v[116:119] offset:20480
	s_waitcnt vmcnt(0)
	ds_write_b128 v110, v[120:123]
	ds_write_b128 v110, v[124:127] offset:4096
	ds_write_b128 v110, v[128:131] offset:8192
	ds_write_b128 v110, v[132:135] offset:12288
	s_waitcnt lgkmcnt(0)
	s_barrier
.LBB0_488:
	s_nop 0
	ds_read_b128 v[112:115], v109
	ds_read_b128 v[116:119], v109 offset:2048
	ds_read_b128 v[120:123], v109 offset:4096
	ds_read_b128 v[124:127], v109 offset:6144
	ds_read_b128 v[128:131], v108 offset:16384
	ds_read_b128 v[132:135], v108 offset:18432
	s_mov_b32 s9, 0x2c0000
	s_add_i32 s8, s8, 2
	s_waitcnt lgkmcnt(0)
	v_mfma_f32_16x16x32_bf16 v[78:81], v[112:115], v[128:131], v[78:81]
	s_waitcnt lgkmcnt(0)
	v_mfma_f32_16x16x32_bf16 v[74:77], v[112:115], v[132:135], v[74:77]
	v_mfma_f32_16x16x32_bf16 v[70:73], v[116:119], v[128:131], v[70:73]
	v_mfma_f32_16x16x32_bf16 v[66:69], v[116:119], v[132:135], v[66:69]
	v_mfma_f32_16x16x32_bf16 v[62:65], v[120:123], v[128:131], v[62:65]
	v_mfma_f32_16x16x32_bf16 v[58:61], v[120:123], v[132:135], v[58:61]
	v_mfma_f32_16x16x32_bf16 v[112:115], v[124:127], v[128:131], v[54:57]
	v_mfma_f32_16x16x32_bf16 v[116:119], v[124:127], v[132:135], v[50:53]
	s_nop 2
	ds_read_b128 v[50:53], v107
	ds_read_b128 v[54:57], v107 offset:2048
	ds_read_b128 v[120:123], v107 offset:4096
	ds_read_b128 v[124:127], v107 offset:6144
	ds_read_b128 v[128:131], v106 offset:16384
	ds_read_b128 v[132:135], v106 offset:18432
	s_waitcnt vmcnt(0)
	ds_write_b128 v110, v[2:5] offset:32768
	ds_write_b128 v110, v[10:13] offset:36864
	ds_write_b128 v110, v[14:17] offset:40960
	ds_write_b128 v110, v[18:21] offset:45056
	ds_write_b128 v110, v[6:9] offset:49152
	ds_write_b128 v110, v[22:25] offset:53248
	v_lshl_add_u64 v[6:7], v[100:101], 0, v[0:1]
	v_add_co_u32_e32 v8, vcc, s15, v6
	global_load_dwordx4 v[2:5], v[6:7], off offset:384
	s_nop 0
	v_addc_co_u32_e32 v9, vcc, 0, v7, vcc
	global_load_dwordx4 v[10:13], v[8:9], off offset:384
	v_add_co_u32_e32 v8, vcc, s16, v6
	v_lshl_add_u64 v[22:23], v[98:99], 0, v[0:1]
	s_nop 0
	v_addc_co_u32_e32 v9, vcc, 0, v7, vcc
	v_add_co_u32_e32 v6, vcc, s17, v6
	global_load_dwordx4 v[14:17], v[8:9], off offset:384
	s_nop 0
	v_addc_co_u32_e32 v7, vcc, 0, v7, vcc
	global_load_dwordx4 v[18:21], v[6:7], off offset:384
	v_add_co_u32_e32 v6, vcc, s9, v22
	s_mov_b32 s9, 0x2d0000
	s_nop 0
	v_addc_co_u32_e32 v7, vcc, 0, v23, vcc
	v_add_co_u32_e32 v22, vcc, s9, v22
	s_waitcnt lgkmcnt(0)
	v_mfma_f32_16x16x32_bf16 v[78:81], v[50:53], v[128:131], v[78:81]
	v_addc_co_u32_e32 v23, vcc, 0, v23, vcc
	global_load_dwordx4 v[6:9], v[6:7], off offset:384
	v_mfma_f32_16x16x32_bf16 v[74:77], v[50:53], v[132:135], v[74:77]
	global_load_dwordx4 v[22:25], v[22:23], off offset:384
	s_waitcnt lgkmcnt(0)
	s_barrier
; template <int NT, bool BKN, bool MASK = false, bool ROWSS = false, class Epi> ...
;     ...
;   for (int kt = 0; kt < nk - 2; kt += 2) {
;     GEMM_COMPUTE(0);
;     GEMM_STORE(ra1, rb1, 1);
;     GEMM_LOAD(ra1, rb1, kt + 3);
;     __syncthreads();
;     GEMM_COMPUTE(1);
;     GEMM_STORE(ra0, rb0, 0);
;     GEMM_LOAD(ra0, rb0, (kt + 4 < nkm1 ? kt + 4 : nkm1));
;     __syncthreads();
;   }
;   GEMM_COMPUTE(0);
;   GEMM_STORE(ra1, rb1, 1);
;   __syncthreads();
;   GEMM_COMPUTE(1);
	v_mfma_f32_16x16x32_bf16 v[70:73], v[54:57], v[128:131], v[70:73]
	s_min_u32 s9, s8, 11
	s_lshl_b32 s94, s9, 7
	v_mfma_f32_16x16x32_bf16 v[66:69], v[54:57], v[132:135], v[66:69]
	v_lshl_add_u64 v[98:99], v[98:99], 0, s[6:7]
	v_lshl_add_u64 v[100:101], v[100:101], 0, s[6:7]
	s_cmp_lt_u32 s8, 12
	v_mfma_f32_16x16x32_bf16 v[50:53], v[120:123], v[128:131], v[62:65]
	v_mfma_f32_16x16x32_bf16 v[54:57], v[120:123], v[132:135], v[58:61]
	v_mfma_f32_16x16x32_bf16 v[58:61], v[124:127], v[128:131], v[112:115]
	v_mfma_f32_16x16x32_bf16 v[62:65], v[124:127], v[132:135], v[116:119]
	s_nop 1
	ds_read_b128 v[112:115], v109 offset:32768
	ds_read_b128 v[116:119], v109 offset:34816
	ds_read_b128 v[120:123], v109 offset:36864
	ds_read_b128 v[124:127], v109 offset:38912
	ds_read_b128 v[128:131], v108 offset:49152
	ds_read_b128 v[132:135], v108 offset:51200
	s_waitcnt lgkmcnt(0)
	v_mfma_f32_16x16x32_bf16 v[78:81], v[112:115], v[128:131], v[78:81]
	v_mfma_f32_16x16x32_bf16 v[74:77], v[112:115], v[132:135], v[74:77]
	v_mfma_f32_16x16x32_bf16 v[70:73], v[116:119], v[128:131], v[70:73]
	v_mfma_f32_16x16x32_bf16 v[66:69], v[116:119], v[132:135], v[66:69]
	v_mfma_f32_16x16x32_bf16 v[50:53], v[120:123], v[128:131], v[50:53]
	v_mfma_f32_16x16x32_bf16 v[54:57], v[120:123], v[132:135], v[54:57]
	v_mfma_f32_16x16x32_bf16 v[112:115], v[124:127], v[128:131], v[58:61]
	v_mfma_f32_16x16x32_bf16 v[116:119], v[124:127], v[132:135], v[62:65]
	s_nop 1
	ds_read_b128 v[58:61], v107 offset:32768
	ds_read_b128 v[62:65], v107 offset:34816
	ds_read_b128 v[120:123], v107 offset:36864
	ds_read_b128 v[124:127], v107 offset:38912
	ds_read_b128 v[128:131], v106 offset:49152
	ds_read_b128 v[132:135], v106 offset:51200
	ds_write_b128 v110, v[26:29]
	ds_write_b128 v110, v[34:37] offset:4096
	ds_write_b128 v110, v[38:41] offset:8192
	ds_write_b128 v110, v[42:45] offset:12288
	ds_write_b128 v110, v[30:33] offset:16384
	ds_write_b128 v110, v[46:49] offset:20480
	v_lshl_add_u64 v[26:27], v[90:91], 0, s[94:95]
	v_lshl_add_u64 v[30:31], v[92:93], 0, s[94:95]
	global_load_dwordx4 v[26:29], v[26:27], off offset:512
	v_lshl_add_u64 v[46:47], v[88:89], 0, s[94:95]
	global_load_dwordx4 v[34:37], v[30:31], off offset:512
	v_lshl_add_u64 v[30:31], v[94:95], 0, s[94:95]
	global_load_dwordx4 v[38:41], v[30:31], off offset:512
	v_lshl_add_u64 v[30:31], v[96:97], 0, s[94:95]
	global_load_dwordx4 v[42:45], v[30:31], off offset:512
	v_lshl_add_u64 v[30:31], v[86:87], 0, s[94:95]
	global_load_dwordx4 v[30:33], v[30:31], off offset:512
	s_waitcnt lgkmcnt(0)
	v_mfma_f32_16x16x32_bf16 v[78:81], v[58:61], v[128:131], v[78:81]
	global_load_dwordx4 v[46:49], v[46:47], off offset:512
	s_waitcnt lgkmcnt(0)
	s_barrier
	v_mfma_f32_16x16x32_bf16 v[74:77], v[58:61], v[132:135], v[74:77]
	v_mfma_f32_16x16x32_bf16 v[70:73], v[62:65], v[128:131], v[70:73]
	v_mfma_f32_16x16x32_bf16 v[66:69], v[62:65], v[132:135], v[66:69]
	v_mfma_f32_16x16x32_bf16 v[62:65], v[120:123], v[128:131], v[50:53]
	v_mfma_f32_16x16x32_bf16 v[58:61], v[120:123], v[132:135], v[54:57]
	v_mfma_f32_16x16x32_bf16 v[54:57], v[124:127], v[128:131], v[112:115]
	v_mfma_f32_16x16x32_bf16 v[50:53], v[124:127], v[132:135], v[116:119]
	s_cbranch_scc1 .LBB0_488
	s_waitcnt vmcnt(0)
	ds_read_b128 v[26:29], v109
	ds_read_b128 v[30:33], v109 offset:2048
	ds_read_b128 v[34:37], v109 offset:4096
	ds_read_b128 v[38:41], v109 offset:6144
	ds_read_b128 v[42:45], v108 offset:16384
	ds_read_b128 v[46:49], v108 offset:18432
	v_lshlrev_b32_e32 v0, 6, v105
	s_add_i32 s1, s1, s3
	s_waitcnt lgkmcnt(1)
	v_mfma_f32_16x16x32_bf16 v[78:81], v[26:29], v[42:45], v[78:81]
	s_waitcnt lgkmcnt(0)
	v_mfma_f32_16x16x32_bf16 v[26:29], v[26:29], v[46:49], v[74:77]
	v_mfma_f32_16x16x32_bf16 v[70:73], v[30:33], v[42:45], v[70:73]
	v_mfma_f32_16x16x32_bf16 v[30:33], v[30:33], v[46:49], v[66:69]
	v_mfma_f32_16x16x32_bf16 v[62:65], v[34:37], v[42:45], v[62:65]
	v_mfma_f32_16x16x32_bf16 v[34:37], v[34:37], v[46:49], v[58:61]
	v_mfma_f32_16x16x32_bf16 v[42:45], v[38:41], v[42:45], v[54:57]
	v_mfma_f32_16x16x32_bf16 v[38:41], v[38:41], v[46:49], v[50:53]
	ds_read_b128 v[46:49], v107
	s_nop 1
	ds_read_b128 v[50:53], v107 offset:2048
	ds_read_b128 v[54:57], v107 offset:4096
	ds_read_b128 v[58:61], v107 offset:6144
	ds_read_b128 v[66:69], v106 offset:16384
	ds_read_b128 v[74:77], v106 offset:18432
	ds_write_b128 v110, v[2:5] offset:32768
	ds_write_b128 v110, v[10:13] offset:36864
	ds_write_b128 v110, v[14:17] offset:40960
	ds_write_b128 v110, v[18:21] offset:45056
	ds_write_b128 v110, v[6:9] offset:49152
	ds_write_b128 v110, v[22:25] offset:53248
	s_waitcnt lgkmcnt(0)
	s_barrier
; __device__ __forceinline__ u16 f2bf(float f) { return (u16)(pack2(f, 0.f) & 0xffffu); }
; __device__ __forceinline__ int tid_() { int t = threadIdx.x; asm volatile("" : "+v"(t)); return t; }
; template <int NT, bool BKN, bool MASK = false, bool ROWSS = false, class Epi> ...
;     ...
;   GEMM_COMPUTE(0);
;   GEMM_STORE(ra1, rb1, 1);
;   __syncthreads();
;   GEMM_COMPUTE(1);
; template <int NT, class VF, class RP>
; __device__ __forceinline__ void epi_staged_bf16(f32x4 (&acc)[4][NT], int r0, int c0, unsigned char* smem, VF vf, RP rowptr) {
;   constexpr int BN = NT * 32, PITCH = BN + 8, CPR = BN / 8;
;   u16* Ts = (u16*)smem;
;   const int t = tid_();
;   __syncthreads();
; #pragma unroll
;   for (int mi = 0; mi < 4; ++mi)
; #pragma unroll
;     for (int ni = 0; ni < NT; ++ni)
; #pragma unroll
;       for (int j = 0; j < 4; ++j) {
;         const int r = r0 + mi * 16 + j, c = c0 + ni * 16;
;         Ts[r * PITCH + c] = f2bf(vf(r, c, acc[mi][ni][j]));
;       }
;   __syncthreads();
	ds_read_b128 v[2:5], v109 offset:32768
	ds_read_b128 v[6:9], v109 offset:34816
	ds_read_b128 v[10:13], v109 offset:36864
	ds_read_b128 v[14:17], v109 offset:38912
	ds_read_b128 v[18:21], v108 offset:49152
	ds_read_b128 v[22:25], v108 offset:51200
	v_mfma_f32_16x16x32_bf16 v[78:81], v[46:49], v[66:69], v[78:81]
	v_mfma_f32_16x16x32_bf16 v[26:29], v[46:49], v[74:77], v[26:29]
	v_mfma_f32_16x16x32_bf16 v[46:49], v[50:53], v[66:69], v[70:73]
	v_mfma_f32_16x16x32_bf16 v[30:33], v[50:53], v[74:77], v[30:33]
	v_mfma_f32_16x16x32_bf16 v[50:53], v[54:57], v[66:69], v[62:65]
	v_mfma_f32_16x16x32_bf16 v[34:37], v[54:57], v[74:77], v[34:37]
	v_mfma_f32_16x16x32_bf16 v[42:45], v[58:61], v[66:69], v[42:45]
	v_mfma_f32_16x16x32_bf16 v[38:41], v[58:61], v[74:77], v[38:41]
	s_waitcnt lgkmcnt(1)
	v_mfma_f32_16x16x32_bf16 v[54:57], v[2:5], v[18:21], v[78:81]
	s_waitcnt lgkmcnt(0)
	v_mfma_f32_16x16x32_bf16 v[2:5], v[2:5], v[22:25], v[26:29]
	v_mfma_f32_16x16x32_bf16 v[26:29], v[6:9], v[18:21], v[46:49]
	v_mfma_f32_16x16x32_bf16 v[6:9], v[6:9], v[22:25], v[30:33]
	v_mfma_f32_16x16x32_bf16 v[30:33], v[10:13], v[18:21], v[50:53]
	v_mfma_f32_16x16x32_bf16 v[10:13], v[10:13], v[22:25], v[34:37]
	v_mfma_f32_16x16x32_bf16 v[18:21], v[14:17], v[18:21], v[42:45]
	v_mfma_f32_16x16x32_bf16 v[14:17], v[14:17], v[22:25], v[38:41]
	ds_read_b128 v[22:25], v107 offset:32768
	ds_read_b128 v[34:37], v107 offset:34816
	s_nop 0
	ds_read_b128 v[38:41], v107 offset:36864
	ds_read_b128 v[42:45], v107 offset:38912
	ds_read_b128 v[46:49], v106 offset:49152
	ds_read_b128 v[50:53], v106 offset:51200
	s_waitcnt lgkmcnt(1)
	v_mfma_f32_16x16x32_bf16 v[54:57], v[22:25], v[46:49], v[54:57]
	s_waitcnt lgkmcnt(0)
	v_mfma_f32_16x16x32_bf16 v[2:5], v[22:25], v[50:53], v[2:5]
	v_mfma_f32_16x16x32_bf16 v[22:25], v[34:37], v[46:49], v[26:29]
	v_mfma_f32_16x16x32_bf16 v[26:29], v[38:41], v[46:49], v[30:33]
	s_nop 2
	v_lshl_or_b32 v30, v104, 2, v0
	v_lshlrev_b32_e32 v0, 1, v103
	v_lshl_or_b32 v0, v102, 6, v0
	v_mov_b32_e32 v32, v187
	v_mad_u64_u32 v[30:31], s[8:9], v30, s96, v[0:1]
	v_cvt_pk_bf16_f32 v0, v55, s0
	s_barrier
	ds_write_b16 v30, v0 offset:144
	v_cvt_pk_bf16_f32 v0, v56, s0
	ds_write_b16 v30, v0 offset:288
	v_cvt_pk_bf16_f32 v0, v57, s0
	ds_write_b16 v30, v0 offset:432
	v_cvt_pk_bf16_f32 v0, v2, s0
	ds_write_b16 v30, v0 offset:32
	v_cvt_pk_bf16_f32 v0, v3, s0
	ds_write_b16 v30, v0 offset:176
	v_cvt_pk_bf16_f32 v0, v4, s0
	ds_write_b16 v30, v0 offset:320
	v_cvt_pk_bf16_f32 v0, v5, s0
	v_mfma_f32_16x16x32_bf16 v[6:9], v[34:37], v[50:53], v[6:9]
	ds_write_b16 v30, v0 offset:464
	v_cvt_pk_bf16_f32 v0, v22, s0
	ds_write_b16 v30, v0 offset:2304
	v_cvt_pk_bf16_f32 v0, v23, s0
	ds_write_b16 v30, v0 offset:2448
	v_cvt_pk_bf16_f32 v0, v24, s0
	ds_write_b16 v30, v0 offset:2592
	v_cvt_pk_bf16_f32 v0, v25, s0
	ds_write_b16 v30, v0 offset:2736
	v_cvt_pk_bf16_f32 v0, v6, s0
	ds_write_b16 v30, v0 offset:2336
	v_cvt_pk_bf16_f32 v0, v7, s0
	ds_write_b16 v30, v0 offset:2480
	v_cvt_pk_bf16_f32 v0, v8, s0
	ds_write_b16 v30, v0 offset:2624
	v_cvt_pk_bf16_f32 v0, v9, s0
	v_mfma_f32_16x16x32_bf16 v[10:13], v[38:41], v[50:53], v[10:13]
	ds_write_b16 v30, v0 offset:2768
	v_cvt_pk_bf16_f32 v0, v26, s0
	ds_write_b16 v30, v0 offset:4608
	v_cvt_pk_bf16_f32 v0, v27, s0
	ds_write_b16 v30, v0 offset:4752
	v_cvt_pk_bf16_f32 v0, v28, s0
	ds_write_b16 v30, v0 offset:4896
	v_cvt_pk_bf16_f32 v0, v29, s0
	v_mfma_f32_16x16x32_bf16 v[18:21], v[42:45], v[46:49], v[18:21]
	ds_write_b16 v30, v0 offset:5040
	v_cvt_pk_bf16_f32 v0, v10, s0
	ds_write_b16 v30, v0 offset:4640
	v_cvt_pk_bf16_f32 v0, v11, s0
	ds_write_b16 v30, v0 offset:4784
	v_cvt_pk_bf16_f32 v0, v12, s0
	ds_write_b16 v30, v0 offset:4928
	v_cvt_pk_bf16_f32 v0, v13, s0
	v_mfma_f32_16x16x32_bf16 v[14:17], v[42:45], v[50:53], v[14:17]
	ds_write_b16 v30, v0 offset:5072
	v_cvt_pk_bf16_f32 v0, v18, s0
	ds_write_b16 v30, v0 offset:6912
	v_cvt_pk_bf16_f32 v0, v19, s0
	ds_write_b16 v30, v0 offset:7056
	v_cvt_pk_bf16_f32 v0, v20, s0
	ds_write_b16 v30, v0 offset:7200
	v_cvt_pk_bf16_f32 v0, v21, s0
	ds_write_b16 v30, v0 offset:7344
	v_cvt_pk_bf16_f32 v0, v14, s0
	ds_write_b16 v30, v0 offset:6944
	v_cvt_pk_bf16_f32 v0, v15, s0
	ds_write_b16 v30, v0 offset:7088
	v_cvt_pk_bf16_f32 v0, v16, s0
	v_cvt_pk_bf16_f32 v33, v54, s0
	ds_write_b16 v30, v0 offset:7232
	v_cvt_pk_bf16_f32 v0, v17, s0
	v_mov_b64_e32 v[2:3], s[4:5]
	ds_write_b16 v30, v33
	ds_write_b16 v30, v0 offset:7376
	s_waitcnt lgkmcnt(0)
	s_barrier
; template <int NT, class VF, class RP>
; __device__ __forceinline__ void epi_staged_bf16(f32x4 (&acc)[4][NT], int r0, int c0, unsigned char* smem, VF vf, RP rowptr) {
;     ...
; #pragma unroll
;   for (int i = 0; i < CPR / 2; ++i) {
;     const int c = t + 256 * i, row = c / CPR, ch = c % CPR;
;     u16* d = rowptr(row);
;     if (d) *(u32x4*)(d + ch * 8) = *(const u32x4*)(Ts + row * PITCH + ch * 8);
;   }
; __device__ __forceinline__ void phase_in_gemm(const Params& p, int l, unsigned char* smem) {
;     ...
;     auto epi = [&](f32x4(&acc)[4][2], int r0, int c0) {
;       auto vf = [&](int, int, float v) { return v; };
;       auto rp = [&](int r) -> u16* { return p.PX + (size_t)(row_base + r) * 1024 + 896; };
;       epi_staged_bf16<2>(acc, r0, c0, smem, vf, rp);
;     };
	global_load_dwordx2 v[4:5], v[2:3], off offset:288
	v_ashrrev_i32_e32 v0, 31, v32
	v_lshrrev_b32_e32 v0, 29, v0
	v_add_u32_e32 v0, v32, v0
	v_ashrrev_i32_e32 v10, 3, v0
	v_add_u32_e32 v6, s40, v10
	v_ashrrev_i32_e32 v7, 31, v6
	v_lshlrev_b64 v[6:7], 11, v[6:7]
	v_and_b32_e32 v0, -8, v0
	v_sub_u32_e32 v0, v32, v0
	v_readlane_b32 s8, v254, 44
	s_add_i32 s38, s38, s8
	s_cmp_lt_i32 s1, s0
	s_waitcnt vmcnt(0) lgkmcnt(0)
	v_lshl_add_u64 v[8:9], v[4:5], 0, v[6:7]
	v_mul_lo_u32 v4, v10, s96
	v_lshlrev_b32_e32 v10, 3, v0
	v_lshl_add_u32 v0, v0, 4, v4
	ds_read_b128 v[4:7], v0
	v_ashrrev_i32_e32 v11, 31, v10
	v_lshl_add_u64 v[8:9], v[10:11], 1, v[8:9]
	v_add_u32_e32 v0, 0x100, v32
	s_waitcnt lgkmcnt(0)
	global_store_dwordx4 v[8:9], v[4:7], off offset:1792
	s_nop 1
	v_ashrrev_i32_e32 v4, 31, v0
	v_lshrrev_b32_e32 v4, 29, v4
	v_add_u32_e32 v10, v0, v4
	global_load_dwordx2 v[4:5], v[2:3], off offset:288
	v_ashrrev_i32_e32 v11, 3, v10
	v_add_u32_e32 v6, s40, v11
	v_ashrrev_i32_e32 v7, 31, v6
	v_lshlrev_b64 v[6:7], 11, v[6:7]
	s_waitcnt vmcnt(0) lgkmcnt(0)
	v_lshl_add_u64 v[8:9], v[4:5], 0, v[6:7]
	v_and_b32_e32 v4, -8, v10
	v_sub_u32_e32 v0, v0, v4
	v_mul_lo_u32 v4, v11, s96
	v_lshlrev_b32_e32 v10, 3, v0
	v_lshl_add_u32 v0, v0, 4, v4
	ds_read_b128 v[4:7], v0
	v_ashrrev_i32_e32 v11, 31, v10
	v_lshl_add_u64 v[8:9], v[10:11], 1, v[8:9]
	v_add_u32_e32 v0, 0x200, v32
	s_waitcnt lgkmcnt(0)
	global_store_dwordx4 v[8:9], v[4:7], off offset:1792
	s_nop 1
	v_ashrrev_i32_e32 v4, 31, v0
	v_lshrrev_b32_e32 v4, 29, v4
	v_add_u32_e32 v10, v0, v4
	global_load_dwordx2 v[4:5], v[2:3], off offset:288
	v_ashrrev_i32_e32 v11, 3, v10
	v_add_u32_e32 v6, s40, v11
	v_ashrrev_i32_e32 v7, 31, v6
	v_lshlrev_b64 v[6:7], 11, v[6:7]
	s_waitcnt vmcnt(0) lgkmcnt(0)
	v_lshl_add_u64 v[8:9], v[4:5], 0, v[6:7]
	v_and_b32_e32 v4, -8, v10
	v_sub_u32_e32 v0, v0, v4
	v_mul_lo_u32 v4, v11, s96
	v_lshlrev_b32_e32 v10, 3, v0
	v_lshl_add_u32 v0, v0, 4, v4
	ds_read_b128 v[4:7], v0
	v_ashrrev_i32_e32 v11, 31, v10
	v_lshl_add_u64 v[8:9], v[10:11], 1, v[8:9]
	v_add_u32_e32 v0, 0x300, v32
	s_waitcnt lgkmcnt(0)
	global_store_dwordx4 v[8:9], v[4:7], off offset:1792
	global_load_dwordx2 v[2:3], v[2:3], off offset:288
	s_nop 0
	v_ashrrev_i32_e32 v4, 31, v0
	v_lshrrev_b32_e32 v4, 29, v4
	v_add_u32_e32 v8, v0, v4
	v_ashrrev_i32_e32 v9, 3, v8
	v_add_u32_e32 v4, s40, v9
	v_ashrrev_i32_e32 v5, 31, v4
	v_lshlrev_b64 v[4:5], 11, v[4:5]
	s_waitcnt vmcnt(0) lgkmcnt(0)
	v_lshl_add_u64 v[6:7], v[2:3], 0, v[4:5]
	v_and_b32_e32 v2, -8, v8
	v_sub_u32_e32 v0, v0, v2
	v_mul_lo_u32 v2, v9, s96
	v_lshlrev_b32_e32 v8, 3, v0
	v_lshl_add_u32 v0, v0, 4, v2
	ds_read_b128 v[2:5], v0
	v_ashrrev_i32_e32 v9, 31, v8
	v_lshl_add_u64 v[6:7], v[8:9], 1, v[6:7]
	s_waitcnt lgkmcnt(0)
	global_store_dwordx4 v[6:7], v[2:5], off offset:1792
	s_cbranch_scc1 .LBB0_487

; #define XCD_FOR(u, T)                                                                                         \
;   for (int _x = bid_() & 7, _gb = gridDim.x >> 3, _hi = (int)(((long)(_x + 1) * (T)) >> 3),                    \
;            u = (int)(((long)_x * (T)) >> 3) + (bid_() >> 3);                                                  \
;        u < _hi; u += _gb)
; __device__ __forceinline__ void phase_mix_a(const Params& p, int l, bool last, unsigned char* smem) {
;   {
;     const u16* W = p.WuqT + (size_t)l * 768 * 256;
;     XCD_FOR(t, 132 * 6) {
.LBB0_542:
	s_or_b64 exec, exec, s[0:1]
	s_mov_b64 s[40:41], s[64:65]
	s_waitcnt lgkmcnt(0)
	s_barrier
	s_mov_b32 s0, s2
	v_mov_b64_e32 v[2:3], s[40:41]
	global_load_dwordx2 v[2:3], v[2:3], off offset:200
	s_and_b32 s0, s0, 7
	s_mul_i32 s1, s0, 0x318
	s_addk_i32 s1, 0x318
	s_lshr_b32 s8, s1, 3
	s_mov_b32 s1, s2
	s_mulk_i32 s0, 0x63
	s_ashr_i32 s1, s1, 3
	s_add_i32 s9, s1, s0
	s_cmp_ge_i32 s9, s8
	s_cbranch_scc1 .LBB0_569
	s_mul_i32 s94, s36, 0x60000
	s_waitcnt vmcnt(0) lgkmcnt(0)
	v_lshl_add_u64 v[134:135], v[2:3], 0, s[94:95]
	s_lshl_b32 s18, s9, 7
	s_branch .LBB0_545

; __device__ __forceinline__ int tid_() { int t = threadIdx.x; asm volatile("" : "+v"(t)); return t; }
; template <int NT, bool BKN, bool MASK = false, bool ROWSS = false, class Epi> ...
;     ...
;   const int t = tid_(), lane = t & 63, wid = t >> 6, wr = wid >> 1, wc = wid & 1, l16 = lane & 15, quad = lane >> 4;
;   const u16* ap[4];
;   const u16* bp[NT];
;   unsigned amask = 0u;
; #pragma unroll
;   for (int i = 0; i < 4; ++i) {
;     const int row = (t >> 3) + 32 * i;
;     const bool v = MASK ? (row < mvalid) : true;
;     amask |= v ? (1u << i) : 0u;
;     int r = v ? row : 0;
;     if (arows) r = arows[r];
;     ap[i] = A + (size_t)r * lda + (t & 7) * 8;
;   }
; #pragma unroll
;   for (int i = 0; i < NT; ++i) {
;     if (!BKN) bp[i] = B + (size_t)((t >> 3) + 32 * i) * ldb + (t & 7) * 8;
;     else { const int c = t + 256 * i; bp[i] = B + (size_t)(c / CPR) * ldb + (c % CPR) * 8; }
;   }
;   const size_t bstep = BKN ? (size_t)64 * ldb : (size_t)64;
;   int nmi = 4;
;   if (MASK) { nmi = (mvalid - wr * 64 + 15) >> 4; nmi = nmi < 0 ? 0 : (nmi > 4 ? 4 : nmi); nmi = __builtin_amdgcn_readfirstlane(nmi); }
;   u32x4 ra0[4], rb0[NT], ra1[4], rb1[NT];
.LBB0_545:
	v_mov_b64_e32 v[2:3], s[40:41]
	global_load_dwordx2 v[2:3], v[2:3], off offset:288
	s_mul_hi_i32 s19, s9, 0x2aaaaaab
	s_lshr_b32 s0, s19, 31
	s_add_i32 s19, s19, s0
	s_lshl_b32 s4, s19, 7
	s_ashr_i32 s5, s4, 31
	v_mov_b32_e32 v146, v187
	s_lshl_b64 s[34:35], s[4:5], 11
	s_mul_i32 s0, s19, -6
	v_ashrrev_i32_e32 v142, 3, v146
	v_lshlrev_b32_e32 v54, 4, v146
	v_and_b32_e32 v0, 0x70, v54
	v_ashrrev_i32_e32 v143, 31, v142
	v_add_u32_e32 v140, 32, v142
	s_add_i32 s0, s9, s0
	v_lshlrev_b64 v[6:7], 11, v[142:143]
	v_ashrrev_i32_e32 v141, 31, v140
	v_add_u32_e32 v138, 64, v142
	s_ashr_i32 s1, s0, 31
	v_ashrrev_i32_e32 v139, 31, v138
	v_add_u32_e32 v136, 0x60, v142
	s_lshl_b64 s[0:1], s[0:1], 16
	v_ashrrev_i32_e32 v137, 31, v136
	v_lshl_add_u64 v[4:5], v[134:135], 0, s[0:1]
	s_waitcnt lgkmcnt(0)
	s_barrier
	v_lshrrev_b32_e32 v80, 4, v146
	v_and_b32_e32 v145, 15, v146
	v_bfe_u32 v132, v146, 1, 3
	v_bfe_u32 v144, v146, 6, 1
	v_and_b32_e32 v54, 0xffffff80, v54
	v_lshlrev_b32_e32 v112, 7, v145
	v_cmp_lt_i32_e32 vcc, v212, v227
	s_waitcnt vmcnt(0)
	v_lshl_add_u64 v[2:3], v[2:3], 0, s[34:35]
	v_lshl_add_u64 v[2:3], v[2:3], 0, v[0:1]
	v_lshl_add_u64 v[78:79], v[2:3], 0, v[6:7]
	v_lshlrev_b64 v[6:7], 11, v[140:141]
	v_lshl_add_u64 v[82:83], v[2:3], 0, v[6:7]
	v_lshlrev_b64 v[6:7], 11, v[138:139]
	v_lshl_add_u64 v[84:85], v[2:3], 0, v[6:7]
	v_lshlrev_b64 v[6:7], 11, v[136:137]
	v_lshl_add_u64 v[86:87], v[2:3], 0, v[6:7]
	v_lshl_add_u64 v[2:3], v[4:5], 0, v[0:1]
	v_lshlrev_b64 v[4:5], 9, v[142:143]
	v_lshl_add_u64 v[88:89], v[2:3], 0, v[4:5]
	v_lshlrev_b64 v[4:5], 9, v[140:141]
	v_lshl_add_u64 v[90:91], v[2:3], 0, v[4:5]
	v_lshlrev_b64 v[4:5], 9, v[138:139]
	v_lshl_add_u64 v[92:93], v[2:3], 0, v[4:5]
	v_lshlrev_b64 v[4:5], 9, v[136:137]
	v_lshl_add_u64 v[94:95], v[2:3], 0, v[4:5]
	global_load_dwordx4 v[14:17], v[78:79], off offset:1024
	global_load_dwordx4 v[18:21], v[82:83], off offset:1024
	global_load_dwordx4 v[6:9], v[84:85], off offset:1024
	global_load_dwordx4 v[2:5], v[86:87], off offset:1024
	global_load_dwordx4 v[26:29], v[88:89], off
	global_load_dwordx4 v[34:37], v[90:91], off
	global_load_dwordx4 v[46:49], v[92:93], off
	global_load_dwordx4 v[50:53], v[94:95], off
	global_load_dwordx4 v[74:77], v[78:79], off offset:1152
	global_load_dwordx4 v[30:33], v[82:83], off offset:1152
	global_load_dwordx4 v[22:25], v[84:85], off offset:1152
	global_load_dwordx4 v[10:13], v[86:87], off offset:1152
	global_load_dwordx4 v[70:73], v[88:89], off offset:128
	global_load_dwordx4 v[42:45], v[90:91], off offset:128
	global_load_dwordx4 v[62:65], v[92:93], off offset:128
	global_load_dwordx4 v[38:41], v[94:95], off offset:128
	v_ashrrev_i32_e32 v0, 7, v146
	v_lshl_or_b32 v133, v0, 13, v112
	v_lshl_or_b32 v141, v144, 13, v112
	v_bfe_u32 v137, v146, 4, 2
	s_waitcnt vmcnt(0) lgkmcnt(0)
	v_and_b32_e32 v56, 0xffff0000, v14
	v_lshlrev_b32_e32 v55, 16, v14
	v_and_b32_e32 v58, 0xffff0000, v15
	v_mul_f32_e32 v56, v56, v56
	v_lshlrev_b32_e32 v57, 16, v15
	v_fmac_f32_e32 v56, v55, v55
	v_mul_f32_e32 v55, v58, v58
	v_and_b32_e32 v60, 0xffff0000, v16
	v_fmac_f32_e32 v55, v57, v57
	v_lshlrev_b32_e32 v59, 16, v16
	v_add_f32_e32 v55, v56, v55
	v_mul_f32_e32 v56, v60, v60
	v_and_b32_e32 v66, 0xffff0000, v17
	v_fmac_f32_e32 v56, v59, v59
	v_lshlrev_b32_e32 v61, 16, v17
	v_add_f32_e32 v55, v56, v55
	v_mul_f32_e32 v56, v66, v66
	v_fmac_f32_e32 v56, v61, v61
	v_add_f32_e32 v81, v56, v55
	v_xor_b32_e32 v55, v80, v146
	v_lshlrev_b32_e32 v55, 4, v55
	v_bitop3_b32 v80, v80, v132, 3 bitop3:0x6c
	v_and_or_b32 v139, v55, s14, v54
	v_lshlrev_b32_e32 v80, 4, v80
	ds_write_b128 v139, v[14:17]
	ds_write_b128 v139, v[18:21] offset:4096
	ds_write_b128 v139, v[6:9] offset:8192
	ds_write_b128 v139, v[2:5] offset:12288
	ds_write_b128 v139, v[26:29] offset:16384
	ds_write_b128 v139, v[34:37] offset:20480
	ds_write_b128 v139, v[46:49] offset:24576
	ds_write_b128 v139, v[50:53] offset:28672
	v_or_b32_e32 v147, v80, v133
	v_or_b32_e32 v148, v80, v141
	global_load_dwordx4 v[46:49], v[78:79], off offset:1280
	global_load_dwordx4 v[34:37], v[82:83], off offset:1280
	global_load_dwordx4 v[26:29], v[84:85], off offset:1280
	global_load_dwordx4 v[14:17], v[86:87], off offset:1280
	global_load_dwordx4 v[50:53], v[88:89], off offset:256
	global_load_dwordx4 v[54:57], v[90:91], off offset:256
	global_load_dwordx4 v[58:61], v[92:93], off offset:256
	global_load_dwordx4 v[66:69], v[94:95], off offset:256
	s_waitcnt lgkmcnt(0)
	s_barrier
; template <int NT, bool BKN, bool MASK = false, bool ROWSS = false, class Epi> ...
;     ...
;   float ss_[4] = {0.f, 0.f, 0.f, 0.f};
;   int stk_ = 0;
;   f32x4 acc[4][NT];
; #pragma unroll
;   for (int i = 0; i < 4; ++i)
; #pragma unroll
;     for (int j = 0; j < NT; ++j) acc[i][j] = (f32x4){0.f, 0.f, 0.f, 0.f};
;   const int nk = K >> 6;
;   const int nkm1 = nk - 1;
;   __syncthreads();
;   GEMM_LOAD(ra0, rb0, 0);
;   GEMM_LOAD(ra1, rb1, 1);
;   GEMM_STORE(ra0, rb0, 0);
;   GEMM_LOAD(ra0, rb0, (2 < nkm1 ? 2 : nkm1));
;   __syncthreads();
;   for (int kt = 0; kt < nk - 2; kt += 2) {
;     GEMM_COMPUTE(0);
;     GEMM_STORE(ra1, rb1, 1);
;     GEMM_LOAD(ra1, rb1, kt + 3);
;     __syncthreads();
	ds_read_b128 v[96:99], v147
	ds_read_b128 v[100:103], v147 offset:2048
	ds_read_b128 v[104:107], v147 offset:4096
	ds_read_b128 v[108:111], v147 offset:6144
	ds_read_b128 v[112:115], v148 offset:16384
	ds_read_b128 v[116:119], v148 offset:18432
	ds_read_b128 v[120:123], v148 offset:20480
	ds_read_b128 v[124:127], v148 offset:22528
	v_bitop3_b32 v80, v137, v132, 4 bitop3:0x36
	v_lshlrev_b32_e32 v80, 4, v80
	v_or_b32_e32 v143, v80, v133
	v_or_b32_e32 v141, v80, v141
	s_waitcnt lgkmcnt(0)
	v_mfma_f32_16x16x32_bf16 v[128:131], v[96:99], v[112:115], 0
	v_and_b32_e32 v132, 0xffff0000, v74
	v_lshlrev_b32_e32 v80, 16, v74
	v_and_b32_e32 v149, 0xffff0000, v75
	v_mfma_f32_16x16x32_bf16 v[150:153], v[96:99], v[116:119], 0
	v_mul_f32_e32 v132, v132, v132
	v_lshlrev_b32_e32 v133, 16, v75
	v_fmac_f32_e32 v132, v80, v80
	v_mfma_f32_16x16x32_bf16 v[154:157], v[96:99], v[120:123], 0
	v_mul_f32_e32 v80, v149, v149
	v_fmac_f32_e32 v80, v133, v133
	v_add_f32_e32 v80, v132, v80
	v_mfma_f32_16x16x32_bf16 v[96:99], v[96:99], v[124:127], 0
	s_waitcnt vmcnt(0)
	v_and_b32_e32 v149, 0xffff0000, v47
	v_mfma_f32_16x16x32_bf16 v[158:161], v[100:103], v[112:115], 0
	v_lshlrev_b32_e32 v133, 16, v47
	v_mfma_f32_16x16x32_bf16 v[162:165], v[100:103], v[116:119], 0
	v_mfma_f32_16x16x32_bf16 v[166:169], v[100:103], v[120:123], 0
	v_mfma_f32_16x16x32_bf16 v[100:103], v[100:103], v[124:127], 0
	v_mfma_f32_16x16x32_bf16 v[170:173], v[104:107], v[112:115], 0
	v_mfma_f32_16x16x32_bf16 v[174:177], v[104:107], v[116:119], 0
	v_mfma_f32_16x16x32_bf16 v[178:181], v[104:107], v[120:123], 0
	v_mfma_f32_16x16x32_bf16 v[104:107], v[104:107], v[124:127], 0
	v_mfma_f32_16x16x32_bf16 v[112:115], v[108:111], v[112:115], 0
	v_mfma_f32_16x16x32_bf16 v[116:119], v[108:111], v[116:119], 0
	v_mfma_f32_16x16x32_bf16 v[120:123], v[108:111], v[120:123], 0
	v_mfma_f32_16x16x32_bf16 v[108:111], v[108:111], v[124:127], 0
	ds_read_b128 v[124:127], v143
	ds_read_b128 v[182:185], v143 offset:2048
	ds_read_b128 v[188:191], v143 offset:4096
	ds_read_b128 v[192:195], v143 offset:6144
	ds_read_b128 v[196:199], v141 offset:16384
	ds_read_b128 v[200:203], v141 offset:18432
	ds_read_b128 v[204:207], v141 offset:20480
	ds_read_b128 v[208:211], v141 offset:22528
	ds_write_b128 v139, v[74:77] offset:32768
	ds_write_b128 v139, v[30:33] offset:36864
	ds_write_b128 v139, v[22:25] offset:40960
	ds_write_b128 v139, v[10:13] offset:45056
	ds_write_b128 v139, v[70:73] offset:49152
	ds_write_b128 v139, v[42:45] offset:53248
	ds_write_b128 v139, v[62:65] offset:57344
	ds_write_b128 v139, v[38:41] offset:61440
	s_waitcnt lgkmcnt(11)
	v_mfma_f32_16x16x32_bf16 v[128:131], v[124:127], v[196:199], v[128:131]
	s_waitcnt lgkmcnt(10)
	v_mfma_f32_16x16x32_bf16 v[150:153], v[124:127], v[200:203], v[150:153]
	s_waitcnt lgkmcnt(9)
	v_mfma_f32_16x16x32_bf16 v[154:157], v[124:127], v[204:207], v[154:157]
	s_waitcnt lgkmcnt(8)
	v_mfma_f32_16x16x32_bf16 v[96:99], v[124:127], v[208:211], v[96:99]
	v_mfma_f32_16x16x32_bf16 v[124:127], v[182:185], v[196:199], v[158:161]
	v_mfma_f32_16x16x32_bf16 v[158:161], v[182:185], v[200:203], v[162:165]
	v_mfma_f32_16x16x32_bf16 v[162:165], v[182:185], v[204:207], v[166:169]
	v_mfma_f32_16x16x32_bf16 v[166:169], v[188:191], v[196:199], v[170:173]
	v_mfma_f32_16x16x32_bf16 v[170:173], v[188:191], v[200:203], v[174:177]
	v_mfma_f32_16x16x32_bf16 v[174:177], v[188:191], v[204:207], v[178:181]
	s_nop 2
	v_and_b32_e32 v179, 0xffff0000, v76
	v_lshlrev_b32_e32 v178, 16, v76
	v_mul_f32_e32 v132, v179, v179
	v_and_b32_e32 v181, 0xffff0000, v77
	v_fmac_f32_e32 v132, v178, v178
	v_lshlrev_b32_e32 v180, 16, v77
	v_add_f32_e32 v80, v132, v80
	v_mul_f32_e32 v132, v181, v181
	v_fmac_f32_e32 v132, v180, v180
	v_add_f32_e32 v80, v132, v80
	v_add_f32_e32 v132, v81, v80
	global_load_dwordx4 v[78:81], v[78:79], off offset:1408
	s_nop 0
	global_load_dwordx4 v[62:65], v[82:83], off offset:1408
	global_load_dwordx4 v[42:45], v[84:85], off offset:1408
	global_load_dwordx4 v[38:41], v[86:87], off offset:1408
	s_nop 0
	global_load_dwordx4 v[82:85], v[88:89], off offset:384
	s_nop 0
	global_load_dwordx4 v[86:89], v[90:91], off offset:384
	global_load_dwordx4 v[70:73], v[92:93], off offset:384
	global_load_dwordx4 v[74:77], v[94:95], off offset:384
	v_mfma_f32_16x16x32_bf16 v[100:103], v[182:185], v[208:211], v[100:103]
	s_waitcnt lgkmcnt(0)
	s_barrier
; template <int NT, bool BKN, bool MASK = false, bool ROWSS = false, class Epi> ...
;     ...
;   for (int kt = 0; kt < nk - 2; kt += 2) {
;     GEMM_COMPUTE(0);
;     GEMM_STORE(ra1, rb1, 1);
;     GEMM_LOAD(ra1, rb1, kt + 3);
;     __syncthreads();
;     GEMM_COMPUTE(1);
;     GEMM_STORE(ra0, rb0, 0);
;     GEMM_LOAD(ra0, rb0, (kt + 4 < nkm1 ? kt + 4 : nkm1));
;     __syncthreads();
;   }
;   GEMM_COMPUTE(0);
;   GEMM_STORE(ra1, rb1, 1);
;   __syncthreads();
;   GEMM_COMPUTE(1);
	v_mfma_f32_16x16x32_bf16 v[104:107], v[188:191], v[208:211], v[104:107]
	v_mfma_f32_16x16x32_bf16 v[112:115], v[192:195], v[196:199], v[112:115]
	v_mfma_f32_16x16x32_bf16 v[116:119], v[192:195], v[200:203], v[116:119]
	v_mfma_f32_16x16x32_bf16 v[120:123], v[192:195], v[204:207], v[120:123]
	v_mfma_f32_16x16x32_bf16 v[108:111], v[192:195], v[208:211], v[108:111]
	ds_read_b128 v[90:93], v147 offset:32768
	ds_read_b128 v[178:181], v147 offset:34816
	ds_read_b128 v[182:185], v147 offset:36864
	ds_read_b128 v[188:191], v147 offset:38912
	ds_read_b128 v[192:195], v148 offset:49152
	ds_read_b128 v[196:199], v148 offset:51200
	ds_read_b128 v[200:203], v148 offset:53248
	ds_read_b128 v[204:207], v148 offset:55296
	s_waitcnt lgkmcnt(0)
	v_mfma_f32_16x16x32_bf16 v[128:131], v[90:93], v[192:195], v[128:131]
	v_mfma_f32_16x16x32_bf16 v[150:153], v[90:93], v[196:199], v[150:153]
	v_mfma_f32_16x16x32_bf16 v[154:157], v[90:93], v[200:203], v[154:157]
	v_mfma_f32_16x16x32_bf16 v[90:93], v[90:93], v[204:207], v[96:99]
	v_mfma_f32_16x16x32_bf16 v[94:97], v[178:181], v[192:195], v[124:127]
	v_mfma_f32_16x16x32_bf16 v[124:127], v[178:181], v[196:199], v[158:161]
	v_mfma_f32_16x16x32_bf16 v[158:161], v[178:181], v[200:203], v[162:165]
	v_mfma_f32_16x16x32_bf16 v[98:101], v[178:181], v[204:207], v[100:103]
	v_mfma_f32_16x16x32_bf16 v[162:165], v[182:185], v[192:195], v[166:169]
	v_mfma_f32_16x16x32_bf16 v[166:169], v[182:185], v[196:199], v[170:173]
	v_mfma_f32_16x16x32_bf16 v[170:173], v[182:185], v[200:203], v[174:177]
	v_mfma_f32_16x16x32_bf16 v[102:105], v[182:185], v[204:207], v[104:107]
	v_mfma_f32_16x16x32_bf16 v[112:115], v[188:191], v[192:195], v[112:115]
	v_mfma_f32_16x16x32_bf16 v[116:119], v[188:191], v[196:199], v[116:119]
	v_mfma_f32_16x16x32_bf16 v[120:123], v[188:191], v[200:203], v[120:123]
	v_mfma_f32_16x16x32_bf16 v[106:109], v[188:191], v[204:207], v[108:111]
	ds_read_b128 v[174:177], v143 offset:32768
	ds_read_b128 v[178:181], v143 offset:34816
	ds_read_b128 v[182:185], v143 offset:36864
	ds_read_b128 v[188:191], v143 offset:38912
	ds_read_b128 v[192:195], v141 offset:49152
	ds_read_b128 v[196:199], v141 offset:51200
	ds_read_b128 v[200:203], v141 offset:53248
	ds_read_b128 v[204:207], v141 offset:55296
	ds_write_b128 v139, v[46:49]
	ds_write_b128 v139, v[34:37] offset:4096
	ds_write_b128 v139, v[26:29] offset:8192
	ds_write_b128 v139, v[14:17] offset:12288
	ds_write_b128 v139, v[50:53] offset:16384
	ds_write_b128 v139, v[54:57] offset:20480
	ds_write_b128 v139, v[58:61] offset:24576
	ds_write_b128 v139, v[66:69] offset:28672
	s_waitcnt lgkmcnt(0)
	v_mfma_f32_16x16x32_bf16 v[110:113], v[188:191], v[192:195], v[112:115]
	s_barrier
	v_mfma_f32_16x16x32_bf16 v[114:117], v[188:191], v[196:199], v[116:119]
	v_mfma_f32_16x16x32_bf16 v[118:121], v[188:191], v[200:203], v[120:123]
	s_nop 2
	v_and_b32_e32 v123, 0xffff0000, v46
	v_lshlrev_b32_e32 v122, 16, v46
	v_mul_f32_e32 v123, v123, v123
	v_fmac_f32_e32 v123, v122, v122
	v_mul_f32_e32 v122, v149, v149
	v_mfma_f32_16x16x32_bf16 v[128:131], v[174:177], v[192:195], v[128:131]
	v_fmac_f32_e32 v122, v133, v133
	v_add_f32_e32 v122, v123, v122
	v_mfma_f32_16x16x32_bf16 v[150:153], v[174:177], v[196:199], v[150:153]
	v_mfma_f32_16x16x32_bf16 v[154:157], v[174:177], v[200:203], v[154:157]
	v_mfma_f32_16x16x32_bf16 v[90:93], v[174:177], v[204:207], v[90:93]
	v_and_b32_e32 v175, 0xffff0000, v48
	v_lshlrev_b32_e32 v174, 16, v48
	v_mul_f32_e32 v123, v175, v175
	v_and_b32_e32 v177, 0xffff0000, v49
	v_fmac_f32_e32 v123, v174, v174
	v_lshlrev_b32_e32 v176, 16, v49
	v_add_f32_e32 v122, v123, v122
	v_mul_f32_e32 v123, v177, v177
	v_mfma_f32_16x16x32_bf16 v[94:97], v[178:181], v[192:195], v[94:97]
	v_fmac_f32_e32 v123, v176, v176
	v_add_f32_e32 v122, v123, v122
	v_add_f32_e32 v149, v132, v122
	v_mfma_f32_16x16x32_bf16 v[124:127], v[178:181], v[196:199], v[124:127]
	v_mfma_f32_16x16x32_bf16 v[158:161], v[178:181], v[200:203], v[158:161]
	v_mfma_f32_16x16x32_bf16 v[98:101], v[178:181], v[204:207], v[98:101]
	v_mfma_f32_16x16x32_bf16 v[162:165], v[182:185], v[192:195], v[162:165]
	v_mfma_f32_16x16x32_bf16 v[166:169], v[182:185], v[196:199], v[166:169]
	v_mfma_f32_16x16x32_bf16 v[170:173], v[182:185], v[200:203], v[170:173]
	v_mfma_f32_16x16x32_bf16 v[102:105], v[182:185], v[204:207], v[102:105]
	ds_read_b128 v[46:49], v147
	ds_read_b128 v[50:53], v147 offset:2048
	ds_read_b128 v[54:57], v147 offset:4096
	ds_read_b128 v[58:61], v147 offset:6144
	ds_read_b128 v[66:69], v148 offset:16384
	ds_read_b128 v[174:177], v148 offset:18432
	ds_read_b128 v[178:181], v148 offset:20480
	ds_read_b128 v[182:185], v148 offset:22528
	v_mfma_f32_16x16x32_bf16 v[106:109], v[188:191], v[204:207], v[106:109]
	s_waitcnt lgkmcnt(0)
	v_mfma_f32_16x16x32_bf16 v[128:131], v[46:49], v[66:69], v[128:131]
	v_mfma_f32_16x16x32_bf16 v[150:153], v[46:49], v[174:177], v[150:153]
	v_mfma_f32_16x16x32_bf16 v[154:157], v[46:49], v[178:181], v[154:157]
	v_mfma_f32_16x16x32_bf16 v[46:49], v[46:49], v[182:185], v[90:93]
	v_mfma_f32_16x16x32_bf16 v[90:93], v[50:53], v[66:69], v[94:97]
	v_mfma_f32_16x16x32_bf16 v[94:97], v[50:53], v[174:177], v[124:127]
	v_mfma_f32_16x16x32_bf16 v[158:161], v[50:53], v[178:181], v[158:161]
	v_mfma_f32_16x16x32_bf16 v[50:53], v[50:53], v[182:185], v[98:101]
	v_mfma_f32_16x16x32_bf16 v[98:101], v[54:57], v[66:69], v[162:165]
	v_mfma_f32_16x16x32_bf16 v[162:165], v[54:57], v[174:177], v[166:169]
	v_mfma_f32_16x16x32_bf16 v[166:169], v[54:57], v[178:181], v[170:173]
	v_mfma_f32_16x16x32_bf16 v[54:57], v[54:57], v[182:185], v[102:105]
	v_mfma_f32_16x16x32_bf16 v[170:173], v[58:61], v[66:69], v[110:113]
	v_mfma_f32_16x16x32_bf16 v[174:177], v[58:61], v[174:177], v[114:117]
	v_mfma_f32_16x16x32_bf16 v[178:181], v[58:61], v[178:181], v[118:121]
	v_mfma_f32_16x16x32_bf16 v[182:185], v[58:61], v[182:185], v[106:109]
	ds_read_b128 v[58:61], v143
	ds_read_b128 v[66:69], v143 offset:2048
	ds_read_b128 v[188:191], v143 offset:4096
	ds_read_b128 v[192:195], v143 offset:6144
	ds_read_b128 v[196:199], v141 offset:16384
	ds_read_b128 v[200:203], v141 offset:18432
	ds_read_b128 v[204:207], v141 offset:20480
	ds_read_b128 v[208:211], v141 offset:22528
	s_waitcnt vmcnt(0)
	ds_write_b128 v139, v[78:81] offset:32768
	ds_write_b128 v139, v[62:65] offset:36864
	ds_write_b128 v139, v[42:45] offset:40960
	ds_write_b128 v139, v[38:41] offset:45056
	ds_write_b128 v139, v[82:85] offset:49152
	ds_write_b128 v139, v[86:89] offset:53248
	ds_write_b128 v139, v[70:73] offset:57344
	ds_write_b128 v139, v[74:77] offset:61440
	s_waitcnt lgkmcnt(0)
	v_mfma_f32_16x16x32_bf16 v[130:133], v[58:61], v[196:199], v[128:131]
	s_barrier
; template <int NT, bool BKN, bool MASK = false, bool ROWSS = false, class Epi> ...
;     ...
;   GEMM_COMPUTE(1);
;     ...
;   if (ROWSS) {
;     float* rs = (float*)(smem + 65536);
; #pragma unroll
;     for (int i = 0; i < 4; ++i) {
;       float s = ss_[i];
;       s += __shfl_xor(s, 1); s += __shfl_xor(s, 2); s += __shfl_xor(s, 4);
;       if ((t & 7) == 0) rs[(t >> 3) + 32 * i] = rsqrtf(s / (float)K + 1e-6f);
;     }
;     __syncthreads();
	v_mfma_f32_16x16x32_bf16 v[126:129], v[58:61], v[200:203], v[150:153]
	s_nop 2
	v_and_b32_e32 v151, 0xffff0000, v78
	v_lshlrev_b32_e32 v150, 16, v78
	v_and_b32_e32 v153, 0xffff0000, v79
	v_mul_f32_e32 v151, v151, v151
	v_lshlrev_b32_e32 v152, 16, v79
	v_fmac_f32_e32 v151, v150, v150
	v_mul_f32_e32 v150, v153, v153
	v_mfma_f32_16x16x32_bf16 v[122:125], v[58:61], v[204:207], v[154:157]
	v_fmac_f32_e32 v150, v152, v152
	v_add_f32_e32 v150, v151, v150
	s_nop 0
	v_and_b32_e32 v155, 0xffff0000, v80
	v_lshlrev_b32_e32 v154, 16, v80
	v_mul_f32_e32 v151, v155, v155
	v_and_b32_e32 v157, 0xffff0000, v81
	v_fmac_f32_e32 v151, v154, v154
	v_lshlrev_b32_e32 v156, 16, v81
	v_add_f32_e32 v150, v151, v150
	v_mul_f32_e32 v151, v157, v157
	v_fmac_f32_e32 v151, v156, v156
	v_mfma_f32_16x16x32_bf16 v[114:117], v[66:69], v[196:199], v[90:93]
	v_add_f32_e32 v150, v151, v150
	v_add_f32_e32 v149, v149, v150
	v_mfma_f32_16x16x32_bf16 v[90:93], v[66:69], v[204:207], v[158:161]
	ds_read_b128 v[70:73], v147 offset:32768
	ds_read_b128 v[74:77], v147 offset:34816
	ds_read_b128 v[78:81], v147 offset:36864
	ds_read_b128 v[82:85], v147 offset:38912
	ds_read_b128 v[86:89], v148 offset:49152
	ds_read_b128 v[150:153], v148 offset:51200
	ds_read_b128 v[154:157], v148 offset:53248
	ds_read_b128 v[158:161], v148 offset:55296
	v_mfma_f32_16x16x32_bf16 v[118:121], v[58:61], v[208:211], v[46:49]
	v_mfma_f32_16x16x32_bf16 v[110:113], v[66:69], v[200:203], v[94:97]
	v_mfma_f32_16x16x32_bf16 v[94:97], v[66:69], v[208:211], v[50:53]
	v_mfma_f32_16x16x32_bf16 v[98:101], v[188:191], v[196:199], v[98:101]
	v_mfma_f32_16x16x32_bf16 v[102:105], v[188:191], v[200:203], v[162:165]
	v_mfma_f32_16x16x32_bf16 v[106:109], v[188:191], v[204:207], v[166:169]
	v_mfma_f32_16x16x32_bf16 v[66:69], v[188:191], v[208:211], v[54:57]
	v_mfma_f32_16x16x32_bf16 v[46:49], v[192:195], v[200:203], v[174:177]
	v_mfma_f32_16x16x32_bf16 v[50:53], v[192:195], v[204:207], v[178:181]
	v_mfma_f32_16x16x32_bf16 v[54:57], v[192:195], v[208:211], v[182:185]
	v_mfma_f32_16x16x32_bf16 v[58:61], v[192:195], v[196:199], v[170:173]
	s_waitcnt lgkmcnt(3)
	v_mfma_f32_16x16x32_bf16 v[114:117], v[74:77], v[86:89], v[114:117]
	v_mfma_f32_16x16x32_bf16 v[130:133], v[70:73], v[86:89], v[130:133]
	s_waitcnt lgkmcnt(2)
	v_mfma_f32_16x16x32_bf16 v[126:129], v[70:73], v[150:153], v[126:129]
	s_waitcnt lgkmcnt(1)
	v_mfma_f32_16x16x32_bf16 v[122:125], v[70:73], v[154:157], v[122:125]
	s_waitcnt lgkmcnt(0)
	v_mfma_f32_16x16x32_bf16 v[70:73], v[70:73], v[158:161], v[118:121]
	v_mfma_f32_16x16x32_bf16 v[118:121], v[74:77], v[150:153], v[110:113]
	v_mfma_f32_16x16x32_bf16 v[90:93], v[74:77], v[154:157], v[90:93]
	v_mfma_f32_16x16x32_bf16 v[74:77], v[74:77], v[158:161], v[94:97]
	v_mfma_f32_16x16x32_bf16 v[162:165], v[78:81], v[86:89], v[98:101]
	v_mfma_f32_16x16x32_bf16 v[166:169], v[78:81], v[150:153], v[102:105]
	v_mfma_f32_16x16x32_bf16 v[170:173], v[78:81], v[154:157], v[106:109]
	v_mfma_f32_16x16x32_bf16 v[66:69], v[78:81], v[158:161], v[66:69]
	v_mfma_f32_16x16x32_bf16 v[46:49], v[82:85], v[150:153], v[46:49]
	v_mfma_f32_16x16x32_bf16 v[50:53], v[82:85], v[154:157], v[50:53]
	v_mfma_f32_16x16x32_bf16 v[150:153], v[82:85], v[158:161], v[54:57]
	s_nop 2
	ds_read_b128 v[54:57], v143 offset:32768
	ds_read_b128 v[78:81], v143 offset:34816
	ds_read_b128 v[154:157], v143 offset:36864
	ds_read_b128 v[158:161], v143 offset:38912
	ds_read_b128 v[174:177], v141 offset:49152
	ds_read_b128 v[178:181], v141 offset:51200
	ds_read_b128 v[182:185], v141 offset:53248
	ds_read_b128 v[188:191], v141 offset:55296
	v_mfma_f32_16x16x32_bf16 v[58:61], v[82:85], v[86:89], v[58:61]
	s_waitcnt lgkmcnt(3)
	v_mfma_f32_16x16x32_bf16 v[82:85], v[78:81], v[174:177], v[114:117]
	s_nop 2
	v_cndmask_b32_e32 v114, v186, v212, vcc
	v_cmp_lt_i32_e32 vcc, v253, v227
	v_lshlrev_b32_e32 v114, 2, v114
	v_and_b32_e32 v117, 7, v146
	v_cndmask_b32_e32 v115, v186, v253, vcc
	v_cmp_lt_i32_e32 vcc, v252, v227
	v_lshlrev_b32_e32 v115, 2, v115
	s_waitcnt lgkmcnt(2)
	v_mfma_f32_16x16x32_bf16 v[86:89], v[78:81], v[178:181], v[118:121]
	v_cndmask_b32_e32 v116, v186, v252, vcc
	v_cmp_eq_u32_e32 vcc, 0, v117
	ds_bpermute_b32 v117, v114, v149
	v_lshlrev_b32_e32 v116, 2, v116
	v_mfma_f32_16x16x32_bf16 v[98:101], v[54:57], v[174:177], v[130:133]
	s_waitcnt lgkmcnt(0)
	v_add_f32_e32 v117, v149, v117
	ds_bpermute_b32 v118, v115, v117
	v_mfma_f32_16x16x32_bf16 v[102:105], v[54:57], v[178:181], v[126:129]
	s_waitcnt lgkmcnt(0)
	v_add_f32_e32 v117, v117, v118
	ds_bpermute_b32 v118, v116, v117
	v_mfma_f32_16x16x32_bf16 v[106:109], v[54:57], v[182:185], v[122:125]
	v_mfma_f32_16x16x32_bf16 v[110:113], v[54:57], v[188:191], v[70:73]
	v_mfma_f32_16x16x32_bf16 v[90:93], v[78:81], v[182:185], v[90:93]
	v_mfma_f32_16x16x32_bf16 v[94:97], v[78:81], v[188:191], v[74:77]
	v_mfma_f32_16x16x32_bf16 v[70:73], v[154:157], v[174:177], v[162:165]
	v_mfma_f32_16x16x32_bf16 v[74:77], v[154:157], v[178:181], v[166:169]
	v_mfma_f32_16x16x32_bf16 v[78:81], v[154:157], v[182:185], v[170:173]
	v_mfma_f32_16x16x32_bf16 v[66:69], v[154:157], v[188:191], v[66:69]
	v_mfma_f32_16x16x32_bf16 v[58:61], v[158:161], v[174:177], v[58:61]
	v_mfma_f32_16x16x32_bf16 v[54:57], v[158:161], v[178:181], v[46:49]
	v_mfma_f32_16x16x32_bf16 v[50:53], v[158:161], v[182:185], v[50:53]
	v_mfma_f32_16x16x32_bf16 v[46:49], v[158:161], v[188:191], v[150:153]
	s_and_saveexec_b64 s[0:1], vcc
	s_cbranch_execz .LBB0_547
	s_waitcnt lgkmcnt(0)
	v_add_f32_e32 v117, v117, v118
	v_fmamk_f32 v117, v117, 0x3b800000, v224
	v_mul_f32_e32 v118, 0x4b800000, v117
	v_cmp_gt_f32_e64 s[38:39], s85, v117
	s_nop 1
	v_cndmask_b32_e64 v117, v117, v118, s[38:39]
	v_rsq_f32_e32 v117, v117
	s_nop 0
	v_mul_f32_e32 v118, 0x45800000, v117
	v_cndmask_b32_e64 v117, v117, v118, s[38:39]
	v_lshl_add_u32 v118, v142, 2, v213
	ds_write_b32 v118, v117

; __device__ __forceinline__ u16 f2bf(float f) { return (u16)(pack2(f, 0.f) & 0xffffu); }
; __device__ __forceinline__ int tid_() { int t = threadIdx.x; asm volatile("" : "+v"(t)); return t; }
; template <int NT, class VF, class RP>
; __device__ __forceinline__ void epi_staged_bf16(f32x4 (&acc)[4][NT], int r0, int c0, unsigned char* smem, VF vf, RP rowptr) {
;   constexpr int BN = NT * 32, PITCH = BN + 8, CPR = BN / 8;
;   u16* Ts = (u16*)smem;
;   const int t = tid_();
;   __syncthreads();
; #pragma unroll
;   for (int mi = 0; mi < 4; ++mi)
; #pragma unroll
;     for (int ni = 0; ni < NT; ++ni)
; #pragma unroll
;       for (int j = 0; j < 4; ++j) {
;         const int r = r0 + mi * 16 + j, c = c0 + ni * 16;
;         Ts[r * PITCH + c] = f2bf(vf(r, c, acc[mi][ni][j]));
;       }
;   __syncthreads();
; __device__ __forceinline__ void phase_mix_a(const Params& p, int l, bool last, unsigned char* smem) {
;     ...
;         const float* rs = (const float*)(smem + 65536);
;         auto vf = [&](int r, int, float v) { return v * rs[r]; };
;         auto rp = [&](int r) -> u16* { return p.QR + (size_t)(row_base + r) * 768 + nt * 128; };
;         epi_staged_bf16<4>(acc, r0, c0, smem, vf, rp);
.LBB0_553:
	s_or_b64 exec, exec, s[0:1]
	v_lshlrev_b32_e32 v0, 6, v0
	s_waitcnt lgkmcnt(0)
	v_lshl_or_b32 v3, v137, 2, v0
	v_mov_b32_e32 v0, v187
	v_lshl_add_u32 v4, v3, 2, v213
	s_barrier
	s_barrier
	ds_read_b128 v[6:9], v4
	s_mulk_i32 s19, 0xfd00
	s_waitcnt lgkmcnt(0)
	v_mul_f32_e32 v2, v98, v6
	v_cvt_pk_bf16_f32 v5, v2, s0
	v_lshlrev_b32_e32 v2, 1, v145
	v_lshl_or_b32 v2, v144, 7, v2
	v_mad_u64_u32 v[10:11], s[0:1], v3, s23, v[2:3]
	ds_write_b16 v10, v5
	v_or_b32_e32 v3, 1, v3
	v_mul_f32_e32 v5, v99, v7
	v_cvt_pk_bf16_f32 v5, v5, s0
	v_mad_u64_u32 v[2:3], s[0:1], v3, s23, v[2:3]
	v_mul_f32_e32 v3, v100, v8
	s_nop 0
	v_cvt_pk_bf16_f32 v3, v3, s0
	ds_write_b16 v2, v3 offset:272
	v_mul_f32_e32 v3, v101, v9
	v_cvt_pk_bf16_f32 v3, v3, s0
	ds_write_b16 v2, v3 offset:544
	v_mul_f32_e32 v3, v102, v6
	v_cvt_pk_bf16_f32 v3, v3, s0
	ds_write_b16 v10, v3 offset:32
	v_mul_f32_e32 v3, v103, v7
	v_cvt_pk_bf16_f32 v3, v3, s0
	ds_write_b16 v2, v3 offset:32
	v_mul_f32_e32 v3, v104, v8
	v_cvt_pk_bf16_f32 v3, v3, s0
	ds_write_b16 v2, v3 offset:304
	v_mul_f32_e32 v3, v105, v9
	v_cvt_pk_bf16_f32 v3, v3, s0
	ds_write_b16 v2, v3 offset:576
	v_mul_f32_e32 v3, v106, v6
	v_cvt_pk_bf16_f32 v3, v3, s0
	ds_write_b16 v10, v3 offset:64
	v_mul_f32_e32 v3, v107, v7
	v_cvt_pk_bf16_f32 v3, v3, s0
	ds_write_b16 v2, v3 offset:64
	v_mul_f32_e32 v3, v108, v8
	v_cvt_pk_bf16_f32 v3, v3, s0
	ds_write_b16 v2, v3 offset:336
	v_mul_f32_e32 v3, v109, v9
	v_cvt_pk_bf16_f32 v3, v3, s0
	ds_write_b16 v2, v3 offset:608
	v_mul_f32_e32 v3, v110, v6
	v_cvt_pk_bf16_f32 v3, v3, s0
	ds_write_b16 v10, v3 offset:96
	v_mul_f32_e32 v3, v111, v7
	v_cvt_pk_bf16_f32 v3, v3, s0
	ds_write_b16 v2, v3 offset:96
	v_mul_f32_e32 v3, v112, v8
	v_cvt_pk_bf16_f32 v3, v3, s0
	ds_write_b16 v2, v3 offset:368
	v_mul_f32_e32 v3, v113, v9
	ds_read_b128 v[6:9], v4 offset:64
	v_cvt_pk_bf16_f32 v3, v3, s0
	ds_write_b16 v2, v3 offset:640
	ds_write_b16 v2, v5
	s_waitcnt lgkmcnt(2)
	v_mul_f32_e32 v3, v82, v6
	v_cvt_pk_bf16_f32 v3, v3, s0
	ds_write_b16 v2, v3 offset:4080
	v_mul_f32_e32 v3, v83, v7
	v_cvt_pk_bf16_f32 v3, v3, s0
	ds_write_b16 v2, v3 offset:4352
	v_mul_f32_e32 v3, v84, v8
	v_cvt_pk_bf16_f32 v3, v3, s0
	ds_write_b16 v2, v3 offset:4624
	v_mul_f32_e32 v3, v85, v9
	v_cvt_pk_bf16_f32 v3, v3, s0
	ds_write_b16 v2, v3 offset:4896
	v_mul_f32_e32 v3, v86, v6
	v_cvt_pk_bf16_f32 v3, v3, s0
	ds_write_b16 v2, v3 offset:4112
	v_mul_f32_e32 v3, v87, v7
	v_cvt_pk_bf16_f32 v3, v3, s0
	ds_write_b16 v2, v3 offset:4384
	v_mul_f32_e32 v3, v88, v8
	v_cvt_pk_bf16_f32 v3, v3, s0
	ds_write_b16 v2, v3 offset:4656
	v_mul_f32_e32 v3, v89, v9
	v_cvt_pk_bf16_f32 v3, v3, s0
	ds_write_b16 v2, v3 offset:4928
	v_mul_f32_e32 v3, v90, v6
	v_cvt_pk_bf16_f32 v3, v3, s0
	ds_write_b16 v2, v3 offset:4144
	v_mul_f32_e32 v3, v91, v7
	v_cvt_pk_bf16_f32 v3, v3, s0
	ds_write_b16 v2, v3 offset:4416
	v_mul_f32_e32 v3, v92, v8
	v_cvt_pk_bf16_f32 v3, v3, s0
	ds_write_b16 v2, v3 offset:4688
	v_mul_f32_e32 v3, v93, v9
	v_cvt_pk_bf16_f32 v3, v3, s0
	ds_write_b16 v2, v3 offset:4960
	v_mul_f32_e32 v3, v94, v6
	v_cvt_pk_bf16_f32 v3, v3, s0
	ds_write_b16 v2, v3 offset:4176
	v_mul_f32_e32 v3, v95, v7
	v_cvt_pk_bf16_f32 v3, v3, s0
	ds_write_b16 v2, v3 offset:4448
	v_mul_f32_e32 v3, v96, v8
	v_cvt_pk_bf16_f32 v3, v3, s0
	ds_write_b16 v2, v3 offset:4720
	v_mul_f32_e32 v3, v97, v9
	ds_read_b128 v[6:9], v4 offset:128
	v_cvt_pk_bf16_f32 v3, v3, s0
	ds_write_b16 v2, v3 offset:4992
	s_waitcnt lgkmcnt(1)
	v_mul_f32_e32 v3, v70, v6
	v_cvt_pk_bf16_f32 v3, v3, s0
	ds_write_b16 v2, v3 offset:8432
	v_mul_f32_e32 v3, v71, v7
	v_cvt_pk_bf16_f32 v3, v3, s0
	ds_write_b16 v2, v3 offset:8704
	v_mul_f32_e32 v3, v72, v8
	v_cvt_pk_bf16_f32 v3, v3, s0
	ds_write_b16 v2, v3 offset:8976
	v_mul_f32_e32 v3, v73, v9
	v_cvt_pk_bf16_f32 v3, v3, s0
	ds_write_b16 v2, v3 offset:9248
	v_mul_f32_e32 v3, v74, v6
	v_cvt_pk_bf16_f32 v3, v3, s0
	ds_write_b16 v2, v3 offset:8464
	v_mul_f32_e32 v3, v75, v7
	v_cvt_pk_bf16_f32 v3, v3, s0
	ds_write_b16 v2, v3 offset:8736
	v_mul_f32_e32 v3, v76, v8
	v_cvt_pk_bf16_f32 v3, v3, s0
	ds_write_b16 v2, v3 offset:9008
	v_mul_f32_e32 v3, v77, v9
	v_cvt_pk_bf16_f32 v3, v3, s0
	ds_write_b16 v2, v3 offset:9280
	v_mul_f32_e32 v3, v78, v6
	v_cvt_pk_bf16_f32 v3, v3, s0
	ds_write_b16 v2, v3 offset:8496
	v_mul_f32_e32 v3, v79, v7
	v_cvt_pk_bf16_f32 v3, v3, s0
	ds_write_b16 v2, v3 offset:8768
	v_mul_f32_e32 v3, v80, v8
	v_cvt_pk_bf16_f32 v3, v3, s0
	ds_write_b16 v2, v3 offset:9040
	v_mul_f32_e32 v3, v81, v9
	v_cvt_pk_bf16_f32 v3, v3, s0
	ds_write_b16 v2, v3 offset:9312
	v_mul_f32_e32 v3, v66, v6
	v_cvt_pk_bf16_f32 v3, v3, s0
	ds_write_b16 v2, v3 offset:8528
	v_mul_f32_e32 v3, v67, v7
	v_cvt_pk_bf16_f32 v3, v3, s0
	ds_read_b128 v[4:7], v4 offset:192
	ds_write_b16 v2, v3 offset:8800
	v_mul_f32_e32 v3, v68, v8
	v_cvt_pk_bf16_f32 v3, v3, s0
	ds_write_b16 v2, v3 offset:9072
	v_mul_f32_e32 v3, v69, v9
	v_cvt_pk_bf16_f32 v3, v3, s0
	ds_write_b16 v2, v3 offset:9344
	s_waitcnt lgkmcnt(3)
	v_mul_f32_e32 v3, v58, v4
	v_cvt_pk_bf16_f32 v3, v3, s0
	ds_write_b16 v2, v3 offset:12784
	v_mul_f32_e32 v3, v59, v5
	v_cvt_pk_bf16_f32 v3, v3, s0
	ds_write_b16 v2, v3 offset:13056
	v_mul_f32_e32 v3, v60, v6
	v_cvt_pk_bf16_f32 v3, v3, s0
	ds_write_b16 v2, v3 offset:13328
	v_mul_f32_e32 v3, v61, v7
	v_cvt_pk_bf16_f32 v3, v3, s0
	ds_write_b16 v2, v3 offset:13600
	v_mul_f32_e32 v3, v54, v4
	v_cvt_pk_bf16_f32 v3, v3, s0
	ds_write_b16 v2, v3 offset:12816
	v_mul_f32_e32 v3, v55, v5
	v_cvt_pk_bf16_f32 v3, v3, s0
	ds_write_b16 v2, v3 offset:13088
	v_mul_f32_e32 v3, v56, v6
	v_cvt_pk_bf16_f32 v3, v3, s0
	ds_write_b16 v2, v3 offset:13360
	v_mul_f32_e32 v3, v57, v7
	v_cvt_pk_bf16_f32 v3, v3, s0
	ds_write_b16 v2, v3 offset:13632
	v_mul_f32_e32 v3, v50, v4
	v_cvt_pk_bf16_f32 v3, v3, s0
	ds_write_b16 v2, v3 offset:12848
	v_mul_f32_e32 v3, v51, v5
	v_cvt_pk_bf16_f32 v3, v3, s0
	ds_write_b16 v2, v3 offset:13120
	v_mul_f32_e32 v3, v52, v6
	v_cvt_pk_bf16_f32 v3, v3, s0
	ds_write_b16 v2, v3 offset:13392
	v_mul_f32_e32 v3, v53, v7
	v_cvt_pk_bf16_f32 v3, v3, s0
	ds_write_b16 v2, v3 offset:13664
	v_mul_f32_e32 v3, v46, v4
	v_cvt_pk_bf16_f32 v3, v3, s0
	ds_write_b16 v2, v3 offset:12880
	v_mul_f32_e32 v3, v47, v5
	v_cvt_pk_bf16_f32 v3, v3, s0
	ds_write_b16 v2, v3 offset:13152
	v_mul_f32_e32 v3, v48, v6
	v_cvt_pk_bf16_f32 v3, v3, s0
	ds_write_b16 v2, v3 offset:13424
	v_mul_f32_e32 v3, v49, v7
	v_cvt_pk_bf16_f32 v3, v3, s0
	ds_write_b16 v2, v3 offset:13696
	v_mov_b64_e32 v[2:3], s[40:41]
	s_waitcnt lgkmcnt(0)
	s_barrier
; template <int NT, class VF, class RP>
; __device__ __forceinline__ void epi_staged_bf16(f32x4 (&acc)[4][NT], int r0, int c0, unsigned char* smem, VF vf, RP rowptr) {
;     ...
; #pragma unroll
;   for (int i = 0; i < CPR / 2; ++i) {
;     const int c = t + 256 * i, row = c / CPR, ch = c % CPR;
;     u16* d = rowptr(row);
;     if (d) *(u32x4*)(d + ch * 8) = *(const u32x4*)(Ts + row * PITCH + ch * 8);
;   }
; __device__ __forceinline__ void phase_mix_a(const Params& p, int l, bool last, unsigned char* smem) {
;     ...
;       auto epi = [&](f32x4(&acc)[4][4], int r0, int c0) {
;         const float* rs = (const float*)(smem + 65536);
;         auto vf = [&](int r, int, float v) { return v * rs[r]; };
;         auto rp = [&](int r) -> u16* { return p.QR + (size_t)(row_base + r) * 768 + nt * 128; };
;         epi_staged_bf16<4>(acc, r0, c0, smem, vf, rp);
	global_load_dwordx2 v[6:7], v[2:3], off offset:328
	v_mov_b64_e32 v[2:3], 0
	v_mov_b64_e32 v[4:5], 0
	s_waitcnt vmcnt(0) lgkmcnt(0)
	v_cmp_ne_u64_e32 vcc, 0, v[6:7]
	s_and_saveexec_b64 s[0:1], vcc
	s_xor_b64 s[0:1], exec, s[0:1]
	s_cbranch_execz .LBB0_555
	v_ashrrev_i32_e32 v4, 31, v0
	v_lshrrev_b32_e32 v4, 28, v4
	v_add_u32_e32 v4, v0, v4
	v_ashrrev_i32_e32 v5, 4, v4
	v_and_b32_e32 v4, -16, v4
	v_sub_u32_e32 v10, v0, v4
	v_mul_lo_u32 v4, v5, s23
	v_add_u32_e32 v8, s4, v5
	s_movk_i32 s5, 0x600
	v_lshl_add_u32 v4, v10, 4, v4
	v_mad_i64_i32 v[8:9], s[34:35], v8, s5, v[6:7]
	ds_read_b128 v[4:7], v4
	s_add_i32 s34, s18, s19
	s_ashr_i32 s35, s34, 31
	v_lshlrev_b32_e32 v10, 3, v10
	v_lshl_add_u64 v[8:9], s[34:35], 1, v[8:9]
	v_ashrrev_i32_e32 v11, 31, v10
	v_lshl_add_u64 v[8:9], v[10:11], 1, v[8:9]
	s_waitcnt lgkmcnt(0)
	global_store_dwordx4 v[8:9], v[4:7], off
	s_nop 1
	v_mov_b64_e32 v[4:5], s[40:41]
	global_load_dwordx2 v[4:5], v[4:5], off offset:328
.LBB0_555:
	s_or_b64 exec, exec, s[0:1]
	s_waitcnt vmcnt(0) lgkmcnt(0)
	v_cmp_ne_u64_e32 vcc, 0, v[4:5]
	s_and_saveexec_b64 s[0:1], vcc
	s_cbranch_execz .LBB0_557
	v_add_u32_e32 v2, 0x100, v0
	v_ashrrev_i32_e32 v3, 31, v2
	v_lshrrev_b32_e32 v3, 28, v3
	v_add_u32_e32 v3, v2, v3
	v_ashrrev_i32_e32 v8, 4, v3
	v_and_b32_e32 v3, -16, v3
	v_sub_u32_e32 v9, v2, v3
	v_mul_lo_u32 v2, v8, s23
	v_add_u32_e32 v6, s4, v8
	s_movk_i32 s5, 0x600
	v_lshl_add_u32 v2, v9, 4, v2
	v_mad_i64_i32 v[6:7], s[34:35], v6, s5, v[4:5]
	ds_read_b128 v[2:5], v2
	s_add_i32 s34, s18, s19
	s_ashr_i32 s35, s34, 31
	v_lshlrev_b32_e32 v8, 3, v9
	v_lshl_add_u64 v[6:7], s[34:35], 1, v[6:7]
	v_ashrrev_i32_e32 v9, 31, v8
	v_lshl_add_u64 v[6:7], v[8:9], 1, v[6:7]
	s_waitcnt lgkmcnt(0)
	global_store_dwordx4 v[6:7], v[2:5], off
	s_nop 1
	v_mov_b64_e32 v[2:3], s[40:41]
	global_load_dwordx2 v[2:3], v[2:3], off offset:328
.LBB0_557:
	s_or_b64 exec, exec, s[0:1]
	v_mov_b64_e32 v[4:5], 0
	s_waitcnt vmcnt(0) lgkmcnt(0)
	v_cmp_ne_u64_e32 vcc, 0, v[2:3]
	v_mov_b64_e32 v[6:7], 0
	s_and_saveexec_b64 s[0:1], vcc
	s_cbranch_execz .LBB0_559
	v_add_u32_e32 v6, 0x200, v0
	v_ashrrev_i32_e32 v7, 31, v6
	v_lshrrev_b32_e32 v7, 28, v7
	v_add_u32_e32 v7, v6, v7
	v_ashrrev_i32_e32 v8, 4, v7
	v_and_b32_e32 v7, -16, v7
	v_sub_u32_e32 v10, v6, v7
	v_mul_lo_u32 v6, v8, s23
	v_add_u32_e32 v9, s4, v8
	s_movk_i32 s5, 0x600
	v_lshl_add_u32 v6, v10, 4, v6
	v_mad_i64_i32 v[2:3], s[34:35], v9, s5, v[2:3]
	ds_read_b128 v[6:9], v6
	s_add_i32 s34, s18, s19
	s_ashr_i32 s35, s34, 31
	v_lshlrev_b32_e32 v10, 3, v10
	v_lshl_add_u64 v[2:3], s[34:35], 1, v[2:3]
	v_ashrrev_i32_e32 v11, 31, v10
	v_lshl_add_u64 v[2:3], v[10:11], 1, v[2:3]
	s_waitcnt lgkmcnt(0)
	global_store_dwordx4 v[2:3], v[6:9], off
	v_mov_b64_e32 v[2:3], s[40:41]
	global_load_dwordx2 v[6:7], v[2:3], off offset:328
.LBB0_559:
	s_or_b64 exec, exec, s[0:1]
	s_waitcnt vmcnt(0) lgkmcnt(0)
	v_cmp_ne_u64_e32 vcc, 0, v[6:7]
	s_and_saveexec_b64 s[0:1], vcc
	s_cbranch_execz .LBB0_561
	v_add_u32_e32 v2, 0x300, v0
	v_ashrrev_i32_e32 v3, 31, v2
	v_lshrrev_b32_e32 v3, 28, v3
	v_add_u32_e32 v3, v2, v3
	v_ashrrev_i32_e32 v4, 4, v3
	v_and_b32_e32 v3, -16, v3
	v_sub_u32_e32 v8, v2, v3
	v_mul_lo_u32 v2, v4, s23
	v_add_u32_e32 v5, s4, v4
	s_movk_i32 s5, 0x600
	v_lshl_add_u32 v2, v8, 4, v2
	v_mad_i64_i32 v[6:7], s[34:35], v5, s5, v[6:7]
	ds_read_b128 v[2:5], v2
	s_add_i32 s34, s18, s19
	s_ashr_i32 s35, s34, 31
	v_lshlrev_b32_e32 v8, 3, v8
	v_lshl_add_u64 v[6:7], s[34:35], 1, v[6:7]
	v_ashrrev_i32_e32 v9, 31, v8
	v_lshl_add_u64 v[6:7], v[8:9], 1, v[6:7]
	s_waitcnt lgkmcnt(0)
	global_store_dwordx4 v[6:7], v[2:5], off
	s_nop 1
	v_mov_b64_e32 v[2:3], s[40:41]
	global_load_dwordx2 v[4:5], v[2:3], off offset:328
; #define XCD_FOR(u, T)                                                                                         \
;   for (int _x = bid_() & 7, _gb = gridDim.x >> 3, _hi = (int)(((long)(_x + 1) * (T)) >> 3),                    \
;            u = (int)(((long)_x * (T)) >> 3) + (bid_() >> 3);                                                  \
;        u < _hi; u += _gb)
; template <int NT, class VF, class RP>
; __device__ __forceinline__ void epi_staged_bf16(f32x4 (&acc)[4][NT], int r0, int c0, unsigned char* smem, VF vf, RP rowptr) {
;     ...
; #pragma unroll
;   for (int i = 0; i < CPR / 2; ++i) {
;     const int c = t + 256 * i, row = c / CPR, ch = c % CPR;
;     u16* d = rowptr(row);
;     if (d) *(u32x4*)(d + ch * 8) = *(const u32x4*)(Ts + row * PITCH + ch * 8);
;   }
; __device__ __forceinline__ void phase_mix_a(const Params& p, int l, bool last, unsigned char* smem) {
;     ...
;   {
;     const u16* W = p.WukvT + (size_t)l * 1024 * 128;
;     XCD_FOR(t, 132 * 8) {
;       const int mt = t >> 3, nt = t & 7, row_base = mt * 128, h = nt >> 1;
.LBB0_561:
	s_or_b64 exec, exec, s[0:1]
	v_mov_b64_e32 v[2:3], 0
	s_waitcnt vmcnt(0) lgkmcnt(0)
	v_cmp_ne_u64_e32 vcc, 0, v[4:5]
	v_mov_b64_e32 v[6:7], 0
	s_and_saveexec_b64 s[0:1], vcc
	s_cbranch_execz .LBB0_563
	v_add_u32_e32 v6, 0x400, v0
	v_ashrrev_i32_e32 v7, 31, v6
	v_lshrrev_b32_e32 v7, 28, v7
	v_add_u32_e32 v7, v6, v7
	v_ashrrev_i32_e32 v10, 4, v7
	v_add_u32_e32 v8, s4, v10
	s_movk_i32 s5, 0x600
	v_mad_i64_i32 v[8:9], s[34:35], v8, s5, v[4:5]
	v_and_b32_e32 v4, -16, v7
	v_sub_u32_e32 v11, v6, v4
	v_mul_lo_u32 v4, v10, s23
	v_lshl_add_u32 v4, v11, 4, v4
	ds_read_b128 v[4:7], v4
	s_add_i32 s34, s18, s19
	s_ashr_i32 s35, s34, 31
	v_lshlrev_b32_e32 v10, 3, v11
	v_lshl_add_u64 v[8:9], s[34:35], 1, v[8:9]
	v_ashrrev_i32_e32 v11, 31, v10
	v_lshl_add_u64 v[8:9], v[10:11], 1, v[8:9]
	s_waitcnt lgkmcnt(0)
	global_store_dwordx4 v[8:9], v[4:7], off
	s_nop 1
	v_mov_b64_e32 v[4:5], s[40:41]
	global_load_dwordx2 v[6:7], v[4:5], off offset:328
.LBB0_563:
	s_or_b64 exec, exec, s[0:1]
	s_waitcnt vmcnt(0) lgkmcnt(0)
	v_cmp_ne_u64_e32 vcc, 0, v[6:7]
	s_and_saveexec_b64 s[0:1], vcc
	s_cbranch_execz .LBB0_565
	v_add_u32_e32 v2, 0x500, v0
	v_ashrrev_i32_e32 v3, 31, v2
	v_lshrrev_b32_e32 v3, 28, v3
	v_add_u32_e32 v3, v2, v3
	v_ashrrev_i32_e32 v4, 4, v3
	v_and_b32_e32 v3, -16, v3
	v_sub_u32_e32 v8, v2, v3
	v_mul_lo_u32 v2, v4, s23
	v_add_u32_e32 v5, s4, v4
	s_movk_i32 s5, 0x600
	v_lshl_add_u32 v2, v8, 4, v2
	v_mad_i64_i32 v[6:7], s[34:35], v5, s5, v[6:7]
	ds_read_b128 v[2:5], v2
	s_add_i32 s34, s18, s19
	s_ashr_i32 s35, s34, 31
	v_lshlrev_b32_e32 v8, 3, v8
	v_lshl_add_u64 v[6:7], s[34:35], 1, v[6:7]
	v_ashrrev_i32_e32 v9, 31, v8
	v_lshl_add_u64 v[6:7], v[8:9], 1, v[6:7]
	s_waitcnt lgkmcnt(0)
	global_store_dwordx4 v[6:7], v[2:5], off
	s_nop 1
	v_mov_b64_e32 v[2:3], s[40:41]
	global_load_dwordx2 v[2:3], v[2:3], off offset:328
.LBB0_565:
	s_or_b64 exec, exec, s[0:1]
	v_mov_b64_e32 v[4:5], 0
	s_waitcnt vmcnt(0) lgkmcnt(0)
	v_cmp_ne_u64_e32 vcc, 0, v[2:3]
	s_and_saveexec_b64 s[0:1], vcc
	s_cbranch_execz .LBB0_567
	v_add_u32_e32 v4, 0x600, v0
	v_ashrrev_i32_e32 v5, 31, v4
	v_lshrrev_b32_e32 v5, 28, v5
	v_add_u32_e32 v5, v4, v5
	v_ashrrev_i32_e32 v8, 4, v5
	v_add_u32_e32 v6, s4, v8
	s_movk_i32 s5, 0x600
	v_mad_i64_i32 v[6:7], s[34:35], v6, s5, v[2:3]
	v_and_b32_e32 v2, -16, v5
	v_sub_u32_e32 v9, v4, v2
	v_mul_lo_u32 v2, v8, s23
	v_lshl_add_u32 v2, v9, 4, v2
	ds_read_b128 v[2:5], v2
	s_add_i32 s34, s18, s19
	s_ashr_i32 s35, s34, 31
	v_lshlrev_b32_e32 v8, 3, v9
	v_lshl_add_u64 v[6:7], s[34:35], 1, v[6:7]
	v_ashrrev_i32_e32 v9, 31, v8
	v_lshl_add_u64 v[6:7], v[8:9], 1, v[6:7]
	s_waitcnt lgkmcnt(0)
	global_store_dwordx4 v[6:7], v[2:5], off
	s_nop 1
	v_mov_b64_e32 v[2:3], s[40:41]
	global_load_dwordx2 v[4:5], v[2:3], off offset:328
.LBB0_567:
	s_or_b64 exec, exec, s[0:1]
	s_waitcnt vmcnt(0) lgkmcnt(0)
	v_cmp_ne_u64_e32 vcc, 0, v[4:5]
	s_and_saveexec_b64 s[0:1], vcc
	s_cbranch_execz .LBB0_544
	v_add_u32_e32 v0, 0x700, v0
	v_ashrrev_i32_e32 v2, 31, v0
	v_lshrrev_b32_e32 v2, 28, v2
	v_add_u32_e32 v2, v0, v2
	v_ashrrev_i32_e32 v3, 4, v2
	v_and_b32_e32 v2, -16, v2
	v_sub_u32_e32 v0, v0, v2
	v_mul_lo_u32 v2, v3, s23
	v_add_u32_e32 v6, s4, v3
	s_movk_i32 s4, 0x600
	v_lshl_add_u32 v2, v0, 4, v2
	v_mad_i64_i32 v[6:7], s[4:5], v6, s4, v[4:5]
	ds_read_b128 v[2:5], v2
	s_add_i32 s4, s18, s19
	s_ashr_i32 s5, s4, 31
	v_lshlrev_b32_e32 v8, 3, v0
	v_lshl_add_u64 v[6:7], s[4:5], 1, v[6:7]
	v_ashrrev_i32_e32 v9, 31, v8
	v_lshl_add_u64 v[6:7], v[8:9], 1, v[6:7]
	s_waitcnt lgkmcnt(0)
	global_store_dwordx4 v[6:7], v[2:5], off
	s_branch .LBB0_544
.LBB0_569:
	s_waitcnt vmcnt(0) lgkmcnt(0)
	v_mov_b64_e32 v[2:3], s[40:41]
	global_load_dwordx2 v[2:3], v[2:3], off offset:208
	s_mov_b32 s0, s2
	s_and_b32 s0, s0, 7
	s_mul_i32 s1, s0, 0x420
	s_addk_i32 s1, 0x420
	s_lshr_b32 s8, s1, 3
	s_mov_b32 s1, s2
	s_mul_i32 s4, s0, 0x84
	s_ashr_i32 s1, s1, 3
	s_add_i32 s9, s4, s1
	s_cmp_ge_i32 s9, s8
	s_mov_b32 s37, s95
	s_cbranch_scc1 .LBB0_600
	s_lshl_b64 s[4:5], s[36:37], 18
	s_mulk_i32 s0, 0x840
	s_lshl_b32 s1, s1, 4
	s_waitcnt vmcnt(0) lgkmcnt(0)
	v_lshl_add_u64 v[90:91], v[2:3], 0, s[4:5]
	s_add_i32 s18, s0, s1
	s_branch .LBB0_573

; template <int NT, bool BKN, bool MASK = false, bool ROWSS = false, class Epi> ...
;     ...
;   float ss_[4] = {0.f, 0.f, 0.f, 0.f};
;   int stk_ = 0;
;   f32x4 acc[4][NT];
; #pragma unroll
;   for (int i = 0; i < 4; ++i)
; #pragma unroll
;     for (int j = 0; j < NT; ++j) acc[i][j] = (f32x4){0.f, 0.f, 0.f, 0.f};
;   const int nk = K >> 6;
;   const int nkm1 = nk - 1;
;   __syncthreads();
;   GEMM_LOAD(ra0, rb0, 0);
;   GEMM_LOAD(ra1, rb1, 1);
;   GEMM_STORE(ra0, rb0, 0);
;   GEMM_LOAD(ra0, rb0, (2 < nkm1 ? 2 : nkm1));
;   __syncthreads();
;   for (int kt = 0; kt < nk - 2; kt += 2) {
;     GEMM_COMPUTE(0);
;     GEMM_STORE(ra1, rb1, 1);
;     GEMM_LOAD(ra1, rb1, kt + 3);
;     __syncthreads();
;     GEMM_COMPUTE(1);
;     GEMM_STORE(ra0, rb0, 0);
;     GEMM_LOAD(ra0, rb0, (kt + 4 < nkm1 ? kt + 4 : nkm1));
;     __syncthreads();
;   }
;   GEMM_COMPUTE(0);
;   GEMM_STORE(ra1, rb1, 1);
;   __syncthreads();
;   GEMM_COMPUTE(1);
.LBB0_573:
	v_mov_b64_e32 v[2:3], s[40:41]
	global_load_dwordx2 v[2:3], v[2:3], off offset:288
	s_and_b32 s4, s18, 0xffffff80
	v_mov_b32_e32 v102, v187
	s_ashr_i32 s5, s4, 31
	s_and_b32 s19, s9, 7
	v_ashrrev_i32_e32 v98, 3, v102
	s_lshl_b64 s[0:1], s[4:5], 11
	v_lshlrev_b32_e32 v43, 4, v102
	v_add_u32_e32 v96, 32, v98
	v_add_u32_e32 v94, 64, v98
	v_add_u32_e32 v92, 0x60, v98
	s_lshl_b32 s94, s19, 15
	v_and_b32_e32 v0, 0x70, v43
	v_ashrrev_i32_e32 v99, 31, v98
	v_ashrrev_i32_e32 v97, 31, v96
	v_ashrrev_i32_e32 v95, 31, v94
	v_ashrrev_i32_e32 v93, 31, v92
	v_lshl_add_u64 v[10:11], v[90:91], 0, s[94:95]
	v_lshlrev_b64 v[4:5], 11, v[96:97]
	v_lshlrev_b64 v[6:7], 11, v[94:95]
	v_lshlrev_b64 v[12:13], 11, v[92:93]
	v_lshl_add_u64 v[14:15], v[10:11], 0, v[0:1]
	v_lshlrev_b64 v[10:11], 8, v[98:99]
	v_lshlrev_b64 v[16:17], 8, v[94:95]
	v_lshl_add_u64 v[10:11], v[14:15], 0, v[10:11]
	v_lshl_add_u64 v[38:39], v[14:15], 0, v[16:17]
	v_lshlrev_b64 v[16:17], 8, v[92:93]
	v_lshl_add_u64 v[40:41], v[14:15], 0, v[16:17]
	s_waitcnt lgkmcnt(0)
	s_barrier
	v_lshrrev_b32_e32 v42, 4, v102
	v_and_b32_e32 v101, 15, v102
	v_bfe_u32 v68, v102, 1, 3
	v_bfe_u32 v100, v102, 6, 1
	v_bfe_u32 v93, v102, 4, 2
	v_cmp_lt_i32_e32 vcc, v212, v227
	s_waitcnt vmcnt(0)
	v_lshl_add_u64 v[2:3], v[2:3], 0, s[0:1]
	v_lshl_add_u64 v[8:9], v[2:3], 0, v[0:1]
	v_lshlrev_b64 v[2:3], 11, v[98:99]
	v_lshl_add_u64 v[2:3], v[8:9], 0, v[2:3]
	v_lshl_add_u64 v[4:5], v[8:9], 0, v[4:5]
	v_lshl_add_u64 v[6:7], v[8:9], 0, v[6:7]
	v_lshl_add_u64 v[8:9], v[8:9], 0, v[12:13]
	v_lshlrev_b64 v[12:13], 8, v[96:97]
	v_lshl_add_u64 v[12:13], v[14:15], 0, v[12:13]
	global_load_dwordx4 v[44:47], v[2:3], off offset:1536
	global_load_dwordx4 v[30:33], v[4:5], off offset:1536
	global_load_dwordx4 v[22:25], v[6:7], off offset:1536
	global_load_dwordx4 v[18:21], v[8:9], off offset:1536
	global_load_dwordx4 v[56:59], v[10:11], off
	global_load_dwordx4 v[60:63], v[12:13], off
	global_load_dwordx4 v[64:67], v[38:39], off
	global_load_dwordx4 v[74:77], v[40:41], off
	global_load_dwordx4 v[34:37], v[2:3], off offset:1664
	global_load_dwordx4 v[70:73], v[4:5], off offset:1664
	global_load_dwordx4 v[50:53], v[6:7], off offset:1664
	global_load_dwordx4 v[26:29], v[8:9], off offset:1664
	global_load_dwordx4 v[14:17], v[10:11], off offset:128
	s_nop 0
	global_load_dwordx4 v[2:5], v[12:13], off offset:128
	global_load_dwordx4 v[6:9], v[38:39], off offset:128
	s_nop 0
	global_load_dwordx4 v[10:13], v[40:41], off offset:128
	v_ashrrev_i32_e32 v0, 7, v102
	s_waitcnt vmcnt(0) lgkmcnt(0)
	v_and_b32_e32 v39, 0xffff0000, v44
	v_lshlrev_b32_e32 v38, 16, v44
	v_and_b32_e32 v41, 0xffff0000, v45
	v_mul_f32_e32 v39, v39, v39
	v_lshlrev_b32_e32 v40, 16, v45
	v_fmac_f32_e32 v39, v38, v38
	v_mul_f32_e32 v38, v41, v41
	v_and_b32_e32 v49, 0xffff0000, v46
	v_fmac_f32_e32 v38, v40, v40
	v_lshlrev_b32_e32 v48, 16, v46
	v_add_f32_e32 v38, v39, v38
	v_mul_f32_e32 v39, v49, v49
	v_and_b32_e32 v55, 0xffff0000, v47
	v_fmac_f32_e32 v39, v48, v48
	v_lshlrev_b32_e32 v54, 16, v47
	v_add_f32_e32 v38, v39, v38
	v_mul_f32_e32 v39, v55, v55
	v_fmac_f32_e32 v39, v54, v54
	v_add_f32_e32 v55, v39, v38
	v_xor_b32_e32 v38, v42, v102
	v_lshlrev_b32_e32 v38, 4, v38
	v_and_b32_e32 v39, 0xffffff80, v43
	v_and_or_b32 v54, v38, s14, v39
	ds_write_b128 v54, v[44:47]
	ds_write_b128 v54, v[30:33] offset:4096
	ds_write_b128 v54, v[22:25] offset:8192
	ds_write_b128 v54, v[18:21] offset:12288
	ds_write_b128 v54, v[56:59] offset:16384
	ds_write_b128 v54, v[60:63] offset:20480
	ds_write_b128 v54, v[64:67] offset:24576
	ds_write_b128 v54, v[74:77] offset:28672
	v_bitop3_b32 v38, v42, v68, 3 bitop3:0x6c
	v_lshlrev_b32_e32 v61, 7, v101
	v_lshlrev_b32_e32 v60, 4, v38
	v_lshl_or_b32 v69, v0, 13, v61
	v_lshl_or_b32 v95, v100, 13, v61
	v_or_b32_e32 v97, v60, v69
	v_or_b32_e32 v99, v60, v95
	s_waitcnt lgkmcnt(0)
	s_barrier
	ds_read_b128 v[38:41], v97
	ds_read_b128 v[42:45], v97 offset:2048
	ds_read_b128 v[46:49], v97 offset:4096
	ds_read_b128 v[56:59], v97 offset:6144
	ds_read_b128 v[60:63], v99 offset:16384
	ds_read_b128 v[64:67], v99 offset:18432
	ds_read_b128 v[74:77], v99 offset:20480
	ds_read_b128 v[78:81], v99 offset:22528
	v_bitop3_b32 v68, v93, v68, 4 bitop3:0x36
	v_lshlrev_b32_e32 v68, 4, v68
	v_or_b32_e32 v69, v68, v69
	v_or_b32_e32 v68, v68, v95
	s_waitcnt lgkmcnt(3)
	v_mfma_f32_16x16x32_bf16 v[82:85], v[38:41], v[60:63], 0
	v_and_b32_e32 v102, 7, v102
	s_waitcnt lgkmcnt(2)
	v_mfma_f32_16x16x32_bf16 v[86:89], v[38:41], v[64:67], 0
	s_waitcnt lgkmcnt(1)
	v_mfma_f32_16x16x32_bf16 v[104:107], v[38:41], v[74:77], 0
	s_waitcnt lgkmcnt(0)
	v_mfma_f32_16x16x32_bf16 v[38:41], v[38:41], v[78:81], 0
	v_mfma_f32_16x16x32_bf16 v[108:111], v[42:45], v[60:63], 0
	v_mfma_f32_16x16x32_bf16 v[112:115], v[42:45], v[64:67], 0
	v_mfma_f32_16x16x32_bf16 v[116:119], v[42:45], v[74:77], 0
	v_mfma_f32_16x16x32_bf16 v[42:45], v[42:45], v[78:81], 0
	v_mfma_f32_16x16x32_bf16 v[120:123], v[46:49], v[60:63], 0
	v_mfma_f32_16x16x32_bf16 v[124:127], v[46:49], v[64:67], 0
	v_mfma_f32_16x16x32_bf16 v[128:131], v[46:49], v[74:77], 0
	v_mfma_f32_16x16x32_bf16 v[46:49], v[46:49], v[78:81], 0
	v_mfma_f32_16x16x32_bf16 v[60:63], v[56:59], v[60:63], 0
	v_mfma_f32_16x16x32_bf16 v[64:67], v[56:59], v[64:67], 0
	v_mfma_f32_16x16x32_bf16 v[74:77], v[56:59], v[74:77], 0
	v_mfma_f32_16x16x32_bf16 v[56:59], v[56:59], v[78:81], 0
	ds_read_b128 v[78:81], v69
	ds_read_b128 v[132:135], v69 offset:2048
	ds_read_b128 v[136:139], v69 offset:4096
	ds_read_b128 v[140:143], v69 offset:6144
	ds_read_b128 v[144:147], v68 offset:16384
	ds_read_b128 v[148:151], v68 offset:18432
	ds_read_b128 v[152:155], v68 offset:20480
	ds_read_b128 v[156:159], v68 offset:22528
	ds_write_b128 v54, v[34:37] offset:32768
	ds_write_b128 v54, v[70:73] offset:36864
	ds_write_b128 v54, v[50:53] offset:40960
	ds_write_b128 v54, v[26:29] offset:45056
	ds_write_b128 v54, v[14:17] offset:49152
	ds_write_b128 v54, v[2:5] offset:53248
	ds_write_b128 v54, v[6:9] offset:57344
	ds_write_b128 v54, v[10:13] offset:61440
	s_waitcnt lgkmcnt(11)
	v_mfma_f32_16x16x32_bf16 v[120:123], v[136:139], v[144:147], v[120:123]
	s_waitcnt lgkmcnt(0)
	s_barrier
; template <int NT, bool BKN, bool MASK = false, bool ROWSS = false, class Epi> ...
;     ...
;   GEMM_COMPUTE(1);
;     ...
;   if (ROWSS) {
;     float* rs = (float*)(smem + 65536);
; #pragma unroll
;     for (int i = 0; i < 4; ++i) {
;       float s = ss_[i];
;       s += __shfl_xor(s, 1); s += __shfl_xor(s, 2); s += __shfl_xor(s, 4);
;       if ((t & 7) == 0) rs[(t >> 3) + 32 * i] = rsqrtf(s / (float)K + 1e-6f);
;     }
;     __syncthreads();
	v_mfma_f32_16x16x32_bf16 v[124:127], v[136:139], v[148:151], v[124:127]
	v_mfma_f32_16x16x32_bf16 v[128:131], v[136:139], v[152:155], v[128:131]
	v_mfma_f32_16x16x32_bf16 v[136:139], v[136:139], v[156:159], v[46:49]
	v_mfma_f32_16x16x32_bf16 v[46:49], v[140:143], v[156:159], v[56:59]
	s_nop 2
	v_and_b32_e32 v57, 0xffff0000, v34
	v_lshlrev_b32_e32 v56, 16, v34
	v_and_b32_e32 v59, 0xffff0000, v35
	v_mul_f32_e32 v57, v57, v57
	v_lshlrev_b32_e32 v58, 16, v35
	v_fmac_f32_e32 v57, v56, v56
	v_mul_f32_e32 v56, v59, v59
	v_mfma_f32_16x16x32_bf16 v[82:85], v[78:81], v[144:147], v[82:85]
	v_fmac_f32_e32 v56, v58, v58
	v_add_f32_e32 v56, v57, v56
	v_mfma_f32_16x16x32_bf16 v[86:89], v[78:81], v[148:151], v[86:89]
	v_mfma_f32_16x16x32_bf16 v[104:107], v[78:81], v[152:155], v[104:107]
	v_mfma_f32_16x16x32_bf16 v[78:81], v[78:81], v[156:159], v[38:41]
	v_mfma_f32_16x16x32_bf16 v[38:41], v[140:143], v[148:151], v[64:67]
	s_nop 2
	v_and_b32_e32 v65, 0xffff0000, v36
	v_lshlrev_b32_e32 v64, 16, v36
	v_mul_f32_e32 v57, v65, v65
	v_and_b32_e32 v67, 0xffff0000, v37
	v_fmac_f32_e32 v57, v64, v64
	v_lshlrev_b32_e32 v66, 16, v37
	v_add_f32_e32 v56, v57, v56
	v_mul_f32_e32 v57, v67, v67
	v_fmac_f32_e32 v57, v66, v66
	v_add_f32_e32 v56, v57, v56
	v_mfma_f32_16x16x32_bf16 v[108:111], v[132:135], v[144:147], v[108:111]
	v_add_f32_e32 v95, v55, v56
	v_mfma_f32_16x16x32_bf16 v[112:115], v[132:135], v[148:151], v[112:115]
	v_mfma_f32_16x16x32_bf16 v[116:119], v[132:135], v[152:155], v[116:119]
	v_mfma_f32_16x16x32_bf16 v[132:135], v[132:135], v[156:159], v[42:45]
	v_mfma_f32_16x16x32_bf16 v[42:45], v[140:143], v[152:155], v[74:77]
	ds_read_b128 v[2:5], v97 offset:32768
	ds_read_b128 v[6:9], v97 offset:34816
	ds_read_b128 v[10:13], v97 offset:36864
	ds_read_b128 v[14:17], v97 offset:38912
	ds_read_b128 v[34:37], v99 offset:49152
	ds_read_b128 v[54:57], v99 offset:51200
	ds_read_b128 v[64:67], v99 offset:53248
	ds_read_b128 v[74:77], v99 offset:55296
	v_cndmask_b32_e32 v97, v186, v212, vcc
	v_cmp_lt_i32_e32 vcc, v253, v227
	v_lshlrev_b32_e32 v97, 2, v97
	v_mfma_f32_16x16x32_bf16 v[60:63], v[140:143], v[144:147], v[60:63]
	v_cndmask_b32_e32 v99, v186, v253, vcc
	v_cmp_lt_i32_e32 vcc, v252, v227
	v_lshlrev_b32_e32 v99, 2, v99
	s_waitcnt lgkmcnt(3)
	v_mfma_f32_16x16x32_bf16 v[82:85], v[2:5], v[34:37], v[82:85]
	v_cndmask_b32_e32 v103, v186, v252, vcc
	v_cmp_eq_u32_e32 vcc, 0, v102
	ds_bpermute_b32 v102, v97, v95
	v_mfma_f32_16x16x32_bf16 v[108:111], v[6:9], v[34:37], v[108:111]
	v_lshlrev_b32_e32 v103, 2, v103
	s_waitcnt lgkmcnt(0)
	v_add_f32_e32 v95, v95, v102
	ds_bpermute_b32 v102, v99, v95
	v_mfma_f32_16x16x32_bf16 v[112:115], v[6:9], v[54:57], v[112:115]
	s_waitcnt lgkmcnt(0)
	v_add_f32_e32 v95, v95, v102
	v_mfma_f32_16x16x32_bf16 v[116:119], v[6:9], v[64:67], v[116:119]
	ds_bpermute_b32 v102, v103, v95
	v_mfma_f32_16x16x32_bf16 v[6:9], v[6:9], v[74:77], v[132:135]
	v_mfma_f32_16x16x32_bf16 v[120:123], v[10:13], v[34:37], v[120:123]
	v_mfma_f32_16x16x32_bf16 v[124:127], v[10:13], v[54:57], v[124:127]
	v_mfma_f32_16x16x32_bf16 v[128:131], v[10:13], v[64:67], v[128:131]
	v_mfma_f32_16x16x32_bf16 v[10:13], v[10:13], v[74:77], v[136:139]
	v_mfma_f32_16x16x32_bf16 v[132:135], v[14:17], v[34:37], v[60:63]
	v_mfma_f32_16x16x32_bf16 v[136:139], v[14:17], v[54:57], v[38:41]
	v_mfma_f32_16x16x32_bf16 v[140:143], v[14:17], v[64:67], v[42:45]
	v_mfma_f32_16x16x32_bf16 v[144:147], v[14:17], v[74:77], v[46:49]
	ds_read_b128 v[14:17], v69 offset:32768
	ds_read_b128 v[34:37], v69 offset:34816
	ds_read_b128 v[148:151], v69 offset:36864
	ds_read_b128 v[152:155], v69 offset:38912
	ds_read_b128 v[156:159], v68 offset:49152
	ds_read_b128 v[160:163], v68 offset:51200
	ds_read_b128 v[164:167], v68 offset:53248
	ds_read_b128 v[168:171], v68 offset:55296
	v_mfma_f32_16x16x32_bf16 v[86:89], v[2:5], v[54:57], v[86:89]
	v_mfma_f32_16x16x32_bf16 v[104:107], v[2:5], v[64:67], v[104:107]
	v_mfma_f32_16x16x32_bf16 v[2:5], v[2:5], v[74:77], v[78:81]
	s_waitcnt lgkmcnt(3)
	v_mfma_f32_16x16x32_bf16 v[74:77], v[14:17], v[156:159], v[82:85]
	s_waitcnt lgkmcnt(2)
	v_mfma_f32_16x16x32_bf16 v[78:81], v[14:17], v[160:163], v[86:89]
	s_waitcnt lgkmcnt(1)
	v_mfma_f32_16x16x32_bf16 v[82:85], v[14:17], v[164:167], v[104:107]
	s_waitcnt lgkmcnt(0)
	v_mfma_f32_16x16x32_bf16 v[86:89], v[14:17], v[168:171], v[2:5]
	v_mfma_f32_16x16x32_bf16 v[54:57], v[34:37], v[156:159], v[108:111]
	v_mfma_f32_16x16x32_bf16 v[58:61], v[34:37], v[160:163], v[112:115]
	v_mfma_f32_16x16x32_bf16 v[62:65], v[34:37], v[164:167], v[116:119]
	v_mfma_f32_16x16x32_bf16 v[66:69], v[34:37], v[168:171], v[6:9]
	v_mfma_f32_16x16x32_bf16 v[38:41], v[148:151], v[156:159], v[120:123]
	v_mfma_f32_16x16x32_bf16 v[42:45], v[148:151], v[160:163], v[124:127]
	v_mfma_f32_16x16x32_bf16 v[46:49], v[148:151], v[164:167], v[128:131]
	v_mfma_f32_16x16x32_bf16 v[34:37], v[148:151], v[168:171], v[10:13]
	v_mfma_f32_16x16x32_bf16 v[14:17], v[152:155], v[156:159], v[132:135]
	v_mfma_f32_16x16x32_bf16 v[10:13], v[152:155], v[160:163], v[136:139]
	v_mfma_f32_16x16x32_bf16 v[6:9], v[152:155], v[164:167], v[140:143]
	v_mfma_f32_16x16x32_bf16 v[2:5], v[152:155], v[168:171], v[144:147]
	s_and_saveexec_b64 s[0:1], vcc
	s_cbranch_execz .LBB0_575
	v_add_f32_e32 v95, v95, v102
	v_fmamk_f32 v95, v95, 0x3c000000, v224
	v_mul_f32_e32 v102, 0x4b800000, v95
	v_cmp_gt_f32_e64 s[38:39], s85, v95
	v_lshl_add_u32 v98, v98, 2, v213
	s_nop 0
	v_cndmask_b32_e64 v95, v95, v102, s[38:39]
	v_rsq_f32_e32 v95, v95
	s_nop 0
	v_mul_f32_e32 v102, 0x45800000, v95
	v_cndmask_b32_e64 v95, v95, v102, s[38:39]
	ds_write_b32 v98, v95

; __device__ __forceinline__ int tid_() { int t = threadIdx.x; asm volatile("" : "+v"(t)); return t; }
; template <class RP>
; __device__ __forceinline__ void epi_staged_bf16_T(f32x4 (&acc)[4][4], int r0, int c0, unsigned char* smem, RP colptr) {
;   constexpr int PITCH = 136;
;   u16* Ts = (u16*)smem;
;   const int t = tid_();
;   __syncthreads();
; #pragma unroll
;   for (int mi = 0; mi < 4; ++mi)
; #pragma unroll
;     for (int ni = 0; ni < 4; ++ni) {
;       u32x2 pk;
;       pk.x = pack2(acc[mi][ni][0], acc[mi][ni][1]);
;       pk.y = pack2(acc[mi][ni][2], acc[mi][ni][3]);
;       *(u32x2*)(Ts + (c0 + ni * 16) * PITCH + r0 + mi * 16) = pk;
;     }
;   __syncthreads();
; __device__ __forceinline__ void phase_mix_a(const Params& p, int l, bool last, unsigned char* smem) {
;     ...
; #pragma unroll
;           for (int mi = 0; mi < 4; ++mi)
; #pragma unroll
;             for (int j = 0; j < 4; ++j) {
;               const float sc = rs[r0 + mi * 16 + j];
; #pragma unroll
;               for (int ni = 0; ni < 4; ++ni) acc[mi][ni][j] *= sc;
;             }
;           auto cp = [&](int c) -> u16* { return p.Vt + ((size_t)(b * 4 + h) * 128 + c) * NPOS + pos_base; };
;           epi_staged_bf16_T(acc, r0, c0, smem, cp);
.LBB0_581:
	s_or_b64 exec, exec, s[0:1]
	s_lshr_b32 s5, s19, 1
	v_lshlrev_b32_e32 v0, 6, v0
	s_bitcmp1_b32 s9, 0
	v_lshl_or_b32 v18, v93, 2, v0
	s_cselect_b64 s[34:35], -1, 0
	s_waitcnt lgkmcnt(0)
	v_lshl_or_b32 v19, v100, 6, v101
	s_mov_b64 s[0:1], -1
	s_and_b64 vcc, exec, s[34:35]
	v_lshl_add_u32 v20, v18, 2, v213
	s_barrier
	s_cbranch_vccz .LBB0_583
	ds_read_b128 v[22:25], v20
	ds_read_b128 v[26:29], v20 offset:64
	v_mul_u32_u24_e32 v0, 0x88, v19
	v_lshlrev_b32_e32 v0, 1, v0
	v_mov_b32_e32 v21, v187
	s_waitcnt lgkmcnt(1)
	v_pk_mul_f32 v[30:31], v[86:87], v[22:23]
	v_pk_mul_f32 v[32:33], v[74:75], v[22:23]
	v_pk_mul_f32 v[50:51], v[78:79], v[22:23]
	v_pk_mul_f32 v[52:53], v[82:83], v[22:23]
	v_pk_mul_f32 v[70:71], v[88:89], v[24:25]
	v_pk_mul_f32 v[72:73], v[76:77], v[24:25]
	v_pk_mul_f32 v[92:93], v[80:81], v[24:25]
	v_pk_mul_f32 v[94:95], v[84:85], v[24:25]
	s_waitcnt lgkmcnt(0)
	v_pk_mul_f32 v[96:97], v[66:67], v[26:27]
	v_pk_mul_f32 v[98:99], v[54:55], v[26:27]
	v_pk_mul_f32 v[100:101], v[58:59], v[26:27]
	v_pk_mul_f32 v[102:103], v[62:63], v[26:27]
	v_pk_mul_f32 v[104:105], v[68:69], v[28:29]
	ds_read_b128 v[22:25], v20 offset:128
	v_pk_mul_f32 v[106:107], v[56:57], v[28:29]
	v_pk_mul_f32 v[108:109], v[60:61], v[28:29]
	v_pk_mul_f32 v[110:111], v[64:65], v[28:29]
	ds_read_b128 v[26:29], v20 offset:192
	v_cvt_pk_bf16_f32 v32, v32, v33
	v_cvt_pk_bf16_f32 v33, v72, v73
	v_lshl_add_u32 v0, v18, 1, v0
	v_cvt_pk_bf16_f32 v30, v30, v31
	v_cvt_pk_bf16_f32 v31, v70, v71
	v_cvt_pk_bf16_f32 v70, v98, v99
	v_cvt_pk_bf16_f32 v71, v106, v107
	s_waitcnt lgkmcnt(0)
	s_barrier
	v_cvt_pk_bf16_f32 v50, v50, v51
	v_cvt_pk_bf16_f32 v51, v92, v93
	ds_write2_b64 v0, v[32:33], v[70:71] offset1:4
	v_cvt_pk_bf16_f32 v32, v100, v101
	v_cvt_pk_bf16_f32 v33, v108, v109
	v_add_u32_e32 v70, 0x1000, v0
	v_cvt_pk_bf16_f32 v52, v52, v53
	v_cvt_pk_bf16_f32 v53, v94, v95
	ds_write2_b64 v70, v[50:51], v[32:33] offset0:32 offset1:36
	v_cvt_pk_bf16_f32 v32, v102, v103
	v_cvt_pk_bf16_f32 v33, v110, v111
	v_add_u32_e32 v71, 0x2000, v0
	v_pk_mul_f32 v[112:113], v[34:35], v[22:23]
	v_pk_mul_f32 v[114:115], v[38:39], v[22:23]
	v_pk_mul_f32 v[116:117], v[42:43], v[22:23]
	v_pk_mul_f32 v[22:23], v[46:47], v[22:23]
	v_pk_mul_f32 v[118:119], v[36:37], v[24:25]
	v_pk_mul_f32 v[120:121], v[40:41], v[24:25]
	v_pk_mul_f32 v[122:123], v[44:45], v[24:25]
	v_pk_mul_f32 v[24:25], v[48:49], v[24:25]
	v_pk_mul_f32 v[124:125], v[2:3], v[26:27]
	v_pk_mul_f32 v[126:127], v[14:15], v[26:27]
	v_pk_mul_f32 v[128:129], v[10:11], v[26:27]
	v_pk_mul_f32 v[26:27], v[6:7], v[26:27]
	v_pk_mul_f32 v[130:131], v[4:5], v[28:29]
	v_pk_mul_f32 v[132:133], v[16:17], v[28:29]
	v_pk_mul_f32 v[134:135], v[12:13], v[28:29]
	v_pk_mul_f32 v[28:29], v[8:9], v[28:29]
	ds_write2_b64 v71, v[52:53], v[32:33] offset0:64 offset1:68
	v_cvt_pk_bf16_f32 v32, v96, v97
	v_cvt_pk_bf16_f32 v33, v104, v105
	v_add_u32_e32 v52, 0x3000, v0
	ds_write2_b64 v52, v[30:31], v[32:33] offset0:96 offset1:100
	v_cvt_pk_bf16_f32 v30, v114, v115
	v_cvt_pk_bf16_f32 v31, v120, v121
	v_cvt_pk_bf16_f32 v22, v22, v23
	v_cvt_pk_bf16_f32 v23, v24, v25
	v_cvt_pk_bf16_f32 v50, v126, v127
	v_cvt_pk_bf16_f32 v51, v132, v133
	v_cvt_pk_bf16_f32 v26, v26, v27
	v_cvt_pk_bf16_f32 v27, v28, v29
	v_cvt_pk_bf16_f32 v32, v116, v117
	v_cvt_pk_bf16_f32 v33, v122, v123
	v_cvt_pk_bf16_f32 v24, v112, v113
	v_cvt_pk_bf16_f32 v25, v118, v119
	ds_write2_b64 v0, v[30:31], v[50:51] offset0:8 offset1:12
	v_cvt_pk_bf16_f32 v30, v128, v129
	v_cvt_pk_bf16_f32 v31, v134, v135
	ds_write2_b64 v71, v[22:23], v[26:27] offset0:72 offset1:76
	v_cvt_pk_bf16_f32 v22, v124, v125
	v_cvt_pk_bf16_f32 v23, v130, v131
	v_mov_b64_e32 v[26:27], s[40:41]
	ds_write2_b64 v70, v[32:33], v[30:31] offset0:40 offset1:44
	ds_write2_b64 v52, v[24:25], v[22:23] offset0:104 offset1:108
	s_waitcnt lgkmcnt(0)
	s_barrier
; template <class RP>
; __device__ __forceinline__ void epi_staged_bf16_T(f32x4 (&acc)[4][4], int r0, int c0, unsigned char* smem, RP colptr) {
;     ...
; #pragma unroll
;   for (int i = 0; i < 8; ++i) {
;     const int c = t + 256 * i, col = c >> 4, ch = c & 15;
;     *(u32x4*)(colptr(col) + ch * 8) = *(const u32x4*)(Ts + col * PITCH + ch * 8);
;   }
; __device__ __forceinline__ void phase_mix_a(const Params& p, int l, bool last, unsigned char* smem) {
;     ...
;           auto cp = [&](int c) -> u16* { return p.Vt + ((size_t)(b * 4 + h) * 128 + c) * NPOS + pos_base; };
;           epi_staged_bf16_T(acc, r0, c0, smem, cp);
	global_load_dwordx2 v[28:29], v[26:27], off offset:344
	s_add_i32 s1, s18, 0xffffc000
	s_and_b32 s19, s18, 0x1f80
	s_ashr_i32 s0, s9, 9
	s_lshr_b32 s1, s1, 8
	s_addk_i32 s19, 0x100
	s_and_b32 s34, s18, 0x80
	v_lshlrev_b32_e32 v0, 4, v21
	s_cmpk_lt_i32 s4, 0x4000
	v_and_b32_e32 v0, 0xf0, v0
	v_ashrrev_i32_e32 v30, 4, v21
	s_cselect_b32 s35, s0, s1
	v_mad_u64_u32 v[22:23], s[0:1], v30, s23, v[0:1]
	s_cselect_b32 s19, s19, s34
	s_lshl_b32 s0, s35, 2
	s_or_b32 s0, s0, s5
	s_ashr_i32 s1, s0, 31
	s_lshl_b64 s[0:1], s[0:1], 7
	v_ashrrev_i32_e32 v31, 31, v30
	ds_read_b128 v[22:25], v22
	v_lshl_add_u64 v[30:31], s[0:1], 0, v[30:31]
	s_lshl_b32 s94, s19, 1
	s_waitcnt vmcnt(0) lgkmcnt(0)
	v_mad_u64_u32 v[28:29], s[34:35], v30, s68, v[28:29]
	v_mad_i32_i24 v29, v31, s68, v29
	v_lshl_add_u64 v[28:29], v[28:29], 0, s[94:95]
	v_lshl_add_u64 v[28:29], v[28:29], 0, v[0:1]
	global_store_dwordx4 v[28:29], v[22:25], off
	global_load_dwordx2 v[28:29], v[26:27], off offset:344
	s_nop 0
	v_add_u32_e32 v22, 0x100, v21
	v_ashrrev_i32_e32 v22, 4, v22
	v_mad_u64_u32 v[24:25], s[34:35], v22, s23, v[0:1]
	v_ashrrev_i32_e32 v23, 31, v22
	v_lshl_add_u64 v[30:31], s[0:1], 0, v[22:23]
	ds_read_b128 v[22:25], v24
	s_waitcnt vmcnt(0) lgkmcnt(0)
	v_mad_u64_u32 v[28:29], s[34:35], v30, s68, v[28:29]
	v_mad_i32_i24 v29, v31, s68, v29
	v_lshl_add_u64 v[28:29], v[28:29], 0, s[94:95]
	v_lshl_add_u64 v[28:29], v[28:29], 0, v[0:1]
	global_store_dwordx4 v[28:29], v[22:25], off
	global_load_dwordx2 v[28:29], v[26:27], off offset:344
	s_nop 0
	v_add_u32_e32 v22, 0x200, v21
	v_ashrrev_i32_e32 v22, 4, v22
	v_mad_u64_u32 v[24:25], s[34:35], v22, s23, v[0:1]
	v_ashrrev_i32_e32 v23, 31, v22
	v_lshl_add_u64 v[30:31], s[0:1], 0, v[22:23]
	ds_read_b128 v[22:25], v24
	s_waitcnt vmcnt(0) lgkmcnt(0)
	v_mad_u64_u32 v[28:29], s[34:35], v30, s68, v[28:29]
	v_mad_i32_i24 v29, v31, s68, v29
	v_lshl_add_u64 v[28:29], v[28:29], 0, s[94:95]
	v_lshl_add_u64 v[28:29], v[28:29], 0, v[0:1]
	global_store_dwordx4 v[28:29], v[22:25], off
	global_load_dwordx2 v[28:29], v[26:27], off offset:344
	s_nop 0
	v_add_u32_e32 v22, 0x300, v21
	v_ashrrev_i32_e32 v22, 4, v22
	v_mad_u64_u32 v[24:25], s[34:35], v22, s23, v[0:1]
	v_ashrrev_i32_e32 v23, 31, v22
	v_lshl_add_u64 v[30:31], s[0:1], 0, v[22:23]
	ds_read_b128 v[22:25], v24
	s_waitcnt vmcnt(0) lgkmcnt(0)
	v_mad_u64_u32 v[28:29], s[34:35], v30, s68, v[28:29]
	v_mad_i32_i24 v29, v31, s68, v29
	v_lshl_add_u64 v[28:29], v[28:29], 0, s[94:95]
	v_lshl_add_u64 v[28:29], v[28:29], 0, v[0:1]
	global_store_dwordx4 v[28:29], v[22:25], off
	global_load_dwordx2 v[28:29], v[26:27], off offset:344
	s_nop 0
	v_add_u32_e32 v22, 0x400, v21
	v_ashrrev_i32_e32 v22, 4, v22
	v_mad_u64_u32 v[24:25], s[34:35], v22, s23, v[0:1]
	v_ashrrev_i32_e32 v23, 31, v22
	v_lshl_add_u64 v[30:31], s[0:1], 0, v[22:23]
	ds_read_b128 v[22:25], v24
	s_waitcnt vmcnt(0) lgkmcnt(0)
	v_mad_u64_u32 v[28:29], s[34:35], v30, s68, v[28:29]
	v_mad_i32_i24 v29, v31, s68, v29
	v_lshl_add_u64 v[28:29], v[28:29], 0, s[94:95]
	v_lshl_add_u64 v[28:29], v[28:29], 0, v[0:1]
	global_store_dwordx4 v[28:29], v[22:25], off
	global_load_dwordx2 v[28:29], v[26:27], off offset:344
	s_nop 0
	v_add_u32_e32 v22, 0x500, v21
	v_ashrrev_i32_e32 v22, 4, v22
	v_mad_u64_u32 v[24:25], s[34:35], v22, s23, v[0:1]
	v_ashrrev_i32_e32 v23, 31, v22
	v_lshl_add_u64 v[30:31], s[0:1], 0, v[22:23]
	ds_read_b128 v[22:25], v24
	s_waitcnt vmcnt(0) lgkmcnt(0)
	v_mad_u64_u32 v[28:29], s[34:35], v30, s68, v[28:29]
	v_mad_i32_i24 v29, v31, s68, v29
	v_lshl_add_u64 v[28:29], v[28:29], 0, s[94:95]
	v_lshl_add_u64 v[28:29], v[28:29], 0, v[0:1]
	global_store_dwordx4 v[28:29], v[22:25], off
	global_load_dwordx2 v[28:29], v[26:27], off offset:344
	s_nop 0
	v_add_u32_e32 v22, 0x600, v21
	v_ashrrev_i32_e32 v22, 4, v22
	v_mad_u64_u32 v[24:25], s[34:35], v22, s23, v[0:1]
	v_ashrrev_i32_e32 v23, 31, v22
	v_lshl_add_u64 v[30:31], s[0:1], 0, v[22:23]
	ds_read_b128 v[22:25], v24
	v_add_u32_e32 v21, 0x700, v21
	s_waitcnt vmcnt(0) lgkmcnt(0)
	v_mad_u64_u32 v[28:29], s[34:35], v30, s68, v[28:29]
	v_mad_i32_i24 v29, v31, s68, v29
	v_lshl_add_u64 v[28:29], v[28:29], 0, s[94:95]
	v_lshl_add_u64 v[28:29], v[28:29], 0, v[0:1]
	global_store_dwordx4 v[28:29], v[22:25], off
	global_load_dwordx2 v[26:27], v[26:27], off offset:344
	s_nop 0
	v_ashrrev_i32_e32 v22, 4, v21
	v_mad_u64_u32 v[24:25], s[34:35], v22, s23, v[0:1]
	v_ashrrev_i32_e32 v23, 31, v22
	v_lshl_add_u64 v[28:29], s[0:1], 0, v[22:23]
	ds_read_b128 v[22:25], v24
	s_waitcnt vmcnt(0) lgkmcnt(0)
	v_mad_u64_u32 v[26:27], s[0:1], v28, s68, v[26:27]
	v_mad_i32_i24 v27, v29, s68, v27
	v_lshl_add_u64 v[26:27], v[26:27], 0, s[94:95]
	v_lshl_add_u64 v[26:27], v[26:27], 0, v[0:1]
	global_store_dwordx4 v[26:27], v[22:25], off
	s_cbranch_execnz .LBB0_572
	s_branch .LBB0_584

; __device__ __forceinline__ u16 f2bf(float f) { return (u16)(pack2(f, 0.f) & 0xffffu); }
; __device__ __forceinline__ int tid_() { int t = threadIdx.x; asm volatile("" : "+v"(t)); return t; }
; template <int NT, class VF, class RP>
; __device__ __forceinline__ void epi_staged_bf16(f32x4 (&acc)[4][NT], int r0, int c0, unsigned char* smem, VF vf, RP rowptr) {
;   constexpr int BN = NT * 32, PITCH = BN + 8, CPR = BN / 8;
;   u16* Ts = (u16*)smem;
;   const int t = tid_();
;   __syncthreads();
; #pragma unroll
;   for (int mi = 0; mi < 4; ++mi)
; #pragma unroll
;     for (int ni = 0; ni < NT; ++ni)
; #pragma unroll
;       for (int j = 0; j < 4; ++j) {
;         const int r = r0 + mi * 16 + j, c = c0 + ni * 16;
;         Ts[r * PITCH + c] = f2bf(vf(r, c, acc[mi][ni][j]));
;       }
;   __syncthreads();
; __device__ __forceinline__ void phase_mix_a(const Params& p, int l, bool last, unsigned char* smem) {
;     ...
;           auto vf = [&](int r, int, float v) { return v * rs[r]; };
;           auto rp = [&](int r) -> u16* { return p.KN + (size_t)(row_base + r) * 512 + h * 128; };
;           epi_staged_bf16<4>(acc, r0, c0, smem, vf, rp);
.LBB0_584:
	v_mov_b32_e32 v0, v187
	s_waitcnt lgkmcnt(0)
	s_barrier
	ds_read_b128 v[22:25], v20
	v_lshlrev_b32_e32 v26, 1, v19
	s_waitcnt lgkmcnt(0)
	v_mul_f32_e32 v21, v74, v22
	v_cvt_pk_bf16_f32 v21, v21, s0
	v_mad_u64_u32 v[28:29], s[0:1], v18, s23, v[26:27]
	v_or_b32_e32 v18, 1, v18
	v_mul_f32_e32 v19, v75, v23
	ds_write_b16 v28, v21
	v_cvt_pk_bf16_f32 v21, v19, s0
	v_mad_u64_u32 v[18:19], s[0:1], v18, s23, v[26:27]
	v_mul_f32_e32 v19, v76, v24
	s_nop 0
	v_cvt_pk_bf16_f32 v19, v19, s0
	ds_write_b16 v18, v19 offset:272
	v_mul_f32_e32 v19, v77, v25
	v_cvt_pk_bf16_f32 v19, v19, s0
	ds_write_b16 v18, v19 offset:544
	v_mul_f32_e32 v19, v78, v22
	v_cvt_pk_bf16_f32 v19, v19, s0
	ds_write_b16 v28, v19 offset:32
	v_mul_f32_e32 v19, v79, v23
	v_cvt_pk_bf16_f32 v19, v19, s0
	ds_write_b16 v18, v19 offset:32
	v_mul_f32_e32 v19, v80, v24
	v_cvt_pk_bf16_f32 v19, v19, s0
	ds_write_b16 v18, v19 offset:304
	v_mul_f32_e32 v19, v81, v25
	v_cvt_pk_bf16_f32 v19, v19, s0
	ds_write_b16 v18, v19 offset:576
	v_mul_f32_e32 v19, v82, v22
	v_cvt_pk_bf16_f32 v19, v19, s0
	ds_write_b16 v28, v19 offset:64
	v_mul_f32_e32 v19, v83, v23
	v_cvt_pk_bf16_f32 v19, v19, s0
	ds_write_b16 v18, v19 offset:64
	v_mul_f32_e32 v19, v84, v24
	v_cvt_pk_bf16_f32 v19, v19, s0
	ds_write_b16 v18, v19 offset:336
	v_mul_f32_e32 v19, v85, v25
	v_cvt_pk_bf16_f32 v19, v19, s0
	ds_write_b16 v18, v19 offset:608
	v_mul_f32_e32 v19, v86, v22
	v_cvt_pk_bf16_f32 v19, v19, s0
	ds_write_b16 v28, v19 offset:96
	v_mul_f32_e32 v19, v87, v23
	v_cvt_pk_bf16_f32 v19, v19, s0
	ds_write_b16 v18, v19 offset:96
	v_mul_f32_e32 v19, v88, v24
	v_cvt_pk_bf16_f32 v19, v19, s0
	ds_write_b16 v18, v19 offset:368
	v_mul_f32_e32 v19, v89, v25
	ds_read_b128 v[22:25], v20 offset:64
	v_cvt_pk_bf16_f32 v19, v19, s0
	ds_write_b16 v18, v19 offset:640
	ds_write_b16 v18, v21
	s_waitcnt lgkmcnt(0)
	v_mul_f32_e32 v19, v54, v22
	v_cvt_pk_bf16_f32 v19, v19, s0
	ds_write_b16 v18, v19 offset:4080
	v_mul_f32_e32 v19, v55, v23
	v_cvt_pk_bf16_f32 v19, v19, s0
	ds_write_b16 v18, v19 offset:4352
	v_mul_f32_e32 v19, v56, v24
	v_cvt_pk_bf16_f32 v19, v19, s0
	ds_write_b16 v18, v19 offset:4624
	v_mul_f32_e32 v19, v57, v25
	v_cvt_pk_bf16_f32 v19, v19, s0
	ds_write_b16 v18, v19 offset:4896
	v_mul_f32_e32 v19, v58, v22
	v_cvt_pk_bf16_f32 v19, v19, s0
	ds_write_b16 v18, v19 offset:4112
	v_mul_f32_e32 v19, v59, v23
	v_cvt_pk_bf16_f32 v19, v19, s0
	ds_write_b16 v18, v19 offset:4384
	v_mul_f32_e32 v19, v60, v24
	v_cvt_pk_bf16_f32 v19, v19, s0
	ds_write_b16 v18, v19 offset:4656
	v_mul_f32_e32 v19, v61, v25
	v_cvt_pk_bf16_f32 v19, v19, s0
	ds_write_b16 v18, v19 offset:4928
	v_mul_f32_e32 v19, v62, v22
	v_cvt_pk_bf16_f32 v19, v19, s0
	ds_write_b16 v18, v19 offset:4144
	v_mul_f32_e32 v19, v63, v23
	v_cvt_pk_bf16_f32 v19, v19, s0
	ds_write_b16 v18, v19 offset:4416
	v_mul_f32_e32 v19, v64, v24
	v_cvt_pk_bf16_f32 v19, v19, s0
	ds_write_b16 v18, v19 offset:4688
	v_mul_f32_e32 v19, v65, v25
	v_cvt_pk_bf16_f32 v19, v19, s0
	ds_write_b16 v18, v19 offset:4960
	v_mul_f32_e32 v19, v66, v22
	v_cvt_pk_bf16_f32 v19, v19, s0
	ds_write_b16 v18, v19 offset:4176
	v_mul_f32_e32 v19, v67, v23
	v_cvt_pk_bf16_f32 v19, v19, s0
	ds_write_b16 v18, v19 offset:4448
	v_mul_f32_e32 v19, v68, v24
	v_cvt_pk_bf16_f32 v19, v19, s0
	ds_write_b16 v18, v19 offset:4720
	v_mul_f32_e32 v19, v69, v25
	ds_read_b128 v[22:25], v20 offset:128
	v_cvt_pk_bf16_f32 v19, v19, s0
	ds_write_b16 v18, v19 offset:4992
	s_waitcnt lgkmcnt(0)
	v_mul_f32_e32 v19, v38, v22
	v_cvt_pk_bf16_f32 v19, v19, s0
	ds_write_b16 v18, v19 offset:8432
	v_mul_f32_e32 v19, v39, v23
	v_cvt_pk_bf16_f32 v19, v19, s0
	ds_write_b16 v18, v19 offset:8704
	v_mul_f32_e32 v19, v40, v24
	v_cvt_pk_bf16_f32 v19, v19, s0
	ds_write_b16 v18, v19 offset:8976
	v_mul_f32_e32 v19, v41, v25
	v_cvt_pk_bf16_f32 v19, v19, s0
	ds_write_b16 v18, v19 offset:9248
	v_mul_f32_e32 v19, v42, v22
	v_cvt_pk_bf16_f32 v19, v19, s0
	ds_write_b16 v18, v19 offset:8464
	v_mul_f32_e32 v19, v43, v23
	v_cvt_pk_bf16_f32 v19, v19, s0
	ds_write_b16 v18, v19 offset:8736
	v_mul_f32_e32 v19, v44, v24
	v_cvt_pk_bf16_f32 v19, v19, s0
	ds_write_b16 v18, v19 offset:9008
	v_mul_f32_e32 v19, v45, v25
	v_cvt_pk_bf16_f32 v19, v19, s0
	ds_write_b16 v18, v19 offset:9280
	v_mul_f32_e32 v19, v46, v22
	v_cvt_pk_bf16_f32 v19, v19, s0
	ds_write_b16 v18, v19 offset:8496
	v_mul_f32_e32 v19, v47, v23
	v_cvt_pk_bf16_f32 v19, v19, s0
	ds_write_b16 v18, v19 offset:8768
	v_mul_f32_e32 v19, v48, v24
	v_cvt_pk_bf16_f32 v19, v19, s0
	ds_write_b16 v18, v19 offset:9040
	v_mul_f32_e32 v19, v49, v25
	v_cvt_pk_bf16_f32 v19, v19, s0
	ds_write_b16 v18, v19 offset:9312
	v_mul_f32_e32 v19, v34, v22
	v_cvt_pk_bf16_f32 v19, v19, s0
	ds_write_b16 v18, v19 offset:8528
	v_mul_f32_e32 v19, v35, v23
	ds_read_b128 v[20:23], v20 offset:192
	v_cvt_pk_bf16_f32 v19, v19, s0
	ds_write_b16 v18, v19 offset:8800
	v_mul_f32_e32 v19, v36, v24
	v_cvt_pk_bf16_f32 v19, v19, s0
	s_waitcnt lgkmcnt(0)
	v_mul_f32_e32 v2, v2, v20
	v_mul_f32_e32 v14, v14, v20
	v_mul_f32_e32 v10, v10, v20
	v_mul_f32_e32 v6, v6, v20
	v_cvt_pk_bf16_f32 v2, v2, s0
	v_cvt_pk_bf16_f32 v14, v14, s0
	v_cvt_pk_bf16_f32 v10, v10, s0
	v_cvt_pk_bf16_f32 v6, v6, s0
	ds_write_b16 v18, v2 offset:12880
	v_mul_f32_e32 v2, v3, v21
	ds_write_b16 v18, v14 offset:12784
	v_mul_f32_e32 v14, v15, v21
	ds_write_b16 v18, v10 offset:12816
	v_mul_f32_e32 v10, v11, v21
	ds_write_b16 v18, v6 offset:12848
	v_mul_f32_e32 v6, v7, v21
	v_cvt_pk_bf16_f32 v2, v2, s0
	v_cvt_pk_bf16_f32 v14, v14, s0
	v_cvt_pk_bf16_f32 v10, v10, s0
	v_cvt_pk_bf16_f32 v6, v6, s0
	ds_write_b16 v18, v2 offset:13152
	v_mul_f32_e32 v2, v4, v22
	ds_write_b16 v18, v14 offset:13056
	v_mul_f32_e32 v14, v16, v22
	ds_write_b16 v18, v10 offset:13088
	v_mul_f32_e32 v10, v12, v22
	ds_write_b16 v18, v6 offset:13120
	v_mul_f32_e32 v6, v8, v22
	v_cvt_pk_bf16_f32 v2, v2, s0
	v_cvt_pk_bf16_f32 v14, v14, s0
	v_cvt_pk_bf16_f32 v10, v10, s0
	v_cvt_pk_bf16_f32 v6, v6, s0
	ds_write_b16 v18, v2 offset:13424
	v_mul_f32_e32 v2, v5, v23
	ds_write_b16 v18, v19 offset:9072
	v_mul_f32_e32 v19, v37, v25
	ds_write_b16 v18, v14 offset:13328
	v_mul_f32_e32 v14, v17, v23
	ds_write_b16 v18, v10 offset:13360
	v_mul_f32_e32 v10, v13, v23
	ds_write_b16 v18, v6 offset:13392
	v_mul_f32_e32 v6, v9, v23
	v_cvt_pk_bf16_f32 v2, v2, s0
	v_cvt_pk_bf16_f32 v19, v19, s0
	v_cvt_pk_bf16_f32 v14, v14, s0
	v_cvt_pk_bf16_f32 v10, v10, s0
	v_cvt_pk_bf16_f32 v6, v6, s0
	ds_write_b16 v18, v2 offset:13696
	v_mov_b64_e32 v[2:3], s[40:41]
	ds_write_b16 v18, v19 offset:9344
	ds_write_b16 v18, v14 offset:13600
	ds_write_b16 v18, v10 offset:13632
	ds_write_b16 v18, v6 offset:13664
	s_waitcnt lgkmcnt(0)
	s_barrier
; template <int NT, class VF, class RP>
; __device__ __forceinline__ void epi_staged_bf16(f32x4 (&acc)[4][NT], int r0, int c0, unsigned char* smem, VF vf, RP rowptr) {
;     ...
; #pragma unroll
;   for (int i = 0; i < CPR / 2; ++i) {
;     const int c = t + 256 * i, row = c / CPR, ch = c % CPR;
;     u16* d = rowptr(row);
;     if (d) *(u32x4*)(d + ch * 8) = *(const u32x4*)(Ts + row * PITCH + ch * 8);
;   }
; __device__ __forceinline__ void phase_mix_a(const Params& p, int l, bool last, unsigned char* smem) {
;     ...
;           auto rp = [&](int r) -> u16* { return p.KN + (size_t)(row_base + r) * 512 + h * 128; };
	global_load_dwordx2 v[6:7], v[2:3], off offset:336
	v_mov_b64_e32 v[2:3], 0
	v_mov_b64_e32 v[4:5], 0
	s_waitcnt vmcnt(0) lgkmcnt(0)
	v_cmp_ne_u64_e32 vcc, 0, v[6:7]
	s_and_saveexec_b64 s[0:1], vcc
	s_cbranch_execz .LBB0_586
	v_ashrrev_i32_e32 v4, 31, v0
	v_lshrrev_b32_e32 v4, 28, v4
	v_add_u32_e32 v10, v0, v4
	v_ashrrev_i32_e32 v11, 4, v10
	v_add_u32_e32 v4, s4, v11
	v_ashrrev_i32_e32 v5, 31, v4
	v_lshlrev_b64 v[4:5], 10, v[4:5]
	v_lshl_add_u64 v[8:9], v[6:7], 0, v[4:5]
	v_and_b32_e32 v4, -16, v10
	v_sub_u32_e32 v10, v0, v4
	v_mul_lo_u32 v4, v11, s23
	v_lshl_add_u32 v4, v10, 4, v4
	ds_read_b128 v[4:7], v4
	s_lshl_b32 s94, s5, 8
	v_lshlrev_b32_e32 v10, 3, v10
	v_lshl_add_u64 v[8:9], v[8:9], 0, s[94:95]
	v_ashrrev_i32_e32 v11, 31, v10
	v_lshl_add_u64 v[8:9], v[10:11], 1, v[8:9]
	s_waitcnt lgkmcnt(0)
	global_store_dwordx4 v[8:9], v[4:7], off
	s_nop 1
	v_mov_b64_e32 v[4:5], s[40:41]
	global_load_dwordx2 v[4:5], v[4:5], off offset:336
.LBB0_586:
	s_or_b64 exec, exec, s[0:1]
	s_waitcnt vmcnt(0) lgkmcnt(0)
	v_cmp_ne_u64_e32 vcc, 0, v[4:5]
	s_and_saveexec_b64 s[0:1], vcc
	s_cbranch_execz .LBB0_588
	v_add_u32_e32 v8, 0x100, v0
	v_ashrrev_i32_e32 v2, 31, v8
	v_lshrrev_b32_e32 v2, 28, v2
	v_add_u32_e32 v9, v8, v2
	v_ashrrev_i32_e32 v10, 4, v9
	v_add_u32_e32 v2, s4, v10
	v_ashrrev_i32_e32 v3, 31, v2
	v_lshlrev_b64 v[2:3], 10, v[2:3]
	v_lshl_add_u64 v[6:7], v[4:5], 0, v[2:3]
	v_and_b32_e32 v2, -16, v9
	v_sub_u32_e32 v8, v8, v2
	v_mul_lo_u32 v2, v10, s23
	v_lshl_add_u32 v2, v8, 4, v2
	ds_read_b128 v[2:5], v2
	s_lshl_b32 s94, s5, 8
	v_lshlrev_b32_e32 v8, 3, v8
	v_lshl_add_u64 v[6:7], v[6:7], 0, s[94:95]
	v_ashrrev_i32_e32 v9, 31, v8
	v_lshl_add_u64 v[6:7], v[8:9], 1, v[6:7]
	s_waitcnt lgkmcnt(0)
	global_store_dwordx4 v[6:7], v[2:5], off
	s_nop 1
	v_mov_b64_e32 v[2:3], s[40:41]
	global_load_dwordx2 v[2:3], v[2:3], off offset:336
.LBB0_588:
	s_or_b64 exec, exec, s[0:1]
	v_mov_b64_e32 v[4:5], 0
	s_waitcnt vmcnt(0) lgkmcnt(0)
	v_cmp_ne_u64_e32 vcc, 0, v[2:3]
	v_mov_b64_e32 v[6:7], 0
	s_and_saveexec_b64 s[0:1], vcc
	s_cbranch_execz .LBB0_590
	v_add_u32_e32 v8, 0x200, v0
	v_ashrrev_i32_e32 v6, 31, v8
	v_lshrrev_b32_e32 v6, 28, v6
	v_add_u32_e32 v9, v8, v6
	v_ashrrev_i32_e32 v10, 4, v9
	v_add_u32_e32 v6, s4, v10
	v_ashrrev_i32_e32 v7, 31, v6
	v_lshlrev_b64 v[6:7], 10, v[6:7]
	v_lshl_add_u64 v[2:3], v[2:3], 0, v[6:7]
	v_and_b32_e32 v6, -16, v9
	v_sub_u32_e32 v11, v8, v6
	v_mul_lo_u32 v6, v10, s23
	v_lshl_add_u32 v6, v11, 4, v6
	ds_read_b128 v[6:9], v6
	s_lshl_b32 s94, s5, 8
	v_lshlrev_b32_e32 v10, 3, v11
	v_lshl_add_u64 v[2:3], v[2:3], 0, s[94:95]
	v_ashrrev_i32_e32 v11, 31, v10
	v_lshl_add_u64 v[2:3], v[10:11], 1, v[2:3]
	s_waitcnt lgkmcnt(0)
	global_store_dwordx4 v[2:3], v[6:9], off
	v_mov_b64_e32 v[2:3], s[40:41]
	global_load_dwordx2 v[6:7], v[2:3], off offset:336
.LBB0_590:
	s_or_b64 exec, exec, s[0:1]
	s_waitcnt vmcnt(0) lgkmcnt(0)
	v_cmp_ne_u64_e32 vcc, 0, v[6:7]
	s_and_saveexec_b64 s[0:1], vcc
	s_cbranch_execz .LBB0_592
	v_add_u32_e32 v4, 0x300, v0
	v_ashrrev_i32_e32 v2, 31, v4
	v_lshrrev_b32_e32 v2, 28, v2
	v_add_u32_e32 v5, v4, v2
	v_ashrrev_i32_e32 v8, 4, v5
	v_add_u32_e32 v2, s4, v8
	v_ashrrev_i32_e32 v3, 31, v2
	v_lshlrev_b64 v[2:3], 10, v[2:3]
	v_lshl_add_u64 v[6:7], v[6:7], 0, v[2:3]
	v_and_b32_e32 v2, -16, v5
	v_sub_u32_e32 v9, v4, v2
	v_mul_lo_u32 v2, v8, s23
	v_lshl_add_u32 v2, v9, 4, v2
	ds_read_b128 v[2:5], v2
	s_lshl_b32 s94, s5, 8
	v_lshlrev_b32_e32 v8, 3, v9
	v_lshl_add_u64 v[6:7], v[6:7], 0, s[94:95]
	v_ashrrev_i32_e32 v9, 31, v8
	v_lshl_add_u64 v[6:7], v[8:9], 1, v[6:7]
	s_waitcnt lgkmcnt(0)
	global_store_dwordx4 v[6:7], v[2:5], off
	s_nop 1
	v_mov_b64_e32 v[2:3], s[40:41]
	global_load_dwordx2 v[4:5], v[2:3], off offset:336
; template <int NT, class VF, class RP>
; __device__ __forceinline__ void epi_staged_bf16(f32x4 (&acc)[4][NT], int r0, int c0, unsigned char* smem, VF vf, RP rowptr) {
;     ...
; #pragma unroll
;   for (int i = 0; i < CPR / 2; ++i) {
;     const int c = t + 256 * i, row = c / CPR, ch = c % CPR;
;     u16* d = rowptr(row);
;     if (d) *(u32x4*)(d + ch * 8) = *(const u32x4*)(Ts + row * PITCH + ch * 8);
;   }
; __device__ __forceinline__ void phase_mix_a(const Params& p, int l, bool last, unsigned char* smem) {
;     ...
;           auto rp = [&](int r) -> u16* { return p.KN + (size_t)(row_base + r) * 512 + h * 128; };
.LBB0_592:
	s_or_b64 exec, exec, s[0:1]
	v_mov_b64_e32 v[2:3], 0
	s_waitcnt vmcnt(0) lgkmcnt(0)
	v_cmp_ne_u64_e32 vcc, 0, v[4:5]
	v_mov_b64_e32 v[6:7], 0
	s_and_saveexec_b64 s[0:1], vcc
	s_cbranch_execz .LBB0_594
	v_add_u32_e32 v10, 0x400, v0
	v_ashrrev_i32_e32 v6, 31, v10
	v_lshrrev_b32_e32 v6, 28, v6
	v_add_u32_e32 v11, v10, v6
	v_ashrrev_i32_e32 v12, 4, v11
	v_add_u32_e32 v6, s4, v12
	v_ashrrev_i32_e32 v7, 31, v6
	v_lshlrev_b64 v[6:7], 10, v[6:7]
	v_lshl_add_u64 v[8:9], v[4:5], 0, v[6:7]
	v_and_b32_e32 v4, -16, v11
	v_sub_u32_e32 v10, v10, v4
	v_mul_lo_u32 v4, v12, s23
	v_lshl_add_u32 v4, v10, 4, v4
	ds_read_b128 v[4:7], v4
	s_lshl_b32 s94, s5, 8
	v_lshlrev_b32_e32 v10, 3, v10
	v_lshl_add_u64 v[8:9], v[8:9], 0, s[94:95]
	v_ashrrev_i32_e32 v11, 31, v10
	v_lshl_add_u64 v[8:9], v[10:11], 1, v[8:9]
	s_waitcnt lgkmcnt(0)
	global_store_dwordx4 v[8:9], v[4:7], off
	s_nop 1
	v_mov_b64_e32 v[4:5], s[40:41]
	global_load_dwordx2 v[6:7], v[4:5], off offset:336
.LBB0_594:
	s_or_b64 exec, exec, s[0:1]
	s_waitcnt vmcnt(0) lgkmcnt(0)
	v_cmp_ne_u64_e32 vcc, 0, v[6:7]
	s_and_saveexec_b64 s[0:1], vcc
	s_cbranch_execz .LBB0_596
	v_add_u32_e32 v4, 0x500, v0
	v_ashrrev_i32_e32 v2, 31, v4
	v_lshrrev_b32_e32 v2, 28, v2
	v_add_u32_e32 v5, v4, v2
	v_ashrrev_i32_e32 v8, 4, v5
	v_add_u32_e32 v2, s4, v8
	v_ashrrev_i32_e32 v3, 31, v2
	v_lshlrev_b64 v[2:3], 10, v[2:3]
	v_lshl_add_u64 v[6:7], v[6:7], 0, v[2:3]
	v_and_b32_e32 v2, -16, v5
	v_sub_u32_e32 v9, v4, v2
	v_mul_lo_u32 v2, v8, s23
	v_lshl_add_u32 v2, v9, 4, v2
	ds_read_b128 v[2:5], v2
	s_lshl_b32 s94, s5, 8
	v_lshlrev_b32_e32 v8, 3, v9
	v_lshl_add_u64 v[6:7], v[6:7], 0, s[94:95]
	v_ashrrev_i32_e32 v9, 31, v8
	v_lshl_add_u64 v[6:7], v[8:9], 1, v[6:7]
	s_waitcnt lgkmcnt(0)
	global_store_dwordx4 v[6:7], v[2:5], off
	s_nop 1
	v_mov_b64_e32 v[2:3], s[40:41]
	global_load_dwordx2 v[2:3], v[2:3], off offset:336
.LBB0_596:
	s_or_b64 exec, exec, s[0:1]
	v_mov_b64_e32 v[4:5], 0
	s_waitcnt vmcnt(0) lgkmcnt(0)
	v_cmp_ne_u64_e32 vcc, 0, v[2:3]
	s_and_saveexec_b64 s[0:1], vcc
	s_cbranch_execz .LBB0_598
	v_add_u32_e32 v8, 0x600, v0
	v_ashrrev_i32_e32 v4, 31, v8
	v_lshrrev_b32_e32 v4, 28, v4
	v_add_u32_e32 v9, v8, v4
	v_ashrrev_i32_e32 v10, 4, v9
	v_add_u32_e32 v4, s4, v10
	v_ashrrev_i32_e32 v5, 31, v4
	v_lshlrev_b64 v[4:5], 10, v[4:5]
	v_lshl_add_u64 v[6:7], v[2:3], 0, v[4:5]
	v_and_b32_e32 v2, -16, v9
	v_sub_u32_e32 v8, v8, v2
	v_mul_lo_u32 v2, v10, s23
	v_lshl_add_u32 v2, v8, 4, v2
	ds_read_b128 v[2:5], v2
	s_lshl_b32 s94, s5, 8
	v_lshlrev_b32_e32 v8, 3, v8
	v_lshl_add_u64 v[6:7], v[6:7], 0, s[94:95]
	v_ashrrev_i32_e32 v9, 31, v8
	v_lshl_add_u64 v[6:7], v[8:9], 1, v[6:7]
	s_waitcnt lgkmcnt(0)
	global_store_dwordx4 v[6:7], v[2:5], off
	s_nop 1
	v_mov_b64_e32 v[2:3], s[40:41]
	global_load_dwordx2 v[4:5], v[2:3], off offset:336
.LBB0_598:
	s_or_b64 exec, exec, s[0:1]
	s_waitcnt vmcnt(0) lgkmcnt(0)
	v_cmp_ne_u64_e32 vcc, 0, v[4:5]
	s_and_saveexec_b64 s[0:1], vcc
	s_cbranch_execz .LBB0_571
	v_add_u32_e32 v0, 0x700, v0
	v_ashrrev_i32_e32 v2, 31, v0
	v_lshrrev_b32_e32 v2, 28, v2
	v_add_u32_e32 v8, v0, v2
	v_ashrrev_i32_e32 v9, 4, v8
	v_add_u32_e32 v2, s4, v9
	v_ashrrev_i32_e32 v3, 31, v2
	v_lshlrev_b64 v[2:3], 10, v[2:3]
	v_lshl_add_u64 v[6:7], v[4:5], 0, v[2:3]
	v_and_b32_e32 v2, -16, v8
	v_sub_u32_e32 v0, v0, v2
	v_mul_lo_u32 v2, v9, s23
	v_lshl_add_u32 v2, v0, 4, v2
	ds_read_b128 v[2:5], v2
	s_lshl_b32 s94, s5, 8
	v_lshlrev_b32_e32 v8, 3, v0
	v_lshl_add_u64 v[6:7], v[6:7], 0, s[94:95]
	v_ashrrev_i32_e32 v9, 31, v8
	v_lshl_add_u64 v[6:7], v[8:9], 1, v[6:7]
	s_waitcnt lgkmcnt(0)
	global_store_dwordx4 v[6:7], v[2:5], off
	s_branch .LBB0_571

; __device__ __forceinline__ void phase_mix_a(const Params& p, int l, bool last, unsigned char* smem) {
;     ...
;       gemm_tile<2, true>(p.Wsgu + (size_t)(l * 4 + h) * 16384, 128, nullptr, 128, p.PX + (size_t)row_base * 1024 + 256 + h * 64, 1024, 128, smem, epi, rsv);
.LBB0_602:
	s_or_b64 exec, exec, s[0:1]
	s_and_b32 s1, s9, 3
	s_or_b32 s34, s1, s18
	s_lshl_b32 s94, s34, 7
	v_lshl_add_u64 v[60:61], s[94:95], 2, v[6:7]
	s_waitcnt lgkmcnt(0)
	v_lshl_add_u64 v[2:3], s[4:5], 2, v[8:9]
	s_lshl_b32 s94, s1, 8
	v_mov_b64_e32 v[58:59], s[40:41]
	v_lshl_add_u64 v[62:63], v[2:3], 0, s[94:95]
	global_load_dwordx2 v[2:3], v[58:59], off offset:240
	global_load_dwordx2 v[4:5], v[58:59], off offset:288
	v_mov_b32_e32 v46, v187
	s_ashr_i32 s39, s38, 31
	v_ashrrev_i32_e32 v10, 31, v46
	v_lshrrev_b32_e32 v10, 29, v10
	v_add_u32_e32 v12, v46, v10
	v_ashrrev_i32_e32 v44, 3, v12
	s_lshl_b32 s94, s34, 15
	s_lshl_b64 s[34:35], s[38:39], 11
	v_ashrrev_i32_e32 v45, 31, v44
	v_and_b32_e32 v12, -8, v12
	v_lshlrev_b64 v[10:11], 11, v[44:45]
	v_sub_u32_e32 v45, v46, v12
	v_lshlrev_b32_e32 v42, 3, v45
	v_ashrrev_i32_e32 v43, 31, v42
	v_add_u32_e32 v12, 0x100, v46
	v_lshlrev_b32_e32 v0, 3, v46
	v_and_b32_e32 v20, 56, v0
	v_lshlrev_b32_e32 v0, 1, v20
	s_waitcnt lgkmcnt(0)
	s_barrier
	s_lshl_b32 s0, s1, 6
	v_lshlrev_b32_e32 v67, 2, v20
	v_lshrrev_b32_e32 v47, 4, v46
	v_bfe_u32 v106, v46, 1, 3
	v_bfe_u32 v64, v46, 6, 1
	v_ashrrev_i32_e32 v65, 7, v46
	v_bfe_u32 v66, v46, 4, 2
	s_add_i32 s9, s9, s3
	s_waitcnt vmcnt(0)
	v_lshl_add_u64 v[2:3], v[2:3], 0, s[94:95]
	v_lshl_add_u64 v[4:5], v[4:5], 0, s[34:35]
	s_lshl_b32 s94, s1, 7
	v_lshl_add_u64 v[8:9], v[4:5], 0, s[94:95]
	v_lshl_add_u64 v[10:11], v[8:9], 0, v[10:11]
	v_lshl_add_u64 v[34:35], v[42:43], 1, v[10:11]
	v_ashrrev_i32_e32 v10, 31, v12
	v_lshrrev_b32_e32 v10, 29, v10
	v_add_u32_e32 v13, v12, v10
	v_ashrrev_i32_e32 v40, 3, v13
	v_ashrrev_i32_e32 v41, 31, v40
	v_lshlrev_b64 v[10:11], 11, v[40:41]
	v_ashrrev_i32_e32 v4, 3, v46
	v_lshl_add_u64 v[8:9], v[8:9], 0, v[10:11]
	v_and_b32_e32 v10, -8, v13
	v_ashrrev_i32_e32 v5, 31, v4
	v_sub_u32_e32 v41, v12, v10
	v_lshl_add_u64 v[2:3], v[2:3], 0, v[0:1]
	v_lshlrev_b64 v[4:5], 8, v[4:5]
	v_lshlrev_b32_e32 v38, 3, v41
	v_lshl_add_u64 v[2:3], v[2:3], 0, v[4:5]
	v_ashrrev_i32_e32 v39, 31, v38
	v_lshl_add_u64 v[36:37], v[38:39], 1, v[8:9]
	v_add_co_u32_e32 v8, vcc, s70, v2
	global_load_dwordx4 v[22:25], v[2:3], off
	s_nop 0
	v_addc_co_u32_e32 v9, vcc, 0, v3, vcc
	global_load_dwordx4 v[26:29], v[8:9], off
	v_add_co_u32_e32 v8, vcc, s69, v2
	s_movk_i32 s1, 0x6000
	s_nop 0
	v_addc_co_u32_e32 v9, vcc, 0, v3, vcc
	global_load_dwordx4 v[30:33], v[8:9], off
	s_mov_b64 s[34:35], 0x2000
	v_add_co_u32_e32 v8, vcc, s1, v2
	v_lshl_add_u64 v[4:5], v[2:3], 0, s[34:35]
	v_lshl_add_u64 v[6:7], v[2:3], 0, s[62:63]
	v_addc_co_u32_e32 v9, vcc, 0, v3, vcc
	v_lshl_add_u64 v[18:19], v[2:3], 0, s[24:25]
	global_load_dwordx4 v[48:51], v[8:9], off
	global_load_dwordx4 v[14:17], v[2:3], off offset:128
	global_load_dwordx4 v[10:13], v[4:5], off offset:128
	s_nop 0
	global_load_dwordx4 v[6:9], v[6:7], off offset:128
	s_nop 0
	global_load_dwordx4 v[2:5], v[18:19], off offset:128
	v_or_b32_e32 v18, 0x10200, v67
	ds_read_b128 v[52:55], v18
	v_or_b32_e32 v39, 0x10210, v67
	v_lshlrev_b32_e32 v43, 4, v46
	v_and_b32_e32 v43, 0xffffff80, v43
	v_and_b32_e32 v0, 15, v46
	s_waitcnt vmcnt(0) lgkmcnt(0)
	v_lshlrev_b32_e32 v18, 16, v22
	v_and_b32_e32 v19, 0xffff0000, v22
	v_pk_mul_f32 v[18:19], v[52:53], v[18:19]
	v_lshlrev_b32_e32 v20, 16, v26
	v_and_b32_e32 v21, 0xffff0000, v26
	v_pk_mul_f32 v[20:21], v[52:53], v[20:21]
	v_cvt_pk_bf16_f32 v18, v18, v19
	v_cvt_pk_bf16_f32 v22, v20, v21
	v_lshlrev_b32_e32 v20, 16, v30
	v_and_b32_e32 v21, 0xffff0000, v30
	v_pk_mul_f32 v[20:21], v[52:53], v[20:21]
	s_nop 0
	v_cvt_pk_bf16_f32 v26, v20, v21
	v_lshlrev_b32_e32 v20, 16, v48
	v_and_b32_e32 v21, 0xffff0000, v48
	v_pk_mul_f32 v[20:21], v[52:53], v[20:21]
	v_lshlrev_b32_e32 v48, 16, v28
	v_cvt_pk_bf16_f32 v30, v20, v21
	v_lshlrev_b32_e32 v20, 16, v23
	v_and_b32_e32 v21, 0xffff0000, v23
	v_pk_mul_f32 v[20:21], v[54:55], v[20:21]
	s_nop 0
	v_cvt_pk_bf16_f32 v19, v20, v21
	v_lshlrev_b32_e32 v20, 16, v27
	v_and_b32_e32 v21, 0xffff0000, v27
	v_pk_mul_f32 v[20:21], v[54:55], v[20:21]
	s_nop 0
	v_cvt_pk_bf16_f32 v23, v20, v21
	v_lshlrev_b32_e32 v20, 16, v31
	v_and_b32_e32 v21, 0xffff0000, v31
	v_pk_mul_f32 v[20:21], v[54:55], v[20:21]
	s_nop 0
	v_cvt_pk_bf16_f32 v27, v20, v21
	v_lshlrev_b32_e32 v20, 16, v49
	v_and_b32_e32 v21, 0xffff0000, v49
	v_pk_mul_f32 v[20:21], v[54:55], v[20:21]
	ds_read_b128 v[52:55], v39
	v_and_b32_e32 v49, 0xffff0000, v28
	v_cvt_pk_bf16_f32 v31, v20, v21
	v_lshlrev_b32_e32 v20, 16, v24
	v_and_b32_e32 v21, 0xffff0000, v24
	s_waitcnt lgkmcnt(0)
	v_pk_mul_f32 v[48:49], v[52:53], v[48:49]
	v_pk_mul_f32 v[20:21], v[52:53], v[20:21]
	v_cvt_pk_bf16_f32 v24, v48, v49
	v_lshlrev_b32_e32 v48, 16, v32
	v_and_b32_e32 v49, 0xffff0000, v32
	v_pk_mul_f32 v[48:49], v[52:53], v[48:49]
	v_cvt_pk_bf16_f32 v20, v20, v21
	v_cvt_pk_bf16_f32 v28, v48, v49
	v_lshlrev_b32_e32 v48, 16, v50
	v_and_b32_e32 v49, 0xffff0000, v50
	v_pk_mul_f32 v[48:49], v[52:53], v[48:49]
	v_xor_b32_e32 v39, v47, v46
	v_cvt_pk_bf16_f32 v32, v48, v49
	v_lshlrev_b32_e32 v48, 16, v25
	v_and_b32_e32 v49, 0xffff0000, v25
	v_pk_mul_f32 v[48:49], v[54:55], v[48:49]
	v_lshlrev_b32_e32 v39, 4, v39
	v_cvt_pk_bf16_f32 v21, v48, v49
	v_lshlrev_b32_e32 v48, 16, v29
	v_and_b32_e32 v49, 0xffff0000, v29
	v_pk_mul_f32 v[48:49], v[54:55], v[48:49]
	v_and_or_b32 v68, v39, s14, v43
	v_cvt_pk_bf16_f32 v25, v48, v49
	v_lshlrev_b32_e32 v48, 16, v33
	v_and_b32_e32 v49, 0xffff0000, v33
	v_pk_mul_f32 v[48:49], v[54:55], v[48:49]
	v_lshlrev_b32_e32 v43, 7, v0
	v_cvt_pk_bf16_f32 v29, v48, v49
	v_lshlrev_b32_e32 v48, 16, v51
	v_and_b32_e32 v49, 0xffff0000, v51
	v_pk_mul_f32 v[48:49], v[54:55], v[48:49]
	v_lshl_or_b32 v107, v65, 13, v43
	v_cvt_pk_bf16_f32 v33, v48, v49
	ds_write_b128 v68, v[18:21]
	ds_write_b128 v68, v[22:25] offset:4096
	ds_write_b128 v68, v[26:29] offset:8192
	ds_write_b128 v68, v[30:33] offset:12288
	v_and_b32_e32 v22, -8, v44
	v_lshlrev_b32_e32 v18, 5, v45
	v_lshlrev_b32_e32 v24, 9, v45
	v_bitop3_b32 v25, v18, v22, 32 bitop3:0x6c
	v_and_b32_e32 v23, 7, v44
	v_add_u32_e32 v18, v25, v24
	v_or_b32_e32 v18, v18, v23
	v_lshlrev_b32_e32 v69, 1, v18
	global_load_dwordx4 v[18:21], v[34:35], off offset:512
	v_or_b32_e32 v24, v23, v24
	v_add_lshl_u32 v70, v24, v25, 1
	v_bitop3_b32 v26, v47, v106, 3 bitop3:0x6c
	v_lshl_or_b32 v110, v64, 12, v43
	v_lshlrev_b32_e32 v0, 2, v0
	v_lshl_or_b32 v0, v64, 7, v0
	s_waitcnt vmcnt(0) lgkmcnt(0)
	ds_write_b16 v69, v18 offset:16384
	ds_write_b16_d16_hi v70, v18 offset:16512
	v_or_b32_e32 v18, 2, v42
	v_lshlrev_b32_e32 v24, 6, v18
	v_lshlrev_b32_e32 v18, 2, v18
	v_and_b32_e32 v18, 40, v18
	v_xad_u32 v18, v18, v22, v24
	v_or_b32_e32 v18, v18, v23
	v_lshlrev_b32_e32 v71, 1, v18
	v_or_b32_e32 v18, 3, v42
	v_lshlrev_b32_e32 v24, 6, v18
	v_lshlrev_b32_e32 v18, 2, v18
	v_and_b32_e32 v18, 40, v18
	v_xad_u32 v18, v18, v22, v24
	v_or_b32_e32 v18, v18, v23
	v_lshlrev_b32_e32 v72, 1, v18
	v_or_b32_e32 v18, 4, v42
	ds_write_b16 v71, v19 offset:16384
	ds_write_b16_d16_hi v72, v19 offset:16384
	v_lshlrev_b32_e32 v19, 6, v18
	v_lshlrev_b32_e32 v18, 2, v18
	v_and_b32_e32 v18, 48, v18
	v_xad_u32 v18, v18, v22, v19
	v_or_b32_e32 v18, v18, v23
	v_lshlrev_b32_e32 v73, 1, v18
	v_or_b32_e32 v18, 5, v42
	v_lshlrev_b32_e32 v19, 6, v18
	v_lshlrev_b32_e32 v18, 2, v18
	v_and_b32_e32 v18, 48, v18
	v_xad_u32 v18, v18, v22, v19
	v_or_b32_e32 v18, v18, v23
	v_lshlrev_b32_e32 v74, 1, v18
	v_or_b32_e32 v18, 6, v42
	v_lshlrev_b32_e32 v19, 6, v18
	v_lshlrev_b32_e32 v18, 2, v18
	v_and_b32_e32 v18, 56, v18
	v_xad_u32 v18, v18, v22, v19
	v_or_b32_e32 v18, v18, v23
	v_lshlrev_b32_e32 v75, 1, v18
	v_or_b32_e32 v18, 7, v42
	v_lshlrev_b32_e32 v19, 6, v18
	v_lshlrev_b32_e32 v18, 2, v18
	v_and_b32_e32 v18, 56, v18
	v_xad_u32 v18, v18, v22, v19
	v_or_b32_e32 v18, v18, v23
	v_lshlrev_b32_e32 v76, 1, v18
	v_and_b32_e32 v22, -8, v40
	v_lshlrev_b32_e32 v18, 5, v41
	v_lshlrev_b32_e32 v24, 9, v41
	v_bitop3_b32 v25, v18, v22, 32 bitop3:0x6c
	v_and_b32_e32 v23, 7, v40
	v_add_u32_e32 v18, v25, v24
	v_or_b32_e32 v18, v18, v23
	ds_write_b16 v73, v20 offset:16384
	ds_write_b16_d16_hi v74, v20 offset:16384
	ds_write_b16 v75, v21 offset:16384
	ds_write_b16_d16_hi v76, v21 offset:16384
	v_lshlrev_b32_e32 v77, 1, v18
	global_load_dwordx4 v[18:21], v[36:37], off offset:512
	v_or_b32_e32 v24, v23, v24
	v_add_lshl_u32 v78, v24, v25, 1
	v_lshlrev_b32_e32 v42, 4, v26
	v_or_b32_e32 v121, v42, v107
	v_or_b32_e32 v122, v42, v110
	s_waitcnt vmcnt(0) lgkmcnt(0)
	ds_write_b16 v77, v18 offset:16384
	ds_write_b16_d16_hi v78, v18 offset:16512
	v_or_b32_e32 v18, 2, v38
	v_lshlrev_b32_e32 v24, 6, v18
	v_lshlrev_b32_e32 v18, 2, v18
	v_and_b32_e32 v18, 40, v18
	v_xad_u32 v18, v18, v22, v24
	v_or_b32_e32 v18, v18, v23
	v_lshlrev_b32_e32 v79, 1, v18
	v_or_b32_e32 v18, 3, v38
	v_lshlrev_b32_e32 v24, 6, v18
	v_lshlrev_b32_e32 v18, 2, v18
	v_and_b32_e32 v18, 40, v18
	v_xad_u32 v18, v18, v22, v24
	v_or_b32_e32 v18, v18, v23
	v_lshlrev_b32_e32 v80, 1, v18
	v_or_b32_e32 v18, 4, v38
	ds_write_b16 v79, v19 offset:16384
	ds_write_b16_d16_hi v80, v19 offset:16384
	v_lshlrev_b32_e32 v19, 6, v18
	v_lshlrev_b32_e32 v18, 2, v18
	v_and_b32_e32 v18, 48, v18
	v_xad_u32 v18, v18, v22, v19
	v_or_b32_e32 v18, v18, v23
	v_lshlrev_b32_e32 v81, 1, v18
	v_or_b32_e32 v18, 5, v38
	v_lshlrev_b32_e32 v19, 6, v18
	v_lshlrev_b32_e32 v18, 2, v18
	v_and_b32_e32 v18, 48, v18
	v_xad_u32 v18, v18, v22, v19
	v_or_b32_e32 v18, v18, v23
	v_lshlrev_b32_e32 v118, 1, v18
	v_or_b32_e32 v18, 6, v38
	v_lshlrev_b32_e32 v19, 6, v18
	v_lshlrev_b32_e32 v18, 2, v18
	v_and_b32_e32 v18, 56, v18
	v_xad_u32 v18, v18, v22, v19
	v_or_b32_e32 v18, v18, v23
	v_lshlrev_b32_e32 v119, 1, v18
	v_or_b32_e32 v18, 7, v38
	v_lshlrev_b32_e32 v19, 6, v18
	v_lshlrev_b32_e32 v18, 2, v18
	v_and_b32_e32 v18, 56, v18
	v_xad_u32 v18, v18, v22, v19
	v_or_b32_e32 v18, v18, v23
	v_lshlrev_b32_e32 v120, 1, v18
	v_add_co_u32_e32 v18, vcc, s16, v34
	ds_write_b16 v81, v20 offset:16384
	s_nop 0
	v_addc_co_u32_e32 v19, vcc, 0, v35, vcc
	ds_write_b16_d16_hi v118, v20 offset:16384
	ds_write_b16 v119, v21 offset:16384
	ds_write_b16_d16_hi v120, v21 offset:16384
	global_load_dwordx4 v[18:21], v[18:19], off offset:512
	v_add_co_u32_e32 v22, vcc, s16, v36
	s_nop 1
	v_addc_co_u32_e32 v23, vcc, 0, v37, vcc
	global_load_dwordx4 v[22:25], v[22:23], off offset:512
	s_waitcnt lgkmcnt(0)
	s_barrier
	ds_read_b128 v[26:29], v121
	ds_read_b128 v[30:33], v121 offset:2048
	ds_read_b128 v[34:37], v121 offset:4096
	ds_read_b128 v[38:41], v121 offset:6144
	ds_read_b128 v[42:45], v122 offset:16384
	ds_read_b128 v[46:49], v122 offset:18432
	s_waitcnt lgkmcnt(0)
	v_mfma_f32_16x16x32_bf16 v[50:53], v[26:29], v[42:45], 0
	v_mfma_f32_16x16x32_bf16 v[54:57], v[26:29], v[46:49], 0
	v_bitop3_b32 v26, v66, v106, 4 bitop3:0x36
	v_lshlrev_b32_e32 v26, 4, v26
	v_or_b32_e32 v123, v26, v107
	v_or_b32_e32 v124, v26, v110
	v_mfma_f32_16x16x32_bf16 v[82:85], v[30:33], v[42:45], 0
	v_mfma_f32_16x16x32_bf16 v[86:89], v[30:33], v[46:49], 0
	v_mfma_f32_16x16x32_bf16 v[94:97], v[34:37], v[46:49], 0
	v_mfma_f32_16x16x32_bf16 v[98:101], v[38:41], v[42:45], 0
	v_mfma_f32_16x16x32_bf16 v[102:105], v[38:41], v[46:49], 0
	ds_read_b128 v[30:33], v123
	ds_read_b128 v[38:41], v123 offset:2048
	ds_read_b128 v[46:49], v123 offset:4096
	ds_read_b128 v[106:109], v123 offset:6144
	ds_read_b128 v[110:113], v124 offset:16384
	ds_read_b128 v[114:117], v124 offset:18432
	v_mfma_f32_16x16x32_bf16 v[90:93], v[34:37], v[42:45], 0
	s_waitcnt lgkmcnt(0)
	v_mfma_f32_16x16x32_bf16 v[34:37], v[38:41], v[110:113], v[82:85]
	s_nop 2
	v_or_b32_e32 v82, 0x10300, v67
	ds_read_b128 v[82:85], v82
	v_mfma_f32_16x16x32_bf16 v[38:41], v[38:41], v[114:117], v[86:89]
	v_or_b32_e32 v67, 0x10310, v67
	s_nop 1
	v_lshlrev_b32_e32 v86, 16, v14
	v_and_b32_e32 v87, 0xffff0000, v14
	s_waitcnt lgkmcnt(0)
	v_pk_mul_f32 v[86:87], v[82:83], v[86:87]
	v_mfma_f32_16x16x32_bf16 v[26:29], v[30:33], v[110:113], v[50:53]
	v_cvt_pk_bf16_f32 v14, v86, v87
	v_lshlrev_b32_e32 v86, 16, v10
	v_and_b32_e32 v87, 0xffff0000, v10
	v_pk_mul_f32 v[86:87], v[82:83], v[86:87]
	v_mfma_f32_16x16x32_bf16 v[30:33], v[30:33], v[114:117], v[54:57]
	v_cvt_pk_bf16_f32 v10, v86, v87
	v_lshlrev_b32_e32 v86, 16, v6
	v_and_b32_e32 v87, 0xffff0000, v6
	v_pk_mul_f32 v[86:87], v[82:83], v[86:87]
	v_mfma_f32_16x16x32_bf16 v[42:45], v[46:49], v[110:113], v[90:93]
	v_cvt_pk_bf16_f32 v6, v86, v87
	v_lshlrev_b32_e32 v86, 16, v2
	v_and_b32_e32 v87, 0xffff0000, v2
	v_pk_mul_f32 v[82:83], v[82:83], v[86:87]
	v_lshlrev_b32_e32 v86, 16, v16
	v_cvt_pk_bf16_f32 v2, v82, v83
	v_lshlrev_b32_e32 v82, 16, v15
	v_and_b32_e32 v83, 0xffff0000, v15
	v_pk_mul_f32 v[82:83], v[84:85], v[82:83]
	v_and_b32_e32 v87, 0xffff0000, v16
	v_cvt_pk_bf16_f32 v15, v82, v83
	v_lshlrev_b32_e32 v82, 16, v11
	v_and_b32_e32 v83, 0xffff0000, v11
	v_pk_mul_f32 v[82:83], v[84:85], v[82:83]
	v_mfma_f32_16x16x32_bf16 v[46:49], v[46:49], v[114:117], v[94:97]
	v_cvt_pk_bf16_f32 v11, v82, v83
	v_lshlrev_b32_e32 v82, 16, v7
	v_and_b32_e32 v83, 0xffff0000, v7
	v_pk_mul_f32 v[82:83], v[84:85], v[82:83]
	v_mfma_f32_16x16x32_bf16 v[50:53], v[106:109], v[110:113], v[98:101]
	v_cvt_pk_bf16_f32 v7, v82, v83
	v_lshlrev_b32_e32 v82, 16, v3
	v_and_b32_e32 v83, 0xffff0000, v3
	v_pk_mul_f32 v[82:83], v[84:85], v[82:83]
	v_mfma_f32_16x16x32_bf16 v[54:57], v[106:109], v[114:117], v[102:105]
	v_cvt_pk_bf16_f32 v3, v82, v83
	ds_read_b128 v[82:85], v67
	s_waitcnt lgkmcnt(0)
	v_pk_mul_f32 v[86:87], v[82:83], v[86:87]
	s_nop 0
	v_cvt_pk_bf16_f32 v16, v86, v87
	v_lshlrev_b32_e32 v86, 16, v12
	v_and_b32_e32 v87, 0xffff0000, v12
	v_pk_mul_f32 v[86:87], v[82:83], v[86:87]
	s_nop 0
	v_cvt_pk_bf16_f32 v12, v86, v87
	v_lshlrev_b32_e32 v86, 16, v8
	v_and_b32_e32 v87, 0xffff0000, v8
	v_pk_mul_f32 v[86:87], v[82:83], v[86:87]
	s_nop 0
	v_cvt_pk_bf16_f32 v8, v86, v87
	v_lshlrev_b32_e32 v86, 16, v4
	v_and_b32_e32 v87, 0xffff0000, v4
	v_pk_mul_f32 v[82:83], v[82:83], v[86:87]
	s_nop 0
	v_cvt_pk_bf16_f32 v4, v82, v83
	v_lshlrev_b32_e32 v82, 16, v17
	v_and_b32_e32 v83, 0xffff0000, v17
	v_pk_mul_f32 v[82:83], v[84:85], v[82:83]
	s_nop 0
	v_cvt_pk_bf16_f32 v17, v82, v83
	v_lshlrev_b32_e32 v82, 16, v13
	v_and_b32_e32 v83, 0xffff0000, v13
	v_pk_mul_f32 v[82:83], v[84:85], v[82:83]
	s_nop 0
	v_cvt_pk_bf16_f32 v13, v82, v83
	v_lshlrev_b32_e32 v82, 16, v9
	v_and_b32_e32 v83, 0xffff0000, v9
	v_pk_mul_f32 v[82:83], v[84:85], v[82:83]
	s_nop 0
	v_cvt_pk_bf16_f32 v9, v82, v83
	v_lshlrev_b32_e32 v82, 16, v5
	v_and_b32_e32 v83, 0xffff0000, v5
	v_pk_mul_f32 v[82:83], v[84:85], v[82:83]
	s_nop 0
	v_cvt_pk_bf16_f32 v5, v82, v83
	ds_write_b128 v68, v[14:17] offset:32768
	ds_write_b128 v68, v[10:13] offset:36864
	ds_write_b128 v68, v[6:9] offset:40960
	ds_write_b128 v68, v[2:5] offset:45056
	s_waitcnt vmcnt(0)
	ds_write_b16 v69, v18 offset:49152
	ds_write_b16_d16_hi v70, v18 offset:49280
	ds_write_b16 v71, v19 offset:49152
	ds_write_b16_d16_hi v72, v19 offset:49152
	ds_write_b16 v73, v20 offset:49152
	ds_write_b16_d16_hi v74, v20 offset:49152
	ds_write_b16 v75, v21 offset:49152
	ds_write_b16_d16_hi v76, v21 offset:49152
	ds_write_b16 v77, v22 offset:49152
	ds_write_b16_d16_hi v78, v22 offset:49280
	ds_write_b16 v79, v23 offset:49152
	ds_write_b16_d16_hi v80, v23 offset:49152
	ds_write_b16 v81, v24 offset:49152
	ds_write_b16_d16_hi v118, v24 offset:49152
	ds_write_b16 v119, v25 offset:49152
	ds_write_b16_d16_hi v120, v25 offset:49152
	s_waitcnt lgkmcnt(0)
	s_barrier
	ds_read_b128 v[2:5], v121 offset:32768
	ds_read_b128 v[6:9], v121 offset:34816
	ds_read_b128 v[10:13], v121 offset:36864
	ds_read_b128 v[14:17], v121 offset:38912
	ds_read_b128 v[18:21], v122 offset:49152
	ds_read_b128 v[22:25], v122 offset:51200
	s_waitcnt lgkmcnt(1)
	v_mfma_f32_16x16x32_bf16 v[26:29], v[2:5], v[18:21], v[26:29]
	s_waitcnt lgkmcnt(0)
	v_mfma_f32_16x16x32_bf16 v[2:5], v[2:5], v[22:25], v[30:33]
	v_mfma_f32_16x16x32_bf16 v[30:33], v[6:9], v[18:21], v[34:37]
	v_mfma_f32_16x16x32_bf16 v[6:9], v[6:9], v[22:25], v[38:41]
	v_mfma_f32_16x16x32_bf16 v[34:37], v[10:13], v[18:21], v[42:45]
	v_mfma_f32_16x16x32_bf16 v[10:13], v[10:13], v[22:25], v[46:49]
	v_mfma_f32_16x16x32_bf16 v[18:21], v[14:17], v[18:21], v[50:53]
	v_mfma_f32_16x16x32_bf16 v[14:17], v[14:17], v[22:25], v[54:57]
	ds_read_b128 v[22:25], v123 offset:32768
	ds_read_b128 v[38:41], v123 offset:34816
	ds_read_b128 v[42:45], v123 offset:36864
	ds_read_b128 v[46:49], v123 offset:38912
	ds_read_b128 v[50:53], v124 offset:49152
	ds_read_b128 v[54:57], v124 offset:51200
	s_waitcnt lgkmcnt(1)
	v_mfma_f32_16x16x32_bf16 v[26:29], v[22:25], v[50:53], v[26:29]
	s_waitcnt lgkmcnt(0)
	v_mfma_f32_16x16x32_bf16 v[22:25], v[22:25], v[54:57], v[2:5]
	v_mfma_f32_16x16x32_bf16 v[2:5], v[46:49], v[54:57], v[14:17]
	s_nop 2
	v_lshlrev_b32_e32 v14, 6, v65
	v_mfma_f32_16x16x32_bf16 v[30:33], v[38:41], v[50:53], v[30:33]
	v_mfma_f32_16x16x32_bf16 v[38:41], v[38:41], v[54:57], v[6:9]
	v_mfma_f32_16x16x32_bf16 v[6:9], v[46:49], v[50:53], v[18:21]
	s_nop 2
	v_lshl_or_b32 v18, v66, 2, v14
	v_ashrrev_i32_e32 v19, 31, v18
	v_mov_b32_e32 v20, v187
	v_lshl_add_u64 v[14:15], v[62:63], 0, v[0:1]
	v_lshl_add_u64 v[16:17], v[18:19], 2, v[60:61]
	s_barrier
; __device__ __forceinline__ int tid_() { int t = threadIdx.x; asm volatile("" : "+v"(t)); return t; }
; __device__ __forceinline__ void phase_mix_a(const Params& p, int l, bool last, unsigned char* smem) {
;     ...
;       auto epi = [&](f32x4(&acc)[4][2], int r0, int c0) {
;         float* Ts = (float*)smem;
;         const int t2 = tid_();
;         __syncthreads();
; #pragma unroll
;         for (int mi = 0; mi < 4; ++mi)
; #pragma unroll
;           for (int ni = 0; ni < 2; ++ni)
; #pragma unroll
;             for (int j = 0; j < 4; ++j) {
;               const int pr = r0 + mi * 16 + j;
;               Ts[pr * 68 + c0 + ni * 16] = acc[mi][ni][j] * sgn[c0 + ni * 16] + bs[pr];
;             }
;         __syncthreads();
	global_load_dword v21, v[14:15], off
	global_load_dword v19, v[16:17], off
	v_mfma_f32_16x16x32_bf16 v[34:37], v[42:45], v[50:53], v[34:37]
	s_waitcnt vmcnt(0) lgkmcnt(0)
	v_fmac_f32_e32 v19, v26, v21
	v_mfma_f32_16x16x32_bf16 v[10:13], v[42:45], v[54:57], v[10:13]
	v_mad_u64_u32 v[42:43], s[34:35], v18, s23, v[0:1]
	ds_write_b32 v42, v19
	global_load_dword v19, v[14:15], off
	global_load_dword v21, v[16:17], off offset:4
	v_or_b32_e32 v18, 1, v18
	s_waitcnt vmcnt(0) lgkmcnt(0)
	v_fmac_f32_e32 v21, v27, v19
	v_mad_u64_u32 v[18:19], s[34:35], v18, s23, v[0:1]
	ds_write_b32 v18, v21
	global_load_dword v0, v[14:15], off
	global_load_dword v19, v[16:17], off offset:8
	s_waitcnt vmcnt(0) lgkmcnt(0)
	v_fmac_f32_e32 v19, v28, v0
	ds_write_b32 v18, v19 offset:272
	global_load_dword v0, v[14:15], off
	global_load_dword v19, v[16:17], off offset:12
	s_waitcnt vmcnt(0) lgkmcnt(0)
	v_fmac_f32_e32 v19, v29, v0
	ds_write_b32 v18, v19 offset:544
	global_load_dword v0, v[14:15], off offset:64
	global_load_dword v19, v[16:17], off
	s_waitcnt vmcnt(0) lgkmcnt(0)
	v_fmac_f32_e32 v19, v22, v0
	ds_write_b32 v42, v19 offset:64
	global_load_dword v0, v[14:15], off offset:64
	global_load_dword v19, v[16:17], off offset:4
	s_waitcnt vmcnt(0) lgkmcnt(0)
	v_fmac_f32_e32 v19, v23, v0
	ds_write_b32 v18, v19 offset:64
	global_load_dword v0, v[14:15], off offset:64
	global_load_dword v19, v[16:17], off offset:8
	s_waitcnt vmcnt(0) lgkmcnt(0)
	v_fmac_f32_e32 v19, v24, v0
	ds_write_b32 v18, v19 offset:336
	global_load_dword v0, v[14:15], off offset:64
	global_load_dword v19, v[16:17], off offset:12
	s_waitcnt vmcnt(0) lgkmcnt(0)
	v_fmac_f32_e32 v19, v25, v0
	ds_write_b32 v18, v19 offset:608
	global_load_dword v0, v[14:15], off
	global_load_dword v19, v[16:17], off offset:64
	s_waitcnt vmcnt(0) lgkmcnt(0)
	v_fmac_f32_e32 v19, v30, v0
	ds_write_b32 v18, v19 offset:4080
	global_load_dword v0, v[14:15], off
	global_load_dword v19, v[16:17], off offset:68
	s_waitcnt vmcnt(0) lgkmcnt(0)
	v_fmac_f32_e32 v19, v31, v0
	ds_write_b32 v18, v19 offset:4352
	global_load_dword v0, v[14:15], off
	global_load_dword v19, v[16:17], off offset:72
	s_waitcnt vmcnt(0) lgkmcnt(0)
	v_fmac_f32_e32 v19, v32, v0
	ds_write_b32 v18, v19 offset:4624
	global_load_dword v0, v[14:15], off
	global_load_dword v19, v[16:17], off offset:76
	s_waitcnt vmcnt(0) lgkmcnt(0)
	v_fmac_f32_e32 v19, v33, v0
	ds_write_b32 v18, v19 offset:4896
	global_load_dword v0, v[14:15], off offset:64
	global_load_dword v19, v[16:17], off offset:64
	s_waitcnt vmcnt(0) lgkmcnt(0)
	v_fmac_f32_e32 v19, v38, v0
	ds_write_b32 v18, v19 offset:4144
	global_load_dword v0, v[14:15], off offset:64
	global_load_dword v19, v[16:17], off offset:68
	s_waitcnt vmcnt(0) lgkmcnt(0)
	v_fmac_f32_e32 v19, v39, v0
	ds_write_b32 v18, v19 offset:4416
	global_load_dword v0, v[14:15], off offset:64
	global_load_dword v19, v[16:17], off offset:72
	s_waitcnt vmcnt(0) lgkmcnt(0)
	v_fmac_f32_e32 v19, v40, v0
	ds_write_b32 v18, v19 offset:4688
	global_load_dword v0, v[14:15], off offset:64
	global_load_dword v19, v[16:17], off offset:76
	s_waitcnt vmcnt(0) lgkmcnt(0)
	v_fmac_f32_e32 v19, v41, v0
	ds_write_b32 v18, v19 offset:4960
	global_load_dword v0, v[14:15], off
	global_load_dword v19, v[16:17], off offset:128
	s_waitcnt vmcnt(0) lgkmcnt(0)
	v_fmac_f32_e32 v19, v34, v0
	ds_write_b32 v18, v19 offset:8432
	global_load_dword v0, v[14:15], off
	global_load_dword v19, v[16:17], off offset:132
	s_waitcnt vmcnt(0) lgkmcnt(0)
	v_fmac_f32_e32 v19, v35, v0
	ds_write_b32 v18, v19 offset:8704
	global_load_dword v0, v[14:15], off
	global_load_dword v19, v[16:17], off offset:136
	s_waitcnt vmcnt(0) lgkmcnt(0)
	v_fmac_f32_e32 v19, v36, v0
	ds_write_b32 v18, v19 offset:8976
	global_load_dword v0, v[14:15], off
	global_load_dword v19, v[16:17], off offset:140
	s_waitcnt vmcnt(0) lgkmcnt(0)
	v_fmac_f32_e32 v19, v37, v0
	ds_write_b32 v18, v19 offset:9248
	global_load_dword v0, v[14:15], off offset:64
	global_load_dword v19, v[16:17], off offset:128
	s_waitcnt vmcnt(0) lgkmcnt(0)
	v_fmac_f32_e32 v19, v10, v0
	ds_write_b32 v18, v19 offset:8496
	global_load_dword v0, v[14:15], off offset:64
	global_load_dword v10, v[16:17], off offset:132
	s_waitcnt vmcnt(0) lgkmcnt(0)
	v_fmac_f32_e32 v10, v11, v0
	ds_write_b32 v18, v10 offset:8768
	global_load_dword v0, v[14:15], off offset:64
	global_load_dword v10, v[16:17], off offset:136
	s_waitcnt vmcnt(0) lgkmcnt(0)
	v_fmac_f32_e32 v10, v12, v0
	ds_write_b32 v18, v10 offset:9040
	global_load_dword v0, v[14:15], off offset:64
	global_load_dword v10, v[16:17], off offset:140
	s_waitcnt vmcnt(0) lgkmcnt(0)
	v_fmac_f32_e32 v10, v13, v0
	ds_write_b32 v18, v10 offset:9312
	global_load_dword v0, v[14:15], off
	global_load_dword v10, v[16:17], off offset:192
	s_waitcnt vmcnt(0) lgkmcnt(0)
	v_fmac_f32_e32 v10, v6, v0
	ds_write_b32 v18, v10 offset:12784
	global_load_dword v0, v[14:15], off
	global_load_dword v6, v[16:17], off offset:196
	s_waitcnt vmcnt(0) lgkmcnt(0)
	v_fmac_f32_e32 v6, v7, v0
	ds_write_b32 v18, v6 offset:13056
	global_load_dword v0, v[14:15], off
	global_load_dword v6, v[16:17], off offset:200
	s_waitcnt vmcnt(0) lgkmcnt(0)
	v_fmac_f32_e32 v6, v8, v0
	ds_write_b32 v18, v6 offset:13328
	global_load_dword v0, v[14:15], off
	global_load_dword v6, v[16:17], off offset:204
	s_waitcnt vmcnt(0) lgkmcnt(0)
	v_fmac_f32_e32 v6, v9, v0
	ds_write_b32 v18, v6 offset:13600
	global_load_dword v0, v[14:15], off offset:64
	global_load_dword v6, v[16:17], off offset:192
	s_waitcnt vmcnt(0) lgkmcnt(0)
	v_fmac_f32_e32 v6, v2, v0
	ds_write_b32 v18, v6 offset:12848
	global_load_dword v0, v[14:15], off offset:64
	global_load_dword v2, v[16:17], off offset:196
	s_waitcnt vmcnt(0) lgkmcnt(0)
	v_fmac_f32_e32 v2, v3, v0
	ds_write_b32 v18, v2 offset:13120
	global_load_dword v0, v[14:15], off offset:64
	global_load_dword v2, v[16:17], off offset:200
	v_ashrrev_i32_e32 v3, 3, v20
	s_waitcnt vmcnt(0) lgkmcnt(0)
	v_fmac_f32_e32 v2, v4, v0
	ds_write_b32 v18, v2 offset:13392
	global_load_dword v0, v[14:15], off offset:64
	global_load_dword v2, v[16:17], off offset:204
	v_add_u32_e32 v4, s38, v3
	s_waitcnt vmcnt(0) lgkmcnt(0)
	v_fmac_f32_e32 v2, v5, v0
	v_ashrrev_i32_e32 v5, 31, v4
	ds_write_b32 v18, v2 offset:13664
	s_waitcnt lgkmcnt(0)
	s_barrier
; __device__ __forceinline__ float bf2f(u16 b) { return __uint_as_float(((unsigned)b) << 16); }
; __device__ __forceinline__ void phase_mix_a(const Params& p, int l, bool last, unsigned char* smem) {
;     ...
; #pragma unroll
;         for (int i = 0; i < 4; ++i) {
;           const int c = t2 + 256 * i, pr = c >> 3, ch = c & 7;
;           const size_t o = (size_t)(row_base + pr) * 1024 + h * 64 + ch * 8;
;           const u32x4 u = *(const u32x4*)(p.PX + o);
;           const float4 z0 = *(const float4*)(Ts + pr * 68 + ch * 8), z1 = *(const float4*)(Ts + pr * 68 + ch * 8 + 4);
;           u32x4 r;
;           r.x = pack2(bf2f((u16)(u.x & 0xffffu)) * z0.x, bf2f((u16)(u.x >> 16)) * z0.y);
;           r.y = pack2(bf2f((u16)(u.y & 0xffffu)) * z0.z, bf2f((u16)(u.y >> 16)) * z0.w);
;           r.z = pack2(bf2f((u16)(u.z & 0xffffu)) * z1.x, bf2f((u16)(u.z >> 16)) * z1.y);
;           r.w = pack2(bf2f((u16)(u.w & 0xffffu)) * z1.z, bf2f((u16)(u.w >> 16)) * z1.w);
;           *(u32x4*)(p.YM + o) = r;
;         }
	v_lshlrev_b64 v[8:9], 10, v[4:5]
	global_load_dwordx4 v[4:7], v[58:59], off offset:288
	v_lshlrev_b32_e32 v0, 3, v20
	v_and_b32_e32 v2, 56, v0
	v_or3_b32 v8, v8, s0, v2
	v_lshlrev_b64 v[22:23], 1, v[8:9]
	v_lshlrev_b32_e32 v0, 2, v2
	s_waitcnt vmcnt(0) lgkmcnt(0)
	v_lshl_add_u64 v[4:5], v[4:5], 0, v[22:23]
	global_load_dwordx4 v[8:11], v[4:5], off
	v_mad_u64_u32 v[4:5], s[34:35], v3, s23, v[0:1]
	ds_read_b128 v[12:15], v4
	ds_read_b128 v[16:19], v4 offset:16
	v_add_u32_e32 v3, 0x100, v20
	v_ashrrev_i32_e32 v3, 3, v3
	s_waitcnt vmcnt(0) lgkmcnt(0)
	v_and_b32_e32 v5, 0xffff0000, v8
	v_lshlrev_b32_e32 v4, 16, v8
	v_pk_mul_f32 v[4:5], v[12:13], v[4:5]
	s_nop 0
	v_cvt_pk_bf16_f32 v8, v4, v5
	v_and_b32_e32 v5, 0xffff0000, v9
	v_lshlrev_b32_e32 v4, 16, v9
	v_pk_mul_f32 v[4:5], v[14:15], v[4:5]
	s_nop 0
	v_cvt_pk_bf16_f32 v9, v4, v5
	v_and_b32_e32 v5, 0xffff0000, v10
	v_lshlrev_b32_e32 v4, 16, v10
	v_pk_mul_f32 v[4:5], v[16:17], v[4:5]
	s_nop 0
	v_cvt_pk_bf16_f32 v10, v4, v5
	v_and_b32_e32 v5, 0xffff0000, v11
	v_lshlrev_b32_e32 v4, 16, v11
	v_pk_mul_f32 v[4:5], v[18:19], v[4:5]
	s_nop 0
	v_cvt_pk_bf16_f32 v11, v4, v5
	v_lshl_add_u64 v[4:5], v[6:7], 0, v[22:23]
	global_store_dwordx4 v[4:5], v[8:11], off
	v_add_u32_e32 v4, s38, v3
	v_ashrrev_i32_e32 v5, 31, v4
	v_lshlrev_b64 v[8:9], 10, v[4:5]
	global_load_dwordx4 v[4:7], v[58:59], off offset:288
	v_or3_b32 v8, v8, s0, v2
	v_lshlrev_b64 v[22:23], 1, v[8:9]
	s_waitcnt vmcnt(0) lgkmcnt(0)
	v_lshl_add_u64 v[4:5], v[4:5], 0, v[22:23]
	global_load_dwordx4 v[8:11], v[4:5], off
	v_mad_u64_u32 v[4:5], s[34:35], v3, s23, v[0:1]
	ds_read_b128 v[12:15], v4
	ds_read_b128 v[16:19], v4 offset:16
	v_add_u32_e32 v3, 0x200, v20
	v_ashrrev_i32_e32 v3, 3, v3
	s_waitcnt vmcnt(0) lgkmcnt(0)
	v_and_b32_e32 v5, 0xffff0000, v8
	v_lshlrev_b32_e32 v4, 16, v8
	v_pk_mul_f32 v[4:5], v[12:13], v[4:5]
	s_nop 0
	v_cvt_pk_bf16_f32 v8, v4, v5
	v_and_b32_e32 v5, 0xffff0000, v9
	v_lshlrev_b32_e32 v4, 16, v9
	v_pk_mul_f32 v[4:5], v[14:15], v[4:5]
	s_nop 0
	v_cvt_pk_bf16_f32 v9, v4, v5
	v_and_b32_e32 v5, 0xffff0000, v10
	v_lshlrev_b32_e32 v4, 16, v10
	v_pk_mul_f32 v[4:5], v[16:17], v[4:5]
	s_nop 0
	v_cvt_pk_bf16_f32 v10, v4, v5
	v_and_b32_e32 v5, 0xffff0000, v11
	v_lshlrev_b32_e32 v4, 16, v11
	v_pk_mul_f32 v[4:5], v[18:19], v[4:5]
	s_nop 0
	v_cvt_pk_bf16_f32 v11, v4, v5
	v_lshl_add_u64 v[4:5], v[6:7], 0, v[22:23]
	global_store_dwordx4 v[4:5], v[8:11], off
	v_add_u32_e32 v4, s38, v3
	v_ashrrev_i32_e32 v5, 31, v4
	v_lshlrev_b64 v[8:9], 10, v[4:5]
	global_load_dwordx4 v[4:7], v[58:59], off offset:288
	v_or3_b32 v8, v8, s0, v2
	v_lshlrev_b64 v[22:23], 1, v[8:9]
	s_waitcnt vmcnt(0) lgkmcnt(0)
	v_lshl_add_u64 v[4:5], v[4:5], 0, v[22:23]
	global_load_dwordx4 v[8:11], v[4:5], off
	v_mad_u64_u32 v[4:5], s[34:35], v3, s23, v[0:1]
	ds_read_b128 v[12:15], v4
	ds_read_b128 v[16:19], v4 offset:16
	v_add_u32_e32 v3, 0x300, v20
	s_waitcnt vmcnt(0) lgkmcnt(0)
	v_and_b32_e32 v5, 0xffff0000, v8
	v_lshlrev_b32_e32 v4, 16, v8
	v_pk_mul_f32 v[4:5], v[12:13], v[4:5]
	s_nop 0
	v_cvt_pk_bf16_f32 v8, v4, v5
	v_and_b32_e32 v5, 0xffff0000, v9
	v_lshlrev_b32_e32 v4, 16, v9
	v_pk_mul_f32 v[4:5], v[14:15], v[4:5]
	s_nop 0
	v_cvt_pk_bf16_f32 v9, v4, v5
	v_and_b32_e32 v5, 0xffff0000, v10
	v_lshlrev_b32_e32 v4, 16, v10
	v_pk_mul_f32 v[4:5], v[16:17], v[4:5]
	s_nop 0
	v_cvt_pk_bf16_f32 v10, v4, v5
	v_and_b32_e32 v5, 0xffff0000, v11
	v_lshlrev_b32_e32 v4, 16, v11
	v_pk_mul_f32 v[4:5], v[18:19], v[4:5]
	s_nop 0
	v_cvt_pk_bf16_f32 v11, v4, v5
	v_lshl_add_u64 v[4:5], v[6:7], 0, v[22:23]
	global_store_dwordx4 v[4:5], v[8:11], off
	s_nop 1
	v_ashrrev_i32_e32 v10, 3, v3
	v_add_u32_e32 v4, s38, v10
	v_ashrrev_i32_e32 v5, 31, v4
	v_lshlrev_b64 v[6:7], 10, v[4:5]
	v_or3_b32 v6, v6, s0, v2
	global_load_dwordx4 v[2:5], v[58:59], off offset:288
	v_lshlrev_b64 v[18:19], 1, v[6:7]
	s_waitcnt vmcnt(0) lgkmcnt(0)
	v_lshl_add_u64 v[2:3], v[2:3], 0, v[18:19]
	global_load_dwordx4 v[6:9], v[2:3], off
	v_mad_u64_u32 v[2:3], s[0:1], v10, s23, v[0:1]
	ds_read_b128 v[10:13], v2
	ds_read_b128 v[14:17], v2 offset:16
	v_readlane_b32 s0, v254, 45
	s_add_i32 s19, s19, s0
	s_cmp_ge_i32 s9, s8
	s_waitcnt vmcnt(0) lgkmcnt(0)
	v_and_b32_e32 v3, 0xffff0000, v6
	v_lshlrev_b32_e32 v2, 16, v6
	v_pk_mul_f32 v[2:3], v[10:11], v[2:3]
	s_nop 0
	v_cvt_pk_bf16_f32 v6, v2, v3
	v_and_b32_e32 v3, 0xffff0000, v7
	v_lshlrev_b32_e32 v2, 16, v7
	v_pk_mul_f32 v[2:3], v[12:13], v[2:3]
	s_nop 0
	v_cvt_pk_bf16_f32 v7, v2, v3
	v_and_b32_e32 v3, 0xffff0000, v8
	v_lshlrev_b32_e32 v2, 16, v8
	v_pk_mul_f32 v[2:3], v[14:15], v[2:3]
	s_nop 0
	v_cvt_pk_bf16_f32 v8, v2, v3
	v_and_b32_e32 v3, 0xffff0000, v9
	v_lshlrev_b32_e32 v2, 16, v9
	v_pk_mul_f32 v[2:3], v[16:17], v[2:3]
	s_nop 0
	v_cvt_pk_bf16_f32 v9, v2, v3
	v_lshl_add_u64 v[2:3], v[4:5], 0, v[18:19]
	global_store_dwordx4 v[2:3], v[6:9], off
	s_cbranch_scc1 .LBB0_605
; __device__ __forceinline__ int tid_() { int t = threadIdx.x; asm volatile("" : "+v"(t)); return t; }
; #define XCD_FOR(u, T)                                                                                         \
;   for (int _x = bid_() & 7, _gb = gridDim.x >> 3, _hi = (int)(((long)(_x + 1) * (T)) >> 3),                    \
;            u = (int)(((long)_x * (T)) >> 3) + (bid_() >> 3);                                                  \
;        u < _hi; u += _gb)
; __device__ __forceinline__ void phase_mix_a(const Params& p, int l, bool last, unsigned char* smem) {
;     ...
;     XCD_FOR(t, nch * 4) {
;       const int ch = t >> 2, h = t & 3, row_base = ch * 128;
;       const float* bs = p.b_sgu + (l * 4 + h) * 128;
;       const float* sgn = p.sgu_norm + l * 256 + h * 64;
;       float* rsv = (float*)(smem + 65536 + 512);
;       {
;         const int t3 = tid_(), q = t3 >> 1, half = t3 & 1;
;         const u16* vp = p.PX + (size_t)(row_base + q) * 1024 + 256 + half * 128;
;         float s = 0.f;
; #pragma unroll
;         for (int i = 0; i < 16; ++i) {
;           const u32x4 w = *(const u32x4*)(vp + i * 8);
;           const float a0 = __uint_as_float(w.x << 16), a1 = __uint_as_float(w.x & 0xffff0000u), a2 = __uint_as_float(w.y << 16), a3 = __uint_as_float(w.y & 0xffff0000u);
;           const float a4 = __uint_as_float(w.z << 16), a5 = __uint_as_float(w.z & 0xffff0000u), a6 = __uint_as_float(w.w << 16), a7 = __uint_as_float(w.w & 0xffff0000u);
;           s += (a0 * a0 + a1 * a1) + (a2 * a2 + a3 * a3) + (a4 * a4 + a5 * a5) + (a6 * a6 + a7 * a7);
;         }
.LBB0_603:
	s_waitcnt vmcnt(0) lgkmcnt(0)
	v_mov_b64_e32 v[2:3], s[40:41]
	v_mov_b32_e32 v0, v187
	global_load_dwordx2 v[6:7], v[2:3], off offset:72
	global_load_dwordx2 v[8:9], v[2:3], off offset:56
	global_load_dwordx2 v[2:3], v[2:3], off offset:288
	s_and_b32 s38, s19, 0xffffff80
	v_ashrrev_i32_e32 v10, 1, v0
	v_add_u32_e32 v4, s38, v10
	v_ashrrev_i32_e32 v5, 31, v4
	v_and_b32_e32 v11, 1, v0
	v_lshlrev_b64 v[4:5], 11, v[4:5]
	v_lshlrev_b32_e32 v0, 8, v11
	v_cmp_lt_i32_e32 vcc, v212, v227
	s_waitcnt vmcnt(0) lgkmcnt(0)
	v_lshl_add_u64 v[2:3], v[2:3], 0, v[4:5]
	v_lshl_add_u64 v[2:3], v[2:3], 0, v[0:1]
	global_load_dwordx4 v[12:15], v[2:3], off offset:512
	s_waitcnt vmcnt(0) lgkmcnt(0)
	v_and_b32_e32 v4, 0xffff0000, v12
	v_lshlrev_b32_e32 v0, 16, v12
	v_and_b32_e32 v12, 0xffff0000, v13
	v_mul_f32_e32 v4, v4, v4
	v_lshlrev_b32_e32 v5, 16, v13
	v_fmac_f32_e32 v4, v0, v0
	v_mul_f32_e32 v0, v12, v12
	v_lshlrev_b32_e32 v13, 16, v14
	v_and_b32_e32 v14, 0xffff0000, v14
	v_fmac_f32_e32 v0, v5, v5
	v_add_f32_e32 v0, v4, v0
	v_mul_f32_e32 v4, v14, v14
	v_lshlrev_b32_e32 v16, 16, v15
	v_and_b32_e32 v15, 0xffff0000, v15
	v_fmac_f32_e32 v4, v13, v13
	v_add_f32_e32 v0, v4, v0
	v_mul_f32_e32 v4, v15, v15
	global_load_dwordx4 v[12:15], v[2:3], off offset:528
	v_fmac_f32_e32 v4, v16, v16
	v_add_f32_e32 v0, v4, v0
	s_waitcnt vmcnt(0) lgkmcnt(0)
	v_and_b32_e32 v5, 0xffff0000, v12
	v_lshlrev_b32_e32 v4, 16, v12
	v_lshlrev_b32_e32 v12, 16, v13
	v_and_b32_e32 v13, 0xffff0000, v13
	v_mul_f32_e32 v5, v5, v5
	v_fmac_f32_e32 v5, v4, v4
	v_mul_f32_e32 v4, v13, v13
	v_lshlrev_b32_e32 v16, 16, v14
	v_and_b32_e32 v14, 0xffff0000, v14
	v_fmac_f32_e32 v4, v12, v12
	v_add_f32_e32 v4, v5, v4
	v_mul_f32_e32 v5, v14, v14
	v_lshlrev_b32_e32 v17, 16, v15
	v_and_b32_e32 v15, 0xffff0000, v15
	v_fmac_f32_e32 v5, v16, v16
	v_add_f32_e32 v4, v5, v4
	v_mul_f32_e32 v5, v15, v15
	global_load_dwordx4 v[12:15], v[2:3], off offset:544
	v_fmac_f32_e32 v5, v17, v17
	v_add_f32_e32 v4, v5, v4
	v_add_f32_e32 v0, v0, v4
	s_waitcnt vmcnt(0) lgkmcnt(0)
	v_and_b32_e32 v5, 0xffff0000, v12
	v_lshlrev_b32_e32 v4, 16, v12
	v_lshlrev_b32_e32 v12, 16, v13
	v_and_b32_e32 v13, 0xffff0000, v13
	v_mul_f32_e32 v5, v5, v5
	v_fmac_f32_e32 v5, v4, v4
	v_mul_f32_e32 v4, v13, v13
	v_lshlrev_b32_e32 v16, 16, v14
	v_and_b32_e32 v14, 0xffff0000, v14
	v_fmac_f32_e32 v4, v12, v12
	v_add_f32_e32 v4, v5, v4
	v_mul_f32_e32 v5, v14, v14
	v_lshlrev_b32_e32 v17, 16, v15
	v_and_b32_e32 v15, 0xffff0000, v15
	v_fmac_f32_e32 v5, v16, v16
	v_add_f32_e32 v4, v5, v4
	v_mul_f32_e32 v5, v15, v15
	global_load_dwordx4 v[12:15], v[2:3], off offset:560
	v_fmac_f32_e32 v5, v17, v17
	v_add_f32_e32 v4, v5, v4
	v_add_f32_e32 v0, v0, v4
	s_waitcnt vmcnt(0) lgkmcnt(0)
	v_and_b32_e32 v5, 0xffff0000, v12
	v_lshlrev_b32_e32 v4, 16, v12
	v_lshlrev_b32_e32 v12, 16, v13
	v_and_b32_e32 v13, 0xffff0000, v13
	v_mul_f32_e32 v5, v5, v5
	v_fmac_f32_e32 v5, v4, v4
	v_mul_f32_e32 v4, v13, v13
	v_lshlrev_b32_e32 v16, 16, v14
	v_and_b32_e32 v14, 0xffff0000, v14
	v_fmac_f32_e32 v4, v12, v12
	v_add_f32_e32 v4, v5, v4
	v_mul_f32_e32 v5, v14, v14
	v_lshlrev_b32_e32 v17, 16, v15
	v_and_b32_e32 v15, 0xffff0000, v15
	v_fmac_f32_e32 v5, v16, v16
	v_add_f32_e32 v4, v5, v4
	v_mul_f32_e32 v5, v15, v15
	global_load_dwordx4 v[12:15], v[2:3], off offset:576
	v_fmac_f32_e32 v5, v17, v17
	v_add_f32_e32 v4, v5, v4
	v_add_f32_e32 v0, v0, v4
	s_waitcnt vmcnt(0) lgkmcnt(0)
	v_and_b32_e32 v5, 0xffff0000, v12
	v_lshlrev_b32_e32 v4, 16, v12
	v_lshlrev_b32_e32 v12, 16, v13
	v_and_b32_e32 v13, 0xffff0000, v13
	v_mul_f32_e32 v5, v5, v5
	v_fmac_f32_e32 v5, v4, v4
	v_mul_f32_e32 v4, v13, v13
	v_lshlrev_b32_e32 v16, 16, v14
	v_and_b32_e32 v14, 0xffff0000, v14
	v_fmac_f32_e32 v4, v12, v12
	v_add_f32_e32 v4, v5, v4
	v_mul_f32_e32 v5, v14, v14
	v_lshlrev_b32_e32 v17, 16, v15
	v_and_b32_e32 v15, 0xffff0000, v15
	v_fmac_f32_e32 v5, v16, v16
	v_add_f32_e32 v4, v5, v4
	v_mul_f32_e32 v5, v15, v15
	global_load_dwordx4 v[12:15], v[2:3], off offset:592
	v_fmac_f32_e32 v5, v17, v17
	v_add_f32_e32 v4, v5, v4
	v_add_f32_e32 v0, v0, v4
	s_waitcnt vmcnt(0) lgkmcnt(0)
	v_and_b32_e32 v5, 0xffff0000, v12
	v_lshlrev_b32_e32 v4, 16, v12
	v_lshlrev_b32_e32 v12, 16, v13
	v_and_b32_e32 v13, 0xffff0000, v13
	v_mul_f32_e32 v5, v5, v5
	v_fmac_f32_e32 v5, v4, v4
	v_mul_f32_e32 v4, v13, v13
	v_lshlrev_b32_e32 v16, 16, v14
	v_and_b32_e32 v14, 0xffff0000, v14
	v_fmac_f32_e32 v4, v12, v12
	v_add_f32_e32 v4, v5, v4
	v_mul_f32_e32 v5, v14, v14
	v_lshlrev_b32_e32 v17, 16, v15
	v_and_b32_e32 v15, 0xffff0000, v15
	v_fmac_f32_e32 v5, v16, v16
	v_add_f32_e32 v4, v5, v4
	v_mul_f32_e32 v5, v15, v15
	global_load_dwordx4 v[12:15], v[2:3], off offset:608
	v_fmac_f32_e32 v5, v17, v17
	v_add_f32_e32 v4, v5, v4
	v_add_f32_e32 v0, v0, v4
	s_waitcnt vmcnt(0) lgkmcnt(0)
	v_and_b32_e32 v5, 0xffff0000, v12
	v_lshlrev_b32_e32 v4, 16, v12
	v_lshlrev_b32_e32 v12, 16, v13
	v_and_b32_e32 v13, 0xffff0000, v13
	v_mul_f32_e32 v5, v5, v5
	v_fmac_f32_e32 v5, v4, v4
	v_mul_f32_e32 v4, v13, v13
	v_lshlrev_b32_e32 v16, 16, v14
	v_and_b32_e32 v14, 0xffff0000, v14
	v_fmac_f32_e32 v4, v12, v12
	v_add_f32_e32 v4, v5, v4
	v_mul_f32_e32 v5, v14, v14
	v_lshlrev_b32_e32 v17, 16, v15
	v_and_b32_e32 v15, 0xffff0000, v15
	v_fmac_f32_e32 v5, v16, v16
	v_add_f32_e32 v4, v5, v4
	v_mul_f32_e32 v5, v15, v15
	global_load_dwordx4 v[12:15], v[2:3], off offset:624
	v_fmac_f32_e32 v5, v17, v17
	v_add_f32_e32 v4, v5, v4
	v_add_f32_e32 v0, v0, v4
	s_waitcnt vmcnt(0) lgkmcnt(0)
; __device__ __forceinline__ void phase_mix_a(const Params& p, int l, bool last, unsigned char* smem) {
;     ...
;         for (int i = 0; i < 16; ++i) {
;           const u32x4 w = *(const u32x4*)(vp + i * 8);
;           const float a0 = __uint_as_float(w.x << 16), a1 = __uint_as_float(w.x & 0xffff0000u), a2 = __uint_as_float(w.y << 16), a3 = __uint_as_float(w.y & 0xffff0000u);
;           const float a4 = __uint_as_float(w.z << 16), a5 = __uint_as_float(w.z & 0xffff0000u), a6 = __uint_as_float(w.w << 16), a7 = __uint_as_float(w.w & 0xffff0000u);
;           s += (a0 * a0 + a1 * a1) + (a2 * a2 + a3 * a3) + (a4 * a4 + a5 * a5) + (a6 * a6 + a7 * a7);
;         }
;         s += __shfl_xor(s, 1);
;         __syncthreads();
;         if (half == 0) rsv[q] = rsqrtf(s * (1.f / 256.f) + 1e-6f);
;       }
	v_and_b32_e32 v5, 0xffff0000, v12
	v_lshlrev_b32_e32 v4, 16, v12
	v_lshlrev_b32_e32 v12, 16, v13
	v_and_b32_e32 v13, 0xffff0000, v13
	v_mul_f32_e32 v5, v5, v5
	v_fmac_f32_e32 v5, v4, v4
	v_mul_f32_e32 v4, v13, v13
	v_lshlrev_b32_e32 v16, 16, v14
	v_and_b32_e32 v14, 0xffff0000, v14
	v_fmac_f32_e32 v4, v12, v12
	v_add_f32_e32 v4, v5, v4
	v_mul_f32_e32 v5, v14, v14
	v_lshlrev_b32_e32 v17, 16, v15
	v_and_b32_e32 v15, 0xffff0000, v15
	v_fmac_f32_e32 v5, v16, v16
	v_add_f32_e32 v4, v5, v4
	v_mul_f32_e32 v5, v15, v15
	global_load_dwordx4 v[12:15], v[2:3], off offset:640
	v_fmac_f32_e32 v5, v17, v17
	v_add_f32_e32 v4, v5, v4
	v_add_f32_e32 v0, v0, v4
	s_waitcnt vmcnt(0) lgkmcnt(0)
	v_and_b32_e32 v5, 0xffff0000, v12
	v_lshlrev_b32_e32 v4, 16, v12
	v_lshlrev_b32_e32 v12, 16, v13
	v_and_b32_e32 v13, 0xffff0000, v13
	v_mul_f32_e32 v5, v5, v5
	v_fmac_f32_e32 v5, v4, v4
	v_mul_f32_e32 v4, v13, v13
	v_lshlrev_b32_e32 v16, 16, v14
	v_and_b32_e32 v14, 0xffff0000, v14
	v_fmac_f32_e32 v4, v12, v12
	v_add_f32_e32 v4, v5, v4
	v_mul_f32_e32 v5, v14, v14
	v_lshlrev_b32_e32 v17, 16, v15
	v_and_b32_e32 v15, 0xffff0000, v15
	v_fmac_f32_e32 v5, v16, v16
	v_add_f32_e32 v4, v5, v4
	v_mul_f32_e32 v5, v15, v15
	global_load_dwordx4 v[12:15], v[2:3], off offset:656
	v_fmac_f32_e32 v5, v17, v17
	v_add_f32_e32 v4, v5, v4
	v_add_f32_e32 v0, v0, v4
	s_waitcnt vmcnt(0) lgkmcnt(0)
	v_and_b32_e32 v5, 0xffff0000, v12
	v_lshlrev_b32_e32 v4, 16, v12
	v_lshlrev_b32_e32 v12, 16, v13
	v_and_b32_e32 v13, 0xffff0000, v13
	v_mul_f32_e32 v5, v5, v5
	v_fmac_f32_e32 v5, v4, v4
	v_mul_f32_e32 v4, v13, v13
	v_lshlrev_b32_e32 v16, 16, v14
	v_and_b32_e32 v14, 0xffff0000, v14
	v_fmac_f32_e32 v4, v12, v12
	v_add_f32_e32 v4, v5, v4
	v_mul_f32_e32 v5, v14, v14
	v_lshlrev_b32_e32 v17, 16, v15
	v_and_b32_e32 v15, 0xffff0000, v15
	v_fmac_f32_e32 v5, v16, v16
	v_add_f32_e32 v4, v5, v4
	v_mul_f32_e32 v5, v15, v15
	global_load_dwordx4 v[12:15], v[2:3], off offset:672
	v_fmac_f32_e32 v5, v17, v17
	v_add_f32_e32 v4, v5, v4
	v_add_f32_e32 v0, v0, v4
	s_waitcnt vmcnt(0) lgkmcnt(0)
	v_and_b32_e32 v5, 0xffff0000, v12
	v_lshlrev_b32_e32 v4, 16, v12
	v_lshlrev_b32_e32 v12, 16, v13
	v_and_b32_e32 v13, 0xffff0000, v13
	v_mul_f32_e32 v5, v5, v5
	v_fmac_f32_e32 v5, v4, v4
	v_mul_f32_e32 v4, v13, v13
	v_lshlrev_b32_e32 v16, 16, v14
	v_and_b32_e32 v14, 0xffff0000, v14
	v_fmac_f32_e32 v4, v12, v12
	v_add_f32_e32 v4, v5, v4
	v_mul_f32_e32 v5, v14, v14
	v_lshlrev_b32_e32 v17, 16, v15
	v_and_b32_e32 v15, 0xffff0000, v15
	v_fmac_f32_e32 v5, v16, v16
	v_add_f32_e32 v4, v5, v4
	v_mul_f32_e32 v5, v15, v15
	global_load_dwordx4 v[12:15], v[2:3], off offset:688
	v_fmac_f32_e32 v5, v17, v17
	v_add_f32_e32 v4, v5, v4
	v_add_f32_e32 v0, v0, v4
	s_waitcnt vmcnt(0) lgkmcnt(0)
	v_and_b32_e32 v5, 0xffff0000, v12
	v_lshlrev_b32_e32 v4, 16, v12
	v_lshlrev_b32_e32 v12, 16, v13
	v_and_b32_e32 v13, 0xffff0000, v13
	v_mul_f32_e32 v5, v5, v5
	v_fmac_f32_e32 v5, v4, v4
	v_mul_f32_e32 v4, v13, v13
	v_lshlrev_b32_e32 v16, 16, v14
	v_and_b32_e32 v14, 0xffff0000, v14
	v_fmac_f32_e32 v4, v12, v12
	v_add_f32_e32 v4, v5, v4
	v_mul_f32_e32 v5, v14, v14
	v_lshlrev_b32_e32 v17, 16, v15
	v_and_b32_e32 v15, 0xffff0000, v15
	v_fmac_f32_e32 v5, v16, v16
	v_add_f32_e32 v4, v5, v4
	v_mul_f32_e32 v5, v15, v15
	global_load_dwordx4 v[12:15], v[2:3], off offset:704
	v_fmac_f32_e32 v5, v17, v17
	v_add_f32_e32 v4, v5, v4
	v_add_f32_e32 v0, v0, v4
	s_waitcnt vmcnt(0) lgkmcnt(0)
	v_and_b32_e32 v5, 0xffff0000, v12
	v_lshlrev_b32_e32 v4, 16, v12
	v_lshlrev_b32_e32 v12, 16, v13
	v_and_b32_e32 v13, 0xffff0000, v13
	v_mul_f32_e32 v5, v5, v5
	v_fmac_f32_e32 v5, v4, v4
	v_mul_f32_e32 v4, v13, v13
	v_lshlrev_b32_e32 v16, 16, v14
	v_and_b32_e32 v14, 0xffff0000, v14
	v_fmac_f32_e32 v4, v12, v12
	v_add_f32_e32 v4, v5, v4
	v_mul_f32_e32 v5, v14, v14
	v_lshlrev_b32_e32 v17, 16, v15
	v_and_b32_e32 v15, 0xffff0000, v15
	v_fmac_f32_e32 v5, v16, v16
	v_add_f32_e32 v4, v5, v4
	v_mul_f32_e32 v5, v15, v15
	global_load_dwordx4 v[12:15], v[2:3], off offset:720
	v_fmac_f32_e32 v5, v17, v17
	v_add_f32_e32 v4, v5, v4
	v_add_f32_e32 v0, v0, v4
	s_waitcnt vmcnt(0) lgkmcnt(0)
	v_and_b32_e32 v5, 0xffff0000, v12
	v_lshlrev_b32_e32 v4, 16, v12
	v_lshlrev_b32_e32 v12, 16, v13
	v_and_b32_e32 v13, 0xffff0000, v13
	v_mul_f32_e32 v5, v5, v5
	v_fmac_f32_e32 v5, v4, v4
	v_mul_f32_e32 v4, v13, v13
	v_lshlrev_b32_e32 v16, 16, v14
	v_and_b32_e32 v14, 0xffff0000, v14
	v_fmac_f32_e32 v4, v12, v12
	v_add_f32_e32 v4, v5, v4
	v_mul_f32_e32 v5, v14, v14
	v_lshlrev_b32_e32 v17, 16, v15
	v_and_b32_e32 v15, 0xffff0000, v15
	v_fmac_f32_e32 v5, v16, v16
	v_add_f32_e32 v4, v5, v4
	v_mul_f32_e32 v5, v15, v15
	global_load_dwordx4 v[12:15], v[2:3], off offset:736
	v_fmac_f32_e32 v5, v17, v17
	v_add_f32_e32 v4, v5, v4
	v_add_f32_e32 v0, v0, v4
	s_waitcnt vmcnt(0) lgkmcnt(0)
	v_and_b32_e32 v5, 0xffff0000, v12
	v_lshlrev_b32_e32 v4, 16, v12
	v_lshlrev_b32_e32 v12, 16, v13
	v_and_b32_e32 v13, 0xffff0000, v13
	v_mul_f32_e32 v5, v5, v5
	v_fmac_f32_e32 v5, v4, v4
	v_mul_f32_e32 v4, v13, v13
	v_lshlrev_b32_e32 v16, 16, v14
	v_and_b32_e32 v14, 0xffff0000, v14
	v_fmac_f32_e32 v4, v12, v12
	v_add_f32_e32 v4, v5, v4
	v_mul_f32_e32 v5, v14, v14
	v_lshlrev_b32_e32 v17, 16, v15
	v_and_b32_e32 v15, 0xffff0000, v15
	v_fmac_f32_e32 v5, v16, v16
	v_add_f32_e32 v4, v5, v4
	v_mul_f32_e32 v5, v15, v15
	v_fmac_f32_e32 v5, v17, v17
	v_add_f32_e32 v4, v5, v4
	v_add_f32_e32 v0, v0, v4
	global_load_dwordx4 v[2:5], v[2:3], off offset:752
	s_waitcnt lgkmcnt(0)
	s_barrier
	s_waitcnt vmcnt(0)
	v_lshlrev_b32_e32 v12, 16, v2
	v_and_b32_e32 v2, 0xffff0000, v2
	v_lshlrev_b32_e32 v13, 16, v3
	v_and_b32_e32 v3, 0xffff0000, v3
	v_mul_f32_e32 v2, v2, v2
	v_mul_f32_e32 v3, v3, v3
	v_lshlrev_b32_e32 v14, 16, v4
	v_and_b32_e32 v4, 0xffff0000, v4
	v_fmac_f32_e32 v2, v12, v12
	v_fmac_f32_e32 v3, v13, v13
	v_add_f32_e32 v2, v2, v3
	v_mul_f32_e32 v3, v4, v4
	v_lshlrev_b32_e32 v15, 16, v5
	v_and_b32_e32 v5, 0xffff0000, v5
	v_fmac_f32_e32 v3, v14, v14
	v_add_f32_e32 v2, v3, v2
	v_mul_f32_e32 v3, v5, v5
	v_fmac_f32_e32 v3, v15, v15
	v_add_f32_e32 v2, v3, v2
	v_add_f32_e32 v0, v0, v2
	v_cndmask_b32_e32 v2, v186, v212, vcc
	v_lshlrev_b32_e32 v2, 2, v2
	ds_bpermute_b32 v2, v2, v0
	v_cmp_eq_u32_e32 vcc, 0, v11
	s_and_saveexec_b64 s[0:1], vcc
	s_cbranch_execz .LBB0_602
	s_waitcnt lgkmcnt(0)
	v_add_f32_e32 v0, v0, v2
	v_fmamk_f32 v0, v0, 0x3b800000, v224
	v_mul_f32_e32 v2, 0x4b800000, v0
	v_cmp_gt_f32_e32 vcc, s85, v0
	s_nop 1
	v_cndmask_b32_e32 v0, v0, v2, vcc
	v_rsq_f32_e32 v0, v0
	s_nop 0
	v_mul_f32_e32 v2, 0x45800000, v0
	v_cndmask_b32_e32 v0, v0, v2, vcc
	v_mov_b32_e32 v2, 0x10200
	v_lshl_add_u32 v2, v10, 2, v2
	ds_write_b32 v2, v0
	s_branch .LBB0_602

; __device__ __forceinline__ int tid_() { int t = threadIdx.x; asm volatile("" : "+v"(t)); return t; }
; #define XCD_FOR(u, T)                                                                                         \
;   for (int _x = bid_() & 7, _gb = gridDim.x >> 3, _hi = (int)(((long)(_x + 1) * (T)) >> 3),                    \
;            u = (int)(((long)_x * (T)) >> 3) + (bid_() >> 3);                                                  \
;        u < _hi; u += _gb)
; template <int NT, bool BKN, bool MASK = false, bool ROWSS = false, class Epi> ...
;     ...
;   const int t = tid_(), lane = t & 63, wid = t >> 6, wr = wid >> 1, wc = wid & 1, l16 = lane & 15, quad = lane >> 4;
;   const u16* ap[4];
;   const u16* bp[NT];
;   unsigned amask = 0u;
; #pragma unroll
;   for (int i = 0; i < 4; ++i) {
;     const int row = (t >> 3) + 32 * i;
;     const bool v = MASK ? (row < mvalid) : true;
;     amask |= v ? (1u << i) : 0u;
;     int r = v ? row : 0;
;     if (arows) r = arows[r];
;     ap[i] = A + (size_t)r * lda + (t & 7) * 8;
;   }
; #pragma unroll
;   for (int i = 0; i < NT; ++i) {
;     if (!BKN) bp[i] = B + (size_t)((t >> 3) + 32 * i) * ldb + (t & 7) * 8;
;     else { const int c = t + 256 * i; bp[i] = B + (size_t)(c / CPR) * ldb + (c % CPR) * 8; }
;   }
;   const size_t bstep = BKN ? (size_t)64 * ldb : (size_t)64;
;   int nmi = 4;
;   if (MASK) { nmi = (mvalid - wr * 64 + 15) >> 4; nmi = nmi < 0 ? 0 : (nmi > 4 ? 4 : nmi); nmi = __builtin_amdgcn_readfirstlane(nmi); }
;   u32x4 ra0[4], rb0[NT], ra1[4], rb1[NT];
; __device__ __forceinline__ void phase_mix_a(const Params& p, int l, bool last, unsigned char* smem) {
;     ...
;     XCD_FOR(t, 512) {
;       const int nh = t & 1, n1 = (t >> 1) & 127, b = t >> 8;
;       auto epi = [&](f32x4(&acc)[4][4], int r0, int c0) {
;         auto vf = [&](int, int, float v) { return v; };
;         auto rp = [&](int m) -> u16* { const int rip = m >> 6, k2 = m & 63; return p.PF + ((size_t)((b * 64 + k2) * 2 + rip) * 128 + n1) * 256 + nh * 128; };
;         epi_staged_bf16<4>(acc, r0, c0, smem, vf, rp);
;       };
;       gemm_tile<4, true>(p.M1 + (size_t)n1 * 16384, 128, nullptr, 128, p.GD + (size_t)b * 2 * SEQ * 256 + (size_t)n1 * 256 + nh * 128, 128 * 256, 128, smem, epi);
;     }
.LBB0_608:
	v_mov_b64_e32 v[34:35], s[40:41]
	s_waitcnt vmcnt(0) lgkmcnt(0)
	global_load_dwordx2 v[2:3], v[34:35], off offset:248
	global_load_dwordx2 v[4:5], v[34:35], off offset:304
	v_mov_b32_e32 v46, v187
	s_ashr_i32 s4, s9, 8
	s_bfe_u32 s19, s9, 0x70001
	v_ashrrev_i32_e32 v9, 31, v46
	s_ashr_i32 s5, s4, 31
	v_lshrrev_b32_e32 v9, 28, v9
	s_lshl_b32 s94, s19, 15
	s_lshl_b64 s[34:35], s[4:5], 23
	v_ashrrev_i32_e32 v6, 3, v46
	v_lshlrev_b32_e32 v8, 4, v46
	v_add_u32_e32 v9, v46, v9
	s_and_b32 s0, s18, 0x80
	v_and_b32_e32 v0, 0x70, v8
	v_ashrrev_i32_e32 v7, 31, v6
	v_and_b32_e32 v17, 0xffffff80, v8
	v_ashrrev_i32_e32 v8, 4, v9
	s_mov_b32 s1, s95
	s_lshl_b32 s0, s0, 1
	v_add_u32_e32 v14, 0x100, v46
	v_lshlrev_b64 v[6:7], 8, v[6:7]
	v_and_b32_e32 v18, -16, v9
	v_ashrrev_i32_e32 v9, 31, v8
	v_lshrrev_b32_e32 v47, 4, v46
	v_add_u32_e32 v15, 0x200, v46
	v_ashrrev_i32_e32 v10, 31, v14
	v_and_b32_e32 v86, -8, v8
	v_and_b32_e32 v87, 7, v8
	v_lshlrev_b64 v[8:9], 16, v[8:9]
	v_add_u32_e32 v16, 0x300, v46
	v_ashrrev_i32_e32 v11, 31, v15
	v_xor_b32_e32 v13, v47, v46
	v_lshrrev_b32_e32 v10, 28, v10
	v_ashrrev_i32_e32 v12, 31, v16
	v_lshrrev_b32_e32 v11, 28, v11
	v_lshlrev_b32_e32 v13, 4, v13
	v_add_u32_e32 v10, v14, v10
	v_lshrrev_b32_e32 v12, 28, v12
	v_add_u32_e32 v11, v15, v11
	v_and_or_b32 v128, v13, s14, v17
	v_sub_u32_e32 v17, v46, v18
	v_ashrrev_i32_e32 v80, 4, v10
	v_and_b32_e32 v18, -16, v10
	v_add_u32_e32 v12, v16, v12
	v_ashrrev_i32_e32 v40, 4, v11
	v_and_b32_e32 v19, -16, v11
	s_movk_i32 s5, 0x6000
	v_ashrrev_i32_e32 v36, 4, v12
	v_and_b32_e32 v20, -16, v12
	v_lshlrev_b32_e32 v82, 3, v17
	v_ashrrev_i32_e32 v83, 31, v82
	v_ashrrev_i32_e32 v37, 31, v36
	s_waitcnt lgkmcnt(0)
	s_barrier
	v_ashrrev_i32_e32 v41, 31, v40
	v_sub_u32_e32 v88, v16, v20
	v_ashrrev_i32_e32 v81, 31, v80
	v_lshlrev_b32_e32 v38, 3, v88
	v_ashrrev_i32_e32 v39, 31, v38
	v_and_b32_e32 v44, 15, v46
	v_bfe_u32 v108, v46, 1, 3
	v_ashrrev_i32_e32 v45, 7, v46
	v_bfe_u32 v161, v46, 6, 1
	v_bfe_u32 v163, v46, 4, 2
	v_bitop3_b32 v46, v163, v108, 4 bitop3:0x36
	v_lshlrev_b32_e32 v46, 4, v46
	s_waitcnt vmcnt(0)
	v_lshl_add_u64 v[2:3], v[2:3], 0, s[94:95]
	v_lshl_add_u64 v[4:5], v[4:5], 0, s[34:35]
	s_lshl_b32 s94, s19, 9
	v_lshl_add_u64 v[4:5], v[4:5], 0, s[94:95]
	v_lshl_add_u64 v[2:3], v[2:3], 0, v[0:1]
	v_lshl_add_u64 v[4:5], v[4:5], 0, s[0:1]
	v_lshl_add_u64 v[2:3], v[2:3], 0, v[6:7]
	v_lshl_add_u64 v[6:7], v[4:5], 0, v[8:9]
	v_add_co_u32_e32 v8, vcc, s70, v2
	global_load_dwordx4 v[48:51], v[2:3], off
	s_nop 0
	v_addc_co_u32_e32 v9, vcc, 0, v3, vcc
	v_add_co_u32_e32 v10, vcc, s69, v2
	v_lshl_add_u64 v[6:7], v[82:83], 1, v[6:7]
	s_nop 0
	v_addc_co_u32_e32 v11, vcc, 0, v3, vcc
	v_add_co_u32_e32 v12, vcc, s5, v2
	v_sub_u32_e32 v0, v14, v18
	s_nop 0
	v_addc_co_u32_e32 v13, vcc, 0, v3, vcc
	global_load_dwordx4 v[52:55], v[8:9], off
	global_load_dwordx4 v[56:59], v[10:11], off
	global_load_dwordx4 v[60:63], v[12:13], off
	global_load_dwordx4 v[64:67], v[6:7], off
	v_lshlrev_b64 v[12:13], 16, v[36:37]
	v_or_b32_e32 v37, 4, v82
	v_sub_u32_e32 v83, v15, v19
	v_lshlrev_b32_e32 v14, 9, v17
	v_lshlrev_b32_e32 v15, 5, v17
	v_lshlrev_b64 v[10:11], 16, v[40:41]
	v_lshlrev_b32_e32 v41, 6, v37
	v_lshlrev_b32_e32 v37, 2, v37
	v_bitop3_b32 v15, v15, v86, 32 bitop3:0x6c
	v_or_b32_e32 v16, v87, v14
	v_or_b32_e32 v17, 2, v82
	v_or_b32_e32 v18, 3, v82
	v_and_b32_e32 v37, 48, v37
	v_add_u32_e32 v14, v15, v14
	v_add_lshl_u32 v129, v16, v15, 1
	v_lshlrev_b32_e32 v15, 6, v17
	v_lshlrev_b32_e32 v16, 2, v17
	v_lshlrev_b32_e32 v17, 6, v18
	v_lshlrev_b32_e32 v18, 2, v18
	v_xad_u32 v37, v37, v86, v41
	v_lshlrev_b64 v[8:9], 16, v[80:81]
	v_or_b32_e32 v14, v14, v87
	v_and_b32_e32 v16, 40, v16
	v_and_b32_e32 v18, 40, v18
	v_or_b32_e32 v37, v37, v87
	v_lshlrev_b32_e32 v130, 1, v14
	v_xad_u32 v14, v16, v86, v15
	v_xad_u32 v15, v18, v86, v17
	v_lshl_add_u64 v[8:9], v[4:5], 0, v[8:9]
	v_lshl_add_u64 v[16:17], v[4:5], 0, v[10:11]
	v_lshl_add_u64 v[4:5], v[4:5], 0, v[12:13]
	v_lshlrev_b32_e32 v133, 1, v37
	v_or_b32_e32 v37, 5, v82
	v_lshl_add_u64 v[4:5], v[38:39], 1, v[4:5]
	v_lshlrev_b32_e32 v39, 6, v37
	v_lshlrev_b32_e32 v37, 2, v37
	v_and_b32_e32 v37, 48, v37
	v_xad_u32 v37, v37, v86, v39
	v_or_b32_e32 v37, v37, v87
	v_lshlrev_b32_e32 v134, 1, v37
	v_or_b32_e32 v37, 6, v82
	v_lshlrev_b32_e32 v39, 6, v37
	v_lshlrev_b32_e32 v37, 2, v37
	v_and_b32_e32 v37, 56, v37
	v_xad_u32 v37, v37, v86, v39
	v_or_b32_e32 v37, v37, v87
	v_lshlrev_b32_e32 v135, 1, v37
	v_or_b32_e32 v37, 7, v82
	v_lshlrev_b32_e32 v39, 6, v37
	v_lshlrev_b32_e32 v37, 2, v37
	v_and_b32_e32 v37, 56, v37
	v_xad_u32 v37, v37, v86, v39
	v_or_b32_e32 v37, v37, v87
	v_lshlrev_b32_e32 v84, 3, v0
	v_lshlrev_b32_e32 v42, 3, v83
	v_lshlrev_b32_e32 v136, 1, v37
	v_and_b32_e32 v37, -8, v80
	v_lshlrev_b32_e32 v41, 9, v0
	v_lshlrev_b32_e32 v0, 5, v0
	v_ashrrev_i32_e32 v43, 31, v42
	v_or_b32_e32 v14, v14, v87
	v_or_b32_e32 v15, v15, v87
	s_mov_b64 s[34:35], 0x2000
	v_and_b32_e32 v39, 7, v80
	v_bitop3_b32 v0, v0, v37, 32 bitop3:0x6c
	v_lshlrev_b32_e32 v131, 1, v14
	v_lshlrev_b32_e32 v132, 1, v15
	v_lshl_add_u64 v[14:15], v[2:3], 0, s[34:35]
	v_lshl_add_u64 v[18:19], v[2:3], 0, s[62:63]
	v_lshl_add_u64 v[22:23], v[2:3], 0, s[24:25]
	global_load_dwordx4 v[10:13], v[2:3], off offset:128
	v_lshl_add_u64 v[2:3], v[42:43], 1, v[16:17]
	v_add_u32_e32 v43, v0, v41
	v_or_b32_e32 v41, v39, v41
	v_or_b32_e32 v43, v43, v39
	v_add_lshl_u32 v0, v41, v0, 1
	v_or_b32_e32 v41, 2, v84
	v_lshlrev_b32_e32 v137, 1, v43
	v_lshlrev_b32_e32 v43, 6, v41
	v_lshlrev_b32_e32 v41, 2, v41
	v_and_b32_e32 v41, 40, v41
	v_xad_u32 v41, v41, v37, v43
	v_or_b32_e32 v41, v41, v39
	v_lshlrev_b32_e32 v138, 1, v41
	v_or_b32_e32 v41, 3, v84
	v_lshlrev_b32_e32 v43, 6, v41
	v_lshlrev_b32_e32 v41, 2, v41
	v_and_b32_e32 v41, 40, v41
	v_xad_u32 v41, v41, v37, v43
	v_or_b32_e32 v41, v41, v39
	v_lshlrev_b32_e32 v139, 1, v41
	v_or_b32_e32 v41, 4, v84
	v_lshlrev_b32_e32 v43, 6, v41
	v_lshlrev_b32_e32 v41, 2, v41
	v_and_b32_e32 v41, 48, v41
	v_xad_u32 v41, v41, v37, v43
	v_or_b32_e32 v41, v41, v39
	v_lshlrev_b32_e32 v140, 1, v41
	v_or_b32_e32 v41, 5, v84
	v_ashrrev_i32_e32 v85, 31, v84
	v_lshlrev_b32_e32 v43, 6, v41
	v_lshlrev_b32_e32 v41, 2, v41
	v_lshl_add_u64 v[8:9], v[84:85], 1, v[8:9]
	v_and_b32_e32 v41, 48, v41
	global_load_dwordx4 v[68:71], v[8:9], off
	s_nop 0
	global_load_dwordx4 v[14:17], v[14:15], off offset:128
	s_nop 0
	global_load_dwordx4 v[18:21], v[18:19], off offset:128
	s_nop 0
	global_load_dwordx4 v[22:25], v[22:23], off offset:128
	s_nop 0
	global_load_dwordx4 v[72:75], v[2:3], off
	global_load_dwordx4 v[76:79], v[4:5], off
	v_xad_u32 v41, v41, v37, v43
	v_or_b32_e32 v41, v41, v39
	v_lshlrev_b32_e32 v141, 1, v41
	v_or_b32_e32 v41, 6, v84
	v_lshlrev_b32_e32 v43, 6, v41
	v_lshlrev_b32_e32 v41, 2, v41
	v_and_b32_e32 v41, 56, v41
	s_mov_b32 s5, 0x400000
	v_xad_u32 v41, v41, v37, v43
	v_add_co_u32_e32 v6, vcc, s5, v6
	v_or_b32_e32 v41, v41, v39
	s_nop 0
	v_addc_co_u32_e32 v7, vcc, 0, v7, vcc
	v_lshlrev_b32_e32 v142, 1, v41
	v_or_b32_e32 v41, 7, v84
	v_add_co_u32_e32 v8, vcc, s5, v8
	v_lshlrev_b32_e32 v43, 6, v41
	v_lshlrev_b32_e32 v41, 2, v41
	v_addc_co_u32_e32 v9, vcc, 0, v9, vcc
	v_and_b32_e32 v41, 56, v41
	v_add_co_u32_e32 v2, vcc, s5, v2
	v_xad_u32 v37, v41, v37, v43
	s_nop 0
	v_addc_co_u32_e32 v3, vcc, 0, v3, vcc
	v_or_b32_e32 v37, v37, v39
	v_add_co_u32_e32 v4, vcc, s5, v4
	v_lshlrev_b32_e32 v143, 1, v37
	v_and_b32_e32 v37, -8, v40
	v_lshlrev_b32_e32 v41, 5, v83
	v_addc_co_u32_e32 v5, vcc, 0, v5, vcc
	v_and_b32_e32 v39, 7, v40
	v_lshlrev_b32_e32 v40, 9, v83
	v_bitop3_b32 v41, v41, v37, 32 bitop3:0x6c
	global_load_dwordx4 v[30:33], v[6:7], off
	global_load_dwordx4 v[26:29], v[8:9], off
	s_nop 0
	global_load_dwordx4 v[6:9], v[2:3], off
	s_nop 0
	global_load_dwordx4 v[2:5], v[4:5], off
	v_add_u32_e32 v43, v41, v40
	v_or_b32_e32 v40, v39, v40
	v_add_lshl_u32 v145, v40, v41, 1
	v_or_b32_e32 v40, 2, v42
	v_lshlrev_b32_e32 v41, 6, v40
	v_lshlrev_b32_e32 v40, 2, v40
	v_and_b32_e32 v40, 40, v40
	v_xad_u32 v40, v40, v37, v41
	v_or_b32_e32 v40, v40, v39
	v_lshlrev_b32_e32 v146, 1, v40
	v_or_b32_e32 v40, 3, v42
	v_lshlrev_b32_e32 v41, 6, v40
	v_lshlrev_b32_e32 v40, 2, v40
	v_and_b32_e32 v40, 40, v40
	v_xad_u32 v40, v40, v37, v41
	v_or_b32_e32 v40, v40, v39
	v_lshlrev_b32_e32 v147, 1, v40
	v_or_b32_e32 v40, 4, v42
	v_lshlrev_b32_e32 v41, 6, v40
	v_lshlrev_b32_e32 v40, 2, v40
	v_and_b32_e32 v40, 48, v40
	v_xad_u32 v40, v40, v37, v41
	v_or_b32_e32 v40, v40, v39
	v_lshlrev_b32_e32 v148, 1, v40
	v_or_b32_e32 v40, 5, v42
	v_lshlrev_b32_e32 v41, 6, v40
	v_lshlrev_b32_e32 v40, 2, v40
	v_and_b32_e32 v40, 48, v40
	v_xad_u32 v40, v40, v37, v41
	v_or_b32_e32 v40, v40, v39
	v_lshlrev_b32_e32 v149, 1, v40
	v_or_b32_e32 v40, 6, v42
	v_lshlrev_b32_e32 v41, 6, v40
	v_lshlrev_b32_e32 v40, 2, v40
	v_and_b32_e32 v40, 56, v40
	v_xad_u32 v40, v40, v37, v41
	v_or_b32_e32 v40, v40, v39
	v_lshlrev_b32_e32 v150, 1, v40
	v_or_b32_e32 v40, 7, v42
	v_lshlrev_b32_e32 v41, 6, v40
	v_lshlrev_b32_e32 v40, 2, v40
	v_and_b32_e32 v40, 56, v40
	v_xad_u32 v37, v40, v37, v41
	v_or_b32_e32 v37, v37, v39
	v_lshlrev_b32_e32 v151, 1, v37
	v_and_b32_e32 v37, -8, v36
	v_lshlrev_b32_e32 v40, 5, v88
	v_or_b32_e32 v43, v43, v39
	v_and_b32_e32 v36, 7, v36
	v_lshlrev_b32_e32 v39, 9, v88
	v_bitop3_b32 v40, v40, v37, 32 bitop3:0x6c
	v_add_u32_e32 v41, v40, v39
	v_or_b32_e32 v39, v36, v39
	v_add_lshl_u32 v153, v39, v40, 1
	v_or_b32_e32 v39, 2, v38
	v_lshlrev_b32_e32 v40, 6, v39
	v_lshlrev_b32_e32 v39, 2, v39
	v_and_b32_e32 v39, 40, v39
	v_xad_u32 v39, v39, v37, v40
	v_or_b32_e32 v39, v39, v36
	v_lshlrev_b32_e32 v154, 1, v39
	v_or_b32_e32 v39, 3, v38
	v_lshlrev_b32_e32 v40, 6, v39
	v_lshlrev_b32_e32 v39, 2, v39
	v_and_b32_e32 v39, 40, v39
	v_xad_u32 v39, v39, v37, v40
	v_or_b32_e32 v39, v39, v36
	v_lshlrev_b32_e32 v155, 1, v39
	v_or_b32_e32 v39, 4, v38
	v_lshlrev_b32_e32 v40, 6, v39
	v_lshlrev_b32_e32 v39, 2, v39
	v_and_b32_e32 v39, 48, v39
	v_xad_u32 v39, v39, v37, v40
	v_or_b32_e32 v39, v39, v36
	v_lshlrev_b32_e32 v156, 1, v39
	v_or_b32_e32 v39, 5, v38
	v_lshlrev_b32_e32 v40, 6, v39
	v_lshlrev_b32_e32 v39, 2, v39
	v_and_b32_e32 v39, 48, v39
	v_xad_u32 v39, v39, v37, v40
	v_or_b32_e32 v39, v39, v36
	v_lshlrev_b32_e32 v157, 1, v39
	v_or_b32_e32 v39, 6, v38
	v_lshlrev_b32_e32 v40, 6, v39
	v_lshlrev_b32_e32 v39, 2, v39
	v_and_b32_e32 v39, 56, v39
	v_xad_u32 v39, v39, v37, v40
	v_or_b32_e32 v39, v39, v36
	v_or_b32_e32 v38, 7, v38
	v_lshlrev_b32_e32 v158, 1, v39
	v_lshlrev_b32_e32 v39, 6, v38
	v_lshlrev_b32_e32 v38, 2, v38
	v_and_b32_e32 v38, 56, v38
	v_xad_u32 v37, v38, v37, v39
	v_or_b32_e32 v41, v41, v36
	v_or_b32_e32 v36, v37, v36
	v_lshlrev_b32_e32 v152, 1, v41
	v_lshlrev_b32_e32 v159, 1, v36
	v_bitop3_b32 v36, v47, v108, 3 bitop3:0x6c
	v_lshlrev_b32_e32 v41, 7, v44
	v_lshlrev_b32_e32 v40, 4, v36
	v_lshl_or_b32 v47, v45, 13, v41
	v_lshlrev_b32_e32 v144, 1, v43
	v_or_b32_e32 v160, v40, v47
	s_waitcnt vmcnt(0) lgkmcnt(0)
	ds_write_b128 v128, v[48:51]
	ds_write_b128 v128, v[52:55] offset:4096
	ds_write_b128 v128, v[56:59] offset:8192
	ds_write_b128 v128, v[60:63] offset:12288
	ds_write_b16 v130, v64 offset:16384
	ds_write_b16_d16_hi v129, v64 offset:16512
	ds_write_b16 v131, v65 offset:16384
	ds_write_b16_d16_hi v132, v65 offset:16384
	ds_write_b16 v133, v66 offset:16384
	ds_write_b16_d16_hi v134, v66 offset:16384
	ds_write_b16 v135, v67 offset:16384
	ds_write_b16_d16_hi v136, v67 offset:16384
	ds_write_b16 v137, v68 offset:16384
	ds_write_b16_d16_hi v0, v68 offset:16512
	ds_write_b16 v138, v69 offset:16384
	ds_write_b16_d16_hi v139, v69 offset:16384
	ds_write_b16 v140, v70 offset:16384
	ds_write_b16_d16_hi v141, v70 offset:16384
	ds_write_b16 v142, v71 offset:16384
	ds_write_b16_d16_hi v143, v71 offset:16384
	ds_write_b16 v144, v72 offset:16384
	ds_write_b16_d16_hi v145, v72 offset:16512
	ds_write_b16 v146, v73 offset:16384
	ds_write_b16_d16_hi v147, v73 offset:16384
	ds_write_b16 v148, v74 offset:16384
	ds_write_b16_d16_hi v149, v74 offset:16384
	ds_write_b16 v150, v75 offset:16384
	ds_write_b16_d16_hi v151, v75 offset:16384
	ds_write_b16 v152, v76 offset:16384
	ds_write_b16_d16_hi v153, v76 offset:16512
	ds_write_b16 v154, v77 offset:16384
	ds_write_b16_d16_hi v155, v77 offset:16384
	ds_write_b16 v156, v78 offset:16384
	ds_write_b16_d16_hi v157, v78 offset:16384
	ds_write_b16 v158, v79 offset:16384
	ds_write_b16_d16_hi v159, v79 offset:16384
	s_waitcnt lgkmcnt(0)
	s_barrier
; template <int NT, bool BKN, bool MASK = false, bool ROWSS = false, class Epi> ...
;     ...
;   for (int kt = 0; kt < nk - 2; kt += 2) {
;     GEMM_COMPUTE(0);
;     GEMM_STORE(ra1, rb1, 1);
;     GEMM_LOAD(ra1, rb1, kt + 3);
;     __syncthreads();
;     GEMM_COMPUTE(1);
;     GEMM_STORE(ra0, rb0, 0);
;     GEMM_LOAD(ra0, rb0, (kt + 4 < nkm1 ? kt + 4 : nkm1));
;     __syncthreads();
;   }
	ds_read_b128 v[36:39], v160
	v_lshl_or_b32 v112, v161, 13, v41
	v_or_b32_e32 v162, v40, v112
	ds_read_b128 v[40:43], v162 offset:16384
	ds_read_b128 v[48:51], v160 offset:2048
	ds_read_b128 v[52:55], v162 offset:18432
	ds_read_b128 v[64:67], v162 offset:20480
	ds_read_b128 v[68:71], v162 offset:22528
	ds_read_b128 v[88:91], v160 offset:4096
	ds_read_b128 v[92:95], v160 offset:6144
	v_or_b32_e32 v164, v46, v47
	ds_read_b128 v[108:111], v164
	v_or_b32_e32 v165, v46, v112
	s_waitcnt lgkmcnt(7)
	v_mfma_f32_16x16x32_bf16 v[56:59], v[36:39], v[40:43], 0
	s_lshl_b32 s19, s4, 7
	s_waitcnt lgkmcnt(5)
	v_mfma_f32_16x16x32_bf16 v[60:63], v[36:39], v[52:55], 0
	s_waitcnt lgkmcnt(4)
	v_mfma_f32_16x16x32_bf16 v[72:75], v[36:39], v[64:67], 0
	s_waitcnt lgkmcnt(3)
	v_mfma_f32_16x16x32_bf16 v[36:39], v[36:39], v[68:71], 0
	v_mfma_f32_16x16x32_bf16 v[76:79], v[48:51], v[40:43], 0
	v_mfma_f32_16x16x32_bf16 v[80:83], v[48:51], v[52:55], 0
	v_mfma_f32_16x16x32_bf16 v[84:87], v[48:51], v[64:67], 0
	v_mfma_f32_16x16x32_bf16 v[48:51], v[48:51], v[68:71], 0
	s_waitcnt lgkmcnt(2)
	v_mfma_f32_16x16x32_bf16 v[96:99], v[88:91], v[40:43], 0
	v_mfma_f32_16x16x32_bf16 v[100:103], v[88:91], v[52:55], 0
	v_mfma_f32_16x16x32_bf16 v[104:107], v[88:91], v[64:67], 0
	v_mfma_f32_16x16x32_bf16 v[88:91], v[88:91], v[68:71], 0
	s_waitcnt lgkmcnt(1)
	v_mfma_f32_16x16x32_bf16 v[40:43], v[92:95], v[40:43], 0
	v_mfma_f32_16x16x32_bf16 v[52:55], v[92:95], v[52:55], 0
	v_mfma_f32_16x16x32_bf16 v[64:67], v[92:95], v[64:67], 0
	v_mfma_f32_16x16x32_bf16 v[68:71], v[92:95], v[68:71], 0
	ds_read_b128 v[92:95], v165 offset:16384
	ds_read_b128 v[112:115], v164 offset:2048
	ds_read_b128 v[116:119], v165 offset:18432
	ds_read_b128 v[120:123], v165 offset:20480
	ds_read_b128 v[124:127], v165 offset:22528
	s_waitcnt lgkmcnt(4)
	v_mfma_f32_16x16x32_bf16 v[56:59], v[108:111], v[92:95], v[56:59]
	s_waitcnt lgkmcnt(2)
	v_mfma_f32_16x16x32_bf16 v[60:63], v[108:111], v[116:119], v[60:63]
	s_waitcnt lgkmcnt(1)
	v_mfma_f32_16x16x32_bf16 v[72:75], v[108:111], v[120:123], v[72:75]
	s_waitcnt lgkmcnt(0)
	v_mfma_f32_16x16x32_bf16 v[36:39], v[108:111], v[124:127], v[36:39]
	v_mfma_f32_16x16x32_bf16 v[76:79], v[112:115], v[92:95], v[76:79]
	v_mfma_f32_16x16x32_bf16 v[80:83], v[112:115], v[116:119], v[80:83]
	v_mfma_f32_16x16x32_bf16 v[84:87], v[112:115], v[120:123], v[84:87]
	v_mfma_f32_16x16x32_bf16 v[46:49], v[112:115], v[124:127], v[48:51]
	ds_read_b128 v[108:111], v164 offset:4096
	ds_read_b128 v[112:115], v164 offset:6144
	ds_write_b128 v128, v[10:13] offset:32768
	ds_write_b128 v128, v[14:17] offset:36864
	ds_write_b128 v128, v[18:21] offset:40960
	ds_write_b128 v128, v[22:25] offset:45056
	ds_write_b16 v130, v30 offset:49152
	ds_write_b16_d16_hi v129, v30 offset:49280
	ds_write_b16 v131, v31 offset:49152
	ds_write_b16_d16_hi v132, v31 offset:49152
	ds_write_b16 v133, v32 offset:49152
	ds_write_b16_d16_hi v134, v32 offset:49152
	ds_write_b16 v135, v33 offset:49152
	ds_write_b16_d16_hi v136, v33 offset:49152
	ds_write_b16 v137, v26 offset:49152
	ds_write_b16_d16_hi v0, v26 offset:49280
	ds_write_b16 v138, v27 offset:49152
	ds_write_b16_d16_hi v139, v27 offset:49152
	ds_write_b16 v140, v28 offset:49152
	ds_write_b16_d16_hi v141, v28 offset:49152
	ds_write_b16 v142, v29 offset:49152
	ds_write_b16_d16_hi v143, v29 offset:49152
	ds_write_b16 v144, v6 offset:49152
	ds_write_b16_d16_hi v145, v6 offset:49280
	ds_write_b16 v146, v7 offset:49152
	ds_write_b16_d16_hi v147, v7 offset:49152
	ds_write_b16 v148, v8 offset:49152
	ds_write_b16_d16_hi v149, v8 offset:49152
	ds_write_b16 v150, v9 offset:49152
	ds_write_b16_d16_hi v151, v9 offset:49152
	ds_write_b16 v152, v2 offset:49152
	ds_write_b16_d16_hi v153, v2 offset:49280
	ds_write_b16 v154, v3 offset:49152
	ds_write_b16_d16_hi v155, v3 offset:49152
	ds_write_b16 v156, v4 offset:49152
	ds_write_b16_d16_hi v157, v4 offset:49152
	ds_write_b16 v158, v5 offset:49152
	ds_write_b16_d16_hi v159, v5 offset:49152
	s_waitcnt lgkmcnt(0)
	s_barrier
	ds_read_b128 v[2:5], v160 offset:32768
	ds_read_b128 v[10:13], v162 offset:49152
	ds_read_b128 v[14:17], v160 offset:34816
	ds_read_b128 v[18:21], v162 offset:51200
	v_mfma_f32_16x16x32_bf16 v[50:53], v[112:115], v[116:119], v[52:55]
	v_lshlrev_b32_e32 v0, 6, v45
	v_lshl_or_b32 v45, v163, 2, v0
	v_mov_b32_e32 v0, v187
	s_waitcnt lgkmcnt(2)
	v_mfma_f32_16x16x32_bf16 v[22:25], v[2:5], v[10:13], v[56:59]
	ds_read_b128 v[30:33], v162 offset:53248
	s_nop 1
	ds_read_b128 v[54:57], v162 offset:55296
	v_mfma_f32_16x16x32_bf16 v[6:9], v[112:115], v[124:127], v[68:71]
	s_waitcnt lgkmcnt(2)
	v_mfma_f32_16x16x32_bf16 v[26:29], v[2:5], v[18:21], v[60:63]
	s_waitcnt lgkmcnt(1)
	v_mfma_f32_16x16x32_bf16 v[58:61], v[2:5], v[30:33], v[72:75]
	s_waitcnt lgkmcnt(0)
	v_mfma_f32_16x16x32_bf16 v[2:5], v[2:5], v[54:57], v[36:39]
	v_mfma_f32_16x16x32_bf16 v[36:39], v[14:17], v[10:13], v[76:79]
	v_mfma_f32_16x16x32_bf16 v[68:71], v[14:17], v[18:21], v[80:83]
	v_mfma_f32_16x16x32_bf16 v[72:75], v[14:17], v[30:33], v[84:87]
	v_mfma_f32_16x16x32_bf16 v[14:17], v[14:17], v[54:57], v[46:49]
	s_nop 2
	ds_read_b128 v[46:49], v160 offset:36864
	ds_read_b128 v[76:79], v160 offset:38912
	v_mfma_f32_16x16x32_bf16 v[96:99], v[108:111], v[92:95], v[96:99]
	v_mfma_f32_16x16x32_bf16 v[40:43], v[112:115], v[92:95], v[40:43]
	v_mfma_f32_16x16x32_bf16 v[100:103], v[108:111], v[116:119], v[100:103]
	v_mfma_f32_16x16x32_bf16 v[104:107], v[108:111], v[120:123], v[104:107]
	v_mfma_f32_16x16x32_bf16 v[88:91], v[108:111], v[124:127], v[88:91]
	v_mfma_f32_16x16x32_bf16 v[64:67], v[112:115], v[120:123], v[64:67]
	s_waitcnt lgkmcnt(1)
	v_mfma_f32_16x16x32_bf16 v[80:83], v[46:49], v[10:13], v[96:99]
	s_waitcnt lgkmcnt(0)
; __device__ __forceinline__ u16 f2bf(float f) { return (u16)(pack2(f, 0.f) & 0xffffu); }
; template <int NT, class VF, class RP>
; __device__ __forceinline__ void epi_staged_bf16(f32x4 (&acc)[4][NT], int r0, int c0, unsigned char* smem, VF vf, RP rowptr) {
;     ...
;   __syncthreads();
; #pragma unroll
;   for (int mi = 0; mi < 4; ++mi)
; #pragma unroll
;     for (int ni = 0; ni < NT; ++ni)
; #pragma unroll
;       for (int j = 0; j < 4; ++j) {
;         const int r = r0 + mi * 16 + j, c = c0 + ni * 16;
;         Ts[r * PITCH + c] = f2bf(vf(r, c, acc[mi][ni][j]));
;       }
;   __syncthreads();
	v_mfma_f32_16x16x32_bf16 v[10:13], v[76:79], v[10:13], v[40:43]
	s_nop 2
	ds_read_b128 v[40:43], v164 offset:32768
	v_mfma_f32_16x16x32_bf16 v[84:87], v[46:49], v[18:21], v[100:103]
	v_mfma_f32_16x16x32_bf16 v[92:95], v[46:49], v[30:33], v[104:107]
	v_mfma_f32_16x16x32_bf16 v[46:49], v[46:49], v[54:57], v[88:91]
	v_mfma_f32_16x16x32_bf16 v[18:21], v[76:79], v[18:21], v[50:53]
	v_mfma_f32_16x16x32_bf16 v[30:33], v[76:79], v[30:33], v[64:67]
	v_mfma_f32_16x16x32_bf16 v[6:9], v[76:79], v[54:57], v[6:9]
	s_nop 0
	ds_read_b128 v[50:53], v165 offset:49152
	ds_read_b128 v[54:57], v164 offset:34816
	ds_read_b128 v[62:65], v165 offset:51200
	ds_read_b128 v[76:79], v165 offset:53248
	ds_read_b128 v[88:91], v165 offset:55296
	s_waitcnt lgkmcnt(4)
	v_mfma_f32_16x16x32_bf16 v[22:25], v[40:43], v[50:53], v[22:25]
	s_waitcnt lgkmcnt(2)
	v_mfma_f32_16x16x32_bf16 v[26:29], v[40:43], v[62:65], v[26:29]
	s_waitcnt lgkmcnt(1)
	v_mfma_f32_16x16x32_bf16 v[58:61], v[40:43], v[76:79], v[58:61]
	s_waitcnt lgkmcnt(0)
	v_mfma_f32_16x16x32_bf16 v[2:5], v[40:43], v[88:91], v[2:5]
	v_mfma_f32_16x16x32_bf16 v[36:39], v[54:57], v[50:53], v[36:39]
	v_mfma_f32_16x16x32_bf16 v[40:43], v[54:57], v[62:65], v[68:71]
	s_nop 5
	v_cvt_pk_bf16_f32 v2, v2, s0
	v_mfma_f32_16x16x32_bf16 v[66:69], v[54:57], v[76:79], v[72:75]
	v_mfma_f32_16x16x32_bf16 v[14:17], v[54:57], v[88:91], v[14:17]
	ds_read_b128 v[54:57], v164 offset:36864
	s_nop 0
	ds_read_b128 v[70:73], v164 offset:38912
	s_waitcnt lgkmcnt(0)
	v_mfma_f32_16x16x32_bf16 v[80:83], v[54:57], v[50:53], v[80:83]
	s_barrier
	v_mfma_f32_16x16x32_bf16 v[10:13], v[70:73], v[50:53], v[10:13]
	v_cvt_pk_bf16_f32 v50, v22, s0
	v_lshlrev_b32_e32 v22, 1, v44
	v_lshl_or_b32 v22, v161, 7, v22
	v_mad_u64_u32 v[44:45], s[34:35], v45, s23, v[22:23]
	ds_write_b16 v44, v2 offset:96
	v_cvt_pk_bf16_f32 v2, v3, s0
	ds_write_b16 v44, v2 offset:368
	v_cvt_pk_bf16_f32 v2, v4, s0
	ds_write_b16 v44, v2 offset:640
	v_cvt_pk_bf16_f32 v2, v5, s0
	ds_write_b16 v44, v2 offset:912
	v_cvt_pk_bf16_f32 v2, v36, s0
	ds_write_b16 v44, v2 offset:4352
	v_cvt_pk_bf16_f32 v2, v37, s0
	ds_write_b16 v44, v2 offset:4624
	v_cvt_pk_bf16_f32 v2, v38, s0
	ds_write_b16 v44, v2 offset:4896
	v_cvt_pk_bf16_f32 v2, v39, s0
	ds_write_b16 v44, v2 offset:5168
	v_cvt_pk_bf16_f32 v2, v40, s0
	ds_write_b16 v44, v2 offset:4384
	v_cvt_pk_bf16_f32 v2, v41, s0
	ds_write_b16 v44, v2 offset:4656
	v_cvt_pk_bf16_f32 v2, v42, s0
	ds_write_b16 v44, v2 offset:4928
	v_cvt_pk_bf16_f32 v2, v43, s0
	ds_write_b16 v44, v2 offset:5200
	v_cvt_pk_bf16_f32 v2, v66, s0
	ds_write_b16 v44, v2 offset:4416
	v_cvt_pk_bf16_f32 v2, v67, s0
	ds_write_b16 v44, v2 offset:4688
	v_cvt_pk_bf16_f32 v2, v68, s0
	ds_write_b16 v44, v2 offset:4960
	v_cvt_pk_bf16_f32 v2, v69, s0
	ds_write_b16 v44, v2 offset:5232
	v_cvt_pk_bf16_f32 v2, v14, s0
	ds_write_b16 v44, v2 offset:4448
	v_cvt_pk_bf16_f32 v2, v15, s0
	ds_write_b16 v44, v2 offset:4720
	v_cvt_pk_bf16_f32 v2, v16, s0
	ds_write_b16 v44, v2 offset:4992
	v_cvt_pk_bf16_f32 v2, v17, s0
	v_mfma_f32_16x16x32_bf16 v[84:87], v[54:57], v[62:65], v[84:87]
	ds_write_b16 v44, v2 offset:5264
	v_cvt_pk_bf16_f32 v2, v80, s0
	ds_write_b16 v44, v2 offset:8704
	v_cvt_pk_bf16_f32 v2, v81, s0
	ds_write_b16 v44, v2 offset:8976
	v_cvt_pk_bf16_f32 v2, v82, s0
	ds_write_b16 v44, v2 offset:9248
	v_cvt_pk_bf16_f32 v2, v83, s0
	v_mfma_f32_16x16x32_bf16 v[92:95], v[54:57], v[76:79], v[92:95]
	ds_write_b16 v44, v2 offset:9520
	v_cvt_pk_bf16_f32 v2, v84, s0
	ds_write_b16 v44, v2 offset:8736
	v_cvt_pk_bf16_f32 v2, v85, s0
	ds_write_b16 v44, v2 offset:9008
	v_cvt_pk_bf16_f32 v2, v86, s0
	ds_write_b16 v44, v2 offset:9280
	v_cvt_pk_bf16_f32 v2, v87, s0
	v_mfma_f32_16x16x32_bf16 v[46:49], v[54:57], v[88:91], v[46:49]
	ds_write_b16 v44, v2 offset:9552
	v_cvt_pk_bf16_f32 v2, v92, s0
	ds_write_b16 v44, v2 offset:8768
	v_cvt_pk_bf16_f32 v2, v93, s0
	ds_write_b16 v44, v2 offset:9040
	v_cvt_pk_bf16_f32 v2, v94, s0
	ds_write_b16 v44, v2 offset:9312
	v_cvt_pk_bf16_f32 v2, v95, s0
	ds_write_b16 v44, v2 offset:9584
	v_cvt_pk_bf16_f32 v2, v46, s0
	ds_write_b16 v44, v2 offset:8800
	v_cvt_pk_bf16_f32 v2, v47, s0
	ds_write_b16 v44, v2 offset:9072
	v_cvt_pk_bf16_f32 v2, v48, s0
	ds_write_b16 v44, v2 offset:9344
	v_cvt_pk_bf16_f32 v2, v49, s0
	v_mfma_f32_16x16x32_bf16 v[18:21], v[70:73], v[62:65], v[18:21]
	ds_write_b16 v44, v2 offset:9616
	v_cvt_pk_bf16_f32 v2, v10, s0
	ds_write_b16 v44, v2 offset:13056
	v_cvt_pk_bf16_f32 v2, v11, s0
	ds_write_b16 v44, v2 offset:13328
	v_cvt_pk_bf16_f32 v2, v12, s0
	ds_write_b16 v44, v2 offset:13600
	v_cvt_pk_bf16_f32 v2, v13, s0
	v_mfma_f32_16x16x32_bf16 v[30:33], v[70:73], v[76:79], v[30:33]
	ds_write_b16 v44, v2 offset:13872
	v_cvt_pk_bf16_f32 v2, v18, s0
	v_cvt_pk_bf16_f32 v22, v23, s0
	ds_write_b16 v44, v2 offset:13088
	v_cvt_pk_bf16_f32 v2, v19, s0
	ds_write_b16 v44, v22 offset:272
	v_cvt_pk_bf16_f32 v22, v24, s0
	ds_write_b16 v44, v2 offset:13360
	v_cvt_pk_bf16_f32 v2, v20, s0
	ds_write_b16 v44, v22 offset:544
	v_cvt_pk_bf16_f32 v22, v25, s0
	ds_write_b16 v44, v2 offset:13632
	v_cvt_pk_bf16_f32 v2, v21, s0
	v_mfma_f32_16x16x32_bf16 v[6:9], v[70:73], v[88:91], v[6:9]
	ds_write_b16 v44, v22 offset:816
	v_cvt_pk_bf16_f32 v22, v26, s0
	ds_write_b16 v44, v2 offset:13904
	v_cvt_pk_bf16_f32 v2, v30, s0
	ds_write_b16 v44, v22 offset:32
	v_cvt_pk_bf16_f32 v22, v27, s0
	ds_write_b16 v44, v2 offset:13120
	v_cvt_pk_bf16_f32 v2, v31, s0
	ds_write_b16 v44, v22 offset:304
	v_cvt_pk_bf16_f32 v22, v28, s0
	ds_write_b16 v44, v2 offset:13392
	v_cvt_pk_bf16_f32 v2, v32, s0
	ds_write_b16 v44, v22 offset:576
	v_cvt_pk_bf16_f32 v22, v29, s0
	ds_write_b16 v44, v2 offset:13664
	v_cvt_pk_bf16_f32 v2, v33, s0
	ds_write_b16 v44, v22 offset:848
	v_cvt_pk_bf16_f32 v22, v58, s0
	ds_write_b16 v44, v2 offset:13936
	v_cvt_pk_bf16_f32 v2, v6, s0
	ds_write_b16 v44, v22 offset:64
	v_cvt_pk_bf16_f32 v22, v59, s0
	ds_write_b16 v44, v2 offset:13152
	v_cvt_pk_bf16_f32 v2, v7, s0
	ds_write_b16 v44, v22 offset:336
	v_cvt_pk_bf16_f32 v22, v60, s0
	ds_write_b16 v44, v2 offset:13424
	v_cvt_pk_bf16_f32 v2, v8, s0
	ds_write_b16 v44, v22 offset:608
	v_cvt_pk_bf16_f32 v22, v61, s0
	ds_write_b16 v44, v2 offset:13696
	v_cvt_pk_bf16_f32 v2, v9, s0
	ds_write_b16 v44, v50
	ds_write_b16 v44, v22 offset:880
	ds_write_b16 v44, v2 offset:13968
	s_waitcnt lgkmcnt(0)
	s_barrier
; template <int NT, class VF, class RP>
; __device__ __forceinline__ void epi_staged_bf16(f32x4 (&acc)[4][NT], int r0, int c0, unsigned char* smem, VF vf, RP rowptr) {
;     ...
; #pragma unroll
;   for (int i = 0; i < CPR / 2; ++i) {
;     const int c = t + 256 * i, row = c / CPR, ch = c % CPR;
;     u16* d = rowptr(row);
;     if (d) *(u32x4*)(d + ch * 8) = *(const u32x4*)(Ts + row * PITCH + ch * 8);
;   }
; __device__ __forceinline__ void phase_mix_a(const Params& p, int l, bool last, unsigned char* smem) {
;     ...
;         auto rp = [&](int m) -> u16* { const int rip = m >> 6, k2 = m & 63; return p.PF + ((size_t)((b * 64 + k2) * 2 + rip) * 128 + n1) * 256 + nh * 128; };
	global_load_dwordx2 v[2:3], v[34:35], off offset:320
	v_ashrrev_i32_e32 v4, 31, v0
	v_lshrrev_b32_e32 v4, 28, v4
	v_add_u32_e32 v4, v0, v4
	v_ashrrev_i32_e32 v6, 4, v4
	v_lshlrev_b32_e32 v5, 1, v6
	v_ashrrev_i32_e32 v4, 10, v4
	v_and_b32_e32 v5, 0x7e, v5
	v_add3_u32 v4, v4, s19, v5
	v_ashrrev_i32_e32 v5, 31, v4
	v_lshlrev_b64 v[4:5], 16, v[4:5]
	s_waitcnt vmcnt(0) lgkmcnt(0)
	v_lshl_add_u64 v[4:5], v[2:3], 0, v[4:5]
	v_lshl_add_u64 v[4:5], v[4:5], 0, s[94:95]
	v_cmp_ne_u64_e32 vcc, 0, v[4:5]
	s_and_saveexec_b64 s[4:5], vcc
	s_cbranch_execz .LBB0_610
	v_lshlrev_b32_e32 v2, 4, v6
	v_sub_u32_e32 v10, v0, v2
	v_mul_lo_u32 v2, v6, s23
	v_lshl_add_u32 v2, v10, 4, v2
	ds_read_b128 v[6:9], v2
	v_lshl_add_u64 v[2:3], v[4:5], 0, s[0:1]
	v_lshlrev_b32_e32 v4, 3, v10
	v_ashrrev_i32_e32 v5, 31, v4
	v_lshl_add_u64 v[2:3], v[4:5], 1, v[2:3]
	s_waitcnt lgkmcnt(0)
	global_store_dwordx4 v[2:3], v[6:9], off
	v_mov_b64_e32 v[2:3], s[40:41]
	global_load_dwordx2 v[2:3], v[2:3], off offset:320
.LBB0_610:
	s_or_b64 exec, exec, s[4:5]
	v_add_u32_e32 v6, 0x100, v0
	v_ashrrev_i32_e32 v4, 31, v6
	v_lshrrev_b32_e32 v4, 28, v4
	v_add_u32_e32 v4, v6, v4
	v_ashrrev_i32_e32 v7, 4, v4
	v_lshlrev_b32_e32 v5, 1, v7
	v_ashrrev_i32_e32 v4, 10, v4
	v_and_b32_e32 v5, 0x7e, v5
	v_add3_u32 v4, v4, s19, v5
	v_ashrrev_i32_e32 v5, 31, v4
	v_lshlrev_b64 v[4:5], 16, v[4:5]
	s_waitcnt vmcnt(0) lgkmcnt(0)
	v_lshl_add_u64 v[4:5], v[2:3], 0, v[4:5]
	v_lshl_add_u64 v[4:5], v[4:5], 0, s[94:95]
	v_cmp_ne_u64_e32 vcc, 0, v[4:5]
	s_and_saveexec_b64 s[4:5], vcc
	s_cbranch_execz .LBB0_612
	v_lshlrev_b32_e32 v2, 4, v7
	v_sub_u32_e32 v10, v6, v2
	v_mul_lo_u32 v2, v7, s23
	v_lshl_add_u32 v2, v10, 4, v2
	ds_read_b128 v[6:9], v2
	s_mov_b32 s1, s95
	v_lshl_add_u64 v[2:3], v[4:5], 0, s[0:1]
	v_lshlrev_b32_e32 v4, 3, v10
	v_ashrrev_i32_e32 v5, 31, v4
	v_lshl_add_u64 v[2:3], v[4:5], 1, v[2:3]
	s_waitcnt lgkmcnt(0)
	global_store_dwordx4 v[2:3], v[6:9], off
	v_mov_b64_e32 v[2:3], s[40:41]
	global_load_dwordx2 v[2:3], v[2:3], off offset:320
.LBB0_612:
	s_or_b64 exec, exec, s[4:5]
	v_add_u32_e32 v6, 0x200, v0
	v_ashrrev_i32_e32 v4, 31, v6
	v_lshrrev_b32_e32 v4, 28, v4
	v_add_u32_e32 v4, v6, v4
	v_ashrrev_i32_e32 v7, 4, v4
	v_lshlrev_b32_e32 v5, 1, v7
	v_ashrrev_i32_e32 v4, 10, v4
	v_and_b32_e32 v5, 0x7e, v5
	v_add3_u32 v4, v4, s19, v5
	v_ashrrev_i32_e32 v5, 31, v4
	v_lshlrev_b64 v[4:5], 16, v[4:5]
	s_waitcnt vmcnt(0) lgkmcnt(0)
	v_lshl_add_u64 v[4:5], v[2:3], 0, v[4:5]
	v_lshl_add_u64 v[4:5], v[4:5], 0, s[94:95]
	v_cmp_ne_u64_e32 vcc, 0, v[4:5]
	s_and_saveexec_b64 s[4:5], vcc
	s_cbranch_execz .LBB0_614
	v_lshlrev_b32_e32 v2, 4, v7
	v_sub_u32_e32 v10, v6, v2
	v_mul_lo_u32 v2, v7, s23
	v_lshl_add_u32 v2, v10, 4, v2
	ds_read_b128 v[6:9], v2
	s_mov_b32 s1, s95
	v_lshl_add_u64 v[2:3], v[4:5], 0, s[0:1]
	v_lshlrev_b32_e32 v4, 3, v10
	v_ashrrev_i32_e32 v5, 31, v4
	v_lshl_add_u64 v[2:3], v[4:5], 1, v[2:3]
	s_waitcnt lgkmcnt(0)
	global_store_dwordx4 v[2:3], v[6:9], off
	v_mov_b64_e32 v[2:3], s[40:41]
	global_load_dwordx2 v[2:3], v[2:3], off offset:320
.LBB0_614:
	s_or_b64 exec, exec, s[4:5]
	v_add_u32_e32 v6, 0x300, v0
	v_ashrrev_i32_e32 v4, 31, v6
	v_lshrrev_b32_e32 v4, 28, v4
	v_add_u32_e32 v4, v6, v4
	v_ashrrev_i32_e32 v7, 4, v4
	v_lshlrev_b32_e32 v5, 1, v7
	v_ashrrev_i32_e32 v4, 10, v4
	v_and_b32_e32 v5, 0x7e, v5
	v_add3_u32 v4, v4, s19, v5
	v_ashrrev_i32_e32 v5, 31, v4
	v_lshlrev_b64 v[4:5], 16, v[4:5]
	s_waitcnt vmcnt(0) lgkmcnt(0)
	v_lshl_add_u64 v[4:5], v[2:3], 0, v[4:5]
	v_lshl_add_u64 v[4:5], v[4:5], 0, s[94:95]
	v_cmp_ne_u64_e32 vcc, 0, v[4:5]
	s_and_saveexec_b64 s[4:5], vcc
	s_cbranch_execz .LBB0_616
	v_lshlrev_b32_e32 v2, 4, v7
	v_sub_u32_e32 v10, v6, v2
	v_mul_lo_u32 v2, v7, s23
	v_lshl_add_u32 v2, v10, 4, v2
	ds_read_b128 v[6:9], v2
	s_mov_b32 s1, s95
	v_lshl_add_u64 v[2:3], v[4:5], 0, s[0:1]
	v_lshlrev_b32_e32 v4, 3, v10
	v_ashrrev_i32_e32 v5, 31, v4
	v_lshl_add_u64 v[2:3], v[4:5], 1, v[2:3]
	s_waitcnt lgkmcnt(0)
	global_store_dwordx4 v[2:3], v[6:9], off
	v_mov_b64_e32 v[2:3], s[40:41]
	global_load_dwordx2 v[2:3], v[2:3], off offset:320
; template <int NT, class VF, class RP>
; __device__ __forceinline__ void epi_staged_bf16(f32x4 (&acc)[4][NT], int r0, int c0, unsigned char* smem, VF vf, RP rowptr) {
;     ...
; #pragma unroll
;   for (int i = 0; i < CPR / 2; ++i) {
;     const int c = t + 256 * i, row = c / CPR, ch = c % CPR;
;     u16* d = rowptr(row);
;     if (d) *(u32x4*)(d + ch * 8) = *(const u32x4*)(Ts + row * PITCH + ch * 8);
;   }
; __device__ __forceinline__ void phase_mix_a(const Params& p, int l, bool last, unsigned char* smem) {
;     ...
;         auto rp = [&](int m) -> u16* { const int rip = m >> 6, k2 = m & 63; return p.PF + ((size_t)((b * 64 + k2) * 2 + rip) * 128 + n1) * 256 + nh * 128; };
.LBB0_616:
	s_or_b64 exec, exec, s[4:5]
	v_add_u32_e32 v6, 0x400, v0
	v_ashrrev_i32_e32 v4, 31, v6
	v_lshrrev_b32_e32 v4, 28, v4
	v_add_u32_e32 v4, v6, v4
	v_ashrrev_i32_e32 v7, 4, v4
	v_lshlrev_b32_e32 v5, 1, v7
	v_ashrrev_i32_e32 v4, 10, v4
	v_and_b32_e32 v5, 0x7e, v5
	v_add3_u32 v4, v4, s19, v5
	v_ashrrev_i32_e32 v5, 31, v4
	v_lshlrev_b64 v[4:5], 16, v[4:5]
	s_waitcnt vmcnt(0) lgkmcnt(0)
	v_lshl_add_u64 v[4:5], v[2:3], 0, v[4:5]
	v_lshl_add_u64 v[4:5], v[4:5], 0, s[94:95]
	v_cmp_ne_u64_e32 vcc, 0, v[4:5]
	s_and_saveexec_b64 s[4:5], vcc
	s_cbranch_execz .LBB0_618
	v_lshlrev_b32_e32 v2, 4, v7
	v_sub_u32_e32 v10, v6, v2
	v_mul_lo_u32 v2, v7, s23
	v_lshl_add_u32 v2, v10, 4, v2
	ds_read_b128 v[6:9], v2
	s_mov_b32 s1, s95
	v_lshl_add_u64 v[2:3], v[4:5], 0, s[0:1]
	v_lshlrev_b32_e32 v4, 3, v10
	v_ashrrev_i32_e32 v5, 31, v4
	v_lshl_add_u64 v[2:3], v[4:5], 1, v[2:3]
	s_waitcnt lgkmcnt(0)
	global_store_dwordx4 v[2:3], v[6:9], off
	v_mov_b64_e32 v[2:3], s[40:41]
	global_load_dwordx2 v[2:3], v[2:3], off offset:320
.LBB0_618:
	s_or_b64 exec, exec, s[4:5]
	v_add_u32_e32 v6, 0x500, v0
	v_ashrrev_i32_e32 v4, 31, v6
	v_lshrrev_b32_e32 v4, 28, v4
	v_add_u32_e32 v4, v6, v4
	v_ashrrev_i32_e32 v7, 4, v4
	v_lshlrev_b32_e32 v5, 1, v7
	v_ashrrev_i32_e32 v4, 10, v4
	v_and_b32_e32 v5, 0x7e, v5
	v_add3_u32 v4, v4, s19, v5
	v_ashrrev_i32_e32 v5, 31, v4
	v_lshlrev_b64 v[4:5], 16, v[4:5]
	s_waitcnt vmcnt(0) lgkmcnt(0)
	v_lshl_add_u64 v[4:5], v[2:3], 0, v[4:5]
	v_lshl_add_u64 v[4:5], v[4:5], 0, s[94:95]
	v_cmp_ne_u64_e32 vcc, 0, v[4:5]
	s_and_saveexec_b64 s[4:5], vcc
	s_cbranch_execz .LBB0_620
	v_lshlrev_b32_e32 v2, 4, v7
	v_sub_u32_e32 v10, v6, v2
	v_mul_lo_u32 v2, v7, s23
	v_lshl_add_u32 v2, v10, 4, v2
	ds_read_b128 v[6:9], v2
	s_mov_b32 s1, s95
	v_lshl_add_u64 v[2:3], v[4:5], 0, s[0:1]
	v_lshlrev_b32_e32 v4, 3, v10
	v_ashrrev_i32_e32 v5, 31, v4
	v_lshl_add_u64 v[2:3], v[4:5], 1, v[2:3]
	s_waitcnt lgkmcnt(0)
	global_store_dwordx4 v[2:3], v[6:9], off
	v_mov_b64_e32 v[2:3], s[40:41]
	global_load_dwordx2 v[2:3], v[2:3], off offset:320
.LBB0_620:
	s_or_b64 exec, exec, s[4:5]
	v_add_u32_e32 v6, 0x600, v0
	v_ashrrev_i32_e32 v4, 31, v6
	v_lshrrev_b32_e32 v4, 28, v4
	v_add_u32_e32 v4, v6, v4
	v_ashrrev_i32_e32 v7, 4, v4
	v_lshlrev_b32_e32 v5, 1, v7
	v_ashrrev_i32_e32 v4, 10, v4
	v_and_b32_e32 v5, 0x7e, v5
	v_add3_u32 v4, v4, s19, v5
	v_ashrrev_i32_e32 v5, 31, v4
	v_lshlrev_b64 v[4:5], 16, v[4:5]
	s_waitcnt vmcnt(0) lgkmcnt(0)
	v_lshl_add_u64 v[4:5], v[2:3], 0, v[4:5]
	v_lshl_add_u64 v[4:5], v[4:5], 0, s[94:95]
	v_cmp_ne_u64_e32 vcc, 0, v[4:5]
	s_and_saveexec_b64 s[4:5], vcc
	s_cbranch_execz .LBB0_622
	v_lshlrev_b32_e32 v2, 4, v7
	v_sub_u32_e32 v10, v6, v2
	v_mul_lo_u32 v2, v7, s23
	v_lshl_add_u32 v2, v10, 4, v2
	ds_read_b128 v[6:9], v2
	s_mov_b32 s1, s95
	v_lshl_add_u64 v[2:3], v[4:5], 0, s[0:1]
	v_lshlrev_b32_e32 v4, 3, v10
	v_ashrrev_i32_e32 v5, 31, v4
	v_lshl_add_u64 v[2:3], v[4:5], 1, v[2:3]
	s_waitcnt lgkmcnt(0)
	global_store_dwordx4 v[2:3], v[6:9], off
	v_mov_b64_e32 v[2:3], s[40:41]
	global_load_dwordx2 v[2:3], v[2:3], off offset:320
.LBB0_622:
	s_or_b64 exec, exec, s[4:5]
	v_add_u32_e32 v0, 0x700, v0
	v_ashrrev_i32_e32 v4, 31, v0
	v_lshrrev_b32_e32 v4, 28, v4
	v_add_u32_e32 v5, v0, v4
	v_ashrrev_i32_e32 v4, 4, v5
	v_lshlrev_b32_e32 v6, 1, v4
	v_ashrrev_i32_e32 v5, 10, v5
	v_and_b32_e32 v6, 0x7e, v6
	v_add3_u32 v6, v5, s19, v6
	v_ashrrev_i32_e32 v7, 31, v6
	v_lshlrev_b64 v[6:7], 16, v[6:7]
	s_waitcnt vmcnt(0) lgkmcnt(0)
	v_lshl_add_u64 v[2:3], v[2:3], 0, v[6:7]
	v_lshl_add_u64 v[2:3], v[2:3], 0, s[94:95]
	v_cmp_ne_u64_e32 vcc, 0, v[2:3]
	s_and_saveexec_b64 s[4:5], vcc
	s_cbranch_execz .LBB0_607
	v_lshlrev_b32_e32 v5, 4, v4
	v_sub_u32_e32 v0, v0, v5
	v_mul_lo_u32 v4, v4, s23
	v_lshl_add_u32 v4, v0, 4, v4
	ds_read_b128 v[4:7], v4
	s_mov_b32 s1, s95
	v_lshlrev_b32_e32 v8, 3, v0
	v_lshl_add_u64 v[2:3], v[2:3], 0, s[0:1]
	v_ashrrev_i32_e32 v9, 31, v8
	v_lshl_add_u64 v[2:3], v[8:9], 1, v[2:3]
	s_waitcnt lgkmcnt(0)
	global_store_dwordx4 v[2:3], v[4:7], off
	s_branch .LBB0_607

; __device__ __forceinline__ u16 f2bf(float f) { return (u16)(pack2(f, 0.f) & 0xffffu); }
; __device__ __forceinline__ int tid_() { int t = threadIdx.x; asm volatile("" : "+v"(t)); return t; }
; __device__ __forceinline__ int bid_() { int b = blockIdx.x; asm volatile("" : "+s"(b)); return b; }
; template <int NT, bool BKN, bool MASK = false, bool ROWSS = false, class Epi> ...
;     ...
;   const int t = tid_(), lane = t & 63, wid = t >> 6, wr = wid >> 1, wc = wid & 1, l16 = lane & 15, quad = lane >> 4;
;   const u16* ap[4];
;   const u16* bp[NT];
;   unsigned amask = 0u;
; #pragma unroll
;   for (int i = 0; i < 4; ++i) {
;     const int row = (t >> 3) + 32 * i;
;     const bool v = MASK ? (row < mvalid) : true;
;     amask |= v ? (1u << i) : 0u;
;     int r = v ? row : 0;
;     if (arows) r = arows[r];
;     ap[i] = A + (size_t)r * lda + (t & 7) * 8;
;   }
; #pragma unroll
;   for (int i = 0; i < NT; ++i) {
;     if (!BKN) bp[i] = B + (size_t)((t >> 3) + 32 * i) * ldb + (t & 7) * 8;
;     else { const int c = t + 256 * i; bp[i] = B + (size_t)(c / CPR) * ldb + (c % CPR) * 8; }
;   }
;   const size_t bstep = BKN ? (size_t)64 * ldb : (size_t)64;
;   int nmi = 4;
;   if (MASK) { nmi = (mvalid - wr * 64 + 15) >> 4; nmi = nmi < 0 ? 0 : (nmi > 4 ? 4 : nmi); nmi = __builtin_amdgcn_readfirstlane(nmi); }
;   u32x4 ra0[4], rb0[NT], ra1[4], rb1[NT];
; __device__ __forceinline__ void phase_mix_a(const Params& p, int l, bool last, unsigned char* smem) {
;     ...
;   if (!last) {
;     for (int t = bid_(); t < 8; t += gridDim.x) {
;       const int nh = t & 1, mt = (t >> 1) & 1, b = t >> 2;
;       auto epi = [&](f32x4(&acc)[4][4], int r0, int c0) {
; #pragma unroll
;         for (int mi = 0; mi < 4; ++mi)
; #pragma unroll
;           for (int ni = 0; ni < 4; ++ni)
; #pragma unroll
;             for (int j = 0; j < 4; ++j) {
;               const int k = mt * 128 + r0 + mi * 16 + j;
;               p.YM[(size_t)(T_LAT + b * CTX + k) * 1024 + 256 + nh * 128 + c0 + ni * 16] = f2bf(acc[mi][ni][j] * (1.f / 128.f));
;             }
;       };
;       gemm_tile<4, true>(p.Mc + (size_t)mt * 128 * 512, 512, nullptr, 128, p.GDc + (size_t)b * 2 * CTX * 256 + nh * 128, 256, 512, smem, epi);
.LBB0_627:
	s_waitcnt vmcnt(0) lgkmcnt(0)
	v_mov_b64_e32 v[2:3], s[40:41]
	global_load_dwordx2 v[50:51], v[2:3], off offset:264
	global_load_dwordx2 v[52:53], v[2:3], off offset:312
	v_mov_b32_e32 v84, v187
	s_ashr_i32 s4, s8, 2
	v_ashrrev_i32_e32 v2, 3, v84
	v_ashrrev_i32_e32 v5, 31, v84
	v_lshrrev_b32_e32 v85, 4, v84
	v_add_u32_e32 v12, 0x100, v84
	v_add_u32_e32 v13, 0x200, v84
	v_add_u32_e32 v14, 0x300, v84
	v_ashrrev_i32_e32 v3, 31, v2
	v_lshrrev_b32_e32 v5, 28, v5
	v_ashrrev_i32_e32 v6, 31, v12
	v_ashrrev_i32_e32 v7, 31, v13
	v_ashrrev_i32_e32 v8, 31, v14
	v_xor_b32_e32 v9, v85, v84
	v_lshlrev_b64 v[62:63], 10, v[2:3]
	v_add_u32_e32 v3, v84, v5
	s_lshl_b32 s0, s9, 1
	s_bfe_u32 s19, s8, 0x10001
	s_lshl_b32 s1, s8, 7
	s_ashr_i32 s5, s4, 31
	v_lshlrev_b32_e32 v4, 4, v84
	v_lshrrev_b32_e32 v5, 28, v6
	v_lshrrev_b32_e32 v6, 28, v7
	v_lshrrev_b32_e32 v7, 28, v8
	v_lshlrev_b32_e32 v8, 4, v9
	v_and_b32_e32 v9, -16, v3
	s_and_b32 s38, s0, 0x100
	s_lshl_b32 s94, s19, 17
	s_and_b32 s18, s1, 0x80
	s_lshl_b64 s[0:1], s[4:5], 18
	v_and_b32_e32 v0, 0x70, v4
	v_and_b32_e32 v4, 0xffffff80, v4
	v_ashrrev_i32_e32 v2, 4, v3
	v_add_u32_e32 v5, v12, v5
	v_sub_u32_e32 v17, v84, v9
	s_mov_b32 s43, s95
	s_lshl_b32 s42, s18, 1
	v_add_u32_e32 v15, v13, v6
	v_add_u32_e32 v16, v14, v7
	v_and_or_b32 v160, v8, s14, v4
	v_ashrrev_i32_e32 v3, 31, v2
	v_ashrrev_i32_e32 v34, 4, v5
	v_and_b32_e32 v18, -16, v5
	v_lshlrev_b32_e32 v36, 3, v17
	v_lshlrev_b64 v[64:65], 9, v[2:3]
	v_ashrrev_i32_e32 v37, 31, v36
	v_lshlrev_b64 v[66:67], 1, v[36:37]
	s_mov_b32 s5, 0x8000
	v_and_b32_e32 v3, -16, v16
	v_and_b32_e32 v37, -8, v2
	v_and_b32_e32 v92, 7, v2
	v_sub_u32_e32 v95, v14, v3
	v_lshlrev_b32_e32 v2, 5, v17
	s_waitcnt lgkmcnt(0)
	s_barrier
	v_ashrrev_i32_e32 v28, 4, v15
	v_lshlrev_b32_e32 v26, 3, v95
	v_bitop3_b32 v2, v2, v37, 32 bitop3:0x6c
	v_ashrrev_i32_e32 v29, 31, v28
	v_ashrrev_i32_e32 v27, 31, v26
	v_lshlrev_b64 v[74:75], 9, v[28:29]
	v_lshlrev_b64 v[82:83], 1, v[26:27]
	v_sub_u32_e32 v93, v12, v18
	v_ashrrev_i32_e32 v35, 31, v34
	v_lshlrev_b32_e32 v90, 3, v93
	v_lshlrev_b64 v[68:69], 9, v[34:35]
	v_ashrrev_i32_e32 v91, 31, v90
	v_lshlrev_b64 v[78:79], 1, v[90:91]
	v_ashrrev_i32_e32 v30, 4, v16
	v_ashrrev_i32_e32 v31, 31, v30
	v_lshlrev_b64 v[76:77], 9, v[30:31]
	v_lshlrev_b32_e32 v31, 9, v93
	v_and_b32_e32 v157, 15, v84
	v_bfe_u32 v156, v84, 6, 1
	v_ashrrev_i32_e32 v158, 7, v84
	v_bfe_u32 v159, v84, 4, 2
	s_waitcnt vmcnt(0)
	v_lshl_add_u64 v[4:5], v[50:51], 0, s[94:95]
	v_lshl_add_u64 v[6:7], v[52:53], 0, s[0:1]
	v_lshl_add_u64 v[6:7], v[6:7], 0, s[42:43]
	v_lshl_add_u64 v[4:5], v[4:5], 0, v[0:1]
	v_lshl_add_u64 v[130:131], v[4:5], 0, v[62:63]
	v_lshl_add_u64 v[4:5], v[6:7], 0, v[64:65]
	v_lshl_add_u64 v[132:133], v[4:5], 0, v[66:67]
	v_add_co_u32_e32 v4, vcc, s5, v130
	v_and_b32_e32 v0, -16, v15
	s_nop 0
	v_addc_co_u32_e32 v5, vcc, 0, v131, vcc
	v_add_co_u32_e32 v8, vcc, s15, v130
	v_sub_u32_e32 v94, v13, v0
	s_nop 0
	v_addc_co_u32_e32 v9, vcc, 0, v131, vcc
	v_add_co_u32_e32 v10, vcc, s55, v130
	v_lshlrev_b32_e32 v0, 9, v17
	global_load_dwordx4 v[38:41], v[130:131], off
	v_addc_co_u32_e32 v11, vcc, 0, v131, vcc
	global_load_dwordx4 v[42:45], v[4:5], off
	global_load_dwordx4 v[46:49], v[8:9], off
	global_load_dwordx4 v[54:57], v[10:11], off
	global_load_dwordx4 v[58:61], v[132:133], off
	v_or_b32_e32 v3, v92, v0
	v_or_b32_e32 v4, 2, v36
	v_or_b32_e32 v5, 3, v36
	v_add_u32_e32 v8, v2, v0
	v_add_lshl_u32 v0, v3, v2, 1
	v_lshlrev_b32_e32 v2, 6, v4
	v_lshlrev_b32_e32 v3, 2, v4
	v_lshlrev_b32_e32 v4, 2, v5
	v_lshlrev_b32_e32 v29, 6, v5
	v_and_b32_e32 v27, 40, v4
	v_xad_u32 v27, v27, v37, v29
	v_or_b32_e32 v27, v27, v92
	v_lshlrev_b32_e32 v163, 1, v27
	v_or_b32_e32 v27, 4, v36
	v_lshlrev_b32_e32 v29, 6, v27
	v_lshlrev_b32_e32 v27, 2, v27
	v_and_b32_e32 v27, 48, v27
	v_and_b32_e32 v3, 40, v3
	v_xad_u32 v27, v27, v37, v29
	v_xad_u32 v2, v3, v37, v2
	v_or_b32_e32 v27, v27, v92
	v_or_b32_e32 v2, v2, v92
	v_lshlrev_b32_e32 v164, 1, v27
	v_or_b32_e32 v27, 5, v36
	v_lshlrev_b32_e32 v32, 3, v94
	v_lshlrev_b32_e32 v162, 1, v2
	v_lshl_add_u64 v[2:3], v[6:7], 0, v[68:69]
	v_lshlrev_b32_e32 v29, 6, v27
	v_lshlrev_b32_e32 v27, 2, v27
	v_ashrrev_i32_e32 v33, 31, v32
	v_or_b32_e32 v5, v8, v92
	v_lshl_add_u64 v[134:135], v[2:3], 0, v[78:79]
	v_add_co_u32_e32 v2, vcc, s5, v132
	v_and_b32_e32 v27, 48, v27
	v_lshlrev_b64 v[80:81], 1, v[32:33]
	v_lshlrev_b32_e32 v161, 1, v5
	v_lshl_add_u64 v[4:5], v[6:7], 0, v[74:75]
	v_addc_co_u32_e32 v3, vcc, 0, v133, vcc
	v_xad_u32 v27, v27, v37, v29
	v_lshl_add_u64 v[142:143], v[4:5], 0, v[80:81]
	v_add_co_u32_e32 v4, vcc, s5, v134
	v_or_b32_e32 v27, v27, v92
	v_lshl_add_u64 v[6:7], v[6:7], 0, v[76:77]
	v_addc_co_u32_e32 v5, vcc, 0, v135, vcc
	v_lshlrev_b32_e32 v165, 1, v27
	v_or_b32_e32 v27, 6, v36
	global_load_dwordx4 v[70:73], v[134:135], off
	v_lshl_add_u64 v[144:145], v[6:7], 0, v[82:83]
	v_add_co_u32_e32 v6, vcc, s5, v142
	v_lshlrev_b32_e32 v29, 6, v27
	v_lshlrev_b32_e32 v27, 2, v27
	v_addc_co_u32_e32 v7, vcc, 0, v143, vcc
	v_and_b32_e32 v27, 56, v27
	v_add_co_u32_e32 v8, vcc, s5, v144
	v_xad_u32 v27, v27, v37, v29
	s_nop 0
	v_addc_co_u32_e32 v9, vcc, 0, v145, vcc
	v_or_b32_e32 v27, v27, v92
	global_load_dwordx4 v[14:17], v[130:131], off offset:128
	global_load_dwordx4 v[86:89], v[142:143], off
	global_load_dwordx4 v[22:25], v[144:145], off
	global_load_dwordx4 v[18:21], v[2:3], off
	global_load_dwordx4 v[10:13], v[4:5], off
	s_nop 0
	global_load_dwordx4 v[2:5], v[6:7], off
	s_nop 0
	global_load_dwordx4 v[6:9], v[8:9], off
	v_lshlrev_b32_e32 v166, 1, v27
	v_or_b32_e32 v27, 7, v36
	v_lshlrev_b32_e32 v29, 6, v27
	v_lshlrev_b32_e32 v27, 2, v27
	v_and_b32_e32 v27, 56, v27
	v_xad_u32 v27, v27, v37, v29
	v_or_b32_e32 v27, v27, v92
	v_lshlrev_b32_e32 v167, 1, v27
	v_and_b32_e32 v27, -8, v34
	v_lshlrev_b32_e32 v33, 5, v93
	v_and_b32_e32 v29, 7, v34
	v_bitop3_b32 v33, v33, v27, 32 bitop3:0x6c
	v_add_u32_e32 v34, v33, v31
	v_or_b32_e32 v31, v29, v31
	v_add_lshl_u32 v168, v31, v33, 1
	v_or_b32_e32 v31, 2, v90
	v_lshlrev_b32_e32 v33, 6, v31
	v_lshlrev_b32_e32 v31, 2, v31
	v_and_b32_e32 v31, 40, v31
	v_xad_u32 v31, v31, v27, v33
	v_or_b32_e32 v31, v31, v29
	v_lshlrev_b32_e32 v170, 1, v31
	v_or_b32_e32 v31, 3, v90
	v_lshlrev_b32_e32 v33, 6, v31
	v_lshlrev_b32_e32 v31, 2, v31
	v_and_b32_e32 v31, 40, v31
	v_xad_u32 v31, v31, v27, v33
	v_or_b32_e32 v31, v31, v29
	v_lshlrev_b32_e32 v171, 1, v31
	v_or_b32_e32 v31, 4, v90
	v_lshlrev_b32_e32 v33, 6, v31
	v_lshlrev_b32_e32 v31, 2, v31
	v_and_b32_e32 v31, 48, v31
	v_xad_u32 v31, v31, v27, v33
	v_or_b32_e32 v31, v31, v29
	v_lshlrev_b32_e32 v172, 1, v31
	v_or_b32_e32 v31, 5, v90
	v_lshlrev_b32_e32 v33, 6, v31
	v_lshlrev_b32_e32 v31, 2, v31
	v_and_b32_e32 v31, 48, v31
	v_xad_u32 v31, v31, v27, v33
	v_or_b32_e32 v31, v31, v29
	v_lshlrev_b32_e32 v173, 1, v31
	v_or_b32_e32 v31, 6, v90
	v_lshlrev_b32_e32 v33, 6, v31
	v_lshlrev_b32_e32 v31, 2, v31
	v_and_b32_e32 v31, 56, v31
	v_xad_u32 v31, v31, v27, v33
	v_or_b32_e32 v31, v31, v29
	v_lshlrev_b32_e32 v174, 1, v31
	v_or_b32_e32 v31, 7, v90
	v_lshlrev_b32_e32 v33, 6, v31
	v_lshlrev_b32_e32 v31, 2, v31
	v_and_b32_e32 v31, 56, v31
	v_xad_u32 v27, v31, v27, v33
	v_or_b32_e32 v27, v27, v29
	v_lshlrev_b32_e32 v175, 1, v27
	v_and_b32_e32 v27, -8, v28
	v_lshlrev_b32_e32 v31, 5, v94
	v_or_b32_e32 v34, v34, v29
	v_and_b32_e32 v28, 7, v28
	v_lshlrev_b32_e32 v29, 9, v94
	v_bitop3_b32 v31, v31, v27, 32 bitop3:0x6c
	v_add_u32_e32 v33, v31, v29
	v_or_b32_e32 v29, v28, v29
	v_add_lshl_u32 v177, v29, v31, 1
	v_or_b32_e32 v29, 2, v32
	v_lshlrev_b32_e32 v31, 6, v29
	v_lshlrev_b32_e32 v29, 2, v29
	v_and_b32_e32 v29, 40, v29
	v_xad_u32 v29, v29, v27, v31
	v_or_b32_e32 v29, v29, v28
	v_lshlrev_b32_e32 v178, 1, v29
	v_or_b32_e32 v29, 3, v32
	v_lshlrev_b32_e32 v31, 6, v29
	v_lshlrev_b32_e32 v29, 2, v29
	v_and_b32_e32 v29, 40, v29
	v_xad_u32 v29, v29, v27, v31
	v_or_b32_e32 v29, v29, v28
	v_lshlrev_b32_e32 v179, 1, v29
	v_or_b32_e32 v29, 4, v32
	v_lshlrev_b32_e32 v31, 6, v29
	v_lshlrev_b32_e32 v29, 2, v29
	v_and_b32_e32 v29, 48, v29
	v_xad_u32 v29, v29, v27, v31
	v_or_b32_e32 v29, v29, v28
	v_lshlrev_b32_e32 v180, 1, v29
	v_or_b32_e32 v29, 5, v32
	v_lshlrev_b32_e32 v31, 6, v29
	v_lshlrev_b32_e32 v29, 2, v29
	v_and_b32_e32 v29, 48, v29
	v_xad_u32 v29, v29, v27, v31
	v_or_b32_e32 v29, v29, v28
	v_lshlrev_b32_e32 v181, 1, v29
	v_or_b32_e32 v29, 6, v32
	v_lshlrev_b32_e32 v31, 6, v29
	v_lshlrev_b32_e32 v29, 2, v29
	v_and_b32_e32 v29, 56, v29
	v_xad_u32 v29, v29, v27, v31
	v_or_b32_e32 v29, v29, v28
	v_lshlrev_b32_e32 v182, 1, v29
	v_or_b32_e32 v29, 7, v32
	v_lshlrev_b32_e32 v31, 6, v29
	v_lshlrev_b32_e32 v29, 2, v29
	v_and_b32_e32 v29, 56, v29
	v_xad_u32 v27, v29, v27, v31
	v_or_b32_e32 v27, v27, v28
	v_or_b32_e32 v33, v33, v28
	v_lshlrev_b32_e32 v183, 1, v27
	v_and_b32_e32 v27, -8, v30
	v_and_b32_e32 v28, 7, v30
	v_lshlrev_b32_e32 v30, 5, v95
	v_lshlrev_b32_e32 v29, 9, v95
	v_bitop3_b32 v30, v30, v27, 32 bitop3:0x6c
	v_add_u32_e32 v31, v30, v29
	v_or_b32_e32 v31, v31, v28
	v_or_b32_e32 v29, v28, v29
	v_lshlrev_b32_e32 v169, 1, v34
	v_lshlrev_b32_e32 v176, 1, v33
	v_lshlrev_b32_e32 v184, 1, v31
	v_add_lshl_u32 v185, v29, v30, 1
	s_waitcnt vmcnt(0) lgkmcnt(0)
	ds_write_b128 v160, v[38:41]
	ds_write_b128 v160, v[42:45] offset:4096
	ds_write_b128 v160, v[46:49] offset:8192
	ds_write_b128 v160, v[54:57] offset:12288
	ds_write_b16 v161, v58 offset:16384
	ds_write_b16_d16_hi v0, v58 offset:16512
	ds_write_b16 v162, v59 offset:16384
	ds_write_b16_d16_hi v163, v59 offset:16384
	ds_write_b16 v164, v60 offset:16384
	ds_write_b16_d16_hi v165, v60 offset:16384
	ds_write_b16 v166, v61 offset:16384
	ds_write_b16_d16_hi v167, v61 offset:16384
	ds_write_b16 v169, v70 offset:16384
	ds_write_b16_d16_hi v168, v70 offset:16512
	ds_write_b16 v170, v71 offset:16384
	ds_write_b16_d16_hi v171, v71 offset:16384
	ds_write_b16 v172, v72 offset:16384
	ds_write_b16_d16_hi v173, v72 offset:16384
	ds_write_b16 v174, v73 offset:16384
	ds_write_b16_d16_hi v175, v73 offset:16384
	ds_write_b16 v176, v86 offset:16384
	ds_write_b16_d16_hi v177, v86 offset:16512
	ds_write_b16 v178, v87 offset:16384
	ds_write_b16_d16_hi v179, v87 offset:16384
	ds_write_b16 v180, v88 offset:16384
	ds_write_b16_d16_hi v181, v88 offset:16384
	ds_write_b16 v182, v89 offset:16384
	ds_write_b16_d16_hi v183, v89 offset:16384
	ds_write_b16 v184, v22 offset:16384
	ds_write_b16_d16_hi v185, v22 offset:16512
	v_or_b32_e32 v22, 2, v26
	v_lshlrev_b32_e32 v29, 6, v22
	v_lshlrev_b32_e32 v22, 2, v22
	v_and_b32_e32 v22, 40, v22
	v_xad_u32 v22, v22, v27, v29
	v_or_b32_e32 v22, v22, v28
	v_lshlrev_b32_e32 v188, 1, v22
	v_or_b32_e32 v22, 3, v26
	v_lshlrev_b32_e32 v29, 6, v22
	v_lshlrev_b32_e32 v22, 2, v22
	v_and_b32_e32 v22, 40, v22
	v_xad_u32 v22, v22, v27, v29
	v_or_b32_e32 v22, v22, v28
	v_lshlrev_b32_e32 v189, 1, v22
	v_or_b32_e32 v22, 4, v26
	ds_write_b16 v188, v23 offset:16384
	ds_write_b16_d16_hi v189, v23 offset:16384
	v_lshlrev_b32_e32 v23, 6, v22
	v_lshlrev_b32_e32 v22, 2, v22
	v_and_b32_e32 v22, 48, v22
	v_xad_u32 v22, v22, v27, v23
	v_or_b32_e32 v22, v22, v28
	v_lshlrev_b32_e32 v190, 1, v22
	v_or_b32_e32 v22, 5, v26
	v_lshlrev_b32_e32 v23, 6, v22
	v_lshlrev_b32_e32 v22, 2, v22
	v_and_b32_e32 v22, 48, v22
	v_xad_u32 v22, v22, v27, v23
	v_or_b32_e32 v22, v22, v28
	v_lshlrev_b32_e32 v191, 1, v22
; template <int NT, bool BKN, bool MASK = false, bool ROWSS = false, class Epi> ...
;     ...
;   float ss_[4] = {0.f, 0.f, 0.f, 0.f};
;   int stk_ = 0;
;   f32x4 acc[4][NT];
; #pragma unroll
;   for (int i = 0; i < 4; ++i)
; #pragma unroll
;     for (int j = 0; j < NT; ++j) acc[i][j] = (f32x4){0.f, 0.f, 0.f, 0.f};
;   const int nk = K >> 6;
;   const int nkm1 = nk - 1;
;   __syncthreads();
;   GEMM_LOAD(ra0, rb0, 0);
;   GEMM_LOAD(ra1, rb1, 1);
;   GEMM_STORE(ra0, rb0, 0);
;   GEMM_LOAD(ra0, rb0, (2 < nkm1 ? 2 : nkm1));
;   __syncthreads();
;   for (int kt = 0; kt < nk - 2; kt += 2) {
;     GEMM_COMPUTE(0);
;     GEMM_STORE(ra1, rb1, 1);
;     GEMM_LOAD(ra1, rb1, kt + 3);
; __device__ __forceinline__ void phase_mix_a(const Params& p, int l, bool last, unsigned char* smem) {
;     ...
;       gemm_tile<4, true>(p.Mc + (size_t)mt * 128 * 512, 512, nullptr, 128, p.GDc + (size_t)b * 2 * CTX * 256 + nh * 128, 256, 512, smem, epi);
	v_or_b32_e32 v22, 6, v26
	v_lshlrev_b32_e32 v23, 6, v22
	v_lshlrev_b32_e32 v22, 2, v22
	v_and_b32_e32 v22, 56, v22
	v_xad_u32 v22, v22, v27, v23
	v_or_b32_e32 v22, v22, v28
	v_lshlrev_b32_e32 v192, 1, v22
	v_or_b32_e32 v22, 7, v26
	v_lshlrev_b32_e32 v23, 6, v22
	v_lshlrev_b32_e32 v22, 2, v22
	v_and_b32_e32 v22, 56, v22
	v_xad_u32 v22, v22, v27, v23
	v_or_b32_e32 v22, v22, v28
	v_lshlrev_b32_e32 v193, 1, v22
	v_add_co_u32_e32 v54, vcc, s15, v132
	v_lshl_add_u64 v[136:137], v[130:131], 0, s[10:11]
	ds_write_b16 v190, v24 offset:16384
	ds_write_b16_d16_hi v191, v24 offset:16384
	ds_write_b16 v192, v25 offset:16384
	ds_write_b16_d16_hi v193, v25 offset:16384
	v_addc_co_u32_e32 v55, vcc, 0, v133, vcc
	v_lshl_add_u64 v[138:139], v[130:131], 0, s[12:13]
	v_lshl_add_u64 v[140:141], v[130:131], 0, s[26:27]
	global_load_dwordx4 v[22:25], v[136:137], off offset:128
	global_load_dwordx4 v[34:37], v[130:131], off offset:256
	global_load_dwordx4 v[26:29], v[138:139], off offset:128
	global_load_dwordx4 v[38:41], v[136:137], off offset:256
	global_load_dwordx4 v[30:33], v[140:141], off offset:128
	global_load_dwordx4 v[42:45], v[138:139], off offset:256
	global_load_dwordx4 v[46:49], v[140:141], off offset:256
	v_add_co_u32_e32 v58, vcc, s15, v134
	v_lshl_add_u64 v[76:77], s[0:1], 0, v[76:77]
	s_nop 0
	v_addc_co_u32_e32 v59, vcc, 0, v135, vcc
	v_add_co_u32_e32 v70, vcc, s15, v142
	global_load_dwordx4 v[54:57], v[54:55], off
	s_nop 0
	global_load_dwordx4 v[58:61], v[58:59], off
	v_addc_co_u32_e32 v71, vcc, 0, v143, vcc
	v_add_co_u32_e32 v86, vcc, s15, v144
	v_lshl_add_u64 v[74:75], s[0:1], 0, v[74:75]
	s_nop 0
	v_addc_co_u32_e32 v87, vcc, 0, v145, vcc
	global_load_dwordx4 v[70:73], v[70:71], off
	s_nop 0
	global_load_dwordx4 v[118:121], v[86:87], off
	v_lshl_add_u64 v[68:69], s[0:1], 0, v[68:69]
	v_lshl_add_u64 v[64:65], s[0:1], 0, v[64:65]
	v_bfe_u32 v86, v84, 1, 3
	v_lshl_add_u64 v[52:53], v[52:53], 0, s[26:27]
	v_lshl_add_u64 v[76:77], v[76:77], 0, v[82:83]
	v_lshl_add_u64 v[74:75], v[74:75], 0, v[80:81]
	v_lshl_add_u64 v[68:69], v[68:69], 0, v[78:79]
	v_lshl_add_u64 v[64:65], v[64:65], 0, v[66:67]
	v_bitop3_b32 v85, v85, v86, 3 bitop3:0x6c
	v_lshlrev_b32_e32 v87, 7, v157
	v_lshl_add_u64 v[146:147], v[52:53], 0, v[76:77]
	v_lshl_add_u64 v[148:149], v[52:53], 0, v[74:75]
	v_lshl_add_u64 v[150:151], v[52:53], 0, v[68:69]
	v_lshl_add_u64 v[152:153], v[52:53], 0, v[64:65]
	v_lshl_add_u64 v[52:53], s[94:95], 0, v[62:63]
	v_and_b32_e32 v62, 7, v84
	v_lshlrev_b32_e32 v85, 4, v85
	v_lshl_or_b32 v88, v158, 13, v87
	v_lshl_or_b32 v87, v156, 13, v87
	v_lshl_or_b32 v52, v62, 4, v52
	v_or_b32_e32 v197, v85, v88
	v_or_b32_e32 v196, v85, v87
	v_bitop3_b32 v85, v159, v86, 4 bitop3:0x36
	v_lshl_add_u64 v[50:51], v[50:51], 0, v[52:53]
	s_mov_b64 s[0:1], 0x18180
	v_lshlrev_b32_e32 v85, 4, v85
	v_lshl_add_u64 v[154:155], v[50:51], 0, s[0:1]
	v_mov_b32_e32 v50, 0
	s_mov_b32 s39, s95
	v_or_b32_e32 v195, v85, v88
	v_or_b32_e32 v194, v85, v87
	s_mov_b32 s0, -2
	v_mov_b32_e32 v51, v50
	v_mov_b32_e32 v52, v50
	v_mov_b32_e32 v53, v50
	v_mov_b32_e32 v62, v50
	v_mov_b32_e32 v63, v50
	v_mov_b32_e32 v64, v50
	v_mov_b32_e32 v65, v50
	v_mov_b32_e32 v66, v50
	v_mov_b32_e32 v67, v50
	v_mov_b32_e32 v68, v50
	v_mov_b32_e32 v69, v50
	v_mov_b32_e32 v74, v50
	v_mov_b32_e32 v75, v50
	v_mov_b32_e32 v76, v50
	v_mov_b32_e32 v77, v50
	v_mov_b32_e32 v78, v50
	v_mov_b32_e32 v79, v50
	v_mov_b32_e32 v80, v50
	v_mov_b32_e32 v81, v50
	v_mov_b32_e32 v82, v50
	v_mov_b32_e32 v83, v50
	v_mov_b32_e32 v84, v50
	v_mov_b32_e32 v85, v50
	v_mov_b32_e32 v86, v50
	v_mov_b32_e32 v87, v50
	v_mov_b32_e32 v88, v50
	v_mov_b32_e32 v89, v50
	v_mov_b32_e32 v90, v50
	v_mov_b32_e32 v91, v50
	v_mov_b32_e32 v92, v50
	v_mov_b32_e32 v93, v50
	v_mov_b32_e32 v94, v50
	v_mov_b32_e32 v95, v50
	v_mov_b32_e32 v96, v50
	v_mov_b32_e32 v97, v50
	v_mov_b32_e32 v98, v50
	v_mov_b32_e32 v99, v50
	v_mov_b32_e32 v100, v50
	v_mov_b32_e32 v101, v50
	v_mov_b32_e32 v102, v50
	v_mov_b32_e32 v103, v50
	v_mov_b32_e32 v104, v50
	v_mov_b32_e32 v105, v50
	v_mov_b32_e32 v106, v50
	v_mov_b32_e32 v107, v50
	v_mov_b32_e32 v108, v50
	v_mov_b32_e32 v109, v50
	v_mov_b32_e32 v110, v50
	v_mov_b32_e32 v111, v50
	v_mov_b32_e32 v112, v50
	v_mov_b32_e32 v113, v50
	v_mov_b32_e32 v114, v50
	v_mov_b32_e32 v115, v50
	v_mov_b32_e32 v116, v50
	v_mov_b32_e32 v117, v50
	v_mov_b32_e32 v122, v50
	v_mov_b32_e32 v123, v50
	v_mov_b32_e32 v124, v50
	v_mov_b32_e32 v125, v50
	v_mov_b32_e32 v126, v50
	v_mov_b32_e32 v127, v50
	v_mov_b32_e32 v128, v50
	v_mov_b32_e32 v129, v50
	s_waitcnt lgkmcnt(0)
	s_barrier
; template <int NT, bool BKN, bool MASK = false, bool ROWSS = false, class Epi> ...
;     ...
;   for (int kt = 0; kt < nk - 2; kt += 2) {
;     GEMM_COMPUTE(0);
;     GEMM_STORE(ra1, rb1, 1);
;     GEMM_LOAD(ra1, rb1, kt + 3);
;     __syncthreads();
;     GEMM_COMPUTE(1);
;     GEMM_STORE(ra0, rb0, 0);
;     GEMM_LOAD(ra0, rb0, (kt + 4 < nkm1 ? kt + 4 : nkm1));
;     __syncthreads();
;   }
.LBB0_628:
	ds_read_b128 v[198:201], v197
	ds_read_b128 v[202:205], v197 offset:2048
	ds_read_b128 v[206:209], v197 offset:4096
	ds_read_b128 v[210:213], v197 offset:6144
	ds_read_b128 v[230:233], v196 offset:16384
	ds_read_b128 v[234:237], v196 offset:18432
	ds_read_b128 v[238:241], v196 offset:20480
	ds_read_b128 v[242:245], v196 offset:22528
	s_mov_b32 s1, 0xfffe8000
	s_waitcnt lgkmcnt(0)
	v_mfma_f32_16x16x32_bf16 v[126:129], v[198:201], v[230:233], v[126:129]
	s_add_i32 s0, s0, 2
	v_mfma_f32_16x16x32_bf16 v[122:125], v[198:201], v[234:237], v[122:125]
	v_mfma_f32_16x16x32_bf16 v[114:117], v[198:201], v[238:241], v[114:117]
	v_mfma_f32_16x16x32_bf16 v[110:113], v[198:201], v[242:245], v[110:113]
	v_mfma_f32_16x16x32_bf16 v[106:109], v[202:205], v[230:233], v[106:109]
	v_mfma_f32_16x16x32_bf16 v[102:105], v[202:205], v[234:237], v[102:105]
	v_mfma_f32_16x16x32_bf16 v[98:101], v[202:205], v[238:241], v[98:101]
	v_mfma_f32_16x16x32_bf16 v[94:97], v[202:205], v[242:245], v[94:97]
	v_mfma_f32_16x16x32_bf16 v[90:93], v[206:209], v[230:233], v[90:93]
	v_mfma_f32_16x16x32_bf16 v[198:201], v[206:209], v[234:237], v[86:89]
	v_mfma_f32_16x16x32_bf16 v[202:205], v[206:209], v[238:241], v[82:85]
	v_mfma_f32_16x16x32_bf16 v[206:209], v[206:209], v[242:245], v[78:81]
	v_mfma_f32_16x16x32_bf16 v[230:233], v[210:213], v[230:233], v[74:77]
	v_mfma_f32_16x16x32_bf16 v[234:237], v[210:213], v[234:237], v[66:69]
	v_mfma_f32_16x16x32_bf16 v[238:241], v[210:213], v[238:241], v[62:65]
	v_mfma_f32_16x16x32_bf16 v[210:213], v[210:213], v[242:245], v[50:53]
	s_nop 1
	ds_read_b128 v[62:65], v195
	ds_read_b128 v[82:85], v195 offset:2048
	ds_read_b128 v[242:245], v195 offset:4096
	ds_read_b128 v[246:249], v195 offset:6144
	ds_read_b128 v[250:253], v194 offset:16384
	ds_read_b128 v[220:223], v194 offset:18432
	ds_read_b128 v[224:227], v194 offset:20480
	ds_read_b128 v[216:219], v194 offset:22528
	s_waitcnt vmcnt(0)
	ds_write_b128 v160, v[14:17] offset:32768
	s_waitcnt vmcnt(0)
	ds_write_b128 v160, v[22:25] offset:36864
	ds_write_b128 v160, v[26:29] offset:40960
	ds_write_b128 v160, v[30:33] offset:45056
	ds_write_b16 v161, v18 offset:49152
	ds_write_b16_d16_hi v0, v18 offset:49280
	ds_write_b16 v162, v19 offset:49152
	ds_write_b16_d16_hi v163, v19 offset:49152
	ds_write_b16 v164, v20 offset:49152
	ds_write_b16_d16_hi v165, v20 offset:49152
	ds_write_b16 v166, v21 offset:49152
	ds_write_b16_d16_hi v167, v21 offset:49152
	ds_write_b16 v169, v10 offset:49152
	ds_write_b16_d16_hi v168, v10 offset:49280
	ds_write_b16 v170, v11 offset:49152
	ds_write_b16_d16_hi v171, v11 offset:49152
	ds_write_b16 v172, v12 offset:49152
	ds_write_b16_d16_hi v173, v12 offset:49152
	ds_write_b16 v174, v13 offset:49152
	ds_write_b16_d16_hi v175, v13 offset:49152
	ds_write_b16 v176, v2 offset:49152
	ds_write_b16_d16_hi v177, v2 offset:49280
	ds_write_b16 v178, v3 offset:49152
	ds_write_b16_d16_hi v179, v3 offset:49152
	ds_write_b16 v180, v4 offset:49152
	ds_write_b16_d16_hi v181, v4 offset:49152
	ds_write_b16 v182, v5 offset:49152
	ds_write_b16_d16_hi v183, v5 offset:49152
	ds_write_b16 v184, v6 offset:49152
	ds_write_b16_d16_hi v185, v6 offset:49280
	ds_write_b16 v188, v7 offset:49152
	ds_write_b16_d16_hi v189, v7 offset:49152
	ds_write_b16 v190, v8 offset:49152
	ds_write_b16_d16_hi v191, v8 offset:49152
	ds_write_b16 v192, v9 offset:49152
	ds_write_b16_d16_hi v193, v9 offset:49152
	v_add_co_u32_e32 v2, vcc, s1, v154
	s_mov_b32 s1, 0xffff0000
	s_nop 0
	v_addc_co_u32_e32 v3, vcc, -1, v155, vcc
	global_load_dwordx4 v[14:17], v[2:3], off
	v_add_co_u32_e32 v2, vcc, s1, v154
	s_movk_i32 s1, 0x8000
	s_nop 0
	v_addc_co_u32_e32 v3, vcc, -1, v155, vcc
	global_load_dwordx4 v[22:25], v[2:3], off
	v_add_co_u32_e32 v2, vcc, s1, v154
	v_lshl_add_u64 v[6:7], v[146:147], 0, s[38:39]
	s_nop 0
	v_addc_co_u32_e32 v3, vcc, -1, v155, vcc
	global_load_dwordx4 v[26:29], v[2:3], off
	global_load_dwordx4 v[30:33], v[154:155], off
	v_lshl_add_u64 v[2:3], v[152:153], 0, s[38:39]
	global_load_dwordx4 v[18:21], v[2:3], off
	v_lshl_add_u64 v[2:3], v[150:151], 0, s[38:39]
	global_load_dwordx4 v[10:13], v[2:3], off
	v_lshl_add_u64 v[2:3], v[148:149], 0, s[38:39]
	s_waitcnt lgkmcnt(0)
	v_mfma_f32_16x16x32_bf16 v[126:129], v[62:65], v[250:253], v[126:129]
	global_load_dwordx4 v[2:5], v[2:3], off
	s_min_u32 s1, s0, 3
	global_load_dwordx4 v[6:9], v[6:7], off
	v_mfma_f32_16x16x32_bf16 v[122:125], v[62:65], v[220:223], v[122:125]
	s_waitcnt lgkmcnt(0)
	s_barrier
; template <int NT, bool BKN, bool MASK = false, bool ROWSS = false, class Epi> ...
;     ...
;   for (int kt = 0; kt < nk - 2; kt += 2) {
;     GEMM_COMPUTE(0);
;     GEMM_STORE(ra1, rb1, 1);
;     GEMM_LOAD(ra1, rb1, kt + 3);
;     __syncthreads();
;     GEMM_COMPUTE(1);
;     GEMM_STORE(ra0, rb0, 0);
;     GEMM_LOAD(ra0, rb0, (kt + 4 < nkm1 ? kt + 4 : nkm1));
;     __syncthreads();
;   }
	v_mfma_f32_16x16x32_bf16 v[50:53], v[62:65], v[224:227], v[114:117]
	s_lshl_b32 s94, s1, 7
	v_lshl_add_u64 v[146:147], v[146:147], 0, s[12:13]
	v_lshl_add_u64 v[148:149], v[148:149], 0, s[12:13]
	v_mfma_f32_16x16x32_bf16 v[62:65], v[62:65], v[216:219], v[110:113]
	v_lshl_add_u64 v[150:151], v[150:151], 0, s[12:13]
	v_lshl_add_u64 v[152:153], v[152:153], 0, s[12:13]
	v_lshl_add_u64 v[154:155], v[154:155], 0, s[6:7]
	v_mfma_f32_16x16x32_bf16 v[66:69], v[82:85], v[250:253], v[106:109]
	v_mfma_f32_16x16x32_bf16 v[74:77], v[82:85], v[220:223], v[102:105]
	v_mfma_f32_16x16x32_bf16 v[78:81], v[82:85], v[224:227], v[98:101]
	v_mfma_f32_16x16x32_bf16 v[82:85], v[82:85], v[216:219], v[94:97]
	v_mfma_f32_16x16x32_bf16 v[86:89], v[242:245], v[250:253], v[90:93]
	v_mfma_f32_16x16x32_bf16 v[90:93], v[242:245], v[220:223], v[198:201]
	v_mfma_f32_16x16x32_bf16 v[94:97], v[242:245], v[224:227], v[202:205]
	v_mfma_f32_16x16x32_bf16 v[98:101], v[242:245], v[216:219], v[206:209]
	v_mfma_f32_16x16x32_bf16 v[102:105], v[246:249], v[250:253], v[230:233]
	v_mfma_f32_16x16x32_bf16 v[106:109], v[246:249], v[220:223], v[234:237]
	v_mfma_f32_16x16x32_bf16 v[110:113], v[246:249], v[224:227], v[238:241]
	v_mfma_f32_16x16x32_bf16 v[114:117], v[246:249], v[216:219], v[210:213]
	ds_read_b128 v[198:201], v197 offset:32768
	ds_read_b128 v[202:205], v197 offset:34816
	ds_read_b128 v[206:209], v197 offset:36864
	ds_read_b128 v[210:213], v197 offset:38912
	ds_read_b128 v[216:219], v196 offset:49152
	ds_read_b128 v[220:223], v196 offset:51200
	ds_read_b128 v[224:227], v196 offset:53248
	ds_read_b128 v[230:233], v196 offset:55296
	s_waitcnt lgkmcnt(0)
	v_mfma_f32_16x16x32_bf16 v[126:129], v[198:201], v[216:219], v[126:129]
	v_mfma_f32_16x16x32_bf16 v[122:125], v[198:201], v[220:223], v[122:125]
	v_mfma_f32_16x16x32_bf16 v[50:53], v[198:201], v[224:227], v[50:53]
	v_mfma_f32_16x16x32_bf16 v[62:65], v[198:201], v[230:233], v[62:65]
	v_mfma_f32_16x16x32_bf16 v[66:69], v[202:205], v[216:219], v[66:69]
	v_mfma_f32_16x16x32_bf16 v[74:77], v[202:205], v[220:223], v[74:77]
	v_mfma_f32_16x16x32_bf16 v[78:81], v[202:205], v[224:227], v[78:81]
	v_mfma_f32_16x16x32_bf16 v[82:85], v[202:205], v[230:233], v[82:85]
	v_mfma_f32_16x16x32_bf16 v[86:89], v[206:209], v[216:219], v[86:89]
	v_mfma_f32_16x16x32_bf16 v[198:201], v[206:209], v[220:223], v[90:93]
	v_mfma_f32_16x16x32_bf16 v[202:205], v[206:209], v[224:227], v[94:97]
	v_mfma_f32_16x16x32_bf16 v[206:209], v[206:209], v[230:233], v[98:101]
	v_mfma_f32_16x16x32_bf16 v[216:219], v[210:213], v[216:219], v[102:105]
	v_mfma_f32_16x16x32_bf16 v[220:223], v[210:213], v[220:223], v[106:109]
	v_mfma_f32_16x16x32_bf16 v[224:227], v[210:213], v[224:227], v[110:113]
	v_mfma_f32_16x16x32_bf16 v[210:213], v[210:213], v[230:233], v[114:117]
	ds_read_b128 v[90:93], v195 offset:32768
	ds_read_b128 v[94:97], v195 offset:34816
	ds_read_b128 v[230:233], v195 offset:36864
	ds_read_b128 v[234:237], v195 offset:38912
	ds_read_b128 v[238:241], v194 offset:49152
	ds_read_b128 v[242:245], v194 offset:51200
	ds_read_b128 v[246:249], v194 offset:53248
	ds_read_b128 v[250:253], v194 offset:55296
	ds_write_b128 v160, v[34:37]
	ds_write_b128 v160, v[38:41] offset:4096
	ds_write_b128 v160, v[42:45] offset:8192
	ds_write_b128 v160, v[46:49] offset:12288
	ds_write_b16 v161, v54 offset:16384
	ds_write_b16_d16_hi v0, v54 offset:16512
	ds_write_b16 v162, v55 offset:16384
	ds_write_b16_d16_hi v163, v55 offset:16384
	ds_write_b16 v164, v56 offset:16384
	ds_write_b16_d16_hi v165, v56 offset:16384
	ds_write_b16 v166, v57 offset:16384
	ds_write_b16_d16_hi v167, v57 offset:16384
	ds_write_b16 v169, v58 offset:16384
	ds_write_b16_d16_hi v168, v58 offset:16512
	ds_write_b16 v170, v59 offset:16384
	ds_write_b16_d16_hi v171, v59 offset:16384
	ds_write_b16 v172, v60 offset:16384
	ds_write_b16_d16_hi v173, v60 offset:16384
	ds_write_b16 v174, v61 offset:16384
	ds_write_b16_d16_hi v175, v61 offset:16384
	ds_write_b16 v176, v70 offset:16384
	ds_write_b16_d16_hi v177, v70 offset:16512
	ds_write_b16 v178, v71 offset:16384
	ds_write_b16_d16_hi v179, v71 offset:16384
	ds_write_b16 v180, v72 offset:16384
	ds_write_b16_d16_hi v181, v72 offset:16384
	ds_write_b16 v182, v73 offset:16384
	ds_write_b16_d16_hi v183, v73 offset:16384
	ds_write_b16 v184, v118 offset:16384
	ds_write_b16_d16_hi v185, v118 offset:16512
	ds_write_b16 v188, v119 offset:16384
	ds_write_b16_d16_hi v189, v119 offset:16384
	ds_write_b16 v190, v120 offset:16384
	ds_write_b16_d16_hi v191, v120 offset:16384
	ds_write_b16 v192, v121 offset:16384
	ds_write_b16_d16_hi v193, v121 offset:16384
	v_lshl_add_u64 v[34:35], v[130:131], 0, s[94:95]
	v_lshl_add_u64 v[38:39], v[136:137], 0, s[94:95]
	v_lshl_add_u64 v[42:43], v[138:139], 0, s[94:95]
	v_lshl_add_u64 v[46:47], v[140:141], 0, s[94:95]
	s_lshl_b32 s94, s1, 15
	v_lshl_add_u64 v[54:55], v[132:133], 0, s[94:95]
	v_add_co_u32_e32 v54, vcc, s16, v54
	v_lshl_add_u64 v[58:59], v[134:135], 0, s[94:95]
	s_nop 0
	v_addc_co_u32_e32 v55, vcc, 0, v55, vcc
	v_add_co_u32_e32 v58, vcc, s16, v58
	v_lshl_add_u64 v[70:71], v[142:143], 0, s[94:95]
	s_nop 0
	v_addc_co_u32_e32 v59, vcc, 0, v59, vcc
	v_add_co_u32_e32 v70, vcc, s16, v70
	v_lshl_add_u64 v[118:119], v[144:145], 0, s[94:95]
	s_nop 0
	v_addc_co_u32_e32 v71, vcc, 0, v71, vcc
	v_add_co_u32_e32 v118, vcc, s16, v118
	global_load_dwordx4 v[34:37], v[34:35], off offset:512
	s_nop 0
	v_addc_co_u32_e32 v119, vcc, 0, v119, vcc
	global_load_dwordx4 v[38:41], v[38:39], off offset:512
	s_waitcnt lgkmcnt(0)
	v_mfma_f32_16x16x32_bf16 v[126:129], v[90:93], v[238:241], v[126:129]
	global_load_dwordx4 v[42:45], v[42:43], off offset:512
	s_cmp_lt_u32 s0, 4
	global_load_dwordx4 v[46:49], v[46:47], off offset:512
	v_mfma_f32_16x16x32_bf16 v[122:125], v[90:93], v[242:245], v[122:125]
	global_load_dwordx4 v[54:57], v[54:55], off
	s_nop 0
	global_load_dwordx4 v[58:61], v[58:59], off
	v_mfma_f32_16x16x32_bf16 v[114:117], v[90:93], v[246:249], v[50:53]
	global_load_dwordx4 v[70:73], v[70:71], off
	s_nop 0
	global_load_dwordx4 v[118:121], v[118:119], off
	v_mfma_f32_16x16x32_bf16 v[110:113], v[90:93], v[250:253], v[62:65]
	s_waitcnt lgkmcnt(0)
	s_barrier
; template <int NT, bool BKN, bool MASK = false, bool ROWSS = false, class Epi> ...
;     ...
;   for (int kt = 0; kt < nk - 2; kt += 2) {
;     GEMM_COMPUTE(0);
;     GEMM_STORE(ra1, rb1, 1);
;     GEMM_LOAD(ra1, rb1, kt + 3);
;     __syncthreads();
;     GEMM_COMPUTE(1);
;     GEMM_STORE(ra0, rb0, 0);
;     GEMM_LOAD(ra0, rb0, (kt + 4 < nkm1 ? kt + 4 : nkm1));
;     __syncthreads();
;   }
;   GEMM_COMPUTE(0);
;   GEMM_STORE(ra1, rb1, 1);
;   __syncthreads();
	v_mfma_f32_16x16x32_bf16 v[106:109], v[94:97], v[238:241], v[66:69]
	v_mfma_f32_16x16x32_bf16 v[102:105], v[94:97], v[242:245], v[74:77]
	v_mfma_f32_16x16x32_bf16 v[98:101], v[94:97], v[246:249], v[78:81]
	v_mfma_f32_16x16x32_bf16 v[94:97], v[94:97], v[250:253], v[82:85]
	v_mfma_f32_16x16x32_bf16 v[90:93], v[230:233], v[238:241], v[86:89]
	v_mfma_f32_16x16x32_bf16 v[86:89], v[230:233], v[242:245], v[198:201]
	v_mfma_f32_16x16x32_bf16 v[82:85], v[230:233], v[246:249], v[202:205]
	v_mfma_f32_16x16x32_bf16 v[78:81], v[230:233], v[250:253], v[206:209]
	v_mfma_f32_16x16x32_bf16 v[74:77], v[234:237], v[238:241], v[216:219]
	v_mfma_f32_16x16x32_bf16 v[66:69], v[234:237], v[242:245], v[220:223]
	v_mfma_f32_16x16x32_bf16 v[62:65], v[234:237], v[246:249], v[224:227]
	v_mfma_f32_16x16x32_bf16 v[50:53], v[234:237], v[250:253], v[210:213]
	s_cbranch_scc1 .LBB0_628
	s_waitcnt vmcnt(0)
	ds_read_b128 v[34:37], v197
	ds_read_b128 v[38:41], v197 offset:2048
	ds_read_b128 v[42:45], v197 offset:4096
	ds_read_b128 v[46:49], v197 offset:6144
	ds_read_b128 v[54:57], v196 offset:16384
	ds_read_b128 v[58:61], v196 offset:18432
	ds_read_b128 v[70:73], v196 offset:20480
	ds_read_b128 v[118:121], v196 offset:22528
	s_lshl_b32 s0, s19, 7
	s_waitcnt lgkmcnt(3)
	v_mfma_f32_16x16x32_bf16 v[126:129], v[34:37], v[54:57], v[126:129]
	s_lshl_b32 s1, s4, 8
	s_or_b32 s0, s1, s0
	s_addk_i32 s0, 0x4000
	s_waitcnt lgkmcnt(2)
	v_mfma_f32_16x16x32_bf16 v[122:125], v[34:37], v[58:61], v[122:125]
	s_lshl_b32 s94, s18, 1
	s_waitcnt lgkmcnt(1)
	v_mfma_f32_16x16x32_bf16 v[114:117], v[34:37], v[70:73], v[114:117]
	s_waitcnt lgkmcnt(0)
	v_mfma_f32_16x16x32_bf16 v[34:37], v[34:37], v[118:121], v[110:113]
	v_mfma_f32_16x16x32_bf16 v[106:109], v[38:41], v[54:57], v[106:109]
	v_mfma_f32_16x16x32_bf16 v[102:105], v[38:41], v[58:61], v[102:105]
	v_mfma_f32_16x16x32_bf16 v[98:101], v[38:41], v[70:73], v[98:101]
	v_mfma_f32_16x16x32_bf16 v[38:41], v[38:41], v[118:121], v[94:97]
	v_mfma_f32_16x16x32_bf16 v[90:93], v[42:45], v[54:57], v[90:93]
	v_mfma_f32_16x16x32_bf16 v[86:89], v[42:45], v[58:61], v[86:89]
	v_mfma_f32_16x16x32_bf16 v[82:85], v[42:45], v[70:73], v[82:85]
	v_mfma_f32_16x16x32_bf16 v[42:45], v[42:45], v[118:121], v[78:81]
	v_mfma_f32_16x16x32_bf16 v[54:57], v[46:49], v[54:57], v[74:77]
	v_mfma_f32_16x16x32_bf16 v[58:61], v[46:49], v[58:61], v[66:69]
	v_mfma_f32_16x16x32_bf16 v[62:65], v[46:49], v[70:73], v[62:65]
	v_mfma_f32_16x16x32_bf16 v[46:49], v[46:49], v[118:121], v[50:53]
	s_nop 2
	ds_read_b128 v[50:53], v195
	ds_read_b128 v[66:69], v195 offset:2048
	ds_read_b128 v[70:73], v195 offset:4096
	ds_read_b128 v[74:77], v195 offset:6144
	ds_read_b128 v[78:81], v194 offset:16384
	ds_read_b128 v[94:97], v194 offset:18432
	ds_read_b128 v[110:113], v194 offset:20480
	ds_read_b128 v[118:121], v194 offset:22528
	ds_write_b128 v160, v[14:17] offset:32768
	ds_write_b128 v160, v[22:25] offset:36864
	ds_write_b128 v160, v[26:29] offset:40960
	ds_write_b128 v160, v[30:33] offset:45056
	ds_write_b16 v161, v18 offset:49152
	ds_write_b16_d16_hi v0, v18 offset:49280
	ds_write_b16 v162, v19 offset:49152
	ds_write_b16_d16_hi v163, v19 offset:49152
	ds_write_b16 v164, v20 offset:49152
	ds_write_b16_d16_hi v165, v20 offset:49152
	ds_write_b16 v166, v21 offset:49152
	ds_write_b16_d16_hi v167, v21 offset:49152
	ds_write_b16 v169, v10 offset:49152
	ds_write_b16_d16_hi v168, v10 offset:49280
	ds_write_b16 v170, v11 offset:49152
	ds_write_b16_d16_hi v171, v11 offset:49152
	ds_write_b16 v172, v12 offset:49152
	ds_write_b16_d16_hi v173, v12 offset:49152
	ds_write_b16 v174, v13 offset:49152
	ds_write_b16_d16_hi v175, v13 offset:49152
	ds_write_b16 v176, v2 offset:49152
	ds_write_b16_d16_hi v177, v2 offset:49280
	ds_write_b16 v178, v3 offset:49152
	ds_write_b16_d16_hi v179, v3 offset:49152
	ds_write_b16 v180, v4 offset:49152
	ds_write_b16_d16_hi v181, v4 offset:49152
	ds_write_b16 v182, v5 offset:49152
	ds_write_b16_d16_hi v183, v5 offset:49152
	ds_write_b16 v184, v6 offset:49152
	ds_write_b16_d16_hi v185, v6 offset:49280
	ds_write_b16 v188, v7 offset:49152
	ds_write_b16_d16_hi v189, v7 offset:49152
	ds_write_b16 v190, v8 offset:49152
	ds_write_b16_d16_hi v191, v8 offset:49152
	ds_write_b16 v192, v9 offset:49152
	ds_write_b16_d16_hi v193, v9 offset:49152
	s_waitcnt lgkmcnt(0)
	v_mfma_f32_16x16x32_bf16 v[126:129], v[50:53], v[78:81], v[126:129]
	s_barrier
; __device__ __forceinline__ u16 f2bf(float f) { return (u16)(pack2(f, 0.f) & 0xffffu); }
; template <int NT, bool BKN, bool MASK = false, bool ROWSS = false, class Epi> ...
;     ...
;   GEMM_COMPUTE(0);
;   GEMM_STORE(ra1, rb1, 1);
;   __syncthreads();
;   GEMM_COMPUTE(1);
; __device__ __forceinline__ void phase_mix_a(const Params& p, int l, bool last, unsigned char* smem) {
;     ...
;       auto epi = [&](f32x4(&acc)[4][4], int r0, int c0) {
; #pragma unroll
;         for (int mi = 0; mi < 4; ++mi)
; #pragma unroll
;           for (int ni = 0; ni < 4; ++ni)
; #pragma unroll
;             for (int j = 0; j < 4; ++j) {
;               const int k = mt * 128 + r0 + mi * 16 + j;
;               p.YM[(size_t)(T_LAT + b * CTX + k) * 1024 + 256 + nh * 128 + c0 + ni * 16] = f2bf(acc[mi][ni][j] * (1.f / 128.f));
	ds_read_b128 v[2:5], v197 offset:32768
	ds_read_b128 v[6:9], v197 offset:34816
	ds_read_b128 v[10:13], v197 offset:36864
	ds_read_b128 v[14:17], v197 offset:38912
	ds_read_b128 v[18:21], v196 offset:49152
	ds_read_b128 v[22:25], v196 offset:51200
	ds_read_b128 v[26:29], v196 offset:53248
	ds_read_b128 v[30:33], v196 offset:55296
	v_mfma_f32_16x16x32_bf16 v[122:125], v[50:53], v[94:97], v[122:125]
	v_lshl_add_u32 v0, v158, 6, s0
	v_mfma_f32_16x16x32_bf16 v[114:117], v[50:53], v[110:113], v[114:117]
	v_mfma_f32_16x16x32_bf16 v[34:37], v[50:53], v[118:121], v[34:37]
	v_mfma_f32_16x16x32_bf16 v[50:53], v[66:69], v[78:81], v[106:109]
	v_mfma_f32_16x16x32_bf16 v[102:105], v[66:69], v[94:97], v[102:105]
	v_mfma_f32_16x16x32_bf16 v[98:101], v[66:69], v[110:113], v[98:101]
	v_mfma_f32_16x16x32_bf16 v[38:41], v[66:69], v[118:121], v[38:41]
	v_mfma_f32_16x16x32_bf16 v[66:69], v[70:73], v[78:81], v[90:93]
	v_mfma_f32_16x16x32_bf16 v[54:57], v[74:77], v[78:81], v[54:57]
	v_mfma_f32_16x16x32_bf16 v[58:61], v[74:77], v[94:97], v[58:61]
	v_mfma_f32_16x16x32_bf16 v[62:65], v[74:77], v[110:113], v[62:65]
	v_mfma_f32_16x16x32_bf16 v[46:49], v[74:77], v[118:121], v[46:49]
	v_mfma_f32_16x16x32_bf16 v[86:89], v[70:73], v[94:97], v[86:89]
	v_mfma_f32_16x16x32_bf16 v[82:85], v[70:73], v[110:113], v[82:85]
	v_mfma_f32_16x16x32_bf16 v[42:45], v[70:73], v[118:121], v[42:45]
	s_waitcnt lgkmcnt(3)
	v_mfma_f32_16x16x32_bf16 v[66:69], v[10:13], v[18:21], v[66:69]
	v_mfma_f32_16x16x32_bf16 v[70:73], v[2:5], v[18:21], v[126:129]
	s_waitcnt lgkmcnt(2)
	v_mfma_f32_16x16x32_bf16 v[74:77], v[2:5], v[22:25], v[122:125]
	s_waitcnt lgkmcnt(1)
	v_mfma_f32_16x16x32_bf16 v[78:81], v[2:5], v[26:29], v[114:117]
	s_waitcnt lgkmcnt(0)
	v_mfma_f32_16x16x32_bf16 v[2:5], v[2:5], v[30:33], v[34:37]
	v_mfma_f32_16x16x32_bf16 v[34:37], v[6:9], v[18:21], v[50:53]
	v_mfma_f32_16x16x32_bf16 v[90:93], v[6:9], v[22:25], v[102:105]
	v_mfma_f32_16x16x32_bf16 v[94:97], v[6:9], v[26:29], v[98:101]
	v_mfma_f32_16x16x32_bf16 v[98:101], v[14:17], v[18:21], v[54:57]
	v_mfma_f32_16x16x32_bf16 v[102:105], v[14:17], v[22:25], v[58:61]
	v_mfma_f32_16x16x32_bf16 v[106:109], v[14:17], v[26:29], v[62:65]
	v_mfma_f32_16x16x32_bf16 v[110:113], v[14:17], v[30:33], v[46:49]
	ds_read_b128 v[14:17], v195 offset:32768
	ds_read_b128 v[18:21], v195 offset:34816
	ds_read_b128 v[114:117], v195 offset:36864
	ds_read_b128 v[118:121], v195 offset:38912
	ds_read_b128 v[122:125], v194 offset:49152
	ds_read_b128 v[126:129], v194 offset:51200
	ds_read_b128 v[130:133], v194 offset:53248
	ds_read_b128 v[134:137], v194 offset:55296
	v_mfma_f32_16x16x32_bf16 v[6:9], v[6:9], v[30:33], v[38:41]
	v_mfma_f32_16x16x32_bf16 v[86:89], v[10:13], v[22:25], v[86:89]
	v_mfma_f32_16x16x32_bf16 v[82:85], v[10:13], v[26:29], v[82:85]
	v_mfma_f32_16x16x32_bf16 v[10:13], v[10:13], v[30:33], v[42:45]
	s_waitcnt lgkmcnt(3)
	v_mfma_f32_16x16x32_bf16 v[30:33], v[114:117], v[122:125], v[66:69]
	s_nop 2
	v_mov_b64_e32 v[66:67], s[40:41]
	global_load_dwordx2 v[66:67], v[66:67], off offset:296
	v_mfma_f32_16x16x32_bf16 v[62:65], v[14:17], v[122:125], v[70:73]
	v_lshl_or_b32 v68, v159, 2, v0
	v_ashrrev_i32_e32 v69, 31, v68
	v_mul_f32_e32 v30, 0x3c000000, v30
	v_lshlrev_b64 v[70:71], 11, v[68:69]
	v_or_b32_e32 v72, 2, v68
	s_nop 2
	v_mul_f32_e32 v0, 0x3c000000, v62
	v_cvt_pk_bf16_f32 v62, v0, s0
	v_lshlrev_b32_e32 v0, 1, v157
	v_lshl_or_b32 v0, v156, 7, v0
	s_waitcnt lgkmcnt(0)
	v_mfma_f32_16x16x32_bf16 v[50:53], v[14:17], v[134:137], v[2:5]
	v_ashrrev_i32_e32 v73, 31, v72
	v_lshlrev_b64 v[72:73], 11, v[72:73]
	v_mul_f32_e32 v64, 0x3c000000, v64
	v_cvt_pk_bf16_f32 v64, v64, s0
	v_mfma_f32_16x16x32_bf16 v[46:49], v[18:21], v[122:125], v[34:37]
	s_nop 2
	v_mul_f32_e32 v50, 0x3c000000, v50
	v_cvt_pk_bf16_f32 v50, v50, s0
	v_cvt_pk_bf16_f32 v30, v30, s0
	v_mfma_f32_16x16x32_bf16 v[54:57], v[14:17], v[130:133], v[78:81]
	v_mul_f32_e32 v32, 0x3c000000, v32
	v_mul_f32_e32 v46, 0x3c000000, v46
	v_cvt_pk_bf16_f32 v46, v46, s0
	v_mfma_f32_16x16x32_bf16 v[34:37], v[18:21], v[134:137], v[6:9]
	v_mul_f32_e32 v48, 0x3c000000, v48
	s_nop 2
	v_mul_f32_e32 v54, 0x3c000000, v54
	v_cvt_pk_bf16_f32 v54, v54, s0
	v_cvt_pk_bf16_f32 v48, v48, s0
	v_mfma_f32_16x16x32_bf16 v[38:41], v[18:21], v[130:133], v[94:97]
	v_mul_f32_e32 v34, 0x3c000000, v34
	v_cvt_pk_bf16_f32 v34, v34, s0
	v_cvt_pk_bf16_f32 v32, v32, s0
	v_mfma_f32_16x16x32_bf16 v[42:45], v[18:21], v[126:129], v[90:93]
	s_waitcnt vmcnt(0)
; __device__ __forceinline__ u16 f2bf(float f) { return (u16)(pack2(f, 0.f) & 0xffffu); }
; __device__ __forceinline__ void phase_mix_a(const Params& p, int l, bool last, unsigned char* smem) {
;     ...
;       auto epi = [&](f32x4(&acc)[4][4], int r0, int c0) {
; #pragma unroll
;         for (int mi = 0; mi < 4; ++mi)
; #pragma unroll
;           for (int ni = 0; ni < 4; ++ni)
; #pragma unroll
;             for (int j = 0; j < 4; ++j) {
;               const int k = mt * 128 + r0 + mi * 16 + j;
;               p.YM[(size_t)(T_LAT + b * CTX + k) * 1024 + 256 + nh * 128 + c0 + ni * 16] = f2bf(acc[mi][ni][j] * (1.f / 128.f));
;             }
;       };
	v_lshl_add_u64 v[70:71], v[66:67], 0, v[70:71]
	v_lshl_add_u64 v[70:71], v[70:71], 0, s[94:95]
	v_lshl_add_u64 v[70:71], v[70:71], 0, v[0:1]
	global_store_short v[70:71], v62, off offset:512
	v_mul_f32_e32 v62, 0x3c000000, v63
	v_cvt_pk_bf16_f32 v69, v62, s0
	v_or_b32_e32 v62, 1, v68
	v_ashrrev_i32_e32 v63, 31, v62
	v_lshlrev_b64 v[62:63], 11, v[62:63]
	v_lshl_add_u64 v[72:73], v[66:67], 0, v[72:73]
	v_lshl_add_u64 v[62:63], v[66:67], 0, v[62:63]
	v_lshl_add_u64 v[72:73], v[72:73], 0, s[94:95]
	v_lshl_add_u64 v[62:63], v[62:63], 0, s[94:95]
	v_lshl_add_u64 v[72:73], v[72:73], 0, v[0:1]
	v_lshl_add_u64 v[62:63], v[62:63], 0, v[0:1]
	global_store_short v[72:73], v64, off offset:512
	v_mul_f32_e32 v64, 0x3c000000, v65
	global_store_short v[62:63], v69, off offset:512
	v_cvt_pk_bf16_f32 v69, v64, s0
	v_or_b32_e32 v64, 3, v68
	global_store_short v[70:71], v50, off offset:608
	v_mul_f32_e32 v50, 0x3c000000, v51
	v_ashrrev_i32_e32 v65, 31, v64
	v_cvt_pk_bf16_f32 v50, v50, s0
	v_lshlrev_b64 v[64:65], 11, v[64:65]
	global_store_short v[62:63], v50, off offset:608
	v_mul_f32_e32 v50, 0x3c000000, v52
	v_lshl_add_u64 v[64:65], v[66:67], 0, v[64:65]
	v_cvt_pk_bf16_f32 v50, v50, s0
	v_lshl_add_u64 v[64:65], v[64:65], 0, s[94:95]
	global_store_short v[72:73], v50, off offset:608
	v_mul_f32_e32 v50, 0x3c000000, v53
	v_lshl_add_u64 v[64:65], v[64:65], 0, v[0:1]
	v_cvt_pk_bf16_f32 v50, v50, s0
	global_store_short v[64:65], v50, off offset:608
	v_or_b32_e32 v50, 16, v68
	v_ashrrev_i32_e32 v51, 31, v50
	v_lshlrev_b64 v[50:51], 11, v[50:51]
	v_lshl_add_u64 v[50:51], v[66:67], 0, v[50:51]
	v_lshl_add_u64 v[50:51], v[50:51], 0, s[94:95]
	v_lshl_add_u64 v[50:51], v[50:51], 0, v[0:1]
	global_store_short v[50:51], v46, off offset:512
	v_mul_f32_e32 v46, 0x3c000000, v47
	v_cvt_pk_bf16_f32 v52, v46, s0
	v_or_b32_e32 v46, 17, v68
	v_ashrrev_i32_e32 v47, 31, v46
	v_lshlrev_b64 v[46:47], 11, v[46:47]
	v_lshl_add_u64 v[46:47], v[66:67], 0, v[46:47]
	v_lshl_add_u64 v[46:47], v[46:47], 0, s[94:95]
	v_lshl_add_u64 v[46:47], v[46:47], 0, v[0:1]
	global_store_short v[46:47], v52, off offset:512
	v_or_b32_e32 v52, 18, v68
	global_store_short v[70:71], v54, off offset:576
	v_mul_f32_e32 v54, 0x3c000000, v55
	v_ashrrev_i32_e32 v53, 31, v52
	v_cvt_pk_bf16_f32 v54, v54, s0
	v_lshlrev_b64 v[52:53], 11, v[52:53]
	global_store_short v[62:63], v54, off offset:576
	v_mul_f32_e32 v54, 0x3c000000, v56
	v_lshl_add_u64 v[52:53], v[66:67], 0, v[52:53]
	v_cvt_pk_bf16_f32 v54, v54, s0
	v_lshl_add_u64 v[52:53], v[52:53], 0, s[94:95]
	global_store_short v[72:73], v54, off offset:576
	v_mul_f32_e32 v54, 0x3c000000, v57
	v_lshl_add_u64 v[52:53], v[52:53], 0, v[0:1]
	v_cvt_pk_bf16_f32 v54, v54, s0
	global_store_short v[52:53], v48, off offset:512
	v_mul_f32_e32 v48, 0x3c000000, v49
	global_store_short v[64:65], v54, off offset:576
	v_cvt_pk_bf16_f32 v54, v48, s0
	v_or_b32_e32 v48, 19, v68
	global_store_short v[50:51], v34, off offset:608
	v_mul_f32_e32 v34, 0x3c000000, v35
	v_ashrrev_i32_e32 v49, 31, v48
	v_cvt_pk_bf16_f32 v34, v34, s0
	v_lshlrev_b64 v[48:49], 11, v[48:49]
	global_store_short v[46:47], v34, off offset:608
	v_mul_f32_e32 v34, 0x3c000000, v36
	v_lshl_add_u64 v[48:49], v[66:67], 0, v[48:49]
	v_cvt_pk_bf16_f32 v34, v34, s0
	v_lshl_add_u64 v[48:49], v[48:49], 0, s[94:95]
	global_store_short v[52:53], v34, off offset:608
	v_mul_f32_e32 v34, 0x3c000000, v37
	v_lshl_add_u64 v[48:49], v[48:49], 0, v[0:1]
	v_cvt_pk_bf16_f32 v34, v34, s0
	global_store_short v[48:49], v34, off offset:608
	v_or_b32_e32 v34, 32, v68
	v_ashrrev_i32_e32 v35, 31, v34
	v_lshlrev_b64 v[34:35], 11, v[34:35]
	v_lshl_add_u64 v[34:35], v[66:67], 0, v[34:35]
	v_lshl_add_u64 v[34:35], v[34:35], 0, s[94:95]
	v_lshl_add_u64 v[34:35], v[34:35], 0, v[0:1]
	global_store_short v[34:35], v30, off offset:512
	v_mul_f32_e32 v30, 0x3c000000, v31
	v_cvt_pk_bf16_f32 v36, v30, s0
	v_or_b32_e32 v30, 33, v68
	v_ashrrev_i32_e32 v31, 31, v30
	v_lshlrev_b64 v[30:31], 11, v[30:31]
	v_lshl_add_u64 v[30:31], v[66:67], 0, v[30:31]
	v_lshl_add_u64 v[30:31], v[30:31], 0, s[94:95]
	v_mul_f32_e32 v38, 0x3c000000, v38
	v_lshl_add_u64 v[30:31], v[30:31], 0, v[0:1]
	v_cvt_pk_bf16_f32 v38, v38, s0
	global_store_short v[30:31], v36, off offset:512
	v_or_b32_e32 v36, 34, v68
	v_mfma_f32_16x16x32_bf16 v[18:21], v[114:117], v[134:137], v[10:13]
	global_store_short v[50:51], v38, off offset:576
	v_mul_f32_e32 v38, 0x3c000000, v39
	v_ashrrev_i32_e32 v37, 31, v36
	v_cvt_pk_bf16_f32 v38, v38, s0
	v_lshlrev_b64 v[36:37], 11, v[36:37]
	global_store_short v[46:47], v38, off offset:576
	v_mul_f32_e32 v38, 0x3c000000, v40
	v_lshl_add_u64 v[36:37], v[66:67], 0, v[36:37]
	v_cvt_pk_bf16_f32 v38, v38, s0
	v_lshl_add_u64 v[36:37], v[36:37], 0, s[94:95]
	global_store_short v[52:53], v38, off offset:576
	v_mul_f32_e32 v38, 0x3c000000, v41
	v_lshl_add_u64 v[36:37], v[36:37], 0, v[0:1]
	v_mul_f32_e32 v18, 0x3c000000, v18
	v_cvt_pk_bf16_f32 v38, v38, s0
	global_store_short v[36:37], v32, off offset:512
	v_mul_f32_e32 v32, 0x3c000000, v33
	v_cvt_pk_bf16_f32 v18, v18, s0
	global_store_short v[48:49], v38, off offset:576
	v_cvt_pk_bf16_f32 v38, v32, s0
	v_or_b32_e32 v32, 35, v68
	global_store_short v[34:35], v18, off offset:608
	v_mul_f32_e32 v18, 0x3c000000, v19
	v_ashrrev_i32_e32 v33, 31, v32
	v_cvt_pk_bf16_f32 v18, v18, s0
	v_lshlrev_b64 v[32:33], 11, v[32:33]
	global_store_short v[30:31], v18, off offset:608
	v_mul_f32_e32 v18, 0x3c000000, v20
	v_lshl_add_u64 v[32:33], v[66:67], 0, v[32:33]
	v_cvt_pk_bf16_f32 v18, v18, s0
	v_lshl_add_u64 v[32:33], v[32:33], 0, s[94:95]
	global_store_short v[36:37], v18, off offset:608
	v_mul_f32_e32 v18, 0x3c000000, v21
; __device__ __forceinline__ u16 f2bf(float f) { return (u16)(pack2(f, 0.f) & 0xffffu); }
; __device__ __forceinline__ int bid_() { int b = blockIdx.x; asm volatile("" : "+s"(b)); return b; }
; __device__ __forceinline__ void phase_mix_a(const Params& p, int l, bool last, unsigned char* smem) {
;     ...
;     for (int t = bid_(); t < 8; t += gridDim.x) {
;     ...
;       auto epi = [&](f32x4(&acc)[4][4], int r0, int c0) {
; #pragma unroll
;         for (int mi = 0; mi < 4; ++mi)
; #pragma unroll
;           for (int ni = 0; ni < 4; ++ni)
; #pragma unroll
;             for (int j = 0; j < 4; ++j) {
;               const int k = mt * 128 + r0 + mi * 16 + j;
;               p.YM[(size_t)(T_LAT + b * CTX + k) * 1024 + 256 + nh * 128 + c0 + ni * 16] = f2bf(acc[mi][ni][j] * (1.f / 128.f));
;             }
;       };
	v_lshl_add_u64 v[32:33], v[32:33], 0, v[0:1]
	v_cvt_pk_bf16_f32 v18, v18, s0
	v_mfma_f32_16x16x32_bf16 v[58:61], v[14:17], v[126:129], v[74:77]
	global_store_short v[32:33], v18, off offset:608
	v_or_b32_e32 v18, 48, v68
	v_ashrrev_i32_e32 v19, 31, v18
	v_mfma_f32_16x16x32_bf16 v[14:17], v[118:121], v[122:125], v[98:101]
	v_lshlrev_b64 v[18:19], 11, v[18:19]
	v_lshl_add_u64 v[18:19], v[66:67], 0, v[18:19]
	v_lshl_add_u64 v[18:19], v[18:19], 0, s[94:95]
	v_lshl_add_u64 v[18:19], v[18:19], 0, v[0:1]
	v_mfma_f32_16x16x32_bf16 v[22:25], v[114:117], v[130:133], v[82:85]
	s_nop 2
	v_mul_f32_e32 v14, 0x3c000000, v14
	v_cvt_pk_bf16_f32 v14, v14, s0
	global_store_short v[18:19], v14, off offset:512
	v_mul_f32_e32 v14, 0x3c000000, v15
	v_cvt_pk_bf16_f32 v20, v14, s0
	v_or_b32_e32 v14, 49, v68
	v_ashrrev_i32_e32 v15, 31, v14
	v_lshlrev_b64 v[14:15], 11, v[14:15]
	v_lshl_add_u64 v[14:15], v[66:67], 0, v[14:15]
	v_lshl_add_u64 v[14:15], v[14:15], 0, s[94:95]
	v_mul_f32_e32 v22, 0x3c000000, v22
	v_lshl_add_u64 v[14:15], v[14:15], 0, v[0:1]
	v_cvt_pk_bf16_f32 v22, v22, s0
	global_store_short v[14:15], v20, off offset:512
	v_or_b32_e32 v20, 50, v68
	global_store_short v[34:35], v22, off offset:576
	v_mul_f32_e32 v22, 0x3c000000, v23
	v_ashrrev_i32_e32 v21, 31, v20
	v_cvt_pk_bf16_f32 v22, v22, s0
	v_lshlrev_b64 v[20:21], 11, v[20:21]
	global_store_short v[30:31], v22, off offset:576
	v_mul_f32_e32 v22, 0x3c000000, v24
	v_lshl_add_u64 v[20:21], v[66:67], 0, v[20:21]
	v_cvt_pk_bf16_f32 v22, v22, s0
	v_mul_f32_e32 v16, 0x3c000000, v16
	v_lshl_add_u64 v[20:21], v[20:21], 0, s[94:95]
	global_store_short v[36:37], v22, off offset:576
	v_mul_f32_e32 v22, 0x3c000000, v25
	v_cvt_pk_bf16_f32 v16, v16, s0
	v_lshl_add_u64 v[20:21], v[20:21], 0, v[0:1]
	v_cvt_pk_bf16_f32 v22, v22, s0
	global_store_short v[20:21], v16, off offset:512
	v_mul_f32_e32 v16, 0x3c000000, v17
	global_store_short v[32:33], v22, off offset:576
	v_cvt_pk_bf16_f32 v22, v16, s0
	v_or_b32_e32 v16, 51, v68
	v_mfma_f32_16x16x32_bf16 v[10:13], v[118:121], v[126:129], v[102:105]
	v_ashrrev_i32_e32 v17, 31, v16
	v_lshlrev_b64 v[16:17], 11, v[16:17]
	v_lshl_add_u64 v[16:17], v[66:67], 0, v[16:17]
	v_lshl_add_u64 v[16:17], v[16:17], 0, s[94:95]
	v_lshl_add_u64 v[16:17], v[16:17], 0, v[0:1]
	s_nop 2
	v_mul_f32_e32 v0, 0x3c000000, v10
	v_cvt_pk_bf16_f32 v0, v0, s0
	global_store_short v[18:19], v0, off offset:544
	v_mul_f32_e32 v0, 0x3c000000, v11
	v_cvt_pk_bf16_f32 v0, v0, s0
	v_mfma_f32_16x16x32_bf16 v[6:9], v[118:121], v[130:133], v[106:109]
	global_store_short v[14:15], v0, off offset:544
	v_mul_f32_e32 v0, 0x3c000000, v12
	v_cvt_pk_bf16_f32 v0, v0, s0
	global_store_short v[20:21], v0, off offset:544
	v_mul_f32_e32 v0, 0x3c000000, v13
	v_cvt_pk_bf16_f32 v0, v0, s0
	global_store_short v[16:17], v0, off offset:544
	s_nop 0
	v_mul_f32_e32 v0, 0x3c000000, v6
	v_cvt_pk_bf16_f32 v0, v0, s0
	global_store_short v[18:19], v0, off offset:576
	v_mul_f32_e32 v0, 0x3c000000, v7
	v_cvt_pk_bf16_f32 v0, v0, s0
	v_mfma_f32_16x16x32_bf16 v[26:29], v[114:117], v[126:129], v[86:89]
	global_store_short v[14:15], v0, off offset:576
	v_mul_f32_e32 v0, 0x3c000000, v8
	v_cvt_pk_bf16_f32 v0, v0, s0
	v_mfma_f32_16x16x32_bf16 v[2:5], v[118:121], v[134:137], v[110:113]
	global_store_short v[20:21], v0, off offset:576
	v_mul_f32_e32 v0, 0x3c000000, v9
	v_cvt_pk_bf16_f32 v0, v0, s0
	v_mul_f32_e32 v58, 0x3c000000, v58
	v_mul_f32_e32 v42, 0x3c000000, v42
	v_mul_f32_e32 v26, 0x3c000000, v26
	global_store_short v[16:17], v0, off offset:576
	s_nop 0
	v_mul_f32_e32 v0, 0x3c000000, v2
	v_cvt_pk_bf16_f32 v58, v58, s0
	v_cvt_pk_bf16_f32 v42, v42, s0
	v_cvt_pk_bf16_f32 v26, v26, s0
	v_cvt_pk_bf16_f32 v0, v0, s0
	global_store_short v[70:71], v58, off offset:544
	v_mul_f32_e32 v58, 0x3c000000, v59
	global_store_short v[50:51], v42, off offset:544
	v_mul_f32_e32 v42, 0x3c000000, v43
	global_store_short v[34:35], v26, off offset:544
	v_mul_f32_e32 v26, 0x3c000000, v27
	global_store_short v[18:19], v0, off offset:608
	v_mul_f32_e32 v0, 0x3c000000, v3
	v_cvt_pk_bf16_f32 v58, v58, s0
	v_cvt_pk_bf16_f32 v42, v42, s0
	v_cvt_pk_bf16_f32 v26, v26, s0
	v_cvt_pk_bf16_f32 v0, v0, s0
	global_store_short v[62:63], v58, off offset:544
	v_mul_f32_e32 v58, 0x3c000000, v60
	global_store_short v[46:47], v42, off offset:544
	v_mul_f32_e32 v42, 0x3c000000, v44
	global_store_short v[30:31], v26, off offset:544
	v_mul_f32_e32 v26, 0x3c000000, v28
	global_store_short v[14:15], v0, off offset:608
	v_mul_f32_e32 v0, 0x3c000000, v4
	v_cvt_pk_bf16_f32 v58, v58, s0
	v_cvt_pk_bf16_f32 v42, v42, s0
	v_cvt_pk_bf16_f32 v26, v26, s0
	v_cvt_pk_bf16_f32 v0, v0, s0
	global_store_short v[72:73], v58, off offset:544
	v_mul_f32_e32 v58, 0x3c000000, v61
	global_store_short v[52:53], v42, off offset:544
	v_mul_f32_e32 v42, 0x3c000000, v45
	global_store_short v[36:37], v26, off offset:544
	v_mul_f32_e32 v26, 0x3c000000, v29
	global_store_short v[20:21], v0, off offset:608
	v_mul_f32_e32 v0, 0x3c000000, v5
	v_cvt_pk_bf16_f32 v58, v58, s0
	v_cvt_pk_bf16_f32 v42, v42, s0
	v_cvt_pk_bf16_f32 v26, v26, s0
	v_cvt_pk_bf16_f32 v0, v0, s0
	v_readlane_b32 s0, v254, 0
	s_add_i32 s8, s8, s0
	v_readlane_b32 s0, v254, 46
	s_add_i32 s9, s9, s0
	s_cmp_lt_i32 s8, 8
	global_store_short v[64:65], v69, off offset:512
	global_store_short v[64:65], v58, off offset:544
	global_store_short v[48:49], v54, off offset:512
	global_store_short v[48:49], v42, off offset:544
	global_store_short v[32:33], v38, off offset:512
	global_store_short v[32:33], v26, off offset:544
	global_store_short v[16:17], v22, off offset:512
	global_store_short v[16:17], v0, off offset:608
	v_readlane_b32 s1, v254, 1
	s_cbranch_scc1 .LBB0_627
	v_mov_b32_e32 v224, 0x358637bd
	v_mov_b32_e32 v225, 0x11800
	v_mov_b32_e32 v226, 0x11804
	v_mov_b32_e32 v227, v229
	v_xor_b32_e32 v249, 32, v186
	v_xor_b32_e32 v250, 16, v186
	v_xor_b32_e32 v251, 8, v186
	v_xor_b32_e32 v252, 4, v186
	v_xor_b32_e32 v253, 2, v186
	v_xor_b32_e32 v212, 1, v186

; __device__ __forceinline__ int tid_() { int t = threadIdx.x; asm volatile("" : "+v"(t)); return t; }
; #define XCD_FOR(u, T)                                                                                         \
;   for (int _x = bid_() & 7, _gb = gridDim.x >> 3, _hi = (int)(((long)(_x + 1) * (T)) >> 3),                    \
;            u = (int)(((long)_x * (T)) >> 3) + (bid_() >> 3);                                                  \
;        u < _hi; u += _gb)
; template <int NT, bool BKN, bool MASK = false, bool ROWSS = false, class Epi> ...
;     ...
;   const int t = tid_(), lane = t & 63, wid = t >> 6, wr = wid >> 1, wc = wid & 1, l16 = lane & 15, quad = lane >> 4;
;   const u16* ap[4];
;   const u16* bp[NT];
;   unsigned amask = 0u;
; #pragma unroll
;   for (int i = 0; i < 4; ++i) {
;     const int row = (t >> 3) + 32 * i;
;     const bool v = MASK ? (row < mvalid) : true;
;     amask |= v ? (1u << i) : 0u;
;     int r = v ? row : 0;
;     if (arows) r = arows[r];
;     ap[i] = A + (size_t)r * lda + (t & 7) * 8;
;   }
; #pragma unroll
;   for (int i = 0; i < NT; ++i) {
;     if (!BKN) bp[i] = B + (size_t)((t >> 3) + 32 * i) * ldb + (t & 7) * 8;
;     else { const int c = t + 256 * i; bp[i] = B + (size_t)(c / CPR) * ldb + (c % CPR) * 8; }
;   }
;   const size_t bstep = BKN ? (size_t)64 * ldb : (size_t)64;
; __device__ __forceinline__ void phase_mix_b(const Params& p, int l, bool last, unsigned char* smem) {
;   XCD_FOR(t, 512) {
;     const int nq = t & 3, k2 = (t >> 2) & 63, b = t >> 8;
;     auto epi = [&](f32x4(&acc)[4][2], int r0, int c0) {
;       auto vf = [&](int, int, float v) { return v * 0.001381067932004976f; };
;       auto rp = [&](int k1) -> u16* { return p.YM + (size_t)(b * SEQ + 64 * k1 + k2) * 1024 + 256 + nq * 64; };
;       epi_staged_bf16<2>(acc, r0, c0, smem, vf, rp);
;     };
;     gemm_tile<2, true>(p.M2, 256, nullptr, 128, p.PF + (size_t)(b * 64 + k2) * 2 * 128 * 256 + nq * 64, 256, 256, smem, epi);
.LBB0_685:
	v_mov_b64_e32 v[18:19], s[4:5]
	global_load_dwordx2 v[10:11], v[18:19], off offset:256
	global_load_dwordx2 v[12:13], v[18:19], off offset:320
	v_mov_b32_e32 v4, v187
	s_ashr_i32 s38, s9, 8
	s_waitcnt vmcnt(0)
	v_ashrrev_i32_e32 v2, 3, v4
	v_ashrrev_i32_e32 v7, 31, v4
	v_add_u32_e32 v8, 0x100, v4
	v_lshrrev_b32_e32 v5, 4, v4
	v_and_b32_e32 v29, 15, v4
	v_bfe_u32 v30, v4, 4, 2
	v_bfe_u32 v9, v4, 1, 3
	v_ashrrev_i32_e32 v3, 31, v2
	v_lshrrev_b32_e32 v7, 29, v7
	v_ashrrev_i32_e32 v16, 31, v8
	v_bfe_u32 v28, v4, 6, 1
	v_lshlrev_b32_e32 v6, 4, v4
	v_ashrrev_i32_e32 v31, 7, v4
	v_xor_b32_e32 v17, v5, v4
	v_bitop3_b32 v5, v5, v9, 3 bitop3:0x6c
	v_lshlrev_b32_e32 v20, 7, v29
	v_bitop3_b32 v9, v30, v9, 4 bitop3:0x36
	v_lshlrev_b64 v[14:15], 9, v[2:3]
	v_add_u32_e32 v3, v4, v7
	v_lshrrev_b32_e32 v7, 29, v16
	v_and_b32_e32 v0, 0x70, v6
	v_and_b32_e32 v6, 0xffffff80, v6
	v_lshlrev_b32_e32 v16, 4, v17
	v_lshl_or_b32 v17, v31, 13, v20
	v_lshl_or_b32 v20, v28, 12, v20
	v_lshlrev_b32_e32 v9, 4, v9
	v_ashrrev_i32_e32 v2, 3, v3
	v_and_b32_e32 v21, -8, v3
	v_add_u32_e32 v7, v8, v7
	v_lshlrev_b32_e32 v5, 4, v5
	v_and_or_b32 v36, v16, s14, v6
	v_or_b32_e32 v32, v9, v17
	v_or_b32_e32 v33, v9, v20
	v_ashrrev_i32_e32 v3, 31, v2
	v_sub_u32_e32 v9, v4, v21
	v_ashrrev_i32_e32 v4, 3, v7
	v_and_b32_e32 v16, -8, v7
	v_or_b32_e32 v34, v5, v17
	v_or_b32_e32 v35, v5, v20
	v_and_b32_e32 v17, -8, v2
	v_and_b32_e32 v20, 7, v2
	v_lshlrev_b64 v[6:7], 9, v[2:3]
	v_lshlrev_b32_e32 v2, 3, v9
	v_ashrrev_i32_e32 v5, 31, v4
	v_sub_u32_e32 v16, v8, v16
	v_lshlrev_b32_e32 v21, 9, v9
	v_lshlrev_b32_e32 v22, 5, v9
	v_and_b32_e32 v23, -8, v4
	v_and_b32_e32 v24, 7, v4
	v_lshlrev_b64 v[8:9], 9, v[4:5]
	v_lshlrev_b32_e32 v4, 3, v16
	v_bitop3_b32 v22, v22, v17, 32 bitop3:0x6c
	v_or_b32_e32 v25, v20, v21
	v_or_b32_e32 v26, 2, v2
	v_or_b32_e32 v27, 3, v2
	v_or_b32_e32 v38, 4, v2
	v_or_b32_e32 v39, 5, v2
	v_or_b32_e32 v40, 6, v2
	v_or_b32_e32 v41, 7, v2
	v_lshlrev_b32_e32 v42, 9, v16
	v_lshlrev_b32_e32 v16, 5, v16
	v_add_u32_e32 v21, v22, v21
	v_add_lshl_u32 v37, v25, v22, 1
	v_lshlrev_b32_e32 v22, 6, v26
	v_lshlrev_b32_e32 v25, 2, v26
	v_lshlrev_b32_e32 v26, 6, v27
	v_lshlrev_b32_e32 v27, 2, v27
	v_lshlrev_b32_e32 v43, 6, v38
	v_lshlrev_b32_e32 v38, 2, v38
	v_lshlrev_b32_e32 v44, 6, v39
	v_lshlrev_b32_e32 v39, 2, v39
	v_lshlrev_b32_e32 v45, 6, v40
	v_lshlrev_b32_e32 v40, 2, v40
	v_lshlrev_b32_e32 v46, 6, v41
	v_lshlrev_b32_e32 v41, 2, v41
	v_bitop3_b32 v16, v16, v23, 32 bitop3:0x6c
	v_or_b32_e32 v47, v24, v42
	v_or_b32_e32 v48, 2, v4
	v_or_b32_e32 v49, 3, v4
	s_bfe_u32 s19, s9, 0x60002
	s_and_b32 s0, s18, 0xc0
	s_lshl_b32 s1, s38, 6
	v_or_b32_e32 v50, 4, v4
	v_or_b32_e32 v51, 5, v4
	v_or_b32_e32 v52, 6, v4
	v_or_b32_e32 v53, 7, v4
	v_or_b32_e32 v21, v21, v20
	v_and_b32_e32 v25, 40, v25
	v_and_b32_e32 v27, 40, v27
	v_and_b32_e32 v54, 48, v38
	v_and_b32_e32 v55, 48, v39
	v_and_b32_e32 v40, 56, v40
	v_and_b32_e32 v41, 56, v41
	v_add_u32_e32 v42, v16, v42
	v_add_lshl_u32 v38, v47, v16, 1
	v_lshlrev_b32_e32 v16, 6, v48
	v_lshlrev_b32_e32 v47, 2, v48
	v_lshlrev_b32_e32 v48, 6, v49
	v_lshlrev_b32_e32 v49, 2, v49
	s_lshl_b32 s94, s0, 1
	s_or_b32 s0, s1, s19
	v_lshlrev_b32_e32 v56, 6, v50
	v_lshlrev_b32_e32 v50, 2, v50
	v_lshlrev_b32_e32 v57, 6, v51
	v_lshlrev_b32_e32 v51, 2, v51
	v_lshlrev_b32_e32 v58, 6, v52
	v_lshlrev_b32_e32 v52, 2, v52
	v_lshlrev_b32_e32 v59, 6, v53
	v_lshlrev_b32_e32 v53, 2, v53
	v_lshlrev_b32_e32 v39, 1, v21
	v_xad_u32 v21, v25, v17, v22
	v_xad_u32 v22, v27, v17, v26
	v_xad_u32 v25, v54, v17, v43
	v_xad_u32 v26, v55, v17, v44
	v_xad_u32 v27, v40, v17, v45
	v_xad_u32 v17, v41, v17, v46
	v_or_b32_e32 v40, v42, v24
	v_and_b32_e32 v41, 40, v47
	v_and_b32_e32 v42, 40, v49
	s_ashr_i32 s1, s0, 31
	v_and_b32_e32 v43, 48, v50
	v_and_b32_e32 v44, 48, v51
	v_and_b32_e32 v45, 56, v52
	v_and_b32_e32 v46, 56, v53
	v_or_b32_e32 v21, v21, v20
	v_or_b32_e32 v22, v22, v20
	v_or_b32_e32 v25, v25, v20
	v_or_b32_e32 v26, v26, v20
	v_or_b32_e32 v27, v27, v20
	v_or_b32_e32 v17, v17, v20
	v_xad_u32 v16, v41, v23, v16
	v_xad_u32 v20, v42, v23, v48
	s_lshl_b64 s[0:1], s[0:1], 17
	v_xad_u32 v47, v43, v23, v56
	v_xad_u32 v48, v44, v23, v57
	v_xad_u32 v49, v45, v23, v58
	v_xad_u32 v23, v46, v23, v59
	v_lshlrev_b32_e32 v46, 1, v17
	v_or_b32_e32 v16, v16, v24
	v_or_b32_e32 v17, v20, v24
	v_lshlrev_b32_e32 v41, 1, v21
	v_or_b32_e32 v20, v47, v24
	v_or_b32_e32 v21, v48, v24
	v_lshlrev_b32_e32 v47, 1, v16
	v_lshlrev_b32_e32 v48, 1, v17
	s_waitcnt lgkmcnt(0)
	v_lshl_add_u64 v[12:13], v[12:13], 0, s[0:1]
	v_lshl_add_u64 v[16:17], v[10:11], 0, v[0:1]
	v_lshlrev_b32_e32 v42, 1, v22
	v_lshlrev_b32_e32 v43, 1, v25
	v_or_b32_e32 v22, v49, v24
	v_or_b32_e32 v23, v23, v24
	v_lshl_add_u64 v[10:11], v[12:13], 0, s[94:95]
	v_lshl_add_u64 v[24:25], v[16:17], 0, v[14:15]
	v_lshl_add_u64 v[6:7], v[10:11], 0, v[6:7]
	v_lshl_add_u64 v[8:9], v[10:11], 0, v[8:9]
	v_add_co_u32_e32 v10, vcc, s69, v24
	s_mov_b64 s[0:1], 0xc000
	s_nop 0
	v_addc_co_u32_e32 v11, vcc, 0, v25, vcc
	v_add_co_u32_e32 v12, vcc, s34, v24
	v_lshlrev_b32_e32 v44, 1, v26
	v_lshlrev_b32_e32 v45, 1, v27
	v_lshl_add_u64 v[26:27], v[24:25], 0, s[0:1]
	v_addc_co_u32_e32 v13, vcc, 0, v25, vcc
	s_mov_b32 s0, 0xc000
	v_add_co_u32_e32 v14, vcc, s0, v24
	v_ashrrev_i32_e32 v3, 31, v2
	v_ashrrev_i32_e32 v5, 31, v4
	v_addc_co_u32_e32 v15, vcc, 0, v25, vcc
	s_barrier
; template <int NT, bool BKN, bool MASK = false, bool ROWSS = false, class Epi> ...
;     ...
;   const int nk = K >> 6;
;   const int nkm1 = nk - 1;
;   __syncthreads();
;   GEMM_LOAD(ra0, rb0, 0);
;   GEMM_LOAD(ra1, rb1, 1);
;   GEMM_STORE(ra0, rb0, 0);
;   GEMM_LOAD(ra0, rb0, (2 < nkm1 ? 2 : nkm1));
;   __syncthreads();
;   for (int kt = 0; kt < nk - 2; kt += 2) {
;     GEMM_COMPUTE(0);
;     GEMM_STORE(ra1, rb1, 1);
;     GEMM_LOAD(ra1, rb1, kt + 3);
	v_lshlrev_b32_e32 v49, 1, v20
	v_lshlrev_b32_e32 v50, 1, v21
	v_lshlrev_b32_e32 v51, 1, v22
	v_lshlrev_b32_e32 v52, 1, v23
	v_lshl_add_u64 v[20:21], v[24:25], 0, s[62:63]
	v_lshl_add_u64 v[22:23], v[24:25], 0, s[10:11]
	global_load_dwordx4 v[54:57], v[24:25], off
	global_load_dwordx4 v[58:61], v[24:25], off offset:128
	v_lshl_add_u64 v[110:111], v[2:3], 1, v[6:7]
	v_lshl_add_u64 v[112:113], v[4:5], 1, v[8:9]
	global_load_dwordx4 v[62:65], v[10:11], off
	global_load_dwordx4 v[66:69], v[12:13], off
	global_load_dwordx4 v[70:73], v[14:15], off
	global_load_dwordx4 v[74:77], v[20:21], off offset:128
	global_load_dwordx4 v[2:5], v[24:25], off offset:256
	global_load_dwordx4 v[78:81], v[22:23], off offset:128
	global_load_dwordx4 v[6:9], v[20:21], off offset:256
	global_load_dwordx4 v[82:85], v[26:27], off offset:128
	global_load_dwordx4 v[10:13], v[22:23], off offset:256
	global_load_dwordx4 v[14:17], v[26:27], off offset:256
	global_load_dwordx4 v[86:89], v[110:111], off
	global_load_dwordx4 v[90:93], v[112:113], off
	v_add_co_u32_e32 v94, vcc, s34, v110
	v_lshlrev_b32_e32 v40, 1, v40
	s_nop 0
	v_addc_co_u32_e32 v95, vcc, 0, v111, vcc
	v_add_co_u32_e32 v98, vcc, s34, v112
	v_lshlrev_b32_e32 v0, 6, v31
	s_nop 0
	v_addc_co_u32_e32 v99, vcc, 0, v113, vcc
	v_add_co_u32_e32 v102, vcc, s15, v110
	v_lshlrev_b32_e32 v29, 1, v29
	s_nop 0
	v_addc_co_u32_e32 v103, vcc, 0, v111, vcc
	v_add_co_u32_e32 v106, vcc, s15, v112
	s_add_i32 s9, s9, s3
	s_nop 0
	v_addc_co_u32_e32 v107, vcc, 0, v113, vcc
	global_load_dwordx4 v[94:97], v[94:95], off
	s_nop 0
	global_load_dwordx4 v[98:101], v[98:99], off
	s_nop 0
	global_load_dwordx4 v[102:105], v[102:103], off
	s_nop 0
	global_load_dwordx4 v[106:109], v[106:107], off
	s_waitcnt vmcnt(0) lgkmcnt(0)
	ds_write_b128 v36, v[54:57]
	ds_write_b128 v36, v[62:65] offset:4096
	ds_write_b128 v36, v[66:69] offset:8192
	ds_write_b128 v36, v[70:73] offset:12288
	ds_write_b16 v39, v86 offset:16384
	ds_write_b16_d16_hi v37, v86 offset:16512
	ds_write_b16 v41, v87 offset:16384
	ds_write_b16_d16_hi v42, v87 offset:16384
	ds_write_b16 v43, v88 offset:16384
	ds_write_b16_d16_hi v44, v88 offset:16384
	ds_write_b16 v45, v89 offset:16384
	ds_write_b16_d16_hi v46, v89 offset:16384
	ds_write_b16 v40, v90 offset:16384
	ds_write_b16_d16_hi v38, v90 offset:16512
	ds_write_b16 v47, v91 offset:16384
	ds_write_b16_d16_hi v48, v91 offset:16384
	ds_write_b16 v49, v92 offset:16384
	ds_write_b16_d16_hi v50, v92 offset:16384
	ds_write_b16 v51, v93 offset:16384
	ds_write_b16_d16_hi v52, v93 offset:16384
	s_waitcnt lgkmcnt(0)
	s_barrier
	ds_read_b128 v[54:57], v34
	ds_read_b128 v[62:65], v35 offset:16384
	ds_read_b128 v[66:69], v34 offset:2048
	ds_read_b128 v[70:73], v35 offset:18432
	ds_read_b128 v[90:93], v34 offset:4096
	v_add_co_u32_e32 v146, vcc, s55, v110
	ds_read_b128 v[114:117], v34 offset:6144
	ds_read_b128 v[118:121], v32
	ds_read_b128 v[122:125], v32 offset:2048
	v_addc_co_u32_e32 v147, vcc, 0, v111, vcc
	v_add_co_u32_e32 v148, vcc, s55, v112
	ds_read_b128 v[126:129], v32 offset:4096
	ds_read_b128 v[130:133], v32 offset:6144
	ds_read_b128 v[134:137], v33 offset:16384
	ds_read_b128 v[142:145], v33 offset:18432
	ds_write_b128 v36, v[58:61] offset:32768
	ds_write_b128 v36, v[74:77] offset:36864
	ds_write_b128 v36, v[78:81] offset:40960
	ds_write_b128 v36, v[82:85] offset:45056
	v_addc_co_u32_e32 v149, vcc, 0, v113, vcc
	s_waitcnt lgkmcnt(11)
	v_mfma_f32_16x16x32_bf16 v[138:141], v[90:93], v[62:65], 0
	global_load_dwordx4 v[74:77], v[24:25], off offset:384
	global_load_dwordx4 v[78:81], v[20:21], off offset:384
	s_nop 0
	global_load_dwordx4 v[20:23], v[22:23], off offset:384
	s_nop 0
	global_load_dwordx4 v[24:27], v[26:27], off offset:384
	s_add_i32 s18, s18, s54
	v_mfma_f32_16x16x32_bf16 v[58:61], v[90:93], v[70:73], 0
	global_load_dwordx4 v[82:85], v[146:147], off
	global_load_dwordx4 v[90:93], v[148:149], off
	ds_write_b16 v39, v94 offset:49152
	ds_write_b16_d16_hi v37, v94 offset:49280
	ds_write_b16 v41, v95 offset:49152
	ds_write_b16_d16_hi v42, v95 offset:49152
	v_mfma_f32_16x16x32_bf16 v[86:89], v[54:57], v[62:65], 0
	ds_write_b16 v43, v96 offset:49152
	ds_write_b16_d16_hi v44, v96 offset:49152
	ds_write_b16 v45, v97 offset:49152
	ds_write_b16_d16_hi v46, v97 offset:49152
	ds_write_b16 v40, v98 offset:49152
	ds_write_b16_d16_hi v38, v98 offset:49280
	ds_write_b16 v47, v99 offset:49152
	ds_write_b16_d16_hi v48, v99 offset:49152
	ds_write_b16 v49, v100 offset:49152
	v_mfma_f32_16x16x32_bf16 v[54:57], v[54:57], v[70:73], 0
	ds_write_b16_d16_hi v50, v100 offset:49152
	ds_write_b16 v51, v101 offset:49152
	ds_write_b16_d16_hi v52, v101 offset:49152
	s_waitcnt lgkmcnt(0)
	s_barrier
; template <int NT, bool BKN, bool MASK = false, bool ROWSS = false, class Epi> ...
;     ...
;   for (int kt = 0; kt < nk - 2; kt += 2) {
;     GEMM_COMPUTE(0);
;     GEMM_STORE(ra1, rb1, 1);
;     GEMM_LOAD(ra1, rb1, kt + 3);
;     __syncthreads();
;     GEMM_COMPUTE(1);
;     GEMM_STORE(ra0, rb0, 0);
;     GEMM_LOAD(ra0, rb0, (kt + 4 < nkm1 ? kt + 4 : nkm1));
;     __syncthreads();
;   }
;   GEMM_COMPUTE(0);
;   GEMM_STORE(ra1, rb1, 1);
;   __syncthreads();
;   GEMM_COMPUTE(1);
	v_mfma_f32_16x16x32_bf16 v[110:113], v[66:69], v[62:65], 0
	ds_read_b128 v[98:101], v34 offset:32768
	v_mfma_f32_16x16x32_bf16 v[66:69], v[66:69], v[70:73], 0
	v_mfma_f32_16x16x32_bf16 v[62:65], v[114:117], v[62:65], 0
	v_mfma_f32_16x16x32_bf16 v[70:73], v[114:117], v[70:73], 0
	v_mfma_f32_16x16x32_bf16 v[86:89], v[118:121], v[134:137], v[86:89]
	v_mfma_f32_16x16x32_bf16 v[54:57], v[118:121], v[142:145], v[54:57]
	v_mfma_f32_16x16x32_bf16 v[110:113], v[122:125], v[134:137], v[110:113]
	v_mfma_f32_16x16x32_bf16 v[66:69], v[122:125], v[142:145], v[66:69]
	ds_read_b128 v[114:117], v35 offset:49152
	ds_read_b128 v[118:121], v34 offset:34816
	ds_read_b128 v[122:125], v35 offset:51200
	s_waitcnt lgkmcnt(0)
	v_mfma_f32_16x16x32_bf16 v[86:89], v[98:101], v[114:117], v[86:89]
	v_mfma_f32_16x16x32_bf16 v[54:57], v[98:101], v[122:125], v[54:57]
	v_mfma_f32_16x16x32_bf16 v[98:101], v[118:121], v[114:117], v[110:113]
	v_mfma_f32_16x16x32_bf16 v[66:69], v[118:121], v[122:125], v[66:69]
	s_nop 1
	ds_read_b128 v[110:113], v34 offset:36864
	ds_read_b128 v[118:121], v34 offset:38912
	v_mfma_f32_16x16x32_bf16 v[94:97], v[126:129], v[134:137], v[138:141]
	v_mfma_f32_16x16x32_bf16 v[58:61], v[126:129], v[142:145], v[58:61]
	v_mfma_f32_16x16x32_bf16 v[62:65], v[130:133], v[134:137], v[62:65]
	v_mfma_f32_16x16x32_bf16 v[70:73], v[130:133], v[142:145], v[70:73]
	ds_read_b128 v[126:129], v32 offset:32768
	ds_read_b128 v[130:133], v32 offset:34816
	s_waitcnt lgkmcnt(0)
	v_mfma_f32_16x16x32_bf16 v[94:97], v[110:113], v[114:117], v[94:97]
	v_mfma_f32_16x16x32_bf16 v[58:61], v[110:113], v[122:125], v[58:61]
	ds_read_b128 v[110:113], v32 offset:36864
	ds_read_b128 v[134:137], v32 offset:38912
	ds_read_b128 v[138:141], v33 offset:49152
	v_mfma_f32_16x16x32_bf16 v[62:65], v[118:121], v[114:117], v[62:65]
	ds_read_b128 v[114:117], v33 offset:51200
	ds_write_b128 v36, v[2:5]
	ds_write_b128 v36, v[6:9] offset:4096
	ds_write_b128 v36, v[10:13] offset:8192
	ds_write_b128 v36, v[14:17] offset:12288
	ds_write_b16 v39, v102 offset:16384
	v_mfma_f32_16x16x32_bf16 v[2:5], v[118:121], v[122:125], v[70:73]
	ds_write_b16_d16_hi v37, v102 offset:16512
	ds_write_b16 v41, v103 offset:16384
	ds_write_b16_d16_hi v42, v103 offset:16384
	ds_write_b16 v43, v104 offset:16384
	ds_write_b16_d16_hi v44, v104 offset:16384
	ds_write_b16 v45, v105 offset:16384
	ds_write_b16_d16_hi v46, v105 offset:16384
	ds_write_b16 v40, v106 offset:16384
	ds_write_b16_d16_hi v38, v106 offset:16512
	ds_write_b16 v47, v107 offset:16384
	ds_write_b16_d16_hi v48, v107 offset:16384
	ds_write_b16 v49, v108 offset:16384
	ds_write_b16_d16_hi v50, v108 offset:16384
	ds_write_b16 v51, v109 offset:16384
	ds_write_b16_d16_hi v52, v109 offset:16384
	s_waitcnt lgkmcnt(0)
	s_barrier
	ds_read_b128 v[70:73], v34
	v_mfma_f32_16x16x32_bf16 v[6:9], v[126:129], v[138:141], v[86:89]
	v_mfma_f32_16x16x32_bf16 v[10:13], v[126:129], v[114:117], v[54:57]
	v_mfma_f32_16x16x32_bf16 v[14:17], v[130:133], v[138:141], v[98:101]
	v_mfma_f32_16x16x32_bf16 v[54:57], v[130:133], v[114:117], v[66:69]
	v_mfma_f32_16x16x32_bf16 v[66:69], v[110:113], v[138:141], v[94:97]
	ds_read_b128 v[86:89], v35 offset:16384
	s_nop 1
	ds_read_b128 v[94:97], v34 offset:2048
	ds_read_b128 v[98:101], v35 offset:18432
	v_mfma_f32_16x16x32_bf16 v[58:61], v[110:113], v[114:117], v[58:61]
	s_waitcnt lgkmcnt(0)
	v_mfma_f32_16x16x32_bf16 v[6:9], v[70:73], v[86:89], v[6:9]
	v_mfma_f32_16x16x32_bf16 v[10:13], v[70:73], v[98:101], v[10:13]
	v_mfma_f32_16x16x32_bf16 v[14:17], v[94:97], v[86:89], v[14:17]
	v_mfma_f32_16x16x32_bf16 v[54:57], v[94:97], v[98:101], v[54:57]
	ds_read_b128 v[70:73], v34 offset:4096
	ds_read_b128 v[94:97], v34 offset:6144
	v_mfma_f32_16x16x32_bf16 v[62:65], v[134:137], v[138:141], v[62:65]
	v_mfma_f32_16x16x32_bf16 v[2:5], v[134:137], v[114:117], v[2:5]
	s_waitcnt lgkmcnt(0)
	v_mfma_f32_16x16x32_bf16 v[66:69], v[70:73], v[86:89], v[66:69]
	v_mfma_f32_16x16x32_bf16 v[58:61], v[70:73], v[98:101], v[58:61]
	ds_read_b128 v[70:73], v32
	v_mfma_f32_16x16x32_bf16 v[62:65], v[94:97], v[86:89], v[62:65]
	v_mfma_f32_16x16x32_bf16 v[2:5], v[94:97], v[98:101], v[2:5]
	ds_read_b128 v[86:89], v33 offset:16384
	ds_read_b128 v[94:97], v32 offset:2048
	ds_read_b128 v[98:101], v33 offset:18432
	s_waitcnt lgkmcnt(0)
	v_mfma_f32_16x16x32_bf16 v[6:9], v[70:73], v[86:89], v[6:9]
	v_mfma_f32_16x16x32_bf16 v[10:13], v[70:73], v[98:101], v[10:13]
	v_mfma_f32_16x16x32_bf16 v[14:17], v[94:97], v[86:89], v[14:17]
	v_mfma_f32_16x16x32_bf16 v[54:57], v[94:97], v[98:101], v[54:57]
	ds_read_b128 v[70:73], v32 offset:4096
	ds_read_b128 v[94:97], v32 offset:6144
	s_waitcnt vmcnt(0)
	ds_write_b128 v36, v[74:77] offset:32768
	ds_write_b128 v36, v[78:81] offset:36864
	ds_write_b128 v36, v[20:23] offset:40960
	ds_write_b128 v36, v[24:27] offset:45056
	ds_write_b16 v39, v82 offset:49152
	ds_write_b16_d16_hi v37, v82 offset:49280
	ds_write_b16 v41, v83 offset:49152
	ds_write_b16_d16_hi v42, v83 offset:49152
	ds_write_b16 v43, v84 offset:49152
	ds_write_b16_d16_hi v44, v84 offset:49152
	ds_write_b16 v45, v85 offset:49152
	ds_write_b16_d16_hi v46, v85 offset:49152
	ds_write_b16 v40, v90 offset:49152
	ds_write_b16_d16_hi v38, v90 offset:49280
	ds_write_b16 v47, v91 offset:49152
	ds_write_b16_d16_hi v48, v91 offset:49152
	ds_write_b16 v49, v92 offset:49152
	ds_write_b16_d16_hi v50, v92 offset:49152
	ds_write_b16 v51, v93 offset:49152
	ds_write_b16_d16_hi v52, v93 offset:49152
	s_waitcnt lgkmcnt(0)
	s_barrier
; __device__ __forceinline__ u16 f2bf(float f) { return (u16)(pack2(f, 0.f) & 0xffffu); }
; __device__ __forceinline__ int tid_() { int t = threadIdx.x; asm volatile("" : "+v"(t)); return t; }
; template <int NT, bool BKN, bool MASK = false, bool ROWSS = false, class Epi> ...
;     ...
;   GEMM_COMPUTE(1);
; template <int NT, class VF, class RP>
; __device__ __forceinline__ void epi_staged_bf16(f32x4 (&acc)[4][NT], int r0, int c0, unsigned char* smem, VF vf, RP rowptr) {
;   constexpr int BN = NT * 32, PITCH = BN + 8, CPR = BN / 8;
;   u16* Ts = (u16*)smem;
;   const int t = tid_();
;   __syncthreads();
; #pragma unroll
;   for (int mi = 0; mi < 4; ++mi)
; #pragma unroll
;     for (int ni = 0; ni < NT; ++ni)
; #pragma unroll
;       for (int j = 0; j < 4; ++j) {
;         const int r = r0 + mi * 16 + j, c = c0 + ni * 16;
;         Ts[r * PITCH + c] = f2bf(vf(r, c, acc[mi][ni][j]));
;       }
;   __syncthreads();
; __device__ __forceinline__ void phase_mix_b(const Params& p, int l, bool last, unsigned char* smem) {
;     ...
;     auto epi = [&](f32x4(&acc)[4][2], int r0, int c0) {
;       auto vf = [&](int, int, float v) { return v * 0.001381067932004976f; };
	ds_read_b128 v[20:23], v34 offset:32768
	ds_read_b128 v[24:27], v35 offset:49152
	ds_read_b128 v[36:39], v34 offset:34816
	ds_read_b128 v[40:43], v35 offset:51200
	s_waitcnt lgkmcnt(2)
	v_mfma_f32_16x16x32_bf16 v[6:9], v[20:23], v[24:27], v[6:9]
	s_waitcnt lgkmcnt(0)
	v_mfma_f32_16x16x32_bf16 v[10:13], v[20:23], v[40:43], v[10:13]
	v_mfma_f32_16x16x32_bf16 v[14:17], v[36:39], v[24:27], v[14:17]
	v_mfma_f32_16x16x32_bf16 v[20:23], v[36:39], v[40:43], v[54:57]
	ds_read_b128 v[36:39], v34 offset:36864
	ds_read_b128 v[44:47], v34 offset:38912
	s_nop 0
	ds_read_b128 v[52:55], v32 offset:32768
	v_mfma_f32_16x16x32_bf16 v[66:69], v[70:73], v[86:89], v[66:69]
	v_mfma_f32_16x16x32_bf16 v[58:61], v[70:73], v[98:101], v[58:61]
	v_mfma_f32_16x16x32_bf16 v[62:65], v[94:97], v[86:89], v[62:65]
	v_mfma_f32_16x16x32_bf16 v[2:5], v[94:97], v[98:101], v[2:5]
	s_waitcnt lgkmcnt(2)
	v_mfma_f32_16x16x32_bf16 v[48:51], v[36:39], v[24:27], v[66:69]
	v_mfma_f32_16x16x32_bf16 v[34:37], v[36:39], v[40:43], v[58:61]
	s_waitcnt lgkmcnt(1)
	v_mfma_f32_16x16x32_bf16 v[24:27], v[44:47], v[24:27], v[62:65]
	s_nop 0
	v_mov_b32_e32 v60, v187
	v_mfma_f32_16x16x32_bf16 v[2:5], v[44:47], v[40:43], v[2:5]
	ds_read_b128 v[38:41], v33 offset:49152
	ds_read_b128 v[42:45], v32 offset:34816
	ds_read_b128 v[56:59], v33 offset:51200
	s_waitcnt lgkmcnt(2)
	v_mfma_f32_16x16x32_bf16 v[6:9], v[52:55], v[38:41], v[6:9]
	s_waitcnt lgkmcnt(0)
	v_mfma_f32_16x16x32_bf16 v[10:13], v[52:55], v[56:59], v[10:13]
	v_mfma_f32_16x16x32_bf16 v[14:17], v[42:45], v[38:41], v[14:17]
	v_mfma_f32_16x16x32_bf16 v[20:23], v[42:45], v[56:59], v[20:23]
	ds_read_b128 v[42:45], v32 offset:36864
	ds_read_b128 v[52:55], v32 offset:38912
	v_lshl_or_b32 v32, v30, 2, v0
	v_lshl_or_b32 v0, v28, 6, v29
	s_waitcnt lgkmcnt(1)
	v_mfma_f32_16x16x32_bf16 v[46:49], v[42:45], v[38:41], v[48:51]
	v_mad_u64_u32 v[32:33], s[0:1], v32, s96, v[0:1]
	v_mul_f32_e32 v0, 0x3ab504f3, v6
	v_mfma_f32_16x16x32_bf16 v[28:31], v[42:45], v[56:59], v[34:37]
	v_mul_f32_e32 v6, 0x3ab504f3, v7
	v_mul_f32_e32 v7, 0x3ab504f3, v8
	v_mul_f32_e32 v8, 0x3ab504f3, v9
	s_waitcnt lgkmcnt(0)
	v_mfma_f32_16x16x32_bf16 v[24:27], v[52:55], v[38:41], v[24:27]
	v_mul_f32_e32 v9, 0x3ab504f3, v10
	v_mul_f32_e32 v10, 0x3ab504f3, v11
	v_mul_f32_e32 v11, 0x3ab504f3, v12
	v_mfma_f32_16x16x32_bf16 v[2:5], v[52:55], v[56:59], v[2:5]
	v_mul_f32_e32 v12, 0x3ab504f3, v13
	v_mul_f32_e32 v13, 0x3ab504f3, v14
	v_mul_f32_e32 v14, 0x3ab504f3, v15
	v_mul_f32_e32 v15, 0x3ab504f3, v16
	v_mul_f32_e32 v16, 0x3ab504f3, v17
	v_mul_f32_e32 v17, 0x3ab504f3, v20
	v_mul_f32_e32 v20, 0x3ab504f3, v21
	v_mul_f32_e32 v21, 0x3ab504f3, v22
	v_mul_f32_e32 v22, 0x3ab504f3, v23
	v_mul_f32_e32 v23, 0x3ab504f3, v46
	v_mul_f32_e32 v33, 0x3ab504f3, v47
	v_mul_f32_e32 v34, 0x3ab504f3, v48
	v_mul_f32_e32 v35, 0x3ab504f3, v49
	v_mul_f32_e32 v28, 0x3ab504f3, v28
	v_mul_f32_e32 v29, 0x3ab504f3, v29
	v_mul_f32_e32 v30, 0x3ab504f3, v30
	v_mul_f32_e32 v31, 0x3ab504f3, v31
	v_mul_f32_e32 v24, 0x3ab504f3, v24
	v_mul_f32_e32 v25, 0x3ab504f3, v25
	v_mul_f32_e32 v26, 0x3ab504f3, v26
	v_mul_f32_e32 v27, 0x3ab504f3, v27
	v_mul_f32_e32 v2, 0x3ab504f3, v2
	v_mul_f32_e32 v3, 0x3ab504f3, v3
	v_mul_f32_e32 v4, 0x3ab504f3, v4
	v_mul_f32_e32 v5, 0x3ab504f3, v5
	v_cvt_pk_bf16_f32 v0, v0, s0
	v_cvt_pk_bf16_f32 v6, v6, s0
	v_cvt_pk_bf16_f32 v7, v7, s0
	s_barrier
	v_cvt_pk_bf16_f32 v8, v8, s0
	v_cvt_pk_bf16_f32 v9, v9, s0
	v_cvt_pk_bf16_f32 v10, v10, s0
	v_cvt_pk_bf16_f32 v11, v11, s0
	v_cvt_pk_bf16_f32 v12, v12, s0
	v_cvt_pk_bf16_f32 v13, v13, s0
	v_cvt_pk_bf16_f32 v14, v14, s0
	v_cvt_pk_bf16_f32 v15, v15, s0
	v_cvt_pk_bf16_f32 v16, v16, s0
	v_cvt_pk_bf16_f32 v17, v17, s0
	v_cvt_pk_bf16_f32 v20, v20, s0
	v_cvt_pk_bf16_f32 v21, v21, s0
	v_cvt_pk_bf16_f32 v22, v22, s0
	v_cvt_pk_bf16_f32 v23, v23, s0
	v_cvt_pk_bf16_f32 v33, v33, s0
	v_cvt_pk_bf16_f32 v34, v34, s0
	v_cvt_pk_bf16_f32 v35, v35, s0
	v_cvt_pk_bf16_f32 v28, v28, s0
	v_cvt_pk_bf16_f32 v29, v29, s0
	v_cvt_pk_bf16_f32 v30, v30, s0
	v_cvt_pk_bf16_f32 v31, v31, s0
	v_cvt_pk_bf16_f32 v24, v24, s0
	v_cvt_pk_bf16_f32 v25, v25, s0
	v_cvt_pk_bf16_f32 v26, v26, s0
	v_cvt_pk_bf16_f32 v27, v27, s0
	v_cvt_pk_bf16_f32 v2, v2, s0
	v_cvt_pk_bf16_f32 v3, v3, s0
	v_cvt_pk_bf16_f32 v4, v4, s0
	v_cvt_pk_bf16_f32 v5, v5, s0
	ds_write_b16 v32, v0
	ds_write_b16 v32, v6 offset:144
	ds_write_b16 v32, v7 offset:288
	ds_write_b16 v32, v8 offset:432
	ds_write_b16 v32, v9 offset:32
	ds_write_b16 v32, v10 offset:176
	ds_write_b16 v32, v11 offset:320
	ds_write_b16 v32, v12 offset:464
	ds_write_b16 v32, v13 offset:2304
	ds_write_b16 v32, v14 offset:2448
	ds_write_b16 v32, v15 offset:2592
	ds_write_b16 v32, v16 offset:2736
	ds_write_b16 v32, v17 offset:2336
	ds_write_b16 v32, v20 offset:2480
	ds_write_b16 v32, v21 offset:2624
	ds_write_b16 v32, v22 offset:2768
	ds_write_b16 v32, v23 offset:4608
	ds_write_b16 v32, v33 offset:4752
	ds_write_b16 v32, v34 offset:4896
	ds_write_b16 v32, v35 offset:5040
	ds_write_b16 v32, v28 offset:4640
	ds_write_b16 v32, v29 offset:4784
	ds_write_b16 v32, v30 offset:4928
	ds_write_b16 v32, v31 offset:5072
	ds_write_b16 v32, v24 offset:6912
	ds_write_b16 v32, v25 offset:7056
	ds_write_b16 v32, v26 offset:7200
	ds_write_b16 v32, v27 offset:7344
	ds_write_b16 v32, v2 offset:6944
	ds_write_b16 v32, v3 offset:7088
	ds_write_b16 v32, v4 offset:7232
	ds_write_b16 v32, v5 offset:7376
	s_waitcnt lgkmcnt(0)
	s_barrier
; __device__ __forceinline__ int tid_() { int t = threadIdx.x; asm volatile("" : "+v"(t)); return t; }
; __device__ __forceinline__ int bid_() { int b = blockIdx.x; asm volatile("" : "+s"(b)); return b; }
; template <int NT, class VF, class RP>
; __device__ __forceinline__ void epi_staged_bf16(f32x4 (&acc)[4][NT], int r0, int c0, unsigned char* smem, VF vf, RP rowptr) {
;     ...
; #pragma unroll
;   for (int i = 0; i < CPR / 2; ++i) {
;     const int c = t + 256 * i, row = c / CPR, ch = c % CPR;
;     u16* d = rowptr(row);
;     if (d) *(u32x4*)(d + ch * 8) = *(const u32x4*)(Ts + row * PITCH + ch * 8);
;   }
; __device__ __forceinline__ void phase_mix_b(const Params& p, int l, bool last, unsigned char* smem) {
;     ...
;   const int tt = tid_(), lane = tt & 63, wid = tt >> 6;
;   const int gw = bid_() * 4 + wid, nw = gridDim.x * 4;
;   const float QSCALE = 0.07216878364870322f * 1.4426950408889634f;
;   for (int row = gw; row < TT; row += nw) {
;     const bool lat = row < T_LAT;
;     const int b = row_batch(row), pos = row_pos(row);
;     float cs = 1.f, sn = 0.f;
;     if (lat) {
;       const int n = row & (SEQ - 1);
;       const int r = lane, sub = r & 31, i = sub & 15;
;       const float ps = (r < 32) ? (float)(n >> 6) : (float)(n & 63);
;       const float fr = __builtin_amdgcn_exp2f(-(float)i * 0.83048202372184058696f);
;       const float ang = ps * fr;
;       sn = __sinf(ang);
;       cs = __cosf(ang);
;     }
	global_load_dwordx2 v[6:7], v[18:19], off offset:296
	v_ashrrev_i32_e32 v0, 31, v60
	v_lshrrev_b32_e32 v0, 29, v0
	v_add_u32_e32 v0, v60, v0
	s_lshl_b32 s0, s38, 13
	v_ashrrev_i32_e32 v2, 3, v0
	v_and_b32_e32 v0, -8, v0
	v_lshl_add_u32 v3, v2, 6, s0
	v_sub_u32_e32 v0, v60, v0
	v_mul_lo_u32 v2, v2, s96
	v_or_b32_e32 v8, s19, v3
	v_lshlrev_b32_e32 v10, 3, v0
	v_lshl_add_u32 v0, v0, 4, v2
	v_ashrrev_i32_e32 v9, 31, v8
	ds_read_b128 v[2:5], v0
	v_lshlrev_b64 v[8:9], 11, v[8:9]
	v_ashrrev_i32_e32 v11, 31, v10
	v_add_u32_e32 v0, 0x100, v60
	s_cmp_ge_i32 s9, s8
	s_waitcnt vmcnt(0) lgkmcnt(0)
	v_lshl_add_u64 v[6:7], v[6:7], 0, v[8:9]
	v_lshl_add_u64 v[6:7], v[6:7], 0, s[94:95]
	v_lshl_add_u64 v[6:7], v[10:11], 1, v[6:7]
	global_store_dwordx4 v[6:7], v[2:5], off offset:512
	global_load_dwordx2 v[6:7], v[18:19], off offset:296
	s_nop 0
	v_ashrrev_i32_e32 v2, 31, v0
	v_lshrrev_b32_e32 v2, 29, v2
	v_add_u32_e32 v2, v0, v2
	v_ashrrev_i32_e32 v3, 3, v2
	v_and_b32_e32 v2, -8, v2
	v_lshl_add_u32 v4, v3, 6, s0
	v_sub_u32_e32 v0, v0, v2
	v_mul_lo_u32 v2, v3, s96
	v_or_b32_e32 v8, s19, v4
	v_lshlrev_b32_e32 v10, 3, v0
	v_lshl_add_u32 v0, v0, 4, v2
	v_ashrrev_i32_e32 v9, 31, v8
	ds_read_b128 v[2:5], v0
	v_lshlrev_b64 v[8:9], 11, v[8:9]
	v_ashrrev_i32_e32 v11, 31, v10
	v_add_u32_e32 v0, 0x200, v60
	s_waitcnt vmcnt(0) lgkmcnt(0)
	v_lshl_add_u64 v[6:7], v[6:7], 0, v[8:9]
	v_lshl_add_u64 v[6:7], v[6:7], 0, s[94:95]
	v_lshl_add_u64 v[6:7], v[10:11], 1, v[6:7]
	global_store_dwordx4 v[6:7], v[2:5], off offset:512
	global_load_dwordx2 v[6:7], v[18:19], off offset:296
	s_nop 0
	v_ashrrev_i32_e32 v2, 31, v0
	v_lshrrev_b32_e32 v2, 29, v2
	v_add_u32_e32 v2, v0, v2
	v_ashrrev_i32_e32 v3, 3, v2
	v_and_b32_e32 v2, -8, v2
	v_lshl_add_u32 v4, v3, 6, s0
	v_sub_u32_e32 v0, v0, v2
	v_mul_lo_u32 v2, v3, s96
	v_or_b32_e32 v8, s19, v4
	v_lshlrev_b32_e32 v10, 3, v0
	v_lshl_add_u32 v0, v0, 4, v2
	v_ashrrev_i32_e32 v9, 31, v8
	ds_read_b128 v[2:5], v0
	v_lshlrev_b64 v[8:9], 11, v[8:9]
	v_ashrrev_i32_e32 v11, 31, v10
	v_add_u32_e32 v0, 0x300, v60
	s_waitcnt vmcnt(0) lgkmcnt(0)
	v_lshl_add_u64 v[6:7], v[6:7], 0, v[8:9]
	v_lshl_add_u64 v[6:7], v[6:7], 0, s[94:95]
	v_lshl_add_u64 v[6:7], v[10:11], 1, v[6:7]
	global_store_dwordx4 v[6:7], v[2:5], off offset:512
	global_load_dwordx2 v[6:7], v[18:19], off offset:296
	s_nop 0
	v_ashrrev_i32_e32 v2, 31, v0
	v_lshrrev_b32_e32 v2, 29, v2
	v_add_u32_e32 v2, v0, v2
	v_ashrrev_i32_e32 v3, 3, v2
	v_and_b32_e32 v2, -8, v2
	v_lshl_add_u32 v4, v3, 6, s0
	v_sub_u32_e32 v0, v0, v2
	v_mul_lo_u32 v2, v3, s96
	v_or_b32_e32 v8, s19, v4
	v_lshlrev_b32_e32 v10, 3, v0
	v_lshl_add_u32 v0, v0, 4, v2
	v_ashrrev_i32_e32 v9, 31, v8
	ds_read_b128 v[2:5], v0
	v_lshlrev_b64 v[8:9], 11, v[8:9]
	v_ashrrev_i32_e32 v11, 31, v10
	s_waitcnt vmcnt(0) lgkmcnt(0)
	v_lshl_add_u64 v[6:7], v[6:7], 0, v[8:9]
	v_lshl_add_u64 v[6:7], v[6:7], 0, s[94:95]
	v_lshl_add_u64 v[6:7], v[10:11], 1, v[6:7]
	global_store_dwordx4 v[6:7], v[2:5], off offset:512
	s_cbranch_scc0 .LBB0_685
.LBB0_686:
	s_waitcnt vmcnt(0)
	v_mov_b32_e32 v3, v187
	s_mov_b32 s0, s2
	v_ashrrev_i32_e32 v0, 6, v3
	s_mul_i32 s94, s36, 0xc0
	v_lshl_add_u32 v2, s0, 2, v0
	v_cmp_gt_i32_e32 vcc, s68, v2
	s_and_saveexec_b64 s[0:1], vcc
	s_cbranch_execz .LBB0_711
	v_mov_b64_e32 v[8:9], s[4:5]
	global_load_dwordx4 v[4:7], v[8:9], off offset:112
	global_load_dwordx2 v[18:19], v[8:9], off offset:288
	global_load_dwordx4 v[10:13], v[8:9], off offset:352
	global_load_dwordx4 v[14:17], v[8:9], off offset:328
	v_and_b32_e32 v8, 63, v3
	s_lshl_b64 s[4:5], s[94:95], 2
	v_lshlrev_b32_e32 v0, 2, v8
	v_cmp_lt_i32_e64 s[40:41], v249, v227
	v_lshlrev_b32_e32 v20, 1, v8
	v_mov_b32_e32 v21, v1
	v_cmp_gt_u32_e32 vcc, 32, v8
	s_waitcnt vmcnt(0) lgkmcnt(0)
	v_lshl_add_u64 v[6:7], v[6:7], 0, s[4:5]
	v_lshl_add_u64 v[6:7], v[6:7], 0, v[0:1]
	global_load_dword v24, v[6:7], off
	global_load_dword v25, v[6:7], off offset:256
	global_load_dword v26, v[6:7], off offset:512
	v_lshl_add_u64 v[4:5], v[4:5], 0, s[4:5]
	v_and_b32_e32 v6, 15, v3
	v_lshl_add_u64 v[4:5], v[4:5], 0, v[0:1]
	v_cndmask_b32_e64 v0, v186, v249, s[40:41]
	v_cmp_lt_i32_e64 s[40:41], v250, v227
	v_cvt_f32_ubyte0_e32 v6, v6
	v_lshlrev_b32_e32 v28, 2, v0
	v_cndmask_b32_e64 v0, v186, v250, s[40:41]
	v_cmp_lt_i32_e64 s[40:41], v251, v227
	v_mul_f32_e32 v6, 0xbf549a78, v6
	v_lshlrev_b32_e32 v29, 2, v0
	v_cndmask_b32_e64 v0, v186, v251, s[40:41]
	v_cmp_lt_i32_e64 s[40:41], v252, v227
	v_exp_f32_e32 v27, v6
	v_lshlrev_b32_e32 v30, 2, v0
	v_cndmask_b32_e64 v0, v186, v252, s[40:41]
	v_cmp_lt_i32_e64 s[40:41], v253, v227
	s_movk_i32 s4, 0x600
	v_lshlrev_b32_e32 v31, 2, v0
	v_cndmask_b32_e64 v0, v186, v253, s[40:41]
	v_cmp_lt_i32_e64 s[40:41], v212, v227
	v_lshl_add_u64 v[8:9], v[10:11], 0, v[20:21]
	v_lshl_add_u64 v[10:11], v[16:17], 0, v[20:21]
	v_mad_i64_i32 v[16:17], s[4:5], v2, s4, 0
	v_and_b32_e32 v3, 16, v3
	v_lshlrev_b32_e32 v32, 2, v0
	v_cndmask_b32_e64 v0, v186, v212, s[40:41]
	v_or_b32_e32 v16, v16, v20
	v_cmp_eq_u32_e64 s[38:39], 0, v3
	v_lshl_add_u64 v[6:7], v[18:19], 0, v[20:21]
	v_lshlrev_b32_e32 v33, 2, v0
	v_lshl_add_u64 v[12:13], v[12:13], 0, v[20:21]
	v_ashrrev_i32_e32 v3, 31, v2
	v_lshl_add_u64 v[14:15], v[14:15], 0, v[16:17]
	s_mov_b64 s[4:5], 0
	s_branch .LBB0_689
.LBB0_688:
	s_or_b64 exec, exec, s[8:9]
	v_mul_f32_e32 v20, v24, v17
	v_mul_f32_e32 v20, v20, v18
	v_mul_f32_e32 v17, v25, v17
	v_or_b32_e32 v18, 3, v36
	v_mul_f32_e32 v17, v17, v19
	v_mad_i64_i32 v[18:19], s[8:9], v18, s71, v[0:1]
	v_cvt_pk_bf16_f32 v0, v20, s0
	v_mad_u64_u32 v[20:21], s[8:9], v18, s20, v[12:13]
	v_readlane_b32 s8, v254, 47
	v_readlane_b32 s9, v254, 48
	v_mad_i32_i24 v21, v19, s20, v21
	global_store_short v[20:21], v0, off
	v_lshl_add_u64 v[2:3], v[2:3], 0, s[8:9]
	s_movk_i32 s8, 0x41ff
	v_cmp_lt_i32_e64 s[40:41], s8, v2
	v_readlane_b32 s8, v254, 49
	v_cvt_pk_bf16_f32 v0, v17, s0
	v_readlane_b32 s9, v254, 50
	global_store_short v[20:21], v0, off offset:128
	v_cvt_pk_bf16_f32 v0, v16, s0
	s_or_b64 s[4:5], s[40:41], s[4:5]
	v_lshl_add_u64 v[14:15], v[14:15], 0, s[8:9]
	global_store_short v[20:21], v0, off offset:256
	s_andn2_b64 exec, exec, s[4:5]
	s_cbranch_execz .LBB0_711

; __device__ __forceinline__ u16 f2bf(float f) { return (u16)(pack2(f, 0.f) & 0xffffu); }
; __device__ __forceinline__ float bf2f(u16 b) { return __uint_as_float(((unsigned)b) << 16); }
; __device__ __forceinline__ void phase_mix_b(const Params& p, int l, bool last, unsigned char* smem) {
;     ...
;     if (lat || !last) {
; #pragma unroll
;       for (int h = 0; h < 4; ++h) {
;         const u16* q = p.QR + (size_t)row * 768 + h * 192;
;         float v0 = bf2f(q[lane]), v1 = bf2f(q[lane + 64]), v2 = bf2f(q[lane + 128]);
;         const float ss = wave_sum(v0 * v0 + v1 * v1 + v2 * v2);
;         const float rstd = rsqrtf(ss * (1.f / 192.f) + 1e-6f);
;         const float* qn = p.q_norm + l * 192;
;         v0 *= rstd * qn[lane]; v1 *= rstd * qn[lane + 64]; v2 *= rstd * qn[lane + 128];
;         if (lat) {
;           const float xp = __shfl_xor(v2, 16);
;           v2 = hi ? (xp * sn + v2 * cs) : (v2 * cs - xp * sn);
;         }
;         u16* o = p.Qall + ((size_t)(b * 4 + h) * NPOS + pos) * 192;
;         o[lane] = f2bf(v0 * QSCALE); o[lane + 64] = f2bf(v1 * QSCALE); o[lane + 128] = f2bf(v2 * QSCALE);
;       }
.LBB0_691:
	s_or_b64 exec, exec, s[8:9]
	v_add_u32_e32 v0, 0xffffc000, v2
	s_and_b64 s[8:9], s[86:87], s[42:43]
	v_lshrrev_b32_e32 v21, 8, v0
	v_and_b32_e32 v0, 0xff, v2
	s_xor_b64 s[8:9], s[8:9], -1
	v_mov_b32_e32 v16, v2
	v_mov_b32_e32 v17, v1
	s_and_saveexec_b64 s[18:19], s[8:9]
	s_xor_b64 s[46:47], exec, s[18:19]
	s_cbranch_execz .LBB0_701
	global_load_ushort v16, v[14:15], off offset:128
	global_load_ushort v17, v[14:15], off offset:256
	global_load_ushort v23, v[14:15], off
	global_load_dword v20, v[4:5], off offset:512
	global_load_dword v19, v[4:5], off
	global_load_dword v18, v[4:5], off offset:256
	s_waitcnt vmcnt(0) lgkmcnt(0)
	v_lshlrev_b32_e32 v22, 16, v16
	v_lshlrev_b32_e32 v17, 16, v17
	v_lshlrev_b32_e32 v16, 16, v23
	v_pk_mul_f32 v[36:37], v[16:17], v[16:17]
	s_nop 0
	v_fma_f32 v23, v22, v22, v36
	v_add_f32_e32 v23, v23, v37
	ds_bpermute_b32 v36, v28, v23
	s_waitcnt lgkmcnt(0)
	v_add_f32_e32 v23, v23, v36
	ds_bpermute_b32 v36, v29, v23
	s_waitcnt lgkmcnt(0)
	v_add_f32_e32 v23, v23, v36
	ds_bpermute_b32 v36, v30, v23
	s_waitcnt lgkmcnt(0)
	v_add_f32_e32 v23, v23, v36
	ds_bpermute_b32 v36, v31, v23
	s_waitcnt lgkmcnt(0)
	v_add_f32_e32 v23, v23, v36
	ds_bpermute_b32 v36, v32, v23
	s_waitcnt lgkmcnt(0)
	v_add_f32_e32 v23, v23, v36
	ds_bpermute_b32 v36, v33, v23
	s_waitcnt lgkmcnt(0)
	v_add_f32_e32 v23, v23, v36
	v_fmamk_f32 v23, v23, 0x3baaaaab, v224
	v_mul_f32_e32 v36, 0x4b800000, v23
	v_cmp_gt_f32_e64 s[42:43], s85, v23
	s_nop 1
	v_cndmask_b32_e64 v23, v23, v36, s[42:43]
	v_rsq_f32_e32 v23, v23
	s_nop 0
	v_mul_f32_e32 v36, 0x45800000, v23
	v_cndmask_b32_e64 v23, v23, v36, s[42:43]
	v_mul_f32_e32 v36, v20, v23
	v_mul_f32_e32 v17, v36, v17
	s_and_saveexec_b64 s[8:9], s[40:41]
	s_cbranch_execz .LBB0_694
	ds_bpermute_b32 v36, v29, v17
	s_waitcnt lgkmcnt(0)
	v_mul_f32_e32 v36, v35, v36
	v_cndmask_b32_e64 v36, v36, -v36, s[38:39]
	v_fmac_f32_e32 v36, v34, v17
	v_mov_b32_e32 v17, v36
.LBB0_694:
	s_or_b64 exec, exec, s[8:9]
	v_ashrrev_i32_e32 v36, 13, v2
	v_cmp_gt_i32_e64 s[42:43], s69, v2
	s_nop 1
	v_cndmask_b32_e64 v21, v21, v36, s[42:43]
	v_and_b32_e32 v36, 0x1fff, v2
	v_add_u32_e32 v36, 0x100, v36
	v_cndmask_b32_e64 v0, v0, v36, s[42:43]
	v_lshlrev_b32_e32 v36, 2, v21
	v_mul_f32_e32 v21, v19, v23
	v_mul_f32_e32 v16, v21, v16
	v_mul_f32_e32 v21, v18, v23
	v_mul_f32_e32 v21, v21, v22
	v_mad_i64_i32 v[22:23], s[8:9], v36, s71, v[0:1]
	v_mul_f32_e32 v16, 0x3dd53b94, v16
	v_mad_u64_u32 v[38:39], s[8:9], v22, s20, v[8:9]
	v_cvt_pk_bf16_f32 v16, v16, s0
	v_mad_i32_i24 v39, v23, s20, v39
	global_store_short v[38:39], v16, off
	v_mul_f32_e32 v16, 0x3dd53b94, v21
	v_cvt_pk_bf16_f32 v16, v16, s0
	global_store_short v[38:39], v16, off offset:128
	v_mul_f32_e32 v16, 0x3dd53b94, v17
	v_cvt_pk_bf16_f32 v16, v16, s0
	global_store_short v[38:39], v16, off offset:256
	global_load_ushort v16, v[14:15], off offset:512
	s_nop 0
	global_load_ushort v17, v[14:15], off offset:640
	global_load_ushort v22, v[14:15], off offset:384
	s_waitcnt vmcnt(0) lgkmcnt(0)
	v_lshlrev_b32_e32 v21, 16, v16
	v_lshlrev_b32_e32 v17, 16, v17
	v_lshlrev_b32_e32 v16, 16, v22
	v_pk_mul_f32 v[22:23], v[16:17], v[16:17]
	s_nop 0
	v_fma_f32 v22, v21, v21, v22
	v_add_f32_e32 v22, v22, v23
	ds_bpermute_b32 v23, v28, v22
	s_waitcnt lgkmcnt(0)
	v_add_f32_e32 v22, v22, v23
	ds_bpermute_b32 v23, v29, v22
	s_waitcnt lgkmcnt(0)
	v_add_f32_e32 v22, v22, v23
	ds_bpermute_b32 v23, v30, v22
	s_waitcnt lgkmcnt(0)
	v_add_f32_e32 v22, v22, v23
	ds_bpermute_b32 v23, v31, v22
	s_waitcnt lgkmcnt(0)
	v_add_f32_e32 v22, v22, v23
	ds_bpermute_b32 v23, v32, v22
	s_waitcnt lgkmcnt(0)
	v_add_f32_e32 v22, v22, v23
	ds_bpermute_b32 v23, v33, v22
	s_waitcnt lgkmcnt(0)
	v_add_f32_e32 v22, v22, v23
	v_fmamk_f32 v22, v22, 0x3baaaaab, v224
	v_mul_f32_e32 v23, 0x4b800000, v22
	v_cmp_gt_f32_e64 s[42:43], s85, v22
	s_nop 1
	v_cndmask_b32_e64 v22, v22, v23, s[42:43]
	v_rsq_f32_e32 v22, v22
	s_nop 0
	v_mul_f32_e32 v23, 0x45800000, v22
	v_cndmask_b32_e64 v22, v22, v23, s[42:43]
	v_mul_f32_e32 v23, v20, v22
	v_mul_f32_e32 v17, v23, v17
	s_and_saveexec_b64 s[8:9], s[40:41]
	s_cbranch_execz .LBB0_696
	ds_bpermute_b32 v23, v29, v17
	s_waitcnt lgkmcnt(0)
	v_mul_f32_e32 v23, v35, v23
	v_cndmask_b32_e64 v23, v23, -v23, s[38:39]
	v_fmac_f32_e32 v23, v34, v17
	v_mov_b32_e32 v17, v23
.LBB0_696:
	s_or_b64 exec, exec, s[8:9]
	v_mul_f32_e32 v23, v19, v22
	v_mul_f32_e32 v22, v18, v22
	v_mul_f32_e32 v21, v22, v21
	v_or_b32_e32 v22, 1, v36
	v_mul_f32_e32 v16, v23, v16
	v_mad_i64_i32 v[22:23], s[8:9], v22, s71, v[0:1]
	v_mul_f32_e32 v16, 0x3dd53b94, v16
	v_mad_u64_u32 v[38:39], s[8:9], v22, s20, v[8:9]
	v_cvt_pk_bf16_f32 v16, v16, s0
	v_mad_i32_i24 v39, v23, s20, v39
	global_store_short v[38:39], v16, off
	v_mul_f32_e32 v16, 0x3dd53b94, v21
	v_cvt_pk_bf16_f32 v16, v16, s0
	global_store_short v[38:39], v16, off offset:128
	v_mul_f32_e32 v16, 0x3dd53b94, v17
	v_cvt_pk_bf16_f32 v16, v16, s0
	global_store_short v[38:39], v16, off offset:256
	global_load_ushort v16, v[14:15], off offset:896
	s_nop 0
	global_load_ushort v17, v[14:15], off offset:1024
	global_load_ushort v22, v[14:15], off offset:768
	s_waitcnt vmcnt(0) lgkmcnt(0)
	v_lshlrev_b32_e32 v21, 16, v16
	v_lshlrev_b32_e32 v17, 16, v17
	v_lshlrev_b32_e32 v16, 16, v22
	v_pk_mul_f32 v[22:23], v[16:17], v[16:17]
	s_nop 0
	v_fma_f32 v22, v21, v21, v22
	v_add_f32_e32 v22, v22, v23
	ds_bpermute_b32 v23, v28, v22
	s_waitcnt lgkmcnt(0)
	v_add_f32_e32 v22, v22, v23
	ds_bpermute_b32 v23, v29, v22
	s_waitcnt lgkmcnt(0)
	v_add_f32_e32 v22, v22, v23
	ds_bpermute_b32 v23, v30, v22
	s_waitcnt lgkmcnt(0)
	v_add_f32_e32 v22, v22, v23
	ds_bpermute_b32 v23, v31, v22
	s_waitcnt lgkmcnt(0)
	v_add_f32_e32 v22, v22, v23
	ds_bpermute_b32 v23, v32, v22
	s_waitcnt lgkmcnt(0)
	v_add_f32_e32 v22, v22, v23
	ds_bpermute_b32 v23, v33, v22
	s_waitcnt lgkmcnt(0)
	v_add_f32_e32 v22, v22, v23
	v_fmamk_f32 v22, v22, 0x3baaaaab, v224
	v_mul_f32_e32 v23, 0x4b800000, v22
	v_cmp_gt_f32_e64 s[42:43], s85, v22
	s_nop 1
	v_cndmask_b32_e64 v22, v22, v23, s[42:43]
	v_rsq_f32_e32 v22, v22
	s_nop 0
	v_mul_f32_e32 v23, 0x45800000, v22
	v_cndmask_b32_e64 v22, v22, v23, s[42:43]
	v_mul_f32_e32 v23, v20, v22
	v_mul_f32_e32 v17, v23, v17
	s_and_saveexec_b64 s[8:9], s[40:41]
	s_cbranch_execz .LBB0_698
	ds_bpermute_b32 v23, v29, v17
	s_waitcnt lgkmcnt(0)
	v_mul_f32_e32 v23, v35, v23
	v_cndmask_b32_e64 v23, v23, -v23, s[38:39]
	v_fmac_f32_e32 v23, v34, v17
	v_mov_b32_e32 v17, v23
; __device__ __forceinline__ u16 f2bf(float f) { return (u16)(pack2(f, 0.f) & 0xffffu); }
; __device__ __forceinline__ float bf2f(u16 b) { return __uint_as_float(((unsigned)b) << 16); }
; __device__ __forceinline__ void phase_mix_b(const Params& p, int l, bool last, unsigned char* smem) {
;     ...
;         u16* o = p.Qall + ((size_t)(b * 4 + h) * NPOS + pos) * 192;
;         o[lane] = f2bf(v0 * QSCALE); o[lane + 64] = f2bf(v1 * QSCALE); o[lane + 128] = f2bf(v2 * QSCALE);
;       }
;     }
;     {
;       const float kr = bf2f(p.PX[(size_t)row * 1024 + 896 + lane]);
; #pragma unroll
;       for (int h = 0; h < 4; ++h) {
;         const u16* kk = p.KN + (size_t)row * 512 + h * 128;
;         float v0 = bf2f(kk[lane]), v1 = bf2f(kk[lane + 64]), v2 = kr;
;         const float ss = wave_sum(v0 * v0 + v1 * v1 + v2 * v2);
;         const float rstd = rsqrtf(ss * (1.f / 192.f) + 1e-6f);
;         const float* kn = p.k_norm + l * 192;
;         v0 *= rstd * kn[lane]; v1 *= rstd * kn[lane + 64]; v2 *= rstd * kn[lane + 128];
;         if (lat) {
;           const float xp = __shfl_xor(v2, 16);
;           v2 = hi ? (xp * sn + v2 * cs) : (v2 * cs - xp * sn);
;         }
.LBB0_698:
	s_or_b64 exec, exec, s[8:9]
	v_mul_f32_e32 v23, v19, v22
	v_mul_f32_e32 v22, v18, v22
	v_mul_f32_e32 v21, v22, v21
	v_or_b32_e32 v22, 2, v36
	v_mul_f32_e32 v16, v23, v16
	v_mad_i64_i32 v[22:23], s[8:9], v22, s71, v[0:1]
	v_mul_f32_e32 v16, 0x3dd53b94, v16
	v_mad_u64_u32 v[38:39], s[8:9], v22, s20, v[8:9]
	v_cvt_pk_bf16_f32 v16, v16, s0
	v_mad_i32_i24 v39, v23, s20, v39
	global_store_short v[38:39], v16, off
	v_mul_f32_e32 v16, 0x3dd53b94, v21
	v_cvt_pk_bf16_f32 v16, v16, s0
	global_store_short v[38:39], v16, off offset:128
	v_mul_f32_e32 v16, 0x3dd53b94, v17
	v_cvt_pk_bf16_f32 v16, v16, s0
	global_store_short v[38:39], v16, off offset:256
	global_load_ushort v16, v[14:15], off offset:1280
	s_nop 0
	global_load_ushort v17, v[14:15], off offset:1408
	global_load_ushort v22, v[14:15], off offset:1152
	s_waitcnt vmcnt(0) lgkmcnt(0)
	v_lshlrev_b32_e32 v21, 16, v16
	v_lshlrev_b32_e32 v17, 16, v17
	v_lshlrev_b32_e32 v16, 16, v22
	v_pk_mul_f32 v[22:23], v[16:17], v[16:17]
	s_nop 0
	v_fma_f32 v22, v21, v21, v22
	v_add_f32_e32 v22, v22, v23
	ds_bpermute_b32 v23, v28, v22
	s_waitcnt lgkmcnt(0)
	v_add_f32_e32 v22, v22, v23
	ds_bpermute_b32 v23, v29, v22
	s_waitcnt lgkmcnt(0)
	v_add_f32_e32 v22, v22, v23
	ds_bpermute_b32 v23, v30, v22
	s_waitcnt lgkmcnt(0)
	v_add_f32_e32 v22, v22, v23
	ds_bpermute_b32 v23, v31, v22
	s_waitcnt lgkmcnt(0)
	v_add_f32_e32 v22, v22, v23
	ds_bpermute_b32 v23, v32, v22
	s_waitcnt lgkmcnt(0)
	v_add_f32_e32 v22, v22, v23
	ds_bpermute_b32 v23, v33, v22
	s_waitcnt lgkmcnt(0)
	v_add_f32_e32 v22, v22, v23
	v_fmamk_f32 v22, v22, 0x3baaaaab, v224
	v_mul_f32_e32 v23, 0x4b800000, v22
	v_cmp_gt_f32_e64 s[42:43], s85, v22
	s_nop 1
	v_cndmask_b32_e64 v22, v22, v23, s[42:43]
	v_rsq_f32_e32 v22, v22
	s_nop 0
	v_mul_f32_e32 v23, 0x45800000, v22
	v_cndmask_b32_e64 v22, v22, v23, s[42:43]
	v_mul_f32_e32 v20, v20, v22
	v_mul_f32_e32 v17, v20, v17
	s_and_saveexec_b64 s[8:9], s[40:41]
	s_cbranch_execz .LBB0_700
	ds_bpermute_b32 v20, v29, v17
	s_waitcnt lgkmcnt(0)
	v_mul_f32_e32 v20, v35, v20
	v_cndmask_b32_e64 v20, v20, -v20, s[38:39]
	v_fmac_f32_e32 v20, v34, v17
	v_mov_b32_e32 v17, v20
.LBB0_700:
	s_or_b64 exec, exec, s[8:9]
	v_mul_f32_e32 v18, v18, v22
	v_mul_f32_e32 v19, v19, v22
	v_mul_f32_e32 v22, v18, v21
	v_or_b32_e32 v18, 3, v36
	v_mul_f32_e32 v16, v19, v16
	v_mad_i64_i32 v[18:19], s[8:9], v18, s71, v[0:1]
	v_mul_f32_e32 v16, 0x3dd53b94, v16
	v_mad_u64_u32 v[20:21], s[8:9], v18, s20, v[8:9]
	v_cvt_pk_bf16_f32 v16, v16, s0
	v_mad_i32_i24 v21, v19, s20, v21
	global_store_short v[20:21], v16, off
	v_mul_f32_e32 v16, 0x3dd53b94, v22
	v_cvt_pk_bf16_f32 v16, v16, s0
	global_store_short v[20:21], v16, off offset:128
	v_mul_f32_e32 v16, 0x3dd53b94, v17
	v_cvt_pk_bf16_f32 v16, v16, s0
	global_store_short v[20:21], v16, off offset:256
	v_mov_b64_e32 v[16:17], v[2:3]
.LBB0_701:
	s_andn2_saveexec_b64 s[8:9], s[46:47]
	v_lshlrev_b32_e32 v36, 2, v21
	s_or_b64 exec, exec, s[8:9]
	v_lshlrev_b64 v[18:19], 11, v[16:17]
	v_lshlrev_b64 v[16:17], 10, v[16:17]
	v_lshl_add_u64 v[20:21], v[6:7], 0, v[18:19]
	v_lshl_add_u64 v[18:19], v[10:11], 0, v[16:17]
	global_load_ushort v16, v[18:19], off offset:128
	global_load_ushort v17, v[18:19], off
	s_nop 0
	global_load_ushort v20, v[20:21], off offset:1792
	s_waitcnt vmcnt(0) lgkmcnt(0)
	v_lshlrev_b32_e32 v22, 16, v16
	v_lshlrev_b32_e32 v17, 16, v17
	v_lshlrev_b32_e32 v16, 16, v20
	v_pk_mul_f32 v[20:21], v[16:17], v[16:17]
	s_nop 0
	v_fma_f32 v21, v22, v22, v21
	v_add_f32_e32 v21, v20, v21
	ds_bpermute_b32 v23, v28, v21
	s_waitcnt lgkmcnt(0)
	v_add_f32_e32 v21, v21, v23
	ds_bpermute_b32 v23, v29, v21
	s_waitcnt lgkmcnt(0)
	v_add_f32_e32 v21, v21, v23
	ds_bpermute_b32 v23, v30, v21
	s_waitcnt lgkmcnt(0)
	v_add_f32_e32 v21, v21, v23
	ds_bpermute_b32 v23, v31, v21
	s_waitcnt lgkmcnt(0)
	v_add_f32_e32 v21, v21, v23
	ds_bpermute_b32 v23, v32, v21
	s_waitcnt lgkmcnt(0)
	v_add_f32_e32 v21, v21, v23
	ds_bpermute_b32 v23, v33, v21
	s_waitcnt lgkmcnt(0)
	v_add_f32_e32 v21, v21, v23
	v_fmamk_f32 v21, v21, 0x3baaaaab, v224
	v_mul_f32_e32 v23, 0x4b800000, v21
	v_cmp_gt_f32_e64 s[42:43], s85, v21
	s_nop 1
	v_cndmask_b32_e64 v21, v21, v23, s[42:43]
	v_rsq_f32_e32 v21, v21
	s_nop 0
	v_mul_f32_e32 v23, 0x45800000, v21
	v_cndmask_b32_e64 v23, v21, v23, s[42:43]
	v_mul_f32_e32 v21, v26, v23
	v_mul_f32_e32 v21, v21, v16
	s_and_saveexec_b64 s[8:9], s[40:41]
	s_cbranch_execz .LBB0_705
	ds_bpermute_b32 v37, v29, v21
	s_waitcnt lgkmcnt(0)
	v_mul_f32_e32 v37, v35, v37
	v_cndmask_b32_e64 v37, v37, -v37, s[38:39]
	v_fmac_f32_e32 v37, v34, v21
	v_mov_b32_e32 v21, v37
; __device__ __forceinline__ u16 f2bf(float f) { return (u16)(pack2(f, 0.f) & 0xffffu); }
; __device__ __forceinline__ float bf2f(u16 b) { return __uint_as_float(((unsigned)b) << 16); }
; __device__ __forceinline__ void phase_mix_b(const Params& p, int l, bool last, unsigned char* smem) {
;     ...
;     {
;       const float kr = bf2f(p.PX[(size_t)row * 1024 + 896 + lane]);
; #pragma unroll
;       for (int h = 0; h < 4; ++h) {
;         const u16* kk = p.KN + (size_t)row * 512 + h * 128;
;         float v0 = bf2f(kk[lane]), v1 = bf2f(kk[lane + 64]), v2 = kr;
;         const float ss = wave_sum(v0 * v0 + v1 * v1 + v2 * v2);
;         const float rstd = rsqrtf(ss * (1.f / 192.f) + 1e-6f);
;         const float* kn = p.k_norm + l * 192;
;         v0 *= rstd * kn[lane]; v1 *= rstd * kn[lane + 64]; v2 *= rstd * kn[lane + 128];
;         if (lat) {
;           const float xp = __shfl_xor(v2, 16);
;           v2 = hi ? (xp * sn + v2 * cs) : (v2 * cs - xp * sn);
;         }
;         u16* o = p.Kb + ((size_t)(b * 4 + h) * NPOS + pos) * 192;
;         o[lane] = f2bf(v0); o[lane + 64] = f2bf(v1); o[lane + 128] = f2bf(v2);
;       }
.LBB0_705:
	s_or_b64 exec, exec, s[8:9]
	v_mul_f32_e32 v37, v24, v23
	v_mul_f32_e32 v23, v25, v23
	v_mul_f32_e32 v17, v37, v17
	v_mul_f32_e32 v37, v23, v22
	v_mad_i64_i32 v[22:23], s[8:9], v36, s71, v[0:1]
	v_mad_u64_u32 v[38:39], s[8:9], v22, s20, v[12:13]
	v_cvt_pk_bf16_f32 v17, v17, s0
	v_mad_i32_i24 v39, v23, s20, v39
	global_store_short v[38:39], v17, off
	v_cvt_pk_bf16_f32 v17, v37, s0
	global_store_short v[38:39], v17, off offset:128
	v_cvt_pk_bf16_f32 v17, v21, s0
	global_store_short v[38:39], v17, off offset:256
	global_load_ushort v17, v[18:19], off offset:384
	s_nop 0
	global_load_ushort v21, v[18:19], off offset:256
	s_waitcnt vmcnt(0) lgkmcnt(0)
	v_lshlrev_b32_e32 v23, 16, v17
	v_lshlrev_b32_e32 v22, 16, v21
	v_pk_mul_f32 v[38:39], v[22:23], v[22:23]
	s_nop 0
	v_add_f32_e32 v17, v38, v39
	v_add_f32_e32 v17, v20, v17
	ds_bpermute_b32 v21, v28, v17
	s_waitcnt lgkmcnt(0)
	v_add_f32_e32 v17, v17, v21
	ds_bpermute_b32 v21, v29, v17
	s_waitcnt lgkmcnt(0)
	v_add_f32_e32 v17, v17, v21
	ds_bpermute_b32 v21, v30, v17
	s_waitcnt lgkmcnt(0)
	v_add_f32_e32 v17, v17, v21
	ds_bpermute_b32 v21, v31, v17
	s_waitcnt lgkmcnt(0)
	v_add_f32_e32 v17, v17, v21
	ds_bpermute_b32 v21, v32, v17
	s_waitcnt lgkmcnt(0)
	v_add_f32_e32 v17, v17, v21
	ds_bpermute_b32 v21, v33, v17
	s_waitcnt lgkmcnt(0)
	v_add_f32_e32 v17, v17, v21
	v_fmamk_f32 v17, v17, 0x3baaaaab, v224
	v_mul_f32_e32 v21, 0x4b800000, v17
	v_cmp_gt_f32_e64 s[42:43], s85, v17
	s_nop 1
	v_cndmask_b32_e64 v17, v17, v21, s[42:43]
	v_rsq_f32_e32 v17, v17
	s_nop 0
	v_mul_f32_e32 v21, 0x45800000, v17
	v_cndmask_b32_e64 v21, v17, v21, s[42:43]
	v_mul_f32_e32 v17, v26, v21
	v_mul_f32_e32 v17, v17, v16
	s_and_saveexec_b64 s[8:9], s[40:41]
	s_cbranch_execz .LBB0_707
	ds_bpermute_b32 v37, v29, v17
	s_waitcnt lgkmcnt(0)
	v_mul_f32_e32 v37, v35, v37
	v_cndmask_b32_e64 v37, v37, -v37, s[38:39]
	v_fmac_f32_e32 v37, v34, v17
	v_mov_b32_e32 v17, v37
.LBB0_707:
	s_or_b64 exec, exec, s[8:9]
	v_mul_f32_e32 v37, v24, v21
	v_mul_f32_e32 v37, v37, v22
	v_mul_f32_e32 v21, v25, v21
	v_or_b32_e32 v22, 1, v36
	v_mul_f32_e32 v21, v21, v23
	v_mad_i64_i32 v[22:23], s[8:9], v22, s71, v[0:1]
	v_mad_u64_u32 v[38:39], s[8:9], v22, s20, v[12:13]
	v_cvt_pk_bf16_f32 v37, v37, s0
	v_mad_i32_i24 v39, v23, s20, v39
	v_cvt_pk_bf16_f32 v21, v21, s0
	v_cvt_pk_bf16_f32 v17, v17, s0
	global_store_short v[38:39], v37, off
	global_store_short v[38:39], v21, off offset:128
	global_store_short v[38:39], v17, off offset:256
	global_load_ushort v17, v[18:19], off offset:640
	s_nop 0
	global_load_ushort v21, v[18:19], off offset:512
	s_waitcnt vmcnt(0) lgkmcnt(0)
	v_lshlrev_b32_e32 v23, 16, v17
	v_lshlrev_b32_e32 v22, 16, v21
	v_pk_mul_f32 v[38:39], v[22:23], v[22:23]
	s_nop 0
	v_add_f32_e32 v17, v38, v39
	v_add_f32_e32 v17, v20, v17
	ds_bpermute_b32 v21, v28, v17
	s_waitcnt lgkmcnt(0)
	v_add_f32_e32 v17, v17, v21
	ds_bpermute_b32 v21, v29, v17
	s_waitcnt lgkmcnt(0)
	v_add_f32_e32 v17, v17, v21
	ds_bpermute_b32 v21, v30, v17
	s_waitcnt lgkmcnt(0)
	v_add_f32_e32 v17, v17, v21
	ds_bpermute_b32 v21, v31, v17
	s_waitcnt lgkmcnt(0)
	v_add_f32_e32 v17, v17, v21
	ds_bpermute_b32 v21, v32, v17
	s_waitcnt lgkmcnt(0)
	v_add_f32_e32 v17, v17, v21
	ds_bpermute_b32 v21, v33, v17
	s_waitcnt lgkmcnt(0)
	v_add_f32_e32 v17, v17, v21
	v_fmamk_f32 v17, v17, 0x3baaaaab, v224
	v_mul_f32_e32 v21, 0x4b800000, v17
	v_cmp_gt_f32_e64 s[42:43], s85, v17
	s_nop 1
	v_cndmask_b32_e64 v17, v17, v21, s[42:43]
	v_rsq_f32_e32 v17, v17
	s_nop 0
	v_mul_f32_e32 v21, 0x45800000, v17
	v_cndmask_b32_e64 v21, v17, v21, s[42:43]
	v_mul_f32_e32 v17, v26, v21
	v_mul_f32_e32 v17, v17, v16
	s_and_saveexec_b64 s[8:9], s[40:41]
	s_cbranch_execz .LBB0_709
	ds_bpermute_b32 v37, v29, v17
	s_waitcnt lgkmcnt(0)
	v_mul_f32_e32 v37, v35, v37
	v_cndmask_b32_e64 v37, v37, -v37, s[38:39]
	v_fmac_f32_e32 v37, v34, v17
	v_mov_b32_e32 v17, v37
.LBB0_709:
	s_or_b64 exec, exec, s[8:9]
	v_mul_f32_e32 v37, v24, v21
	v_mul_f32_e32 v37, v37, v22
	v_mul_f32_e32 v21, v25, v21
	v_or_b32_e32 v22, 2, v36
	v_mul_f32_e32 v21, v21, v23
	v_mad_i64_i32 v[22:23], s[8:9], v22, s71, v[0:1]
	v_mad_u64_u32 v[38:39], s[8:9], v22, s20, v[12:13]
	v_cvt_pk_bf16_f32 v37, v37, s0
	v_mad_i32_i24 v39, v23, s20, v39
	v_cvt_pk_bf16_f32 v21, v21, s0
	v_cvt_pk_bf16_f32 v17, v17, s0
	global_store_short v[38:39], v37, off
	global_store_short v[38:39], v21, off offset:128
	global_store_short v[38:39], v17, off offset:256
	global_load_ushort v17, v[18:19], off offset:896
	s_nop 0
	global_load_ushort v18, v[18:19], off offset:768
	s_waitcnt vmcnt(0) lgkmcnt(0)
	v_lshlrev_b32_e32 v19, 16, v17
	v_lshlrev_b32_e32 v18, 16, v18
	v_pk_mul_f32 v[22:23], v[18:19], v[18:19]
	s_nop 0
	v_add_f32_e32 v17, v22, v23
	v_add_f32_e32 v17, v20, v17
	ds_bpermute_b32 v20, v28, v17
	s_waitcnt lgkmcnt(0)
	v_add_f32_e32 v17, v17, v20
	ds_bpermute_b32 v20, v29, v17
	s_waitcnt lgkmcnt(0)
	v_add_f32_e32 v17, v17, v20
	ds_bpermute_b32 v20, v30, v17
	s_waitcnt lgkmcnt(0)
	v_add_f32_e32 v17, v17, v20
	ds_bpermute_b32 v20, v31, v17
	s_waitcnt lgkmcnt(0)
	v_add_f32_e32 v17, v17, v20
	ds_bpermute_b32 v20, v32, v17
	s_waitcnt lgkmcnt(0)
	v_add_f32_e32 v17, v17, v20
	ds_bpermute_b32 v20, v33, v17
	s_waitcnt lgkmcnt(0)
	v_add_f32_e32 v17, v17, v20
	v_fmamk_f32 v17, v17, 0x3baaaaab, v224
	v_mul_f32_e32 v20, 0x4b800000, v17
	v_cmp_gt_f32_e64 s[42:43], s85, v17
	s_nop 1
	v_cndmask_b32_e64 v17, v17, v20, s[42:43]
	v_rsq_f32_e32 v17, v17
	s_nop 0
	v_mul_f32_e32 v20, 0x45800000, v17
	v_cndmask_b32_e64 v17, v17, v20, s[42:43]
	v_mul_f32_e32 v20, v26, v17
	v_mul_f32_e32 v16, v20, v16
	s_and_saveexec_b64 s[8:9], s[40:41]
	s_cbranch_execz .LBB0_688
	ds_bpermute_b32 v20, v29, v16
	s_waitcnt lgkmcnt(0)
	v_mul_f32_e32 v20, v35, v20
	v_cndmask_b32_e64 v20, v20, -v20, s[38:39]
	v_fmac_f32_e32 v20, v34, v16
	v_mov_b32_e32 v16, v20
	s_branch .LBB0_688

; __device__ __forceinline__ int tid_() { int t = threadIdx.x; asm volatile("" : "+v"(t)); return t; }
; __device__ __forceinline__ int bid_() { int b = blockIdx.x; asm volatile("" : "+s"(b)); return b; }
; __device__ __forceinline__ void phase_attn(const Params& p, int l, bool last, unsigned char* smem) {
;   float shift;
;   {
;     const int lane = tid_() & 63;
;     float mq = 0.f, mk = 0.f;
; #pragma unroll
;     for (int i = 0; i < 3; ++i) { mq = fmaxf(mq, fabsf(p.q_norm[l * 192 + lane + 64 * i])); mk = fmaxf(mk, fabsf(p.k_norm[l * 192 + lane + 64 * i])); }
; #pragma unroll
;     for (int o = 32; o; o >>= 1) { mq = fmaxf(mq, __shfl_xor(mq, o)); mk = fmaxf(mk, __shfl_xor(mk, o)); }
;     const float bound = 192.f * mq * mk * (0.07216878364870322f * 1.4426950408889634f);
;     shift = fmaxf(0.f, bound - 24.f);
;   }
;   const int x = bid_() & 7, j = bid_() >> 3, gb = gridDim.x >> 3;
;   for (int q = j; q < 64; q += gb) attn_item(p, x >> 2, x & 3, 2 + q, shift, smem);
.LBB0_763:
	s_or_b64 exec, exec, s[0:1]
	s_mov_b64 s[4:5], s[64:65]
	s_waitcnt lgkmcnt(0)
	s_barrier
	v_mov_b32_e32 v0, v187
	v_mov_b64_e32 v[2:3], s[4:5]
	global_load_dwordx4 v[2:5], v[2:3], off offset:112
	v_and_or_b32 v0, v0, 63, s94
	v_lshlrev_b64 v[6:7], 2, v[0:1]
	v_cmp_lt_i32_e32 vcc, v249, v227
	s_mov_b32 s18, s2
	s_mov_b32 s0, s2
	s_waitcnt vmcnt(0) lgkmcnt(0)
	v_lshl_add_u64 v[2:3], v[2:3], 0, v[6:7]
	global_load_dword v0, v[2:3], off
	v_lshl_add_u64 v[4:5], v[4:5], 0, v[6:7]
	global_load_dword v6, v[4:5], off
	global_load_dword v7, v[2:3], off offset:256
	global_load_dword v8, v[4:5], off offset:256
	s_nop 0
	global_load_dword v2, v[2:3], off offset:512
	v_cndmask_b32_e32 v3, v186, v249, vcc
	v_lshlrev_b32_e32 v229, 2, v3
	v_cmp_lt_i32_e32 vcc, v250, v227
	s_waitcnt vmcnt(0) lgkmcnt(0)
	v_max_f32_e64 v0, |v0|, |v0|
	v_max_f32_e32 v0, 0, v0
	v_max_f32_e64 v6, |v6|, |v6|
	v_max3_f32 v0, v0, |v7|, |v2|
	global_load_dword v2, v[4:5], off offset:512
	ds_bpermute_b32 v3, v229, v0
	v_max_f32_e32 v6, 0, v6
	s_and_b32 s19, s18, 7
	s_waitcnt lgkmcnt(0)
	v_max_f32_e32 v3, v3, v3
	v_max_f32_e32 v0, v0, v3
	s_ashr_i32 s8, s0, 3
	s_cmp_gt_i32 s8, 63
	s_mul_i32 s9, s19, 0x2100
	s_mul_i32 s40, s19, 0x318000
	s_mul_i32 s42, s19, 0x210000
	s_waitcnt vmcnt(0)
	v_max3_f32 v2, v6, |v8|, |v2|
	ds_bpermute_b32 v3, v229, v2
	s_waitcnt lgkmcnt(0)
	v_max_f32_e32 v3, v3, v3
	v_max_f32_e32 v2, v2, v3
	v_cndmask_b32_e32 v3, v186, v250, vcc
	v_lshlrev_b32_e32 v230, 2, v3
	ds_bpermute_b32 v3, v230, v0
	v_cmp_lt_i32_e32 vcc, v251, v227
	s_waitcnt lgkmcnt(0)
	v_max_f32_e32 v3, v3, v3
	v_max_f32_e32 v0, v0, v3
	ds_bpermute_b32 v3, v230, v2
	s_waitcnt lgkmcnt(0)
	v_max_f32_e32 v3, v3, v3
	v_max_f32_e32 v2, v2, v3
	v_cndmask_b32_e32 v3, v186, v251, vcc
	v_lshlrev_b32_e32 v231, 2, v3
	ds_bpermute_b32 v3, v231, v0
	v_cmp_lt_i32_e32 vcc, v252, v227
	s_waitcnt lgkmcnt(0)
	v_max_f32_e32 v3, v3, v3
	v_max_f32_e32 v0, v0, v3
	ds_bpermute_b32 v3, v231, v2
	s_waitcnt lgkmcnt(0)
	v_max_f32_e32 v3, v3, v3
	v_max_f32_e32 v2, v2, v3
	v_cndmask_b32_e32 v3, v186, v252, vcc
	v_lshlrev_b32_e32 v232, 2, v3
	ds_bpermute_b32 v3, v232, v0
	v_cmp_lt_i32_e32 vcc, v253, v227
	s_waitcnt lgkmcnt(0)
	v_max_f32_e32 v3, v3, v3
	v_max_f32_e32 v0, v0, v3
	ds_bpermute_b32 v3, v232, v2
	s_waitcnt lgkmcnt(0)
	v_max_f32_e32 v3, v3, v3
	v_max_f32_e32 v2, v2, v3
	v_cndmask_b32_e32 v3, v186, v253, vcc
	v_lshlrev_b32_e32 v233, 2, v3
	ds_bpermute_b32 v3, v233, v0
	v_cmp_lt_i32_e32 vcc, v212, v227
	s_waitcnt lgkmcnt(0)
	v_max_f32_e32 v3, v3, v3
	v_max_f32_e32 v0, v0, v3
	ds_bpermute_b32 v3, v233, v2
	s_waitcnt lgkmcnt(0)
	v_max_f32_e32 v3, v3, v3
	v_max_f32_e32 v2, v2, v3
	v_cndmask_b32_e32 v3, v186, v212, vcc
	v_lshlrev_b32_e32 v234, 2, v3
	ds_bpermute_b32 v3, v234, v0
	s_waitcnt lgkmcnt(0)
	v_max_f32_e32 v3, v3, v3
	v_max_f32_e32 v0, v0, v3
	ds_bpermute_b32 v3, v234, v2
	v_mul_f32_e32 v0, 0x43400000, v0
	s_waitcnt lgkmcnt(0)
	v_max_f32_e32 v3, v3, v3
	v_max_f32_e32 v2, v2, v3
	v_mul_f32_e32 v0, v2, v0
	v_mov_b32_e32 v2, 0xc1c00000
	v_fmamk_f32 v0, v0, 0x3dd53b94, v2
	v_max_f32_e32 v2, 0, v0
	v_cmp_lt_f32_e64 s[38:39], 0, v2
	s_cbranch_scc1 .LBB0_776
	s_lshr_b32 s0, s19, 2
	s_lshl_b32 s1, s18, 7
	s_and_b32 s1, s1, 0x180
	s_lshl_b32 s48, s0, 13
	s_lshl_b32 s49, s0, 8
	s_mov_b32 s41, s95
	s_mov_b32 s43, s95
	s_addk_i32 s48, 0xff00
	s_bitset1_b32 s49, 14
	v_mov_b32_e32 v3, v2
	v_mov_b32_e32 v4, v2
	v_mov_b32_e32 v5, v2
	s_lshl_b32 s46, s1, 1
	s_mov_b32 s50, s8
	s_branch .LBB0_766
.LBB0_765:
	s_or_b64 exec, exec, s[0:1]
	v_exp_f32_e32 v185, v46
	v_exp_f32_e32 v193, v47
	v_exp_f32_e32 v195, v48
	v_exp_f32_e32 v199, v49
	v_exp_f32_e32 v201, v50
	v_exp_f32_e32 v203, v51
	v_exp_f32_e32 v205, v52
	v_exp_f32_e32 v47, v53
	v_exp_f32_e32 v173, v14
	v_add_f32_e32 v110, 0, v171
	v_add_f32_e32 v0, 0, v0
	v_exp_f32_e32 v171, v15
	v_pk_add_f32 v[48:49], v[184:185], v[0:1]
	v_exp_f32_e32 v177, v16
	v_pk_add_f32 v[48:49], v[192:193], v[48:49]
	v_cvt_pk_bf16_f32 v102, v185, v193
	v_cvt_pk_bf16_f32 v103, v195, v199
	v_cvt_pk_bf16_f32 v104, v201, v203
	v_cvt_pk_bf16_f32 v105, v205, v47
	v_exp_f32_e32 v175, v17
	v_mov_b32_e32 v111, v1
	v_pk_add_f32 v[48:49], v[194:195], v[48:49]
	v_exp_f32_e32 v181, v6
	s_waitcnt lgkmcnt(2)
	v_mfma_f32_16x16x32_bf16 v[50:53], v[90:93], v[102:105], v[34:37]
	v_add_f32_e64 v48, v198, v48
	v_add_f32_e64 v49, v199, v49
	v_exp_f32_e32 v179, v7
	v_exp_f32_e32 v183, v8
	v_pk_add_f32 v[34:35], v[172:173], v[110:111]
	v_exp_f32_e32 v113, v9
	v_pk_add_f32 v[34:35], v[170:171], v[34:35]
	v_pk_add_f32 v[48:49], v[200:201], v[48:49]
	v_pk_add_f32 v[34:35], v[176:177], v[34:35]
	v_pk_add_f32 v[48:49], v[202:203], v[48:49]
	v_pk_add_f32 v[34:35], v[174:175], v[34:35]
	v_pk_add_f32 v[48:49], v[204:205], v[48:49]
	v_mov_b32_e32 v46, v196
	v_pk_add_f32 v[34:35], v[180:181], v[34:35]
	v_pk_add_f32 v[48:49], v[46:47], v[48:49]
	v_cvt_pk_bf16_f32 v106, v173, v171
	v_cvt_pk_bf16_f32 v107, v177, v175
	v_cvt_pk_bf16_f32 v108, v181, v179
	v_cvt_pk_bf16_f32 v109, v183, v113
	v_pk_add_f32 v[34:35], v[178:179], v[34:35]
	v_add_f32_e32 v0, v48, v49
	v_mfma_f32_16x16x32_bf16 v[46:49], v[86:89], v[102:105], v[10:13]
	v_add_f32_e64 v34, v182, v34
	v_add_f32_e64 v35, v183, v35
	v_mov_b32_e32 v112, v197
	s_add_i32 s50, s50, s3
	s_waitcnt lgkmcnt(1)
	v_mfma_f32_16x16x32_bf16 v[10:13], v[94:97], v[106:109], v[62:65]
	s_cmp_gt_i32 s50, 63
	s_nop 1
	v_add3_u32 v62, s34, v208, v188
	v_mfma_f32_16x16x32_bf16 v[42:45], v[94:97], v[102:105], v[42:45]
	v_add_f32_e64 v94, v112, v34
	v_add_f32_e64 v95, v113, v35
	v_add_u32_e32 v34, 0x4800, v62
	v_add3_u32 v63, s34, v206, v188
	ds_read2_b64 v[34:37], v34 offset1:4
	v_add_u32_e32 v63, 0x4800, v63
	s_waitcnt lgkmcnt(1)
	v_mfma_f32_16x16x32_bf16 v[6:9], v[98:101], v[106:109], v[82:85]
	v_add_u32_e32 v62, 0x5000, v62
	s_movk_i32 s34, 0x100
	s_nop 0
	ds_read2_b64 v[82:85], v63 offset1:4
	v_mfma_f32_16x16x32_bf16 v[18:21], v[86:89], v[106:109], v[18:21]
	v_mfma_f32_16x16x32_bf16 v[14:17], v[90:93], v[106:109], v[38:41]
	ds_read2_b64 v[86:89], v62 offset0:64 offset1:68
	ds_read2_b64 v[90:93], v62 offset0:224 offset1:228
	s_waitcnt lgkmcnt(0)
	s_barrier
; __device__ __forceinline__ void attn_item(const Params& p, int b, int h, int qt, float shift, unsigned char* smem) {
;     ...
; #pragma unroll
;   for (int qi = 0; qi < 2; ++qi) {
;     float ls = qi ? lrun1 : lrun0;
;     ls += __shfl_xor(ls, 16);
;     ls += __shfl_xor(ls, 32);
;     const float inv = 1.f / ls;
;     const int pos = qt * 128 + wid * 32 + qi * 16 + l16;
;     const int row = (pos < CTX) ? (T_LAT + b * CTX + pos) : (b * SEQ + pos - CTX);
;     u16* orow = p.YM + (size_t)row * 1024 + 512 + h * 128 + quad * 4;
; #pragma unroll
;     for (int vt = 0; vt < 8; ++vt) {
;       u32x2 pk;
;       pk.x = pack2(o[vt][qi][0] * inv, o[vt][qi][1] * inv);
;       pk.y = pack2(o[vt][qi][2] * inv, o[vt][qi][3] * inv);
;       *(u32x2*)(orow + vt * 16) = pk;
;     }
;   }
	v_mfma_f32_16x16x32_bf16 v[38:41], v[98:101], v[102:105], v[66:69]
	v_mfma_f32_16x16x32_bf16 v[66:69], v[34:37], v[102:105], v[22:25]
	v_mfma_f32_16x16x32_bf16 v[34:37], v[34:37], v[106:109], v[26:29]
	v_mfma_f32_16x16x32_bf16 v[26:29], v[86:89], v[106:109], v[70:73]
	s_nop 2
	v_add_u32_e32 v70, s47, v190
	v_mfma_f32_16x16x32_bf16 v[62:65], v[82:85], v[102:105], v[30:33]
	s_mov_b32 s47, s95
	v_mfma_f32_16x16x32_bf16 v[30:33], v[82:85], v[106:109], v[54:57]
	v_mfma_f32_16x16x32_bf16 v[54:57], v[90:93], v[102:105], v[74:77]
	s_nop 2
	v_or_b32_e32 v77, v70, v189
	ds_bpermute_b32 v70, v230, v0
	v_mfma_f32_16x16x32_bf16 v[22:25], v[90:93], v[106:109], v[78:81]
	v_mov_b32_e32 v189, v1
	v_add_f32_e32 v76, v94, v95
	s_waitcnt lgkmcnt(0)
	v_add_f32_e32 v0, v0, v70
	ds_bpermute_b32 v70, v229, v0
	v_mov_b32_e32 v78, s48
	v_mov_b32_e32 v79, s49
	v_mfma_f32_16x16x32_bf16 v[58:61], v[86:89], v[102:105], v[58:61]
	s_waitcnt lgkmcnt(0)
	v_add_f32_e32 v0, v0, v70
	v_div_scale_f32 v70, s[0:1], v0, v0, 1.0
	v_rcp_f32_e32 v71, v70
	s_nop 0
	v_fma_f32 v72, -v70, v71, 1.0
	v_fmac_f32_e32 v71, v72, v71
	v_div_scale_f32 v72, vcc, 1.0, v0, 1.0
	v_mul_f32_e32 v73, v72, v71
	v_fma_f32 v74, -v70, v73, v72
	v_fmac_f32_e32 v73, v74, v71
	v_fma_f32 v70, -v70, v73, v72
	v_div_fmas_f32 v70, v70, v71, v73
	v_cmp_gt_i32_e32 vcc, s34, v77
	v_div_fixup_f32 v0, v70, v0, 1.0
	v_pk_mul_f32 v[38:39], v[38:39], v[0:1] op_sel_hi:[1,0]
	v_cndmask_b32_e32 v70, v78, v79, vcc
	v_add_u32_e32 v72, v70, v77
	v_mov_b64_e32 v[70:71], s[4:5]
	global_load_dwordx2 v[74:75], v[70:71], off offset:296
	v_ashrrev_i32_e32 v73, 31, v72
	v_lshlrev_b64 v[72:73], 11, v[72:73]
	v_pk_mul_f32 v[40:41], v[40:41], v[0:1] op_sel_hi:[1,0]
	v_cvt_pk_bf16_f32 v38, v38, v39
	v_cvt_pk_bf16_f32 v39, v40, v41
	v_pk_mul_f32 v[40:41], v[68:69], v[0:1] op_sel_hi:[1,0]
	v_pk_mul_f32 v[46:47], v[46:47], v[0:1] op_sel_hi:[1,0]
	v_pk_mul_f32 v[48:49], v[48:49], v[0:1] op_sel_hi:[1,0]
	v_cvt_pk_bf16_f32 v46, v46, v47
	v_cvt_pk_bf16_f32 v47, v48, v49
	v_pk_mul_f32 v[48:49], v[52:53], v[0:1] op_sel_hi:[1,0]
	v_pk_mul_f32 v[42:43], v[42:43], v[0:1] op_sel_hi:[1,0]
	v_pk_mul_f32 v[44:45], v[44:45], v[0:1] op_sel_hi:[1,0]
	v_cvt_pk_bf16_f32 v42, v42, v43
	v_cvt_pk_bf16_f32 v43, v44, v45
	s_waitcnt vmcnt(0) lgkmcnt(0)
	v_lshl_add_u64 v[72:73], v[74:75], 0, v[72:73]
	v_lshl_add_u64 v[72:73], v[72:73], 0, s[46:47]
	v_lshl_add_u64 v[72:73], v[72:73], 0, v[188:189]
	global_store_dwordx2 v[72:73], v[38:39], off offset:1120
	v_pk_mul_f32 v[38:39], v[66:67], v[0:1] op_sel_hi:[1,0]
	global_store_dwordx2 v[72:73], v[46:47], off offset:1024
	v_cvt_pk_bf16_f32 v38, v38, v39
	v_cvt_pk_bf16_f32 v39, v40, v41
	global_store_dwordx2 v[72:73], v[38:39], off offset:1152
	v_pk_mul_f32 v[38:39], v[62:63], v[0:1] op_sel_hi:[1,0]
	v_pk_mul_f32 v[40:41], v[64:65], v[0:1] op_sel_hi:[1,0]
	v_cvt_pk_bf16_f32 v38, v38, v39
	v_cvt_pk_bf16_f32 v39, v40, v41
	global_store_dwordx2 v[72:73], v[38:39], off offset:1184
	v_pk_mul_f32 v[38:39], v[58:59], v[0:1] op_sel_hi:[1,0]
	v_pk_mul_f32 v[40:41], v[60:61], v[0:1] op_sel_hi:[1,0]
	v_cvt_pk_bf16_f32 v38, v38, v39
	v_cvt_pk_bf16_f32 v39, v40, v41
	v_pk_mul_f32 v[46:47], v[50:51], v[0:1] op_sel_hi:[1,0]
	global_store_dwordx2 v[72:73], v[38:39], off offset:1216
	v_pk_mul_f32 v[38:39], v[54:55], v[0:1] op_sel_hi:[1,0]
	v_pk_mul_f32 v[40:41], v[56:57], v[0:1] op_sel_hi:[1,0]
	ds_bpermute_b32 v0, v230, v76
	v_cvt_pk_bf16_f32 v38, v38, v39
	v_cvt_pk_bf16_f32 v39, v40, v41
	global_store_dwordx2 v[72:73], v[38:39], off offset:1248
	global_store_dwordx2 v[72:73], v[42:43], off offset:1088
	s_waitcnt lgkmcnt(0)
	v_add_f32_e32 v0, v76, v0
	ds_bpermute_b32 v38, v229, v0
	v_cvt_pk_bf16_f32 v46, v46, v47
	v_cvt_pk_bf16_f32 v47, v48, v49
	global_store_dwordx2 v[72:73], v[46:47], off offset:1056
	s_waitcnt lgkmcnt(0)
	v_add_f32_e32 v0, v0, v38
	v_div_scale_f32 v38, s[0:1], v0, v0, 1.0
	v_rcp_f32_e32 v39, v38
	s_nop 0
	v_fma_f32 v40, -v38, v39, 1.0
	v_fmac_f32_e32 v39, v40, v39
	v_div_scale_f32 v40, vcc, 1.0, v0, 1.0
	v_mul_f32_e32 v41, v40, v39
	v_fma_f32 v42, -v38, v41, v40
	v_fmac_f32_e32 v41, v42, v39
	v_fma_f32 v38, -v38, v41, v40
	v_div_fmas_f32 v38, v38, v39, v41
	global_load_dwordx2 v[40:41], v[70:71], off offset:296
	v_div_fixup_f32 v0, v38, v0, 1.0
	v_or_b32_e32 v38, 16, v77
	v_cmp_gt_i32_e32 vcc, s34, v38
	v_pk_mul_f32 v[6:7], v[6:7], v[0:1] op_sel_hi:[1,0]
	v_pk_mul_f32 v[8:9], v[8:9], v[0:1] op_sel_hi:[1,0]
	v_cndmask_b32_e32 v39, v78, v79, vcc
	v_add_u32_e32 v38, v39, v38
	v_ashrrev_i32_e32 v39, 31, v38
	v_lshlrev_b64 v[38:39], 11, v[38:39]
	v_cvt_pk_bf16_f32 v6, v6, v7
	v_cvt_pk_bf16_f32 v7, v8, v9
	v_pk_mul_f32 v[8:9], v[36:37], v[0:1] op_sel_hi:[1,0]
	v_pk_mul_f32 v[18:19], v[18:19], v[0:1] op_sel_hi:[1,0]
	v_pk_mul_f32 v[20:21], v[20:21], v[0:1] op_sel_hi:[1,0]
	v_pk_mul_f32 v[14:15], v[14:15], v[0:1] op_sel_hi:[1,0]
	v_pk_mul_f32 v[16:17], v[16:17], v[0:1] op_sel_hi:[1,0]
	v_pk_mul_f32 v[10:11], v[10:11], v[0:1] op_sel_hi:[1,0]
	v_pk_mul_f32 v[12:13], v[12:13], v[0:1] op_sel_hi:[1,0]
	v_cvt_pk_bf16_f32 v18, v18, v19
	v_cvt_pk_bf16_f32 v19, v20, v21
	v_cvt_pk_bf16_f32 v14, v14, v15
	v_cvt_pk_bf16_f32 v15, v16, v17
	v_cvt_pk_bf16_f32 v10, v10, v11
	v_cvt_pk_bf16_f32 v11, v12, v13
	s_waitcnt vmcnt(0) lgkmcnt(0)
	v_lshl_add_u64 v[38:39], v[40:41], 0, v[38:39]
	v_lshl_add_u64 v[38:39], v[38:39], 0, s[46:47]
	v_lshl_add_u64 v[38:39], v[38:39], 0, v[188:189]
	global_store_dwordx2 v[38:39], v[6:7], off offset:1120
	v_pk_mul_f32 v[6:7], v[34:35], v[0:1] op_sel_hi:[1,0]
	global_store_dwordx2 v[38:39], v[18:19], off offset:1024
	v_cvt_pk_bf16_f32 v6, v6, v7
	v_cvt_pk_bf16_f32 v7, v8, v9
	global_store_dwordx2 v[38:39], v[6:7], off offset:1152
	v_pk_mul_f32 v[6:7], v[30:31], v[0:1] op_sel_hi:[1,0]
	v_pk_mul_f32 v[8:9], v[32:33], v[0:1] op_sel_hi:[1,0]
	v_cvt_pk_bf16_f32 v6, v6, v7
	v_cvt_pk_bf16_f32 v7, v8, v9
	global_store_dwordx2 v[38:39], v[6:7], off offset:1184
	v_pk_mul_f32 v[6:7], v[26:27], v[0:1] op_sel_hi:[1,0]
	v_pk_mul_f32 v[8:9], v[28:29], v[0:1] op_sel_hi:[1,0]
	v_cvt_pk_bf16_f32 v6, v6, v7
	v_cvt_pk_bf16_f32 v7, v8, v9
	global_store_dwordx2 v[38:39], v[6:7], off offset:1216
	v_pk_mul_f32 v[6:7], v[22:23], v[0:1] op_sel_hi:[1,0]
	v_pk_mul_f32 v[8:9], v[24:25], v[0:1] op_sel_hi:[1,0]
	v_cvt_pk_bf16_f32 v6, v6, v7
	v_cvt_pk_bf16_f32 v7, v8, v9
	global_store_dwordx2 v[38:39], v[14:15], off offset:1056
	global_store_dwordx2 v[38:39], v[10:11], off offset:1088
	global_store_dwordx2 v[38:39], v[6:7], off offset:1248
	s_cbranch_scc1 .LBB0_776
; __device__ __forceinline__ int tid_() { int t = threadIdx.x; asm volatile("" : "+v"(t)); return t; }
; __device__ __forceinline__ void attn_item(const Params& p, int b, int h, int qt, float shift, unsigned char* smem) {
;     ...
;   const int t = tid_(), lane = t & 63, wid = t >> 6, l16 = lane & 15, quad = lane >> 4;
;   const int nkeys = (qt < 2) ? CTX : NPOS;
;   const int ntile = nkeys >> 5;
;   const u16* Qp = p.Qall + ((size_t)(b * 4 + h) * NPOS + qt * 128 + wid * 32) * 192;
;   const u16* kp = p.Kb + (size_t)(b * 4 + h) * NPOS * 192 + t * 8;
;   const u16* vp = p.Vt + (size_t)(b * 4 + h) * 128 * NPOS + (size_t)(t >> 2) * NPOS + (t & 3) * 8;
;   const u16* qlane = Qp + (size_t)l16 * 192 + quad * 8;
;   bf16x8 bq[2][6];
; #pragma unroll
;   for (int qi = 0; qi < 2; ++qi)
; #pragma unroll
;     for (int ks = 0; ks < 6; ++ks) bq[qi][ks] = *(const bf16x8*)(qlane + qi * 16 * 192 + ks * 32);
;   f32x4 o[8][2];
; #pragma unroll
;   for (int vt = 0; vt < 8; ++vt)
; #pragma unroll
;     for (int qi = 0; qi < 2; ++qi) o[vt][qi] = (f32x4){0.f, 0.f, 0.f, 0.f};
;   float lrun0 = 0.f, lrun1 = 0.f;
;   u32x4 rk[3], rv[2];
;   f32x4 sA[2][2], sB[2][2];
;     ...
;   __syncthreads();
;   ATT_LOAD(0);
;   ATT_STORE(0);
;   ATT_LOAD(1);
.LBB0_766:
	v_mov_b32_e32 v70, v187
	v_mov_b64_e32 v[6:7], s[4:5]
	global_load_dwordx4 v[54:57], v[6:7], off offset:344
	s_lshl_b32 s47, s50, 7
	s_addk_i32 s47, 0x100
	s_ashr_i32 s1, s47, 31
	v_ashrrev_i32_e32 v0, 1, v70
	s_add_u32 s0, s9, s47
	v_and_b32_e32 v190, 0xffffffe0, v0
	s_addc_u32 s1, 0, s1
	v_ashrrev_i32_e32 v191, 31, v190
	v_lshl_add_u64 v[8:9], s[0:1], 0, v[190:191]
	v_and_b32_e32 v189, 15, v70
	v_mul_u32_u24_e32 v0, 0xc0, v189
	v_bfe_u32 v12, v70, 4, 2
	v_lshlrev_b32_e32 v0, 1, v0
	v_lshlrev_b32_e32 v58, 3, v70
	v_ashrrev_i32_e32 v59, 31, v58
	v_lshlrev_b32_e32 v188, 3, v12
	v_ashrrev_i32_e32 v71, 2, v70
	v_and_b32_e32 v191, 24, v58
	v_lshlrev_b32_e32 v66, 1, v191
	v_mov_b32_e32 v67, v1
	s_cmp_lt_i32 s50, 0
	v_lshlrev_b32_e32 v237, 4, v70
	s_cselect_b32 s55, 8, 0x108
	s_mov_b32 s51, 0
	s_mov_b32 s52, 1
	s_mov_b32 s53, 3
	s_mov_b32 s54, 2
	s_add_i32 s56, s55, -1
	v_mul_u32_u24_e32 v208, 0x50, v189
	s_mov_b32 s57, 0
	s_waitcnt vmcnt(0) lgkmcnt(0)
	v_mad_u64_u32 v[10:11], s[0:1], v8, s20, v[56:57]
	global_load_dwordx2 v[56:57], v[6:7], off offset:360
	v_mad_i32_i24 v11, v9, s20, v11
	v_lshl_add_u64 v[6:7], v[10:11], 0, v[0:1]
	v_lshlrev_b32_e32 v0, 4, v12
	v_lshl_add_u64 v[10:11], v[6:7], 0, v[0:1]
	global_load_dwordx4 v[46:49], v[10:11], off
	global_load_dwordx4 v[34:37], v[10:11], off offset:64
	global_load_dwordx4 v[30:33], v[10:11], off offset:128
	global_load_dwordx4 v[18:21], v[10:11], off offset:192
	global_load_dwordx4 v[14:17], v[10:11], off offset:256
	global_load_dwordx4 v[6:9], v[10:11], off offset:320
	v_add_co_u32_e32 v10, vcc, s84, v10
	v_lshl_add_u64 v[54:55], v[54:55], 0, s[42:43]
	s_nop 0
	v_addc_co_u32_e32 v11, vcc, 0, v11, vcc
	global_load_dwordx4 v[50:53], v[10:11], off offset:2048
	global_load_dwordx4 v[42:45], v[10:11], off offset:2112
	global_load_dwordx4 v[38:41], v[10:11], off offset:2176
	global_load_dwordx4 v[26:29], v[10:11], off offset:2240
	global_load_dwordx4 v[22:25], v[10:11], off offset:2304
	s_nop 0
	global_load_dwordx4 v[10:13], v[10:11], off offset:2368
	s_waitcnt lgkmcnt(0)
	s_barrier
	v_mad_i64_i32 v[68:69], s[0:1], v71, s68, v[54:55]
	v_lshl_add_u64 v[194:195], v[68:69], 0, v[66:67]
	global_load_dwordx4 v[72:75], v[194:195], off
	s_mov_b32 s0, 0x2aaaaaab
	v_mul_hi_i32 v67, v70, s0
	v_lshrrev_b32_e32 v80, 31, v67
	v_ashrrev_i32_e32 v67, 2, v67
	v_add_u32_e32 v100, v67, v80
	v_mul_lo_u32 v67, v100, 24
	v_sub_u32_e32 v67, v70, v67
	v_mul_lo_u32 v209, v100, s73
	v_lshlrev_b32_e32 v210, 4, v67
	v_add_u32_e32 v101, v209, v210
	v_mad_u32_u24 v106, v189, s73, v0
	v_and_b32_e32 v0, 3, v70
	v_lshlrev_b32_e32 v0, 4, v0
	v_add_u32_e32 v244, 0xb800, v106
	v_add_u32_e32 v245, 0x5c00, v106
	s_waitcnt vmcnt(0)
	v_lshl_add_u64 v[56:57], v[56:57], 0, s[40:41]
	v_lshl_add_u64 v[192:193], v[58:59], 1, v[56:57]
	global_load_dwordx4 v[62:65], v[192:193], off
	v_add_co_u32_e32 v54, vcc, s84, v192
	s_nop 1
	v_addc_co_u32_e32 v55, vcc, 0, v193, vcc
	global_load_dwordx4 v[58:61], v[54:55], off
	v_add_co_u32_e32 v54, vcc, s70, v192
	s_nop 1
	v_addc_co_u32_e32 v55, vcc, 0, v193, vcc
	global_load_dwordx4 v[54:57], v[54:55], off
	v_add_co_u32_e32 v68, vcc, s72, v194
	s_nop 1
	v_addc_co_u32_e32 v69, vcc, 0, v195, vcc
	global_load_dwordx4 v[76:79], v[68:69], off
	s_waitcnt vmcnt(0) lgkmcnt(0)
	ds_write_b128 v101, v[62:65]
	v_add_u32_e32 v62, 0x100, v70
	v_mul_hi_i32 v63, v62, s0
	v_lshrrev_b32_e32 v64, 31, v63
	v_ashrrev_i32_e32 v63, 2, v63
	v_add_u32_e32 v102, v63, v64
	v_mul_lo_u32 v63, v102, 24
	v_sub_u32_e32 v62, v62, v63
	v_mul_lo_u32 v211, v102, s73
	v_lshlrev_b32_e32 v212, 4, v62
	v_add_u32_e32 v103, v211, v212
	ds_write_b128 v103, v[58:61]
	v_add_u32_e32 v58, 0x200, v70
	v_mul_hi_i32 v59, v58, s0
	v_lshrrev_b32_e32 v60, 31, v59
	v_ashrrev_i32_e32 v59, 2, v59
	v_add_u32_e32 v104, v59, v60
	v_mul_lo_u32 v59, v104, 24
	v_sub_u32_e32 v58, v58, v59
	v_mul_lo_u32 v213, v104, s73
	v_lshlrev_b32_e32 v235, 4, v58
	s_movk_i32 s0, 0x50
	v_add_u32_e32 v105, v213, v235
	v_mul_lo_u32 v236, v71, s0
	s_movk_i32 s0, 0x3000
	ds_write_b128 v105, v[54:57]
	v_add_u32_e32 v71, v66, v236
	v_add_co_u32_e32 v54, vcc, s0, v192
	ds_write_b128 v71, v[72:75] offset:13312
	ds_write_b128 v71, v[76:79] offset:18432
	v_addc_co_u32_e32 v55, vcc, 0, v193, vcc
	global_load_dwordx4 v[72:75], v[54:55], off
	v_add_co_u32_e32 v54, vcc, s69, v192
	s_movk_i32 s0, 0x5000
	s_nop 0
	v_addc_co_u32_e32 v55, vcc, 0, v193, vcc
	global_load_dwordx4 v[76:79], v[54:55], off
	v_add_co_u32_e32 v54, vcc, s0, v192
	v_lshlrev_b32_e32 v70, 5, v104
	s_nop 0
	v_addc_co_u32_e32 v55, vcc, 0, v193, vcc
	global_load_dwordx4 v[80:83], v[54:55], off
	global_load_dwordx4 v[84:87], v[194:195], off offset:64
	global_load_dwordx4 v[88:91], v[68:69], off offset:64
	s_waitcnt lgkmcnt(0)
	s_barrier
; __device__ __forceinline__ void attn_item(const Params& p, int b, int h, int qt, float shift, unsigned char* smem) {
;     ...
;   ATT_S(sA, 0);
;   ATT_STORE(1);
;   __syncthreads();
	ds_read_b128 v[54:57], v106
	ds_read_b128 v[92:95], v106 offset:64
	s_waitcnt lgkmcnt(0)
	v_mfma_f32_16x16x32_bf16 v[58:61], v[54:57], v[46:49], 0
	ds_read_b128 v[62:65], v106 offset:6656
	ds_read_b128 v[96:99], v106 offset:320
	v_add_u32_e32 v238, 0x13400, v70
	v_mfma_f32_16x16x32_bf16 v[54:57], v[54:57], v[50:53], 0
	v_add_u32_e32 v243, 0xd800, v70
	v_mov_b32_e32 v70, 0
	v_mov_b32_e32 v110, v70
	v_mfma_f32_16x16x32_bf16 v[58:61], v[92:95], v[34:37], v[58:61]
	v_mov_b32_e32 v111, v70
	v_mov_b32_e32 v112, v70
	v_mov_b32_e32 v113, v70
	v_mfma_f32_16x16x32_bf16 v[54:57], v[92:95], v[42:45], v[54:57]
	ds_read_b128 v[92:95], v106 offset:6720
	v_mov_b32_e32 v114, v70
	v_mov_b32_e32 v115, v70
	s_waitcnt lgkmcnt(0)
	v_mfma_f32_16x16x32_bf16 v[66:69], v[62:65], v[46:49], 0
	v_mov_b32_e32 v116, v70
	v_mov_b32_e32 v117, v70
	v_mov_b32_e32 v104, v70
	v_mfma_f32_16x16x32_bf16 v[62:65], v[62:65], v[50:53], 0
	v_mov_b32_e32 v107, v70
	v_mov_b32_e32 v108, v70
	v_mov_b32_e32 v109, v70
	v_mfma_f32_16x16x32_bf16 v[66:69], v[92:95], v[34:37], v[66:69]
	v_mov_b32_e32 v118, v70
	v_mov_b32_e32 v119, v70
	v_mov_b32_e32 v120, v70
	v_mfma_f32_16x16x32_bf16 v[62:65], v[92:95], v[42:45], v[62:65]
	ds_read_b128 v[92:95], v106 offset:128
	v_mov_b32_e32 v121, v70
	v_mov_b32_e32 v122, v70
	s_waitcnt lgkmcnt(0)
	v_mfma_f32_16x16x32_bf16 v[58:61], v[92:95], v[30:33], v[58:61]
	v_mov_b32_e32 v123, v70
	v_mov_b32_e32 v124, v70
	v_mov_b32_e32 v125, v70
	v_mfma_f32_16x16x32_bf16 v[54:57], v[92:95], v[38:41], v[54:57]
	ds_read_b128 v[92:95], v106 offset:6784
	v_mov_b32_e32 v126, v70
	v_mov_b32_e32 v127, v70
	s_waitcnt lgkmcnt(0)
	v_mfma_f32_16x16x32_bf16 v[66:69], v[92:95], v[30:33], v[66:69]
	v_mov_b32_e32 v128, v70
	v_mov_b32_e32 v129, v70
	v_mov_b32_e32 v130, v70
	v_mfma_f32_16x16x32_bf16 v[62:65], v[92:95], v[38:41], v[62:65]
	ds_read_b128 v[92:95], v106 offset:192
	v_mov_b32_e32 v131, v70
	v_mov_b32_e32 v132, v70
	s_waitcnt lgkmcnt(0)
	v_mfma_f32_16x16x32_bf16 v[58:61], v[92:95], v[18:21], v[58:61]
	v_mov_b32_e32 v133, v70
	v_mov_b32_e32 v196, v70
	v_mov_b32_e32 v197, v70
	v_mfma_f32_16x16x32_bf16 v[54:57], v[92:95], v[26:29], v[54:57]
	ds_read_b128 v[92:95], v106 offset:6848
	s_waitcnt lgkmcnt(0)
	v_mfma_f32_16x16x32_bf16 v[66:69], v[92:95], v[18:21], v[66:69]
	v_mfma_f32_16x16x32_bf16 v[62:65], v[92:95], v[26:29], v[62:65]
	ds_read_b128 v[92:95], v106 offset:256
	s_waitcnt lgkmcnt(0)
	v_mfma_f32_16x16x32_bf16 v[58:61], v[92:95], v[14:17], v[58:61]
	v_mfma_f32_16x16x32_bf16 v[54:57], v[92:95], v[22:25], v[54:57]
	ds_read_b128 v[92:95], v106 offset:6912
	s_waitcnt lgkmcnt(0)
	v_mfma_f32_16x16x32_bf16 v[66:69], v[92:95], v[14:17], v[66:69]
	v_mfma_f32_16x16x32_bf16 v[92:95], v[92:95], v[22:25], v[62:65]
	v_mfma_f32_16x16x32_bf16 v[62:65], v[96:99], v[6:9], v[58:61]
	s_nop 2
	ds_read_b128 v[58:61], v106 offset:6976
	v_mfma_f32_16x16x32_bf16 v[54:57], v[96:99], v[10:13], v[54:57]
	s_waitcnt vmcnt(0)
	ds_write_b128 v101, v[72:75] offset:23552
	ds_write_b128 v103, v[76:79] offset:23552
	ds_write_b128 v105, v[80:83] offset:23552
	ds_write_b128 v71, v[84:87] offset:36864
	ds_write_b128 v71, v[88:91] offset:41984
	v_lshlrev_b32_e32 v71, 5, v102
	v_lshlrev_b32_e32 v72, 5, v100
	s_waitcnt lgkmcnt(5)
	v_mfma_f32_16x16x32_bf16 v[66:69], v[58:61], v[6:9], v[66:69]
	v_add_u32_e32 v239, 0x12400, v71
	v_add_u32_e32 v240, 0x11400, v72
	v_add_u32_e32 v241, 0xb800, v72
	v_mfma_f32_16x16x32_bf16 v[58:61], v[58:61], v[10:13], v[92:95]
	v_add_u32_e32 v242, 0xc800, v71
	v_mov_b32_e32 v71, v70
	v_mov_b32_e32 v72, v70
	v_mov_b32_e32 v73, v70
	v_mov_b32_e32 v74, v70
	v_mov_b32_e32 v75, v70
	v_mov_b32_e32 v76, v70
	v_mov_b32_e32 v77, v70
	v_mov_b32_e32 v78, v70
	v_mov_b32_e32 v79, v70
	v_mov_b32_e32 v80, v70
	v_mov_b32_e32 v81, v70
	v_mov_b32_e32 v82, v70
	v_mov_b32_e32 v83, v70
	v_mov_b32_e32 v84, v70
	v_mov_b32_e32 v85, v70
	v_mov_b32_e32 v90, v70
	v_mov_b32_e32 v91, v70
	v_mov_b32_e32 v92, v70
	v_mov_b32_e32 v93, v70
	v_mov_b32_e32 v98, v70
	v_mov_b32_e32 v99, v70
	v_mov_b32_e32 v100, v70
	v_mov_b32_e32 v101, v70
	v_mov_b32_e32 v86, v70
	v_mov_b32_e32 v87, v70
	v_mov_b32_e32 v88, v70
	v_mov_b32_e32 v89, v70
	v_mov_b32_e32 v94, v70
	v_mov_b32_e32 v95, v70
	v_mov_b32_e32 v96, v70
	v_mov_b32_e32 v97, v70
	v_mov_b32_e32 v102, v70
	v_mov_b32_e32 v103, v70
	v_mov_b32_e32 v105, v70
	v_mov_b32_e32 v106, v70
	s_waitcnt lgkmcnt(0)
	s_barrier
	s_branch .LBB0_768

.LBB0_768:
	s_add_i32 s0, s52, 1
	s_min_u32 s0, s0, s56
	s_mul_i32 s94, s0, 0x3000
	v_lshl_add_u64 v[142:143], v[192:193], 0, s[94:95]
	v_add_co_u32_e32 v138, vcc, s84, v142
	s_lshl_b32 s94, s0, 6
	s_nop 0
	v_addc_co_u32_e32 v139, vcc, 0, v143, vcc
	global_load_dwordx4 v[134:137], v[142:143], off
	s_nop 0
	global_load_dwordx4 v[138:141], v[138:139], off
	v_add_co_u32_e32 v142, vcc, s70, v142
	v_lshl_add_u64 v[146:147], v[194:195], 0, s[94:95]
	s_nop 0
	v_addc_co_u32_e32 v143, vcc, 0, v143, vcc
	v_add_co_u32_e32 v150, vcc, s72, v146
	global_load_dwordx4 v[142:145], v[142:143], off
	s_nop 0
	v_addc_co_u32_e32 v151, vcc, 0, v147, vcc
	global_load_dwordx4 v[146:149], v[146:147], off
	s_nop 0
	global_load_dwordx4 v[150:153], v[150:151], off
	s_mul_hi_u32 s0, s51, 0xaaaaaaab
	s_lshr_b32 s0, s0, 1
	s_mul_i32 s0, s0, 0x11400
	v_subrev_u32_e32 v154, s0, v208
	v_add_u32_e32 v248, s57, v188
	v_add_u32_e32 v246, v248, v154
	v_add_u32_e32 v154, 0x3000, v246
	ds_read2_b64 v[170:173], v154 offset0:128 offset1:132
	v_add_u32_e32 v154, 0x3800, v246
	ds_read2_b64 v[174:177], v154 offset0:32 offset1:36
	ds_read2_b64 v[178:181], v154 offset0:192 offset1:196
	v_add_u32_e32 v154, 0x4000, v246
	ds_read2_b64 v[182:185], v154 offset0:96 offset1:100
	s_and_saveexec_b64 s[0:1], s[38:39]
	s_cbranch_execz .LBB0_770
	v_sub_f32_e32 v65, v65, v5
	v_sub_f32_e32 v64, v64, v4
	v_sub_f32_e32 v63, v63, v3
	v_sub_f32_e32 v62, v62, v2
	v_sub_f32_e32 v57, v57, v5
	v_sub_f32_e32 v56, v56, v4
	v_sub_f32_e32 v55, v55, v3
	v_sub_f32_e32 v54, v54, v2
	v_sub_f32_e32 v69, v69, v5
	v_sub_f32_e32 v68, v68, v4
	v_sub_f32_e32 v67, v67, v3
	v_sub_f32_e32 v66, v66, v2
	v_sub_f32_e32 v61, v61, v5
	v_sub_f32_e32 v60, v60, v4
	v_sub_f32_e32 v59, v59, v3
	v_sub_f32_e32 v58, v58, v2
.LBB0_770:
	s_or_b64 exec, exec, s[0:1]
	s_mul_hi_u32 s1, s54, 0xaaaaaaab
	s_mul_hi_u32 s0, s52, 0xaaaaaaab
	s_lshr_b32 s34, s1, 1
	s_lshr_b32 s0, s0, 1
	s_mul_i32 s34, s34, 0x11400
	v_add_u32_e32 v154, 0xec00, v236
	s_mul_i32 s0, s0, 0x11400
	v_subrev_u32_e32 v220, s34, v154
	v_add_u32_e32 v154, 0x10000, v236
	v_subrev_u32_e32 v221, s34, v154
	v_subrev_u32_e32 v154, s0, v245
	v_subrev_u32_e32 v216, s0, v208
	v_subrev_u32_e32 v217, s34, v241
	v_subrev_u32_e32 v218, s34, v242
	v_subrev_u32_e32 v219, s34, v243
	s_setprio 1
	v_add_u32_e32 v202, s57, v154
	ds_read_b128 v[154:157], v202
	ds_read_b128 v[198:201], v202 offset:64
	ds_read_b128 v[162:165], v202 offset:6656
	v_exp_f32_e32 v206, v63
	v_exp_f32_e32 v204, v65
	v_exp_f32_e32 v207, v55
	v_exp_f32_e32 v205, v57
	v_exp_f32_e32 v65, v58
	v_exp_f32_e32 v203, v59
	s_waitcnt lgkmcnt(0)
	v_mfma_f32_16x16x32_bf16 v[158:161], v[154:157], v[46:49], 0
	v_exp_f32_e32 v63, v60
	v_cvt_pk_bf16_f32 v60, v65, v203
	v_mfma_f32_16x16x32_bf16 v[154:157], v[154:157], v[50:53], 0
	v_mfma_f32_16x16x32_bf16 v[158:161], v[198:201], v[34:37], v[158:161]
	v_mfma_f32_16x16x32_bf16 v[154:157], v[198:201], v[42:45], v[154:157]
	ds_read_b128 v[198:201], v202 offset:6720
	v_mfma_f32_16x16x32_bf16 v[166:169], v[162:165], v[46:49], 0
	v_mfma_f32_16x16x32_bf16 v[162:165], v[162:165], v[50:53], 0
	s_waitcnt lgkmcnt(0)
	v_mfma_f32_16x16x32_bf16 v[166:169], v[198:201], v[34:37], v[166:169]
	v_mfma_f32_16x16x32_bf16 v[162:165], v[198:201], v[42:45], v[162:165]
	ds_read_b128 v[198:201], v202 offset:128
	s_waitcnt lgkmcnt(0)
	v_mfma_f32_16x16x32_bf16 v[158:161], v[198:201], v[30:33], v[158:161]
	v_mfma_f32_16x16x32_bf16 v[154:157], v[198:201], v[38:41], v[154:157]
	ds_read_b128 v[198:201], v202 offset:6784
	s_waitcnt lgkmcnt(0)
	v_mfma_f32_16x16x32_bf16 v[166:169], v[198:201], v[30:33], v[166:169]
	v_mfma_f32_16x16x32_bf16 v[162:165], v[198:201], v[38:41], v[162:165]
	ds_read_b128 v[198:201], v202 offset:192
	s_waitcnt lgkmcnt(0)
	v_mfma_f32_16x16x32_bf16 v[158:161], v[198:201], v[18:21], v[158:161]
	v_mfma_f32_16x16x32_bf16 v[154:157], v[198:201], v[26:29], v[154:157]
	ds_read_b128 v[198:201], v202 offset:6848
	s_waitcnt lgkmcnt(0)
	v_mfma_f32_16x16x32_bf16 v[166:169], v[198:201], v[18:21], v[166:169]
	v_mfma_f32_16x16x32_bf16 v[162:165], v[198:201], v[26:29], v[162:165]
	ds_read_b128 v[198:201], v202 offset:256
	s_waitcnt lgkmcnt(0)
	v_mfma_f32_16x16x32_bf16 v[158:161], v[198:201], v[14:17], v[158:161]
	v_mfma_f32_16x16x32_bf16 v[154:157], v[198:201], v[22:25], v[154:157]
	ds_read_b128 v[198:201], v202 offset:6912
	s_waitcnt lgkmcnt(0)
	v_mfma_f32_16x16x32_bf16 v[166:169], v[198:201], v[14:17], v[166:169]
	v_mfma_f32_16x16x32_bf16 v[162:165], v[198:201], v[22:25], v[162:165]
	ds_read_b128 v[198:201], v202 offset:320
	s_waitcnt lgkmcnt(0)
	v_mfma_f32_16x16x32_bf16 v[158:161], v[198:201], v[6:9], v[158:161]
	v_mfma_f32_16x16x32_bf16 v[154:157], v[198:201], v[10:13], v[154:157]
	ds_read_b128 v[198:201], v202 offset:6976
	v_exp_f32_e32 v202, v67
	v_exp_f32_e32 v67, v61
	s_waitcnt lgkmcnt(0)
	v_mfma_f32_16x16x32_bf16 v[166:169], v[198:201], v[6:9], v[166:169]
	v_cvt_pk_bf16_f32 v61, v63, v67
	v_mfma_f32_16x16x32_bf16 v[162:165], v[198:201], v[10:13], v[162:165]
	v_exp_f32_e32 v200, v62
	v_exp_f32_e32 v198, v64
	v_exp_f32_e32 v64, v66
	v_exp_f32_e32 v62, v68
	v_exp_f32_e32 v66, v69
	v_exp_f32_e32 v201, v54
	v_exp_f32_e32 v199, v56
	v_cvt_pk_bf16_f32 v54, v200, v206
	v_cvt_pk_bf16_f32 v55, v198, v204
	v_cvt_pk_bf16_f32 v56, v64, v202
	v_cvt_pk_bf16_f32 v57, v62, v66
	v_cvt_pk_bf16_f32 v58, v201, v207
	v_cvt_pk_bf16_f32 v59, v199, v205
	v_add_u32_e32 v68, 0x4800, v246
	v_mfma_f32_16x16x32_bf16 v[114:117], v[170:173], v[54:57], v[114:117]
	v_mfma_f32_16x16x32_bf16 v[110:113], v[170:173], v[58:61], v[110:113]
	v_mfma_f32_16x16x32_bf16 v[98:101], v[174:177], v[54:57], v[98:101]
	v_mfma_f32_16x16x32_bf16 v[90:93], v[174:177], v[58:61], v[90:93]
	ds_read2_b64 v[170:173], v68 offset1:4
	ds_read2_b64 v[174:177], v68 offset0:160 offset1:164
	v_add_u32_e32 v68, 0x5000, v246
	v_mfma_f32_16x16x32_bf16 v[82:85], v[178:181], v[54:57], v[82:85]
	v_mfma_f32_16x16x32_bf16 v[78:81], v[178:181], v[58:61], v[78:81]
	v_mfma_f32_16x16x32_bf16 v[74:77], v[182:185], v[54:57], v[74:77]
	v_mfma_f32_16x16x32_bf16 v[70:73], v[182:185], v[58:61], v[70:73]
	ds_read2_b64 v[178:181], v68 offset0:64 offset1:68
	ds_read2_b64 v[182:185], v68 offset0:224 offset1:228
	s_waitcnt lgkmcnt(0)
	v_mfma_f32_16x16x32_bf16 v[86:89], v[170:173], v[54:57], v[86:89]
	v_mfma_f32_16x16x32_bf16 v[94:97], v[170:173], v[58:61], v[94:97]
	v_mfma_f32_16x16x32_bf16 v[102:105], v[174:177], v[54:57], v[102:105]
	v_mfma_f32_16x16x32_bf16 v[106:109], v[174:177], v[58:61], v[106:109]
	v_mfma_f32_16x16x32_bf16 v[118:121], v[178:181], v[54:57], v[118:121]
	v_mfma_f32_16x16x32_bf16 v[122:125], v[178:181], v[58:61], v[122:125]
	v_mfma_f32_16x16x32_bf16 v[126:129], v[182:185], v[54:57], v[126:129]
	v_mfma_f32_16x16x32_bf16 v[130:133], v[182:185], v[58:61], v[130:133]
	s_setprio 0
	v_add_u32_e32 v246, s57, v237
	v_add_u32_e32 v54, v246, v217
	s_waitcnt vmcnt(0)
	ds_write_b128 v54, v[134:137]
	v_add_u32_e32 v54, v246, v218
	ds_write_b128 v54, v[138:141]
	v_add_u32_e32 v54, v246, v219
	v_add_u32_e32 v247, s57, v0
	s_add_i32 s52, s52, 2
	ds_write_b128 v54, v[142:145]
	v_add_u32_e32 v54, v247, v220
	s_min_u32 s0, s52, s56
	ds_write_b128 v54, v[146:149]
	v_add_u32_e32 v54, v247, v221
	s_mul_i32 s94, s0, 0x3000
	ds_write_b128 v54, v[150:153]
	v_lshl_add_u64 v[54:55], v[192:193], 0, s[94:95]
	v_add_co_u32_e32 v56, vcc, s84, v54
	s_waitcnt lgkmcnt(0)
	s_nop 0
	v_addc_co_u32_e32 v57, vcc, 0, v55, vcc
	s_barrier
	global_load_dwordx4 v[134:137], v[54:55], off
	global_load_dwordx4 v[138:141], v[56:57], off
	v_add_co_u32_e32 v54, vcc, s70, v54
	s_lshl_b32 s94, s0, 6
	s_nop 0
	v_addc_co_u32_e32 v55, vcc, 0, v55, vcc
	global_load_dwordx4 v[142:145], v[54:55], off
	v_lshl_add_u64 v[54:55], v[194:195], 0, s[94:95]
	v_add_co_u32_e32 v56, vcc, s72, v54
	v_add_u32_e32 v248, v248, v216
	s_nop 0
	v_addc_co_u32_e32 v57, vcc, 0, v55, vcc
	global_load_dwordx4 v[146:149], v[54:55], off
	global_load_dwordx4 v[150:153], v[56:57], off
	v_add_u32_e32 v54, 0x9000, v248
	ds_read2_b64 v[170:173], v54 offset1:4
	ds_read2_b64 v[174:177], v54 offset0:160 offset1:164
	v_add_u32_e32 v54, 0x9800, v248
	ds_read2_b64 v[178:181], v54 offset0:64 offset1:68
	ds_read2_b64 v[182:185], v54 offset0:224 offset1:228
	s_and_saveexec_b64 s[0:1], s[38:39]
	s_cbranch_execz .LBB0_767
	v_sub_f32_e32 v161, v161, v5
	v_sub_f32_e32 v160, v160, v4
	v_sub_f32_e32 v159, v159, v3
	v_sub_f32_e32 v158, v158, v2
	v_sub_f32_e32 v157, v157, v5
	v_sub_f32_e32 v156, v156, v4
	v_sub_f32_e32 v155, v155, v3
	v_sub_f32_e32 v154, v154, v2
	v_sub_f32_e32 v169, v169, v5
	v_sub_f32_e32 v168, v168, v4
	v_sub_f32_e32 v167, v167, v3
	v_sub_f32_e32 v166, v166, v2
	v_sub_f32_e32 v165, v165, v5
	v_sub_f32_e32 v164, v164, v4
	v_sub_f32_e32 v163, v163, v3
	v_sub_f32_e32 v162, v162, v2
	s_branch .LBB0_767
.LBB0_772:
	s_mul_i32 s94, s56, 0x3000
	v_lshl_add_u64 v[142:143], v[192:193], 0, s[94:95]
	v_add_co_u32_e32 v138, vcc, 0x1000, v142
	s_lshl_b32 s94, s56, 6
	s_nop 0
	v_addc_co_u32_e32 v139, vcc, 0, v143, vcc
	global_load_dwordx4 v[134:137], v[142:143], off
	s_nop 0
	global_load_dwordx4 v[138:141], v[138:139], off
	v_add_co_u32_e32 v142, vcc, 0x2000, v142
	v_lshl_add_u64 v[146:147], v[194:195], 0, s[94:95]
	s_nop 0
	v_addc_co_u32_e32 v143, vcc, 0, v143, vcc
	v_add_co_u32_e32 v150, vcc, 0x108000, v146
	global_load_dwordx4 v[142:145], v[142:143], off
	s_nop 0
	v_addc_co_u32_e32 v151, vcc, 0, v147, vcc
	global_load_dwordx4 v[146:149], v[146:147], off
	s_nop 0
	global_load_dwordx4 v[150:153], v[150:151], off
	s_add_i32 s0, s55, 0xfffe
	s_and_b32 s1, s0, 0xffff
	s_mul_i32 s1, s1, 0xaaab
	s_lshr_b32 s1, s1, 17
	s_mul_i32 s1, s1, 3
	s_sub_i32 s0, s0, s1
	s_mulk_i32 s0, 0x2e00
	s_and_b32 s0, s0, 0xfe00
	s_lshl_b32 s35, s0, 1
	v_or_b32_e32 v0, s35, v188
	v_add_u32_e32 v0, v0, v208
	v_add_u32_e32 v154, 0x3000, v0
	v_add_u32_e32 v162, 0x3800, v0
	v_add_u32_e32 v0, 0x4000, v0
	ds_read2_b64 v[154:157], v154 offset0:128 offset1:132
	ds_read2_b64 v[158:161], v162 offset0:32 offset1:36
	ds_read2_b64 v[162:165], v162 offset0:192 offset1:196
	ds_read2_b64 v[166:169], v0 offset0:96 offset1:100
	s_and_saveexec_b64 s[0:1], s[38:39]
	s_cbranch_execz .LBB0_774
	v_sub_f32_e32 v65, v65, v5
	v_sub_f32_e32 v64, v64, v4
	v_sub_f32_e32 v63, v63, v3
	v_sub_f32_e32 v62, v62, v2
	v_sub_f32_e32 v57, v57, v5
	v_sub_f32_e32 v56, v56, v4
	v_sub_f32_e32 v55, v55, v3
	v_sub_f32_e32 v54, v54, v2
	v_sub_f32_e32 v69, v69, v5
	v_sub_f32_e32 v68, v68, v4
	v_sub_f32_e32 v67, v67, v3
	v_sub_f32_e32 v66, v66, v2
	v_sub_f32_e32 v61, v61, v5
	v_sub_f32_e32 v60, v60, v4
	v_sub_f32_e32 v59, v59, v3
	v_sub_f32_e32 v58, v58, v2

; __device__ __forceinline__ void attn_item(const Params& p, int b, int h, int qt, float shift, unsigned char* smem) {
;     ...
; #pragma unroll
;   for (int qi = 0; qi < 2; ++qi) {
;     float ls = qi ? lrun1 : lrun0;
;     ls += __shfl_xor(ls, 16);
;     ls += __shfl_xor(ls, 32);
;     const float inv = 1.f / ls;
;     const int pos = qt * 128 + wid * 32 + qi * 16 + l16;
;     const int row = (pos < CTX) ? (T_LAT + b * CTX + pos) : (b * SEQ + pos - CTX);
;     u16* orow = p.YM + (size_t)row * 1024 + 512 + h * 128 + quad * 4;
; #pragma unroll
;     for (int vt = 0; vt < 8; ++vt) {
;       u32x2 pk;
;       pk.x = pack2(o[vt][qi][0] * inv, o[vt][qi][1] * inv);
;       pk.y = pack2(o[vt][qi][2] * inv, o[vt][qi][3] * inv);
;       *(u32x2*)(orow + vt * 16) = pk;
;     }
;   }
.LBB0_778:
	s_or_b64 exec, exec, s[0:1]
	v_exp_f32_e32 v185, v46
	v_exp_f32_e32 v193, v47
	v_exp_f32_e32 v195, v48
	v_exp_f32_e32 v197, v49
	v_exp_f32_e32 v199, v50
	v_exp_f32_e32 v201, v51
	v_exp_f32_e32 v205, v52
	v_exp_f32_e32 v47, v53
	v_exp_f32_e32 v173, v14
	v_add_f32_e32 v110, 0, v171
	v_exp_f32_e32 v171, v15
	v_add_f32_e32 v0, 0, v0
	v_exp_f32_e32 v177, v16
	v_pk_add_f32 v[48:49], v[184:185], v[0:1]
	v_cvt_pk_bf16_f32 v102, v185, v193
	v_cvt_pk_bf16_f32 v103, v195, v197
	v_cvt_pk_bf16_f32 v104, v199, v201
	v_cvt_pk_bf16_f32 v105, v205, v47
	v_exp_f32_e32 v175, v17
	v_mov_b32_e32 v111, v1
	v_pk_add_f32 v[48:49], v[192:193], v[48:49]
	v_exp_f32_e32 v181, v6
	s_waitcnt lgkmcnt(2)
	v_mfma_f32_16x16x32_bf16 v[50:53], v[90:93], v[102:105], v[34:37]
	v_add_f32_e64 v48, v194, v48
	v_add_f32_e64 v49, v195, v49
	v_exp_f32_e32 v179, v7
	v_pk_add_f32 v[48:49], v[196:197], v[48:49]
	v_pk_add_f32 v[34:35], v[172:173], v[110:111]
	v_exp_f32_e32 v183, v8
	v_pk_add_f32 v[34:35], v[170:171], v[34:35]
	v_exp_f32_e32 v113, v9
	v_pk_add_f32 v[34:35], v[176:177], v[34:35]
	v_pk_add_f32 v[48:49], v[198:199], v[48:49]
	v_pk_add_f32 v[34:35], v[174:175], v[34:35]
	v_pk_add_f32 v[48:49], v[200:201], v[48:49]
	v_pk_add_f32 v[34:35], v[180:181], v[34:35]
	v_pk_add_f32 v[48:49], v[204:205], v[48:49]
	v_mov_b32_e32 v46, v202
	v_pk_add_f32 v[34:35], v[178:179], v[34:35]
	v_pk_add_f32 v[48:49], v[46:47], v[48:49]
	v_cvt_pk_bf16_f32 v106, v173, v171
	v_cvt_pk_bf16_f32 v107, v177, v175
	v_cvt_pk_bf16_f32 v108, v181, v179
	v_cvt_pk_bf16_f32 v109, v183, v113
	v_pk_add_f32 v[34:35], v[182:183], v[34:35]
	v_mov_b32_e32 v112, v203
	v_add_f32_e32 v0, v48, v49
	v_mfma_f32_16x16x32_bf16 v[46:49], v[86:89], v[102:105], v[10:13]
	s_movk_i32 s34, 0x100
	s_add_i32 s8, s8, s3
	s_cmp_lt_i32 s8, 2
	s_waitcnt lgkmcnt(1)
	v_mfma_f32_16x16x32_bf16 v[42:45], v[94:97], v[102:105], v[42:45]
	v_mfma_f32_16x16x32_bf16 v[10:13], v[94:97], v[106:109], v[62:65]
	v_add_f32_e64 v94, v112, v34
	v_add_f32_e64 v95, v113, v35
	v_add_u32_e32 v34, 0xa000, v191
	ds_read2_b64 v[34:37], v34 offset0:128 offset1:132
	v_add_u32_e32 v62, 0xa800, v191
	v_mfma_f32_16x16x32_bf16 v[18:21], v[86:89], v[106:109], v[18:21]
	s_waitcnt lgkmcnt(1)
	v_mfma_f32_16x16x32_bf16 v[6:9], v[98:101], v[106:109], v[82:85]
	s_nop 2
	ds_read2_b64 v[82:85], v62 offset0:32 offset1:36
	ds_read2_b64 v[86:89], v62 offset0:192 offset1:196
	v_add_u32_e32 v62, 0xb000, v191
	v_mfma_f32_16x16x32_bf16 v[14:17], v[90:93], v[106:109], v[38:41]
	ds_read2_b64 v[90:93], v62 offset0:96 offset1:100
	s_waitcnt lgkmcnt(0)
	s_barrier
	v_mfma_f32_16x16x32_bf16 v[38:41], v[98:101], v[102:105], v[66:69]
	v_mfma_f32_16x16x32_bf16 v[66:69], v[34:37], v[102:105], v[22:25]
	v_mfma_f32_16x16x32_bf16 v[34:37], v[34:37], v[106:109], v[26:29]
	v_mfma_f32_16x16x32_bf16 v[26:29], v[86:89], v[106:109], v[70:73]
	s_nop 2
	v_add_u32_e32 v70, s46, v190
	v_mfma_f32_16x16x32_bf16 v[62:65], v[82:85], v[102:105], v[30:33]
	v_mfma_f32_16x16x32_bf16 v[30:33], v[82:85], v[106:109], v[54:57]
	v_mfma_f32_16x16x32_bf16 v[54:57], v[90:93], v[102:105], v[74:77]
	s_nop 2
	v_or_b32_e32 v77, v70, v189
	ds_bpermute_b32 v70, v230, v0
	v_mfma_f32_16x16x32_bf16 v[22:25], v[90:93], v[106:109], v[78:81]
	v_mov_b32_e32 v189, v1
	v_add_f32_e32 v76, v94, v95
	s_waitcnt lgkmcnt(0)
	v_add_f32_e32 v0, v0, v70
	ds_bpermute_b32 v70, v229, v0
	v_mov_b32_e32 v78, s18
	v_mov_b32_e32 v79, s19
	v_mfma_f32_16x16x32_bf16 v[58:61], v[86:89], v[102:105], v[58:61]
	s_waitcnt lgkmcnt(0)
	v_add_f32_e32 v0, v0, v70
	v_div_scale_f32 v70, s[0:1], v0, v0, 1.0
	v_rcp_f32_e32 v71, v70
	s_nop 0
	v_fma_f32 v72, -v70, v71, 1.0
	v_fmac_f32_e32 v71, v72, v71
	v_div_scale_f32 v72, vcc, 1.0, v0, 1.0
	v_mul_f32_e32 v73, v72, v71
	v_fma_f32 v74, -v70, v73, v72
	v_fmac_f32_e32 v73, v74, v71
	v_fma_f32 v70, -v70, v73, v72
	v_div_fmas_f32 v70, v70, v71, v73
	v_cmp_gt_i32_e32 vcc, s34, v77
	v_div_fixup_f32 v0, v70, v0, 1.0
	v_pk_mul_f32 v[38:39], v[38:39], v[0:1] op_sel_hi:[1,0]
	v_cndmask_b32_e32 v70, v78, v79, vcc
	v_add_u32_e32 v72, v70, v77
	v_mov_b64_e32 v[70:71], s[4:5]
	global_load_dwordx2 v[74:75], v[70:71], off offset:296
	v_ashrrev_i32_e32 v73, 31, v72
	v_lshlrev_b64 v[72:73], 11, v[72:73]
	v_pk_mul_f32 v[40:41], v[40:41], v[0:1] op_sel_hi:[1,0]
	v_cvt_pk_bf16_f32 v38, v38, v39
	v_cvt_pk_bf16_f32 v39, v40, v41
	v_pk_mul_f32 v[40:41], v[68:69], v[0:1] op_sel_hi:[1,0]
	v_pk_mul_f32 v[46:47], v[46:47], v[0:1] op_sel_hi:[1,0]
	v_pk_mul_f32 v[48:49], v[48:49], v[0:1] op_sel_hi:[1,0]
	v_cvt_pk_bf16_f32 v46, v46, v47
	v_cvt_pk_bf16_f32 v47, v48, v49
	v_pk_mul_f32 v[48:49], v[52:53], v[0:1] op_sel_hi:[1,0]
	v_pk_mul_f32 v[42:43], v[42:43], v[0:1] op_sel_hi:[1,0]
	v_pk_mul_f32 v[44:45], v[44:45], v[0:1] op_sel_hi:[1,0]
	v_cvt_pk_bf16_f32 v42, v42, v43
	v_cvt_pk_bf16_f32 v43, v44, v45
	s_waitcnt vmcnt(0) lgkmcnt(0)
	v_lshl_add_u64 v[72:73], v[74:75], 0, v[72:73]
	v_lshl_add_u64 v[72:73], v[72:73], 0, s[94:95]
	v_lshl_add_u64 v[72:73], v[72:73], 0, v[188:189]
	global_store_dwordx2 v[72:73], v[38:39], off offset:1120
	v_pk_mul_f32 v[38:39], v[66:67], v[0:1] op_sel_hi:[1,0]
	global_store_dwordx2 v[72:73], v[46:47], off offset:1024
	v_cvt_pk_bf16_f32 v38, v38, v39
	v_cvt_pk_bf16_f32 v39, v40, v41
	global_store_dwordx2 v[72:73], v[38:39], off offset:1152
	v_pk_mul_f32 v[38:39], v[62:63], v[0:1] op_sel_hi:[1,0]
	v_pk_mul_f32 v[40:41], v[64:65], v[0:1] op_sel_hi:[1,0]
	v_cvt_pk_bf16_f32 v38, v38, v39
	v_cvt_pk_bf16_f32 v39, v40, v41
	global_store_dwordx2 v[72:73], v[38:39], off offset:1184
	v_pk_mul_f32 v[38:39], v[58:59], v[0:1] op_sel_hi:[1,0]
	v_pk_mul_f32 v[40:41], v[60:61], v[0:1] op_sel_hi:[1,0]
	v_cvt_pk_bf16_f32 v38, v38, v39
	v_cvt_pk_bf16_f32 v39, v40, v41
	v_pk_mul_f32 v[46:47], v[50:51], v[0:1] op_sel_hi:[1,0]
	global_store_dwordx2 v[72:73], v[38:39], off offset:1216
	v_pk_mul_f32 v[38:39], v[54:55], v[0:1] op_sel_hi:[1,0]
	v_pk_mul_f32 v[40:41], v[56:57], v[0:1] op_sel_hi:[1,0]
	ds_bpermute_b32 v0, v230, v76
	v_cvt_pk_bf16_f32 v38, v38, v39
	v_cvt_pk_bf16_f32 v39, v40, v41
	global_store_dwordx2 v[72:73], v[38:39], off offset:1248
	global_store_dwordx2 v[72:73], v[42:43], off offset:1088
	s_waitcnt lgkmcnt(0)
; __device__ __forceinline__ int tid_() { int t = threadIdx.x; asm volatile("" : "+v"(t)); return t; }
; __device__ __forceinline__ void attn_item(const Params& p, int b, int h, int qt, float shift, unsigned char* smem) {
;   constexpr int STAGE = 32 * 208 + 128 * 40;
;   u16* sbase = (u16*)smem;
;   const int t = tid_(), lane = t & 63, wid = t >> 6, l16 = lane & 15, quad = lane >> 4;
;   const int nkeys = (qt < 2) ? CTX : NPOS;
;   const int ntile = nkeys >> 5;
;   const u16* Qp = p.Qall + ((size_t)(b * 4 + h) * NPOS + qt * 128 + wid * 32) * 192;
;   const u16* kp = p.Kb + (size_t)(b * 4 + h) * NPOS * 192 + t * 8;
;   const u16* vp = p.Vt + (size_t)(b * 4 + h) * 128 * NPOS + (size_t)(t >> 2) * NPOS + (t & 3) * 8;
;   const u16* qlane = Qp + (size_t)l16 * 192 + quad * 8;
;   bf16x8 bq[2][6];
; #pragma unroll
;   for (int qi = 0; qi < 2; ++qi)
; #pragma unroll
;     for (int ks = 0; ks < 6; ++ks) bq[qi][ks] = *(const bf16x8*)(qlane + qi * 16 * 192 + ks * 32);
;     ...
; #pragma unroll
;   for (int qi = 0; qi < 2; ++qi) {
;     float ls = qi ? lrun1 : lrun0;
;     ls += __shfl_xor(ls, 16);
;     ls += __shfl_xor(ls, 32);
;     const float inv = 1.f / ls;
;     const int pos = qt * 128 + wid * 32 + qi * 16 + l16;
;     const int row = (pos < CTX) ? (T_LAT + b * CTX + pos) : (b * SEQ + pos - CTX);
;     u16* orow = p.YM + (size_t)row * 1024 + 512 + h * 128 + quad * 4;
; #pragma unroll
;     for (int vt = 0; vt < 8; ++vt) {
;       u32x2 pk;
;       pk.x = pack2(o[vt][qi][0] * inv, o[vt][qi][1] * inv);
;       pk.y = pack2(o[vt][qi][2] * inv, o[vt][qi][3] * inv);
;       *(u32x2*)(orow + vt * 16) = pk;
;     }
;   }
	v_add_f32_e32 v0, v76, v0
	ds_bpermute_b32 v38, v229, v0
	v_cvt_pk_bf16_f32 v46, v46, v47
	v_cvt_pk_bf16_f32 v47, v48, v49
	global_store_dwordx2 v[72:73], v[46:47], off offset:1056
	s_waitcnt lgkmcnt(0)
	v_add_f32_e32 v0, v0, v38
	v_div_scale_f32 v38, s[0:1], v0, v0, 1.0
	v_rcp_f32_e32 v39, v38
	s_nop 0
	v_fma_f32 v40, -v38, v39, 1.0
	v_fmac_f32_e32 v39, v40, v39
	v_div_scale_f32 v40, vcc, 1.0, v0, 1.0
	v_mul_f32_e32 v41, v40, v39
	v_fma_f32 v42, -v38, v41, v40
	v_fmac_f32_e32 v41, v42, v39
	v_fma_f32 v38, -v38, v41, v40
	v_div_fmas_f32 v38, v38, v39, v41
	global_load_dwordx2 v[40:41], v[70:71], off offset:296
	v_div_fixup_f32 v0, v38, v0, 1.0
	v_or_b32_e32 v38, 16, v77
	v_cmp_gt_i32_e32 vcc, s34, v38
	v_pk_mul_f32 v[6:7], v[6:7], v[0:1] op_sel_hi:[1,0]
	v_pk_mul_f32 v[8:9], v[8:9], v[0:1] op_sel_hi:[1,0]
	v_cndmask_b32_e32 v39, v78, v79, vcc
	v_add_u32_e32 v38, v39, v38
	v_ashrrev_i32_e32 v39, 31, v38
	v_lshlrev_b64 v[38:39], 11, v[38:39]
	v_cvt_pk_bf16_f32 v6, v6, v7
	v_cvt_pk_bf16_f32 v7, v8, v9
	v_pk_mul_f32 v[8:9], v[36:37], v[0:1] op_sel_hi:[1,0]
	v_pk_mul_f32 v[18:19], v[18:19], v[0:1] op_sel_hi:[1,0]
	v_pk_mul_f32 v[20:21], v[20:21], v[0:1] op_sel_hi:[1,0]
	v_pk_mul_f32 v[14:15], v[14:15], v[0:1] op_sel_hi:[1,0]
	v_pk_mul_f32 v[16:17], v[16:17], v[0:1] op_sel_hi:[1,0]
	v_pk_mul_f32 v[10:11], v[10:11], v[0:1] op_sel_hi:[1,0]
	v_pk_mul_f32 v[12:13], v[12:13], v[0:1] op_sel_hi:[1,0]
	v_cvt_pk_bf16_f32 v18, v18, v19
	v_cvt_pk_bf16_f32 v19, v20, v21
	v_cvt_pk_bf16_f32 v14, v14, v15
	v_cvt_pk_bf16_f32 v15, v16, v17
	v_cvt_pk_bf16_f32 v10, v10, v11
	v_cvt_pk_bf16_f32 v11, v12, v13
	s_waitcnt vmcnt(0) lgkmcnt(0)
	v_lshl_add_u64 v[38:39], v[40:41], 0, v[38:39]
	v_lshl_add_u64 v[38:39], v[38:39], 0, s[94:95]
	v_lshl_add_u64 v[38:39], v[38:39], 0, v[188:189]
	global_store_dwordx2 v[38:39], v[6:7], off offset:1120
	v_pk_mul_f32 v[6:7], v[34:35], v[0:1] op_sel_hi:[1,0]
	global_store_dwordx2 v[38:39], v[18:19], off offset:1024
	v_cvt_pk_bf16_f32 v6, v6, v7
	v_cvt_pk_bf16_f32 v7, v8, v9
	global_store_dwordx2 v[38:39], v[6:7], off offset:1152
	v_pk_mul_f32 v[6:7], v[30:31], v[0:1] op_sel_hi:[1,0]
	v_pk_mul_f32 v[8:9], v[32:33], v[0:1] op_sel_hi:[1,0]
	v_cvt_pk_bf16_f32 v6, v6, v7
	v_cvt_pk_bf16_f32 v7, v8, v9
	global_store_dwordx2 v[38:39], v[6:7], off offset:1184
	v_pk_mul_f32 v[6:7], v[26:27], v[0:1] op_sel_hi:[1,0]
	v_pk_mul_f32 v[8:9], v[28:29], v[0:1] op_sel_hi:[1,0]
	v_cvt_pk_bf16_f32 v6, v6, v7
	v_cvt_pk_bf16_f32 v7, v8, v9
	global_store_dwordx2 v[38:39], v[6:7], off offset:1216
	v_pk_mul_f32 v[6:7], v[22:23], v[0:1] op_sel_hi:[1,0]
	v_pk_mul_f32 v[8:9], v[24:25], v[0:1] op_sel_hi:[1,0]
	v_cvt_pk_bf16_f32 v6, v6, v7
	v_cvt_pk_bf16_f32 v7, v8, v9
	global_store_dwordx2 v[38:39], v[14:15], off offset:1056
	global_store_dwordx2 v[38:39], v[10:11], off offset:1088
	global_store_dwordx2 v[38:39], v[6:7], off offset:1248
	s_cbranch_scc0 .LBB0_790
.LBB0_779:
	v_mov_b32_e32 v74, v187
	v_mov_b64_e32 v[6:7], s[4:5]
	global_load_dwordx4 v[54:57], v[6:7], off offset:344
	s_lshl_b32 s46, s8, 7
	s_ashr_i32 s1, s46, 31
	v_ashrrev_i32_e32 v0, 1, v74
	s_add_u32 s0, s9, s46
	v_and_b32_e32 v190, 0xffffffe0, v0
	s_addc_u32 s1, 0, s1
	v_ashrrev_i32_e32 v191, 31, v190
	v_lshl_add_u64 v[8:9], s[0:1], 0, v[190:191]
	v_and_b32_e32 v189, 15, v74
	v_mul_u32_u24_e32 v0, 0xc0, v189
	v_bfe_u32 v12, v74, 4, 2
	v_lshlrev_b32_e32 v0, 1, v0
	v_lshlrev_b32_e32 v58, 3, v74
	v_ashrrev_i32_e32 v59, 31, v58
	v_lshlrev_b32_e32 v188, 3, v12
	v_and_b32_e32 v191, 24, v58
	v_ashrrev_i32_e32 v75, 2, v74
	v_lshlrev_b32_e32 v66, 1, v191
	v_mov_b32_e32 v67, v1
	v_mad_i64_i32 v[70:71], s[0:1], v75, s68, 0
	s_mov_b32 s47, 1
	v_mul_u32_u24_e32 v239, 0x1a0, v189
	s_waitcnt vmcnt(0) lgkmcnt(0)
	v_mad_u64_u32 v[10:11], s[0:1], v8, s20, v[56:57]
	global_load_dwordx2 v[56:57], v[6:7], off offset:360
	v_mad_i32_i24 v11, v9, s20, v11
	v_lshl_add_u64 v[6:7], v[10:11], 0, v[0:1]
	v_lshlrev_b32_e32 v0, 4, v12
	v_lshl_add_u64 v[10:11], v[6:7], 0, v[0:1]
	global_load_dwordx4 v[46:49], v[10:11], off
	global_load_dwordx4 v[34:37], v[10:11], off offset:64
	global_load_dwordx4 v[30:33], v[10:11], off offset:128
	global_load_dwordx4 v[18:21], v[10:11], off offset:192
	global_load_dwordx4 v[14:17], v[10:11], off offset:256
	global_load_dwordx4 v[6:9], v[10:11], off offset:320
	v_add_co_u32_e32 v10, vcc, s84, v10
	v_lshl_add_u64 v[72:73], v[54:55], 0, s[42:43]
	s_nop 0
	v_addc_co_u32_e32 v11, vcc, 0, v11, vcc
	global_load_dwordx4 v[50:53], v[10:11], off offset:2048
	global_load_dwordx4 v[42:45], v[10:11], off offset:2112
	global_load_dwordx4 v[38:41], v[10:11], off offset:2176
	global_load_dwordx4 v[26:29], v[10:11], off offset:2240
	global_load_dwordx4 v[22:25], v[10:11], off offset:2304
	s_nop 0
	global_load_dwordx4 v[10:13], v[10:11], off offset:2368
	s_waitcnt lgkmcnt(0)
	s_barrier
; __device__ __forceinline__ void attn_item(const Params& p, int b, int h, int qt, float shift, unsigned char* smem) {
;     ...
;   __syncthreads();
;   ATT_LOAD(0);
;   ATT_STORE(0);
;   ATT_LOAD(1);
;   __syncthreads();
;   ATT_S(sA, 0);
;   ATT_STORE(1);
;   __syncthreads();
	v_mad_i64_i32 v[68:69], s[0:1], v75, s68, v[72:73]
	v_lshl_add_u64 v[194:195], v[68:69], 0, v[66:67]
	global_load_dwordx4 v[76:79], v[194:195], off
	s_mov_b32 s0, 0x2aaaaaab
	v_mul_hi_i32 v67, v74, s0
	v_lshrrev_b32_e32 v68, 31, v67
	v_ashrrev_i32_e32 v67, 2, v67
	v_add_u32_e32 v67, v67, v68
	v_mul_lo_u32 v240, v67, s73
	v_mul_lo_u32 v67, v67, 24
	v_sub_u32_e32 v67, v74, v67
	v_lshlrev_b32_e32 v241, 4, v67
	v_add_u32_e32 v235, v240, v241
	s_movk_i32 s1, 0x3000
	v_mad_u32_u24 v0, v189, s73, v0
	s_waitcnt vmcnt(0)
	v_lshl_add_u64 v[56:57], v[56:57], 0, s[40:41]
	v_lshl_add_u64 v[192:193], v[58:59], 1, v[56:57]
	global_load_dwordx4 v[62:65], v[192:193], off
	v_add_co_u32_e32 v54, vcc, s84, v192
	s_nop 1
	v_addc_co_u32_e32 v55, vcc, 0, v193, vcc
	global_load_dwordx4 v[58:61], v[54:55], off
	v_add_co_u32_e32 v54, vcc, s70, v192
	s_nop 1
	v_addc_co_u32_e32 v55, vcc, 0, v193, vcc
	global_load_dwordx4 v[54:57], v[54:55], off
	v_add_co_u32_e32 v196, vcc, s72, v194
	s_nop 1
	v_addc_co_u32_e32 v197, vcc, 0, v195, vcc
	global_load_dwordx4 v[80:83], v[196:197], off
	s_waitcnt vmcnt(0) lgkmcnt(0)
	ds_write_b128 v235, v[62:65]
	v_add_u32_e32 v62, 0x100, v74
	v_mul_hi_i32 v63, v62, s0
	v_lshrrev_b32_e32 v64, 31, v63
	v_ashrrev_i32_e32 v63, 2, v63
	v_add_u32_e32 v63, v63, v64
	v_mul_lo_u32 v242, v63, s73
	v_mul_lo_u32 v63, v63, 24
	v_sub_u32_e32 v62, v62, v63
	v_lshlrev_b32_e32 v243, 4, v62
	v_add_u32_e32 v236, v242, v243
	ds_write_b128 v236, v[58:61]
	v_add_u32_e32 v58, 0x200, v74
	v_mul_hi_i32 v59, v58, s0
	v_lshrrev_b32_e32 v60, 31, v59
	v_ashrrev_i32_e32 v59, 2, v59
	v_add_u32_e32 v59, v59, v60
	v_mul_lo_u32 v244, v59, s73
	v_mul_lo_u32 v59, v59, 24
	v_sub_u32_e32 v58, v58, v59
	v_lshlrev_b32_e32 v245, 4, v58
	s_movk_i32 s0, 0x50
	v_add_u32_e32 v237, v244, v245
	v_mul_lo_u32 v246, v75, s0
	ds_write_b128 v237, v[54:57]
	v_add_u32_e32 v238, v66, v246
	v_add_co_u32_e32 v54, vcc, s1, v192
	ds_write_b128 v238, v[76:79] offset:13312
	ds_write_b128 v238, v[80:83] offset:18432
	v_addc_co_u32_e32 v55, vcc, 0, v193, vcc
	global_load_dwordx4 v[76:79], v[54:55], off
	v_add_co_u32_e32 v54, vcc, s69, v192
	s_movk_i32 s1, 0x5000
	s_nop 0
	v_addc_co_u32_e32 v55, vcc, 0, v193, vcc
	global_load_dwordx4 v[80:83], v[54:55], off
	v_add_co_u32_e32 v54, vcc, s1, v192
	v_and_b32_e32 v74, 3, v74
	s_nop 0
	v_addc_co_u32_e32 v55, vcc, 0, v193, vcc
	global_load_dwordx4 v[84:87], v[54:55], off
	global_load_dwordx4 v[88:91], v[194:195], off offset:64
	global_load_dwordx4 v[92:95], v[196:197], off offset:64
	s_waitcnt lgkmcnt(0)
	s_barrier
	ds_read_b128 v[54:57], v0
	ds_read_b128 v[96:99], v0 offset:64
	s_waitcnt lgkmcnt(0)
	v_mfma_f32_16x16x32_bf16 v[58:61], v[54:57], v[46:49], 0
	ds_read_b128 v[62:65], v0 offset:6656
	ds_read_b128 v[100:103], v0 offset:320
	v_mov_b32_e32 v75, 0x500
	v_mfma_f32_16x16x32_bf16 v[54:57], v[54:57], v[50:53], 0
	v_lshl_or_b32 v70, v74, 4, v70
	v_mad_u32_u24 v247, v189, s0, v75
	v_lshl_add_u64 v[70:71], v[72:73], 0, v[70:71]
	v_mfma_f32_16x16x32_bf16 v[58:61], v[96:99], v[34:37], v[58:61]
	s_mov_b64 s[0:1], 0x108080
	v_lshl_add_u64 v[198:199], v[70:71], 0, s[0:1]
	s_mov_b64 s[0:1], 0xb000
	v_mfma_f32_16x16x32_bf16 v[54:57], v[96:99], v[42:45], v[54:57]
	ds_read_b128 v[96:99], v0 offset:6720
	v_mov_b32_e32 v70, 0
	v_lshl_add_u64 v[200:201], v[192:193], 0, s[0:1]
	s_waitcnt lgkmcnt(0)
	v_mfma_f32_16x16x32_bf16 v[66:69], v[62:65], v[46:49], 0
	v_mov_b32_e32 v71, v70
	v_mov_b32_e32 v72, v70
	v_mov_b32_e32 v73, v70
	v_mfma_f32_16x16x32_bf16 v[62:65], v[62:65], v[50:53], 0
	v_mov_b32_e32 v74, v70
	v_mov_b32_e32 v75, v70
	v_mov_b32_e32 v106, v70
	v_mfma_f32_16x16x32_bf16 v[66:69], v[96:99], v[34:37], v[66:69]
	v_mov_b32_e32 v107, v70
	v_mov_b32_e32 v108, v70
	v_mov_b32_e32 v109, v70
	v_mfma_f32_16x16x32_bf16 v[62:65], v[96:99], v[42:45], v[62:65]
	ds_read_b128 v[96:99], v0 offset:128
	v_mov_b32_e32 v118, v70
	v_mov_b32_e32 v119, v70
	s_waitcnt lgkmcnt(0)
	v_mfma_f32_16x16x32_bf16 v[58:61], v[96:99], v[30:33], v[58:61]
	v_mov_b32_e32 v120, v70
	v_mov_b32_e32 v121, v70
	v_mov_b32_e32 v104, v70
	v_mfma_f32_16x16x32_bf16 v[54:57], v[96:99], v[38:41], v[54:57]
	ds_read_b128 v[96:99], v0 offset:6784
	v_mov_b32_e32 v105, v70
	v_mov_b32_e32 v110, v70
	s_waitcnt lgkmcnt(0)
	v_mfma_f32_16x16x32_bf16 v[66:69], v[96:99], v[30:33], v[66:69]
	v_mov_b32_e32 v111, v70
	v_mov_b32_e32 v112, v70
	v_mov_b32_e32 v113, v70
	v_mfma_f32_16x16x32_bf16 v[62:65], v[96:99], v[38:41], v[62:65]
	ds_read_b128 v[96:99], v0 offset:192
	v_mov_b32_e32 v114, v70
	v_mov_b32_e32 v115, v70
	s_waitcnt lgkmcnt(0)
	v_mfma_f32_16x16x32_bf16 v[58:61], v[96:99], v[18:21], v[58:61]
	v_mov_b32_e32 v116, v70
	v_mov_b32_e32 v117, v70
	v_mov_b32_e32 v122, v70
	v_mfma_f32_16x16x32_bf16 v[54:57], v[96:99], v[26:29], v[54:57]
	ds_read_b128 v[96:99], v0 offset:6848
	v_mov_b32_e32 v123, v70
	v_mov_b32_e32 v124, v70
	s_waitcnt lgkmcnt(0)
	v_mfma_f32_16x16x32_bf16 v[66:69], v[96:99], v[18:21], v[66:69]
	v_mov_b32_e32 v125, v70
	v_mov_b32_e32 v126, v70
	v_mov_b32_e32 v127, v70
	v_mfma_f32_16x16x32_bf16 v[62:65], v[96:99], v[26:29], v[62:65]
	ds_read_b128 v[96:99], v0 offset:256
	v_mov_b32_e32 v128, v70
	v_mov_b32_e32 v129, v70
	s_waitcnt lgkmcnt(0)
	v_mfma_f32_16x16x32_bf16 v[58:61], v[96:99], v[14:17], v[58:61]
	v_mov_b32_e32 v130, v70
	v_mov_b32_e32 v131, v70
	v_mov_b32_e32 v132, v70
	v_mfma_f32_16x16x32_bf16 v[54:57], v[96:99], v[22:25], v[54:57]
	ds_read_b128 v[96:99], v0 offset:6912
	v_mov_b32_e32 v133, v70
	v_mov_b32_e32 v202, v70
	s_waitcnt lgkmcnt(0)
	v_mfma_f32_16x16x32_bf16 v[66:69], v[96:99], v[14:17], v[66:69]
	v_mov_b32_e32 v203, v70
	v_mfma_f32_16x16x32_bf16 v[96:99], v[96:99], v[22:25], v[62:65]
	v_mfma_f32_16x16x32_bf16 v[62:65], v[100:103], v[6:9], v[58:61]
	s_nop 2
	ds_read_b128 v[58:61], v0 offset:6976
	v_mfma_f32_16x16x32_bf16 v[54:57], v[100:103], v[10:13], v[54:57]
	s_waitcnt vmcnt(0)
	ds_write_b128 v235, v[76:79] offset:23552
	ds_write_b128 v236, v[80:83] offset:23552
	ds_write_b128 v237, v[84:87] offset:23552
	ds_write_b128 v238, v[88:91] offset:36864
	ds_write_b128 v238, v[92:95] offset:41984
	v_mul_u32_u24_e32 v0, 0x50, v189
	v_mov_b32_e32 v76, v70
	s_waitcnt lgkmcnt(5)
	v_mfma_f32_16x16x32_bf16 v[66:69], v[58:61], v[6:9], v[66:69]
	v_mov_b32_e32 v77, v70
	v_mov_b32_e32 v78, v70
	v_mov_b32_e32 v79, v70
	v_mfma_f32_16x16x32_bf16 v[58:61], v[58:61], v[10:13], v[96:99]
	v_mov_b32_e32 v80, v70
	v_mov_b32_e32 v81, v70
	v_mov_b32_e32 v82, v70
	v_mov_b32_e32 v83, v70
	v_mov_b32_e32 v84, v70
	v_mov_b32_e32 v85, v70
	v_mov_b32_e32 v86, v70
	v_mov_b32_e32 v87, v70
	v_mov_b32_e32 v88, v70
	v_mov_b32_e32 v89, v70
	v_mov_b32_e32 v94, v70
	v_mov_b32_e32 v95, v70
	v_mov_b32_e32 v96, v70
	v_mov_b32_e32 v97, v70
	v_mov_b32_e32 v90, v70
	v_mov_b32_e32 v91, v70
	v_mov_b32_e32 v92, v70
	v_mov_b32_e32 v93, v70
	v_mov_b32_e32 v98, v70
	v_mov_b32_e32 v99, v70
	v_mov_b32_e32 v100, v70
	v_mov_b32_e32 v101, v70
	v_mov_b32_e32 v102, v70
	v_mov_b32_e32 v103, v70
	s_waitcnt lgkmcnt(0)
	s_barrier
.LBB0_780:
	s_movk_i32 s0, 0xb000
	v_add_co_u32_e32 v134, vcc, s0, v200
	s_movk_i32 s0, 0xc000
	s_nop 0
	v_addc_co_u32_e32 v135, vcc, -1, v201, vcc
	v_add_co_u32_e32 v138, vcc, s0, v200
	s_movk_i32 s0, 0xd000
	s_nop 0
	v_addc_co_u32_e32 v139, vcc, -1, v201, vcc
	v_add_co_u32_e32 v142, vcc, s0, v200
	s_mov_b32 s0, 0xffef8000
	s_nop 0
	v_addc_co_u32_e32 v143, vcc, -1, v201, vcc
	v_add_co_u32_e32 v146, vcc, s0, v198
	global_load_dwordx4 v[134:137], v[134:135], off
	s_nop 0
	global_load_dwordx4 v[138:141], v[138:139], off
	v_addc_co_u32_e32 v147, vcc, -1, v199, vcc
	global_load_dwordx4 v[142:145], v[142:143], off
	s_nop 0
	global_load_dwordx4 v[146:149], v[146:147], off
	s_nop 0
	global_load_dwordx4 v[150:153], v[198:199], off
	s_cmp_lt_u32 s47, 4
	s_cselect_b32 s0, -1, -4
	s_add_i32 s35, s0, s47
	s_mulk_i32 s35, 0x5c00
	v_or_b32_e32 v154, s35, v188
	v_add_u32_e32 v154, v154, v0
	v_add_u32_e32 v155, 0x3000, v154
	ds_read2_b64 v[170:173], v155 offset0:128 offset1:132
	v_add_u32_e32 v155, 0x3800, v154
	v_add_u32_e32 v154, 0x4000, v154
	ds_read2_b64 v[174:177], v155 offset0:32 offset1:36
	ds_read2_b64 v[178:181], v155 offset0:192 offset1:196
	ds_read2_b64 v[182:185], v154 offset0:96 offset1:100
	s_and_saveexec_b64 s[0:1], s[38:39]
	s_cbranch_execz .LBB0_782
	v_sub_f32_e32 v65, v65, v5
	v_sub_f32_e32 v64, v64, v4
	v_sub_f32_e32 v63, v63, v3
	v_sub_f32_e32 v62, v62, v2
	v_sub_f32_e32 v57, v57, v5
	v_sub_f32_e32 v56, v56, v4
	v_sub_f32_e32 v55, v55, v3
	v_sub_f32_e32 v54, v54, v2
	v_sub_f32_e32 v69, v69, v5
	v_sub_f32_e32 v68, v68, v4
	v_sub_f32_e32 v67, v67, v3
	v_sub_f32_e32 v66, v66, v2
	v_sub_f32_e32 v61, v61, v5
	v_sub_f32_e32 v60, v60, v4
	v_sub_f32_e32 v59, v59, v3
	v_sub_f32_e32 v58, v58, v2
.LBB0_782:
	s_or_b64 exec, exec, s[0:1]
	s_setprio 1
	s_mul_i32 s0, s47, 0xab
	s_bfe_u32 s1, s0, 0x70009
	s_mul_i32 s1, s1, 3
	s_sub_i32 s1, s47, s1
	s_and_b32 s34, s1, 0xff
	s_mulk_i32 s34, 0x5c00
	v_lshl_or_b32 v154, v188, 1, s34
	v_add_u32_e32 v208, v154, v239
	ds_read_b128 v[154:157], v208
	ds_read_b128 v[204:207], v208 offset:64
	ds_read_b128 v[162:165], v208 offset:6656
	v_exp_f32_e32 v212, v63
	v_exp_f32_e32 v210, v65
	v_exp_f32_e32 v213, v55
	v_exp_f32_e32 v211, v57
	v_exp_f32_e32 v65, v58
	v_exp_f32_e32 v209, v59
	s_waitcnt lgkmcnt(0)
	v_mfma_f32_16x16x32_bf16 v[158:161], v[154:157], v[46:49], 0
	v_exp_f32_e32 v63, v60
	v_cvt_pk_bf16_f32 v60, v65, v209
	v_mfma_f32_16x16x32_bf16 v[154:157], v[154:157], v[50:53], 0
	v_mfma_f32_16x16x32_bf16 v[158:161], v[204:207], v[34:37], v[158:161]
	v_mfma_f32_16x16x32_bf16 v[154:157], v[204:207], v[42:45], v[154:157]
	ds_read_b128 v[204:207], v208 offset:6720
	v_mfma_f32_16x16x32_bf16 v[166:169], v[162:165], v[46:49], 0
	v_mfma_f32_16x16x32_bf16 v[162:165], v[162:165], v[50:53], 0
	s_waitcnt lgkmcnt(0)
	v_mfma_f32_16x16x32_bf16 v[166:169], v[204:207], v[34:37], v[166:169]
	v_mfma_f32_16x16x32_bf16 v[162:165], v[204:207], v[42:45], v[162:165]
	ds_read_b128 v[204:207], v208 offset:128
	s_waitcnt lgkmcnt(0)
	v_mfma_f32_16x16x32_bf16 v[158:161], v[204:207], v[30:33], v[158:161]
	v_mfma_f32_16x16x32_bf16 v[154:157], v[204:207], v[38:41], v[154:157]
	ds_read_b128 v[204:207], v208 offset:6784
	s_waitcnt lgkmcnt(0)
	v_mfma_f32_16x16x32_bf16 v[166:169], v[204:207], v[30:33], v[166:169]
	v_mfma_f32_16x16x32_bf16 v[162:165], v[204:207], v[38:41], v[162:165]
	ds_read_b128 v[204:207], v208 offset:192
	s_waitcnt lgkmcnt(0)
	v_mfma_f32_16x16x32_bf16 v[158:161], v[204:207], v[18:21], v[158:161]
	v_mfma_f32_16x16x32_bf16 v[154:157], v[204:207], v[26:29], v[154:157]
	ds_read_b128 v[204:207], v208 offset:6848
	s_waitcnt lgkmcnt(0)
	v_mfma_f32_16x16x32_bf16 v[166:169], v[204:207], v[18:21], v[166:169]
	v_mfma_f32_16x16x32_bf16 v[162:165], v[204:207], v[26:29], v[162:165]
	ds_read_b128 v[204:207], v208 offset:256
	s_waitcnt lgkmcnt(0)
	v_mfma_f32_16x16x32_bf16 v[158:161], v[204:207], v[14:17], v[158:161]
	v_mfma_f32_16x16x32_bf16 v[154:157], v[204:207], v[22:25], v[154:157]
	ds_read_b128 v[204:207], v208 offset:6912
	s_waitcnt lgkmcnt(0)
	v_mfma_f32_16x16x32_bf16 v[166:169], v[204:207], v[14:17], v[166:169]
	v_mfma_f32_16x16x32_bf16 v[162:165], v[204:207], v[22:25], v[162:165]
	ds_read_b128 v[204:207], v208 offset:320
	s_waitcnt lgkmcnt(0)
	v_mfma_f32_16x16x32_bf16 v[158:161], v[204:207], v[6:9], v[158:161]
	v_mfma_f32_16x16x32_bf16 v[154:157], v[204:207], v[10:13], v[154:157]
	ds_read_b128 v[204:207], v208 offset:6976
	v_exp_f32_e32 v208, v67
	v_exp_f32_e32 v67, v61
	s_waitcnt lgkmcnt(0)
	v_mfma_f32_16x16x32_bf16 v[166:169], v[204:207], v[6:9], v[166:169]
	v_cvt_pk_bf16_f32 v61, v63, v67
	v_mfma_f32_16x16x32_bf16 v[162:165], v[204:207], v[10:13], v[162:165]
	v_exp_f32_e32 v206, v62
	v_exp_f32_e32 v204, v64
	v_exp_f32_e32 v64, v66
	v_exp_f32_e32 v62, v68
	v_exp_f32_e32 v66, v69
	v_exp_f32_e32 v207, v54
	v_exp_f32_e32 v205, v56
	v_add3_u32 v68, s35, v0, v188
	v_cvt_pk_bf16_f32 v54, v206, v212
	v_cvt_pk_bf16_f32 v55, v204, v210
	v_cvt_pk_bf16_f32 v56, v64, v208
	v_cvt_pk_bf16_f32 v57, v62, v66
	v_cvt_pk_bf16_f32 v58, v207, v213
	v_cvt_pk_bf16_f32 v59, v205, v211
	v_add_u32_e32 v69, 0x4800, v68
	v_mfma_f32_16x16x32_bf16 v[118:121], v[170:173], v[54:57], v[118:121]
	v_add_u32_e32 v68, 0x5000, v68
	v_mfma_f32_16x16x32_bf16 v[106:109], v[170:173], v[58:61], v[106:109]
	ds_read2_b64 v[170:173], v69 offset1:4
	v_add3_u32 v69, s35, v247, v188
	v_add_u32_e32 v69, 0x4800, v69
	v_mfma_f32_16x16x32_bf16 v[94:97], v[174:177], v[54:57], v[94:97]
	v_mfma_f32_16x16x32_bf16 v[86:89], v[174:177], v[58:61], v[86:89]
	ds_read2_b64 v[174:177], v69 offset1:4
	v_mfma_f32_16x16x32_bf16 v[82:85], v[178:181], v[54:57], v[82:85]
	v_mfma_f32_16x16x32_bf16 v[78:81], v[178:181], v[58:61], v[78:81]
	v_mfma_f32_16x16x32_bf16 v[74:77], v[182:185], v[54:57], v[74:77]
	v_mfma_f32_16x16x32_bf16 v[70:73], v[182:185], v[58:61], v[70:73]
	ds_read2_b64 v[178:181], v68 offset0:64 offset1:68
	ds_read2_b64 v[182:185], v68 offset0:224 offset1:228
	s_waitcnt lgkmcnt(0)
	v_mfma_f32_16x16x32_bf16 v[90:93], v[170:173], v[54:57], v[90:93]
	v_mfma_f32_16x16x32_bf16 v[98:101], v[170:173], v[58:61], v[98:101]
	v_mfma_f32_16x16x32_bf16 v[102:105], v[174:177], v[54:57], v[102:105]
	v_mfma_f32_16x16x32_bf16 v[110:113], v[174:177], v[58:61], v[110:113]
	v_mfma_f32_16x16x32_bf16 v[114:117], v[178:181], v[54:57], v[114:117]
	v_mfma_f32_16x16x32_bf16 v[122:125], v[178:181], v[58:61], v[122:125]
	v_mfma_f32_16x16x32_bf16 v[126:129], v[182:185], v[54:57], v[126:129]
	v_mfma_f32_16x16x32_bf16 v[130:133], v[182:185], v[58:61], v[130:133]
	s_setprio 0
	s_addk_i32 s0, 0xab
	s_bfe_u32 s0, s0, 0x70009
	s_mul_i32 s0, s0, 3
	s_sub_i32 s0, s47, s0
	s_add_i32 s0, s0, 1
	s_and_b32 s35, s0, 0xff
	s_mulk_i32 s35, 0x5c00
	v_add3_u32 v54, s35, v240, v241
	s_waitcnt vmcnt(0)
	ds_write_b128 v54, v[134:137]
	v_add3_u32 v54, s35, v242, v243
	ds_write_b128 v54, v[138:141]
	v_add3_u32 v54, s35, v244, v245
	ds_write_b128 v54, v[142:145]
	v_lshl_or_b32 v54, v191, 1, s35
	v_add_u32_e32 v54, v54, v246
	s_movk_i32 s0, 0xe000
	ds_write_b128 v54, v[146:149] offset:13312
	ds_write_b128 v54, v[150:153] offset:18432
	v_add_co_u32_e32 v54, vcc, s0, v200
	s_movk_i32 s0, 0xf000
	s_nop 0
	v_addc_co_u32_e32 v55, vcc, -1, v201, vcc
	v_add_co_u32_e32 v56, vcc, s0, v200
	s_mov_b32 s0, 0xffef8040
	s_nop 0
	v_addc_co_u32_e32 v57, vcc, -1, v201, vcc
	s_waitcnt lgkmcnt(0)
	s_barrier
	global_load_dwordx4 v[134:137], v[54:55], off
	global_load_dwordx4 v[142:145], v[56:57], off
	global_load_dwordx4 v[138:141], v[200:201], off
	v_add_co_u32_e32 v54, vcc, s0, v198
	s_nop 1
	v_addc_co_u32_e32 v55, vcc, -1, v199, vcc
	global_load_dwordx4 v[146:149], v[54:55], off
	global_load_dwordx4 v[150:153], v[198:199], off offset:64
	v_or_b32_e32 v54, s34, v188
	v_add_u32_e32 v54, v54, v0
	v_add_u32_e32 v55, 0x3000, v54
	ds_read2_b64 v[170:173], v55 offset0:128 offset1:132
	v_add_u32_e32 v55, 0x3800, v54
	v_add_u32_e32 v54, 0x4000, v54
	ds_read2_b64 v[174:177], v55 offset0:32 offset1:36
	ds_read2_b64 v[178:181], v55 offset0:192 offset1:196
	ds_read2_b64 v[182:185], v54 offset0:96 offset1:100
	s_and_saveexec_b64 s[0:1], s[38:39]
	s_cbranch_execz .LBB0_784
	v_sub_f32_e32 v161, v161, v5
	v_sub_f32_e32 v160, v160, v4
	v_sub_f32_e32 v159, v159, v3
	v_sub_f32_e32 v158, v158, v2
	v_sub_f32_e32 v157, v157, v5
	v_sub_f32_e32 v156, v156, v4
	v_sub_f32_e32 v155, v155, v3
	v_sub_f32_e32 v154, v154, v2
	v_sub_f32_e32 v169, v169, v5
	v_sub_f32_e32 v168, v168, v4
	v_sub_f32_e32 v167, v167, v3
	v_sub_f32_e32 v166, v166, v2
	v_sub_f32_e32 v165, v165, v5
	v_sub_f32_e32 v164, v164, v4
	v_sub_f32_e32 v163, v163, v3
	v_sub_f32_e32 v162, v162, v2

; __device__ __forceinline__ void attn_item(const Params& p, int b, int h, int qt, float shift, unsigned char* smem) {
;     ...
;   ATT_STEP(sB, sA, ntile - 1);
.LBB0_786:
	v_add_co_u32_e32 v134, vcc, 0x15000, v192
	v_add_u32_e32 v191, v188, v0
	s_nop 0
	v_addc_co_u32_e32 v135, vcc, 0, v193, vcc
	v_add_co_u32_e32 v138, vcc, 0x16000, v192
	v_add_u32_e32 v0, 0x3000, v191
	s_nop 0
	v_addc_co_u32_e32 v139, vcc, 0, v193, vcc
	v_add_co_u32_e32 v142, vcc, 0x17000, v192
	global_load_dwordx4 v[134:137], v[134:135], off
	s_nop 0
	global_load_dwordx4 v[138:141], v[138:139], off
	v_addc_co_u32_e32 v143, vcc, 0, v193, vcc
	global_load_dwordx4 v[142:145], v[142:143], off
	s_nop 0
	global_load_dwordx4 v[146:149], v[194:195], off offset:448
	global_load_dwordx4 v[150:153], v[196:197], off offset:448
	ds_read2_b64 v[154:157], v0 offset0:128 offset1:132
	v_add_u32_e32 v0, 0x3800, v191
	ds_read2_b64 v[158:161], v0 offset0:32 offset1:36
	ds_read2_b64 v[162:165], v0 offset0:192 offset1:196
	v_add_u32_e32 v0, 0x4000, v191
	ds_read2_b64 v[166:169], v0 offset0:96 offset1:100
	s_and_saveexec_b64 s[0:1], s[38:39]
	s_cbranch_execz .LBB0_788
	v_sub_f32_e32 v65, v65, v5
	v_sub_f32_e32 v64, v64, v4
	v_sub_f32_e32 v63, v63, v3
	v_sub_f32_e32 v62, v62, v2
	v_sub_f32_e32 v57, v57, v5
	v_sub_f32_e32 v56, v56, v4
	v_sub_f32_e32 v55, v55, v3
	v_sub_f32_e32 v54, v54, v2
	v_sub_f32_e32 v69, v69, v5
	v_sub_f32_e32 v68, v68, v4
	v_sub_f32_e32 v67, v67, v3
	v_sub_f32_e32 v66, v66, v2
	v_sub_f32_e32 v61, v61, v5
	v_sub_f32_e32 v60, v60, v4
	v_sub_f32_e32 v59, v59, v3
	v_sub_f32_e32 v58, v58, v2

; #define XCD_FOR(u, T)                                                                                         \
;   for (int _x = bid_() & 7, _gb = gridDim.x >> 3, _hi = (int)(((long)(_x + 1) * (T)) >> 3),                    \
;            u = (int)(((long)_x * (T)) >> 3) + (bid_() >> 3);                                                  \
;        u < _hi; u += _gb)
; __device__ __forceinline__ void phase_out_gemm(const Params& p, int l, bool last, const float* slat, const float* sctx, float* dlat, float* dctx, unsigned char* smem) {
;   const u16* W = p.WoutT + (size_t)l * 1024 * 1024;
;   XCD_FOR(t, 128 * 8) {
;     const int mt = t >> 3, nt = t & 7, row_base = mt * 128;
.LBB0_842:
	s_or_b64 exec, exec, s[0:1]
	s_and_b64 s[0:1], exec, s[86:87]
	s_cselect_b32 s0, 0x110, 16
	s_mov_b64 s[38:39], s[64:65]
	s_add_u32 s0, s64, s0
	s_waitcnt lgkmcnt(0)
	s_barrier
	s_addc_u32 s1, s65, 0
	v_mov_b64_e32 v[2:3], s[38:39]
	s_load_dwordx2 s[40:41], s[0:1], 0x0
	s_load_dwordx2 s[4:5], s[64:65], 0xa8
	s_load_dwordx2 s[82:83], s[64:65], 0x110
	global_load_dwordx2 v[132:133], v[2:3], off offset:216
	s_mov_b32 s0, s2
	s_and_b32 s0, s0, 7
	s_lshl_b32 s1, s0, 10
	s_addk_i32 s1, 0x400
	s_mov_b32 s8, s2
	s_lshr_b32 s18, s1, 3
	s_lshl_b32 s9, s0, 7
	s_ashr_i32 s1, s8, 3
	s_lshl_b32 s94, s36, 21
	s_add_i32 s19, s1, s9
	s_cmp_ge_i32 s19, s18
	s_waitcnt vmcnt(0) lgkmcnt(0)
	v_lshl_add_u64 v[130:131], v[132:133], 0, s[94:95]
	s_cbranch_scc1 .LBB0_851
	s_and_b64 s[34:35], exec, s[86:87]
	s_cselect_b32 s9, 0xa8, 0
	s_add_u32 s34, s64, s9
	s_addc_u32 s35, s65, 0
	s_load_dwordx2 s[42:43], s[34:35], 0x0
	s_lshr_b32 s50, s8, 3
	s_lshl_b64 s[8:9], s[36:37], 21
	s_lshl_b32 s0, s0, 11
	s_lshl_b32 s1, s1, 4
	v_lshl_add_u64 v[134:135], v[132:133], 0, s[8:9]
	s_add_i32 s51, s0, s1
	s_branch .LBB0_845

; #define XCD_FOR(u, T)                                                                                         \
;   for (int _x = bid_() & 7, _gb = gridDim.x >> 3, _hi = (int)(((long)(_x + 1) * (T)) >> 3),                    \
;            u = (int)(((long)_x * (T)) >> 3) + (bid_() >> 3);                                                  \
;        u < _hi; u += _gb)
; template <int NT, bool BKN, bool MASK = false, bool ROWSS = false, class Epi> ...
;     ...
;   float ss_[4] = {0.f, 0.f, 0.f, 0.f};
;   int stk_ = 0;
;   f32x4 acc[4][NT];
; #pragma unroll
;   for (int i = 0; i < 4; ++i)
; #pragma unroll
;     for (int j = 0; j < NT; ++j) acc[i][j] = (f32x4){0.f, 0.f, 0.f, 0.f};
;   const int nk = K >> 6;
;   const int nkm1 = nk - 1;
;   __syncthreads();
;   GEMM_LOAD(ra0, rb0, 0);
;   GEMM_LOAD(ra1, rb1, 1);
;   GEMM_STORE(ra0, rb0, 0);
;   GEMM_LOAD(ra0, rb0, (2 < nkm1 ? 2 : nkm1));
;   __syncthreads();
; __device__ __forceinline__ void phase_out_gemm(const Params& p, int l, bool last, const float* slat, const float* sctx, float* dlat, float* dctx, unsigned char* smem) {
;     ...
;   XCD_FOR(t, 128 * 8) {
;     const int mt = t >> 3, nt = t & 7, row_base = mt * 128;
;     const float* g1 = p.mada + (size_t)(l * 3 + (row_base >> 13)) * 6144 + 2 * 1024 + nt * 128;
;     const float* xs = slat + (size_t)row_base * DM;
;     float* xd = dlat + (size_t)row_base * DM;
;     auto epi = [&](f32x4(&acc)[4][4], int r0, int c0) { epi_staged_residual(acc, r0, c0, smem, g1, xs + nt * 128, xd + nt * 128); };
;     gemm_tile<4, false>(p.YM + (size_t)row_base * 1024, 1024, nullptr, 128, W + (size_t)nt * 128 * 1024, 1024, 1024, smem, epi);
.LBB0_845:
	s_nop 0
	v_mov_b64_e32 v[2:3], s[38:39]
	global_load_dwordx2 v[124:125], v[2:3], off offset:296
	global_load_dwordx2 v[136:137], v[2:3], off offset:184
	v_mov_b32_e32 v159, v187
	s_and_b32 s52, s19, 7
	s_mov_b32 s47, s95
	v_ashrrev_i32_e32 v4, 3, v159
	s_lshl_b32 s46, s52, 18
	v_lshlrev_b32_e32 v123, 4, v159
	v_ashrrev_i32_e32 v5, 31, v4
	v_lshl_add_u64 v[2:3], v[130:131], 0, s[46:47]
	v_and_b32_e32 v0, 0x70, v123
	v_lshlrev_b64 v[154:155], 11, v[4:5]
	s_mov_b64 s[46:47], 0x20000
	s_lshl_b32 s9, s19, 4
	v_lshl_add_u64 v[2:3], v[2:3], 0, v[0:1]
	v_lshl_add_u64 v[8:9], v[154:155], 0, s[46:47]
	s_mov_b64 s[46:47], 0x30000
	s_and_b32 s48, s9, 0xffffff80
	v_lshl_add_u64 v[6:7], v[154:155], 0, s[12:13]
	v_lshl_add_u64 v[22:23], v[154:155], 0, s[46:47]
	v_lshl_add_u64 v[138:139], v[2:3], 0, v[154:155]
	s_waitcnt lgkmcnt(0)
	s_barrier
	s_ashr_i32 s49, s48, 31
	v_lshl_add_u64 v[140:141], v[2:3], 0, v[6:7]
	v_lshl_add_u64 v[142:143], v[2:3], 0, v[8:9]
	v_lshl_add_u64 v[144:145], v[2:3], 0, v[22:23]
	global_load_dwordx4 v[168:171], v[138:139], off
	global_load_dwordx4 v[2:5], v[138:139], off offset:128
	global_load_dwordx4 v[172:175], v[142:143], off
	global_load_dwordx4 v[10:13], v[142:143], off offset:128
	global_load_dwordx4 v[176:179], v[140:141], off
	global_load_dwordx4 v[34:37], v[138:139], off offset:256
	global_load_dwordx4 v[14:17], v[140:141], off offset:128
	global_load_dwordx4 v[38:41], v[140:141], off offset:256
	global_load_dwordx4 v[180:183], v[144:145], off
	global_load_dwordx4 v[42:45], v[142:143], off offset:256
	global_load_dwordx4 v[18:21], v[144:145], off offset:128
	global_load_dwordx4 v[46:49], v[144:145], off offset:256
	s_lshl_b64 s[34:35], s[48:49], 11
	s_and_b32 s1, s50, 7
	s_and_b32 s0, s51, 0xffffff80
	v_and_b32_e32 v162, 15, v159
	v_bfe_u32 v160, v159, 4, 2
	v_bfe_u32 v156, v159, 1, 3
	s_lshl_b32 s94, s1, 18
	s_ashr_i32 s1, s0, 31
	v_bfe_u32 v161, v159, 6, 1
	v_ashrrev_i32_e32 v158, 7, v159
	v_lshlrev_b32_e32 v163, 7, v162
	v_and_b32_e32 v123, 0xffffff80, v123
	v_lshl_or_b32 v164, v158, 13, v163
	v_lshl_or_b32 v184, v161, 13, v163
	v_mov_b32_e32 v78, 0
	v_and_b32_e32 v204, 7, v159
	s_mov_b32 s8, -2
	v_mov_b32_e32 v79, v78
	v_mov_b32_e32 v80, v78
	v_mov_b32_e32 v81, v78
	v_mov_b32_e32 v66, v78
	v_mov_b32_e32 v67, v78
	v_mov_b32_e32 v68, v78
	v_mov_b32_e32 v69, v78
	v_mov_b32_e32 v70, v78
	v_mov_b32_e32 v71, v78
	v_mov_b32_e32 v72, v78
	v_mov_b32_e32 v73, v78
	v_mov_b32_e32 v74, v78
	v_mov_b32_e32 v75, v78
	v_mov_b32_e32 v76, v78
	v_mov_b32_e32 v77, v78
	v_mov_b32_e32 v86, v78
	v_mov_b32_e32 v87, v78
	v_mov_b32_e32 v88, v78
	v_mov_b32_e32 v89, v78
	v_mov_b32_e32 v90, v78
	v_mov_b32_e32 v91, v78
	v_mov_b32_e32 v92, v78
	v_mov_b32_e32 v93, v78
	v_mov_b32_e32 v82, v78
	v_mov_b32_e32 v83, v78
	v_mov_b32_e32 v84, v78
	v_mov_b32_e32 v85, v78
	v_mov_b32_e32 v126, v78
	v_mov_b32_e32 v127, v78
	v_mov_b32_e32 v128, v78
	v_mov_b32_e32 v129, v78
	v_mov_b32_e32 v106, v78
	v_mov_b32_e32 v107, v78
	s_waitcnt vmcnt(0)
	v_lshl_add_u64 v[24:25], v[124:125], 0, s[34:35]
	v_lshl_add_u64 v[24:25], v[24:25], 0, v[0:1]
	v_lshl_add_u64 v[146:147], v[24:25], 0, v[154:155]
	v_lshl_add_u64 v[148:149], v[24:25], 0, v[6:7]
	v_lshl_add_u64 v[150:151], v[24:25], 0, v[8:9]
	v_lshl_add_u64 v[152:153], v[24:25], 0, v[22:23]
	global_load_dwordx4 v[188:191], v[146:147], off
	global_load_dwordx4 v[192:195], v[148:149], off
	global_load_dwordx4 v[196:199], v[150:151], off
	global_load_dwordx4 v[200:203], v[152:153], off
	global_load_dwordx4 v[6:9], v[146:147], off offset:128
	global_load_dwordx4 v[22:25], v[150:151], off offset:128
	global_load_dwordx4 v[50:53], v[146:147], off offset:256
	global_load_dwordx4 v[26:29], v[148:149], off offset:128
	global_load_dwordx4 v[54:57], v[148:149], off offset:256
	global_load_dwordx4 v[58:61], v[150:151], off offset:256
	global_load_dwordx4 v[30:33], v[152:153], off offset:128
	global_load_dwordx4 v[62:65], v[152:153], off offset:256
	v_lshrrev_b32_e32 v0, 4, v159
	v_xor_b32_e32 v157, v0, v159
	v_bitop3_b32 v0, v0, v156, 3 bitop3:0x6c
	v_bitop3_b32 v156, v160, v156, 4 bitop3:0x36
	s_lshl_b64 s[34:35], s[0:1], 11
	v_lshlrev_b32_e32 v157, 4, v157
	v_lshlrev_b32_e32 v0, 4, v0
	v_lshlrev_b32_e32 v156, 4, v156
	v_and_or_b32 v167, v157, s14, v123
	v_or_b32_e32 v165, v0, v164
	v_or_b32_e32 v166, v0, v184
	v_or_b32_e32 v163, v156, v164
	v_or_b32_e32 v164, v156, v184
	v_lshl_add_u64 v[156:157], s[94:95], 0, v[154:155]
	v_lshl_add_u64 v[184:185], v[154:155], 0, s[34:35]
	v_mov_b32_e32 v108, v78
	v_mov_b32_e32 v109, v78
	v_mov_b32_e32 v114, v78
	v_mov_b32_e32 v115, v78
	v_mov_b32_e32 v116, v78
	v_mov_b32_e32 v117, v78
	v_mov_b32_e32 v118, v78
	v_mov_b32_e32 v119, v78
	v_mov_b32_e32 v120, v78
	v_mov_b32_e32 v121, v78
	v_mov_b32_e32 v98, v78
	v_mov_b32_e32 v99, v78
	v_mov_b32_e32 v100, v78
	v_mov_b32_e32 v101, v78
	v_mov_b32_e32 v94, v78
	v_mov_b32_e32 v95, v78
	v_mov_b32_e32 v96, v78
	v_mov_b32_e32 v97, v78
	v_mov_b32_e32 v102, v78
	v_mov_b32_e32 v103, v78
	v_mov_b32_e32 v104, v78
	v_mov_b32_e32 v105, v78
	v_mov_b32_e32 v110, v78
	v_mov_b32_e32 v111, v78
	v_mov_b32_e32 v112, v78
	v_mov_b32_e32 v113, v78
	v_mov_b32_e32 v122, v78
	s_lshl_b64 s[0:1], s[48:49], 10
	v_lshl_add_u64 v[154:155], v[134:135], 0, v[156:157]
	v_lshl_add_u64 v[156:157], v[124:125], 0, v[184:185]
	v_lshlrev_b32_e32 v0, 4, v204
	v_mov_b32_e32 v123, v78
	v_mov_b32_e32 v124, v78
	v_mov_b32_e32 v125, v78
	s_waitcnt lgkmcnt(0)
	ds_write_b128 v167, v[168:171] offset:16384
	ds_write_b128 v167, v[176:179] offset:20480
	ds_write_b128 v167, v[172:175] offset:24576
	ds_write_b128 v167, v[180:183] offset:28672
	s_waitcnt vmcnt(0)
	ds_write_b128 v167, v[188:191]
	ds_write_b128 v167, v[192:195] offset:4096
	ds_write_b128 v167, v[196:199] offset:8192
	ds_write_b128 v167, v[200:203] offset:12288
	s_waitcnt lgkmcnt(0)
	s_barrier
; template <int NT, bool BKN, bool MASK = false, bool ROWSS = false, class Epi> ...
;     ...
;   float ss_[4] = {0.f, 0.f, 0.f, 0.f};
;   int stk_ = 0;
;   f32x4 acc[4][NT];
; #pragma unroll
;   for (int i = 0; i < 4; ++i)
; #pragma unroll
;     for (int j = 0; j < NT; ++j) acc[i][j] = (f32x4){0.f, 0.f, 0.f, 0.f};
;   const int nk = K >> 6;
;   const int nkm1 = nk - 1;
;   __syncthreads();
;   GEMM_LOAD(ra0, rb0, 0);
;   GEMM_LOAD(ra1, rb1, 1);
;   GEMM_STORE(ra0, rb0, 0);
;   GEMM_LOAD(ra0, rb0, (2 < nkm1 ? 2 : nkm1));
;   __syncthreads();
;   for (int kt = 0; kt < nk - 2; kt += 2) {
;     GEMM_COMPUTE(0);
;     GEMM_STORE(ra1, rb1, 1);
;     GEMM_LOAD(ra1, rb1, kt + 3);
;     __syncthreads();
;     GEMM_COMPUTE(1);
;     GEMM_STORE(ra0, rb0, 0);
;     GEMM_LOAD(ra0, rb0, (kt + 4 < nkm1 ? kt + 4 : nkm1));
;     __syncthreads();
;   }
.LBB0_846:
	ds_read_b128 v[168:171], v165
	ds_read_b128 v[172:175], v166 offset:16384
	ds_read_b128 v[176:179], v165 offset:2048
	ds_read_b128 v[180:183], v166 offset:18432
	ds_read_b128 v[188:191], v166 offset:20480
	ds_read_b128 v[192:195], v166 offset:22528
	s_add_i32 s8, s8, 2
	s_waitcnt lgkmcnt(0)
	v_mfma_f32_16x16x32_bf16 v[122:125], v[168:171], v[172:175], v[122:125]
	s_min_u32 s9, s8, 11
	s_lshl_b32 s94, s9, 7
	s_cmp_lt_u32 s8, 12
	s_waitcnt lgkmcnt(2)
	v_mfma_f32_16x16x32_bf16 v[110:113], v[168:171], v[180:183], v[110:113]
	s_waitcnt lgkmcnt(1)
	v_mfma_f32_16x16x32_bf16 v[102:105], v[168:171], v[188:191], v[102:105]
	s_waitcnt lgkmcnt(0)
	v_mfma_f32_16x16x32_bf16 v[94:97], v[168:171], v[192:195], v[94:97]
	v_mfma_f32_16x16x32_bf16 v[98:101], v[176:179], v[172:175], v[98:101]
	v_mfma_f32_16x16x32_bf16 v[118:121], v[176:179], v[180:183], v[118:121]
	v_mfma_f32_16x16x32_bf16 v[114:117], v[176:179], v[188:191], v[114:117]
	v_mfma_f32_16x16x32_bf16 v[106:109], v[176:179], v[192:195], v[106:109]
	ds_read_b128 v[168:171], v165 offset:4096
	ds_read_b128 v[176:179], v165 offset:6144
	s_waitcnt lgkmcnt(0)
	v_mfma_f32_16x16x32_bf16 v[126:129], v[168:171], v[172:175], v[126:129]
	v_mfma_f32_16x16x32_bf16 v[82:85], v[168:171], v[180:183], v[82:85]
	v_mfma_f32_16x16x32_bf16 v[90:93], v[168:171], v[188:191], v[90:93]
	v_mfma_f32_16x16x32_bf16 v[86:89], v[168:171], v[192:195], v[86:89]
	s_waitcnt lgkmcnt(0)
	v_mfma_f32_16x16x32_bf16 v[74:77], v[176:179], v[172:175], v[74:77]
	v_mfma_f32_16x16x32_bf16 v[70:73], v[176:179], v[180:183], v[70:73]
	ds_read_b128 v[168:171], v163
	ds_read_b128 v[172:175], v163 offset:2048
	ds_read_b128 v[180:183], v164 offset:16384
	v_mfma_f32_16x16x32_bf16 v[66:69], v[176:179], v[188:191], v[66:69]
	v_mfma_f32_16x16x32_bf16 v[78:81], v[176:179], v[192:195], v[78:81]
	ds_read_b128 v[176:179], v163 offset:4096
	ds_read_b128 v[188:191], v163 offset:6144
	ds_read_b128 v[192:195], v164 offset:18432
	ds_read_b128 v[196:199], v164 offset:20480
	ds_read_b128 v[200:203], v164 offset:22528
	s_waitcnt vmcnt(0)
	ds_write_b128 v167, v[6:9] offset:32768
	ds_write_b128 v167, v[26:29] offset:36864
	ds_write_b128 v167, v[22:25] offset:40960
	ds_write_b128 v167, v[30:33] offset:45056
	ds_write_b128 v167, v[2:5] offset:49152
	ds_write_b128 v167, v[14:17] offset:53248
	ds_write_b128 v167, v[10:13] offset:57344
	v_lshl_add_u64 v[2:3], v[156:157], 0, v[0:1]
	v_add_co_u32_e32 v12, vcc, s15, v2
	v_lshl_add_u64 v[10:11], v[154:155], 0, v[0:1]
	s_nop 0
	v_addc_co_u32_e32 v13, vcc, 0, v3, vcc
	v_add_co_u32_e32 v14, vcc, s16, v2
	ds_write_b128 v167, v[18:21] offset:61440
	s_nop 0
	v_addc_co_u32_e32 v15, vcc, 0, v3, vcc
	v_add_co_u32_e32 v16, vcc, s17, v2
	s_waitcnt lgkmcnt(13)
	v_mfma_f32_16x16x32_bf16 v[122:125], v[168:171], v[180:183], v[122:125]
	v_addc_co_u32_e32 v17, vcc, 0, v3, vcc
	v_add_co_u32_e32 v18, vcc, s15, v10
	s_waitcnt lgkmcnt(10)
	v_mfma_f32_16x16x32_bf16 v[110:113], v[168:171], v[192:195], v[110:113]
	v_addc_co_u32_e32 v19, vcc, 0, v11, vcc
	v_add_co_u32_e32 v20, vcc, s16, v10
	s_waitcnt lgkmcnt(9)
	v_mfma_f32_16x16x32_bf16 v[102:105], v[168:171], v[196:199], v[102:105]
	v_addc_co_u32_e32 v21, vcc, 0, v11, vcc
	global_load_dwordx4 v[6:9], v[2:3], off offset:384
	s_waitcnt lgkmcnt(0)
	v_mfma_f32_16x16x32_bf16 v[94:97], v[168:171], v[200:203], v[94:97]
	v_add_co_u32_e32 v168, vcc, s17, v10
	global_load_dwordx4 v[2:5], v[10:11], off offset:384
	s_nop 0
	v_addc_co_u32_e32 v169, vcc, 0, v11, vcc
	global_load_dwordx4 v[26:29], v[12:13], off offset:384
	global_load_dwordx4 v[22:25], v[14:15], off offset:384
	global_load_dwordx4 v[30:33], v[16:17], off offset:384
	s_nop 0
	global_load_dwordx4 v[14:17], v[18:19], off offset:384
	global_load_dwordx4 v[10:13], v[20:21], off offset:384
	s_nop 0
	global_load_dwordx4 v[18:21], v[168:169], off offset:384
	s_waitcnt lgkmcnt(0)
	s_barrier
	ds_read_b128 v[168:171], v165 offset:32768
	v_mfma_f32_16x16x32_bf16 v[98:101], v[172:175], v[180:183], v[98:101]
	v_lshl_add_u64 v[154:155], v[154:155], 0, s[6:7]
	v_lshl_add_u64 v[156:157], v[156:157], 0, s[6:7]
	v_mfma_f32_16x16x32_bf16 v[118:121], v[172:175], v[192:195], v[118:121]
	v_mfma_f32_16x16x32_bf16 v[114:117], v[172:175], v[196:199], v[114:117]
	v_mfma_f32_16x16x32_bf16 v[106:109], v[172:175], v[200:203], v[106:109]
	v_mfma_f32_16x16x32_bf16 v[126:129], v[176:179], v[180:183], v[126:129]
	v_mfma_f32_16x16x32_bf16 v[82:85], v[176:179], v[192:195], v[82:85]
	v_mfma_f32_16x16x32_bf16 v[90:93], v[176:179], v[196:199], v[90:93]
	v_mfma_f32_16x16x32_bf16 v[86:89], v[176:179], v[200:203], v[86:89]
	v_mfma_f32_16x16x32_bf16 v[74:77], v[188:191], v[180:183], v[74:77]
	ds_read_b128 v[172:175], v166 offset:49152
	ds_read_b128 v[176:179], v165 offset:34816
	ds_read_b128 v[180:183], v166 offset:51200
	v_mfma_f32_16x16x32_bf16 v[70:73], v[188:191], v[192:195], v[70:73]
	v_mfma_f32_16x16x32_bf16 v[66:69], v[188:191], v[196:199], v[66:69]
	v_mfma_f32_16x16x32_bf16 v[78:81], v[188:191], v[200:203], v[78:81]
	ds_read_b128 v[188:191], v166 offset:53248
	ds_read_b128 v[192:195], v166 offset:55296
	s_waitcnt lgkmcnt(0)
	v_mfma_f32_16x16x32_bf16 v[122:125], v[168:171], v[172:175], v[122:125]
	v_mfma_f32_16x16x32_bf16 v[110:113], v[168:171], v[180:183], v[110:113]
	v_mfma_f32_16x16x32_bf16 v[102:105], v[168:171], v[188:191], v[102:105]
	v_mfma_f32_16x16x32_bf16 v[94:97], v[168:171], v[192:195], v[94:97]
	v_mfma_f32_16x16x32_bf16 v[98:101], v[176:179], v[172:175], v[98:101]
	v_mfma_f32_16x16x32_bf16 v[118:121], v[176:179], v[180:183], v[118:121]
	v_mfma_f32_16x16x32_bf16 v[114:117], v[176:179], v[188:191], v[114:117]
	v_mfma_f32_16x16x32_bf16 v[106:109], v[176:179], v[192:195], v[106:109]
	ds_read_b128 v[168:171], v165 offset:36864
	ds_read_b128 v[176:179], v165 offset:38912
	s_waitcnt lgkmcnt(0)
; template <int NT, bool BKN, bool MASK = false, bool ROWSS = false, class Epi> ...
;     ...
;   for (int kt = 0; kt < nk - 2; kt += 2) {
;     GEMM_COMPUTE(0);
;     GEMM_STORE(ra1, rb1, 1);
;     GEMM_LOAD(ra1, rb1, kt + 3);
;     __syncthreads();
;     GEMM_COMPUTE(1);
;     GEMM_STORE(ra0, rb0, 0);
;     GEMM_LOAD(ra0, rb0, (kt + 4 < nkm1 ? kt + 4 : nkm1));
;     __syncthreads();
;   }
;   GEMM_COMPUTE(0);
;   GEMM_STORE(ra1, rb1, 1);
;   __syncthreads();
;   GEMM_COMPUTE(1);
	v_mfma_f32_16x16x32_bf16 v[126:129], v[168:171], v[172:175], v[126:129]
	v_mfma_f32_16x16x32_bf16 v[82:85], v[168:171], v[180:183], v[82:85]
	v_mfma_f32_16x16x32_bf16 v[90:93], v[168:171], v[188:191], v[90:93]
	v_mfma_f32_16x16x32_bf16 v[86:89], v[168:171], v[192:195], v[86:89]
	ds_read_b128 v[168:171], v163 offset:32768
	v_mfma_f32_16x16x32_bf16 v[74:77], v[176:179], v[172:175], v[74:77]
	v_mfma_f32_16x16x32_bf16 v[70:73], v[176:179], v[180:183], v[70:73]
	v_mfma_f32_16x16x32_bf16 v[66:69], v[176:179], v[188:191], v[66:69]
	v_mfma_f32_16x16x32_bf16 v[78:81], v[176:179], v[192:195], v[78:81]
	ds_read_b128 v[172:175], v164 offset:49152
	ds_read_b128 v[176:179], v163 offset:34816
	ds_read_b128 v[180:183], v164 offset:51200
	ds_read_b128 v[188:191], v164 offset:53248
	ds_read_b128 v[192:195], v164 offset:55296
	s_waitcnt lgkmcnt(0)
	v_mfma_f32_16x16x32_bf16 v[122:125], v[168:171], v[172:175], v[122:125]
	v_mfma_f32_16x16x32_bf16 v[110:113], v[168:171], v[180:183], v[110:113]
	v_mfma_f32_16x16x32_bf16 v[102:105], v[168:171], v[188:191], v[102:105]
	v_mfma_f32_16x16x32_bf16 v[94:97], v[168:171], v[192:195], v[94:97]
	ds_read_b128 v[168:171], v163 offset:36864
	ds_read_b128 v[196:199], v163 offset:38912
	ds_write_b128 v167, v[50:53]
	ds_write_b128 v167, v[54:57] offset:4096
	ds_write_b128 v167, v[58:61] offset:8192
	ds_write_b128 v167, v[62:65] offset:12288
	ds_write_b128 v167, v[34:37] offset:16384
	ds_write_b128 v167, v[38:41] offset:20480
	ds_write_b128 v167, v[42:45] offset:24576
	ds_write_b128 v167, v[46:49] offset:28672
	v_lshl_add_u64 v[34:35], v[146:147], 0, s[94:95]
	v_lshl_add_u64 v[36:37], v[148:149], 0, s[94:95]
	v_lshl_add_u64 v[38:39], v[150:151], 0, s[94:95]
	v_lshl_add_u64 v[40:41], v[152:153], 0, s[94:95]
	v_lshl_add_u64 v[42:43], v[138:139], 0, s[94:95]
	v_lshl_add_u64 v[44:45], v[140:141], 0, s[94:95]
	v_lshl_add_u64 v[46:47], v[142:143], 0, s[94:95]
	v_lshl_add_u64 v[48:49], v[144:145], 0, s[94:95]
	global_load_dwordx4 v[50:53], v[34:35], off offset:512
	global_load_dwordx4 v[54:57], v[36:37], off offset:512
	global_load_dwordx4 v[58:61], v[38:39], off offset:512
	global_load_dwordx4 v[62:65], v[40:41], off offset:512
	s_nop 0
	global_load_dwordx4 v[34:37], v[42:43], off offset:512
	global_load_dwordx4 v[38:41], v[44:45], off offset:512
	s_nop 0
	global_load_dwordx4 v[42:45], v[46:47], off offset:512
	v_mfma_f32_16x16x32_bf16 v[98:101], v[176:179], v[172:175], v[98:101]
	global_load_dwordx4 v[46:49], v[48:49], off offset:512
	s_waitcnt lgkmcnt(0)
	s_barrier
	v_mfma_f32_16x16x32_bf16 v[118:121], v[176:179], v[180:183], v[118:121]
	v_mfma_f32_16x16x32_bf16 v[114:117], v[176:179], v[188:191], v[114:117]
	v_mfma_f32_16x16x32_bf16 v[106:109], v[176:179], v[192:195], v[106:109]
	v_mfma_f32_16x16x32_bf16 v[126:129], v[168:171], v[172:175], v[126:129]
	v_mfma_f32_16x16x32_bf16 v[82:85], v[168:171], v[180:183], v[82:85]
	v_mfma_f32_16x16x32_bf16 v[90:93], v[168:171], v[188:191], v[90:93]
	v_mfma_f32_16x16x32_bf16 v[86:89], v[168:171], v[192:195], v[86:89]
	v_mfma_f32_16x16x32_bf16 v[74:77], v[196:199], v[172:175], v[74:77]
	v_mfma_f32_16x16x32_bf16 v[70:73], v[196:199], v[180:183], v[70:73]
	v_mfma_f32_16x16x32_bf16 v[66:69], v[196:199], v[188:191], v[66:69]
	v_mfma_f32_16x16x32_bf16 v[78:81], v[196:199], v[192:195], v[78:81]
	s_cbranch_scc1 .LBB0_846
	s_waitcnt vmcnt(0)
	ds_read_b128 v[34:37], v165
	ds_read_b128 v[38:41], v166 offset:16384
	ds_read_b128 v[46:49], v166 offset:18432
	ds_read_b128 v[54:57], v166 offset:20480
	ds_read_b128 v[62:65], v166 offset:22528
	s_ashr_i32 s8, s19, 9
	s_waitcnt lgkmcnt(3)
	v_mfma_f32_16x16x32_bf16 v[42:45], v[34:37], v[38:41], v[122:125]
	s_mul_i32 s9, s36, 3
	s_add_i32 s8, s8, s9
	v_mov_b32_e32 v0, 0x6000
	s_waitcnt lgkmcnt(2)
	v_mfma_f32_16x16x32_bf16 v[50:53], v[34:37], v[46:49], v[110:113]
	s_lshl_b32 s94, s52, 9
	s_waitcnt lgkmcnt(1)
	v_mfma_f32_16x16x32_bf16 v[58:61], v[34:37], v[54:57], v[102:105]
	s_waitcnt lgkmcnt(0)
	v_mfma_f32_16x16x32_bf16 v[34:37], v[34:37], v[62:65], v[94:97]
	s_nop 2
	ds_read_b128 v[94:97], v165 offset:2048
	s_waitcnt lgkmcnt(0)
	v_mfma_f32_16x16x32_bf16 v[98:101], v[94:97], v[38:41], v[98:101]
	v_mfma_f32_16x16x32_bf16 v[102:105], v[94:97], v[46:49], v[118:121]
	v_mfma_f32_16x16x32_bf16 v[110:113], v[94:97], v[54:57], v[114:117]
	v_mfma_f32_16x16x32_bf16 v[94:97], v[94:97], v[62:65], v[106:109]
	s_nop 2
	ds_read_b128 v[106:109], v165 offset:4096
	s_waitcnt lgkmcnt(0)
	v_mfma_f32_16x16x32_bf16 v[114:117], v[106:109], v[38:41], v[126:129]
	v_mfma_f32_16x16x32_bf16 v[82:85], v[106:109], v[46:49], v[82:85]
	v_mfma_f32_16x16x32_bf16 v[90:93], v[106:109], v[54:57], v[90:93]
	v_mfma_f32_16x16x32_bf16 v[86:89], v[106:109], v[62:65], v[86:89]
	ds_read_b128 v[106:109], v165 offset:6144
	s_waitcnt lgkmcnt(0)
	v_mfma_f32_16x16x32_bf16 v[54:57], v[106:109], v[54:57], v[66:69]
	s_nop 2
	ds_read_b128 v[66:69], v163
	v_mfma_f32_16x16x32_bf16 v[38:41], v[106:109], v[38:41], v[74:77]
	v_mfma_f32_16x16x32_bf16 v[46:49], v[106:109], v[46:49], v[70:73]
	s_nop 1
	ds_read_b128 v[74:77], v164 offset:18432
	v_mfma_f32_16x16x32_bf16 v[62:65], v[106:109], v[62:65], v[78:81]
	ds_read_b128 v[70:73], v164 offset:16384
	ds_read_b128 v[106:109], v164 offset:22528
	s_nop 0
	ds_read_b128 v[78:81], v164 offset:20480
	s_waitcnt lgkmcnt(2)
	v_mfma_f32_16x16x32_bf16 v[42:45], v[66:69], v[70:73], v[42:45]
	v_mfma_f32_16x16x32_bf16 v[50:53], v[66:69], v[74:77], v[50:53]
	s_waitcnt lgkmcnt(0)
	v_mfma_f32_16x16x32_bf16 v[58:61], v[66:69], v[78:81], v[58:61]
	v_mfma_f32_16x16x32_bf16 v[34:37], v[66:69], v[106:109], v[34:37]
	ds_read_b128 v[66:69], v163 offset:2048
	s_waitcnt lgkmcnt(0)
	v_mfma_f32_16x16x32_bf16 v[98:101], v[66:69], v[70:73], v[98:101]
	v_mfma_f32_16x16x32_bf16 v[102:105], v[66:69], v[74:77], v[102:105]
	v_mfma_f32_16x16x32_bf16 v[110:113], v[66:69], v[78:81], v[110:113]
	v_mfma_f32_16x16x32_bf16 v[66:69], v[66:69], v[106:109], v[94:97]
	s_nop 2
	ds_read_b128 v[94:97], v163 offset:4096
	s_waitcnt lgkmcnt(0)
	v_mfma_f32_16x16x32_bf16 v[114:117], v[94:97], v[70:73], v[114:117]
	v_mfma_f32_16x16x32_bf16 v[82:85], v[94:97], v[74:77], v[82:85]
	v_mfma_f32_16x16x32_bf16 v[90:93], v[94:97], v[78:81], v[90:93]
	v_mfma_f32_16x16x32_bf16 v[86:89], v[94:97], v[106:109], v[86:89]
	ds_read_b128 v[94:97], v163 offset:6144
	ds_write_b128 v167, v[6:9] offset:32768
	ds_write_b128 v167, v[26:29] offset:36864
	ds_write_b128 v167, v[22:25] offset:40960
	ds_write_b128 v167, v[30:33] offset:45056
	ds_write_b128 v167, v[2:5] offset:49152
	ds_write_b128 v167, v[14:17] offset:53248
	ds_write_b128 v167, v[10:13] offset:57344
	ds_write_b128 v167, v[18:21] offset:61440
	s_waitcnt lgkmcnt(0)
	s_barrier
; __device__ __forceinline__ int tid_() { int t = threadIdx.x; asm volatile("" : "+v"(t)); return t; }
; template <int NT, bool BKN, bool MASK = false, bool ROWSS = false, class Epi> ...
;     ...
;   GEMM_COMPUTE(0);
;   GEMM_STORE(ra1, rb1, 1);
;   __syncthreads();
;   GEMM_COMPUTE(1);
; __device__ __forceinline__ void epi_staged_residual(f32x4 (&acc)[4][4], int r0, int c0, unsigned char* smem, const float* __restrict__ g,
;                                                     const float* __restrict__ xs, float* __restrict__ xd) {
;   constexpr int PITCH = 132;
;   float* Ts = (float*)smem;
;   const int t = tid_();
;   const int wr = r0 >> 6;
; #pragma unroll
;   for (int pass = 0; pass < 2; ++pass) {
;     __syncthreads();
;     if (wr == pass) {
; #pragma unroll
;       for (int mi = 0; mi < 4; ++mi)
; #pragma unroll
;         for (int ni = 0; ni < 4; ++ni)
; #pragma unroll
;           for (int j = 0; j < 4; ++j) Ts[((r0 & 63) + mi * 16 + j) * PITCH + c0 + ni * 16] = acc[mi][ni][j];
;     }
	ds_read_b128 v[2:5], v165 offset:32768
	ds_read_b128 v[10:13], v166 offset:49152
	s_waitcnt lgkmcnt(0)
	v_mfma_f32_16x16x32_bf16 v[14:17], v[2:5], v[10:13], v[42:45]
	ds_read_b128 v[18:21], v166 offset:51200
	ds_read_b128 v[26:29], v166 offset:53248
	s_nop 0
	ds_read_b128 v[42:45], v166 offset:55296
	s_waitcnt lgkmcnt(2)
	v_mfma_f32_16x16x32_bf16 v[22:25], v[2:5], v[18:21], v[50:53]
	s_waitcnt lgkmcnt(1)
	v_mfma_f32_16x16x32_bf16 v[30:33], v[2:5], v[26:29], v[58:61]
	s_waitcnt lgkmcnt(0)
	v_mfma_f32_16x16x32_bf16 v[2:5], v[2:5], v[42:45], v[34:37]
	s_nop 2
	ds_read_b128 v[34:37], v165 offset:34816
	v_mfma_f32_16x16x32_bf16 v[6:9], v[94:97], v[106:109], v[62:65]
	ds_read_b128 v[106:109], v164 offset:53248
	s_waitcnt lgkmcnt(1)
	v_mfma_f32_16x16x32_bf16 v[50:53], v[34:37], v[10:13], v[98:101]
	v_mfma_f32_16x16x32_bf16 v[58:61], v[34:37], v[18:21], v[102:105]
	v_mfma_f32_16x16x32_bf16 v[62:65], v[34:37], v[26:29], v[110:113]
	s_nop 1
	ds_read_b128 v[102:105], v164 offset:51200
	v_mfma_f32_16x16x32_bf16 v[34:37], v[34:37], v[42:45], v[66:69]
	ds_read_b128 v[110:113], v164 offset:55296
	s_nop 1
	ds_read_b128 v[66:69], v165 offset:36864
	v_mfma_f32_16x16x32_bf16 v[46:49], v[94:97], v[74:77], v[46:49]
	s_waitcnt lgkmcnt(0)
	v_mfma_f32_16x16x32_bf16 v[74:77], v[66:69], v[18:21], v[82:85]
	s_nop 2
	ds_read_b128 v[82:85], v165 offset:38912
	v_mfma_f32_16x16x32_bf16 v[54:57], v[94:97], v[78:81], v[54:57]
	v_mfma_f32_16x16x32_bf16 v[78:81], v[66:69], v[26:29], v[90:93]
	s_waitcnt lgkmcnt(0)
	v_mfma_f32_16x16x32_bf16 v[90:93], v[82:85], v[18:21], v[46:49]
	ds_read_b128 v[18:21], v163 offset:32768
	v_mfma_f32_16x16x32_bf16 v[38:41], v[94:97], v[70:73], v[38:41]
	v_mfma_f32_16x16x32_bf16 v[94:97], v[82:85], v[26:29], v[54:57]
	s_nop 2
	ds_read_b128 v[54:57], v164 offset:49152
	v_mfma_f32_16x16x32_bf16 v[70:73], v[66:69], v[10:13], v[114:117]
	v_mfma_f32_16x16x32_bf16 v[66:69], v[66:69], v[42:45], v[86:89]
	s_nop 1
	ds_read_b128 v[114:117], v163 offset:38912
	v_mfma_f32_16x16x32_bf16 v[86:89], v[82:85], v[10:13], v[38:41]
	v_mfma_f32_16x16x32_bf16 v[98:101], v[82:85], v[42:45], v[6:9]
	v_mov_b32_e32 v84, v187
	s_waitcnt lgkmcnt(1)
	v_mfma_f32_16x16x32_bf16 v[6:9], v[18:21], v[54:57], v[14:17]
	v_mfma_f32_16x16x32_bf16 v[14:17], v[18:21], v[102:105], v[22:25]
	v_mfma_f32_16x16x32_bf16 v[10:13], v[18:21], v[106:109], v[30:33]
	v_mfma_f32_16x16x32_bf16 v[18:21], v[18:21], v[110:113], v[2:5]
	s_nop 2
	ds_read_b128 v[2:5], v163 offset:34816
	s_waitcnt lgkmcnt(0)
	v_mfma_f32_16x16x32_bf16 v[26:29], v[2:5], v[54:57], v[50:53]
	s_nop 2
	ds_read_b128 v[50:53], v163 offset:36864
	v_mfma_f32_16x16x32_bf16 v[38:41], v[2:5], v[102:105], v[58:61]
	v_mfma_f32_16x16x32_bf16 v[22:25], v[2:5], v[106:109], v[62:65]
	v_mfma_f32_16x16x32_bf16 v[30:33], v[2:5], v[110:113], v[34:37]
	v_mad_i64_i32 v[2:3], s[8:9], s8, v0, v[136:137]
	v_lshlrev_b32_e32 v0, 2, v84
	v_and_b32_e32 v0, 0x7c, v0
	v_lshl_add_u64 v[2:3], v[2:3], 0, s[94:95]
	v_lshlrev_b32_e32 v0, 2, v0
	v_lshl_add_u64 v[2:3], v[2:3], 0, v[0:1]
	v_add_co_u32_e32 v2, vcc, 0x2000, v2
	s_waitcnt lgkmcnt(0)
	v_mfma_f32_16x16x32_bf16 v[34:37], v[50:53], v[54:57], v[70:73]
	v_addc_co_u32_e32 v3, vcc, 0, v3, vcc
	global_load_dwordx4 v[2:5], v[2:3], off
	v_mfma_f32_16x16x32_bf16 v[42:45], v[50:53], v[102:105], v[74:77]
	s_movk_i32 s8, 0x80
	v_cmp_gt_u32_e32 vcc, s8, v159
	s_waitcnt lgkmcnt(0)
	v_mfma_f32_16x16x32_bf16 v[46:49], v[50:53], v[106:109], v[78:81]
	s_barrier
	v_mfma_f32_16x16x32_bf16 v[50:53], v[50:53], v[110:113], v[66:69]
	s_nop 2
	v_mul_u32_u24_e32 v66, 0x210, v160
	v_mfma_f32_16x16x32_bf16 v[54:57], v[114:117], v[54:57], v[86:89]
	v_mfma_f32_16x16x32_bf16 v[58:61], v[114:117], v[102:105], v[90:93]
	s_nop 1
	v_lshlrev_b32_e32 v87, 2, v66
	v_lshl_or_b32 v86, v161, 6, v162
	v_mfma_f32_16x16x32_bf16 v[62:65], v[114:117], v[106:109], v[94:97]
	v_mfma_f32_16x16x32_bf16 v[66:69], v[114:117], v[110:113], v[98:101]
	s_and_saveexec_b64 s[8:9], vcc
	s_cbranch_execz .LBB0_849
	v_lshl_add_u32 v70, v86, 2, v87
	v_add_u32_e32 v71, 0x400, v70
	ds_write2_b32 v70, v6, v14 offset1:16
	ds_write2_b32 v70, v7, v15 offset0:132 offset1:148
	ds_write2_b32 v71, v8, v16 offset0:8 offset1:24
	ds_write2_b32 v71, v9, v17 offset0:140 offset1:156
	ds_write2_b32 v70, v10, v18 offset0:32 offset1:48
	ds_write2_b32 v70, v11, v19 offset0:164 offset1:180
	ds_write2_b32 v71, v12, v20 offset0:40 offset1:56
	ds_write2_b32 v71, v13, v21 offset0:172 offset1:188
	v_add_u32_e32 v71, 0x2000, v70
	v_add_u32_e32 v72, 0x2400, v70
	ds_write2_b32 v71, v26, v38 offset0:64 offset1:80
	ds_write2_b32 v71, v27, v39 offset0:196 offset1:212
	ds_write2_b32 v72, v28, v40 offset0:72 offset1:88
	ds_write2_b32 v72, v29, v41 offset0:204 offset1:220
	ds_write2_b32 v71, v22, v30 offset0:96 offset1:112
	ds_write2_b32 v71, v23, v31 offset0:228 offset1:244
	ds_write2_b32 v72, v24, v32 offset0:104 offset1:120
	ds_write2_b32 v72, v25, v33 offset0:236 offset1:252
	v_add_u32_e32 v71, 0x4000, v70
	v_add_u32_e32 v72, 0x4400, v70
	v_add_u32_e32 v73, 0x4800, v70
	ds_write2_b32 v71, v34, v42 offset0:128 offset1:144
	ds_write2_b32 v72, v35, v43 offset0:4 offset1:20
	ds_write2_b32 v72, v36, v44 offset0:136 offset1:152
	ds_write2_b32 v73, v37, v45 offset0:12 offset1:28
	ds_write2_b32 v71, v46, v50 offset0:160 offset1:176
	ds_write2_b32 v72, v47, v51 offset0:36 offset1:52
	ds_write2_b32 v72, v48, v52 offset0:168 offset1:184
	ds_write2_b32 v73, v49, v53 offset0:44 offset1:60
	v_add_u32_e32 v71, 0x6000, v70
	v_add_u32_e32 v72, 0x6400, v70
	v_add_u32_e32 v70, 0x6800, v70
	ds_write2_b32 v71, v54, v58 offset0:192 offset1:208
	ds_write2_b32 v72, v55, v59 offset0:68 offset1:84
	ds_write2_b32 v72, v56, v60 offset0:200 offset1:216
	ds_write2_b32 v70, v57, v61 offset0:76 offset1:92
	ds_write2_b32 v71, v62, v66 offset0:224 offset1:240
	ds_write2_b32 v72, v63, v67 offset0:100 offset1:116
	ds_write2_b32 v72, v64, v68 offset0:232 offset1:248
	ds_write2_b32 v70, v65, v69 offset0:108 offset1:124

; #define XCD_FOR(u, T)                                                                                         \
;   for (int _x = bid_() & 7, _gb = gridDim.x >> 3, _hi = (int)(((long)(_x + 1) * (T)) >> 3),                    \
;            u = (int)(((long)_x * (T)) >> 3) + (bid_() >> 3);                                                  \
;        u < _hi; u += _gb)
; template <int NT, bool BKN, bool MASK = false, bool ROWSS = false, class Epi> ...
;     ...
;   float ss_[4] = {0.f, 0.f, 0.f, 0.f};
;   int stk_ = 0;
;   f32x4 acc[4][NT];
; #pragma unroll
;   for (int i = 0; i < 4; ++i)
; #pragma unroll
;     for (int j = 0; j < NT; ++j) acc[i][j] = (f32x4){0.f, 0.f, 0.f, 0.f};
;   const int nk = K >> 6;
;   const int nkm1 = nk - 1;
;   __syncthreads();
;   GEMM_LOAD(ra0, rb0, 0);
;   GEMM_LOAD(ra1, rb1, 1);
;   GEMM_STORE(ra0, rb0, 0);
;   GEMM_LOAD(ra0, rb0, (2 < nkm1 ? 2 : nkm1));
;   __syncthreads();
;   for (int kt = 0; kt < nk - 2; kt += 2) {
;     GEMM_COMPUTE(0);
;     GEMM_STORE(ra1, rb1, 1);
;     GEMM_LOAD(ra1, rb1, kt + 3);
;     __syncthreads();
;     GEMM_COMPUTE(1);
;     GEMM_STORE(ra0, rb0, 0);
;     GEMM_LOAD(ra0, rb0, (kt + 4 < nkm1 ? kt + 4 : nkm1));
;     __syncthreads();
;   }
; __device__ __forceinline__ void phase_out_gemm(const Params& p, int l, bool last, const float* slat, const float* sctx, float* dlat, float* dctx, unsigned char* smem) {
;     ...
;   if (!last) {
;     XCD_FOR(t, 4 * 32) {
;       const int mt = t >> 5, nt = t & 31, row_base = mt * 128;
;       const float* g1 = p.mada + (size_t)(l * 3 + 2) * 6144 + 2 * 1024 + nt * 32;
;       const float* xs = sctx + (size_t)row_base * DM;
;       float* xd = dctx + (size_t)row_base * DM;
;       auto epi = [&](f32x4(&acc)[4][1], int r0, int c0) {
; #pragma unroll
;         for (int mi = 0; mi < 4; ++mi) {
;           const float g = g1[c0];
; #pragma unroll
;           for (int j = 0; j < 4; ++j) {
;             const size_t o = (size_t)(r0 + mi * 16 + j) * DM + nt * 32 + c0;
;             xd[o] = xs[o] + g * acc[mi][0][j];
;           }
;         }
;       };
;       gemm_tile<1, false>(p.YM + (size_t)(T_LAT + row_base) * 1024, 1024, nullptr, 128, W + (size_t)nt * 32 * 1024, 1024, 1024, smem, epi);
.LBB0_854:
	v_mov_b64_e32 v[2:3], s[38:39]
	global_load_dwordx2 v[60:61], v[2:3], off offset:184
	global_load_dwordx2 v[42:43], v[2:3], off offset:296
	s_lshl_b32 s34, s9, 2
	s_and_b32 s44, s34, 0xffffff80
	s_ashr_i32 s45, s44, 31
	v_mov_b32_e32 v46, v187
	s_lshl_b64 s[34:35], s[44:45], 11
	s_and_b32 s37, s9, 31
	v_ashrrev_i32_e32 v6, 3, v46
	v_lshlrev_b32_e32 v48, 4, v46
	v_and_b32_e32 v0, 0x70, v48
	v_ashrrev_i32_e32 v7, 31, v6
	v_lshlrev_b64 v[44:45], 11, v[6:7]
	s_waitcnt lgkmcnt(0)
	s_barrier
	v_lshrrev_b32_e32 v47, 4, v46
	v_and_b32_e32 v48, 0xffffff80, v48
	s_and_b32 s0, s18, 31
	s_lshl_b32 s94, s0, 16
	s_and_b32 s0, s19, 0xffffff80
	s_addk_i32 s0, 0x4000
	v_and_b32_e32 v77, 15, v46
	v_bfe_u32 v79, v46, 4, 2
	s_ashr_i32 s1, s0, 31
	v_bfe_u32 v76, v46, 6, 1
	v_ashrrev_i32_e32 v78, 7, v46
	s_lshl_b64 s[0:1], s[0:1], 11
	s_waitcnt vmcnt(0)
	v_lshl_add_u64 v[2:3], v[42:43], 0, s[34:35]
	s_lshl_b32 s34, s37, 16
	s_mov_b32 s35, s95
	v_lshl_add_u64 v[2:3], v[2:3], 0, v[0:1]
	v_lshl_add_u64 v[4:5], v[130:131], 0, s[34:35]
	v_lshl_add_u64 v[2:3], v[2:3], 0, v[44:45]
	s_mov_b64 s[34:35], 0x2000000
	v_lshl_add_u64 v[62:63], v[2:3], 0, s[34:35]
	s_mov_b64 s[34:35], 0x2010000
	v_lshl_add_u64 v[64:65], v[2:3], 0, s[34:35]
	s_mov_b64 s[34:35], 0x2020000
	v_lshl_add_u64 v[66:67], v[2:3], 0, s[34:35]
	s_mov_b64 s[34:35], 0x2030000
	v_lshl_add_u64 v[68:69], v[2:3], 0, s[34:35]
	s_brev_b32 s34, 64
	v_add_co_u32_e32 v6, vcc, s34, v2
	s_mov_b32 s34, 0x2010000
	s_nop 0
	v_addc_co_u32_e32 v7, vcc, 0, v3, vcc
	global_load_dwordx4 v[22:25], v[6:7], off
	v_add_co_u32_e32 v6, vcc, s34, v2
	s_mov_b32 s34, 0x2020000
	s_nop 0
	v_addc_co_u32_e32 v7, vcc, 0, v3, vcc
	global_load_dwordx4 v[26:29], v[6:7], off
	v_add_co_u32_e32 v6, vcc, s34, v2
	s_mov_b32 s34, 0x2030000
	s_nop 0
	v_addc_co_u32_e32 v7, vcc, 0, v3, vcc
	v_add_co_u32_e32 v2, vcc, s34, v2
	global_load_dwordx4 v[30:33], v[6:7], off
	s_nop 0
	v_addc_co_u32_e32 v3, vcc, 0, v3, vcc
	v_lshl_add_u64 v[4:5], v[4:5], 0, v[44:45]
	global_load_dwordx4 v[34:37], v[2:3], off
	v_lshl_add_u64 v[70:71], v[4:5], 0, v[0:1]
	global_load_dwordx4 v[38:41], v[70:71], off
	global_load_dwordx4 v[2:5], v[62:63], off offset:128
	global_load_dwordx4 v[6:9], v[64:65], off offset:128
	global_load_dwordx4 v[10:13], v[66:67], off offset:128
	global_load_dwordx4 v[14:17], v[68:69], off offset:128
	global_load_dwordx4 v[18:21], v[70:71], off offset:128
	v_xor_b32_e32 v0, v47, v46
	v_lshlrev_b32_e32 v0, 4, v0
	v_and_or_b32 v80, v0, s14, v48
	v_bfe_u32 v0, v46, 1, 3
	v_lshlrev_b32_e32 v48, 7, v77
	v_bitop3_b32 v47, v47, v0, 3 bitop3:0x6c
	v_bitop3_b32 v0, v79, v0, 4 bitop3:0x36
	v_lshl_or_b32 v49, v76, 11, v48
	v_lshlrev_b32_e32 v47, 4, v47
	v_lshl_or_b32 v48, v78, 13, v48
	v_lshlrev_b32_e32 v0, 4, v0
	v_or_b32_e32 v83, v47, v48
	v_or_b32_e32 v84, v49, v47
	v_or_b32_e32 v81, v0, v48
	v_or_b32_e32 v82, v49, v0
	v_and_b32_e32 v0, 7, v46
	v_lshl_add_u64 v[46:47], s[94:95], 0, v[44:45]
	v_lshl_add_u64 v[44:45], v[44:45], 0, s[0:1]
	v_lshl_add_u64 v[74:75], v[42:43], 0, v[44:45]
	v_mov_b32_e32 v42, 0
	v_lshlrev_b32_e32 v0, 4, v0
	v_lshl_add_u64 v[72:73], v[58:59], 0, v[46:47]
	s_mov_b32 s0, -2
	v_mov_b32_e32 v43, v42
	v_mov_b32_e32 v44, v42
	v_mov_b32_e32 v45, v42
	v_mov_b32_e32 v46, v42
	v_mov_b32_e32 v47, v42
	v_mov_b32_e32 v48, v42
	v_mov_b32_e32 v49, v42
	v_mov_b32_e32 v50, v42
	v_mov_b32_e32 v51, v42
	v_mov_b32_e32 v52, v42
	v_mov_b32_e32 v53, v42
	v_mov_b32_e32 v54, v42
	v_mov_b32_e32 v55, v42
	v_mov_b32_e32 v56, v42
	v_mov_b32_e32 v57, v42
	s_waitcnt vmcnt(0) lgkmcnt(0)
	ds_write_b128 v80, v[22:25]
	ds_write_b128 v80, v[26:29] offset:4096
	ds_write_b128 v80, v[30:33] offset:8192
	ds_write_b128 v80, v[34:37] offset:12288
	ds_write_b128 v80, v[38:41] offset:16384
	global_load_dwordx4 v[22:25], v[62:63], off offset:256
	global_load_dwordx4 v[26:29], v[64:65], off offset:256
	global_load_dwordx4 v[30:33], v[66:67], off offset:256
	global_load_dwordx4 v[34:37], v[68:69], off offset:256
	global_load_dwordx4 v[38:41], v[70:71], off offset:256
	s_waitcnt lgkmcnt(0)
	s_barrier
.LBB0_855:
	ds_read_b128 v[86:89], v83
	ds_read_b128 v[90:93], v83 offset:2048
	ds_read_b128 v[94:97], v83 offset:4096
	ds_read_b128 v[98:101], v83 offset:6144
	ds_read_b128 v[102:105], v84 offset:16384
	s_add_i32 s0, s0, 2
	s_min_u32 s1, s0, 11
	s_lshl_b32 s94, s1, 7
	s_cmp_lt_u32 s0, 12
	s_waitcnt lgkmcnt(0)
	v_mfma_f32_16x16x32_bf16 v[42:45], v[86:89], v[102:105], v[42:45]
	v_mfma_f32_16x16x32_bf16 v[46:49], v[90:93], v[102:105], v[46:49]
	v_mfma_f32_16x16x32_bf16 v[50:53], v[94:97], v[102:105], v[50:53]
	v_mfma_f32_16x16x32_bf16 v[54:57], v[98:101], v[102:105], v[54:57]
	ds_read_b128 v[86:89], v81
	ds_read_b128 v[90:93], v81 offset:2048
	ds_read_b128 v[94:97], v81 offset:4096
	ds_read_b128 v[98:101], v81 offset:6144
	ds_read_b128 v[102:105], v82 offset:16384
	ds_write_b128 v80, v[2:5] offset:32768
	ds_write_b128 v80, v[6:9] offset:36864
	ds_write_b128 v80, v[10:13] offset:40960
	ds_write_b128 v80, v[14:17] offset:45056
	ds_write_b128 v80, v[18:21] offset:49152
	v_lshl_add_u64 v[14:15], v[74:75], 0, v[0:1]
	v_add_co_u32_e32 v6, vcc, s15, v14
	global_load_dwordx4 v[2:5], v[14:15], off offset:384
	s_nop 0
	v_addc_co_u32_e32 v7, vcc, 0, v15, vcc
	v_add_co_u32_e32 v10, vcc, s16, v14
	v_lshl_add_u64 v[18:19], v[72:73], 0, v[0:1]
	s_nop 0
	v_addc_co_u32_e32 v11, vcc, 0, v15, vcc
	v_add_co_u32_e32 v14, vcc, s17, v14
	s_waitcnt lgkmcnt(0)
	v_mfma_f32_16x16x32_bf16 v[42:45], v[86:89], v[102:105], v[42:45]
	v_addc_co_u32_e32 v15, vcc, 0, v15, vcc
	global_load_dwordx4 v[6:9], v[6:7], off offset:384
	v_mfma_f32_16x16x32_bf16 v[46:49], v[90:93], v[102:105], v[46:49]
	global_load_dwordx4 v[10:13], v[10:11], off offset:384
	v_lshl_add_u64 v[72:73], v[72:73], 0, s[6:7]
	global_load_dwordx4 v[14:17], v[14:15], off offset:384
	v_mfma_f32_16x16x32_bf16 v[50:53], v[94:97], v[102:105], v[50:53]
	global_load_dwordx4 v[18:21], v[18:19], off
	s_waitcnt lgkmcnt(0)
	s_barrier
; template <int NT, bool BKN, bool MASK = false, bool ROWSS = false, class Epi> ...
;     ...
;   for (int kt = 0; kt < nk - 2; kt += 2) {
;     GEMM_COMPUTE(0);
;     GEMM_STORE(ra1, rb1, 1);
;     GEMM_LOAD(ra1, rb1, kt + 3);
;     __syncthreads();
;     GEMM_COMPUTE(1);
;     GEMM_STORE(ra0, rb0, 0);
;     GEMM_LOAD(ra0, rb0, (kt + 4 < nkm1 ? kt + 4 : nkm1));
;     __syncthreads();
;   }
;   GEMM_COMPUTE(0);
;   GEMM_STORE(ra1, rb1, 1);
;   __syncthreads();
;   GEMM_COMPUTE(1);
; __device__ __forceinline__ void phase_out_gemm(const Params& p, int l, bool last, const float* slat, const float* sctx, float* dlat, float* dctx, unsigned char* smem) {
;     ...
;       auto epi = [&](f32x4(&acc)[4][1], int r0, int c0) {
; #pragma unroll
;         for (int mi = 0; mi < 4; ++mi) {
;           const float g = g1[c0];
; #pragma unroll
;           for (int j = 0; j < 4; ++j) {
;             const size_t o = (size_t)(r0 + mi * 16 + j) * DM + nt * 32 + c0;
;             xd[o] = xs[o] + g * acc[mi][0][j];
;           }
;         }
	v_mfma_f32_16x16x32_bf16 v[54:57], v[98:101], v[102:105], v[54:57]
	ds_read_b128 v[86:89], v83 offset:32768
	ds_read_b128 v[90:93], v83 offset:34816
	ds_read_b128 v[94:97], v83 offset:36864
	ds_read_b128 v[98:101], v83 offset:38912
	ds_read_b128 v[102:105], v84 offset:49152
	v_lshl_add_u64 v[74:75], v[74:75], 0, s[6:7]
	s_waitcnt lgkmcnt(0)
	v_mfma_f32_16x16x32_bf16 v[42:45], v[86:89], v[102:105], v[42:45]
	v_mfma_f32_16x16x32_bf16 v[46:49], v[90:93], v[102:105], v[46:49]
	v_mfma_f32_16x16x32_bf16 v[50:53], v[94:97], v[102:105], v[50:53]
	v_mfma_f32_16x16x32_bf16 v[54:57], v[98:101], v[102:105], v[54:57]
	ds_read_b128 v[86:89], v81 offset:32768
	ds_read_b128 v[90:93], v81 offset:34816
	ds_read_b128 v[94:97], v81 offset:36864
	ds_read_b128 v[98:101], v81 offset:38912
	ds_read_b128 v[102:105], v82 offset:49152
	s_waitcnt vmcnt(0)
	ds_write_b128 v80, v[22:25]
	ds_write_b128 v80, v[26:29] offset:4096
	ds_write_b128 v80, v[30:33] offset:8192
	ds_write_b128 v80, v[34:37] offset:12288
	ds_write_b128 v80, v[38:41] offset:16384
	v_lshl_add_u64 v[22:23], v[62:63], 0, s[94:95]
	v_lshl_add_u64 v[26:27], v[64:65], 0, s[94:95]
	v_lshl_add_u64 v[30:31], v[66:67], 0, s[94:95]
	v_lshl_add_u64 v[34:35], v[68:69], 0, s[94:95]
	v_lshl_add_u64 v[38:39], v[70:71], 0, s[94:95]
	global_load_dwordx4 v[22:25], v[22:23], off offset:512
	s_waitcnt lgkmcnt(0)
	v_mfma_f32_16x16x32_bf16 v[42:45], v[86:89], v[102:105], v[42:45]
	global_load_dwordx4 v[26:29], v[26:27], off offset:512
	s_nop 0
	global_load_dwordx4 v[30:33], v[30:31], off offset:512
	v_mfma_f32_16x16x32_bf16 v[46:49], v[90:93], v[102:105], v[46:49]
	global_load_dwordx4 v[34:37], v[34:35], off offset:512
	s_nop 0
	global_load_dwordx4 v[38:41], v[38:39], off offset:512
	v_mfma_f32_16x16x32_bf16 v[50:53], v[94:97], v[102:105], v[50:53]
	s_waitcnt lgkmcnt(0)
	s_barrier
	v_mfma_f32_16x16x32_bf16 v[54:57], v[98:101], v[102:105], v[54:57]
	s_cbranch_scc1 .LBB0_855
	s_lshl_b64 s[0:1], s[44:45], 12
	s_add_u32 s44, s40, s0
	s_waitcnt vmcnt(0)
	v_lshl_add_u64 v[22:23], s[42:43], 2, v[60:61]
	s_addc_u32 s45, s41, s1
	s_lshl_b32 s94, s37, 7
	v_lshl_add_u64 v[60:61], v[22:23], 0, s[94:95]
	ds_read_b128 v[22:25], v83
	ds_read_b128 v[26:29], v83 offset:2048
	ds_read_b128 v[30:33], v83 offset:4096
	ds_read_b128 v[34:37], v83 offset:6144
	ds_read_b128 v[38:41], v84 offset:16384
	v_lshlrev_b32_e32 v0, 6, v78
	s_waitcnt lgkmcnt(0)
	v_mfma_f32_16x16x32_bf16 v[22:25], v[22:25], v[38:41], v[42:45]
	s_mov_b32 s34, 0xe000
	s_add_u32 s0, s82, s0
	s_addc_u32 s1, s83, s1
	v_mfma_f32_16x16x32_bf16 v[26:29], v[26:29], v[38:41], v[46:49]
	s_add_i32 s9, s9, s3
	s_add_i32 s18, s18, s3
	v_mfma_f32_16x16x32_bf16 v[30:33], v[30:33], v[38:41], v[50:53]
	v_mfma_f32_16x16x32_bf16 v[34:37], v[34:37], v[38:41], v[54:57]
	ds_read_b128 v[38:41], v81
	ds_read_b128 v[42:45], v81 offset:2048
	ds_read_b128 v[46:49], v81 offset:4096
	ds_read_b128 v[50:53], v81 offset:6144
	ds_read_b128 v[54:57], v82 offset:16384
	ds_write_b128 v80, v[2:5] offset:32768
	ds_write_b128 v80, v[6:9] offset:36864
	ds_write_b128 v80, v[10:13] offset:40960
	ds_write_b128 v80, v[14:17] offset:45056
	ds_write_b128 v80, v[18:21] offset:49152
	s_waitcnt lgkmcnt(0)
	s_barrier
	ds_read_b128 v[2:5], v83 offset:32768
	ds_read_b128 v[6:9], v83 offset:34816
	ds_read_b128 v[10:13], v83 offset:36864
	ds_read_b128 v[14:17], v83 offset:38912
	ds_read_b128 v[18:21], v84 offset:49152
	v_mfma_f32_16x16x32_bf16 v[22:25], v[38:41], v[54:57], v[22:25]
	v_mfma_f32_16x16x32_bf16 v[26:29], v[42:45], v[54:57], v[26:29]
	v_mfma_f32_16x16x32_bf16 v[30:33], v[46:49], v[54:57], v[30:33]
	v_mfma_f32_16x16x32_bf16 v[34:37], v[50:53], v[54:57], v[34:37]
	s_waitcnt lgkmcnt(0)
	v_mfma_f32_16x16x32_bf16 v[2:5], v[2:5], v[18:21], v[22:25]
	v_mfma_f32_16x16x32_bf16 v[6:9], v[6:9], v[18:21], v[26:29]
	v_mfma_f32_16x16x32_bf16 v[22:25], v[10:13], v[18:21], v[30:33]
	v_mfma_f32_16x16x32_bf16 v[18:21], v[14:17], v[18:21], v[34:37]
	ds_read_b128 v[10:13], v81 offset:32768
	ds_read_b128 v[26:29], v81 offset:34816
	ds_read_b128 v[30:33], v81 offset:36864
	ds_read_b128 v[34:37], v81 offset:38912
	ds_read_b128 v[38:41], v82 offset:49152
	s_waitcnt lgkmcnt(0)
	v_mfma_f32_16x16x32_bf16 v[14:17], v[10:13], v[38:41], v[2:5]
	v_mfma_f32_16x16x32_bf16 v[2:5], v[34:37], v[38:41], v[18:21]
	s_nop 2
	v_lshl_or_b32 v18, v79, 2, v0
	v_lshlrev_b32_e32 v0, 2, v77
	v_lshl_or_b32 v0, v76, 6, v0
	v_ashrrev_i32_e32 v19, 31, v18
	v_mfma_f32_16x16x32_bf16 v[10:13], v[26:29], v[38:41], v[6:9]
	v_lshl_add_u64 v[20:21], v[60:61], 0, v[0:1]
	v_or_b32_e32 v0, s94, v0
	v_add_co_u32_e32 v20, vcc, s34, v20
	v_mfma_f32_16x16x32_bf16 v[6:9], v[30:33], v[38:41], v[22:25]
	s_nop 0
	v_addc_co_u32_e32 v21, vcc, 0, v21, vcc
	global_load_dword v26, v[20:21], off
	v_lshlrev_b64 v[22:23], 12, v[18:19]
	v_or_b32_e32 v22, v22, v0
	v_lshl_add_u64 v[24:25], s[44:45], 0, v[22:23]
	global_load_dword v19, v[24:25], off
	v_lshl_add_u64 v[22:23], s[0:1], 0, v[22:23]
	s_waitcnt vmcnt(0) lgkmcnt(0)
	v_fmac_f32_e32 v19, v14, v26
	global_store_dword v[22:23], v19, off
	v_or_b32_e32 v22, 1, v18
	v_ashrrev_i32_e32 v23, 31, v22
	v_lshlrev_b64 v[22:23], 12, v[22:23]
	v_or_b32_e32 v22, v22, v0
	v_lshl_add_u64 v[24:25], s[44:45], 0, v[22:23]
	global_load_dword v19, v[24:25], off
	s_waitcnt vmcnt(0)
; __device__ __forceinline__ void phase_out_gemm(const Params& p, int l, bool last, const float* slat, const float* sctx, float* dlat, float* dctx, unsigned char* smem) {
;     ...
;       auto epi = [&](f32x4(&acc)[4][1], int r0, int c0) {
; #pragma unroll
;         for (int mi = 0; mi < 4; ++mi) {
;           const float g = g1[c0];
; #pragma unroll
;           for (int j = 0; j < 4; ++j) {
;             const size_t o = (size_t)(r0 + mi * 16 + j) * DM + nt * 32 + c0;
;             xd[o] = xs[o] + g * acc[mi][0][j];
;           }
;         }
	v_fmac_f32_e32 v19, v15, v26
	v_lshl_add_u64 v[14:15], s[0:1], 0, v[22:23]
	global_store_dword v[14:15], v19, off
	v_or_b32_e32 v14, 2, v18
	v_ashrrev_i32_e32 v15, 31, v14
	v_lshlrev_b64 v[14:15], 12, v[14:15]
	v_or_b32_e32 v14, v14, v0
	v_lshl_add_u64 v[22:23], s[44:45], 0, v[14:15]
	global_load_dword v19, v[22:23], off
	v_lshl_add_u64 v[14:15], s[0:1], 0, v[14:15]
	s_waitcnt vmcnt(0)
	v_fmac_f32_e32 v19, v16, v26
	global_store_dword v[14:15], v19, off
	v_or_b32_e32 v14, 3, v18
	v_ashrrev_i32_e32 v15, 31, v14
	v_lshlrev_b64 v[14:15], 12, v[14:15]
	v_or_b32_e32 v14, v14, v0
	v_lshl_add_u64 v[22:23], s[44:45], 0, v[14:15]
	global_load_dword v16, v[22:23], off
	v_lshl_add_u64 v[14:15], s[0:1], 0, v[14:15]
	s_waitcnt vmcnt(0)
	v_fmac_f32_e32 v16, v17, v26
	global_store_dword v[14:15], v16, off
	v_or_b32_e32 v14, 16, v18
	v_ashrrev_i32_e32 v15, 31, v14
	v_lshlrev_b64 v[14:15], 12, v[14:15]
	v_or_b32_e32 v14, v14, v0
	v_lshl_add_u64 v[16:17], s[44:45], 0, v[14:15]
	global_load_dword v19, v[20:21], off
	v_lshl_add_u64 v[14:15], s[0:1], 0, v[14:15]
	global_load_dword v16, v[16:17], off
	s_waitcnt vmcnt(0) lgkmcnt(0)
	v_fmac_f32_e32 v16, v10, v19
	global_store_dword v[14:15], v16, off
	v_or_b32_e32 v14, 17, v18
	v_ashrrev_i32_e32 v15, 31, v14
	v_lshlrev_b64 v[14:15], 12, v[14:15]
	v_or_b32_e32 v14, v14, v0
	v_lshl_add_u64 v[16:17], s[44:45], 0, v[14:15]
	global_load_dword v16, v[16:17], off
	s_waitcnt vmcnt(0)
	v_fmac_f32_e32 v16, v11, v19
	v_lshl_add_u64 v[10:11], s[0:1], 0, v[14:15]
	global_store_dword v[10:11], v16, off
	v_or_b32_e32 v10, 18, v18
	v_ashrrev_i32_e32 v11, 31, v10
	v_lshlrev_b64 v[10:11], 12, v[10:11]
	v_or_b32_e32 v10, v10, v0
	v_lshl_add_u64 v[14:15], s[44:45], 0, v[10:11]
	global_load_dword v14, v[14:15], off
	v_lshl_add_u64 v[10:11], s[0:1], 0, v[10:11]
	s_waitcnt vmcnt(0)
	v_fmac_f32_e32 v14, v12, v19
	global_store_dword v[10:11], v14, off
	v_or_b32_e32 v10, 19, v18
	v_ashrrev_i32_e32 v11, 31, v10
	v_lshlrev_b64 v[10:11], 12, v[10:11]
	v_or_b32_e32 v10, v10, v0
	v_lshl_add_u64 v[14:15], s[44:45], 0, v[10:11]
	global_load_dword v12, v[14:15], off
	v_lshl_add_u64 v[10:11], s[0:1], 0, v[10:11]
	s_waitcnt vmcnt(0)
	v_fmac_f32_e32 v12, v13, v19
	global_store_dword v[10:11], v12, off
	v_or_b32_e32 v10, 32, v18
	v_ashrrev_i32_e32 v11, 31, v10
	v_lshlrev_b64 v[10:11], 12, v[10:11]
	v_or_b32_e32 v10, v10, v0
	v_lshl_add_u64 v[12:13], s[44:45], 0, v[10:11]
	global_load_dword v14, v[20:21], off
	v_lshl_add_u64 v[10:11], s[0:1], 0, v[10:11]
	global_load_dword v12, v[12:13], off
	s_waitcnt vmcnt(0) lgkmcnt(0)
	v_fmac_f32_e32 v12, v6, v14
	global_store_dword v[10:11], v12, off
	v_or_b32_e32 v10, 33, v18
	v_ashrrev_i32_e32 v11, 31, v10
	v_lshlrev_b64 v[10:11], 12, v[10:11]
	v_or_b32_e32 v10, v10, v0
	v_lshl_add_u64 v[12:13], s[44:45], 0, v[10:11]
	global_load_dword v12, v[12:13], off
	s_waitcnt vmcnt(0)
	v_fmac_f32_e32 v12, v7, v14
	v_lshl_add_u64 v[6:7], s[0:1], 0, v[10:11]
	global_store_dword v[6:7], v12, off
	v_or_b32_e32 v6, 34, v18
	v_ashrrev_i32_e32 v7, 31, v6
	v_lshlrev_b64 v[6:7], 12, v[6:7]
	v_or_b32_e32 v6, v6, v0
	v_lshl_add_u64 v[10:11], s[44:45], 0, v[6:7]
	global_load_dword v10, v[10:11], off
	v_lshl_add_u64 v[6:7], s[0:1], 0, v[6:7]
	s_waitcnt vmcnt(0)
	v_fmac_f32_e32 v10, v8, v14
	global_store_dword v[6:7], v10, off
	v_or_b32_e32 v6, 35, v18
	v_ashrrev_i32_e32 v7, 31, v6
	v_lshlrev_b64 v[6:7], 12, v[6:7]
	v_or_b32_e32 v6, v6, v0
	v_lshl_add_u64 v[10:11], s[44:45], 0, v[6:7]
	global_load_dword v8, v[10:11], off
	v_lshl_add_u64 v[6:7], s[0:1], 0, v[6:7]
	s_waitcnt vmcnt(0)
	v_fmac_f32_e32 v8, v9, v14
	global_store_dword v[6:7], v8, off
	v_or_b32_e32 v6, 48, v18
	v_ashrrev_i32_e32 v7, 31, v6
	v_lshlrev_b64 v[6:7], 12, v[6:7]
	v_or_b32_e32 v6, v6, v0
	v_lshl_add_u64 v[8:9], s[44:45], 0, v[6:7]
	global_load_dword v10, v[20:21], off
	v_lshl_add_u64 v[6:7], s[0:1], 0, v[6:7]
	global_load_dword v8, v[8:9], off
	s_waitcnt vmcnt(0) lgkmcnt(0)
	v_fmac_f32_e32 v8, v2, v10
	global_store_dword v[6:7], v8, off
	v_or_b32_e32 v6, 49, v18
	v_ashrrev_i32_e32 v7, 31, v6
	v_lshlrev_b64 v[6:7], 12, v[6:7]
	v_or_b32_e32 v6, v6, v0
	v_lshl_add_u64 v[8:9], s[44:45], 0, v[6:7]
	global_load_dword v8, v[8:9], off
	s_waitcnt vmcnt(0)
	v_fmac_f32_e32 v8, v3, v10
	v_lshl_add_u64 v[2:3], s[0:1], 0, v[6:7]
	global_store_dword v[2:3], v8, off
	v_or_b32_e32 v2, 50, v18
	v_ashrrev_i32_e32 v3, 31, v2
	v_lshlrev_b64 v[2:3], 12, v[2:3]
	v_or_b32_e32 v2, v2, v0
	v_lshl_add_u64 v[6:7], s[44:45], 0, v[2:3]
	global_load_dword v6, v[6:7], off
	v_lshl_add_u64 v[2:3], s[0:1], 0, v[2:3]
	s_waitcnt vmcnt(0)
	v_fmac_f32_e32 v6, v4, v10
	global_store_dword v[2:3], v6, off
	v_or_b32_e32 v2, 51, v18
	v_ashrrev_i32_e32 v3, 31, v2
	v_lshlrev_b64 v[2:3], 12, v[2:3]
	v_or_b32_e32 v2, v2, v0
	v_lshl_add_u64 v[6:7], s[44:45], 0, v[2:3]
	global_load_dword v0, v[6:7], off
	v_lshl_add_u64 v[2:3], s[0:1], 0, v[2:3]
	v_readlane_b32 s0, v254, 51
	s_add_i32 s19, s19, s0
	s_cmp_lt_i32 s9, s8
	s_waitcnt vmcnt(0)
	v_fmac_f32_e32 v0, v5, v10
	global_store_dword v[2:3], v0, off
	s_cbranch_scc1 .LBB0_854

; __device__ __forceinline__ int tid_() { int t = threadIdx.x; asm volatile("" : "+v"(t)); return t; }
; __device__ __forceinline__ int bid_() { int b = blockIdx.x; asm volatile("" : "+s"(b)); return b; }
; __device__ __forceinline__ void phase_router(const Params& p, int l, const float* xlat, const float* xctx, int nrows) {
;   const int t = tid_(), lane = t & 63, wid = t >> 6, l16 = lane & 15, quad = lane >> 4;
;   const int gw = bid_() * 4 + wid, nw = gridDim.x * 4;
;   const int ntile = nrows >> 4;
;   for (int tile = gw; tile < ntile; tile += nw) {
;     const int row0 = tile * 16;
;     const int cond = row_cond(row0);
;     const float* xr = (row0 < T_LAT ? xlat + (size_t)(row0 + l16) * DM : xctx + (size_t)(row0 - T_LAT + l16) * DM) + quad * 4;
;     const float* wp = p.WR2 + (size_t)(l * 3 + cond) * 16384 + quad * 64 + l16;
.LBB0_909:
	s_or_b64 exec, exec, s[0:1]
	s_and_b64 s[0:1], exec, s[86:87]
	s_mov_b64 s[38:39], s[64:65]
	v_mov_b32_e32 v0, v187
	s_cselect_b32 s37, 0x4000, s68
	s_waitcnt lgkmcnt(0)
	s_barrier
	s_mov_b32 s0, s2
	v_ashrrev_i32_e32 v2, 6, v0
	s_lshr_b32 s8, s37, 4
	v_lshl_add_u32 v11, s0, 2, v2
	v_cmp_gt_i32_e32 vcc, s8, v11
	s_and_saveexec_b64 s[40:41], vcc
	s_cbranch_execz .LBB0_914
	v_mov_b64_e32 v[2:3], s[38:39]
	global_load_dwordx4 v[2:5], v[2:3], off offset:392
	v_and_b32_e32 v20, 15, v0
	v_bfe_u32 v0, v0, 4, 2
	v_lshlrev_b32_e32 v10, 2, v0
	v_lshlrev_b32_e32 v0, 8, v0
	v_or_b32_e32 v23, 1, v10
	v_or_b32_e32 v25, 2, v10
	v_or_b32_e32 v27, 3, v10
	v_or_b32_e32 v21, 0xffffc000, v20
	s_mov_b64 s[42:43], 0
	s_waitcnt vmcnt(0) lgkmcnt(0)
	v_lshl_add_u64 v[2:3], v[2:3], 0, v[0:1]
	v_lshlrev_b32_e32 v0, 2, v20
	v_lshl_add_u64 v[2:3], v[2:3], 0, v[0:1]
	v_or_b32_e32 v0, v10, v214
	v_lshlrev_b32_e32 v22, 2, v0
	v_or_b32_e32 v0, v23, v214
	v_lshlrev_b32_e32 v24, 2, v0
	v_or_b32_e32 v0, v25, v214
	v_lshlrev_b32_e32 v26, 2, v0
	v_or_b32_e32 v0, v27, v214
	v_lshlrev_b32_e32 v28, 2, v0

; __device__ __forceinline__ void phase_router(const Params& p, int l, const float* xlat, const float* xctx, int nrows) {
;     ...
;     for (int s = 0; s < 64; ++s) {
;       const float4 a = *(const float4*)(xr + s * 16);
;       const float b0 = wp[s * 256], b1 = wp[s * 256 + 16], b2 = wp[s * 256 + 32], b3 = wp[s * 256 + 48];
;       ss += a.x * a.x + a.y * a.y + a.z * a.z + a.w * a.w;
;       acc = __builtin_amdgcn_mfma_f32_16x16x4f32(a.x, b0, acc, 0, 0, 0);
;       acc = __builtin_amdgcn_mfma_f32_16x16x4f32(a.y, b1, acc, 0, 0, 0);
;       acc = __builtin_amdgcn_mfma_f32_16x16x4f32(a.z, b2, acc, 0, 0, 0);
;       acc = __builtin_amdgcn_mfma_f32_16x16x4f32(a.w, b3, acc, 0, 0, 0);
;     }
;     ss += __shfl_xor(ss, 16);
;     ss += __shfl_xor(ss, 32);
;     const float rstd = rsqrtf(ss * (1.f / 1024.f) + 1e-6f);
;     const float ce = p.CE[(l * 3 + cond) * 16 + l16];
; #pragma unroll
;     for (int j = 0; j < 4; ++j) {
;       const int tk = quad * 4 + j;
;       const float r = __shfl(rstd, tk);
;       const float lg = acc[j] * r + ce;
;       float mx = lg;
; #pragma unroll
;       for (int o = 8; o; o >>= 1) mx = fmaxf(mx, __shfl_xor(mx, o));
;       const float ex = __expf(lg - mx);
;       float sm = ex;
; #pragma unroll
;       for (int o = 8; o; o >>= 1) sm += __shfl_xor(sm, o);
;       const float aff = ex / sm;
;       const int row = row0 + tk;
;       if (row < T_LAT) p.AFFT[(size_t)((row >> 13) * 16 + l16) * SEQ + (row & (SEQ - 1))] = aff;
;       else { const int rc = row - T_LAT; p.AFFT[(size_t)32 * SEQ + ((rc >> 8) * 16 + l16) * CTX + (rc & 255)] = aff; }
.LBB0_912:
	v_lshl_add_u64 v[18:19], v[14:15], 0, s[0:1]
	global_load_dword v13, v[16:17], off
	global_load_dword v38, v[16:17], off offset:64
	global_load_dword v39, v[16:17], off offset:128
	global_load_dword v40, v[16:17], off offset:192
	global_load_dwordx4 v[30:33], v[18:19], off
	s_add_u32 s0, s0, 0x100
	s_addc_u32 s1, s1, 0
	s_cmpk_eq_i32 s0, 0x1000
	s_waitcnt vmcnt(0) lgkmcnt(0)
	v_mfma_f32_16x16x4_f32 v[6:9], v30, v13, v[6:9]
	v_mul_f32_e64 v34, v30, v30
	v_mul_f32_e64 v35, v31, v31
	v_mul_f32_e64 v36, v32, v32
	v_mul_f32_e64 v37, v33, v33
	v_add_f32_e32 v34, v34, v35
	v_add_f32_e32 v34, v34, v36
	v_add_f32_e32 v34, v34, v37
	v_add_f32_e32 v0, v0, v34
	v_mfma_f32_16x16x4_f32 v[6:9], v31, v38, v[6:9]
	v_mfma_f32_16x16x4_f32 v[6:9], v32, v39, v[6:9]
	v_mfma_f32_16x16x4_f32 v[6:9], v33, v40, v[6:9]
	global_load_dword v13, v[16:17], off offset:1024
	global_load_dword v38, v[16:17], off offset:1088
	global_load_dword v39, v[16:17], off offset:1152
	global_load_dword v40, v[16:17], off offset:1216
	global_load_dwordx4 v[30:33], v[18:19], off offset:64
	s_waitcnt vmcnt(0)
	v_pk_mul_f32 v[34:35], v[30:31], v[30:31]
	s_waitcnt lgkmcnt(0)
	v_mfma_f32_16x16x4_f32 v[6:9], v30, v13, v[6:9]
	v_mul_f32_e64 v36, v32, v32
	v_mul_f32_e64 v37, v33, v33
	v_add_f32_e32 v34, v34, v35
	v_add_f32_e32 v34, v34, v36
	v_add_f32_e32 v34, v34, v37
	v_add_f32_e32 v0, v0, v34
	v_mfma_f32_16x16x4_f32 v[6:9], v31, v38, v[6:9]
	v_mfma_f32_16x16x4_f32 v[6:9], v32, v39, v[6:9]
	v_mfma_f32_16x16x4_f32 v[6:9], v33, v40, v[6:9]
	global_load_dword v13, v[16:17], off offset:2048
	global_load_dword v38, v[16:17], off offset:2112
	global_load_dword v39, v[16:17], off offset:2176
	global_load_dword v40, v[16:17], off offset:2240
	global_load_dwordx4 v[30:33], v[18:19], off offset:128
	s_waitcnt vmcnt(0)
	v_pk_mul_f32 v[34:35], v[30:31], v[30:31]
	s_waitcnt lgkmcnt(0)
	v_mfma_f32_16x16x4_f32 v[6:9], v30, v13, v[6:9]
	v_mul_f32_e64 v36, v32, v32
	v_mul_f32_e64 v37, v33, v33
	v_add_f32_e32 v34, v34, v35
	v_add_f32_e32 v34, v34, v36
	v_add_f32_e32 v34, v34, v37
	v_add_f32_e32 v0, v0, v34
	v_mfma_f32_16x16x4_f32 v[6:9], v31, v38, v[6:9]
	v_mfma_f32_16x16x4_f32 v[6:9], v32, v39, v[6:9]
	v_mfma_f32_16x16x4_f32 v[6:9], v33, v40, v[6:9]
	global_load_dword v13, v[16:17], off offset:3072
	global_load_dword v36, v[16:17], off offset:3136
	global_load_dword v37, v[16:17], off offset:3200
	global_load_dword v38, v[16:17], off offset:3264
	global_load_dwordx4 v[30:33], v[18:19], off offset:192
	v_lshl_add_u64 v[16:17], v[16:17], 0, s[92:93]
	s_waitcnt vmcnt(0)
	v_pk_mul_f32 v[18:19], v[30:31], v[30:31]
	s_waitcnt lgkmcnt(0)
	v_mfma_f32_16x16x4_f32 v[6:9], v30, v13, v[6:9]
	v_mul_f32_e64 v34, v32, v32
	v_mul_f32_e64 v35, v33, v33
	v_add_f32_e32 v18, v18, v19
	v_add_f32_e32 v18, v18, v34
	v_add_f32_e32 v18, v18, v35
	v_add_f32_e32 v0, v0, v18
	v_mfma_f32_16x16x4_f32 v[6:9], v31, v36, v[6:9]
	v_mfma_f32_16x16x4_f32 v[6:9], v32, v37, v[6:9]
	v_mfma_f32_16x16x4_f32 v[6:9], v33, v38, v[6:9]
	s_cbranch_scc0 .LBB0_912
	ds_bpermute_b32 v13, v230, v0
	v_lshl_or_b32 v12, v12, 4, v20
	s_mov_b32 s0, 0xfffff0
	v_mov_b32_e32 v14, 0x40000
	s_waitcnt lgkmcnt(0)
	v_add_f32_e32 v0, v0, v13
	ds_bpermute_b32 v13, v229, v0
	s_waitcnt lgkmcnt(0)
	v_add_f32_e32 v0, v0, v13
	v_fmamk_f32 v0, v0, 0x3a800000, v224
	v_cmp_gt_f32_e32 vcc, s85, v0
	v_mul_f32_e32 v13, 0x4b800000, v0
	s_nop 0
	v_cndmask_b32_e32 v0, v0, v13, vcc
	v_rsq_f32_e32 v0, v0
	s_nop 0
	v_mul_f32_e32 v13, 0x45800000, v0
	v_cndmask_b32_e32 v18, v0, v13, vcc
	v_ashrrev_i32_e32 v13, 31, v12
	v_lshl_add_u64 v[12:13], v[12:13], 2, v[4:5]
	global_load_dword v17, v[12:13], off
	v_add_u32_e32 v0, 0xffffc000, v29
	v_mov_b64_e32 v[12:13], s[38:39]
	v_lshrrev_b32_e32 v0, 4, v0
	global_load_dwordx2 v[12:13], v[12:13], off offset:376
	v_and_or_b32 v0, v0, s0, v20
	v_lshl_add_u32 v16, v0, 8, v14
	v_ashrrev_i32_e32 v0, 5, v11
	v_and_or_b32 v14, v0, -16, v20
	ds_bpermute_b32 v0, v22, v18
	v_ashrrev_i32_e32 v15, 31, v14
	v_lshlrev_b64 v[14:15], 15, v[14:15]
	s_waitcnt vmcnt(0) lgkmcnt(0)
	v_fma_f32 v0, v6, v0, v17
	ds_bpermute_b32 v6, v231, v0
	v_lshl_add_u64 v[14:15], v[12:13], 0, v[14:15]
	s_waitcnt lgkmcnt(0)
	v_max_f32_e32 v6, v6, v6
	v_max_f32_e32 v6, v0, v6
	ds_bpermute_b32 v19, v232, v6
	s_waitcnt lgkmcnt(0)
	v_max_f32_e32 v19, v19, v19
	v_max_f32_e32 v6, v6, v19
	ds_bpermute_b32 v19, v233, v6
	s_waitcnt lgkmcnt(0)
	v_max_f32_e32 v19, v19, v19
	v_max_f32_e32 v6, v6, v19
	ds_bpermute_b32 v19, v234, v6
	s_waitcnt lgkmcnt(0)
	v_max_f32_e32 v19, v19, v19
	v_max_f32_e32 v6, v6, v19
	v_sub_f32_e32 v0, v0, v6
	v_mul_f32_e32 v0, 0x3fb8aa3b, v0
	v_exp_f32_e32 v0, v0
	ds_bpermute_b32 v6, v231, v0
	s_waitcnt lgkmcnt(0)
	v_add_f32_e32 v6, v0, v6
	ds_bpermute_b32 v19, v232, v6
	s_waitcnt lgkmcnt(0)
	v_add_f32_e32 v6, v6, v19
	ds_bpermute_b32 v19, v233, v6
	s_waitcnt lgkmcnt(0)
	v_add_f32_e32 v6, v6, v19
	ds_bpermute_b32 v19, v234, v6
	s_waitcnt lgkmcnt(0)
	v_add_f32_e32 v6, v6, v19
	v_div_scale_f32 v19, s[0:1], v6, v6, v0
	v_rcp_f32_e32 v30, v19
	s_movk_i32 s0, 0xfc
	v_fma_f32 v31, -v19, v30, 1.0
	v_fmac_f32_e32 v30, v31, v30
	v_div_scale_f32 v31, vcc, v0, v6, v0
	v_mul_f32_e32 v32, v31, v30
	v_fma_f32 v33, -v19, v32, v31
	v_fmac_f32_e32 v32, v33, v30
	v_fma_f32 v19, -v19, v32, v31
	v_div_fmas_f32 v19, v19, v30, v32
	v_div_fixup_f32 v6, v19, v6, v0
	v_or_b32_e32 v0, v29, v10
	v_cmp_gt_i32_e32 vcc, s69, v0
	v_and_or_b32 v0, v0, s0, v16
	s_movk_i32 s0, 0x1ffc
	v_bitop3_b32 v19, v29, s0, v10 bitop3:0xc8
	v_cndmask_b32_e32 v0, v0, v19, vcc
	v_cndmask_b32_e32 v31, v13, v15, vcc
	v_cndmask_b32_e32 v30, v12, v14, vcc
	v_lshl_add_u64 v[30:31], v[0:1], 2, v[30:31]
	ds_bpermute_b32 v0, v24, v18
	global_store_dword v[30:31], v6, off
	s_waitcnt lgkmcnt(0)
; __device__ __forceinline__ void phase_router(const Params& p, int l, const float* xlat, const float* xctx, int nrows) {
;     ...
; #pragma unroll
;     for (int j = 0; j < 4; ++j) {
;       const int tk = quad * 4 + j;
;       const float r = __shfl(rstd, tk);
;       const float lg = acc[j] * r + ce;
;       float mx = lg;
; #pragma unroll
;       for (int o = 8; o; o >>= 1) mx = fmaxf(mx, __shfl_xor(mx, o));
;       const float ex = __expf(lg - mx);
;       float sm = ex;
; #pragma unroll
;       for (int o = 8; o; o >>= 1) sm += __shfl_xor(sm, o);
;       const float aff = ex / sm;
;       const int row = row0 + tk;
;       if (row < T_LAT) p.AFFT[(size_t)((row >> 13) * 16 + l16) * SEQ + (row & (SEQ - 1))] = aff;
;       else { const int rc = row - T_LAT; p.AFFT[(size_t)32 * SEQ + ((rc >> 8) * 16 + l16) * CTX + (rc & 255)] = aff; }
;     }
	v_fma_f32 v0, v7, v0, v17
	ds_bpermute_b32 v6, v231, v0
	s_waitcnt lgkmcnt(0)
	v_max_f32_e32 v6, v6, v6
	v_max_f32_e32 v6, v0, v6
	ds_bpermute_b32 v7, v232, v6
	s_waitcnt lgkmcnt(0)
	v_max_f32_e32 v7, v7, v7
	v_max_f32_e32 v6, v6, v7
	ds_bpermute_b32 v7, v233, v6
	s_waitcnt lgkmcnt(0)
	v_max_f32_e32 v7, v7, v7
	v_max_f32_e32 v6, v6, v7
	ds_bpermute_b32 v7, v234, v6
	s_waitcnt lgkmcnt(0)
	v_max_f32_e32 v7, v7, v7
	v_max_f32_e32 v6, v6, v7
	v_sub_f32_e32 v0, v0, v6
	v_mul_f32_e32 v0, 0x3fb8aa3b, v0
	v_exp_f32_e32 v0, v0
	ds_bpermute_b32 v6, v231, v0
	s_waitcnt lgkmcnt(0)
	v_add_f32_e32 v6, v0, v6
	ds_bpermute_b32 v7, v232, v6
	s_waitcnt lgkmcnt(0)
	v_add_f32_e32 v6, v6, v7
	ds_bpermute_b32 v7, v233, v6
	s_waitcnt lgkmcnt(0)
	v_add_f32_e32 v6, v6, v7
	ds_bpermute_b32 v7, v234, v6
	s_waitcnt lgkmcnt(0)
	v_add_f32_e32 v6, v6, v7
	v_div_scale_f32 v7, s[0:1], v6, v6, v0
	v_rcp_f32_e32 v19, v7
	s_movk_i32 s0, 0x1ffd
	v_fma_f32 v30, -v7, v19, 1.0
	v_fmac_f32_e32 v19, v30, v19
	v_div_scale_f32 v30, vcc, v0, v6, v0
	v_mul_f32_e32 v31, v30, v19
	v_fma_f32 v32, -v7, v31, v30
	v_fmac_f32_e32 v31, v32, v19
	v_fma_f32 v7, -v7, v31, v30
	v_div_fmas_f32 v7, v7, v19, v31
	v_div_fixup_f32 v19, v7, v6, v0
	v_or_b32_e32 v0, v29, v23
	v_bitop3_b32 v6, v29, s0, v23 bitop3:0xc8
	s_movk_i32 s0, 0xfd
	v_cmp_gt_i32_e32 vcc, s69, v0
	v_and_or_b32 v0, v0, s0, v16
	s_nop 0
	v_cndmask_b32_e32 v0, v0, v6, vcc
	v_cndmask_b32_e32 v7, v13, v15, vcc
	v_cndmask_b32_e32 v6, v12, v14, vcc
	v_lshl_add_u64 v[6:7], v[0:1], 2, v[6:7]
	ds_bpermute_b32 v0, v26, v18
	global_store_dword v[6:7], v19, off
	s_waitcnt lgkmcnt(0)
	v_fma_f32 v0, v8, v0, v17
	ds_bpermute_b32 v6, v231, v0
	s_waitcnt lgkmcnt(0)
	v_max_f32_e32 v6, v6, v6
	v_max_f32_e32 v6, v0, v6
	ds_bpermute_b32 v7, v232, v6
	s_waitcnt lgkmcnt(0)
	v_max_f32_e32 v7, v7, v7
	v_max_f32_e32 v6, v6, v7
	ds_bpermute_b32 v7, v233, v6
	s_waitcnt lgkmcnt(0)
	v_max_f32_e32 v7, v7, v7
	v_max_f32_e32 v6, v6, v7
	ds_bpermute_b32 v7, v234, v6
	s_waitcnt lgkmcnt(0)
	v_max_f32_e32 v7, v7, v7
	v_max_f32_e32 v6, v6, v7
	v_sub_f32_e32 v0, v0, v6
	v_mul_f32_e32 v0, 0x3fb8aa3b, v0
	v_exp_f32_e32 v0, v0
	ds_bpermute_b32 v6, v231, v0
	s_waitcnt lgkmcnt(0)
	v_add_f32_e32 v6, v0, v6
	ds_bpermute_b32 v7, v232, v6
	s_waitcnt lgkmcnt(0)
	v_add_f32_e32 v6, v6, v7
	ds_bpermute_b32 v7, v233, v6
	s_waitcnt lgkmcnt(0)
	v_add_f32_e32 v6, v6, v7
	ds_bpermute_b32 v7, v234, v6
	s_waitcnt lgkmcnt(0)
	v_add_f32_e32 v6, v6, v7
	v_div_scale_f32 v7, s[0:1], v6, v6, v0
	v_rcp_f32_e32 v8, v7
	s_movk_i32 s0, 0x1ffe
	v_fma_f32 v19, -v7, v8, 1.0
	v_fmac_f32_e32 v8, v19, v8
	v_div_scale_f32 v19, vcc, v0, v6, v0
	v_mul_f32_e32 v30, v19, v8
	v_fma_f32 v31, -v7, v30, v19
	v_fmac_f32_e32 v30, v31, v8
	v_fma_f32 v7, -v7, v30, v19
	v_div_fmas_f32 v7, v7, v8, v30
	v_div_fixup_f32 v8, v7, v6, v0
	v_or_b32_e32 v0, v29, v25
	v_bitop3_b32 v6, v29, s0, v25 bitop3:0xc8
	s_movk_i32 s0, 0xfe
	v_cmp_gt_i32_e32 vcc, s69, v0
	v_and_or_b32 v0, v0, s0, v16
	s_nop 0
	v_cndmask_b32_e32 v0, v0, v6, vcc
	v_cndmask_b32_e32 v7, v13, v15, vcc
	v_cndmask_b32_e32 v6, v12, v14, vcc
	v_lshl_add_u64 v[6:7], v[0:1], 2, v[6:7]
	ds_bpermute_b32 v0, v28, v18
	global_store_dword v[6:7], v8, off
	s_waitcnt lgkmcnt(0)
	v_fmac_f32_e32 v17, v9, v0
	ds_bpermute_b32 v0, v231, v17
	s_waitcnt lgkmcnt(0)
	v_max_f32_e32 v0, v0, v0
	v_max_f32_e32 v0, v17, v0
	ds_bpermute_b32 v6, v232, v0
	s_waitcnt lgkmcnt(0)
	v_max_f32_e32 v6, v6, v6
	v_max_f32_e32 v0, v0, v6
	ds_bpermute_b32 v6, v233, v0
	s_waitcnt lgkmcnt(0)
	v_max_f32_e32 v6, v6, v6
	v_max_f32_e32 v0, v0, v6
	ds_bpermute_b32 v6, v234, v0
	s_waitcnt lgkmcnt(0)
	v_max_f32_e32 v6, v6, v6
	v_max_f32_e32 v0, v0, v6
	v_sub_f32_e32 v0, v17, v0
	v_mul_f32_e32 v0, 0x3fb8aa3b, v0
	v_exp_f32_e32 v0, v0
	ds_bpermute_b32 v6, v231, v0
	s_waitcnt lgkmcnt(0)
	v_add_f32_e32 v6, v0, v6
	ds_bpermute_b32 v7, v232, v6
	s_waitcnt lgkmcnt(0)
	v_add_f32_e32 v6, v6, v7
	ds_bpermute_b32 v7, v233, v6
	s_waitcnt lgkmcnt(0)
	v_add_f32_e32 v6, v6, v7
	ds_bpermute_b32 v7, v234, v6
	s_waitcnt lgkmcnt(0)
	v_add_f32_e32 v6, v6, v7
	v_div_scale_f32 v7, s[0:1], v6, v6, v0
	v_rcp_f32_e32 v8, v7
	s_movk_i32 s0, 0x1fff
	v_fma_f32 v9, -v7, v8, 1.0
	v_fmac_f32_e32 v8, v9, v8
	v_div_scale_f32 v9, vcc, v0, v6, v0
	v_mul_f32_e32 v17, v9, v8
	v_fma_f32 v18, -v7, v17, v9
	v_fmac_f32_e32 v17, v18, v8
	v_fma_f32 v7, -v7, v17, v9
	v_div_fmas_f32 v7, v7, v8, v17
	v_div_fixup_f32 v8, v7, v6, v0
	v_or_b32_e32 v0, v29, v27
	v_bitop3_b32 v6, v29, s0, v27 bitop3:0xc8
	s_movk_i32 s0, 0xff
	v_cmp_gt_i32_e32 vcc, s69, v0
	v_and_or_b32 v0, v0, s0, v16
	v_readlane_b32 s0, v254, 47
	v_cndmask_b32_e32 v0, v0, v6, vcc
	v_cndmask_b32_e32 v7, v13, v15, vcc
	v_add_u32_e32 v11, s0, v11
	v_cndmask_b32_e32 v6, v12, v14, vcc
	v_cmp_le_i32_e32 vcc, s8, v11
	v_lshl_add_u64 v[6:7], v[0:1], 2, v[6:7]
	s_or_b64 s[42:43], vcc, s[42:43]
	global_store_dword v[6:7], v8, off
	v_readlane_b32 s1, v254, 48
	s_andn2_b64 exec, exec, s[42:43]
	s_cbranch_execnz .LBB0_911

; __device__ __forceinline__ int bid_() { int b = blockIdx.x; asm volatile("" : "+s"(b)); return b; }
; __device__ __forceinline__ void phase_topk(const Params& p, bool last, unsigned char* smem) {
;     ...
;   for (int inst = bid_(); inst < ninst; inst += gridDim.x) {
;     const bool lat = inst < 32;
;     const int n = lat ? SEQ : CTX, cap = lat ? 1024 : 32;
;     const float* src = lat ? p.AFFT + (size_t)inst * SEQ : p.AFFT + (size_t)32 * SEQ + (inst - 32) * CTX;
;     const int rowbase = lat ? (inst >> 4) * SEQ : T_LAT + ((inst - 32) >> 4) * CTX;
;     for (int i = t; i < n; i += 256) key[i] = __float_as_uint(src[i]);
.LBB0_969:
	v_mov_b64_e32 v[2:3], s[0:1]
	global_load_dwordx2 v[4:5], v[2:3], off offset:376
	s_cmp_gt_i32 s86, 31
	s_cselect_b64 s[88:89], -1, 0
	s_cmp_lt_i32 s86, 32
	s_cselect_b64 s[64:65], -1, 0
	s_mov_b64 s[8:9], -1
	s_and_b64 vcc, exec, s[88:89]
	s_cbranch_vccnz .LBB0_973
	s_ashr_i32 s87, s86, 31
	s_lshl_b64 s[8:9], s[86:87], 15
	s_waitcnt vmcnt(0) lgkmcnt(0)
	v_lshl_add_u64 v[2:3], v[4:5], 0, s[8:9]
	s_cbranch_execz .LBB0_974

; __device__ __forceinline__ void phase_topk(const Params& p, bool last, unsigned char* smem) {
;     ...
;     for (int i = t; i < n; i += 256) key[i] = __float_as_uint(src[i]);
.LBB0_980:
	v_ashrrev_i32_e32 v13, 31, v5
	v_mov_b32_e32 v12, v5
	v_ashrrev_i32_e32 v15, 31, v4
	v_mov_b32_e32 v14, v4
	v_lshl_add_u64 v[14:15], v[14:15], 2, v[2:3]
	v_lshl_add_u64 v[12:13], v[12:13], 2, v[2:3]
	global_load_dword v14, v[14:15], off
	s_nop 0
	global_load_dword v12, v[12:13], off
	v_add_u32_e32 v10, -2, v10
	v_cmp_eq_u32_e64 s[60:61], 0, v10
	v_add_u32_e32 v5, 0x200, v5
	v_add_u32_e32 v4, 0x200, v4
	s_or_b64 s[18:19], s[60:61], s[18:19]
	s_waitcnt vmcnt(0) lgkmcnt(0)
	ds_write2st64_b32 v11, v14, v12 offset1:4
	v_add_u32_e32 v11, 0x800, v11
	s_andn2_b64 exec, exec, s[18:19]
	s_cbranch_execnz .LBB0_980
	s_or_b64 exec, exec, s[18:19]
	v_cmp_ne_u32_e64 s[60:61], v0, v9
	v_lshl_add_u32 v4, v9, 8, v6
	s_orn2_b64 s[18:19], s[60:61], exec

; __device__ __forceinline__ void phase_topk(const Params& p, bool last, unsigned char* smem) {
;     ...
;     for (int i = t; i < n; i += 256) key[i] = __float_as_uint(src[i]);
.LBB0_984:
	global_load_dword v5, v[2:3], off
	v_add_u32_e32 v4, 0x100, v4
	s_mov_b64 s[18:19], 0x400
	v_cmp_le_i32_e64 s[60:61], s35, v4
	v_lshl_add_u64 v[2:3], v[2:3], 0, s[18:19]
	s_or_b64 s[8:9], s[60:61], s[8:9]
	s_waitcnt vmcnt(0) lgkmcnt(0)
	ds_write_b32 v0, v5
	v_add_u32_e32 v0, 0x400, v0
	s_andn2_b64 exec, exec, s[8:9]
	s_cbranch_execnz .LBB0_984

; __device__ __forceinline__ void phase_topk(const Params& p, bool last, unsigned char* smem) {
;     ...
;     const int per = n >> 8;
;     unsigned cgt = 0u, ceq = 0u;
;     for (int i = 0; i < per; ++i) {
;       const unsigned k = key[t * per + i];
;       cgt += (k > prefix) ? 1u : 0u;
;       ceq += (k == prefix) ? 1u : 0u;
;     }
;     unsigned ngt, neq;
;     unsigned og = block_incl_scan(cgt, wsum, lane, wid, ngt) - cgt;
;     unsigned oe = block_incl_scan(ceq, wsum, lane, wid, neq) - ceq;
;     int* idx = p.IDXG + (size_t)inst * 1024;
;     float* gt = p.GATE + (size_t)inst * 1024;
;     int* inv = p.INV + (size_t)rowbase * 16 + (inst & 15);
;     for (int i = 0; i < per; ++i) {
;       const int e = t * per + i;
;       const unsigned k = key[e];
;       int slot = -1;
;       if (k > prefix) {
;         slot = (int)og; ++og;
;       } else if (k == prefix) {
;         if (oe < remaining) slot = (int)(ngt + oe);
;         ++oe;
;       }
;       if (slot >= 0) { idx[slot] = rowbase + e; gt[slot] = __uint_as_float(k); }
;       inv[(size_t)e * 16] = slot;
;     }
.LBB0_1026:
	ds_bpermute_b32 v2, v17, v13
	s_waitcnt lgkmcnt(0)
	s_barrier
	v_cndmask_b32_e64 v2, v2, 0, s[38:39]
	v_add_u32_e32 v2, v2, v13
	ds_bpermute_b32 v3, v18, v2
	s_waitcnt lgkmcnt(0)
	v_cndmask_b32_e64 v3, v3, 0, s[40:41]
	v_add_u32_e32 v2, v3, v2
	ds_bpermute_b32 v3, v19, v2
	s_waitcnt lgkmcnt(0)
	v_cndmask_b32_e64 v3, v3, 0, s[42:43]
	v_add_u32_e32 v2, v3, v2
	ds_bpermute_b32 v3, v20, v2
	s_waitcnt lgkmcnt(0)
	v_cndmask_b32_e64 v3, v3, 0, s[44:45]
	v_add_u32_e32 v2, v3, v2
	ds_bpermute_b32 v3, v21, v2
	s_waitcnt lgkmcnt(0)
	v_cndmask_b32_e64 v3, v3, 0, s[46:47]
	v_add_u32_e32 v2, v3, v2
	ds_bpermute_b32 v3, v22, v2
	s_waitcnt lgkmcnt(0)
	v_cndmask_b32_e64 v3, v3, 0, s[48:49]
	v_add_u32_e32 v15, v3, v2
	s_and_saveexec_b64 s[8:9], s[50:51]
	ds_write_b32 v23, v15 offset:33792
	s_or_b64 exec, exec, s[8:9]
	ds_bpermute_b32 v2, v17, v0
	s_waitcnt lgkmcnt(0)
	s_barrier
	v_cndmask_b32_e64 v2, v2, 0, s[38:39]
	v_add_u32_e32 v2, v2, v0
	ds_bpermute_b32 v3, v18, v2
	s_waitcnt lgkmcnt(0)
	v_cndmask_b32_e64 v3, v3, 0, s[40:41]
	v_add_u32_e32 v2, v3, v2
	ds_bpermute_b32 v3, v19, v2
	s_waitcnt lgkmcnt(0)
	v_cndmask_b32_e64 v3, v3, 0, s[42:43]
	v_add_u32_e32 v2, v3, v2
	ds_bpermute_b32 v3, v20, v2
	s_waitcnt lgkmcnt(0)
	v_cndmask_b32_e64 v3, v3, 0, s[44:45]
	v_add_u32_e32 v2, v3, v2
	ds_bpermute_b32 v3, v21, v2
	s_waitcnt lgkmcnt(0)
	v_cndmask_b32_e64 v3, v3, 0, s[46:47]
	v_add_u32_e32 v14, v3, v2
	ds_bpermute_b32 v27, v22, v14
	ds_read_b128 v[2:5], v1 offset:33792
	s_waitcnt lgkmcnt(0)
	s_barrier
	v_cndmask_b32_e64 v27, v27, 0, s[48:49]
	v_add_u32_e32 v14, v27, v14
	s_and_saveexec_b64 s[8:9], s[50:51]
	ds_write_b32 v23, v14 offset:33792
	s_or_b64 exec, exec, s[8:9]
	v_add_u32_e32 v27, v3, v2
	v_add_u32_e32 v27, v27, v4
	v_add_u32_e32 v27, v27, v5
	v_cndmask_b32_e64 v2, 0, v2, s[52:53]
	v_sub_u32_e32 v5, v15, v13
	v_cndmask_b32_e64 v3, 0, v3, s[54:55]
	v_cndmask_b32_e64 v4, 0, v4, s[56:57]
	v_add_u32_e32 v2, v5, v2
	v_add3_u32 v13, v2, v3, v4
	s_waitcnt lgkmcnt(0)
	s_barrier
	ds_read_b96 v[2:4], v1 offset:33792
	v_sub_u32_e32 v0, v14, v0
	s_ashr_i32 s87, s86, 31
	s_lshl_b64 s[8:9], s[86:87], 12
	s_ashr_i32 s59, s58, 31
	s_waitcnt lgkmcnt(0)
	v_cndmask_b32_e64 v2, 0, v2, s[52:53]
	v_cndmask_b32_e64 v3, 0, v3, s[54:55]
	v_cndmask_b32_e64 v4, 0, v4, s[56:57]
	v_add_u32_e32 v0, v0, v2
	v_add3_u32 v28, v0, v3, v4
	v_mov_b64_e32 v[4:5], s[0:1]
	global_load_dwordx4 v[30:33], v[4:5], off offset:408
	s_waitcnt vmcnt(0) lgkmcnt(0)
	v_lshl_add_u64 v[2:3], v[30:31], 0, s[8:9]
	global_load_dwordx2 v[4:5], v[4:5], off offset:384
	s_waitcnt vmcnt(0) lgkmcnt(0)
	v_lshl_add_u64 v[4:5], v[4:5], 0, s[8:9]
	s_lshl_b64 s[8:9], s[58:59], 6
	v_lshl_add_u64 v[14:15], v[32:33], 0, s[8:9]
	s_and_b32 s8, s86, 15
	s_lshl_b32 s94, s8, 2
	v_lshl_add_u64 v[14:15], v[14:15], 0, s[94:95]
	s_branch .LBB0_1032
.LBB0_1031:
	s_or_b64 exec, exec, s[8:9]
	v_lshlrev_b64 v[32:33], 6, v[12:13]
	s_add_i32 s18, s18, -1
	v_lshl_add_u64 v[32:33], v[14:15], 0, v[32:33]
	v_add_u32_e32 v9, 4, v9
	v_add_u32_e32 v12, 1, v12
	s_cmp_eq_u32 s18, 0
	v_mov_b32_e32 v13, v30
	global_store_dword v[32:33], v0, off
	s_cbranch_scc1 .LBB0_968
.LBB0_1032:
	ds_read_b32 v29, v9
	s_waitcnt lgkmcnt(0)
	v_cmp_le_u32_e32 vcc, v29, v10
	s_and_saveexec_b64 s[8:9], vcc
	s_xor_b64 s[8:9], exec, s[8:9]
	v_cmp_lt_u32_e32 vcc, v28, v11
	v_cmp_eq_u32_e64 s[60:61], v29, v10
	v_add_u32_e32 v0, v27, v28
	s_and_b64 vcc, s[60:61], vcc
	v_addc_co_u32_e64 v28, s[62:63], 0, v28, s[60:61]
	s_mov_b64 s[62:63], 0x4000
	v_cndmask_b32_e32 v0, -1, v0, vcc
	s_or_saveexec_b64 s[8:9], s[8:9]
	v_mov_b32_e32 v30, v13
	s_xor_b64 exec, exec, s[8:9]
	v_add_u32_e32 v30, 1, v13
	v_mov_b32_e32 v0, v13
	s_or_b64 exec, exec, s[8:9]
	v_ashrrev_i32_e32 v13, 31, v12
	v_cmp_lt_i32_e32 vcc, -1, v0
	s_and_saveexec_b64 s[8:9], vcc
	s_cbranch_execz .LBB0_1031
	v_lshlrev_b64 v[32:33], 2, v[0:1]
	v_add_u32_e32 v31, s58, v12
	v_lshl_add_u64 v[34:35], v[2:3], 0, v[32:33]
	v_lshl_add_u64 v[32:33], v[4:5], 0, v[32:33]
	global_store_dword v[34:35], v31, off
	global_store_dword v[32:33], v29, off
	s_branch .LBB0_1031

; __device__ __forceinline__ int tid_() { int t = threadIdx.x; asm volatile("" : "+v"(t)); return t; }
; __device__ __forceinline__ int bid_() { int b = blockIdx.x; asm volatile("" : "+s"(b)); return b; }
; template <int R>
; __device__ __forceinline__ void phase_modulate(const Params& p, int l, const float* xlat, const float* xctx, int nrows, int chunk, int bskip) {
;   const int t = tid_(), lane = t & 63, wid = t >> 6;
;   const int bb = bid_() - bskip;
;   if (bb < 0) return;
;   const int gw = bb * 4 + wid, nw = ((int)gridDim.x - bskip) * 4;
;   for (int row0 = gw * R; row0 < nrows; row0 += nw * R) {
;     const float* xr = row0 < T_LAT ? xlat + (size_t)row0 * DM : xctx + (size_t)(row0 - T_LAT) * DM;
;     const float* sh = p.mada + (size_t)(l * 3 + row_cond(row0)) * 6144 + chunk * 1024;
;     const float* sc = sh + 1024;
;     float4 v[R][4];
; #pragma unroll
;     for (int r = 0; r < R; ++r)
; #pragma unroll
;       for (int i = 0; i < 4; ++i) v[r][i] = *(const float4*)(xr + (size_t)r * DM + i * 256 + lane * 4);
;     float rstd[R];
; #pragma unroll
;     for (int r = 0; r < R; ++r) {
;       float ss = 0.f;
; #pragma unroll
;       for (int i = 0; i < 4; ++i) ss += v[r][i].x * v[r][i].x + v[r][i].y * v[r][i].y + v[r][i].z * v[r][i].z + v[r][i].w * v[r][i].w;
;       ss = wave_sum(ss);
;       rstd[r] = rsqrtf(ss * (1.f / 1024.f) + 1e-6f);
;     }
.LBB0_1042:
	s_or_b64 exec, exec, s[0:1]
	v_mov_b64_e32 v[60:61], s[40:41]
	global_load_dwordx2 v[6:7], v[60:61], off offset:184
	v_min_i32_e32 v0, 0x4000, v46
	v_ashrrev_i32_e32 v0, 13, v0
	s_mul_i32 s0, s36, 3
	v_add_u32_e32 v0, s0, v0
	v_mul_hi_i32_i24_e32 v9, 0x6000, v0
	v_mul_i32_i24_e32 v8, 0x6000, v0
	s_mov_b64 s[0:1], 0x3000
	v_lshlrev_b32_e32 v0, 2, v48
	v_lshl_add_u64 v[78:79], v[4:5], 0, v[0:1]
	v_add_co_u32_e32 v76, vcc, s84, v78
	v_lshlrev_b64 v[62:63], 11, v[2:3]
	s_nop 0
	v_addc_co_u32_e32 v77, vcc, 0, v79, vcc
	v_add_co_u32_e32 v108, vcc, s70, v78
	v_mov_b32_e32 v55, v1
	s_nop 0
	v_addc_co_u32_e32 v109, vcc, 0, v79, vcc
	v_mov_b32_e32 v57, v1
	v_mov_b32_e32 v59, v1
	v_lshl_add_u64 v[46:47], v[46:47], 0, s[44:45]
	v_lshl_add_u64 v[50:51], v[50:51], 0, s[4:5]
	s_waitcnt vmcnt(0) lgkmcnt(0)
	v_lshl_add_u64 v[6:7], v[6:7], 0, v[8:9]
	v_lshl_add_u64 v[70:71], v[6:7], 0, s[0:1]
	v_lshl_add_u64 v[68:69], v[6:7], 0, s[62:63]
	v_lshl_add_u64 v[4:5], v[68:69], 0, v[0:1]
	v_lshl_add_u64 v[6:7], v[70:71], 0, v[0:1]
	global_load_dwordx4 v[34:37], v[78:79], off
	global_load_dwordx4 v[10:13], v[4:5], off
	s_nop 0
	global_load_dwordx4 v[6:9], v[6:7], off
	v_lshlrev_b32_e32 v0, 1, v48
	global_load_dwordx2 v[4:5], v[60:61], off offset:280
	s_movk_i32 s0, 0x3000
	v_add_co_u32_e32 v96, vcc, s0, v78
	s_mov_b32 s0, 0x358637bd
	s_nop 0
	v_addc_co_u32_e32 v97, vcc, 0, v79, vcc
	v_mov_b64_e32 v[110:111], s[0:1]
	s_mov_b32 s0, 0x3a800000
	v_lshl_add_u64 v[72:73], v[68:69], 0, v[54:55]
	v_lshl_add_u64 v[74:75], v[70:71], 0, v[54:55]
	v_lshl_add_u64 v[64:65], v[68:69], 0, v[56:57]
	v_lshl_add_u64 v[66:67], v[70:71], 0, v[56:57]
	v_lshl_add_u64 v[68:69], v[68:69], 0, v[58:59]
	v_lshl_add_u64 v[70:71], v[70:71], 0, v[58:59]
	s_waitcnt vmcnt(0)
	v_mov_b32_e32 v24, v35
	v_mov_b32_e32 v22, v34
	v_mov_b32_e32 v18, v36
	v_mov_b32_e32 v20, v37
	s_waitcnt lgkmcnt(0)
	v_lshl_add_u64 v[2:3], v[4:5], 0, v[62:63]
	v_lshl_add_u64 v[84:85], v[2:3], 0, v[0:1]
	global_load_dwordx4 v[2:5], v[108:109], off offset:-4096
	global_load_dwordx4 v[14:17], v[108:109], off
	global_load_dwordx4 v[42:45], v[78:79], off offset:1024
	global_load_dwordx4 v[38:41], v[76:77], off offset:1024
	v_pk_add_f32 v[102:103], v[12:13], 1.0 op_sel_hi:[1,0]
	v_pk_add_f32 v[104:105], v[10:11], 1.0 op_sel_hi:[1,0]
	global_load_dwordx4 v[10:13], v[96:97], off
	s_waitcnt vmcnt(3)
	v_mov_b32_e32 v28, v15
	s_waitcnt vmcnt(2)
	v_mov_b32_e32 v25, v43
	v_mov_b32_e32 v23, v42
	v_pk_mul_f32 v[24:25], v[24:25], v[24:25]
	v_mov_b32_e32 v19, v44
	v_pk_fma_f32 v[22:23], v[22:23], v[22:23], v[24:25]
	v_mov_b32_e32 v24, v3
	s_waitcnt vmcnt(1)
	v_mov_b32_e32 v25, v39
	v_mov_b32_e32 v21, v45
	v_pk_fma_f32 v[18:19], v[18:19], v[18:19], v[22:23]
	v_mov_b32_e32 v22, v2
	v_mov_b32_e32 v23, v38
	v_pk_mul_f32 v[24:25], v[24:25], v[24:25]
	v_pk_fma_f32 v[80:81], v[20:21], v[20:21], v[18:19]
	v_mov_b32_e32 v18, v4
	v_mov_b32_e32 v19, v40
	v_pk_fma_f32 v[22:23], v[22:23], v[22:23], v[24:25]
	v_mov_b32_e32 v20, v5
	v_pk_fma_f32 v[18:19], v[18:19], v[18:19], v[22:23]
	global_load_dwordx4 v[22:25], v[108:109], off offset:1024
	v_mov_b32_e32 v21, v41
	v_mov_b32_e32 v26, v14
	v_pk_fma_f32 v[82:83], v[20:21], v[20:21], v[18:19]
	v_mov_b32_e32 v18, v16
	v_mov_b32_e32 v20, v17
	s_waitcnt vmcnt(0)
	v_mov_b32_e32 v29, v23
	v_mov_b32_e32 v27, v22
	v_pk_mul_f32 v[28:29], v[28:29], v[28:29]
	v_mov_b32_e32 v19, v24
	v_pk_fma_f32 v[26:27], v[26:27], v[26:27], v[28:29]
	v_mov_b32_e32 v21, v25
	v_pk_fma_f32 v[18:19], v[18:19], v[18:19], v[26:27]
	s_nop 0
	v_pk_fma_f32 v[98:99], v[20:21], v[20:21], v[18:19]
	global_load_dwordx4 v[18:21], v[96:97], off offset:1024
	v_mov_b32_e32 v32, v11
	v_mov_b32_e32 v30, v10
	v_mov_b32_e32 v26, v12
	v_mov_b32_e32 v28, v13
	s_waitcnt vmcnt(0)
	v_mov_b32_e32 v33, v19
	v_mov_b32_e32 v31, v18
	v_pk_mul_f32 v[32:33], v[32:33], v[32:33]
	v_mov_b32_e32 v27, v20
	v_pk_fma_f32 v[30:31], v[30:31], v[30:31], v[32:33]
	v_mov_b32_e32 v29, v21
	v_pk_fma_f32 v[26:27], v[26:27], v[26:27], v[30:31]
	s_nop 0
	v_pk_fma_f32 v[106:107], v[28:29], v[28:29], v[26:27]
	global_load_dwordx4 v[86:89], v[78:79], off offset:2048
	global_load_dwordx4 v[112:115], v[76:77], off offset:2048
	global_load_dwordx4 v[30:33], v[108:109], off offset:2048
	global_load_dwordx4 v[26:29], v[96:97], off offset:2048
	global_load_dwordx4 v[116:119], v[78:79], off offset:3072
	global_load_dwordx4 v[120:123], v[76:77], off offset:3072
	s_waitcnt vmcnt(5)
	v_mov_b32_e32 v94, v87
	v_mov_b32_e32 v92, v86
	v_mov_b32_e32 v78, v88
	v_mov_b32_e32 v90, v89
	s_waitcnt vmcnt(1)
	v_mov_b32_e32 v95, v117
	v_mov_b32_e32 v93, v116
	v_pk_mul_f32 v[94:95], v[94:95], v[94:95]
	v_mov_b32_e32 v79, v118
	v_pk_fma_f32 v[92:93], v[92:93], v[92:93], v[94:95]
	v_mov_b32_e32 v94, v113
	s_waitcnt vmcnt(0)
	v_mov_b32_e32 v95, v121
	v_pk_fma_f32 v[78:79], v[78:79], v[78:79], v[92:93]
	v_mov_b32_e32 v92, v112
	v_mov_b32_e32 v93, v120
	v_pk_mul_f32 v[94:95], v[94:95], v[94:95]
	v_mov_b32_e32 v91, v119
	v_mov_b32_e32 v76, v114
	v_mov_b32_e32 v77, v122
	v_pk_fma_f32 v[92:93], v[92:93], v[92:93], v[94:95]
	v_pk_fma_f32 v[78:79], v[90:91], v[90:91], v[78:79]
	v_mov_b32_e32 v90, v115
	v_mov_b32_e32 v91, v123
	v_pk_fma_f32 v[76:77], v[76:77], v[76:77], v[92:93]
	s_nop 0
	v_pk_fma_f32 v[76:77], v[90:91], v[90:91], v[76:77]
	v_mov_b32_e32 v90, v82
	v_mov_b32_e32 v91, v80
	v_mov_b32_e32 v80, v83
	v_pk_add_f32 v[80:81], v[90:91], v[80:81]
	v_mov_b32_e32 v82, v76
	v_mov_b32_e32 v83, v78
	v_pk_add_f32 v[80:81], v[80:81], v[82:83]
	v_mov_b32_e32 v78, v77
	v_pk_add_f32 v[76:77], v[80:81], v[78:79]
	ds_bpermute_b32 v79, v229, v77
	ds_bpermute_b32 v78, v229, v76
	s_waitcnt lgkmcnt(0)
; template <int R>
; __device__ __forceinline__ void phase_modulate(const Params& p, int l, const float* xlat, const float* xctx, int nrows, int chunk, int bskip) {
;     ...
;     float rstd[R];
; #pragma unroll
;     for (int r = 0; r < R; ++r) {
;       float ss = 0.f;
; #pragma unroll
;       for (int i = 0; i < 4; ++i) ss += v[r][i].x * v[r][i].x + v[r][i].y * v[r][i].y + v[r][i].z * v[r][i].z + v[r][i].w * v[r][i].w;
;       ss = wave_sum(ss);
;       rstd[r] = rsqrtf(ss * (1.f / 1024.f) + 1e-6f);
;     }
; #pragma unroll
;     for (int i = 0; i < 4; ++i) {
;       const int col = i * 256 + lane * 4;
;       const float4 s4 = *(const float4*)(sc + col);
;       const float4 h4 = *(const float4*)(sh + col);
; #pragma unroll
;       for (int r = 0; r < R; ++r) {
;         u32x2 pk;
;         pk.x = pack2(v[r][i].x * rstd[r] * (1.f + s4.x) + h4.x, v[r][i].y * rstd[r] * (1.f + s4.y) + h4.y);
;         pk.y = pack2(v[r][i].z * rstd[r] * (1.f + s4.z) + h4.z, v[r][i].w * rstd[r] * (1.f + s4.w) + h4.w);
;         *(u32x2*)(p.H + (size_t)(row0 + r) * DM + col) = pk;
;       }
;     }
	v_pk_add_f32 v[76:77], v[76:77], v[78:79]
	ds_bpermute_b32 v79, v230, v77
	ds_bpermute_b32 v78, v230, v76
	s_waitcnt lgkmcnt(0)
	v_pk_add_f32 v[76:77], v[76:77], v[78:79]
	ds_bpermute_b32 v79, v231, v77
	ds_bpermute_b32 v78, v231, v76
	s_waitcnt lgkmcnt(0)
	v_pk_add_f32 v[76:77], v[76:77], v[78:79]
	ds_bpermute_b32 v79, v232, v77
	ds_bpermute_b32 v78, v232, v76
	s_waitcnt lgkmcnt(0)
	v_pk_add_f32 v[76:77], v[76:77], v[78:79]
	ds_bpermute_b32 v79, v233, v77
	ds_bpermute_b32 v78, v233, v76
	s_waitcnt lgkmcnt(0)
	v_pk_add_f32 v[76:77], v[76:77], v[78:79]
	ds_bpermute_b32 v79, v234, v77
	ds_bpermute_b32 v78, v234, v76
	s_waitcnt lgkmcnt(0)
	v_pk_add_f32 v[76:77], v[76:77], v[78:79]
	s_nop 0
	v_pk_fma_f32 v[76:77], v[76:77], s[0:1], v[110:111] op_sel_hi:[1,0,0]
	s_nop 0
	v_mul_f32_e32 v49, 0x4b800000, v77
	v_cmp_gt_f32_e64 s[38:39], s85, v77
	v_cmp_gt_f32_e32 vcc, s85, v76
	s_nop 0
	v_cndmask_b32_e64 v49, v77, v49, s[38:39]
	v_rsq_f32_e32 v49, v49
	s_nop 0
	v_mul_f32_e32 v55, 0x45800000, v49
	v_cndmask_b32_e64 v78, v49, v55, s[38:39]
	v_pk_mul_f32 v[34:35], v[34:35], v[78:79] op_sel_hi:[1,0]
	v_pk_mul_f32 v[92:93], v[42:43], v[78:79] op_sel_hi:[1,0]
	v_pk_fma_f32 v[34:35], v[34:35], v[104:105], v[6:7]
	v_pk_mul_f32 v[90:91], v[44:45], v[78:79] op_sel_hi:[1,0]
	v_cvt_pk_bf16_f32 v100, v34, v35
	v_pk_mul_f32 v[34:35], v[36:37], v[78:79] op_sel_hi:[1,0]
	v_pk_mul_f32 v[82:83], v[86:87], v[78:79] op_sel_hi:[1,0]
	v_pk_fma_f32 v[34:35], v[34:35], v[102:103], v[8:9]
	v_pk_mul_f32 v[80:81], v[88:89], v[78:79] op_sel_hi:[1,0]
	v_cvt_pk_bf16_f32 v101, v34, v35
	v_mul_f32_e32 v34, 0x4b800000, v76
	v_cndmask_b32_e32 v34, v76, v34, vcc
	v_rsq_f32_e32 v34, v34
	v_pk_mul_f32 v[44:45], v[116:117], v[78:79] op_sel_hi:[1,0]
	v_pk_mul_f32 v[42:43], v[118:119], v[78:79] op_sel_hi:[1,0]
	v_mov_b32_e32 v116, v27
	v_mul_f32_e32 v35, 0x45800000, v34
	v_cndmask_b32_e32 v34, v34, v35, vcc
	v_pk_mul_f32 v[2:3], v[2:3], v[34:35] op_sel_hi:[1,0]
	v_pk_mul_f32 v[88:89], v[38:39], v[34:35] op_sel_hi:[1,0]
	v_pk_fma_f32 v[2:3], v[2:3], v[104:105], v[6:7]
	v_pk_mul_f32 v[86:87], v[40:41], v[34:35] op_sel_hi:[1,0]
	v_cvt_pk_bf16_f32 v94, v2, v3
	v_pk_mul_f32 v[2:3], v[4:5], v[34:35] op_sel_hi:[1,0]
	v_pk_mul_f32 v[78:79], v[112:113], v[34:35] op_sel_hi:[1,0]
	v_pk_mul_f32 v[76:77], v[114:115], v[34:35] op_sel_hi:[1,0]
	v_pk_mul_f32 v[40:41], v[120:121], v[34:35] op_sel_hi:[1,0]
	v_pk_mul_f32 v[38:39], v[122:123], v[34:35] op_sel_hi:[1,0]
	global_load_dwordx4 v[34:37], v[108:109], off offset:3072
	v_mov_b32_e32 v112, v31
	v_pk_fma_f32 v[2:3], v[2:3], v[102:103], v[8:9]
	v_mov_b32_e32 v108, v30
	v_cvt_pk_bf16_f32 v95, v2, v3
	v_mov_b32_e32 v2, v32
	v_mov_b32_e32 v4, v33
	v_mov_b32_e32 v114, v26
	s_waitcnt vmcnt(0)
	v_mov_b32_e32 v113, v35
	v_mov_b32_e32 v109, v34
	v_pk_mul_f32 v[112:113], v[112:113], v[112:113]
	v_mov_b32_e32 v3, v36
	v_pk_fma_f32 v[108:109], v[108:109], v[108:109], v[112:113]
	v_mov_b32_e32 v5, v37
	v_pk_fma_f32 v[2:3], v[2:3], v[2:3], v[108:109]
	v_mov_b32_e32 v112, v29
	v_pk_fma_f32 v[108:109], v[4:5], v[4:5], v[2:3]
	global_load_dwordx4 v[2:5], v[96:97], off offset:3072
	v_mov_b32_e32 v96, v28
	global_store_dwordx2 v[84:85], v[100:101], off
	s_waitcnt vmcnt(0)
	v_mov_b32_e32 v117, v3
	v_mov_b32_e32 v115, v2
	v_pk_mul_f32 v[116:117], v[116:117], v[116:117]
	v_mov_b32_e32 v97, v4
	v_pk_fma_f32 v[114:115], v[114:115], v[114:115], v[116:117]
	v_mov_b32_e32 v113, v5
	v_pk_fma_f32 v[96:97], v[96:97], v[96:97], v[114:115]
	s_nop 0
	v_pk_fma_f32 v[96:97], v[112:113], v[112:113], v[96:97]
	v_mov_b32_e32 v112, v106
	v_mov_b32_e32 v113, v98
	v_mov_b32_e32 v98, v107
	v_pk_add_f32 v[98:99], v[112:113], v[98:99]
	v_mov_b32_e32 v106, v96
	v_mov_b32_e32 v107, v108
	v_pk_add_f32 v[98:99], v[98:99], v[106:107]
	v_mov_b32_e32 v108, v97
	v_pk_add_f32 v[96:97], v[98:99], v[108:109]
	ds_bpermute_b32 v99, v229, v97
	ds_bpermute_b32 v98, v229, v96
	s_waitcnt lgkmcnt(0)
	v_pk_add_f32 v[96:97], v[96:97], v[98:99]
	ds_bpermute_b32 v99, v230, v97
	ds_bpermute_b32 v98, v230, v96
	s_waitcnt lgkmcnt(0)
	v_pk_add_f32 v[96:97], v[96:97], v[98:99]
	ds_bpermute_b32 v99, v231, v97
	ds_bpermute_b32 v98, v231, v96
	s_waitcnt lgkmcnt(0)
	v_pk_add_f32 v[96:97], v[96:97], v[98:99]
	ds_bpermute_b32 v99, v232, v97
	ds_bpermute_b32 v98, v232, v96
	s_waitcnt lgkmcnt(0)
	v_pk_add_f32 v[96:97], v[96:97], v[98:99]
	ds_bpermute_b32 v99, v233, v97
	ds_bpermute_b32 v98, v233, v96
	s_waitcnt lgkmcnt(0)
	v_pk_add_f32 v[96:97], v[96:97], v[98:99]
	ds_bpermute_b32 v99, v234, v97
	ds_bpermute_b32 v98, v234, v96
	s_waitcnt lgkmcnt(0)
	v_pk_add_f32 v[96:97], v[96:97], v[98:99]
	s_nop 0
	v_pk_fma_f32 v[108:109], v[96:97], s[0:1], v[110:111] op_sel_hi:[1,0,0]
	s_movk_i32 s0, 0xf800
	v_mul_f32_e32 v49, 0x4b800000, v109
	v_cmp_gt_f32_e64 s[38:39], s85, v109
	v_cmp_gt_f32_e32 vcc, s85, v108
	s_nop 0
	v_cndmask_b32_e64 v49, v109, v49, s[38:39]
	v_rsq_f32_e32 v49, v49
	s_nop 0
	v_mul_f32_e32 v55, 0x45800000, v49
	v_cndmask_b32_e64 v110, v49, v55, s[38:39]
	v_pk_mul_f32 v[14:15], v[14:15], v[110:111] op_sel_hi:[1,0]
	v_pk_mul_f32 v[96:97], v[24:25], v[110:111] op_sel_hi:[1,0]
	v_pk_fma_f32 v[14:15], v[104:105], v[14:15], v[6:7]
	v_pk_mul_f32 v[24:25], v[32:33], v[110:111] op_sel_hi:[1,0]
	v_cvt_pk_bf16_f32 v106, v14, v15
	v_pk_mul_f32 v[14:15], v[16:17], v[110:111] op_sel_hi:[1,0]
	v_pk_mul_f32 v[98:99], v[22:23], v[110:111] op_sel_hi:[1,0]
	v_pk_fma_f32 v[14:15], v[102:103], v[14:15], v[8:9]
	v_pk_mul_f32 v[22:23], v[34:35], v[110:111] op_sel_hi:[1,0]
	v_cvt_pk_bf16_f32 v107, v14, v15
	v_mul_f32_e32 v14, 0x4b800000, v108
	v_cndmask_b32_e32 v14, v108, v14, vcc
	v_rsq_f32_e32 v14, v14
	v_pk_mul_f32 v[30:31], v[30:31], v[110:111] op_sel_hi:[1,0]
	v_pk_mul_f32 v[16:17], v[36:37], v[110:111] op_sel_hi:[1,0]
	v_mul_f32_e32 v15, 0x45800000, v14
	v_cndmask_b32_e32 v14, v14, v15, vcc
	v_pk_mul_f32 v[10:11], v[10:11], v[14:15] op_sel_hi:[1,0]
	v_pk_mul_f32 v[2:3], v[2:3], v[14:15] op_sel_hi:[1,0]
	v_pk_fma_f32 v[6:7], v[104:105], v[10:11], v[6:7]
	v_pk_mul_f32 v[10:11], v[20:21], v[14:15] op_sel_hi:[1,0]
	v_cvt_pk_bf16_f32 v32, v6, v7
	v_pk_mul_f32 v[6:7], v[12:13], v[14:15] op_sel_hi:[1,0]
	v_pk_mul_f32 v[12:13], v[18:19], v[14:15] op_sel_hi:[1,0]
	global_load_dwordx2 v[18:19], v[60:61], off offset:280
	v_pk_fma_f32 v[6:7], v[102:103], v[6:7], v[8:9]
	v_pk_mul_f32 v[8:9], v[26:27], v[14:15] op_sel_hi:[1,0]
	v_cvt_pk_bf16_f32 v33, v6, v7
	v_pk_mul_f32 v[6:7], v[28:29], v[14:15] op_sel_hi:[1,0]
	v_pk_mul_f32 v[4:5], v[4:5], v[14:15] op_sel_hi:[1,0]
	s_waitcnt vmcnt(0) lgkmcnt(0)
; template <int R>
; __device__ __forceinline__ void phase_modulate(const Params& p, int l, const float* xlat, const float* xctx, int nrows, int chunk, int bskip) {
;     ...
; #pragma unroll
;     for (int i = 0; i < 4; ++i) {
;       const int col = i * 256 + lane * 4;
;       const float4 s4 = *(const float4*)(sc + col);
;       const float4 h4 = *(const float4*)(sh + col);
; #pragma unroll
;       for (int r = 0; r < R; ++r) {
;         u32x2 pk;
;         pk.x = pack2(v[r][i].x * rstd[r] * (1.f + s4.x) + h4.x, v[r][i].y * rstd[r] * (1.f + s4.y) + h4.y);
;         pk.y = pack2(v[r][i].z * rstd[r] * (1.f + s4.z) + h4.z, v[r][i].w * rstd[r] * (1.f + s4.w) + h4.w);
;         *(u32x2*)(p.H + (size_t)(row0 + r) * DM + col) = pk;
;       }
;     }
	v_lshl_add_u64 v[18:19], v[18:19], 0, v[52:53]
	v_add_co_u32_e32 v18, vcc, s0, v18
	s_movk_i32 s0, 0xfa00
	s_nop 0
	v_addc_co_u32_e32 v19, vcc, -1, v19, vcc
	global_store_dwordx2 v[18:19], v[94:95], off
	global_load_dwordx2 v[18:19], v[60:61], off offset:280
	s_waitcnt vmcnt(0) lgkmcnt(0)
	v_lshl_add_u64 v[18:19], v[18:19], 0, v[52:53]
	global_store_dwordx2 v[18:19], v[106:107], off
	global_load_dwordx2 v[18:19], v[60:61], off offset:280
	s_waitcnt vmcnt(0) lgkmcnt(0)
	v_lshl_add_u64 v[18:19], v[18:19], 0, v[52:53]
	global_store_dwordx2 v[18:19], v[32:33], off offset:2048
	global_load_dwordx4 v[18:21], v[72:73], off
	s_nop 0
	global_load_dwordx4 v[26:29], v[74:75], off
	s_waitcnt vmcnt(0) lgkmcnt(0)
	v_pk_add_f32 v[18:19], v[18:19], 1.0 op_sel_hi:[1,0]
	v_pk_add_f32 v[20:21], v[20:21], 1.0 op_sel_hi:[1,0]
	v_pk_fma_f32 v[32:33], v[92:93], v[18:19], v[26:27]
	v_pk_fma_f32 v[34:35], v[90:91], v[20:21], v[28:29]
	v_cvt_pk_bf16_f32 v32, v32, v33
	v_cvt_pk_bf16_f32 v33, v34, v35
	global_load_dwordx2 v[34:35], v[60:61], off offset:280
	v_pk_fma_f32 v[12:13], v[12:13], v[18:19], v[26:27]
	v_pk_fma_f32 v[10:11], v[10:11], v[20:21], v[28:29]
	v_cvt_pk_bf16_f32 v12, v12, v13
	v_cvt_pk_bf16_f32 v13, v10, v11
	s_waitcnt vmcnt(0) lgkmcnt(0)
	v_lshl_add_u64 v[34:35], v[34:35], 0, v[62:63]
	v_lshl_add_u64 v[34:35], v[34:35], 0, v[0:1]
	global_store_dwordx2 v[34:35], v[32:33], off offset:512
	v_pk_fma_f32 v[32:33], v[88:89], v[18:19], v[26:27]
	v_pk_fma_f32 v[34:35], v[86:87], v[20:21], v[28:29]
	v_cvt_pk_bf16_f32 v32, v32, v33
	v_cvt_pk_bf16_f32 v33, v34, v35
	global_load_dwordx2 v[34:35], v[60:61], off offset:280
	s_waitcnt vmcnt(0) lgkmcnt(0)
	v_lshl_add_u64 v[34:35], v[34:35], 0, v[52:53]
	v_add_co_u32_e32 v34, vcc, s0, v34
	s_movk_i32 s0, 0xfc00
	s_nop 0
	v_addc_co_u32_e32 v35, vcc, -1, v35, vcc
	global_store_dwordx2 v[34:35], v[32:33], off
	v_pk_fma_f32 v[32:33], v[98:99], v[18:19], v[26:27]
	v_pk_fma_f32 v[34:35], v[96:97], v[20:21], v[28:29]
	v_cvt_pk_bf16_f32 v32, v32, v33
	v_cvt_pk_bf16_f32 v33, v34, v35
	global_load_dwordx2 v[34:35], v[60:61], off offset:280
	s_waitcnt vmcnt(0) lgkmcnt(0)
	v_lshl_add_u64 v[34:35], v[34:35], 0, v[52:53]
	global_store_dwordx2 v[34:35], v[32:33], off offset:512
	global_load_dwordx2 v[10:11], v[60:61], off offset:280
	s_waitcnt vmcnt(0) lgkmcnt(0)
	v_lshl_add_u64 v[10:11], v[10:11], 0, v[52:53]
	global_store_dwordx2 v[10:11], v[12:13], off offset:2560
	global_load_dwordx4 v[10:13], v[64:65], off
	s_nop 0
	global_load_dwordx4 v[18:21], v[66:67], off
	s_waitcnt vmcnt(0) lgkmcnt(0)
	v_pk_add_f32 v[10:11], v[10:11], 1.0 op_sel_hi:[1,0]
	v_pk_add_f32 v[12:13], v[12:13], 1.0 op_sel_hi:[1,0]
	v_pk_fma_f32 v[26:27], v[82:83], v[10:11], v[18:19]
	v_pk_fma_f32 v[28:29], v[80:81], v[12:13], v[20:21]
	v_cvt_pk_bf16_f32 v26, v26, v27
	v_cvt_pk_bf16_f32 v27, v28, v29
	global_load_dwordx2 v[28:29], v[60:61], off offset:280
	v_pk_fma_f32 v[24:25], v[24:25], v[12:13], v[20:21]
	v_pk_fma_f32 v[8:9], v[8:9], v[10:11], v[18:19]
	v_pk_fma_f32 v[6:7], v[6:7], v[12:13], v[20:21]
	v_cvt_pk_bf16_f32 v8, v8, v9
	v_cvt_pk_bf16_f32 v9, v6, v7
	s_waitcnt vmcnt(0) lgkmcnt(0)
	v_lshl_add_u64 v[28:29], v[28:29], 0, v[62:63]
	v_lshl_add_u64 v[28:29], v[28:29], 0, v[0:1]
	global_store_dwordx2 v[28:29], v[26:27], off offset:1024
	v_pk_fma_f32 v[26:27], v[78:79], v[10:11], v[18:19]
	v_pk_fma_f32 v[28:29], v[76:77], v[12:13], v[20:21]
	v_cvt_pk_bf16_f32 v26, v26, v27
	v_cvt_pk_bf16_f32 v27, v28, v29
	global_load_dwordx2 v[28:29], v[60:61], off offset:280
	s_waitcnt vmcnt(0) lgkmcnt(0)
	v_lshl_add_u64 v[28:29], v[28:29], 0, v[52:53]
	v_add_co_u32_e32 v28, vcc, s0, v28
	s_movk_i32 s0, 0xfe00
	s_nop 0
	v_addc_co_u32_e32 v29, vcc, -1, v29, vcc
	global_store_dwordx2 v[28:29], v[26:27], off
	v_pk_fma_f32 v[26:27], v[30:31], v[10:11], v[18:19]
	s_nop 0
	v_cvt_pk_bf16_f32 v26, v26, v27
	v_cvt_pk_bf16_f32 v27, v24, v25
	global_load_dwordx2 v[24:25], v[60:61], off offset:280
	s_waitcnt vmcnt(0) lgkmcnt(0)
	v_lshl_add_u64 v[24:25], v[24:25], 0, v[52:53]
	global_store_dwordx2 v[24:25], v[26:27], off offset:1024
	global_load_dwordx2 v[6:7], v[60:61], off offset:280
	s_waitcnt vmcnt(0) lgkmcnt(0)
	v_lshl_add_u64 v[6:7], v[6:7], 0, v[52:53]
	global_store_dwordx2 v[6:7], v[8:9], off offset:3072
	global_load_dwordx4 v[6:9], v[68:69], off
	s_nop 0
	global_load_dwordx4 v[10:13], v[70:71], off
	s_waitcnt vmcnt(0) lgkmcnt(0)
	v_pk_add_f32 v[6:7], v[6:7], 1.0 op_sel_hi:[1,0]
	v_pk_add_f32 v[8:9], v[8:9], 1.0 op_sel_hi:[1,0]
	v_pk_fma_f32 v[18:19], v[44:45], v[6:7], v[10:11]
	v_pk_fma_f32 v[20:21], v[42:43], v[8:9], v[12:13]
	v_cvt_pk_bf16_f32 v18, v18, v19
	v_cvt_pk_bf16_f32 v19, v20, v21
	global_load_dwordx2 v[20:21], v[60:61], off offset:280
	v_pk_fma_f32 v[16:17], v[16:17], v[8:9], v[12:13]
	v_pk_fma_f32 v[2:3], v[2:3], v[6:7], v[10:11]
	v_pk_fma_f32 v[4:5], v[4:5], v[8:9], v[12:13]
	v_cvt_pk_bf16_f32 v2, v2, v3
	v_cvt_pk_bf16_f32 v3, v4, v5
	s_waitcnt vmcnt(0) lgkmcnt(0)
	v_lshl_add_u64 v[20:21], v[20:21], 0, v[62:63]
	v_lshl_add_u64 v[20:21], v[20:21], 0, v[0:1]
	global_store_dwordx2 v[20:21], v[18:19], off offset:1536
	v_pk_fma_f32 v[18:19], v[40:41], v[6:7], v[10:11]
	v_pk_fma_f32 v[20:21], v[38:39], v[8:9], v[12:13]
	v_cvt_pk_bf16_f32 v18, v18, v19
	v_cvt_pk_bf16_f32 v19, v20, v21
	global_load_dwordx2 v[20:21], v[60:61], off offset:280
	s_waitcnt vmcnt(0) lgkmcnt(0)
	v_lshl_add_u64 v[20:21], v[20:21], 0, v[52:53]
	v_add_co_u32_e32 v20, vcc, s0, v20
	s_nop 1
	v_addc_co_u32_e32 v21, vcc, -1, v21, vcc
	global_store_dwordx2 v[20:21], v[18:19], off
	v_pk_fma_f32 v[18:19], v[22:23], v[6:7], v[10:11]
	v_cmp_le_i32_e32 vcc, s37, v46
	v_cvt_pk_bf16_f32 v18, v18, v19
	v_cvt_pk_bf16_f32 v19, v16, v17
	global_load_dwordx2 v[16:17], v[60:61], off offset:280
	s_or_b64 s[48:49], vcc, s[48:49]
	s_waitcnt vmcnt(0) lgkmcnt(0)
	v_lshl_add_u64 v[16:17], v[16:17], 0, v[52:53]
	global_store_dwordx2 v[16:17], v[18:19], off offset:1536
	global_load_dwordx2 v[4:5], v[60:61], off offset:280
	s_waitcnt vmcnt(0) lgkmcnt(0)
	v_lshl_add_u64 v[4:5], v[4:5], 0, v[52:53]
	v_lshl_add_u64 v[52:53], v[52:53], 0, s[46:47]
	global_store_dwordx2 v[4:5], v[2:3], off offset:3584
	s_andn2_b64 exec, exec, s[48:49]
	s_cbranch_execz .LBB0_1045

; __device__ __forceinline__ int tid_() { int t = threadIdx.x; asm volatile("" : "+v"(t)); return t; }
; template <int NT, bool BKN, bool MASK = false, bool ROWSS = false, class Epi> ...
;     ...
;   const int t = tid_(), lane = t & 63, wid = t >> 6, wr = wid >> 1, wc = wid & 1, l16 = lane & 15, quad = lane >> 4;
;   const u16* ap[4];
;   const u16* bp[NT];
;   unsigned amask = 0u;
; #pragma unroll
;   for (int i = 0; i < 4; ++i) {
;     const int row = (t >> 3) + 32 * i;
;     const bool v = MASK ? (row < mvalid) : true;
;     amask |= v ? (1u << i) : 0u;
;     int r = v ? row : 0;
;     if (arows) r = arows[r];
;     ap[i] = A + (size_t)r * lda + (t & 7) * 8;
;   }
; #pragma unroll
;   for (int i = 0; i < NT; ++i) {
;     if (!BKN) bp[i] = B + (size_t)((t >> 3) + 32 * i) * ldb + (t & 7) * 8;
;     else { const int c = t + 256 * i; bp[i] = B + (size_t)(c / CPR) * ldb + (c % CPR) * 8; }
;   }
;   const size_t bstep = BKN ? (size_t)64 * ldb : (size_t)64;
;   int nmi = 4;
;   if (MASK) { nmi = (mvalid - wr * 64 + 15) >> 4; nmi = nmi < 0 ? 0 : (nmi > 4 ? 4 : nmi); nmi = __builtin_amdgcn_readfirstlane(nmi); }
;   u32x4 ra0[4], rb0[NT], ra1[4], rb1[NT];
; __device__ __forceinline__ void phase_moe_up(const Params& p, int l, bool last, unsigned char* smem) {
;     ...
;     int inst, mt, nt, mvalid, hid_row;
;     if (pass == npass - 1) { const int e_ = t >> 7, b_ = (t >> 6) & 1; inst = b_ * 16 + e_; mt = (t >> 3) & 7; nt = t & 7; mvalid = 128; hid_row = inst * 1024 + mt * 128; }
;     else { const int e_ = t >> 4, b_ = (t >> 3) & 1; inst = 32 + b_ * 16 + e_; mt = 0; nt = t & 7; mvalid = 32; hid_row = 32768 + (inst - 32) * 128; }
;     const int e = inst & 15;
;     const u16* W = p.WguT + (size_t)(l * 16 + e) * 1024 * 1024 + (size_t)nt * 128 * 1024;
.LBB0_1107:
	v_mov_b64_e32 v[2:3], s[4:5]
	global_load_dwordx2 v[158:159], v[2:3], off offset:224
	global_load_dwordx2 v[160:161], v[2:3], off offset:280
	s_nop 0
	global_load_dwordx2 v[2:3], v[2:3], off offset:408
	s_lshl_b32 s9, s38, 20
	s_and_b32 s9, s9, 0xf00000
	s_and_b32 s83, s64, 7
	s_or_b32 s94, s9, s18
	s_ashr_i32 s39, s38, 31
	s_lshl_b64 s[38:39], s[38:39], 12
	s_and_b32 s8, s65, 7
	s_lshl_b32 s8, s8, 18
	s_and_b64 vcc, exec, s[34:35]
	s_waitcnt vmcnt(0) lgkmcnt(0)
	v_lshl_add_u64 v[4:5], s[94:95], 1, v[158:159]
	s_lshl_b32 s94, s83, 18
	v_lshl_add_u64 v[162:163], v[4:5], 0, s[94:95]
	v_lshl_add_u64 v[4:5], v[2:3], 0, s[38:39]
	s_lshl_b32 s94, s40, 2
	v_lshl_add_u64 v[164:165], v[4:5], 0, s[94:95]
	v_cmp_ne_u64_e64 s[38:39], 0, v[2:3]
	s_mov_b64 s[40:41], -1
	s_cbranch_vccz .LBB0_1150
	v_mov_b32_e32 v18, v187
	s_nop 0
	v_ashrrev_i32_e32 v10, 3, v18
	v_cmp_gt_i32_e64 s[40:41], s86, v10
	s_nop 1
	v_cndmask_b32_e64 v2, 0, v10, s[40:41]
	s_and_saveexec_b64 s[0:1], s[38:39]
	s_cbranch_execz .LBB0_1110
	v_ashrrev_i32_e32 v3, 31, v2
	v_lshl_add_u64 v[2:3], v[2:3], 2, v[164:165]
	global_load_dword v2, v[2:3], off
.LBB0_1110:
	s_or_b64 exec, exec, s[0:1]
	v_add_u32_e32 v12, 32, v10
	v_cmp_gt_i32_e64 s[42:43], s86, v12
	s_nop 1
	v_cndmask_b32_e64 v4, 0, v12, s[42:43]
	s_and_saveexec_b64 s[0:1], s[38:39]
	s_cbranch_execz .LBB0_1112
	v_ashrrev_i32_e32 v5, 31, v4
	v_lshl_add_u64 v[4:5], v[4:5], 2, v[164:165]
	global_load_dword v4, v[4:5], off
.LBB0_1112:
	s_or_b64 exec, exec, s[0:1]
	v_add_u32_e32 v14, 64, v10
	v_cmp_gt_i32_e64 s[44:45], s86, v14
	s_nop 1
	v_cndmask_b32_e64 v6, 0, v14, s[44:45]
	s_and_saveexec_b64 s[0:1], s[38:39]
	s_cbranch_execz .LBB0_1114
	v_ashrrev_i32_e32 v7, 31, v6
	v_lshl_add_u64 v[6:7], v[6:7], 2, v[164:165]
	global_load_dword v6, v[6:7], off
.LBB0_1114:
	s_or_b64 exec, exec, s[0:1]
	v_add_u32_e32 v16, 0x60, v10
	v_cmp_gt_i32_e64 s[46:47], s86, v16
	s_nop 1
	v_cndmask_b32_e64 v8, 0, v16, s[46:47]
	s_and_saveexec_b64 s[0:1], s[38:39]
	s_cbranch_execz .LBB0_1116
	v_ashrrev_i32_e32 v9, 31, v8
	v_lshl_add_u64 v[8:9], v[8:9], 2, v[164:165]
	global_load_dword v8, v[8:9], off
.LBB0_1116:
	s_or_b64 exec, exec, s[0:1]
	v_lshlrev_b32_e32 v19, 4, v18
	v_and_b32_e32 v0, 0x70, v19
	s_waitcnt vmcnt(0) lgkmcnt(0)
	v_ashrrev_i32_e32 v3, 31, v2
	v_lshl_add_u64 v[32:33], v[160:161], 0, v[0:1]
	v_lshlrev_b64 v[2:3], 11, v[2:3]
	v_ashrrev_i32_e32 v5, 31, v4
	v_ashrrev_i32_e32 v7, 31, v6
	v_ashrrev_i32_e32 v9, 31, v8
	v_lshl_add_u64 v[166:167], v[32:33], 0, v[2:3]
	v_lshlrev_b64 v[4:5], 11, v[4:5]
	v_lshlrev_b64 v[6:7], 11, v[6:7]
	v_lshlrev_b64 v[8:9], 11, v[8:9]
	s_barrier
	global_load_dwordx4 v[20:23], v[166:167], off
	v_lshl_add_u64 v[168:169], v[32:33], 0, v[4:5]
	v_lshl_add_u64 v[170:171], v[32:33], 0, v[6:7]
	v_lshl_add_u64 v[172:173], v[32:33], 0, v[8:9]
	global_load_dwordx4 v[24:27], v[168:169], off
	global_load_dwordx4 v[28:31], v[170:171], off
	global_load_dwordx4 v[32:35], v[172:173], off
	global_load_dwordx4 v[36:39], v[166:167], off offset:128
	global_load_dwordx4 v[40:43], v[168:169], off offset:128
	global_load_dwordx4 v[44:47], v[170:171], off offset:128
	global_load_dwordx4 v[48:51], v[172:173], off offset:128
	v_ashrrev_i32_e32 v11, 31, v10
	v_ashrrev_i32_e32 v13, 31, v12
	v_ashrrev_i32_e32 v15, 31, v14
	v_ashrrev_i32_e32 v17, 31, v16
	v_lshlrev_b64 v[64:65], 11, v[10:11]
	v_lshlrev_b64 v[10:11], 11, v[12:13]
	v_lshlrev_b64 v[12:13], 11, v[14:15]
	v_lshlrev_b64 v[14:15], 11, v[16:17]
	v_lshl_add_u64 v[16:17], v[162:163], 0, v[0:1]
	v_lshrrev_b32_e32 v0, 4, v18
	v_ashrrev_i32_e32 v66, 1, v18
	v_and_b32_e32 v197, 0xffffffc0, v66
	v_lshl_add_u64 v[174:175], v[16:17], 0, v[64:65]
	v_sub_u32_e32 v66, s86, v197
	v_and_b32_e32 v19, 0xffffff80, v19
	v_lshl_add_u64 v[176:177], v[16:17], 0, v[10:11]
	v_lshl_add_u64 v[178:179], v[16:17], 0, v[12:13]
	v_lshl_add_u64 v[180:181], v[16:17], 0, v[14:15]
	global_load_dwordx4 v[10:13], v[174:175], off
	global_load_dwordx4 v[14:17], v[176:177], off
	global_load_dwordx4 v[52:55], v[178:179], off
	global_load_dwordx4 v[56:59], v[180:181], off
	global_load_dwordx4 v[60:63], v[166:167], off offset:256
	global_load_dwordx4 v[102:105], v[168:169], off offset:256
	global_load_dwordx4 v[106:109], v[170:171], off offset:256
	global_load_dwordx4 v[122:125], v[172:173], off offset:256
	v_ashrrev_i32_e32 v66, 4, v66
	v_med3_i32 v74, v66, 0, 4
	global_load_dwordx4 v[66:69], v[174:175], off offset:128
	global_load_dwordx4 v[70:73], v[178:179], off offset:128
	v_readfirstlane_b32 s48, v74
	s_cmp_gt_i32 s48, 0
	s_cselect_b64 s[56:57], -1, 0
	s_cmp_gt_i32 s48, 1
	s_cselect_b64 s[0:1], -1, 0
	s_cmp_gt_i32 s48, 2
	v_and_b32_e32 v194, 15, v18
	s_cselect_b64 s[58:59], -1, 0
	s_cmp_gt_i32 s48, 3
	s_cselect_b64 s[60:61], -1, 0
	s_add_i32 s94, s18, s9
	v_bfe_u32 v196, v18, 4, 2
	s_lshl_b64 s[48:49], s[94:95], 1
	s_add_u32 s48, s48, s8
	s_addc_u32 s49, s49, 0
	v_lshrrev_b32_e32 v195, 6, v18
	s_mov_b32 s87, -2
	s_waitcnt vmcnt(0) lgkmcnt(0)
; template <int NT, bool BKN, bool MASK = false, bool ROWSS = false, class Epi> ...
;     ...
; #pragma unroll
;   for (int i = 0; i < 4; ++i)
; #pragma unroll
;     for (int j = 0; j < NT; ++j) acc[i][j] = (f32x4){0.f, 0.f, 0.f, 0.f};
;   const int nk = K >> 6;
;   const int nkm1 = nk - 1;
;   __syncthreads();
;   GEMM_LOAD(ra0, rb0, 0);
;   GEMM_LOAD(ra1, rb1, 1);
;   GEMM_STORE(ra0, rb0, 0);
;   GEMM_LOAD(ra0, rb0, (2 < nkm1 ? 2 : nkm1));
;   __syncthreads();
	v_cndmask_b32_e64 v23, 0, v23, s[40:41]
	v_cndmask_b32_e64 v22, 0, v22, s[40:41]
	v_cndmask_b32_e64 v21, 0, v21, s[40:41]
	v_cndmask_b32_e64 v82, 0, v36, s[40:41]
	v_xor_b32_e32 v36, v0, v18
	v_lshlrev_b32_e32 v36, 4, v36
	v_cndmask_b32_e64 v20, 0, v20, s[40:41]
	v_and_or_b32 v200, v36, s14, v19
	v_cndmask_b32_e64 v27, 0, v27, s[42:43]
	v_cndmask_b32_e64 v26, 0, v26, s[42:43]
	v_cndmask_b32_e64 v25, 0, v25, s[42:43]
	v_cndmask_b32_e64 v24, 0, v24, s[42:43]
	v_cndmask_b32_e64 v31, 0, v31, s[44:45]
	v_cndmask_b32_e64 v30, 0, v30, s[44:45]
	v_cndmask_b32_e64 v29, 0, v29, s[44:45]
	v_cndmask_b32_e64 v28, 0, v28, s[44:45]
	ds_write_b128 v200, v[20:23]
	ds_write_b128 v200, v[24:27] offset:4096
	ds_write_b128 v200, v[28:31] offset:8192
	global_load_dwordx4 v[110:113], v[174:175], off offset:256
	global_load_dwordx4 v[74:77], v[176:177], off offset:128
	global_load_dwordx4 v[114:117], v[176:177], off offset:256
	global_load_dwordx4 v[118:121], v[178:179], off offset:256
	global_load_dwordx4 v[78:81], v[180:181], off offset:128
	global_load_dwordx4 v[126:129], v[180:181], off offset:256
	v_cndmask_b32_e64 v35, 0, v35, s[46:47]
	v_cndmask_b32_e64 v34, 0, v34, s[46:47]
	v_cndmask_b32_e64 v33, 0, v33, s[46:47]
	v_cndmask_b32_e64 v32, 0, v32, s[46:47]
	ds_write_b128 v200, v[32:35] offset:12288
	ds_write_b128 v200, v[10:13] offset:16384
	ds_write_b128 v200, v[14:17] offset:20480
	ds_write_b128 v200, v[52:55] offset:24576
	ds_write_b128 v200, v[56:59] offset:28672
	v_bfe_u32 v11, v18, 1, 3
	v_lshlrev_b32_e32 v12, 7, v18
	v_or_b32_e32 v10, v197, v194
	v_bitop3_b32 v0, v0, v11, 3 bitop3:0x6c
	v_and_b32_e32 v12, 0x2000, v12
	v_lshlrev_b32_e32 v0, 4, v0
	v_lshlrev_b32_e32 v10, 7, v10
	v_lshl_or_b32 v12, v194, 7, v12
	v_or_b32_e32 v201, v0, v10
	v_or_b32_e32 v202, v0, v12
	v_bitop3_b32 v0, v196, v11, 4 bitop3:0x36
	v_lshlrev_b32_e32 v0, 4, v0
	v_or_b32_e32 v198, v0, v10
	v_lshl_add_u64 v[10:11], s[48:49], 0, v[64:65]
	v_lshl_add_u64 v[182:183], v[158:159], 0, v[10:11]
	v_lshl_add_u64 v[10:11], v[160:161], 0, s[30:31]
	v_lshl_add_u64 v[190:191], v[10:11], 0, v[4:5]
	v_mov_b32_e32 v4, v1
	v_mov_b32_e32 v5, v1
	v_cndmask_b32_e64 v85, 0, v39, s[40:41]
	v_cndmask_b32_e64 v84, 0, v38, s[40:41]
	v_cndmask_b32_e64 v83, 0, v37, s[40:41]
	v_cndmask_b32_e64 v89, 0, v43, s[42:43]
	v_cndmask_b32_e64 v88, 0, v42, s[42:43]
	v_cndmask_b32_e64 v87, 0, v41, s[42:43]
	v_cndmask_b32_e64 v86, 0, v40, s[42:43]
	v_cndmask_b32_e64 v93, 0, v47, s[44:45]
	v_cndmask_b32_e64 v92, 0, v46, s[44:45]
	v_cndmask_b32_e64 v91, 0, v45, s[44:45]
	v_cndmask_b32_e64 v90, 0, v44, s[44:45]
	v_cndmask_b32_e64 v97, 0, v51, s[46:47]
	v_cndmask_b32_e64 v96, 0, v50, s[46:47]
	v_cndmask_b32_e64 v95, 0, v49, s[46:47]
	v_cndmask_b32_e64 v94, 0, v48, s[46:47]
	v_cndmask_b32_e64 v101, 0, v63, s[40:41]
	v_cndmask_b32_e64 v100, 0, v62, s[40:41]
	v_cndmask_b32_e64 v99, 0, v61, s[40:41]
	v_cndmask_b32_e64 v98, 0, v60, s[40:41]
	v_or_b32_e32 v199, v0, v12
	v_and_b32_e32 v0, 7, v18
	v_lshl_add_u64 v[184:185], v[10:11], 0, v[8:9]
	v_lshl_add_u64 v[188:189], v[10:11], 0, v[6:7]
	v_lshl_add_u64 v[192:193], v[10:11], 0, v[2:3]
	v_mov_b32_e32 v2, v1
	v_mov_b32_e32 v3, v1
	v_mov_b64_e32 v[8:9], v[4:5]
	v_mov_b64_e32 v[12:13], v[4:5]
	v_mov_b64_e32 v[16:17], v[4:5]
	v_mov_b64_e32 v[20:21], v[4:5]
	v_mov_b64_e32 v[24:25], v[4:5]
	v_mov_b64_e32 v[28:29], v[4:5]
	v_mov_b64_e32 v[32:33], v[4:5]
	v_mov_b64_e32 v[36:37], v[4:5]
	v_mov_b64_e32 v[40:41], v[4:5]
	v_mov_b64_e32 v[44:45], v[4:5]
	v_mov_b64_e32 v[48:49], v[4:5]
	v_mov_b64_e32 v[52:53], v[4:5]
	v_mov_b64_e32 v[56:57], v[4:5]
	v_mov_b64_e32 v[60:61], v[4:5]
	v_mov_b64_e32 v[64:65], v[4:5]
	v_cndmask_b32_e64 v105, 0, v105, s[42:43]
	v_cndmask_b32_e64 v104, 0, v104, s[42:43]
	v_cndmask_b32_e64 v103, 0, v103, s[42:43]
	v_cndmask_b32_e64 v102, 0, v102, s[42:43]
	v_cndmask_b32_e64 v109, 0, v109, s[44:45]
	v_cndmask_b32_e64 v108, 0, v108, s[44:45]
	v_cndmask_b32_e64 v107, 0, v107, s[44:45]
	v_cndmask_b32_e64 v106, 0, v106, s[44:45]
	v_cndmask_b32_e64 v125, 0, v125, s[46:47]
	v_cndmask_b32_e64 v124, 0, v124, s[46:47]
	v_cndmask_b32_e64 v123, 0, v123, s[46:47]
	v_cndmask_b32_e64 v122, 0, v122, s[46:47]
	v_lshlrev_b32_e32 v0, 4, v0
	v_mov_b64_e32 v[6:7], v[2:3]
	v_mov_b64_e32 v[10:11], v[2:3]
	v_mov_b64_e32 v[14:15], v[2:3]
	v_mov_b64_e32 v[18:19], v[2:3]
	v_mov_b64_e32 v[22:23], v[2:3]
	v_mov_b64_e32 v[26:27], v[2:3]
	v_mov_b64_e32 v[30:31], v[2:3]
	v_mov_b64_e32 v[34:35], v[2:3]
	v_mov_b64_e32 v[38:39], v[2:3]
	v_mov_b64_e32 v[42:43], v[2:3]
	v_mov_b64_e32 v[46:47], v[2:3]
	v_mov_b64_e32 v[50:51], v[2:3]
	v_mov_b64_e32 v[54:55], v[2:3]
	v_mov_b64_e32 v[58:59], v[2:3]
	v_mov_b64_e32 v[62:63], v[2:3]
	s_waitcnt lgkmcnt(0)
	s_barrier
	s_branch .LBB0_1118
; template <int NT, bool BKN, bool MASK = false, bool ROWSS = false, class Epi> ...
;     ...
;   for (int kt = 0; kt < nk - 2; kt += 2) {
;     GEMM_COMPUTE(0);
;     GEMM_STORE(ra1, rb1, 1);
;     GEMM_LOAD(ra1, rb1, kt + 3);
;     __syncthreads();
;     GEMM_COMPUTE(1);
;     GEMM_STORE(ra0, rb0, 0);
;     GEMM_LOAD(ra0, rb0, (kt + 4 < nkm1 ? kt + 4 : nkm1));
;     __syncthreads();
;   }
.LBB0_1117:
	s_add_i32 s87, s87, 2
	s_min_u32 s88, s87, 11
	s_lshl_b32 s94, s88, 7
	ds_write_b128 v200, v[98:101]
	ds_write_b128 v200, v[102:105] offset:4096
	ds_write_b128 v200, v[106:109] offset:8192
	ds_write_b128 v200, v[122:125] offset:12288
	ds_write_b128 v200, v[110:113] offset:16384
	ds_write_b128 v200, v[114:117] offset:20480
	ds_write_b128 v200, v[118:121] offset:24576
	ds_write_b128 v200, v[126:129] offset:28672
	v_lshl_add_u64 v[106:107], v[170:171], 0, s[94:95]
	v_lshl_add_u64 v[110:111], v[172:173], 0, s[94:95]
	global_load_dwordx4 v[106:109], v[106:107], off offset:512
	v_lshl_add_u64 v[98:99], v[166:167], 0, s[94:95]
	global_load_dwordx4 v[110:113], v[110:111], off offset:512
	v_lshl_add_u64 v[102:103], v[168:169], 0, s[94:95]
	global_load_dwordx4 v[98:101], v[98:99], off offset:512
	v_lshl_add_u64 v[114:115], v[176:177], 0, s[94:95]
	global_load_dwordx4 v[102:105], v[102:103], off offset:512
	v_lshl_add_u64 v[118:119], v[178:179], 0, s[94:95]
	v_lshl_add_u64 v[126:127], v[180:181], 0, s[94:95]
	global_load_dwordx4 v[118:121], v[118:119], off offset:512
	s_waitcnt vmcnt(0) lgkmcnt(0)
	v_cndmask_b32_e64 v85, 0, v145, s[40:41]
	global_load_dwordx4 v[126:129], v[126:127], off offset:512
	v_cndmask_b32_e64 v84, 0, v144, s[40:41]
	v_cndmask_b32_e64 v83, 0, v143, s[40:41]
	v_cndmask_b32_e64 v82, 0, v142, s[40:41]
	v_cndmask_b32_e64 v89, 0, v141, s[42:43]
	v_cndmask_b32_e64 v88, 0, v140, s[42:43]
	v_cndmask_b32_e64 v87, 0, v139, s[42:43]
	v_cndmask_b32_e64 v86, 0, v138, s[42:43]
	v_cndmask_b32_e64 v93, 0, v137, s[44:45]
	v_cndmask_b32_e64 v92, 0, v136, s[44:45]
	v_cndmask_b32_e64 v91, 0, v135, s[44:45]
	v_cndmask_b32_e64 v90, 0, v134, s[44:45]
	v_cndmask_b32_e64 v97, 0, v133, s[46:47]
	v_cndmask_b32_e64 v96, 0, v132, s[46:47]
	v_cndmask_b32_e64 v95, 0, v131, s[46:47]
	v_cndmask_b32_e64 v94, 0, v130, s[46:47]
	v_lshl_add_u64 v[182:183], v[182:183], 0, s[6:7]
	v_lshl_add_u64 v[184:185], v[184:185], 0, s[6:7]
	v_lshl_add_u64 v[188:189], v[188:189], 0, s[6:7]
	v_lshl_add_u64 v[190:191], v[190:191], 0, s[6:7]
	v_lshl_add_u64 v[192:193], v[192:193], 0, s[6:7]
	s_cmp_gt_u32 s87, 11
	global_load_dwordx4 v[114:117], v[114:115], off offset:512
	v_cndmask_b32_e64 v109, 0, v109, s[44:45]
	v_cndmask_b32_e64 v108, 0, v108, s[44:45]
	v_cndmask_b32_e64 v123, 0, v111, s[46:47]
	v_cndmask_b32_e64 v122, 0, v110, s[46:47]
	v_lshl_add_u64 v[110:111], v[174:175], 0, s[94:95]
	v_cndmask_b32_e64 v125, 0, v113, s[46:47]
	v_cndmask_b32_e64 v124, 0, v112, s[46:47]
	global_load_dwordx4 v[110:113], v[110:111], off offset:512
	v_cndmask_b32_e64 v101, 0, v101, s[40:41]
	v_cndmask_b32_e64 v100, 0, v100, s[40:41]
	v_cndmask_b32_e64 v99, 0, v99, s[40:41]
	v_cndmask_b32_e64 v98, 0, v98, s[40:41]
	v_cndmask_b32_e64 v105, 0, v105, s[42:43]
	v_cndmask_b32_e64 v104, 0, v104, s[42:43]
	v_cndmask_b32_e64 v103, 0, v103, s[42:43]
	v_cndmask_b32_e64 v102, 0, v102, s[42:43]
	v_cndmask_b32_e64 v107, 0, v107, s[44:45]
	v_cndmask_b32_e64 v106, 0, v106, s[44:45]
	s_waitcnt lgkmcnt(0)
	s_barrier
	s_cbranch_scc1 .LBB0_1170

.LBB0_1130:
	ds_write_b128 v200, v[66:69] offset:49152
	s_waitcnt vmcnt(0)
	ds_write_b128 v200, v[74:77] offset:53248
	ds_write_b128 v200, v[70:73] offset:57344
	ds_write_b128 v200, v[78:81] offset:61440
	v_lshl_add_u64 v[66:67], v[192:193], 0, v[0:1]
	s_waitcnt lgkmcnt(5)
	global_load_dwordx4 v[142:145], v[66:67], off
	v_lshl_add_u64 v[66:67], v[190:191], 0, v[0:1]
	v_lshl_add_u64 v[70:71], v[182:183], 0, v[0:1]
	global_load_dwordx4 v[138:141], v[66:67], off
	v_lshl_add_u64 v[66:67], v[188:189], 0, v[0:1]
	v_add_co_u32_e32 v72, vcc, s15, v70
	global_load_dwordx4 v[134:137], v[66:67], off
	v_lshl_add_u64 v[66:67], v[184:185], 0, v[0:1]
	v_addc_co_u32_e32 v73, vcc, 0, v71, vcc
	global_load_dwordx4 v[130:133], v[66:67], off
	s_nop 0
	global_load_dwordx4 v[66:69], v[70:71], off offset:384
	global_load_dwordx4 v[74:77], v[72:73], off offset:384
	v_add_co_u32_e32 v72, vcc, s16, v70
	s_nop 1
	v_addc_co_u32_e32 v73, vcc, 0, v71, vcc
	v_add_co_u32_e32 v78, vcc, 0x30000, v70
	s_nop 1
	v_addc_co_u32_e32 v79, vcc, 0, v71, vcc
	global_load_dwordx4 v[70:73], v[72:73], off offset:384
	s_nop 0
	global_load_dwordx4 v[78:81], v[78:79], off offset:384
	ds_write_b128 v200, v[82:85] offset:32768
	ds_write_b128 v200, v[86:89] offset:36864
	ds_write_b128 v200, v[90:93] offset:40960
	ds_write_b128 v200, v[94:97] offset:45056
	s_waitcnt lgkmcnt(0)
	s_barrier
	ds_read_b128 v[154:157], v201 offset:34816
	ds_read_b128 v[150:153], v201 offset:36864
	ds_read_b128 v[82:85], v201 offset:38912
	ds_read_b128 v[86:89], v202 offset:49152
	ds_read_b128 v[90:93], v202 offset:51200
	ds_read_b128 v[94:97], v202 offset:53248
	ds_read_b128 v[146:149], v202 offset:55296
	s_and_b64 vcc, exec, s[54:55]
	s_cbranch_vccnz .LBB0_1132
	ds_read_b128 v[204:207], v201 offset:32768
	s_waitcnt lgkmcnt(0)
	v_mfma_f32_16x16x32_bf16 v[62:65], v[204:207], v[86:89], v[62:65]
	v_mfma_f32_16x16x32_bf16 v[58:61], v[204:207], v[90:93], v[58:61]
	v_mfma_f32_16x16x32_bf16 v[54:57], v[204:207], v[94:97], v[54:57]
	v_mfma_f32_16x16x32_bf16 v[50:53], v[204:207], v[146:149], v[50:53]

; __device__ __forceinline__ int tid_() { int t = threadIdx.x; asm volatile("" : "+v"(t)); return t; }
; template <int NT, bool BKN, bool MASK = false, bool ROWSS = false, class Epi> ...
;     ...
;   const int t = tid_(), lane = t & 63, wid = t >> 6, wr = wid >> 1, wc = wid & 1, l16 = lane & 15, quad = lane >> 4;
;   const u16* ap[4];
;   const u16* bp[NT];
;   unsigned amask = 0u;
; #pragma unroll
;   for (int i = 0; i < 4; ++i) {
;     const int row = (t >> 3) + 32 * i;
;     const bool v = MASK ? (row < mvalid) : true;
;     amask |= v ? (1u << i) : 0u;
;     int r = v ? row : 0;
;     if (arows) r = arows[r];
;     ap[i] = A + (size_t)r * lda + (t & 7) * 8;
;   }
; #pragma unroll
;   for (int i = 0; i < NT; ++i) {
;     if (!BKN) bp[i] = B + (size_t)((t >> 3) + 32 * i) * ldb + (t & 7) * 8;
;     else { const int c = t + 256 * i; bp[i] = B + (size_t)(c / CPR) * ldb + (c % CPR) * 8; }
;   }
;   const size_t bstep = BKN ? (size_t)64 * ldb : (size_t)64;
;   int nmi = 4;
;   if (MASK) { nmi = (mvalid - wr * 64 + 15) >> 4; nmi = nmi < 0 ? 0 : (nmi > 4 ? 4 : nmi); nmi = __builtin_amdgcn_readfirstlane(nmi); }
;   u32x4 ra0[4], rb0[NT], ra1[4], rb1[NT];
;     ...
;   float ss_[4] = {0.f, 0.f, 0.f, 0.f};
;   int stk_ = 0;
;   f32x4 acc[4][NT];
; #pragma unroll
;   for (int i = 0; i < 4; ++i)
; #pragma unroll
;     for (int j = 0; j < NT; ++j) acc[i][j] = (f32x4){0.f, 0.f, 0.f, 0.f};
;   const int nk = K >> 6;
;   const int nkm1 = nk - 1;
;   __syncthreads();
;   GEMM_LOAD(ra0, rb0, 0);
;   GEMM_LOAD(ra1, rb1, 1);
;   GEMM_STORE(ra0, rb0, 0);
;   GEMM_LOAD(ra0, rb0, (2 < nkm1 ? 2 : nkm1));
;   __syncthreads();
.LBB0_1150:
	s_and_b64 vcc, exec, s[40:41]
	s_cbranch_vccz .LBB0_1201
	v_mov_b32_e32 v68, v187
	s_nop 0
	v_ashrrev_i32_e32 v66, 3, v68
	v_ashrrev_i32_e32 v67, 31, v66
	v_mov_b32_e32 v4, v66
	s_and_saveexec_b64 s[0:1], s[38:39]
	s_cbranch_execz .LBB0_1153
	v_lshl_add_u64 v[2:3], v[66:67], 2, v[164:165]
	global_load_dword v4, v[2:3], off
.LBB0_1153:
	s_or_b64 exec, exec, s[0:1]
	v_add_u32_e32 v2, 32, v66
	v_mov_b32_e32 v8, v2
	s_and_saveexec_b64 s[0:1], s[38:39]
	s_cbranch_execz .LBB0_1155
	v_lshl_add_u64 v[6:7], v[66:67], 2, v[164:165]
	global_load_dword v8, v[6:7], off offset:128
.LBB0_1155:
	s_or_b64 exec, exec, s[0:1]
	v_add_u32_e32 v6, 64, v66
	v_mov_b32_e32 v10, v6
	s_and_saveexec_b64 s[0:1], s[38:39]
	s_cbranch_execz .LBB0_1157
	v_lshl_add_u64 v[10:11], v[66:67], 2, v[164:165]
	global_load_dword v10, v[10:11], off offset:256
.LBB0_1157:
	s_or_b64 exec, exec, s[0:1]
	s_and_saveexec_b64 s[0:1], s[38:39]
	s_xor_b64 s[0:1], exec, s[0:1]
	s_cbranch_execz .LBB0_1159
	v_lshl_add_u64 v[12:13], v[66:67], 2, v[164:165]
	global_load_dword v14, v[12:13], off offset:384
	s_waitcnt vmcnt(0) lgkmcnt(0)
	v_ashrrev_i32_e32 v15, 31, v14
.LBB0_1159:
	s_or_saveexec_b64 s[0:1], s[0:1]
	v_add_u32_e32 v12, 0x60, v66
	v_ashrrev_i32_e32 v13, 31, v12
	s_xor_b64 exec, exec, s[0:1]
	v_mov_b64_e32 v[14:15], v[12:13]
	s_or_b64 exec, exec, s[0:1]
	v_lshlrev_b32_e32 v18, 4, v68
	v_and_b32_e32 v0, 0x70, v18
	s_waitcnt vmcnt(0) lgkmcnt(0)
	v_ashrrev_i32_e32 v5, 31, v4
	v_ashrrev_i32_e32 v3, 31, v2
	v_lshlrev_b64 v[106:107], 11, v[4:5]
	v_lshl_add_u64 v[4:5], v[162:163], 0, v[0:1]
	v_lshlrev_b64 v[2:3], 11, v[2:3]
	v_ashrrev_i32_e32 v7, 31, v6
	v_lshl_add_u64 v[140:141], v[4:5], 0, v[2:3]
	v_lshlrev_b64 v[2:3], 11, v[6:7]
	v_lshl_add_u64 v[142:143], v[4:5], 0, v[2:3]
	v_lshlrev_b64 v[2:3], 11, v[12:13]
	v_lshl_add_u64 v[16:17], v[160:161], 0, v[0:1]
	v_lshlrev_b64 v[110:111], 11, v[66:67]
	v_lshl_add_u64 v[144:145], v[4:5], 0, v[2:3]
	v_lshrrev_b32_e32 v0, 4, v68
	v_and_b32_e32 v162, 15, v68
	v_bfe_u32 v165, v68, 4, 2
	v_bfe_u32 v2, v68, 1, 3
	v_ashrrev_i32_e32 v11, 31, v10
	v_ashrrev_i32_e32 v9, 31, v8
	v_lshl_add_u64 v[138:139], v[4:5], 0, v[110:111]
	v_ashrrev_i32_e32 v164, 7, v68
	v_lshlrev_b32_e32 v3, 7, v68
	v_xor_b32_e32 v4, v0, v68
	v_bitop3_b32 v0, v0, v2, 3 bitop3:0x6c
	v_lshlrev_b32_e32 v6, 7, v162
	v_bitop3_b32 v2, v165, v2, 4 bitop3:0x36
	v_lshlrev_b64 v[102:103], 11, v[10:11]
	v_lshlrev_b64 v[104:105], 11, v[8:9]
	v_lshl_add_u64 v[134:135], v[16:17], 0, v[106:107]
	v_lshlrev_b64 v[108:109], 11, v[14:15]
	v_and_b32_e32 v5, 0xffffff80, v18
	v_lshlrev_b32_e32 v4, 4, v4
	v_lshlrev_b32_e32 v0, 4, v0
	v_lshl_or_b32 v7, v164, 13, v6
	v_and_or_b32 v3, v3, s70, v6
	v_lshlrev_b32_e32 v2, 4, v2
	v_lshl_add_u64 v[130:131], v[16:17], 0, v[102:103]
	v_lshl_add_u64 v[132:133], v[16:17], 0, v[104:105]
	v_lshl_add_u64 v[136:137], v[16:17], 0, v[108:109]
	s_barrier
	global_load_dwordx4 v[70:73], v[134:135], off
	global_load_dwordx4 v[74:77], v[132:133], off
	global_load_dwordx4 v[78:81], v[130:131], off
	global_load_dwordx4 v[82:85], v[136:137], off
	global_load_dwordx4 v[86:89], v[138:139], off
	global_load_dwordx4 v[90:93], v[140:141], off
	global_load_dwordx4 v[94:97], v[142:143], off
	global_load_dwordx4 v[98:101], v[144:145], off
	v_and_or_b32 v170, v4, s14, v5
	v_or_b32_e32 v169, v0, v7
	v_or_b32_e32 v168, v0, v3
	v_or_b32_e32 v167, v2, v7
	v_or_b32_e32 v166, v2, v3
	global_load_dwordx4 v[14:17], v[134:135], off offset:128
	global_load_dwordx4 v[6:9], v[130:131], off offset:128
	global_load_dwordx4 v[2:5], v[138:139], off offset:128
	global_load_dwordx4 v[22:25], v[142:143], off offset:128
	global_load_dwordx4 v[34:37], v[134:135], off offset:256
	global_load_dwordx4 v[10:13], v[132:133], off offset:128
	global_load_dwordx4 v[38:41], v[132:133], off offset:256
	global_load_dwordx4 v[42:45], v[130:131], off offset:256
	global_load_dwordx4 v[18:21], v[136:137], off offset:128
	global_load_dwordx4 v[46:49], v[136:137], off offset:256
	global_load_dwordx4 v[50:53], v[138:139], off offset:256
	global_load_dwordx4 v[30:33], v[140:141], off offset:128
	global_load_dwordx4 v[58:61], v[140:141], off offset:256
	global_load_dwordx4 v[54:57], v[142:143], off offset:256
	global_load_dwordx4 v[26:29], v[144:145], off offset:128
	global_load_dwordx4 v[62:65], v[144:145], off offset:256
	s_add_i32 s94, s18, s9
	s_lshl_b64 s[0:1], s[94:95], 1
	s_add_u32 s0, s0, s8
	v_lshlrev_b64 v[66:67], 11, v[66:67]
	s_addc_u32 s1, s1, 0
	v_lshl_add_u64 v[66:67], s[0:1], 0, v[66:67]
	v_lshl_add_u64 v[146:147], v[158:159], 0, v[66:67]
	v_lshl_add_u64 v[66:67], s[0:1], 0, v[110:111]
	v_lshl_add_u64 v[66:67], v[158:159], 0, v[66:67]
	v_and_b32_e32 v0, 7, v68
	v_lshl_add_u64 v[148:149], v[66:67], 0, s[30:31]
	v_lshl_add_u64 v[66:67], v[160:161], 0, s[30:31]
	v_mov_b32_e32 v118, 0
	v_lshrrev_b32_e32 v163, 6, v68
	v_lshlrev_b32_e32 v0, 4, v0
	v_lshl_add_u64 v[150:151], v[66:67], 0, v[108:109]
	v_lshl_add_u64 v[152:153], v[66:67], 0, v[102:103]
	v_lshl_add_u64 v[154:155], v[66:67], 0, v[104:105]
	v_lshl_add_u64 v[156:157], v[66:67], 0, v[106:107]
	s_mov_b32 s0, -2
	v_mov_b32_e32 v119, v118
	v_mov_b32_e32 v120, v118
	v_mov_b32_e32 v121, v118
	v_mov_b32_e32 v122, v118
	v_mov_b32_e32 v123, v118
	v_mov_b32_e32 v124, v118
	v_mov_b32_e32 v125, v118
	v_mov_b32_e32 v126, v118
	v_mov_b32_e32 v127, v118
	v_mov_b32_e32 v128, v118
	v_mov_b32_e32 v129, v118
	v_mov_b32_e32 v106, v118
	v_mov_b32_e32 v107, v118
	v_mov_b32_e32 v108, v118
	s_waitcnt vmcnt(0) lgkmcnt(0)
; template <int NT, bool BKN, bool MASK = false, bool ROWSS = false, class Epi> ...
;     ...
;   for (int kt = 0; kt < nk - 2; kt += 2) {
;     GEMM_COMPUTE(0);
;     GEMM_STORE(ra1, rb1, 1);
;     GEMM_LOAD(ra1, rb1, kt + 3);
;     __syncthreads();
	ds_write_b128 v170, v[70:73]
	ds_write_b128 v170, v[74:77] offset:4096
	ds_write_b128 v170, v[78:81] offset:8192
	ds_write_b128 v170, v[82:85] offset:12288
	ds_write_b128 v170, v[86:89] offset:16384
	ds_write_b128 v170, v[90:93] offset:20480
	ds_write_b128 v170, v[94:97] offset:24576
	ds_write_b128 v170, v[98:101] offset:28672
	v_mov_b32_e32 v94, v118
	v_mov_b32_e32 v95, v118
	v_mov_b32_e32 v96, v118
	v_mov_b32_e32 v97, v118
	v_mov_b32_e32 v98, v118
	v_mov_b32_e32 v99, v118
	v_mov_b32_e32 v100, v118
	v_mov_b32_e32 v101, v118
	v_mov_b32_e32 v109, v118
	v_mov_b32_e32 v110, v118
	v_mov_b32_e32 v111, v118
	v_mov_b32_e32 v112, v118
	v_mov_b32_e32 v113, v118
	v_mov_b32_e32 v102, v118
	v_mov_b32_e32 v103, v118
	v_mov_b32_e32 v104, v118
	v_mov_b32_e32 v105, v118
	v_mov_b32_e32 v114, v118
	v_mov_b32_e32 v115, v118
	v_mov_b32_e32 v116, v118
	v_mov_b32_e32 v117, v118
	v_mov_b32_e32 v82, v118
	v_mov_b32_e32 v83, v118
	v_mov_b32_e32 v84, v118
	v_mov_b32_e32 v85, v118
	v_mov_b32_e32 v86, v118
	v_mov_b32_e32 v87, v118
	v_mov_b32_e32 v88, v118
	v_mov_b32_e32 v89, v118
	v_mov_b32_e32 v90, v118
	v_mov_b32_e32 v91, v118
	v_mov_b32_e32 v92, v118
	v_mov_b32_e32 v93, v118
	v_mov_b32_e32 v70, v118
	v_mov_b32_e32 v71, v118
	v_mov_b32_e32 v72, v118
	v_mov_b32_e32 v73, v118
	v_mov_b32_e32 v66, v118
	v_mov_b32_e32 v67, v118
	v_mov_b32_e32 v68, v118
	v_mov_b32_e32 v69, v118
	v_mov_b32_e32 v74, v118
	v_mov_b32_e32 v75, v118
	v_mov_b32_e32 v76, v118
	v_mov_b32_e32 v77, v118
	v_mov_b32_e32 v78, v118
	v_mov_b32_e32 v79, v118
	v_mov_b32_e32 v80, v118
	v_mov_b32_e32 v81, v118
	s_waitcnt lgkmcnt(0)
	s_barrier
.LBB0_1162:
	ds_read_b128 v[158:161], v169
	ds_read_b128 v[172:175], v168 offset:16384
	ds_read_b128 v[176:179], v169 offset:2048
	ds_read_b128 v[180:183], v168 offset:18432
	ds_read_b128 v[188:191], v168 offset:20480
	ds_read_b128 v[192:195], v168 offset:22528
	s_add_i32 s0, s0, 2
	s_waitcnt lgkmcnt(0)
	v_mfma_f32_16x16x32_bf16 v[78:81], v[158:161], v[172:175], v[78:81]
	s_min_u32 s1, s0, 11
	s_lshl_b32 s94, s1, 7
	s_cmp_lt_u32 s0, 12
	s_waitcnt lgkmcnt(2)
	v_mfma_f32_16x16x32_bf16 v[74:77], v[158:161], v[180:183], v[74:77]
	s_waitcnt lgkmcnt(1)
	v_mfma_f32_16x16x32_bf16 v[66:69], v[158:161], v[188:191], v[66:69]
	s_waitcnt lgkmcnt(0)
	v_mfma_f32_16x16x32_bf16 v[70:73], v[158:161], v[192:195], v[70:73]
	v_mfma_f32_16x16x32_bf16 v[90:93], v[176:179], v[172:175], v[90:93]
	v_mfma_f32_16x16x32_bf16 v[86:89], v[176:179], v[180:183], v[86:89]
	v_mfma_f32_16x16x32_bf16 v[82:85], v[176:179], v[188:191], v[82:85]
	v_mfma_f32_16x16x32_bf16 v[114:117], v[176:179], v[192:195], v[114:117]
	ds_read_b128 v[158:161], v169 offset:4096
	ds_read_b128 v[176:179], v169 offset:6144
	s_waitcnt lgkmcnt(0)
	v_mfma_f32_16x16x32_bf16 v[102:105], v[158:161], v[172:175], v[102:105]
	v_mfma_f32_16x16x32_bf16 v[110:113], v[158:161], v[180:183], v[110:113]
	v_mfma_f32_16x16x32_bf16 v[106:109], v[158:161], v[188:191], v[106:109]
	v_mfma_f32_16x16x32_bf16 v[98:101], v[158:161], v[192:195], v[98:101]
	ds_read_b128 v[158:161], v167
	s_waitcnt lgkmcnt(1)
	v_mfma_f32_16x16x32_bf16 v[94:97], v[176:179], v[172:175], v[94:97]
	v_mfma_f32_16x16x32_bf16 v[126:129], v[176:179], v[180:183], v[126:129]
	v_mfma_f32_16x16x32_bf16 v[122:125], v[176:179], v[188:191], v[122:125]
	v_mfma_f32_16x16x32_bf16 v[118:121], v[176:179], v[192:195], v[118:121]
	ds_read_b128 v[172:175], v166 offset:16384
	ds_read_b128 v[176:179], v167 offset:2048
	ds_read_b128 v[180:183], v166 offset:18432
	ds_read_b128 v[188:191], v166 offset:20480
	ds_read_b128 v[192:195], v166 offset:22528
	ds_read_b128 v[196:199], v167 offset:4096
	ds_read_b128 v[200:203], v167 offset:6144
	s_waitcnt vmcnt(0)
	ds_write_b128 v170, v[14:17] offset:32768
	ds_write_b128 v170, v[10:13] offset:36864
	ds_write_b128 v170, v[6:9] offset:40960
	ds_write_b128 v170, v[18:21] offset:45056
	ds_write_b128 v170, v[2:5] offset:49152
	ds_write_b128 v170, v[30:33] offset:53248
	ds_write_b128 v170, v[22:25] offset:57344
	ds_write_b128 v170, v[26:29] offset:61440
	v_lshl_add_u64 v[2:3], v[156:157], 0, v[0:1]
	v_lshl_add_u64 v[4:5], v[154:155], 0, v[0:1]
	v_lshl_add_u64 v[6:7], v[152:153], 0, v[0:1]
	v_lshl_add_u64 v[18:19], v[150:151], 0, v[0:1]
	v_lshl_add_u64 v[22:23], v[148:149], 0, v[0:1]
	v_lshl_add_u64 v[24:25], v[146:147], 0, v[0:1]
	global_load_dwordx4 v[14:17], v[2:3], off
	global_load_dwordx4 v[10:13], v[4:5], off
	s_nop 0
	global_load_dwordx4 v[6:9], v[6:7], off
	s_nop 0
	global_load_dwordx4 v[18:21], v[18:19], off
	s_nop 0
	global_load_dwordx4 v[2:5], v[22:23], off
	v_add_co_u32_e32 v22, vcc, s15, v24
	s_waitcnt lgkmcnt(0)
	v_mfma_f32_16x16x32_bf16 v[78:81], v[158:161], v[172:175], v[78:81]
	v_addc_co_u32_e32 v23, vcc, 0, v25, vcc
	v_add_co_u32_e32 v26, vcc, s16, v24
	v_mfma_f32_16x16x32_bf16 v[74:77], v[158:161], v[180:183], v[74:77]
	s_nop 0
	v_addc_co_u32_e32 v27, vcc, 0, v25, vcc
	v_add_co_u32_e32 v28, vcc, s17, v24
	v_mfma_f32_16x16x32_bf16 v[66:69], v[158:161], v[188:191], v[66:69]
	s_nop 0
	v_addc_co_u32_e32 v29, vcc, 0, v25, vcc
	global_load_dwordx4 v[30:33], v[22:23], off offset:384
	s_nop 0
	global_load_dwordx4 v[22:25], v[26:27], off offset:384
	s_nop 0
	global_load_dwordx4 v[26:29], v[28:29], off offset:384
	v_mfma_f32_16x16x32_bf16 v[70:73], v[158:161], v[192:195], v[70:73]
	s_waitcnt lgkmcnt(0)
	s_barrier
; template <int NT, bool BKN, bool MASK = false, bool ROWSS = false, class Epi> ...
;     ...
;     GEMM_COMPUTE(1);
;     GEMM_STORE(ra0, rb0, 0);
;     GEMM_LOAD(ra0, rb0, (kt + 4 < nkm1 ? kt + 4 : nkm1));
;     __syncthreads();
;   }
	ds_read_b128 v[158:161], v169 offset:32768
	v_mfma_f32_16x16x32_bf16 v[90:93], v[176:179], v[172:175], v[90:93]
	v_lshl_add_u64 v[146:147], v[146:147], 0, s[6:7]
	v_lshl_add_u64 v[148:149], v[148:149], 0, s[6:7]
	v_lshl_add_u64 v[150:151], v[150:151], 0, s[6:7]
	v_mfma_f32_16x16x32_bf16 v[86:89], v[176:179], v[180:183], v[86:89]
	v_lshl_add_u64 v[152:153], v[152:153], 0, s[6:7]
	v_lshl_add_u64 v[154:155], v[154:155], 0, s[6:7]
	v_lshl_add_u64 v[156:157], v[156:157], 0, s[6:7]
	v_mfma_f32_16x16x32_bf16 v[82:85], v[176:179], v[188:191], v[82:85]
	v_mfma_f32_16x16x32_bf16 v[114:117], v[176:179], v[192:195], v[114:117]
	v_mfma_f32_16x16x32_bf16 v[102:105], v[196:199], v[172:175], v[102:105]
	v_mfma_f32_16x16x32_bf16 v[110:113], v[196:199], v[180:183], v[110:113]
	v_mfma_f32_16x16x32_bf16 v[106:109], v[196:199], v[188:191], v[106:109]
	v_mfma_f32_16x16x32_bf16 v[98:101], v[196:199], v[192:195], v[98:101]
	v_mfma_f32_16x16x32_bf16 v[94:97], v[200:203], v[172:175], v[94:97]
	v_mfma_f32_16x16x32_bf16 v[126:129], v[200:203], v[180:183], v[126:129]
	ds_read_b128 v[172:175], v168 offset:49152
	ds_read_b128 v[176:179], v169 offset:34816
	ds_read_b128 v[180:183], v168 offset:51200
	v_mfma_f32_16x16x32_bf16 v[122:125], v[200:203], v[188:191], v[122:125]
	v_mfma_f32_16x16x32_bf16 v[118:121], v[200:203], v[192:195], v[118:121]
	ds_read_b128 v[188:191], v168 offset:53248
	ds_read_b128 v[192:195], v168 offset:55296
	s_waitcnt lgkmcnt(0)
	v_mfma_f32_16x16x32_bf16 v[78:81], v[158:161], v[172:175], v[78:81]
	v_mfma_f32_16x16x32_bf16 v[74:77], v[158:161], v[180:183], v[74:77]
	v_mfma_f32_16x16x32_bf16 v[66:69], v[158:161], v[188:191], v[66:69]
	v_mfma_f32_16x16x32_bf16 v[70:73], v[158:161], v[192:195], v[70:73]
	v_mfma_f32_16x16x32_bf16 v[90:93], v[176:179], v[172:175], v[90:93]
	v_mfma_f32_16x16x32_bf16 v[86:89], v[176:179], v[180:183], v[86:89]
	v_mfma_f32_16x16x32_bf16 v[82:85], v[176:179], v[188:191], v[82:85]
	v_mfma_f32_16x16x32_bf16 v[114:117], v[176:179], v[192:195], v[114:117]
	ds_read_b128 v[158:161], v169 offset:36864
	ds_read_b128 v[176:179], v169 offset:38912
	s_waitcnt lgkmcnt(0)
	v_mfma_f32_16x16x32_bf16 v[102:105], v[158:161], v[172:175], v[102:105]
	v_mfma_f32_16x16x32_bf16 v[110:113], v[158:161], v[180:183], v[110:113]
	v_mfma_f32_16x16x32_bf16 v[106:109], v[158:161], v[188:191], v[106:109]
	v_mfma_f32_16x16x32_bf16 v[98:101], v[158:161], v[192:195], v[98:101]
	ds_read_b128 v[158:161], v167 offset:32768
	v_mfma_f32_16x16x32_bf16 v[94:97], v[176:179], v[172:175], v[94:97]
	v_mfma_f32_16x16x32_bf16 v[126:129], v[176:179], v[180:183], v[126:129]
	v_mfma_f32_16x16x32_bf16 v[122:125], v[176:179], v[188:191], v[122:125]
	v_mfma_f32_16x16x32_bf16 v[118:121], v[176:179], v[192:195], v[118:121]
	ds_read_b128 v[172:175], v166 offset:49152
	ds_read_b128 v[176:179], v167 offset:34816
	ds_read_b128 v[180:183], v166 offset:51200
	ds_read_b128 v[188:191], v166 offset:53248
	ds_read_b128 v[192:195], v166 offset:55296
	s_waitcnt lgkmcnt(0)
	v_mfma_f32_16x16x32_bf16 v[78:81], v[158:161], v[172:175], v[78:81]
	v_mfma_f32_16x16x32_bf16 v[74:77], v[158:161], v[180:183], v[74:77]
	v_mfma_f32_16x16x32_bf16 v[66:69], v[158:161], v[188:191], v[66:69]
	v_mfma_f32_16x16x32_bf16 v[70:73], v[158:161], v[192:195], v[70:73]
	ds_read_b128 v[158:161], v167 offset:36864
	ds_read_b128 v[196:199], v167 offset:38912
	ds_write_b128 v170, v[34:37]
	ds_write_b128 v170, v[38:41] offset:4096
	ds_write_b128 v170, v[42:45] offset:8192
	ds_write_b128 v170, v[46:49] offset:12288
	ds_write_b128 v170, v[50:53] offset:16384
	ds_write_b128 v170, v[58:61] offset:20480
	ds_write_b128 v170, v[54:57] offset:24576
	ds_write_b128 v170, v[62:65] offset:28672
	v_lshl_add_u64 v[34:35], v[134:135], 0, s[94:95]
	v_lshl_add_u64 v[38:39], v[132:133], 0, s[94:95]
	v_lshl_add_u64 v[42:43], v[130:131], 0, s[94:95]
	v_lshl_add_u64 v[46:47], v[136:137], 0, s[94:95]
	v_lshl_add_u64 v[50:51], v[138:139], 0, s[94:95]
	v_lshl_add_u64 v[54:55], v[140:141], 0, s[94:95]
	v_lshl_add_u64 v[56:57], v[142:143], 0, s[94:95]
	v_lshl_add_u64 v[62:63], v[144:145], 0, s[94:95]
	global_load_dwordx4 v[34:37], v[34:35], off offset:512
	s_nop 0
	global_load_dwordx4 v[38:41], v[38:39], off offset:512
	s_nop 0
	global_load_dwordx4 v[42:45], v[42:43], off offset:512
	s_nop 0
	global_load_dwordx4 v[46:49], v[46:47], off offset:512
	s_nop 0
	global_load_dwordx4 v[50:53], v[50:51], off offset:512
	s_nop 0
	global_load_dwordx4 v[58:61], v[54:55], off offset:512
	s_nop 0
	global_load_dwordx4 v[54:57], v[56:57], off offset:512
	v_mfma_f32_16x16x32_bf16 v[90:93], v[176:179], v[172:175], v[90:93]
	global_load_dwordx4 v[62:65], v[62:63], off offset:512
	s_waitcnt lgkmcnt(0)
	s_barrier
	v_mfma_f32_16x16x32_bf16 v[86:89], v[176:179], v[180:183], v[86:89]
	v_mfma_f32_16x16x32_bf16 v[82:85], v[176:179], v[188:191], v[82:85]
	v_mfma_f32_16x16x32_bf16 v[114:117], v[176:179], v[192:195], v[114:117]
	v_mfma_f32_16x16x32_bf16 v[102:105], v[158:161], v[172:175], v[102:105]
	v_mfma_f32_16x16x32_bf16 v[110:113], v[158:161], v[180:183], v[110:113]
	v_mfma_f32_16x16x32_bf16 v[106:109], v[158:161], v[188:191], v[106:109]
	v_mfma_f32_16x16x32_bf16 v[98:101], v[158:161], v[192:195], v[98:101]
	v_mfma_f32_16x16x32_bf16 v[94:97], v[196:199], v[172:175], v[94:97]
	v_mfma_f32_16x16x32_bf16 v[126:129], v[196:199], v[180:183], v[126:129]
	v_mfma_f32_16x16x32_bf16 v[122:125], v[196:199], v[188:191], v[122:125]
	v_mfma_f32_16x16x32_bf16 v[118:121], v[196:199], v[192:195], v[118:121]
	s_cbranch_scc1 .LBB0_1162
; __device__ __forceinline__ u16 f2bf(float f) { return (u16)(pack2(f, 0.f) & 0xffffu); }
; __device__ __forceinline__ int tid_() { int t = threadIdx.x; asm volatile("" : "+v"(t)); return t; }
; __device__ __forceinline__ float silu_f(float x) { return x / (1.f + __expf(-x)); }
; template <int NT, bool BKN, bool MASK = false, bool ROWSS = false, class Epi> ...
;     ...
;   GEMM_COMPUTE(0);
;   GEMM_STORE(ra1, rb1, 1);
;   __syncthreads();
;   GEMM_COMPUTE(1);
; __device__ __forceinline__ void phase_moe_up(const Params& p, int l, bool last, unsigned char* smem) {
;     ...
;     auto epi = [&](f32x4(&acc)[4][4], int r0, int c0) {
;       u16* Ts = (u16*)smem;
;       const int t2 = tid_();
;       __syncthreads();
; #pragma unroll
;       for (int mi = 0; mi < 4; ++mi)
; #pragma unroll
;         for (int n2 = 0; n2 < 2; ++n2)
; #pragma unroll
;           for (int j = 0; j < 4; ++j) {
;             const int m = r0 + mi * 16 + j;
;             const int fl = (c0 >> 6) * 32 + n2 * 16 + (c0 & 15);
;             Ts[m * 72 + fl] = f2bf(silu_f(acc[mi][2 * n2][j]) * acc[mi][2 * n2 + 1][j]);
;           }
	s_waitcnt vmcnt(0)
	ds_read_b128 v[34:37], v169
	ds_read_b128 v[38:41], v169 offset:2048
	ds_read_b128 v[42:45], v169 offset:4096
	ds_read_b128 v[46:49], v169 offset:6144
	ds_read_b128 v[50:53], v168 offset:16384
	ds_read_b128 v[54:57], v168 offset:18432
	ds_read_b128 v[58:61], v168 offset:20480
	ds_read_b128 v[62:65], v168 offset:22528
	v_lshlrev_b32_e32 v0, 6, v164
	s_waitcnt lgkmcnt(3)
	v_mfma_f32_16x16x32_bf16 v[78:81], v[34:37], v[50:53], v[78:81]
	v_lshl_or_b32 v0, v165, 2, v0
	v_mul_lo_u32 v0, v0, s96
	s_waitcnt lgkmcnt(2)
	v_mfma_f32_16x16x32_bf16 v[74:77], v[34:37], v[54:57], v[74:77]
	s_waitcnt lgkmcnt(1)
	v_mfma_f32_16x16x32_bf16 v[66:69], v[34:37], v[58:61], v[66:69]
	s_waitcnt lgkmcnt(0)
	v_mfma_f32_16x16x32_bf16 v[34:37], v[34:37], v[62:65], v[70:73]
	v_mfma_f32_16x16x32_bf16 v[70:73], v[38:41], v[50:53], v[90:93]
	v_mfma_f32_16x16x32_bf16 v[86:89], v[38:41], v[54:57], v[86:89]
	v_mfma_f32_16x16x32_bf16 v[82:85], v[38:41], v[58:61], v[82:85]
	v_mfma_f32_16x16x32_bf16 v[38:41], v[38:41], v[62:65], v[114:117]
	v_mfma_f32_16x16x32_bf16 v[90:93], v[42:45], v[50:53], v[102:105]
	v_mfma_f32_16x16x32_bf16 v[102:105], v[42:45], v[54:57], v[110:113]
	v_mfma_f32_16x16x32_bf16 v[106:109], v[42:45], v[58:61], v[106:109]
	v_mfma_f32_16x16x32_bf16 v[42:45], v[42:45], v[62:65], v[98:101]
	v_mfma_f32_16x16x32_bf16 v[50:53], v[46:49], v[50:53], v[94:97]
	v_mfma_f32_16x16x32_bf16 v[54:57], v[46:49], v[54:57], v[126:129]
	v_mfma_f32_16x16x32_bf16 v[58:61], v[46:49], v[58:61], v[122:125]
	v_mfma_f32_16x16x32_bf16 v[46:49], v[46:49], v[62:65], v[118:121]
	ds_read_b128 v[62:65], v167
	ds_read_b128 v[94:97], v167 offset:2048
	ds_read_b128 v[98:101], v167 offset:4096
	ds_read_b128 v[110:113], v167 offset:6144
	ds_read_b128 v[114:117], v166 offset:16384
	ds_read_b128 v[118:121], v166 offset:18432
	ds_read_b128 v[122:125], v166 offset:20480
	ds_read_b128 v[126:129], v166 offset:22528
	ds_write_b128 v170, v[14:17] offset:32768
	ds_write_b128 v170, v[10:13] offset:36864
	ds_write_b128 v170, v[6:9] offset:40960
	ds_write_b128 v170, v[18:21] offset:45056
	ds_write_b128 v170, v[2:5] offset:49152
	ds_write_b128 v170, v[30:33] offset:53248
	ds_write_b128 v170, v[22:25] offset:57344
	ds_write_b128 v170, v[26:29] offset:61440
	s_waitcnt lgkmcnt(0)
	v_mfma_f32_16x16x32_bf16 v[78:81], v[62:65], v[114:117], v[78:81]
	s_barrier
	ds_read_b128 v[2:5], v169 offset:32768
	ds_read_b128 v[6:9], v169 offset:34816
	ds_read_b128 v[10:13], v169 offset:36864
	ds_read_b128 v[14:17], v169 offset:38912
	ds_read_b128 v[18:21], v168 offset:49152
	ds_read_b128 v[22:25], v168 offset:51200
	ds_read_b128 v[26:29], v168 offset:53248
	ds_read_b128 v[30:33], v168 offset:55296
	v_mfma_f32_16x16x32_bf16 v[74:77], v[62:65], v[118:121], v[74:77]
	v_mfma_f32_16x16x32_bf16 v[66:69], v[62:65], v[122:125], v[66:69]
	v_mfma_f32_16x16x32_bf16 v[34:37], v[62:65], v[126:129], v[34:37]
	v_mfma_f32_16x16x32_bf16 v[62:65], v[94:97], v[114:117], v[70:73]
	v_mfma_f32_16x16x32_bf16 v[70:73], v[94:97], v[118:121], v[86:89]
	v_mfma_f32_16x16x32_bf16 v[86:89], v[98:101], v[114:117], v[90:93]
	v_mfma_f32_16x16x32_bf16 v[90:93], v[98:101], v[118:121], v[102:105]
	v_mfma_f32_16x16x32_bf16 v[50:53], v[110:113], v[114:117], v[50:53]
	v_mfma_f32_16x16x32_bf16 v[54:57], v[110:113], v[118:121], v[54:57]
	v_mfma_f32_16x16x32_bf16 v[58:61], v[110:113], v[122:125], v[58:61]
	v_mfma_f32_16x16x32_bf16 v[46:49], v[110:113], v[126:129], v[46:49]
	s_waitcnt lgkmcnt(3)
	v_mfma_f32_16x16x32_bf16 v[78:81], v[2:5], v[18:21], v[78:81]
	v_mfma_f32_16x16x32_bf16 v[82:85], v[94:97], v[122:125], v[82:85]
	v_mfma_f32_16x16x32_bf16 v[38:41], v[94:97], v[126:129], v[38:41]
	v_mfma_f32_16x16x32_bf16 v[94:97], v[98:101], v[122:125], v[106:109]
	v_mfma_f32_16x16x32_bf16 v[42:45], v[98:101], v[126:129], v[42:45]
	s_waitcnt lgkmcnt(2)
	v_mfma_f32_16x16x32_bf16 v[74:77], v[2:5], v[22:25], v[74:77]
	s_waitcnt lgkmcnt(1)
	v_mfma_f32_16x16x32_bf16 v[66:69], v[2:5], v[26:29], v[66:69]
	s_waitcnt lgkmcnt(0)
	v_mfma_f32_16x16x32_bf16 v[2:5], v[2:5], v[30:33], v[34:37]
	v_mfma_f32_16x16x32_bf16 v[34:37], v[6:9], v[18:21], v[62:65]
	v_mfma_f32_16x16x32_bf16 v[70:73], v[6:9], v[22:25], v[70:73]
	v_mfma_f32_16x16x32_bf16 v[86:89], v[10:13], v[18:21], v[86:89]
	v_mfma_f32_16x16x32_bf16 v[90:93], v[10:13], v[22:25], v[90:93]
	v_mfma_f32_16x16x32_bf16 v[98:101], v[14:17], v[18:21], v[50:53]
	v_mfma_f32_16x16x32_bf16 v[102:105], v[14:17], v[22:25], v[54:57]
	v_mfma_f32_16x16x32_bf16 v[106:109], v[14:17], v[26:29], v[58:61]
	v_mfma_f32_16x16x32_bf16 v[110:113], v[14:17], v[30:33], v[46:49]
	ds_read_b128 v[14:17], v167 offset:32768
	ds_read_b128 v[18:21], v167 offset:34816
	ds_read_b128 v[22:25], v167 offset:36864
	ds_read_b128 v[114:117], v167 offset:38912
	ds_read_b128 v[118:121], v166 offset:49152
	ds_read_b128 v[122:125], v166 offset:51200
	ds_read_b128 v[126:129], v166 offset:53248
	ds_read_b128 v[130:133], v166 offset:55296
	s_waitcnt lgkmcnt(3)
	v_mfma_f32_16x16x32_bf16 v[58:61], v[14:17], v[118:121], v[78:81]
	s_waitcnt lgkmcnt(1)
	v_mfma_f32_16x16x32_bf16 v[50:53], v[14:17], v[126:129], v[66:69]
	v_mfma_f32_16x16x32_bf16 v[46:49], v[18:21], v[122:125], v[70:73]
	s_nop 4
	v_mul_f32_e32 v68, 0xbfb8aa3b, v58
	v_exp_f32_e32 v68, v68
	v_lshlrev_b32_e32 v67, 5, v163
	v_mfma_f32_16x16x32_bf16 v[62:65], v[14:17], v[122:125], v[74:77]
	v_and_or_b32 v67, v67, 32, v162
	v_add_f32_e32 v68, 1.0, v68
	v_div_scale_f32 v69, s[0:1], v68, v68, v58
	v_rcp_f32_e32 v70, v69
	v_mov_b32_e32 v66, v187
	v_lshl_add_u32 v0, v67, 1, v0
	v_fma_f32 v71, -v69, v70, 1.0
	v_fmac_f32_e32 v70, v71, v70
	v_div_scale_f32 v71, vcc, v58, v68, v58
	v_mul_f32_e32 v72, v71, v70
	v_fma_f32 v73, -v69, v72, v71
	v_fmac_f32_e32 v72, v73, v70
	v_fma_f32 v69, -v69, v72, v71
	v_div_fmas_f32 v69, v69, v70, v72
	v_div_fixup_f32 v58, v69, v68, v58
	v_mul_f32_e32 v58, v62, v58
	v_cvt_pk_bf16_f32 v58, v58, s0
	s_waitcnt lgkmcnt(0)
	s_barrier
; __device__ __forceinline__ u16 f2bf(float f) { return (u16)(pack2(f, 0.f) & 0xffffu); }
; __device__ __forceinline__ float silu_f(float x) { return x / (1.f + __expf(-x)); }
; __device__ __forceinline__ void phase_moe_up(const Params& p, int l, bool last, unsigned char* smem) {
;     ...
; #pragma unroll
;       for (int mi = 0; mi < 4; ++mi)
; #pragma unroll
;         for (int n2 = 0; n2 < 2; ++n2)
; #pragma unroll
;           for (int j = 0; j < 4; ++j) {
;             const int m = r0 + mi * 16 + j;
;             const int fl = (c0 >> 6) * 32 + n2 * 16 + (c0 & 15);
;             Ts[m * 72 + fl] = f2bf(silu_f(acc[mi][2 * n2][j]) * acc[mi][2 * n2 + 1][j]);
;           }
	ds_write_b16 v0, v58
	v_mul_f32_e32 v58, 0xbfb8aa3b, v59
	v_exp_f32_e32 v58, v58
	v_mfma_f32_16x16x32_bf16 v[54:57], v[14:17], v[130:133], v[2:5]
	v_add_f32_e32 v58, 1.0, v58
	v_div_scale_f32 v62, s[0:1], v58, v58, v59
	v_rcp_f32_e32 v67, v62
	v_mfma_f32_16x16x32_bf16 v[94:97], v[10:13], v[26:29], v[94:97]
	v_fma_f32 v68, -v62, v67, 1.0
	v_fmac_f32_e32 v67, v68, v67
	v_div_scale_f32 v68, vcc, v59, v58, v59
	v_mul_f32_e32 v69, v68, v67
	v_fma_f32 v70, -v62, v69, v68
	v_fmac_f32_e32 v69, v70, v67
	v_fma_f32 v62, -v62, v69, v68
	v_div_fmas_f32 v62, v62, v67, v69
	v_div_fixup_f32 v58, v62, v58, v59
	v_mul_f32_e32 v58, v63, v58
	v_cvt_pk_bf16_f32 v58, v58, s0
	ds_write_b16 v0, v58 offset:144
	v_mul_f32_e32 v58, 0xbfb8aa3b, v60
	v_exp_f32_e32 v58, v58
	v_mfma_f32_16x16x32_bf16 v[10:13], v[10:13], v[30:33], v[42:45]
	v_add_f32_e32 v58, 1.0, v58
	v_div_scale_f32 v59, s[0:1], v58, v58, v60
	v_rcp_f32_e32 v62, v59
	v_mfma_f32_16x16x32_bf16 v[42:45], v[18:21], v[118:121], v[34:37]
	v_fma_f32 v63, -v59, v62, 1.0
	v_fmac_f32_e32 v62, v63, v62
	v_div_scale_f32 v63, vcc, v60, v58, v60
	v_mul_f32_e32 v67, v63, v62
	v_fma_f32 v68, -v59, v67, v63
	v_fmac_f32_e32 v67, v68, v62
	v_fma_f32 v59, -v59, v67, v63
	v_div_fmas_f32 v59, v59, v62, v67
	v_div_fixup_f32 v58, v59, v58, v60
	v_mul_f32_e32 v58, v64, v58
	v_cvt_pk_bf16_f32 v58, v58, s0
	ds_write_b16 v0, v58 offset:288
	v_mul_f32_e32 v58, 0xbfb8aa3b, v61
	v_exp_f32_e32 v58, v58
	v_mfma_f32_16x16x32_bf16 v[82:85], v[6:9], v[26:29], v[82:85]
	v_add_f32_e32 v58, 1.0, v58
	v_div_scale_f32 v59, s[0:1], v58, v58, v61
	v_rcp_f32_e32 v60, v59
	v_mfma_f32_16x16x32_bf16 v[34:37], v[18:21], v[126:129], v[82:85]
	v_fma_f32 v62, -v59, v60, 1.0
	v_fmac_f32_e32 v60, v62, v60
	v_div_scale_f32 v62, vcc, v61, v58, v61
	v_mul_f32_e32 v63, v62, v60
	v_fma_f32 v64, -v59, v63, v62
	v_fmac_f32_e32 v63, v64, v60
	v_fma_f32 v59, -v59, v63, v62
	v_div_fmas_f32 v59, v59, v60, v63
	v_div_fixup_f32 v58, v59, v58, v61
	v_mul_f32_e32 v58, v65, v58
	v_cvt_pk_bf16_f32 v58, v58, s0
	ds_write_b16 v0, v58 offset:432
	v_mul_f32_e32 v58, 0xbfb8aa3b, v50
	v_exp_f32_e32 v58, v58
	v_mfma_f32_16x16x32_bf16 v[6:9], v[6:9], v[30:33], v[38:41]
	v_add_f32_e32 v58, 1.0, v58
	v_div_scale_f32 v59, s[0:1], v58, v58, v50
	v_rcp_f32_e32 v60, v59
	v_mfma_f32_16x16x32_bf16 v[38:41], v[18:21], v[130:133], v[6:9]
	v_fma_f32 v61, -v59, v60, 1.0
	v_fmac_f32_e32 v60, v61, v60
	v_div_scale_f32 v61, vcc, v50, v58, v50
	v_mul_f32_e32 v62, v61, v60
	v_fma_f32 v63, -v59, v62, v61
	v_fmac_f32_e32 v62, v63, v60
	v_fma_f32 v59, -v59, v62, v61
	v_div_fmas_f32 v59, v59, v60, v62
	v_div_fixup_f32 v50, v59, v58, v50
	v_mul_f32_e32 v50, v54, v50
	v_cvt_pk_bf16_f32 v50, v50, s0
	ds_write_b16 v0, v50 offset:32
	v_mul_f32_e32 v50, 0xbfb8aa3b, v51
	v_exp_f32_e32 v50, v50
	v_mfma_f32_16x16x32_bf16 v[26:29], v[22:25], v[118:121], v[86:89]
	v_add_f32_e32 v50, 1.0, v50
	v_div_scale_f32 v54, s[0:1], v50, v50, v51
	v_rcp_f32_e32 v58, v54
	v_mfma_f32_16x16x32_bf16 v[30:33], v[22:25], v[122:125], v[90:93]
	v_fma_f32 v59, -v54, v58, 1.0
	v_fmac_f32_e32 v58, v59, v58
	v_div_scale_f32 v59, vcc, v51, v50, v51
	v_mul_f32_e32 v60, v59, v58
	v_fma_f32 v61, -v54, v60, v59
	v_fmac_f32_e32 v60, v61, v58
	v_fma_f32 v54, -v54, v60, v59
	v_div_fmas_f32 v54, v54, v58, v60
	v_div_fixup_f32 v50, v54, v50, v51
	v_mul_f32_e32 v50, v55, v50
	v_cvt_pk_bf16_f32 v50, v50, s0
	ds_write_b16 v0, v50 offset:176
	v_mul_f32_e32 v50, 0xbfb8aa3b, v52
	v_exp_f32_e32 v50, v50
	v_mfma_f32_16x16x32_bf16 v[18:21], v[22:25], v[126:129], v[94:97]
	v_add_f32_e32 v50, 1.0, v50
	v_div_scale_f32 v51, s[0:1], v50, v50, v52
	v_rcp_f32_e32 v54, v51
	v_mfma_f32_16x16x32_bf16 v[22:25], v[22:25], v[130:133], v[10:13]
	v_fma_f32 v55, -v51, v54, 1.0
	v_fmac_f32_e32 v54, v55, v54
	v_div_scale_f32 v55, vcc, v52, v50, v52
	v_mul_f32_e32 v58, v55, v54
	v_fma_f32 v59, -v51, v58, v55
	v_fmac_f32_e32 v58, v59, v54
	v_fma_f32 v51, -v51, v58, v55
	v_div_fmas_f32 v51, v51, v54, v58
	v_div_fixup_f32 v50, v51, v50, v52
	v_mul_f32_e32 v50, v56, v50
	v_cvt_pk_bf16_f32 v50, v50, s0
	ds_write_b16 v0, v50 offset:320
	v_mul_f32_e32 v50, 0xbfb8aa3b, v53
	v_exp_f32_e32 v50, v50
	v_mfma_f32_16x16x32_bf16 v[10:13], v[114:117], v[118:121], v[98:101]
	v_add_f32_e32 v50, 1.0, v50
	v_div_scale_f32 v51, s[0:1], v50, v50, v53
	v_rcp_f32_e32 v52, v51
	v_mfma_f32_16x16x32_bf16 v[14:17], v[114:117], v[122:125], v[102:105]
	v_fma_f32 v54, -v51, v52, 1.0
	v_fmac_f32_e32 v52, v54, v52
	v_div_scale_f32 v54, vcc, v53, v50, v53
	v_mul_f32_e32 v55, v54, v52
	v_fma_f32 v56, -v51, v55, v54
	v_fmac_f32_e32 v55, v56, v52
	v_fma_f32 v51, -v51, v55, v54
	v_div_fmas_f32 v51, v51, v52, v55
	v_div_fixup_f32 v50, v51, v50, v53
	v_mul_f32_e32 v50, v57, v50
	v_cvt_pk_bf16_f32 v50, v50, s0
	ds_write_b16 v0, v50 offset:464
	v_mul_f32_e32 v50, 0xbfb8aa3b, v42
	v_exp_f32_e32 v50, v50
	v_mfma_f32_16x16x32_bf16 v[2:5], v[114:117], v[126:129], v[106:109]
	v_add_f32_e32 v50, 1.0, v50
	v_div_scale_f32 v51, s[0:1], v50, v50, v42
	v_rcp_f32_e32 v52, v51
	v_mfma_f32_16x16x32_bf16 v[6:9], v[114:117], v[130:133], v[110:113]
	v_fma_f32 v53, -v51, v52, 1.0
	v_fmac_f32_e32 v52, v53, v52
	v_div_scale_f32 v53, vcc, v42, v50, v42
	v_mul_f32_e32 v54, v53, v52
	v_fma_f32 v55, -v51, v54, v53
	v_fmac_f32_e32 v54, v55, v52
	v_fma_f32 v51, -v51, v54, v53
	v_div_fmas_f32 v51, v51, v52, v54
	v_div_fixup_f32 v42, v51, v50, v42
	v_mul_f32_e32 v42, v46, v42
	v_cvt_pk_bf16_f32 v42, v42, s0
	ds_write_b16 v0, v42 offset:2304
	v_mul_f32_e32 v42, 0xbfb8aa3b, v43
	v_exp_f32_e32 v42, v42
	s_nop 0
	v_add_f32_e32 v42, 1.0, v42
	v_div_scale_f32 v46, s[0:1], v42, v42, v43
	v_rcp_f32_e32 v50, v46
	s_nop 0
	v_fma_f32 v51, -v46, v50, 1.0
; __device__ __forceinline__ u16 f2bf(float f) { return (u16)(pack2(f, 0.f) & 0xffffu); }
; __device__ __forceinline__ float silu_f(float x) { return x / (1.f + __expf(-x)); }
; __device__ __forceinline__ void phase_moe_up(const Params& p, int l, bool last, unsigned char* smem) {
;     ...
; #pragma unroll
;       for (int mi = 0; mi < 4; ++mi)
; #pragma unroll
;         for (int n2 = 0; n2 < 2; ++n2)
; #pragma unroll
;           for (int j = 0; j < 4; ++j) {
;             const int m = r0 + mi * 16 + j;
;             const int fl = (c0 >> 6) * 32 + n2 * 16 + (c0 & 15);
;             Ts[m * 72 + fl] = f2bf(silu_f(acc[mi][2 * n2][j]) * acc[mi][2 * n2 + 1][j]);
;           }
	v_fmac_f32_e32 v50, v51, v50
	v_div_scale_f32 v51, vcc, v43, v42, v43
	v_mul_f32_e32 v52, v51, v50
	v_fma_f32 v53, -v46, v52, v51
	v_fmac_f32_e32 v52, v53, v50
	v_fma_f32 v46, -v46, v52, v51
	v_div_fmas_f32 v46, v46, v50, v52
	v_div_fixup_f32 v42, v46, v42, v43
	v_mul_f32_e32 v42, v47, v42
	v_cvt_pk_bf16_f32 v42, v42, s0
	ds_write_b16 v0, v42 offset:2448
	v_mul_f32_e32 v42, 0xbfb8aa3b, v44
	v_exp_f32_e32 v42, v42
	s_nop 0
	v_add_f32_e32 v42, 1.0, v42
	v_div_scale_f32 v43, s[0:1], v42, v42, v44
	v_rcp_f32_e32 v46, v43
	s_nop 0
	v_fma_f32 v47, -v43, v46, 1.0
	v_fmac_f32_e32 v46, v47, v46
	v_div_scale_f32 v47, vcc, v44, v42, v44
	v_mul_f32_e32 v50, v47, v46
	v_fma_f32 v51, -v43, v50, v47
	v_fmac_f32_e32 v50, v51, v46
	v_fma_f32 v43, -v43, v50, v47
	v_div_fmas_f32 v43, v43, v46, v50
	v_div_fixup_f32 v42, v43, v42, v44
	v_mul_f32_e32 v42, v48, v42
	v_cvt_pk_bf16_f32 v42, v42, s0
	ds_write_b16 v0, v42 offset:2592
	v_mul_f32_e32 v42, 0xbfb8aa3b, v45
	v_exp_f32_e32 v42, v42
	s_nop 0
	v_add_f32_e32 v42, 1.0, v42
	v_div_scale_f32 v43, s[0:1], v42, v42, v45
	v_rcp_f32_e32 v44, v43
	s_nop 0
	v_fma_f32 v46, -v43, v44, 1.0
	v_fmac_f32_e32 v44, v46, v44
	v_div_scale_f32 v46, vcc, v45, v42, v45
	v_mul_f32_e32 v47, v46, v44
	v_fma_f32 v48, -v43, v47, v46
	v_fmac_f32_e32 v47, v48, v44
	v_fma_f32 v43, -v43, v47, v46
	v_div_fmas_f32 v43, v43, v44, v47
	v_div_fixup_f32 v42, v43, v42, v45
	v_mul_f32_e32 v42, v49, v42
	v_cvt_pk_bf16_f32 v42, v42, s0
	ds_write_b16 v0, v42 offset:2736
	v_mul_f32_e32 v42, 0xbfb8aa3b, v34
	v_exp_f32_e32 v42, v42
	s_nop 0
	v_add_f32_e32 v42, 1.0, v42
	v_div_scale_f32 v43, s[0:1], v42, v42, v34
	v_rcp_f32_e32 v44, v43
	s_nop 0
	v_fma_f32 v45, -v43, v44, 1.0
	v_fmac_f32_e32 v44, v45, v44
	v_div_scale_f32 v45, vcc, v34, v42, v34
	v_mul_f32_e32 v46, v45, v44
	v_fma_f32 v47, -v43, v46, v45
	v_fmac_f32_e32 v46, v47, v44
	v_fma_f32 v43, -v43, v46, v45
	v_div_fmas_f32 v43, v43, v44, v46
	v_div_fixup_f32 v34, v43, v42, v34
	v_mul_f32_e32 v34, v38, v34
	v_cvt_pk_bf16_f32 v34, v34, s0
	ds_write_b16 v0, v34 offset:2336
	v_mul_f32_e32 v34, 0xbfb8aa3b, v35
	v_exp_f32_e32 v34, v34
	s_nop 0
	v_add_f32_e32 v34, 1.0, v34
	v_div_scale_f32 v38, s[0:1], v34, v34, v35
	v_rcp_f32_e32 v42, v38
	s_nop 0
	v_fma_f32 v43, -v38, v42, 1.0
	v_fmac_f32_e32 v42, v43, v42
	v_div_scale_f32 v43, vcc, v35, v34, v35
	v_mul_f32_e32 v44, v43, v42
	v_fma_f32 v45, -v38, v44, v43
	v_fmac_f32_e32 v44, v45, v42
	v_fma_f32 v38, -v38, v44, v43
	v_div_fmas_f32 v38, v38, v42, v44
	v_div_fixup_f32 v34, v38, v34, v35
	v_mul_f32_e32 v34, v39, v34
	v_cvt_pk_bf16_f32 v34, v34, s0
	ds_write_b16 v0, v34 offset:2480
	v_mul_f32_e32 v34, 0xbfb8aa3b, v36
	v_exp_f32_e32 v34, v34
	s_nop 0
	v_add_f32_e32 v34, 1.0, v34
	v_div_scale_f32 v35, s[0:1], v34, v34, v36
	v_rcp_f32_e32 v38, v35
	s_nop 0
	v_fma_f32 v39, -v35, v38, 1.0
	v_fmac_f32_e32 v38, v39, v38
	v_div_scale_f32 v39, vcc, v36, v34, v36
	v_mul_f32_e32 v42, v39, v38
	v_fma_f32 v43, -v35, v42, v39
	v_fmac_f32_e32 v42, v43, v38
	v_fma_f32 v35, -v35, v42, v39
	v_div_fmas_f32 v35, v35, v38, v42
	v_div_fixup_f32 v34, v35, v34, v36
	v_mul_f32_e32 v34, v40, v34
	v_cvt_pk_bf16_f32 v34, v34, s0
	ds_write_b16 v0, v34 offset:2624
	v_mul_f32_e32 v34, 0xbfb8aa3b, v37
	v_exp_f32_e32 v34, v34
	s_nop 0
	v_add_f32_e32 v34, 1.0, v34
	v_div_scale_f32 v35, s[0:1], v34, v34, v37
	v_rcp_f32_e32 v36, v35
	s_nop 0
	v_fma_f32 v38, -v35, v36, 1.0
	v_fmac_f32_e32 v36, v38, v36
	v_div_scale_f32 v38, vcc, v37, v34, v37
	v_mul_f32_e32 v39, v38, v36
	v_fma_f32 v40, -v35, v39, v38
	v_fmac_f32_e32 v39, v40, v36
	v_fma_f32 v35, -v35, v39, v38
	v_div_fmas_f32 v35, v35, v36, v39
	v_div_fixup_f32 v34, v35, v34, v37
	v_mul_f32_e32 v34, v41, v34
	v_cvt_pk_bf16_f32 v34, v34, s0
	ds_write_b16 v0, v34 offset:2768
	v_mul_f32_e32 v34, 0xbfb8aa3b, v26
	v_exp_f32_e32 v34, v34
	s_nop 0
	v_add_f32_e32 v34, 1.0, v34
	v_div_scale_f32 v35, s[0:1], v34, v34, v26
	v_rcp_f32_e32 v36, v35
	s_nop 0
	v_fma_f32 v37, -v35, v36, 1.0
	v_fmac_f32_e32 v36, v37, v36
	v_div_scale_f32 v37, vcc, v26, v34, v26
	v_mul_f32_e32 v38, v37, v36
	v_fma_f32 v39, -v35, v38, v37
	v_fmac_f32_e32 v38, v39, v36
	v_fma_f32 v35, -v35, v38, v37
	v_div_fmas_f32 v35, v35, v36, v38
	v_div_fixup_f32 v26, v35, v34, v26
	v_mul_f32_e32 v26, v30, v26
	v_cvt_pk_bf16_f32 v26, v26, s0
	ds_write_b16 v0, v26 offset:4608
	v_mul_f32_e32 v26, 0xbfb8aa3b, v27
	v_exp_f32_e32 v26, v26
	s_nop 0
	v_add_f32_e32 v26, 1.0, v26
	v_div_scale_f32 v30, s[0:1], v26, v26, v27
	v_rcp_f32_e32 v34, v30
	s_nop 0
	v_fma_f32 v35, -v30, v34, 1.0
	v_fmac_f32_e32 v34, v35, v34
	v_div_scale_f32 v35, vcc, v27, v26, v27
	v_mul_f32_e32 v36, v35, v34
	v_fma_f32 v37, -v30, v36, v35
	v_fmac_f32_e32 v36, v37, v34
	v_fma_f32 v30, -v30, v36, v35
	v_div_fmas_f32 v30, v30, v34, v36
	v_div_fixup_f32 v26, v30, v26, v27
	v_mul_f32_e32 v26, v31, v26
	v_cvt_pk_bf16_f32 v26, v26, s0
	ds_write_b16 v0, v26 offset:4752
	v_mul_f32_e32 v26, 0xbfb8aa3b, v28
	v_exp_f32_e32 v26, v26
	s_nop 0
	v_add_f32_e32 v26, 1.0, v26
	v_div_scale_f32 v27, s[0:1], v26, v26, v28
	v_rcp_f32_e32 v30, v27
	s_nop 0
	v_fma_f32 v31, -v27, v30, 1.0
	v_fmac_f32_e32 v30, v31, v30
	v_div_scale_f32 v31, vcc, v28, v26, v28
	v_mul_f32_e32 v34, v31, v30
	v_fma_f32 v35, -v27, v34, v31
	v_fmac_f32_e32 v34, v35, v30
	v_fma_f32 v27, -v27, v34, v31
	v_div_fmas_f32 v27, v27, v30, v34
	v_div_fixup_f32 v26, v27, v26, v28
	v_mul_f32_e32 v26, v32, v26
	v_cvt_pk_bf16_f32 v26, v26, s0
	ds_write_b16 v0, v26 offset:4896
	v_mul_f32_e32 v26, 0xbfb8aa3b, v29
	v_exp_f32_e32 v26, v26
	s_nop 0
	v_add_f32_e32 v26, 1.0, v26
	v_div_scale_f32 v27, s[0:1], v26, v26, v29
	v_rcp_f32_e32 v28, v27
	s_nop 0
	v_fma_f32 v30, -v27, v28, 1.0
; __device__ __forceinline__ u16 f2bf(float f) { return (u16)(pack2(f, 0.f) & 0xffffu); }
; __device__ __forceinline__ float silu_f(float x) { return x / (1.f + __expf(-x)); }
; __device__ __forceinline__ void phase_moe_up(const Params& p, int l, bool last, unsigned char* smem) {
;     ...
; #pragma unroll
;       for (int mi = 0; mi < 4; ++mi)
; #pragma unroll
;         for (int n2 = 0; n2 < 2; ++n2)
; #pragma unroll
;           for (int j = 0; j < 4; ++j) {
;             const int m = r0 + mi * 16 + j;
;             const int fl = (c0 >> 6) * 32 + n2 * 16 + (c0 & 15);
;             Ts[m * 72 + fl] = f2bf(silu_f(acc[mi][2 * n2][j]) * acc[mi][2 * n2 + 1][j]);
;           }
	v_fmac_f32_e32 v28, v30, v28
	v_div_scale_f32 v30, vcc, v29, v26, v29
	v_mul_f32_e32 v31, v30, v28
	v_fma_f32 v32, -v27, v31, v30
	v_fmac_f32_e32 v31, v32, v28
	v_fma_f32 v27, -v27, v31, v30
	v_div_fmas_f32 v27, v27, v28, v31
	v_div_fixup_f32 v26, v27, v26, v29
	v_mul_f32_e32 v26, v33, v26
	v_cvt_pk_bf16_f32 v26, v26, s0
	ds_write_b16 v0, v26 offset:5040
	v_mul_f32_e32 v26, 0xbfb8aa3b, v18
	v_exp_f32_e32 v26, v26
	s_nop 0
	v_add_f32_e32 v26, 1.0, v26
	v_div_scale_f32 v27, s[0:1], v26, v26, v18
	v_rcp_f32_e32 v28, v27
	s_nop 0
	v_fma_f32 v29, -v27, v28, 1.0
	v_fmac_f32_e32 v28, v29, v28
	v_div_scale_f32 v29, vcc, v18, v26, v18
	v_mul_f32_e32 v30, v29, v28
	v_fma_f32 v31, -v27, v30, v29
	v_fmac_f32_e32 v30, v31, v28
	v_fma_f32 v27, -v27, v30, v29
	v_div_fmas_f32 v27, v27, v28, v30
	v_div_fixup_f32 v18, v27, v26, v18
	v_mul_f32_e32 v18, v22, v18
	v_cvt_pk_bf16_f32 v18, v18, s0
	ds_write_b16 v0, v18 offset:4640
	v_mul_f32_e32 v18, 0xbfb8aa3b, v19
	v_exp_f32_e32 v18, v18
	s_nop 0
	v_add_f32_e32 v18, 1.0, v18
	v_div_scale_f32 v22, s[0:1], v18, v18, v19
	v_rcp_f32_e32 v26, v22
	s_nop 0
	v_fma_f32 v27, -v22, v26, 1.0
	v_fmac_f32_e32 v26, v27, v26
	v_div_scale_f32 v27, vcc, v19, v18, v19
	v_mul_f32_e32 v28, v27, v26
	v_fma_f32 v29, -v22, v28, v27
	v_fmac_f32_e32 v28, v29, v26
	v_fma_f32 v22, -v22, v28, v27
	v_div_fmas_f32 v22, v22, v26, v28
	v_div_fixup_f32 v18, v22, v18, v19
	v_mul_f32_e32 v18, v23, v18
	v_cvt_pk_bf16_f32 v18, v18, s0
	ds_write_b16 v0, v18 offset:4784
	v_mul_f32_e32 v18, 0xbfb8aa3b, v20
	v_exp_f32_e32 v18, v18
	s_nop 0
	v_add_f32_e32 v18, 1.0, v18
	v_div_scale_f32 v19, s[0:1], v18, v18, v20
	v_rcp_f32_e32 v22, v19
	s_nop 0
	v_fma_f32 v23, -v19, v22, 1.0
	v_fmac_f32_e32 v22, v23, v22
	v_div_scale_f32 v23, vcc, v20, v18, v20
	v_mul_f32_e32 v26, v23, v22
	v_fma_f32 v27, -v19, v26, v23
	v_fmac_f32_e32 v26, v27, v22
	v_fma_f32 v19, -v19, v26, v23
	v_div_fmas_f32 v19, v19, v22, v26
	v_div_fixup_f32 v18, v19, v18, v20
	v_mul_f32_e32 v18, v24, v18
	v_cvt_pk_bf16_f32 v18, v18, s0
	ds_write_b16 v0, v18 offset:4928
	v_mul_f32_e32 v18, 0xbfb8aa3b, v21
	v_exp_f32_e32 v18, v18
	s_nop 0
	v_add_f32_e32 v18, 1.0, v18
	v_div_scale_f32 v19, s[0:1], v18, v18, v21
	v_rcp_f32_e32 v20, v19
	s_nop 0
	v_fma_f32 v22, -v19, v20, 1.0
	v_fmac_f32_e32 v20, v22, v20
	v_div_scale_f32 v22, vcc, v21, v18, v21
	v_mul_f32_e32 v23, v22, v20
	v_fma_f32 v24, -v19, v23, v22
	v_fmac_f32_e32 v23, v24, v20
	v_fma_f32 v19, -v19, v23, v22
	v_div_fmas_f32 v19, v19, v20, v23
	v_div_fixup_f32 v18, v19, v18, v21
	v_mul_f32_e32 v18, v25, v18
	v_cvt_pk_bf16_f32 v18, v18, s0
	ds_write_b16 v0, v18 offset:5072
	v_mul_f32_e32 v18, 0xbfb8aa3b, v10
	v_exp_f32_e32 v18, v18
	s_nop 0
	v_add_f32_e32 v18, 1.0, v18
	v_div_scale_f32 v19, s[0:1], v18, v18, v10
	v_rcp_f32_e32 v20, v19
	s_nop 0
	v_fma_f32 v21, -v19, v20, 1.0
	v_fmac_f32_e32 v20, v21, v20
	v_div_scale_f32 v21, vcc, v10, v18, v10
	v_mul_f32_e32 v22, v21, v20
	v_fma_f32 v23, -v19, v22, v21
	v_fmac_f32_e32 v22, v23, v20
	v_fma_f32 v19, -v19, v22, v21
	v_div_fmas_f32 v19, v19, v20, v22
	v_div_fixup_f32 v10, v19, v18, v10
	v_mul_f32_e32 v10, v14, v10
	v_cvt_pk_bf16_f32 v10, v10, s0
	ds_write_b16 v0, v10 offset:6912
	v_mul_f32_e32 v10, 0xbfb8aa3b, v11
	v_exp_f32_e32 v10, v10
	s_nop 0
	v_add_f32_e32 v10, 1.0, v10
	v_div_scale_f32 v14, s[0:1], v10, v10, v11
	v_rcp_f32_e32 v18, v14
	s_nop 0
	v_fma_f32 v19, -v14, v18, 1.0
	v_fmac_f32_e32 v18, v19, v18
	v_div_scale_f32 v19, vcc, v11, v10, v11
	v_mul_f32_e32 v20, v19, v18
	v_fma_f32 v21, -v14, v20, v19
	v_fmac_f32_e32 v20, v21, v18
	v_fma_f32 v14, -v14, v20, v19
	v_div_fmas_f32 v14, v14, v18, v20
	v_div_fixup_f32 v10, v14, v10, v11
	v_mul_f32_e32 v10, v15, v10
	v_cvt_pk_bf16_f32 v10, v10, s0
	ds_write_b16 v0, v10 offset:7056
	v_mul_f32_e32 v10, 0xbfb8aa3b, v12
	v_exp_f32_e32 v10, v10
	s_nop 0
	v_add_f32_e32 v10, 1.0, v10
	v_div_scale_f32 v11, s[0:1], v10, v10, v12
	v_rcp_f32_e32 v14, v11
	s_nop 0
	v_fma_f32 v15, -v11, v14, 1.0
	v_fmac_f32_e32 v14, v15, v14
	v_div_scale_f32 v15, vcc, v12, v10, v12
	v_mul_f32_e32 v18, v15, v14
	v_fma_f32 v19, -v11, v18, v15
	v_fmac_f32_e32 v18, v19, v14
	v_fma_f32 v11, -v11, v18, v15
	v_div_fmas_f32 v11, v11, v14, v18
	v_div_fixup_f32 v10, v11, v10, v12
	v_mul_f32_e32 v10, v16, v10
	v_cvt_pk_bf16_f32 v10, v10, s0
	ds_write_b16 v0, v10 offset:7200
	v_mul_f32_e32 v10, 0xbfb8aa3b, v13
	v_exp_f32_e32 v10, v10
	s_nop 0
	v_add_f32_e32 v10, 1.0, v10
	v_div_scale_f32 v11, s[0:1], v10, v10, v13
	v_rcp_f32_e32 v12, v11
	s_nop 0
	v_fma_f32 v14, -v11, v12, 1.0
	v_fmac_f32_e32 v12, v14, v12
; __device__ __forceinline__ u16 f2bf(float f) { return (u16)(pack2(f, 0.f) & 0xffffu); }
; __device__ __forceinline__ float silu_f(float x) { return x / (1.f + __expf(-x)); }
; __device__ __forceinline__ void phase_moe_up(const Params& p, int l, bool last, unsigned char* smem) {
;     ...
;           for (int j = 0; j < 4; ++j) {
;             const int m = r0 + mi * 16 + j;
;             const int fl = (c0 >> 6) * 32 + n2 * 16 + (c0 & 15);
;             Ts[m * 72 + fl] = f2bf(silu_f(acc[mi][2 * n2][j]) * acc[mi][2 * n2 + 1][j]);
;           }
;       __syncthreads();
; #pragma unroll
;       for (int i = 0; i < 4; ++i) {
;         const int c = t2 + 256 * i, row = c >> 3, ch = c & 7;
;         if (row < mvalid) *(u32x4*)(p.HID + (size_t)(hid_row + row) * 512 + nt * 64 + ch * 8) = *(const u32x4*)(Ts + row * 72 + ch * 8);
;       }
	v_div_scale_f32 v14, vcc, v13, v10, v13
	v_mul_f32_e32 v15, v14, v12
	v_fma_f32 v16, -v11, v15, v14
	v_fmac_f32_e32 v15, v16, v12
	v_fma_f32 v11, -v11, v15, v14
	v_div_fmas_f32 v11, v11, v12, v15
	v_div_fixup_f32 v10, v11, v10, v13
	v_mul_f32_e32 v10, v17, v10
	v_cvt_pk_bf16_f32 v10, v10, s0
	ds_write_b16 v0, v10 offset:7344
	v_mul_f32_e32 v10, 0xbfb8aa3b, v2
	v_exp_f32_e32 v10, v10
	s_nop 0
	v_add_f32_e32 v10, 1.0, v10
	v_div_scale_f32 v11, s[0:1], v10, v10, v2
	v_rcp_f32_e32 v12, v11
	s_nop 0
	v_fma_f32 v13, -v11, v12, 1.0
	v_fmac_f32_e32 v12, v13, v12
	v_div_scale_f32 v13, vcc, v2, v10, v2
	v_mul_f32_e32 v14, v13, v12
	v_fma_f32 v15, -v11, v14, v13
	v_fmac_f32_e32 v14, v15, v12
	v_fma_f32 v11, -v11, v14, v13
	v_div_fmas_f32 v11, v11, v12, v14
	v_div_fixup_f32 v2, v11, v10, v2
	v_mul_f32_e32 v2, v6, v2
	v_cvt_pk_bf16_f32 v2, v2, s0
	ds_write_b16 v0, v2 offset:6944
	v_mul_f32_e32 v2, 0xbfb8aa3b, v3
	v_exp_f32_e32 v2, v2
	s_nop 0
	v_add_f32_e32 v2, 1.0, v2
	v_div_scale_f32 v6, s[0:1], v2, v2, v3
	v_rcp_f32_e32 v10, v6
	s_nop 0
	v_fma_f32 v11, -v6, v10, 1.0
	v_fmac_f32_e32 v10, v11, v10
	v_div_scale_f32 v11, vcc, v3, v2, v3
	v_mul_f32_e32 v12, v11, v10
	v_fma_f32 v13, -v6, v12, v11
	v_fmac_f32_e32 v12, v13, v10
	v_fma_f32 v6, -v6, v12, v11
	v_div_fmas_f32 v6, v6, v10, v12
	v_div_fixup_f32 v2, v6, v2, v3
	v_mul_f32_e32 v2, v7, v2
	v_cvt_pk_bf16_f32 v2, v2, s0
	ds_write_b16 v0, v2 offset:7088
	v_mul_f32_e32 v2, 0xbfb8aa3b, v4
	v_exp_f32_e32 v2, v2
	s_nop 0
	v_add_f32_e32 v2, 1.0, v2
	v_div_scale_f32 v3, s[0:1], v2, v2, v4
	v_rcp_f32_e32 v6, v3
	s_nop 0
	v_fma_f32 v7, -v3, v6, 1.0
	v_fmac_f32_e32 v6, v7, v6
	v_div_scale_f32 v7, vcc, v4, v2, v4
	v_mul_f32_e32 v10, v7, v6
	v_fma_f32 v11, -v3, v10, v7
	v_fmac_f32_e32 v10, v11, v6
	v_fma_f32 v3, -v3, v10, v7
	v_div_fmas_f32 v3, v3, v6, v10
	v_div_fixup_f32 v2, v3, v2, v4
	v_mul_f32_e32 v2, v8, v2
	v_cvt_pk_bf16_f32 v2, v2, s0
	ds_write_b16 v0, v2 offset:7232
	v_mul_f32_e32 v2, 0xbfb8aa3b, v5
	v_exp_f32_e32 v2, v2
	s_nop 0
	v_add_f32_e32 v2, 1.0, v2
	v_div_scale_f32 v3, s[0:1], v2, v2, v5
	v_rcp_f32_e32 v4, v3
	s_nop 0
	v_fma_f32 v6, -v3, v4, 1.0
	v_fmac_f32_e32 v4, v6, v4
	v_div_scale_f32 v6, vcc, v5, v2, v5
	v_mul_f32_e32 v7, v6, v4
	v_fma_f32 v8, -v3, v7, v6
	v_fmac_f32_e32 v7, v8, v4
	v_fma_f32 v3, -v3, v7, v6
	v_div_fmas_f32 v3, v3, v4, v7
	v_div_fixup_f32 v2, v3, v2, v5
	v_mul_f32_e32 v2, v9, v2
	v_cvt_pk_bf16_f32 v2, v2, s0
	ds_write_b16 v0, v2 offset:7376
	v_lshlrev_b32_e32 v0, 3, v66
	v_and_b32_e32 v0, 56, v0
	v_ashrrev_i32_e32 v3, 3, v66
	v_lshlrev_b32_e32 v2, 1, v0
	v_cmp_gt_i32_e32 vcc, s86, v3
	s_waitcnt lgkmcnt(0)
	s_barrier
	s_and_saveexec_b64 s[0:1], vcc
	s_cbranch_execz .LBB0_1165
	v_mov_b64_e32 v[4:5], s[4:5]
	global_load_dwordx2 v[8:9], v[4:5], off offset:368
	v_mad_u64_u32 v[4:5], s[8:9], v3, s96, v[2:3]
	v_add_u32_e32 v10, s82, v3
	ds_read_b128 v[4:7], v4
	v_ashrrev_i32_e32 v11, 31, v10
	v_lshlrev_b64 v[10:11], 10, v[10:11]
	s_lshl_b32 s94, s83, 7
	v_mov_b32_e32 v3, v1
	s_waitcnt vmcnt(0) lgkmcnt(0)
	v_lshl_add_u64 v[8:9], v[8:9], 0, v[10:11]
	v_lshl_add_u64 v[8:9], v[8:9], 0, s[94:95]
	v_lshl_add_u64 v[8:9], v[8:9], 0, v[2:3]
	global_store_dwordx4 v[8:9], v[4:7], off
.LBB0_1165:
	s_or_b64 exec, exec, s[0:1]
	v_add_u32_e32 v3, 0x100, v66
	v_ashrrev_i32_e32 v3, 3, v3
	v_cmp_gt_i32_e32 vcc, s86, v3
	s_and_saveexec_b64 s[0:1], vcc
	s_cbranch_execz .LBB0_1167
	v_mov_b64_e32 v[4:5], s[4:5]
	global_load_dwordx2 v[8:9], v[4:5], off offset:368
	v_mad_u64_u32 v[4:5], s[8:9], v3, s96, v[2:3]
	v_add_u32_e32 v10, s82, v3
	ds_read_b128 v[4:7], v4
	v_ashrrev_i32_e32 v11, 31, v10
	v_lshlrev_b64 v[10:11], 10, v[10:11]
	s_lshl_b32 s94, s83, 7
	v_mov_b32_e32 v3, v1
	s_waitcnt vmcnt(0) lgkmcnt(0)
	v_lshl_add_u64 v[8:9], v[8:9], 0, v[10:11]
	v_lshl_add_u64 v[8:9], v[8:9], 0, s[94:95]
	v_lshl_add_u64 v[8:9], v[8:9], 0, v[2:3]
	global_store_dwordx4 v[8:9], v[4:7], off
.LBB0_1167:
	s_or_b64 exec, exec, s[0:1]
	v_add_u32_e32 v3, 0x200, v66
	v_ashrrev_i32_e32 v3, 3, v3
	v_cmp_gt_i32_e32 vcc, s86, v3
	s_and_saveexec_b64 s[0:1], vcc
	s_cbranch_execz .LBB0_1169
	v_mov_b64_e32 v[4:5], s[4:5]
	global_load_dwordx2 v[8:9], v[4:5], off offset:368
	v_mad_u64_u32 v[4:5], s[8:9], v3, s96, v[2:3]
	v_add_u32_e32 v10, s82, v3
	ds_read_b128 v[4:7], v4
	v_ashrrev_i32_e32 v11, 31, v10
	v_lshlrev_b64 v[10:11], 10, v[10:11]
	s_lshl_b32 s94, s83, 7
	v_mov_b32_e32 v3, v1
	s_waitcnt vmcnt(0) lgkmcnt(0)
	v_lshl_add_u64 v[8:9], v[8:9], 0, v[10:11]
	v_lshl_add_u64 v[8:9], v[8:9], 0, s[94:95]
	v_lshl_add_u64 v[2:3], v[8:9], 0, v[2:3]
	global_store_dwordx4 v[2:3], v[4:7], off

; __device__ __forceinline__ u16 f2bf(float f) { return (u16)(pack2(f, 0.f) & 0xffffu); }
; __device__ __forceinline__ float silu_f(float x) { return x / (1.f + __expf(-x)); }
; __device__ __forceinline__ void phase_moe_up(const Params& p, int l, bool last, unsigned char* smem) {
;     ...
; #pragma unroll
;       for (int mi = 0; mi < 4; ++mi)
; #pragma unroll
;         for (int n2 = 0; n2 < 2; ++n2)
; #pragma unroll
;           for (int j = 0; j < 4; ++j) {
;             const int m = r0 + mi * 16 + j;
;             const int fl = (c0 >> 6) * 32 + n2 * 16 + (c0 & 15);
;             Ts[m * 72 + fl] = f2bf(silu_f(acc[mi][2 * n2][j]) * acc[mi][2 * n2 + 1][j]);
;           }
.LBB0_1194:
	s_waitcnt lgkmcnt(4)
	v_mul_f32_e32 v66, 0xbfb8aa3b, v62
	v_exp_f32_e32 v68, v66
	v_lshl_or_b32 v0, v196, 2, v197
	v_lshlrev_b32_e32 v67, 5, v195
	v_and_or_b32 v67, v67, 32, v194
	v_add_f32_e32 v68, 1.0, v68
	v_div_scale_f32 v69, s[0:1], v68, v68, v62
	s_waitcnt lgkmcnt(3)
	v_rcp_f32_e32 v70, v69
	v_mul_lo_u32 v0, v0, s96
	v_mov_b32_e32 v66, v187
	v_lshl_add_u32 v0, v67, 1, v0
	v_fma_f32 v71, -v69, v70, 1.0
	v_fmac_f32_e32 v70, v71, v70
	v_div_scale_f32 v71, vcc, v62, v68, v62
	v_mul_f32_e32 v72, v71, v70
	v_fma_f32 v73, -v69, v72, v71
	v_fmac_f32_e32 v72, v73, v70
	v_fma_f32 v69, -v69, v72, v71
	v_div_fmas_f32 v69, v69, v70, v72
	v_mul_f32_e32 v70, 0xbfb8aa3b, v63
	v_exp_f32_e32 v70, v70
	v_div_fixup_f32 v62, v69, v68, v62
	v_mul_f32_e32 v58, v58, v62
	v_cvt_pk_bf16_f32 v58, v58, s0
	v_add_f32_e32 v62, 1.0, v70
	v_div_scale_f32 v68, s[0:1], v62, v62, v63
	v_rcp_f32_e32 v69, v68
	s_waitcnt lgkmcnt(0)
	s_barrier
	ds_write_b16 v0, v58
	v_fma_f32 v58, -v68, v69, 1.0
	v_fmac_f32_e32 v69, v58, v69
	v_div_scale_f32 v58, vcc, v63, v62, v63
	v_mul_f32_e32 v67, v58, v69
	v_fma_f32 v70, -v68, v67, v58
	v_fmac_f32_e32 v67, v70, v69
	v_fma_f32 v58, -v68, v67, v58
	v_mul_f32_e32 v68, 0xbfb8aa3b, v64
	v_exp_f32_e32 v68, v68
	v_div_fmas_f32 v58, v58, v69, v67
	v_div_fixup_f32 v58, v58, v62, v63
	v_mul_f32_e32 v58, v59, v58
	v_add_f32_e32 v62, 1.0, v68
	v_div_scale_f32 v63, s[0:1], v62, v62, v64
	v_rcp_f32_e32 v67, v63
	s_nop 0
	v_cvt_pk_bf16_f32 v58, v58, s0
	ds_write_b16 v0, v58 offset:144
	v_fma_f32 v58, -v63, v67, 1.0
	v_fmac_f32_e32 v67, v58, v67
	v_div_scale_f32 v58, vcc, v64, v62, v64
	v_mul_f32_e32 v59, v58, v67
	v_fma_f32 v68, -v63, v59, v58
	v_fmac_f32_e32 v59, v68, v67
	v_fma_f32 v58, -v63, v59, v58
	v_mul_f32_e32 v63, 0xbfb8aa3b, v65
	v_exp_f32_e32 v63, v63
	v_div_fmas_f32 v58, v58, v67, v59
	v_div_fixup_f32 v58, v58, v62, v64
	v_mul_f32_e32 v58, v60, v58
	v_add_f32_e32 v59, 1.0, v63
	v_div_scale_f32 v62, s[0:1], v59, v59, v65
	v_rcp_f32_e32 v63, v62
	s_nop 0
	v_cvt_pk_bf16_f32 v58, v58, s0
	ds_write_b16 v0, v58 offset:288
	v_fma_f32 v58, -v62, v63, 1.0
	v_fmac_f32_e32 v63, v58, v63
	v_div_scale_f32 v58, vcc, v65, v59, v65
	v_mul_f32_e32 v60, v58, v63
	v_fma_f32 v64, -v62, v60, v58
	v_fmac_f32_e32 v60, v64, v63
	v_fma_f32 v58, -v62, v60, v58
	v_mul_f32_e32 v62, 0xbfb8aa3b, v54
	v_exp_f32_e32 v62, v62
	v_div_fmas_f32 v58, v58, v63, v60
	v_div_fixup_f32 v58, v58, v59, v65
	v_mul_f32_e32 v58, v61, v58
	v_add_f32_e32 v59, 1.0, v62
	v_div_scale_f32 v60, s[0:1], v59, v59, v54
	v_rcp_f32_e32 v62, v60
	s_nop 0
	v_cvt_pk_bf16_f32 v58, v58, s0
	ds_write_b16 v0, v58 offset:432
	v_fma_f32 v58, -v60, v62, 1.0
	v_fmac_f32_e32 v62, v58, v62
	v_div_scale_f32 v58, vcc, v54, v59, v54
	v_mul_f32_e32 v61, v58, v62
	v_fma_f32 v63, -v60, v61, v58
	v_fmac_f32_e32 v61, v63, v62
	v_fma_f32 v58, -v60, v61, v58
	v_mul_f32_e32 v60, 0xbfb8aa3b, v55
	v_exp_f32_e32 v60, v60
	v_div_fmas_f32 v58, v58, v62, v61
	v_div_fixup_f32 v54, v58, v59, v54
	v_mul_f32_e32 v50, v50, v54
	v_add_f32_e32 v58, 1.0, v60
	v_div_scale_f32 v59, s[0:1], v58, v58, v55
	v_rcp_f32_e32 v60, v59
	s_nop 0
	v_cvt_pk_bf16_f32 v50, v50, s0
	ds_write_b16 v0, v50 offset:32
	v_fma_f32 v50, -v59, v60, 1.0
	v_fmac_f32_e32 v60, v50, v60
	v_div_scale_f32 v50, vcc, v55, v58, v55
	v_mul_f32_e32 v54, v50, v60
	v_fma_f32 v61, -v59, v54, v50
	v_fmac_f32_e32 v54, v61, v60
	v_fma_f32 v50, -v59, v54, v50
	v_mul_f32_e32 v59, 0xbfb8aa3b, v56
	v_exp_f32_e32 v59, v59
	v_div_fmas_f32 v50, v50, v60, v54
	v_div_fixup_f32 v50, v50, v58, v55
	v_mul_f32_e32 v50, v51, v50
	v_add_f32_e32 v54, 1.0, v59
	v_div_scale_f32 v55, s[0:1], v54, v54, v56
	v_rcp_f32_e32 v58, v55
	s_nop 0
	v_cvt_pk_bf16_f32 v50, v50, s0
	ds_write_b16 v0, v50 offset:176
	v_fma_f32 v50, -v55, v58, 1.0
	v_fmac_f32_e32 v58, v50, v58
	v_div_scale_f32 v50, vcc, v56, v54, v56
	v_mul_f32_e32 v51, v50, v58
	v_fma_f32 v59, -v55, v51, v50
	v_fmac_f32_e32 v51, v59, v58
	v_fma_f32 v50, -v55, v51, v50
	v_mul_f32_e32 v55, 0xbfb8aa3b, v57
	v_exp_f32_e32 v55, v55
	v_div_fmas_f32 v50, v50, v58, v51
	v_div_fixup_f32 v50, v50, v54, v56
	v_mul_f32_e32 v50, v52, v50
	v_add_f32_e32 v51, 1.0, v55
	v_div_scale_f32 v54, s[0:1], v51, v51, v57
	v_rcp_f32_e32 v55, v54
	s_nop 0
	v_cvt_pk_bf16_f32 v50, v50, s0
	ds_write_b16 v0, v50 offset:320
	v_fma_f32 v50, -v54, v55, 1.0
	v_fmac_f32_e32 v55, v50, v55
	v_div_scale_f32 v50, vcc, v57, v51, v57
	v_mul_f32_e32 v52, v50, v55
	v_fma_f32 v56, -v54, v52, v50
	v_fmac_f32_e32 v52, v56, v55
	v_fma_f32 v50, -v54, v52, v50
	v_mul_f32_e32 v54, 0xbfb8aa3b, v46
	v_exp_f32_e32 v54, v54
	v_div_fmas_f32 v50, v50, v55, v52
	v_div_fixup_f32 v50, v50, v51, v57
	v_mul_f32_e32 v50, v53, v50
	v_add_f32_e32 v51, 1.0, v54
	v_div_scale_f32 v52, s[0:1], v51, v51, v46
	v_rcp_f32_e32 v54, v52
	s_nop 0
	v_cvt_pk_bf16_f32 v50, v50, s0
	ds_write_b16 v0, v50 offset:464
	v_fma_f32 v50, -v52, v54, 1.0
	v_fmac_f32_e32 v54, v50, v54
	v_div_scale_f32 v50, vcc, v46, v51, v46
	v_mul_f32_e32 v53, v50, v54
	v_fma_f32 v55, -v52, v53, v50
	v_fmac_f32_e32 v53, v55, v54
	v_fma_f32 v50, -v52, v53, v50
	v_mul_f32_e32 v52, 0xbfb8aa3b, v47
	v_exp_f32_e32 v52, v52
	v_div_fmas_f32 v50, v50, v54, v53
	v_div_fixup_f32 v46, v50, v51, v46
	v_mul_f32_e32 v42, v42, v46
	v_add_f32_e32 v50, 1.0, v52
	v_div_scale_f32 v51, s[0:1], v50, v50, v47
	v_rcp_f32_e32 v52, v51
	s_nop 0
	v_cvt_pk_bf16_f32 v42, v42, s0
	ds_write_b16 v0, v42 offset:2304
	v_fma_f32 v42, -v51, v52, 1.0
	v_fmac_f32_e32 v52, v42, v52
	v_div_scale_f32 v42, vcc, v47, v50, v47
	v_mul_f32_e32 v46, v42, v52
	v_fma_f32 v53, -v51, v46, v42
	v_fmac_f32_e32 v46, v53, v52
	v_fma_f32 v42, -v51, v46, v42
	v_mul_f32_e32 v51, 0xbfb8aa3b, v48
; __device__ __forceinline__ u16 f2bf(float f) { return (u16)(pack2(f, 0.f) & 0xffffu); }
; __device__ __forceinline__ float silu_f(float x) { return x / (1.f + __expf(-x)); }
; __device__ __forceinline__ void phase_moe_up(const Params& p, int l, bool last, unsigned char* smem) {
;     ...
; #pragma unroll
;       for (int mi = 0; mi < 4; ++mi)
; #pragma unroll
;         for (int n2 = 0; n2 < 2; ++n2)
; #pragma unroll
;           for (int j = 0; j < 4; ++j) {
;             const int m = r0 + mi * 16 + j;
;             const int fl = (c0 >> 6) * 32 + n2 * 16 + (c0 & 15);
;             Ts[m * 72 + fl] = f2bf(silu_f(acc[mi][2 * n2][j]) * acc[mi][2 * n2 + 1][j]);
;           }
	v_exp_f32_e32 v51, v51
	v_div_fmas_f32 v42, v42, v52, v46
	v_div_fixup_f32 v42, v42, v50, v47
	v_mul_f32_e32 v42, v43, v42
	v_add_f32_e32 v46, 1.0, v51
	v_div_scale_f32 v47, s[0:1], v46, v46, v48
	v_rcp_f32_e32 v50, v47
	s_nop 0
	v_cvt_pk_bf16_f32 v42, v42, s0
	ds_write_b16 v0, v42 offset:2448
	v_fma_f32 v42, -v47, v50, 1.0
	v_fmac_f32_e32 v50, v42, v50
	v_div_scale_f32 v42, vcc, v48, v46, v48
	v_mul_f32_e32 v43, v42, v50
	v_fma_f32 v51, -v47, v43, v42
	v_fmac_f32_e32 v43, v51, v50
	v_fma_f32 v42, -v47, v43, v42
	v_mul_f32_e32 v47, 0xbfb8aa3b, v49
	v_exp_f32_e32 v47, v47
	v_div_fmas_f32 v42, v42, v50, v43
	v_div_fixup_f32 v42, v42, v46, v48
	v_mul_f32_e32 v42, v44, v42
	v_add_f32_e32 v43, 1.0, v47
	v_div_scale_f32 v46, s[0:1], v43, v43, v49
	v_rcp_f32_e32 v47, v46
	s_nop 0
	v_cvt_pk_bf16_f32 v42, v42, s0
	ds_write_b16 v0, v42 offset:2592
	v_fma_f32 v42, -v46, v47, 1.0
	v_fmac_f32_e32 v47, v42, v47
	v_div_scale_f32 v42, vcc, v49, v43, v49
	v_mul_f32_e32 v44, v42, v47
	v_fma_f32 v48, -v46, v44, v42
	v_fmac_f32_e32 v44, v48, v47
	v_fma_f32 v42, -v46, v44, v42
	v_mul_f32_e32 v46, 0xbfb8aa3b, v38
	v_exp_f32_e32 v46, v46
	v_div_fmas_f32 v42, v42, v47, v44
	v_div_fixup_f32 v42, v42, v43, v49
	v_mul_f32_e32 v42, v45, v42
	v_add_f32_e32 v43, 1.0, v46
	v_div_scale_f32 v44, s[0:1], v43, v43, v38
	v_rcp_f32_e32 v46, v44
	s_nop 0
	v_cvt_pk_bf16_f32 v42, v42, s0
	ds_write_b16 v0, v42 offset:2736
	v_fma_f32 v42, -v44, v46, 1.0
	v_fmac_f32_e32 v46, v42, v46
	v_div_scale_f32 v42, vcc, v38, v43, v38
	v_mul_f32_e32 v45, v42, v46
	v_fma_f32 v47, -v44, v45, v42
	v_fmac_f32_e32 v45, v47, v46
	v_fma_f32 v42, -v44, v45, v42
	v_mul_f32_e32 v44, 0xbfb8aa3b, v39
	v_exp_f32_e32 v44, v44
	v_div_fmas_f32 v42, v42, v46, v45
	v_div_fixup_f32 v38, v42, v43, v38
	v_mul_f32_e32 v34, v34, v38
	v_add_f32_e32 v42, 1.0, v44
	v_div_scale_f32 v43, s[0:1], v42, v42, v39
	v_rcp_f32_e32 v44, v43
	s_nop 0
	v_cvt_pk_bf16_f32 v34, v34, s0
	ds_write_b16 v0, v34 offset:2336
	v_fma_f32 v34, -v43, v44, 1.0
	v_fmac_f32_e32 v44, v34, v44
	v_div_scale_f32 v34, vcc, v39, v42, v39
	v_mul_f32_e32 v38, v34, v44
	v_fma_f32 v45, -v43, v38, v34
	v_fmac_f32_e32 v38, v45, v44
	v_fma_f32 v34, -v43, v38, v34
	v_mul_f32_e32 v43, 0xbfb8aa3b, v40
	v_exp_f32_e32 v43, v43
	v_div_fmas_f32 v34, v34, v44, v38
	v_div_fixup_f32 v34, v34, v42, v39
	v_mul_f32_e32 v34, v35, v34
	v_add_f32_e32 v38, 1.0, v43
	v_div_scale_f32 v39, s[0:1], v38, v38, v40
	v_rcp_f32_e32 v42, v39
	s_nop 0
	v_cvt_pk_bf16_f32 v34, v34, s0
	ds_write_b16 v0, v34 offset:2480
	v_fma_f32 v34, -v39, v42, 1.0
	v_fmac_f32_e32 v42, v34, v42
	v_div_scale_f32 v34, vcc, v40, v38, v40
	v_mul_f32_e32 v35, v34, v42
	v_fma_f32 v43, -v39, v35, v34
	v_fmac_f32_e32 v35, v43, v42
	v_fma_f32 v34, -v39, v35, v34
	v_mul_f32_e32 v39, 0xbfb8aa3b, v41
	v_exp_f32_e32 v39, v39
	v_div_fmas_f32 v34, v34, v42, v35
	v_div_fixup_f32 v34, v34, v38, v40
	v_mul_f32_e32 v34, v36, v34
	v_add_f32_e32 v35, 1.0, v39
	v_div_scale_f32 v38, s[0:1], v35, v35, v41
	v_rcp_f32_e32 v39, v38
	s_nop 0
	v_cvt_pk_bf16_f32 v34, v34, s0
	ds_write_b16 v0, v34 offset:2624
	v_fma_f32 v34, -v38, v39, 1.0
	v_fmac_f32_e32 v39, v34, v39
	v_div_scale_f32 v34, vcc, v41, v35, v41
	v_mul_f32_e32 v36, v34, v39
	v_fma_f32 v40, -v38, v36, v34
	v_fmac_f32_e32 v36, v40, v39
	v_fma_f32 v34, -v38, v36, v34
	v_mul_f32_e32 v38, 0xbfb8aa3b, v30
	v_exp_f32_e32 v38, v38
	v_div_fmas_f32 v34, v34, v39, v36
	v_div_fixup_f32 v34, v34, v35, v41
	v_mul_f32_e32 v34, v37, v34
	v_add_f32_e32 v35, 1.0, v38
	v_div_scale_f32 v36, s[0:1], v35, v35, v30
	v_rcp_f32_e32 v38, v36
	s_nop 0
	v_cvt_pk_bf16_f32 v34, v34, s0
	ds_write_b16 v0, v34 offset:2768
	v_fma_f32 v34, -v36, v38, 1.0
	v_fmac_f32_e32 v38, v34, v38
	v_div_scale_f32 v34, vcc, v30, v35, v30
	v_mul_f32_e32 v37, v34, v38
	v_fma_f32 v39, -v36, v37, v34
	v_fmac_f32_e32 v37, v39, v38
	v_fma_f32 v34, -v36, v37, v34
	v_mul_f32_e32 v36, 0xbfb8aa3b, v31
	v_exp_f32_e32 v36, v36
	v_div_fmas_f32 v34, v34, v38, v37
	v_div_fixup_f32 v30, v34, v35, v30
	v_mul_f32_e32 v26, v26, v30
	v_add_f32_e32 v34, 1.0, v36
	v_div_scale_f32 v35, s[0:1], v34, v34, v31
	v_rcp_f32_e32 v36, v35
	s_nop 0
	v_cvt_pk_bf16_f32 v26, v26, s0
	ds_write_b16 v0, v26 offset:4608
	v_fma_f32 v26, -v35, v36, 1.0
	v_fmac_f32_e32 v36, v26, v36
	v_div_scale_f32 v26, vcc, v31, v34, v31
	v_mul_f32_e32 v30, v26, v36
	v_fma_f32 v37, -v35, v30, v26
	v_fmac_f32_e32 v30, v37, v36
	v_fma_f32 v26, -v35, v30, v26
	v_mul_f32_e32 v35, 0xbfb8aa3b, v32
	v_exp_f32_e32 v35, v35
	v_div_fmas_f32 v26, v26, v36, v30
	v_div_fixup_f32 v26, v26, v34, v31
	v_mul_f32_e32 v26, v27, v26
	v_add_f32_e32 v30, 1.0, v35
	v_div_scale_f32 v31, s[0:1], v30, v30, v32
	v_rcp_f32_e32 v34, v31
	s_nop 0
	v_cvt_pk_bf16_f32 v26, v26, s0
	ds_write_b16 v0, v26 offset:4752
	v_fma_f32 v26, -v31, v34, 1.0
	v_fmac_f32_e32 v34, v26, v34
	v_div_scale_f32 v26, vcc, v32, v30, v32
	v_mul_f32_e32 v27, v26, v34
	v_fma_f32 v35, -v31, v27, v26
	v_fmac_f32_e32 v27, v35, v34
	v_fma_f32 v26, -v31, v27, v26
	v_mul_f32_e32 v31, 0xbfb8aa3b, v33
	v_exp_f32_e32 v31, v31
	v_div_fmas_f32 v26, v26, v34, v27
	v_div_fixup_f32 v26, v26, v30, v32
	v_mul_f32_e32 v26, v28, v26
	v_add_f32_e32 v27, 1.0, v31
	v_div_scale_f32 v30, s[0:1], v27, v27, v33
	v_rcp_f32_e32 v31, v30
	s_nop 0
	v_cvt_pk_bf16_f32 v26, v26, s0
	ds_write_b16 v0, v26 offset:4896
	v_fma_f32 v26, -v30, v31, 1.0
	v_fmac_f32_e32 v31, v26, v31
	v_div_scale_f32 v26, vcc, v33, v27, v33
	v_mul_f32_e32 v28, v26, v31
	v_fma_f32 v32, -v30, v28, v26
	v_fmac_f32_e32 v28, v32, v31
	v_fma_f32 v26, -v30, v28, v26
	v_mul_f32_e32 v30, 0xbfb8aa3b, v22
	v_exp_f32_e32 v30, v30
	v_div_fmas_f32 v26, v26, v31, v28
	v_div_fixup_f32 v26, v26, v27, v33
; __device__ __forceinline__ u16 f2bf(float f) { return (u16)(pack2(f, 0.f) & 0xffffu); }
; __device__ __forceinline__ float silu_f(float x) { return x / (1.f + __expf(-x)); }
; __device__ __forceinline__ void phase_moe_up(const Params& p, int l, bool last, unsigned char* smem) {
;     ...
; #pragma unroll
;       for (int mi = 0; mi < 4; ++mi)
; #pragma unroll
;         for (int n2 = 0; n2 < 2; ++n2)
; #pragma unroll
;           for (int j = 0; j < 4; ++j) {
;             const int m = r0 + mi * 16 + j;
;             const int fl = (c0 >> 6) * 32 + n2 * 16 + (c0 & 15);
;             Ts[m * 72 + fl] = f2bf(silu_f(acc[mi][2 * n2][j]) * acc[mi][2 * n2 + 1][j]);
;           }
	v_mul_f32_e32 v26, v29, v26
	v_add_f32_e32 v27, 1.0, v30
	v_div_scale_f32 v28, s[0:1], v27, v27, v22
	v_rcp_f32_e32 v30, v28
	s_nop 0
	v_cvt_pk_bf16_f32 v26, v26, s0
	ds_write_b16 v0, v26 offset:5040
	v_fma_f32 v26, -v28, v30, 1.0
	v_fmac_f32_e32 v30, v26, v30
	v_div_scale_f32 v26, vcc, v22, v27, v22
	v_mul_f32_e32 v29, v26, v30
	v_fma_f32 v31, -v28, v29, v26
	v_fmac_f32_e32 v29, v31, v30
	v_fma_f32 v26, -v28, v29, v26
	v_mul_f32_e32 v28, 0xbfb8aa3b, v23
	v_exp_f32_e32 v28, v28
	v_div_fmas_f32 v26, v26, v30, v29
	v_div_fixup_f32 v22, v26, v27, v22
	v_mul_f32_e32 v18, v18, v22
	v_add_f32_e32 v26, 1.0, v28
	v_div_scale_f32 v27, s[0:1], v26, v26, v23
	v_rcp_f32_e32 v28, v27
	s_nop 0
	v_cvt_pk_bf16_f32 v18, v18, s0
	ds_write_b16 v0, v18 offset:4640
	v_fma_f32 v18, -v27, v28, 1.0
	v_fmac_f32_e32 v28, v18, v28
	v_div_scale_f32 v18, vcc, v23, v26, v23
	v_mul_f32_e32 v22, v18, v28
	v_fma_f32 v29, -v27, v22, v18
	v_fmac_f32_e32 v22, v29, v28
	v_fma_f32 v18, -v27, v22, v18
	v_mul_f32_e32 v27, 0xbfb8aa3b, v24
	v_exp_f32_e32 v27, v27
	v_div_fmas_f32 v18, v18, v28, v22
	v_div_fixup_f32 v18, v18, v26, v23
	v_mul_f32_e32 v18, v19, v18
	v_add_f32_e32 v22, 1.0, v27
	v_div_scale_f32 v23, s[0:1], v22, v22, v24
	v_rcp_f32_e32 v26, v23
	s_nop 0
	v_cvt_pk_bf16_f32 v18, v18, s0
	ds_write_b16 v0, v18 offset:4784
	v_fma_f32 v18, -v23, v26, 1.0
	v_fmac_f32_e32 v26, v18, v26
	v_div_scale_f32 v18, vcc, v24, v22, v24
	v_mul_f32_e32 v19, v18, v26
	v_fma_f32 v27, -v23, v19, v18
	v_fmac_f32_e32 v19, v27, v26
	v_fma_f32 v18, -v23, v19, v18
	v_mul_f32_e32 v23, 0xbfb8aa3b, v25
	v_exp_f32_e32 v23, v23
	v_div_fmas_f32 v18, v18, v26, v19
	v_div_fixup_f32 v18, v18, v22, v24
	v_mul_f32_e32 v18, v20, v18
	v_add_f32_e32 v19, 1.0, v23
	v_div_scale_f32 v22, s[0:1], v19, v19, v25
	v_rcp_f32_e32 v23, v22
	s_nop 0
	v_cvt_pk_bf16_f32 v18, v18, s0
	ds_write_b16 v0, v18 offset:4928
	v_fma_f32 v18, -v22, v23, 1.0
	v_fmac_f32_e32 v23, v18, v23
	v_div_scale_f32 v18, vcc, v25, v19, v25
	v_mul_f32_e32 v20, v18, v23
	v_fma_f32 v24, -v22, v20, v18
	v_fmac_f32_e32 v20, v24, v23
	v_fma_f32 v18, -v22, v20, v18
	v_mul_f32_e32 v22, 0xbfb8aa3b, v14
	v_exp_f32_e32 v22, v22
	v_div_fmas_f32 v18, v18, v23, v20
	v_div_fixup_f32 v18, v18, v19, v25
	v_mul_f32_e32 v18, v21, v18
	v_add_f32_e32 v19, 1.0, v22
	v_div_scale_f32 v20, s[0:1], v19, v19, v14
	v_rcp_f32_e32 v22, v20
	s_nop 0
	v_cvt_pk_bf16_f32 v18, v18, s0
	ds_write_b16 v0, v18 offset:5072
	v_fma_f32 v18, -v20, v22, 1.0
	v_fmac_f32_e32 v22, v18, v22
	v_div_scale_f32 v18, vcc, v14, v19, v14
	v_mul_f32_e32 v21, v18, v22
	v_fma_f32 v23, -v20, v21, v18
	v_fmac_f32_e32 v21, v23, v22
	v_fma_f32 v18, -v20, v21, v18
	v_mul_f32_e32 v20, 0xbfb8aa3b, v15
	v_exp_f32_e32 v20, v20
	v_div_fmas_f32 v18, v18, v22, v21
	v_div_fixup_f32 v14, v18, v19, v14
	v_mul_f32_e32 v10, v10, v14
	v_add_f32_e32 v18, 1.0, v20
	v_div_scale_f32 v19, s[0:1], v18, v18, v15
	v_rcp_f32_e32 v20, v19
	s_nop 0
	v_cvt_pk_bf16_f32 v10, v10, s0
	ds_write_b16 v0, v10 offset:6912
	v_fma_f32 v10, -v19, v20, 1.0
	v_fmac_f32_e32 v20, v10, v20
	v_div_scale_f32 v10, vcc, v15, v18, v15
	v_mul_f32_e32 v14, v10, v20
	v_fma_f32 v21, -v19, v14, v10
	v_fmac_f32_e32 v14, v21, v20
	v_fma_f32 v10, -v19, v14, v10
	v_mul_f32_e32 v19, 0xbfb8aa3b, v16
	v_exp_f32_e32 v19, v19
	v_div_fmas_f32 v10, v10, v20, v14
	v_div_fixup_f32 v10, v10, v18, v15
	v_mul_f32_e32 v10, v11, v10
	v_add_f32_e32 v14, 1.0, v19
	v_div_scale_f32 v15, s[0:1], v14, v14, v16
	v_rcp_f32_e32 v18, v15
	s_nop 0
	v_cvt_pk_bf16_f32 v10, v10, s0
	ds_write_b16 v0, v10 offset:7056
	v_fma_f32 v10, -v15, v18, 1.0
	v_fmac_f32_e32 v18, v10, v18
	v_div_scale_f32 v10, vcc, v16, v14, v16
	v_mul_f32_e32 v11, v10, v18
	v_fma_f32 v19, -v15, v11, v10
	v_fmac_f32_e32 v11, v19, v18
	v_fma_f32 v10, -v15, v11, v10
	v_mul_f32_e32 v15, 0xbfb8aa3b, v17
	v_exp_f32_e32 v15, v15
	v_div_fmas_f32 v10, v10, v18, v11
	v_div_fixup_f32 v10, v10, v14, v16
	v_mul_f32_e32 v10, v12, v10
	v_add_f32_e32 v11, 1.0, v15
	v_div_scale_f32 v14, s[0:1], v11, v11, v17
	v_rcp_f32_e32 v15, v14
	s_nop 0
	v_cvt_pk_bf16_f32 v10, v10, s0
	ds_write_b16 v0, v10 offset:7200
	v_fma_f32 v10, -v14, v15, 1.0
	v_fmac_f32_e32 v15, v10, v15
	v_div_scale_f32 v10, vcc, v17, v11, v17
	v_mul_f32_e32 v12, v10, v15
	v_fma_f32 v16, -v14, v12, v10
	v_fmac_f32_e32 v12, v16, v15
	v_fma_f32 v10, -v14, v12, v10
	v_mul_f32_e32 v14, 0xbfb8aa3b, v6
	v_exp_f32_e32 v14, v14
	v_div_fmas_f32 v10, v10, v15, v12
	v_div_fixup_f32 v10, v10, v11, v17
	v_mul_f32_e32 v10, v13, v10
	v_add_f32_e32 v11, 1.0, v14
	v_div_scale_f32 v12, s[0:1], v11, v11, v6
	v_rcp_f32_e32 v14, v12
	s_nop 0
	v_cvt_pk_bf16_f32 v10, v10, s0
	ds_write_b16 v0, v10 offset:7344
	v_fma_f32 v10, -v12, v14, 1.0
	v_fmac_f32_e32 v14, v10, v14
	v_div_scale_f32 v10, vcc, v6, v11, v6
	v_mul_f32_e32 v13, v10, v14
	v_fma_f32 v15, -v12, v13, v10
	v_fmac_f32_e32 v13, v15, v14
	v_fma_f32 v10, -v12, v13, v10
	v_mul_f32_e32 v12, 0xbfb8aa3b, v7
	v_exp_f32_e32 v12, v12
	v_div_fmas_f32 v10, v10, v14, v13
	v_div_fixup_f32 v6, v10, v11, v6
	v_mul_f32_e32 v2, v2, v6
	v_add_f32_e32 v10, 1.0, v12
	v_div_scale_f32 v11, s[0:1], v10, v10, v7
	v_rcp_f32_e32 v12, v11
	s_nop 0
	v_cvt_pk_bf16_f32 v2, v2, s0
	ds_write_b16 v0, v2 offset:6944
	v_fma_f32 v2, -v11, v12, 1.0
	v_fmac_f32_e32 v12, v2, v12
	v_div_scale_f32 v2, vcc, v7, v10, v7
	v_mul_f32_e32 v6, v2, v12
	v_fma_f32 v13, -v11, v6, v2
	v_fmac_f32_e32 v6, v13, v12
	v_fma_f32 v2, -v11, v6, v2
	v_mul_f32_e32 v11, 0xbfb8aa3b, v8
	v_exp_f32_e32 v11, v11
	v_div_fmas_f32 v2, v2, v12, v6
	v_div_fixup_f32 v2, v2, v10, v7
	v_mul_f32_e32 v2, v3, v2
	v_add_f32_e32 v6, 1.0, v11
	v_div_scale_f32 v7, s[0:1], v6, v6, v8
	v_rcp_f32_e32 v10, v7
	s_nop 0
	v_cvt_pk_bf16_f32 v2, v2, s0
	ds_write_b16 v0, v2 offset:7088
	v_fma_f32 v2, -v7, v10, 1.0
	v_fmac_f32_e32 v10, v2, v10
	v_div_scale_f32 v2, vcc, v8, v6, v8
	v_mul_f32_e32 v3, v2, v10
	v_fma_f32 v11, -v7, v3, v2
	v_fmac_f32_e32 v3, v11, v10
	v_fma_f32 v2, -v7, v3, v2
	v_mul_f32_e32 v7, 0xbfb8aa3b, v9
	v_exp_f32_e32 v7, v7
	v_div_fmas_f32 v2, v2, v10, v3
	v_div_fixup_f32 v2, v2, v6, v8
	v_mul_f32_e32 v2, v4, v2
	v_add_f32_e32 v3, 1.0, v7
	v_div_scale_f32 v6, s[0:1], v3, v3, v9
	v_rcp_f32_e32 v7, v6
	s_nop 0
	v_cvt_pk_bf16_f32 v2, v2, s0
	ds_write_b16 v0, v2 offset:7232
	v_fma_f32 v2, -v6, v7, 1.0
	v_fmac_f32_e32 v7, v2, v7
	v_div_scale_f32 v2, vcc, v9, v3, v9
	v_mul_f32_e32 v4, v2, v7
	v_fma_f32 v8, -v6, v4, v2
	v_fmac_f32_e32 v4, v8, v7
	v_fma_f32 v2, -v6, v4, v2
	v_div_fmas_f32 v2, v2, v7, v4
	v_div_fixup_f32 v2, v2, v3, v9
	v_mul_f32_e32 v2, v5, v2
	v_cvt_pk_bf16_f32 v2, v2, s0
	ds_write_b16 v0, v2 offset:7376
	v_lshlrev_b32_e32 v0, 3, v66
	v_and_b32_e32 v0, 56, v0
	v_ashrrev_i32_e32 v3, 3, v66
	v_lshlrev_b32_e32 v2, 1, v0
	v_cmp_gt_i32_e32 vcc, s86, v3
	s_waitcnt lgkmcnt(0)
	s_barrier
; __device__ __forceinline__ void phase_moe_up(const Params& p, int l, bool last, unsigned char* smem) {
;     ...
; #pragma unroll
;       for (int i = 0; i < 4; ++i) {
;         const int c = t2 + 256 * i, row = c >> 3, ch = c & 7;
;         if (row < mvalid) *(u32x4*)(p.HID + (size_t)(hid_row + row) * 512 + nt * 64 + ch * 8) = *(const u32x4*)(Ts + row * 72 + ch * 8);
;       }
	s_and_saveexec_b64 s[0:1], vcc
	s_xor_b64 s[0:1], exec, s[0:1]
	s_cbranch_execz .LBB0_1196
	v_mov_b64_e32 v[4:5], s[4:5]
	global_load_dwordx2 v[8:9], v[4:5], off offset:368
	v_mad_u64_u32 v[4:5], s[40:41], v3, s96, v[2:3]
	v_add_u32_e32 v10, s82, v3
	ds_read_b128 v[4:7], v4
	v_ashrrev_i32_e32 v11, 31, v10
	v_lshlrev_b64 v[10:11], 10, v[10:11]
	s_lshl_b32 s94, s83, 7
	v_mov_b32_e32 v3, v1
	s_waitcnt vmcnt(0) lgkmcnt(0)
	v_lshl_add_u64 v[8:9], v[8:9], 0, v[10:11]
	v_lshl_add_u64 v[8:9], v[8:9], 0, s[94:95]
	v_lshl_add_u64 v[8:9], v[8:9], 0, v[2:3]
	global_store_dwordx4 v[8:9], v[4:7], off
.LBB0_1196:
	s_or_b64 exec, exec, s[0:1]
	v_add_u32_e32 v3, 0x100, v66
	v_ashrrev_i32_e32 v3, 3, v3
	v_cmp_gt_i32_e32 vcc, s86, v3
	s_and_saveexec_b64 s[0:1], vcc
	s_cbranch_execz .LBB0_1198
	v_mov_b64_e32 v[4:5], s[4:5]
	global_load_dwordx2 v[8:9], v[4:5], off offset:368
	v_mad_u64_u32 v[4:5], s[40:41], v3, s96, v[2:3]
	v_add_u32_e32 v10, s82, v3
	ds_read_b128 v[4:7], v4
	v_ashrrev_i32_e32 v11, 31, v10
	v_lshlrev_b64 v[10:11], 10, v[10:11]
	s_lshl_b32 s94, s83, 7
	v_mov_b32_e32 v3, v1
	s_waitcnt vmcnt(0) lgkmcnt(0)
	v_lshl_add_u64 v[8:9], v[8:9], 0, v[10:11]
	v_lshl_add_u64 v[8:9], v[8:9], 0, s[94:95]
	v_lshl_add_u64 v[8:9], v[8:9], 0, v[2:3]
	global_store_dwordx4 v[8:9], v[4:7], off
.LBB0_1198:
	s_or_b64 exec, exec, s[0:1]
	v_add_u32_e32 v3, 0x200, v66
	v_ashrrev_i32_e32 v3, 3, v3
	v_cmp_gt_i32_e32 vcc, s86, v3
	s_and_saveexec_b64 s[0:1], vcc
	s_cbranch_execz .LBB0_1200
	v_mov_b64_e32 v[4:5], s[4:5]
	global_load_dwordx2 v[8:9], v[4:5], off offset:368
	v_mad_u64_u32 v[4:5], s[40:41], v3, s96, v[2:3]
	v_add_u32_e32 v10, s82, v3
	ds_read_b128 v[4:7], v4
	v_ashrrev_i32_e32 v11, 31, v10
	v_lshlrev_b64 v[10:11], 10, v[10:11]
	s_lshl_b32 s94, s83, 7
	v_mov_b32_e32 v3, v1
	s_waitcnt vmcnt(0) lgkmcnt(0)
	v_lshl_add_u64 v[8:9], v[8:9], 0, v[10:11]
	v_lshl_add_u64 v[8:9], v[8:9], 0, s[94:95]
	v_lshl_add_u64 v[2:3], v[8:9], 0, v[2:3]
	global_store_dwordx4 v[2:3], v[4:7], off

; __device__ __forceinline__ void phase_moe_up(const Params& p, int l, bool last, unsigned char* smem) {
;     ...
; #pragma unroll
;       for (int i = 0; i < 4; ++i) {
;         const int c = t2 + 256 * i, row = c >> 3, ch = c & 7;
;         if (row < mvalid) *(u32x4*)(p.HID + (size_t)(hid_row + row) * 512 + nt * 64 + ch * 8) = *(const u32x4*)(Ts + row * 72 + ch * 8);
;       }
.LBB0_1202:
	v_mov_b64_e32 v[4:5], s[4:5]
	global_load_dwordx2 v[6:7], v[4:5], off offset:368
	v_mul_lo_u32 v3, v2, s96
	v_add_u32_e32 v8, s82, v2
	v_lshl_add_u32 v2, v0, 1, v3
	v_ashrrev_i32_e32 v9, 31, v8
	ds_read_b128 v[2:5], v2
	v_lshlrev_b64 v[8:9], 10, v[8:9]
	s_lshl_b32 s94, s83, 7
	s_waitcnt vmcnt(0) lgkmcnt(0)
	v_lshl_add_u64 v[6:7], v[6:7], 0, v[8:9]
	v_lshl_add_u64 v[6:7], v[6:7], 0, s[94:95]
	v_lshl_add_u64 v[6:7], v[0:1], 1, v[6:7]
	global_store_dwordx4 v[6:7], v[2:5], off
	s_branch .LBB0_1102

; template <int NT, bool BKN, bool MASK = false, bool ROWSS = false, class Epi> ...
;     ...
;   const int t = tid_(), lane = t & 63, wid = t >> 6, wr = wid >> 1, wc = wid & 1, l16 = lane & 15, quad = lane >> 4;
;   const u16* ap[4];
;   const u16* bp[NT];
;   unsigned amask = 0u;
; #pragma unroll
;   for (int i = 0; i < 4; ++i) {
;     const int row = (t >> 3) + 32 * i;
;     const bool v = MASK ? (row < mvalid) : true;
;     amask |= v ? (1u << i) : 0u;
;     int r = v ? row : 0;
;     if (arows) r = arows[r];
;     ap[i] = A + (size_t)r * lda + (t & 7) * 8;
;   }
; #pragma unroll
;   for (int i = 0; i < NT; ++i) {
;     if (!BKN) bp[i] = B + (size_t)((t >> 3) + 32 * i) * ldb + (t & 7) * 8;
;     else { const int c = t + 256 * i; bp[i] = B + (size_t)(c / CPR) * ldb + (c % CPR) * 8; }
;   }
;   const size_t bstep = BKN ? (size_t)64 * ldb : (size_t)64;
;   int nmi = 4;
;   if (MASK) { nmi = (mvalid - wr * 64 + 15) >> 4; nmi = nmi < 0 ? 0 : (nmi > 4 ? 4 : nmi); nmi = __builtin_amdgcn_readfirstlane(nmi); }
;   u32x4 ra0[4], rb0[NT], ra1[4], rb1[NT];
; __device__ __forceinline__ void phase_moe_down(const Params& p, int l, bool last, unsigned char* smem) {
;     ...
;   XCD_FOR(t, ((pass == npass - 1) ? 2048 : 256)) {
;     int inst, mt, nt, mvalid, hid_row;
;     if (pass == npass - 1) { const int e_ = t >> 7, b_ = (t >> 6) & 1; inst = b_ * 16 + e_; mt = (t >> 3) & 7; nt = t & 7; mvalid = 128; hid_row = inst * 1024 + mt * 128; }
;     else { const int e_ = t >> 4, b_ = (t >> 3) & 1; inst = 32 + b_ * 16 + e_; mt = 0; nt = t & 7; mvalid = 32; hid_row = 32768 + (inst - 32) * 128; }
;     const int e = inst & 15;
;     const float* gate = p.GATE + (size_t)inst * 1024 + mt * 128;
;     const u16* W = p.WdT + (size_t)(l * 16 + e) * 1024 * 512 + (size_t)nt * 128 * 512;
;     u16* yb = p.YB + (size_t)hid_row * 1024 + nt * 128;
;     auto epi = [&](f32x4(&acc)[4][4], int r0, int c0) {
;       auto vf = [&](int r, int, float v) { return (r < mvalid ? gate[r] : 0.f) * v; };
;       auto rp = [&](int r) -> u16* { return r < mvalid ? yb + (size_t)r * 1024 : nullptr; };
;       epi_staged_bf16<4>(acc, r0, c0, smem, vf, rp);
;     };
;     if (mvalid == 128) gemm_tile<4, false, false>(p.HID + (size_t)hid_row * 512, 512, nullptr, 128, W, 512, 512, smem, epi);
;     else gemm_tile<4, false, true>(p.HID + (size_t)hid_row * 512, 512, nullptr, mvalid, W, 512, 512, smem, epi);
.LBB0_1272:
	v_mov_b64_e32 v[2:3], s[4:5]
	global_load_dwordx2 v[4:5], v[2:3], off offset:384
	s_ashr_i32 s39, s38, 31
	s_lshl_b64 s[40:41], s[38:39], 12
	s_lshl_b32 s94, s8, 2
	s_lshl_b32 s8, s38, 19
	s_and_b32 s8, s8, 0x780000
	s_or_b32 s8, s8, s18
	s_and_b32 s42, s57, 7
	s_ashr_i32 s37, s36, 31
	s_and_b64 vcc, exec, s[34:35]
	global_load_dwordx2 v[164:165], v[2:3], off offset:424
	s_waitcnt vmcnt(0) lgkmcnt(0)
	v_lshl_add_u64 v[4:5], v[4:5], 0, s[40:41]
	v_lshl_add_u64 v[162:163], v[4:5], 0, s[94:95]
	global_load_dwordx2 v[4:5], v[2:3], off offset:232
	s_lshl_b32 s94, s8, 1
	global_load_dwordx2 v[2:3], v[2:3], off offset:368
	s_lshl_b64 s[8:9], s[36:37], 11
	s_waitcnt vmcnt(0) lgkmcnt(0)
	v_lshl_add_u64 v[4:5], v[4:5], 0, s[94:95]
	s_lshl_b32 s94, s42, 17
	v_lshl_add_u64 v[166:167], v[4:5], 0, s[94:95]
	v_lshl_add_u64 v[4:5], v[164:165], 0, s[8:9]
	s_lshl_b32 s94, s42, 8
	s_lshl_b64 s[8:9], s[36:37], 10
	v_lshl_add_u64 v[160:161], v[4:5], 0, s[94:95]
	v_lshl_add_u64 v[168:169], v[2:3], 0, s[8:9]
	s_mov_b64 s[36:37], -1
	s_cbranch_vccz .LBB0_1278
	v_mov_b32_e32 v140, v187
	s_nop 0
	v_ashrrev_i32_e32 v4, 3, v140
	v_cmp_gt_i32_e64 s[40:41], s60, v4
	v_lshlrev_b32_e32 v3, 4, v140
	v_and_b32_e32 v0, 0x70, v3
	v_cndmask_b32_e64 v8, 0, v4, s[40:41]
	v_ashrrev_i32_e32 v9, 31, v8
	v_lshl_add_u64 v[6:7], v[168:169], 0, v[0:1]
	v_lshlrev_b64 v[8:9], 10, v[8:9]
	v_lshl_add_u64 v[170:171], v[6:7], 0, v[8:9]
	v_add_u32_e32 v8, 32, v4
	v_cmp_gt_i32_e64 s[42:43], s60, v8
	v_ashrrev_i32_e32 v5, 31, v4
	v_ashrrev_i32_e32 v9, 31, v8
	v_cndmask_b32_e64 v10, 0, v8, s[42:43]
	v_ashrrev_i32_e32 v11, 31, v10
	v_lshlrev_b64 v[10:11], 10, v[10:11]
	v_lshl_add_u64 v[172:173], v[6:7], 0, v[10:11]
	v_add_u32_e32 v10, 64, v4
	v_cmp_gt_i32_e64 s[44:45], s60, v10
	v_ashrrev_i32_e32 v11, 31, v10
	s_barrier
	v_cndmask_b32_e64 v12, 0, v10, s[44:45]
	v_ashrrev_i32_e32 v13, 31, v12
	v_lshlrev_b64 v[12:13], 10, v[12:13]
	v_lshl_add_u64 v[174:175], v[6:7], 0, v[12:13]
	v_add_u32_e32 v12, 0x60, v4
	v_cmp_gt_i32_e64 s[38:39], s60, v12
	v_lshlrev_b64 v[4:5], 10, v[4:5]
	v_ashrrev_i32_e32 v13, 31, v12
	v_cndmask_b32_e64 v14, 0, v12, s[38:39]
	v_ashrrev_i32_e32 v15, 31, v14
	v_lshlrev_b64 v[14:15], 10, v[14:15]
	v_lshl_add_u64 v[176:177], v[6:7], 0, v[14:15]
	v_lshl_add_u64 v[6:7], v[166:167], 0, v[0:1]
	v_lshl_add_u64 v[178:179], v[6:7], 0, v[4:5]
	v_lshlrev_b64 v[4:5], 10, v[8:9]
	v_lshl_add_u64 v[180:181], v[6:7], 0, v[4:5]
	v_lshlrev_b64 v[4:5], 10, v[10:11]
	v_lshl_add_u64 v[182:183], v[6:7], 0, v[4:5]
	v_lshlrev_b64 v[4:5], 10, v[12:13]
	v_lshl_add_u64 v[184:185], v[6:7], 0, v[4:5]
	global_load_dwordx4 v[4:7], v[170:171], off
	global_load_dwordx4 v[8:11], v[172:173], off
	global_load_dwordx4 v[12:15], v[174:175], off
	global_load_dwordx4 v[16:19], v[176:177], off
	global_load_dwordx4 v[20:23], v[178:179], off
	global_load_dwordx4 v[24:27], v[180:181], off
	global_load_dwordx4 v[28:31], v[182:183], off
	global_load_dwordx4 v[32:35], v[184:185], off
	global_load_dwordx4 v[128:131], v[170:171], off offset:128
	global_load_dwordx4 v[120:123], v[172:173], off offset:128
	global_load_dwordx4 v[124:127], v[174:175], off offset:128
	global_load_dwordx4 v[108:111], v[176:177], off offset:128
	global_load_dwordx4 v[100:103], v[178:179], off offset:128
	global_load_dwordx4 v[104:107], v[180:181], off offset:128
	global_load_dwordx4 v[112:115], v[182:183], off offset:128
	global_load_dwordx4 v[116:119], v[184:185], off offset:128
	v_ashrrev_i32_e32 v0, 1, v140
	v_and_b32_e32 v190, 0xffffffc0, v0
	v_sub_u32_e32 v0, s60, v190
	v_ashrrev_i32_e32 v0, 4, v0
	v_lshrrev_b32_e32 v2, 4, v140
	v_med3_i32 v0, v0, 0, 4
	v_and_b32_e32 v3, 0xffffff80, v3
	v_readfirstlane_b32 s8, v0
	v_xor_b32_e32 v0, v2, v140
	v_lshlrev_b32_e32 v0, 4, v0
	v_and_or_b32 v191, v0, s14, v3
	v_and_b32_e32 v189, 15, v140
	v_bfe_u32 v141, v140, 1, 3
	v_bfe_u32 v188, v140, 6, 1
	v_bitop3_b32 v0, v2, v141, 3 bitop3:0x6c
	v_lshlrev_b32_e32 v2, 6, v189
	v_or_b32_e32 v142, v190, v189
	v_lshlrev_b32_e32 v0, 4, v0
	v_lshl_or_b32 v143, v188, 12, v2
	v_lshl_or_b32 v192, v142, 7, v0
	v_lshl_or_b32 v193, v143, 1, v0
	s_cmp_gt_i32 s8, 0
	s_cselect_b64 s[36:37], -1, 0
	s_cmp_lt_i32 s8, 1
	s_waitcnt vmcnt(0) lgkmcnt(0)
	v_cndmask_b32_e64 v7, 0, v7, s[40:41]
	v_cndmask_b32_e64 v6, 0, v6, s[40:41]
	v_cndmask_b32_e64 v5, 0, v5, s[40:41]
	v_cndmask_b32_e64 v4, 0, v4, s[40:41]
	v_cndmask_b32_e64 v11, 0, v11, s[42:43]
	v_cndmask_b32_e64 v10, 0, v10, s[42:43]
	v_cndmask_b32_e64 v9, 0, v9, s[42:43]
	v_cndmask_b32_e64 v8, 0, v8, s[42:43]
	v_cndmask_b32_e64 v15, 0, v15, s[44:45]
	v_cndmask_b32_e64 v14, 0, v14, s[44:45]
	v_cndmask_b32_e64 v13, 0, v13, s[44:45]
	v_cndmask_b32_e64 v12, 0, v12, s[44:45]
	v_cndmask_b32_e64 v19, 0, v19, s[38:39]
	v_cndmask_b32_e64 v18, 0, v18, s[38:39]
	v_cndmask_b32_e64 v17, 0, v17, s[38:39]
	v_cndmask_b32_e64 v16, 0, v16, s[38:39]
	ds_write_b128 v191, v[4:7]
	ds_write_b128 v191, v[8:11] offset:4096
	ds_write_b128 v191, v[12:15] offset:8192
	ds_write_b128 v191, v[16:19] offset:12288
	ds_write_b128 v191, v[20:23] offset:16384
	ds_write_b128 v191, v[24:27] offset:20480
	ds_write_b128 v191, v[28:31] offset:24576
	ds_write_b128 v191, v[32:35] offset:28672
	global_load_dwordx4 v[88:91], v[170:171], off offset:256
	global_load_dwordx4 v[92:95], v[172:173], off offset:256
	global_load_dwordx4 v[76:79], v[174:175], off offset:256
	global_load_dwordx4 v[68:71], v[176:177], off offset:256
	global_load_dwordx4 v[72:75], v[178:179], off offset:256
	global_load_dwordx4 v[80:83], v[180:181], off offset:256
	global_load_dwordx4 v[84:87], v[182:183], off offset:256
	global_load_dwordx4 v[96:99], v[184:185], off offset:256
	s_waitcnt lgkmcnt(0)
	s_barrier
	ds_read_b128 v[20:23], v192 offset:2048
	ds_read_b128 v[16:19], v192 offset:4096
	ds_read_b128 v[4:7], v192 offset:6144
	ds_read_b128 v[8:11], v193 offset:16384
	ds_read_b128 v[12:15], v193 offset:18432
	ds_read_b128 v[132:135], v193 offset:20480
	ds_read_b128 v[136:139], v193 offset:22528
	s_cbranch_scc1 .LBB0_1422
	ds_read_b128 v[24:27], v192
	s_waitcnt lgkmcnt(0)
	v_mfma_f32_16x16x32_bf16 v[64:67], v[24:27], v[8:11], 0
	v_mfma_f32_16x16x32_bf16 v[60:63], v[24:27], v[12:15], 0
	v_mfma_f32_16x16x32_bf16 v[56:59], v[24:27], v[132:135], 0
	v_mfma_f32_16x16x32_bf16 v[52:55], v[24:27], v[136:139], 0
	s_cmp_gt_i32 s8, 1
	s_cselect_b64 s[0:1], -1, 0
	s_cmp_lt_i32 s8, 2
	s_cbranch_scc1 .LBB0_1423

; template <int NT, bool BKN, bool MASK = false, bool ROWSS = false, class Epi> ...
;     ...
;   float ss_[4] = {0.f, 0.f, 0.f, 0.f};
;   int stk_ = 0;
;   f32x4 acc[4][NT];
; #pragma unroll
;   for (int i = 0; i < 4; ++i)
; #pragma unroll
;     for (int j = 0; j < NT; ++j) acc[i][j] = (f32x4){0.f, 0.f, 0.f, 0.f};
;   const int nk = K >> 6;
;   const int nkm1 = nk - 1;
;   __syncthreads();
;   GEMM_LOAD(ra0, rb0, 0);
;   GEMM_LOAD(ra1, rb1, 1);
;   GEMM_STORE(ra0, rb0, 0);
;   GEMM_LOAD(ra0, rb0, (2 < nkm1 ? 2 : nkm1));
;   __syncthreads();
;   for (int kt = 0; kt < nk - 2; kt += 2) {
;     GEMM_COMPUTE(0);
;     GEMM_STORE(ra1, rb1, 1);
;     GEMM_LOAD(ra1, rb1, kt + 3);
.LBB0_1278:
	s_and_b64 vcc, exec, s[36:37]
	s_cbranch_vccz .LBB0_1659
	v_mov_b32_e32 v85, v187
	s_waitcnt lgkmcnt(0)
	v_ashrrev_i32_e32 v2, 3, v85
	v_lshlrev_b32_e32 v12, 4, v85
	v_ashrrev_i32_e32 v3, 31, v2
	v_and_b32_e32 v0, 0x70, v12
	v_lshlrev_b64 v[2:3], 10, v[2:3]
	v_lshl_add_u64 v[4:5], v[168:169], 0, v[0:1]
	v_lshl_add_u64 v[6:7], v[2:3], 0, s[10:11]
	v_lshl_add_u64 v[8:9], v[2:3], 0, s[12:13]
	v_lshl_add_u64 v[10:11], v[2:3], 0, s[26:27]
	v_lshl_add_u64 v[66:67], v[4:5], 0, v[2:3]
	v_lshl_add_u64 v[68:69], v[4:5], 0, v[6:7]
	v_lshl_add_u64 v[70:71], v[4:5], 0, v[8:9]
	v_lshl_add_u64 v[72:73], v[4:5], 0, v[10:11]
	v_lshl_add_u64 v[4:5], v[166:167], 0, v[0:1]
	v_lshl_add_u64 v[74:75], v[4:5], 0, v[2:3]
	v_lshl_add_u64 v[76:77], v[4:5], 0, v[6:7]
	v_lshl_add_u64 v[78:79], v[4:5], 0, v[8:9]
	v_lshl_add_u64 v[80:81], v[4:5], 0, v[10:11]
	s_barrier
	global_load_dwordx4 v[34:37], v[66:67], off
	global_load_dwordx4 v[38:41], v[74:75], off
	global_load_dwordx4 v[42:45], v[68:69], off
	global_load_dwordx4 v[46:49], v[70:71], off
	global_load_dwordx4 v[50:53], v[72:73], off
	global_load_dwordx4 v[54:57], v[76:77], off
	global_load_dwordx4 v[58:61], v[78:79], off
	global_load_dwordx4 v[62:65], v[80:81], off
	v_lshrrev_b32_e32 v2, 4, v85
	v_bfe_u32 v86, v85, 1, 3
	v_xor_b32_e32 v3, v2, v85
	v_and_b32_e32 v4, 0xffffff80, v12
	v_bitop3_b32 v2, v2, v86, 3 bitop3:0x6c
	v_lshlrev_b32_e32 v3, 4, v3
	v_lshlrev_b32_e32 v89, 4, v2
	v_and_or_b32 v87, v3, s14, v4
	global_load_dwordx4 v[90:93], v[66:67], off offset:128
	global_load_dwordx4 v[94:97], v[74:75], off offset:128
	global_load_dwordx4 v[2:5], v[66:67], off offset:256
	global_load_dwordx4 v[6:9], v[74:75], off offset:256
	global_load_dwordx4 v[98:101], v[70:71], off offset:128
	global_load_dwordx4 v[102:105], v[78:79], off offset:128
	global_load_dwordx4 v[106:109], v[68:69], off offset:128
	global_load_dwordx4 v[10:13], v[68:69], off offset:256
	global_load_dwordx4 v[14:17], v[70:71], off offset:256
	global_load_dwordx4 v[110:113], v[72:73], off offset:128
	global_load_dwordx4 v[18:21], v[72:73], off offset:256
	global_load_dwordx4 v[114:117], v[76:77], off offset:128
	global_load_dwordx4 v[22:25], v[76:77], off offset:256
	global_load_dwordx4 v[26:29], v[78:79], off offset:256
	global_load_dwordx4 v[118:121], v[80:81], off offset:128
	global_load_dwordx4 v[30:33], v[80:81], off offset:256
	v_and_b32_e32 v82, 15, v85
	v_ashrrev_i32_e32 v0, 7, v85
	v_lshlrev_b32_e32 v88, 7, v82
	v_lshl_or_b32 v158, v0, 13, v88
	v_or_b32_e32 v84, v89, v158
	v_bfe_u32 v83, v85, 6, 1
	v_bfe_u32 v85, v85, 4, 2
	v_lshl_or_b32 v159, v83, 13, v88
	v_bitop3_b32 v86, v85, v86, 4 bitop3:0x36
	v_or_b32_e32 v88, v89, v159
	v_lshlrev_b32_e32 v89, 4, v86
	v_or_b32_e32 v86, v89, v158
	v_or_b32_e32 v89, v89, v159
	v_lshlrev_b32_e32 v0, 6, v0
	s_waitcnt vmcnt(0) lgkmcnt(0)
	ds_write_b128 v87, v[34:37]
	ds_write_b128 v87, v[38:41] offset:16384
	ds_write_b128 v87, v[42:45] offset:4096
	ds_write_b128 v87, v[46:49] offset:8192
	ds_write_b128 v87, v[50:53] offset:12288
	ds_write_b128 v87, v[54:57] offset:20480
	ds_write_b128 v87, v[58:61] offset:24576
	ds_write_b128 v87, v[62:65] offset:28672
	s_waitcnt lgkmcnt(0)
	s_barrier
	ds_read_b128 v[34:37], v84
	ds_read_b128 v[122:125], v84 offset:2048
	ds_read_b128 v[138:141], v84 offset:4096
	ds_read_b128 v[154:157], v84 offset:6144
	ds_read_b128 v[38:41], v88 offset:16384
	ds_read_b128 v[46:49], v88 offset:18432
	ds_read_b128 v[54:57], v88 offset:20480
	ds_read_b128 v[62:65], v88 offset:22528
	ds_read_b128 v[166:169], v86
	ds_read_b128 v[188:191], v86 offset:6144
	s_waitcnt lgkmcnt(5)
	v_mfma_f32_16x16x32_bf16 v[42:45], v[34:37], v[38:41], 0
	ds_read_b128 v[182:185], v89 offset:22528
	s_waitcnt lgkmcnt(5)
	v_mfma_f32_16x16x32_bf16 v[50:53], v[34:37], v[46:49], 0
	s_waitcnt lgkmcnt(4)
	v_mfma_f32_16x16x32_bf16 v[58:61], v[34:37], v[54:57], 0
	s_waitcnt lgkmcnt(3)
	v_mfma_f32_16x16x32_bf16 v[34:37], v[34:37], v[62:65], 0
	v_mfma_f32_16x16x32_bf16 v[126:129], v[122:125], v[38:41], 0
	v_mfma_f32_16x16x32_bf16 v[130:133], v[122:125], v[46:49], 0
	v_mfma_f32_16x16x32_bf16 v[134:137], v[122:125], v[54:57], 0
	v_mfma_f32_16x16x32_bf16 v[122:125], v[122:125], v[62:65], 0
	v_mfma_f32_16x16x32_bf16 v[142:145], v[138:141], v[38:41], 0
	v_mfma_f32_16x16x32_bf16 v[146:149], v[138:141], v[46:49], 0
	v_mfma_f32_16x16x32_bf16 v[150:153], v[138:141], v[54:57], 0
	v_mfma_f32_16x16x32_bf16 v[138:141], v[138:141], v[62:65], 0
	v_mfma_f32_16x16x32_bf16 v[38:41], v[154:157], v[38:41], 0
	v_mfma_f32_16x16x32_bf16 v[46:49], v[154:157], v[46:49], 0
	v_mfma_f32_16x16x32_bf16 v[54:57], v[154:157], v[54:57], 0
	v_mfma_f32_16x16x32_bf16 v[154:157], v[154:157], v[62:65], 0
	ds_read_b128 v[62:65], v89 offset:16384
	s_waitcnt lgkmcnt(0)
	v_mfma_f32_16x16x32_bf16 v[170:173], v[166:169], v[62:65], v[42:45]
	s_nop 2
	ds_read_b128 v[42:45], v89 offset:18432
	s_waitcnt lgkmcnt(0)
	v_mfma_f32_16x16x32_bf16 v[174:177], v[166:169], v[42:45], v[50:53]
	s_nop 2
	ds_read_b128 v[50:53], v89 offset:20480
	s_waitcnt lgkmcnt(0)
	v_mfma_f32_16x16x32_bf16 v[178:181], v[166:169], v[50:53], v[58:61]
	v_mfma_f32_16x16x32_bf16 v[166:169], v[166:169], v[182:185], v[34:37]
	s_nop 2
	ds_read_b128 v[34:37], v86 offset:2048
	s_waitcnt lgkmcnt(0)
	v_mfma_f32_16x16x32_bf16 v[126:129], v[34:37], v[62:65], v[126:129]
	v_mfma_f32_16x16x32_bf16 v[130:133], v[34:37], v[42:45], v[130:133]
	v_mfma_f32_16x16x32_bf16 v[134:137], v[34:37], v[50:53], v[134:137]
	v_mfma_f32_16x16x32_bf16 v[122:125], v[34:37], v[182:185], v[122:125]
	ds_read_b128 v[34:37], v86 offset:4096
	ds_write_b128 v87, v[90:93] offset:32768
	ds_write_b128 v87, v[106:109] offset:36864
	ds_write_b128 v87, v[98:101] offset:40960
	ds_write_b128 v87, v[110:113] offset:45056
	ds_write_b128 v87, v[94:97] offset:49152
	ds_write_b128 v87, v[114:117] offset:53248
	ds_write_b128 v87, v[102:105] offset:57344
	ds_write_b128 v87, v[118:121] offset:61440
	s_waitcnt lgkmcnt(8)
	v_mfma_f32_16x16x32_bf16 v[142:145], v[34:37], v[62:65], v[142:145]
	v_mfma_f32_16x16x32_bf16 v[146:149], v[34:37], v[42:45], v[146:149]
	v_mfma_f32_16x16x32_bf16 v[150:153], v[34:37], v[50:53], v[150:153]
	v_mfma_f32_16x16x32_bf16 v[138:141], v[34:37], v[182:185], v[138:141]
	v_mfma_f32_16x16x32_bf16 v[192:195], v[188:191], v[62:65], v[38:41]
	v_mfma_f32_16x16x32_bf16 v[196:199], v[188:191], v[42:45], v[46:49]
	v_mfma_f32_16x16x32_bf16 v[200:203], v[188:191], v[50:53], v[54:57]
	global_load_dwordx4 v[34:37], v[66:67], off offset:384
	global_load_dwordx4 v[38:41], v[68:69], off offset:384
	global_load_dwordx4 v[42:45], v[70:71], off offset:384
	global_load_dwordx4 v[46:49], v[72:73], off offset:384
	global_load_dwordx4 v[50:53], v[74:75], off offset:384
	global_load_dwordx4 v[54:57], v[76:77], off offset:384
	global_load_dwordx4 v[58:61], v[78:79], off offset:384
	global_load_dwordx4 v[62:65], v[80:81], off offset:384
	s_waitcnt lgkmcnt(0)
	s_barrier
; template <int NT, bool BKN, bool MASK = false, bool ROWSS = false, class Epi> ...
;     ...
;   for (int kt = 0; kt < nk - 2; kt += 2) {
;     GEMM_COMPUTE(0);
;     GEMM_STORE(ra1, rb1, 1);
;     GEMM_LOAD(ra1, rb1, kt + 3);
;     __syncthreads();
;     GEMM_COMPUTE(1);
;     GEMM_STORE(ra0, rb0, 0);
;     GEMM_LOAD(ra0, rb0, (kt + 4 < nkm1 ? kt + 4 : nkm1));
;     __syncthreads();
;   }
	ds_read_b128 v[90:93], v84 offset:32768
	ds_read_b128 v[98:101], v88 offset:49152
	v_mfma_f32_16x16x32_bf16 v[94:97], v[188:191], v[182:185], v[154:157]
	ds_read_b128 v[106:109], v88 offset:51200
	ds_read_b128 v[114:117], v88 offset:53248
	s_nop 0
	ds_read_b128 v[154:157], v88 offset:55296
	s_waitcnt lgkmcnt(0)
	v_mfma_f32_16x16x32_bf16 v[102:105], v[90:93], v[98:101], v[170:173]
	s_nop 2
	ds_read_b128 v[170:173], v86 offset:32768
	v_mfma_f32_16x16x32_bf16 v[110:113], v[90:93], v[106:109], v[174:177]
	v_mfma_f32_16x16x32_bf16 v[118:121], v[90:93], v[114:117], v[178:181]
	s_nop 1
	ds_read_b128 v[174:177], v89 offset:53248
	v_mfma_f32_16x16x32_bf16 v[90:93], v[90:93], v[154:157], v[166:169]
	ds_read_b128 v[178:181], v89 offset:55296
	s_nop 1
	ds_read_b128 v[166:169], v84 offset:34816
	s_waitcnt lgkmcnt(0)
	v_mfma_f32_16x16x32_bf16 v[126:129], v[166:169], v[98:101], v[126:129]
	v_mfma_f32_16x16x32_bf16 v[130:133], v[166:169], v[106:109], v[130:133]
	v_mfma_f32_16x16x32_bf16 v[134:137], v[166:169], v[114:117], v[134:137]
	v_mfma_f32_16x16x32_bf16 v[122:125], v[166:169], v[154:157], v[122:125]
	ds_read_b128 v[166:169], v84 offset:36864
	s_waitcnt lgkmcnt(0)
	v_mfma_f32_16x16x32_bf16 v[142:145], v[166:169], v[98:101], v[142:145]
	v_mfma_f32_16x16x32_bf16 v[146:149], v[166:169], v[106:109], v[146:149]
	v_mfma_f32_16x16x32_bf16 v[150:153], v[166:169], v[114:117], v[150:153]
	v_mfma_f32_16x16x32_bf16 v[138:141], v[166:169], v[154:157], v[138:141]
	ds_read_b128 v[166:169], v84 offset:38912
	s_waitcnt lgkmcnt(0)
	v_mfma_f32_16x16x32_bf16 v[98:101], v[166:169], v[98:101], v[192:195]
	v_mfma_f32_16x16x32_bf16 v[106:109], v[166:169], v[106:109], v[196:199]
	v_mfma_f32_16x16x32_bf16 v[114:117], v[166:169], v[114:117], v[200:203]
	v_mfma_f32_16x16x32_bf16 v[94:97], v[166:169], v[154:157], v[94:97]
	ds_read_b128 v[154:157], v89 offset:49152
	ds_read_b128 v[166:169], v89 offset:51200
	s_waitcnt lgkmcnt(0)
	v_mfma_f32_16x16x32_bf16 v[102:105], v[170:173], v[154:157], v[102:105]
	v_mfma_f32_16x16x32_bf16 v[110:113], v[170:173], v[166:169], v[110:113]
	v_mfma_f32_16x16x32_bf16 v[118:121], v[170:173], v[174:177], v[118:121]
	v_mfma_f32_16x16x32_bf16 v[90:93], v[170:173], v[178:181], v[90:93]
	ds_read_b128 v[170:173], v86 offset:34816
	s_waitcnt lgkmcnt(0)
	v_mfma_f32_16x16x32_bf16 v[126:129], v[170:173], v[154:157], v[126:129]
	v_mfma_f32_16x16x32_bf16 v[130:133], v[170:173], v[166:169], v[130:133]
	v_mfma_f32_16x16x32_bf16 v[134:137], v[170:173], v[174:177], v[134:137]
	v_mfma_f32_16x16x32_bf16 v[122:125], v[170:173], v[178:181], v[122:125]
	ds_read_b128 v[170:173], v86 offset:36864
	s_waitcnt lgkmcnt(0)
	v_mfma_f32_16x16x32_bf16 v[142:145], v[170:173], v[154:157], v[142:145]
	v_mfma_f32_16x16x32_bf16 v[146:149], v[170:173], v[166:169], v[146:149]
	v_mfma_f32_16x16x32_bf16 v[150:153], v[170:173], v[174:177], v[150:153]
	v_mfma_f32_16x16x32_bf16 v[138:141], v[170:173], v[178:181], v[138:141]
	ds_read_b128 v[170:173], v86 offset:38912
	ds_write_b128 v87, v[2:5]
	ds_write_b128 v87, v[10:13] offset:4096
	ds_write_b128 v87, v[14:17] offset:8192
	ds_write_b128 v87, v[18:21] offset:12288
	ds_write_b128 v87, v[6:9] offset:16384
	ds_write_b128 v87, v[22:25] offset:20480
	ds_write_b128 v87, v[26:29] offset:24576
	ds_write_b128 v87, v[30:33] offset:28672
	global_load_dwordx4 v[2:5], v[66:67], off offset:512
	global_load_dwordx4 v[6:9], v[68:69], off offset:512
	global_load_dwordx4 v[10:13], v[70:71], off offset:512
	global_load_dwordx4 v[14:17], v[72:73], off offset:512
	global_load_dwordx4 v[18:21], v[74:75], off offset:512
	global_load_dwordx4 v[22:25], v[76:77], off offset:512
	global_load_dwordx4 v[26:29], v[78:79], off offset:512
	global_load_dwordx4 v[30:33], v[80:81], off offset:512
	s_waitcnt lgkmcnt(0)
	v_mfma_f32_16x16x32_bf16 v[98:101], v[170:173], v[154:157], v[98:101]
	s_barrier
	ds_read_b128 v[154:157], v84
	v_mfma_f32_16x16x32_bf16 v[106:109], v[170:173], v[166:169], v[106:109]
	ds_read_b128 v[166:169], v88 offset:16384
	v_mfma_f32_16x16x32_bf16 v[114:117], v[170:173], v[174:177], v[114:117]
	ds_read_b128 v[174:177], v88 offset:20480
	v_mfma_f32_16x16x32_bf16 v[94:97], v[170:173], v[178:181], v[94:97]
	ds_read_b128 v[170:173], v88 offset:18432
	ds_read_b128 v[178:181], v88 offset:22528
	s_waitcnt lgkmcnt(0)
	v_mfma_f32_16x16x32_bf16 v[102:105], v[154:157], v[166:169], v[102:105]
	v_mfma_f32_16x16x32_bf16 v[110:113], v[154:157], v[170:173], v[110:113]
	v_mfma_f32_16x16x32_bf16 v[118:121], v[154:157], v[174:177], v[118:121]
	v_mfma_f32_16x16x32_bf16 v[90:93], v[154:157], v[178:181], v[90:93]
	ds_read_b128 v[154:157], v84 offset:2048
	s_waitcnt lgkmcnt(0)
	v_mfma_f32_16x16x32_bf16 v[126:129], v[154:157], v[166:169], v[126:129]
	v_mfma_f32_16x16x32_bf16 v[130:133], v[154:157], v[170:173], v[130:133]
	v_mfma_f32_16x16x32_bf16 v[134:137], v[154:157], v[174:177], v[134:137]
	v_mfma_f32_16x16x32_bf16 v[122:125], v[154:157], v[178:181], v[122:125]
	ds_read_b128 v[154:157], v84 offset:4096
	s_waitcnt lgkmcnt(0)
	v_mfma_f32_16x16x32_bf16 v[142:145], v[154:157], v[166:169], v[142:145]
	v_mfma_f32_16x16x32_bf16 v[146:149], v[154:157], v[170:173], v[146:149]
	v_mfma_f32_16x16x32_bf16 v[150:153], v[154:157], v[174:177], v[150:153]
	v_mfma_f32_16x16x32_bf16 v[138:141], v[154:157], v[178:181], v[138:141]
	ds_read_b128 v[154:157], v84 offset:6144
	s_waitcnt lgkmcnt(0)
	v_mfma_f32_16x16x32_bf16 v[98:101], v[154:157], v[166:169], v[98:101]
	ds_read_b128 v[166:169], v86
	v_mfma_f32_16x16x32_bf16 v[106:109], v[154:157], v[170:173], v[106:109]
	ds_read_b128 v[170:173], v89 offset:18432
	v_mfma_f32_16x16x32_bf16 v[114:117], v[154:157], v[174:177], v[114:117]
	ds_read_b128 v[174:177], v89 offset:20480
	v_mfma_f32_16x16x32_bf16 v[94:97], v[154:157], v[178:181], v[94:97]
	ds_read_b128 v[154:157], v89 offset:16384
	ds_read_b128 v[178:181], v89 offset:22528
	s_waitcnt lgkmcnt(0)
; template <int NT, bool BKN, bool MASK = false, bool ROWSS = false, class Epi> ...
;     ...
;   for (int kt = 0; kt < nk - 2; kt += 2) {
;     GEMM_COMPUTE(0);
;     GEMM_STORE(ra1, rb1, 1);
;     GEMM_LOAD(ra1, rb1, kt + 3);
;     __syncthreads();
;     GEMM_COMPUTE(1);
;     GEMM_STORE(ra0, rb0, 0);
;     GEMM_LOAD(ra0, rb0, (kt + 4 < nkm1 ? kt + 4 : nkm1));
;     __syncthreads();
;   }
	v_mfma_f32_16x16x32_bf16 v[102:105], v[166:169], v[154:157], v[102:105]
	v_mfma_f32_16x16x32_bf16 v[110:113], v[166:169], v[170:173], v[110:113]
	v_mfma_f32_16x16x32_bf16 v[118:121], v[166:169], v[174:177], v[118:121]
	v_mfma_f32_16x16x32_bf16 v[90:93], v[166:169], v[178:181], v[90:93]
	ds_read_b128 v[166:169], v86 offset:2048
	s_waitcnt lgkmcnt(0)
	v_mfma_f32_16x16x32_bf16 v[126:129], v[166:169], v[154:157], v[126:129]
	v_mfma_f32_16x16x32_bf16 v[130:133], v[166:169], v[170:173], v[130:133]
	v_mfma_f32_16x16x32_bf16 v[134:137], v[166:169], v[174:177], v[134:137]
	v_mfma_f32_16x16x32_bf16 v[122:125], v[166:169], v[178:181], v[122:125]
	ds_read_b128 v[166:169], v86 offset:4096
	s_waitcnt lgkmcnt(0)
	v_mfma_f32_16x16x32_bf16 v[142:145], v[166:169], v[154:157], v[142:145]
	v_mfma_f32_16x16x32_bf16 v[146:149], v[166:169], v[170:173], v[146:149]
	v_mfma_f32_16x16x32_bf16 v[150:153], v[166:169], v[174:177], v[150:153]
	v_mfma_f32_16x16x32_bf16 v[138:141], v[166:169], v[178:181], v[138:141]
	ds_read_b128 v[166:169], v86 offset:6144
	s_waitcnt vmcnt(0)
	ds_write_b128 v87, v[34:37] offset:32768
	ds_write_b128 v87, v[38:41] offset:36864
	ds_write_b128 v87, v[42:45] offset:40960
	ds_write_b128 v87, v[46:49] offset:45056
	ds_write_b128 v87, v[50:53] offset:49152
	ds_write_b128 v87, v[54:57] offset:53248
	ds_write_b128 v87, v[58:61] offset:57344
	ds_write_b128 v87, v[62:65] offset:61440
	global_load_dwordx4 v[34:37], v[66:67], off offset:640
	global_load_dwordx4 v[38:41], v[68:69], off offset:640
	global_load_dwordx4 v[42:45], v[70:71], off offset:640
	global_load_dwordx4 v[46:49], v[72:73], off offset:640
	global_load_dwordx4 v[50:53], v[74:75], off offset:640
	global_load_dwordx4 v[54:57], v[76:77], off offset:640
	global_load_dwordx4 v[58:61], v[78:79], off offset:640
	global_load_dwordx4 v[62:65], v[80:81], off offset:640
	s_waitcnt lgkmcnt(0)
	v_mfma_f32_16x16x32_bf16 v[98:101], v[166:169], v[154:157], v[98:101]
	s_barrier
	ds_read_b128 v[154:157], v84 offset:32768
	v_mfma_f32_16x16x32_bf16 v[106:109], v[166:169], v[170:173], v[106:109]
	ds_read_b128 v[170:173], v88 offset:51200
	v_mfma_f32_16x16x32_bf16 v[114:117], v[166:169], v[174:177], v[114:117]
	ds_read_b128 v[174:177], v88 offset:53248
	v_mfma_f32_16x16x32_bf16 v[94:97], v[166:169], v[178:181], v[94:97]
	ds_read_b128 v[166:169], v88 offset:49152
	ds_read_b128 v[178:181], v88 offset:55296
	s_waitcnt lgkmcnt(0)
	v_mfma_f32_16x16x32_bf16 v[102:105], v[154:157], v[166:169], v[102:105]
	v_mfma_f32_16x16x32_bf16 v[110:113], v[154:157], v[170:173], v[110:113]
	v_mfma_f32_16x16x32_bf16 v[118:121], v[154:157], v[174:177], v[118:121]
	v_mfma_f32_16x16x32_bf16 v[90:93], v[154:157], v[178:181], v[90:93]
	ds_read_b128 v[154:157], v84 offset:34816
	s_waitcnt lgkmcnt(0)
	v_mfma_f32_16x16x32_bf16 v[126:129], v[154:157], v[166:169], v[126:129]
	v_mfma_f32_16x16x32_bf16 v[130:133], v[154:157], v[170:173], v[130:133]
	v_mfma_f32_16x16x32_bf16 v[134:137], v[154:157], v[174:177], v[134:137]
	v_mfma_f32_16x16x32_bf16 v[122:125], v[154:157], v[178:181], v[122:125]
	ds_read_b128 v[154:157], v84 offset:36864
	s_waitcnt lgkmcnt(0)
	v_mfma_f32_16x16x32_bf16 v[142:145], v[154:157], v[166:169], v[142:145]
	v_mfma_f32_16x16x32_bf16 v[146:149], v[154:157], v[170:173], v[146:149]
	v_mfma_f32_16x16x32_bf16 v[150:153], v[154:157], v[174:177], v[150:153]
	v_mfma_f32_16x16x32_bf16 v[138:141], v[154:157], v[178:181], v[138:141]
	ds_read_b128 v[154:157], v84 offset:38912
	s_waitcnt lgkmcnt(0)
	v_mfma_f32_16x16x32_bf16 v[98:101], v[154:157], v[166:169], v[98:101]
	ds_read_b128 v[166:169], v86 offset:32768
	v_mfma_f32_16x16x32_bf16 v[106:109], v[154:157], v[170:173], v[106:109]
	ds_read_b128 v[170:173], v89 offset:51200
	v_mfma_f32_16x16x32_bf16 v[114:117], v[154:157], v[174:177], v[114:117]
	ds_read_b128 v[174:177], v89 offset:53248
	v_mfma_f32_16x16x32_bf16 v[94:97], v[154:157], v[178:181], v[94:97]
	ds_read_b128 v[154:157], v89 offset:49152
	ds_read_b128 v[178:181], v89 offset:55296
	s_waitcnt lgkmcnt(0)
	v_mfma_f32_16x16x32_bf16 v[102:105], v[166:169], v[154:157], v[102:105]
	v_mfma_f32_16x16x32_bf16 v[110:113], v[166:169], v[170:173], v[110:113]
	v_mfma_f32_16x16x32_bf16 v[118:121], v[166:169], v[174:177], v[118:121]
	v_mfma_f32_16x16x32_bf16 v[90:93], v[166:169], v[178:181], v[90:93]
	ds_read_b128 v[166:169], v86 offset:34816
	s_waitcnt lgkmcnt(0)
	v_mfma_f32_16x16x32_bf16 v[126:129], v[166:169], v[154:157], v[126:129]
	v_mfma_f32_16x16x32_bf16 v[130:133], v[166:169], v[170:173], v[130:133]
	v_mfma_f32_16x16x32_bf16 v[134:137], v[166:169], v[174:177], v[134:137]
	v_mfma_f32_16x16x32_bf16 v[122:125], v[166:169], v[178:181], v[122:125]
	ds_read_b128 v[166:169], v86 offset:36864
	s_waitcnt lgkmcnt(0)
	v_mfma_f32_16x16x32_bf16 v[142:145], v[166:169], v[154:157], v[142:145]
	v_mfma_f32_16x16x32_bf16 v[146:149], v[166:169], v[170:173], v[146:149]
	v_mfma_f32_16x16x32_bf16 v[150:153], v[166:169], v[174:177], v[150:153]
	v_mfma_f32_16x16x32_bf16 v[138:141], v[166:169], v[178:181], v[138:141]
	ds_read_b128 v[166:169], v86 offset:38912
	ds_write_b128 v87, v[2:5]
	ds_write_b128 v87, v[6:9] offset:4096
	ds_write_b128 v87, v[10:13] offset:8192
	ds_write_b128 v87, v[14:17] offset:12288
	ds_write_b128 v87, v[18:21] offset:16384
	ds_write_b128 v87, v[22:25] offset:20480
	ds_write_b128 v87, v[26:29] offset:24576
	ds_write_b128 v87, v[30:33] offset:28672
	global_load_dwordx4 v[2:5], v[66:67], off offset:768
	global_load_dwordx4 v[6:9], v[68:69], off offset:768
	global_load_dwordx4 v[10:13], v[70:71], off offset:768
	global_load_dwordx4 v[14:17], v[72:73], off offset:768
	global_load_dwordx4 v[18:21], v[74:75], off offset:768
	global_load_dwordx4 v[22:25], v[76:77], off offset:768
	global_load_dwordx4 v[26:29], v[78:79], off offset:768
	global_load_dwordx4 v[30:33], v[80:81], off offset:768
	s_waitcnt lgkmcnt(0)
	v_mfma_f32_16x16x32_bf16 v[98:101], v[166:169], v[154:157], v[98:101]
	s_barrier
; template <int NT, bool BKN, bool MASK = false, bool ROWSS = false, class Epi> ...
;     ...
;   for (int kt = 0; kt < nk - 2; kt += 2) {
;     GEMM_COMPUTE(0);
;     GEMM_STORE(ra1, rb1, 1);
;     GEMM_LOAD(ra1, rb1, kt + 3);
;     __syncthreads();
;     GEMM_COMPUTE(1);
;     GEMM_STORE(ra0, rb0, 0);
;     GEMM_LOAD(ra0, rb0, (kt + 4 < nkm1 ? kt + 4 : nkm1));
;     __syncthreads();
;   }
	ds_read_b128 v[154:157], v84
	v_mfma_f32_16x16x32_bf16 v[106:109], v[166:169], v[170:173], v[106:109]
	ds_read_b128 v[170:173], v88 offset:18432
	v_mfma_f32_16x16x32_bf16 v[114:117], v[166:169], v[174:177], v[114:117]
	ds_read_b128 v[174:177], v88 offset:20480
	v_mfma_f32_16x16x32_bf16 v[94:97], v[166:169], v[178:181], v[94:97]
	ds_read_b128 v[166:169], v88 offset:16384
	ds_read_b128 v[178:181], v88 offset:22528
	s_waitcnt lgkmcnt(0)
	v_mfma_f32_16x16x32_bf16 v[102:105], v[154:157], v[166:169], v[102:105]
	v_mfma_f32_16x16x32_bf16 v[110:113], v[154:157], v[170:173], v[110:113]
	v_mfma_f32_16x16x32_bf16 v[118:121], v[154:157], v[174:177], v[118:121]
	v_mfma_f32_16x16x32_bf16 v[90:93], v[154:157], v[178:181], v[90:93]
	ds_read_b128 v[154:157], v84 offset:2048
	s_waitcnt lgkmcnt(0)
	v_mfma_f32_16x16x32_bf16 v[126:129], v[154:157], v[166:169], v[126:129]
	v_mfma_f32_16x16x32_bf16 v[130:133], v[154:157], v[170:173], v[130:133]
	v_mfma_f32_16x16x32_bf16 v[134:137], v[154:157], v[174:177], v[134:137]
	v_mfma_f32_16x16x32_bf16 v[122:125], v[154:157], v[178:181], v[122:125]
	ds_read_b128 v[154:157], v84 offset:4096
	s_waitcnt lgkmcnt(0)
	v_mfma_f32_16x16x32_bf16 v[142:145], v[154:157], v[166:169], v[142:145]
	v_mfma_f32_16x16x32_bf16 v[146:149], v[154:157], v[170:173], v[146:149]
	v_mfma_f32_16x16x32_bf16 v[150:153], v[154:157], v[174:177], v[150:153]
	v_mfma_f32_16x16x32_bf16 v[138:141], v[154:157], v[178:181], v[138:141]
	ds_read_b128 v[154:157], v84 offset:6144
	s_waitcnt lgkmcnt(0)
	v_mfma_f32_16x16x32_bf16 v[98:101], v[154:157], v[166:169], v[98:101]
	ds_read_b128 v[166:169], v86
	v_mfma_f32_16x16x32_bf16 v[106:109], v[154:157], v[170:173], v[106:109]
	ds_read_b128 v[170:173], v89 offset:18432
	v_mfma_f32_16x16x32_bf16 v[114:117], v[154:157], v[174:177], v[114:117]
	ds_read_b128 v[174:177], v89 offset:20480
	v_mfma_f32_16x16x32_bf16 v[94:97], v[154:157], v[178:181], v[94:97]
	ds_read_b128 v[154:157], v89 offset:16384
	ds_read_b128 v[178:181], v89 offset:22528
	s_waitcnt lgkmcnt(0)
	v_mfma_f32_16x16x32_bf16 v[102:105], v[166:169], v[154:157], v[102:105]
	v_mfma_f32_16x16x32_bf16 v[110:113], v[166:169], v[170:173], v[110:113]
	v_mfma_f32_16x16x32_bf16 v[118:121], v[166:169], v[174:177], v[118:121]
	v_mfma_f32_16x16x32_bf16 v[90:93], v[166:169], v[178:181], v[90:93]
	ds_read_b128 v[166:169], v86 offset:2048
	s_waitcnt lgkmcnt(0)
	v_mfma_f32_16x16x32_bf16 v[126:129], v[166:169], v[154:157], v[126:129]
	v_mfma_f32_16x16x32_bf16 v[130:133], v[166:169], v[170:173], v[130:133]
	v_mfma_f32_16x16x32_bf16 v[134:137], v[166:169], v[174:177], v[134:137]
	v_mfma_f32_16x16x32_bf16 v[122:125], v[166:169], v[178:181], v[122:125]
	ds_read_b128 v[166:169], v86 offset:4096
	s_waitcnt lgkmcnt(0)
	v_mfma_f32_16x16x32_bf16 v[142:145], v[166:169], v[154:157], v[142:145]
	v_mfma_f32_16x16x32_bf16 v[146:149], v[166:169], v[170:173], v[146:149]
	v_mfma_f32_16x16x32_bf16 v[150:153], v[166:169], v[174:177], v[150:153]
	v_mfma_f32_16x16x32_bf16 v[138:141], v[166:169], v[178:181], v[138:141]
	ds_read_b128 v[166:169], v86 offset:6144
	s_waitcnt vmcnt(0)
	ds_write_b128 v87, v[34:37] offset:32768
	ds_write_b128 v87, v[38:41] offset:36864
	ds_write_b128 v87, v[42:45] offset:40960
	ds_write_b128 v87, v[46:49] offset:45056
	ds_write_b128 v87, v[50:53] offset:49152
	ds_write_b128 v87, v[54:57] offset:53248
	ds_write_b128 v87, v[58:61] offset:57344
	ds_write_b128 v87, v[62:65] offset:61440
	global_load_dwordx4 v[34:37], v[66:67], off offset:896
	global_load_dwordx4 v[38:41], v[68:69], off offset:896
	global_load_dwordx4 v[42:45], v[70:71], off offset:896
	global_load_dwordx4 v[46:49], v[72:73], off offset:896
	global_load_dwordx4 v[50:53], v[74:75], off offset:896
	global_load_dwordx4 v[54:57], v[76:77], off offset:896
	global_load_dwordx4 v[58:61], v[78:79], off offset:896
	global_load_dwordx4 v[62:65], v[80:81], off offset:896
	s_waitcnt lgkmcnt(0)
	s_barrier
	ds_read_b128 v[66:69], v84 offset:32768
	ds_read_b128 v[74:77], v88 offset:49152
	v_mfma_f32_16x16x32_bf16 v[70:73], v[166:169], v[178:181], v[94:97]
	s_nop 2
	ds_read_b128 v[94:97], v88 offset:51200
	v_mfma_f32_16x16x32_bf16 v[98:101], v[166:169], v[154:157], v[98:101]
	ds_read_b128 v[154:157], v88 offset:55296
	s_waitcnt lgkmcnt(0)
	v_mfma_f32_16x16x32_bf16 v[78:81], v[66:69], v[74:77], v[102:105]
	v_mfma_f32_16x16x32_bf16 v[102:105], v[66:69], v[94:97], v[110:113]
	s_nop 2
	ds_read_b128 v[110:113], v88 offset:53248
	s_waitcnt lgkmcnt(0)
	v_mfma_f32_16x16x32_bf16 v[118:121], v[66:69], v[110:113], v[118:121]
	v_mfma_f32_16x16x32_bf16 v[66:69], v[66:69], v[154:157], v[90:93]
	s_nop 2
	ds_read_b128 v[90:93], v84 offset:34816
	s_waitcnt lgkmcnt(0)
	v_mfma_f32_16x16x32_bf16 v[126:129], v[90:93], v[74:77], v[126:129]
	v_mfma_f32_16x16x32_bf16 v[130:133], v[90:93], v[94:97], v[130:133]
	v_mfma_f32_16x16x32_bf16 v[134:137], v[90:93], v[110:113], v[134:137]
	v_mfma_f32_16x16x32_bf16 v[90:93], v[90:93], v[154:157], v[122:125]
	s_nop 2
	ds_read_b128 v[122:125], v84 offset:36864
	s_waitcnt lgkmcnt(0)
	v_mfma_f32_16x16x32_bf16 v[142:145], v[122:125], v[74:77], v[142:145]
	v_mfma_f32_16x16x32_bf16 v[146:149], v[122:125], v[94:97], v[146:149]
	v_mfma_f32_16x16x32_bf16 v[150:153], v[122:125], v[110:113], v[150:153]
	v_mfma_f32_16x16x32_bf16 v[122:125], v[122:125], v[154:157], v[138:141]
	s_nop 2
	ds_read_b128 v[138:141], v84 offset:38912
	v_mfma_f32_16x16x32_bf16 v[106:109], v[166:169], v[170:173], v[106:109]
	v_mfma_f32_16x16x32_bf16 v[114:117], v[166:169], v[174:177], v[114:117]
	s_waitcnt lgkmcnt(0)
; template <int NT, bool BKN, bool MASK = false, bool ROWSS = false, class Epi> ...
;     ...
;   for (int kt = 0; kt < nk - 2; kt += 2) {
;     GEMM_COMPUTE(0);
;     GEMM_STORE(ra1, rb1, 1);
;     GEMM_LOAD(ra1, rb1, kt + 3);
;     __syncthreads();
;     GEMM_COMPUTE(1);
;     GEMM_STORE(ra0, rb0, 0);
;     GEMM_LOAD(ra0, rb0, (kt + 4 < nkm1 ? kt + 4 : nkm1));
;     __syncthreads();
;   }
;   GEMM_COMPUTE(0);
;   GEMM_STORE(ra1, rb1, 1);
;   __syncthreads();
;   GEMM_COMPUTE(1);
	v_mfma_f32_16x16x32_bf16 v[94:97], v[138:141], v[94:97], v[106:109]
	s_nop 4
	ds_read_b128 v[106:109], v86 offset:32768
	v_mfma_f32_16x16x32_bf16 v[74:77], v[138:141], v[74:77], v[98:101]
	v_mfma_f32_16x16x32_bf16 v[98:101], v[138:141], v[110:113], v[114:117]
	ds_read_b128 v[110:113], v89 offset:49152
	v_mfma_f32_16x16x32_bf16 v[70:73], v[138:141], v[154:157], v[70:73]
	s_nop 0
	ds_read_b128 v[114:117], v89 offset:51200
	ds_read_b128 v[138:141], v89 offset:53248
	ds_read_b128 v[154:157], v89 offset:55296
	s_waitcnt lgkmcnt(0)
	v_mfma_f32_16x16x32_bf16 v[78:81], v[106:109], v[110:113], v[78:81]
	v_mfma_f32_16x16x32_bf16 v[102:105], v[106:109], v[114:117], v[102:105]
	v_mfma_f32_16x16x32_bf16 v[118:121], v[106:109], v[138:141], v[118:121]
	v_mfma_f32_16x16x32_bf16 v[66:69], v[106:109], v[154:157], v[66:69]
	ds_read_b128 v[106:109], v86 offset:34816
	s_waitcnt lgkmcnt(0)
	v_mfma_f32_16x16x32_bf16 v[126:129], v[106:109], v[110:113], v[126:129]
	v_mfma_f32_16x16x32_bf16 v[130:133], v[106:109], v[114:117], v[130:133]
	v_mfma_f32_16x16x32_bf16 v[134:137], v[106:109], v[138:141], v[134:137]
	v_mfma_f32_16x16x32_bf16 v[90:93], v[106:109], v[154:157], v[90:93]
	ds_read_b128 v[106:109], v86 offset:36864
	s_waitcnt lgkmcnt(0)
	v_mfma_f32_16x16x32_bf16 v[142:145], v[106:109], v[110:113], v[142:145]
	v_mfma_f32_16x16x32_bf16 v[146:149], v[106:109], v[114:117], v[146:149]
	v_mfma_f32_16x16x32_bf16 v[150:153], v[106:109], v[138:141], v[150:153]
	v_mfma_f32_16x16x32_bf16 v[106:109], v[106:109], v[154:157], v[122:125]
	s_nop 2
	ds_read_b128 v[122:125], v86 offset:38912
	ds_write_b128 v87, v[2:5]
	ds_write_b128 v87, v[6:9] offset:4096
	ds_write_b128 v87, v[10:13] offset:8192
	ds_write_b128 v87, v[14:17] offset:12288
	ds_write_b128 v87, v[18:21] offset:16384
	ds_write_b128 v87, v[22:25] offset:20480
	ds_write_b128 v87, v[26:29] offset:24576
	ds_write_b128 v87, v[30:33] offset:28672
	s_waitcnt lgkmcnt(0)
	s_barrier
	ds_read_b128 v[2:5], v84
	ds_read_b128 v[10:13], v88 offset:16384
	v_mfma_f32_16x16x32_bf16 v[6:9], v[122:125], v[154:157], v[70:73]
	ds_read_b128 v[18:21], v88 offset:18432
	ds_read_b128 v[26:29], v88 offset:20480
	s_nop 0
	ds_read_b128 v[70:73], v88 offset:22528
	s_waitcnt lgkmcnt(0)
	v_mfma_f32_16x16x32_bf16 v[14:17], v[2:5], v[10:13], v[78:81]
	v_mfma_f32_16x16x32_bf16 v[22:25], v[2:5], v[18:21], v[102:105]
	v_mfma_f32_16x16x32_bf16 v[30:33], v[2:5], v[26:29], v[118:121]
	v_mfma_f32_16x16x32_bf16 v[2:5], v[2:5], v[70:73], v[66:69]
	s_nop 2
	ds_read_b128 v[66:69], v84 offset:2048
	v_mfma_f32_16x16x32_bf16 v[74:77], v[122:125], v[110:113], v[74:77]
	s_waitcnt lgkmcnt(0)
	v_mfma_f32_16x16x32_bf16 v[78:81], v[66:69], v[10:13], v[126:129]
	v_mfma_f32_16x16x32_bf16 v[102:105], v[66:69], v[18:21], v[130:133]
	v_mfma_f32_16x16x32_bf16 v[110:113], v[66:69], v[26:29], v[134:137]
	v_mfma_f32_16x16x32_bf16 v[66:69], v[66:69], v[70:73], v[90:93]
	s_nop 2
	ds_read_b128 v[90:93], v84 offset:4096
	v_mfma_f32_16x16x32_bf16 v[94:97], v[122:125], v[114:117], v[94:97]
	v_mfma_f32_16x16x32_bf16 v[98:101], v[122:125], v[138:141], v[98:101]
	s_waitcnt lgkmcnt(0)
	v_mfma_f32_16x16x32_bf16 v[114:117], v[90:93], v[10:13], v[142:145]
	v_mfma_f32_16x16x32_bf16 v[118:121], v[90:93], v[18:21], v[146:149]
	v_mfma_f32_16x16x32_bf16 v[122:125], v[90:93], v[26:29], v[150:153]
	v_mfma_f32_16x16x32_bf16 v[90:93], v[90:93], v[70:73], v[106:109]
	s_nop 2
	ds_read_b128 v[106:109], v84 offset:6144
	s_waitcnt lgkmcnt(0)
	v_mfma_f32_16x16x32_bf16 v[10:13], v[106:109], v[10:13], v[74:77]
	s_nop 2
	ds_read_b128 v[74:77], v86
	v_mfma_f32_16x16x32_bf16 v[18:21], v[106:109], v[18:21], v[94:97]
	v_mfma_f32_16x16x32_bf16 v[26:29], v[106:109], v[26:29], v[98:101]
	s_nop 1
	ds_read_b128 v[94:97], v89 offset:18432
	ds_read_b128 v[98:101], v89 offset:20480
	v_mfma_f32_16x16x32_bf16 v[6:9], v[106:109], v[70:73], v[6:9]
	ds_read_b128 v[70:73], v89 offset:16384
	ds_read_b128 v[106:109], v89 offset:22528
	s_waitcnt lgkmcnt(0)
	v_mfma_f32_16x16x32_bf16 v[14:17], v[74:77], v[70:73], v[14:17]
	v_mfma_f32_16x16x32_bf16 v[22:25], v[74:77], v[94:97], v[22:25]
	v_mfma_f32_16x16x32_bf16 v[30:33], v[74:77], v[98:101], v[30:33]
	v_mfma_f32_16x16x32_bf16 v[2:5], v[74:77], v[106:109], v[2:5]
	ds_read_b128 v[74:77], v86 offset:2048
	s_waitcnt lgkmcnt(0)
	v_mfma_f32_16x16x32_bf16 v[78:81], v[74:77], v[70:73], v[78:81]
	v_mfma_f32_16x16x32_bf16 v[102:105], v[74:77], v[94:97], v[102:105]
	v_mfma_f32_16x16x32_bf16 v[110:113], v[74:77], v[98:101], v[110:113]
	v_mfma_f32_16x16x32_bf16 v[66:69], v[74:77], v[106:109], v[66:69]
	ds_read_b128 v[74:77], v86 offset:4096
	s_waitcnt lgkmcnt(0)
	v_mfma_f32_16x16x32_bf16 v[114:117], v[74:77], v[70:73], v[114:117]
	v_mfma_f32_16x16x32_bf16 v[118:121], v[74:77], v[94:97], v[118:121]
	v_mfma_f32_16x16x32_bf16 v[122:125], v[74:77], v[98:101], v[122:125]
	v_mfma_f32_16x16x32_bf16 v[74:77], v[74:77], v[106:109], v[90:93]
	s_nop 2
	ds_read_b128 v[90:93], v86 offset:6144
	s_waitcnt vmcnt(0)
	ds_write_b128 v87, v[34:37] offset:32768
	ds_write_b128 v87, v[38:41] offset:36864
	ds_write_b128 v87, v[42:45] offset:40960
	ds_write_b128 v87, v[46:49] offset:45056
	ds_write_b128 v87, v[50:53] offset:49152
	ds_write_b128 v87, v[54:57] offset:53248
	ds_write_b128 v87, v[58:61] offset:57344
	ds_write_b128 v87, v[62:65] offset:61440
	s_waitcnt lgkmcnt(0)
	s_barrier
; __device__ __forceinline__ u16 f2bf(float f) { return (u16)(pack2(f, 0.f) & 0xffffu); }
; __device__ __forceinline__ int tid_() { int t = threadIdx.x; asm volatile("" : "+v"(t)); return t; }
; template <int NT, class VF, class RP>
; __device__ __forceinline__ void epi_staged_bf16(f32x4 (&acc)[4][NT], int r0, int c0, unsigned char* smem, VF vf, RP rowptr) {
;   constexpr int BN = NT * 32, PITCH = BN + 8, CPR = BN / 8;
;   u16* Ts = (u16*)smem;
;   const int t = tid_();
;   __syncthreads();
; #pragma unroll
;   for (int mi = 0; mi < 4; ++mi)
; #pragma unroll
;     for (int ni = 0; ni < NT; ++ni)
; #pragma unroll
;       for (int j = 0; j < 4; ++j) {
;         const int r = r0 + mi * 16 + j, c = c0 + ni * 16;
;         Ts[r * PITCH + c] = f2bf(vf(r, c, acc[mi][ni][j]));
; __device__ __forceinline__ void phase_moe_down(const Params& p, int l, bool last, unsigned char* smem) {
;     ...
;     auto epi = [&](f32x4(&acc)[4][4], int r0, int c0) {
;       auto vf = [&](int r, int, float v) { return (r < mvalid ? gate[r] : 0.f) * v; };
;       auto rp = [&](int r) -> u16* { return r < mvalid ? yb + (size_t)r * 1024 : nullptr; };
;       epi_staged_bf16<4>(acc, r0, c0, smem, vf, rp);
	ds_read_b128 v[34:37], v84 offset:32768
	ds_read_b128 v[54:57], v84 offset:36864
	ds_read_b128 v[38:41], v88 offset:49152
	ds_read_b128 v[42:45], v88 offset:51200
	ds_read_b128 v[46:49], v88 offset:53248
	ds_read_b128 v[50:53], v88 offset:55296
	s_waitcnt lgkmcnt(3)
	v_mfma_f32_16x16x32_bf16 v[14:17], v[34:37], v[38:41], v[14:17]
	s_waitcnt lgkmcnt(2)
	v_mfma_f32_16x16x32_bf16 v[22:25], v[34:37], v[42:45], v[22:25]
	s_waitcnt lgkmcnt(1)
	v_mfma_f32_16x16x32_bf16 v[30:33], v[34:37], v[46:49], v[30:33]
	s_waitcnt lgkmcnt(0)
	v_mfma_f32_16x16x32_bf16 v[2:5], v[34:37], v[50:53], v[2:5]
	ds_read_b128 v[34:37], v84 offset:34816
	v_mfma_f32_16x16x32_bf16 v[10:13], v[90:93], v[70:73], v[10:13]
	v_mfma_f32_16x16x32_bf16 v[18:21], v[90:93], v[94:97], v[18:21]
	v_mfma_f32_16x16x32_bf16 v[26:29], v[90:93], v[98:101], v[26:29]
	v_mfma_f32_16x16x32_bf16 v[6:9], v[90:93], v[106:109], v[6:9]
	v_mfma_f32_16x16x32_bf16 v[94:97], v[54:57], v[42:45], v[118:121]
	v_mfma_f32_16x16x32_bf16 v[98:101], v[54:57], v[46:49], v[122:125]
	s_nop 1
	ds_read_b128 v[118:121], v89 offset:53248
	s_waitcnt lgkmcnt(1)
	v_mfma_f32_16x16x32_bf16 v[70:73], v[34:37], v[38:41], v[78:81]
	ds_read_b128 v[122:125], v89 offset:55296
	v_mfma_f32_16x16x32_bf16 v[78:81], v[34:37], v[42:45], v[102:105]
	v_mfma_f32_16x16x32_bf16 v[90:93], v[34:37], v[46:49], v[110:113]
	v_mfma_f32_16x16x32_bf16 v[34:37], v[34:37], v[50:53], v[66:69]
	v_mfma_f32_16x16x32_bf16 v[66:69], v[54:57], v[38:41], v[114:117]
	v_mfma_f32_16x16x32_bf16 v[74:77], v[54:57], v[50:53], v[74:77]
	ds_read_b128 v[54:57], v84 offset:38912
	s_nop 0
	ds_read_b128 v[114:117], v89 offset:51200
	s_waitcnt lgkmcnt(1)
	v_mfma_f32_16x16x32_bf16 v[102:105], v[54:57], v[42:45], v[18:21]
	s_nop 2
	ds_read_b128 v[18:21], v86 offset:32768
	v_mfma_f32_16x16x32_bf16 v[110:113], v[54:57], v[50:53], v[6:9]
	s_nop 2
	ds_read_b128 v[6:9], v89 offset:49152
	s_waitcnt lgkmcnt(1)
	v_mfma_f32_16x16x32_bf16 v[50:53], v[18:21], v[122:125], v[2:5]
	s_nop 2
	ds_read_b128 v[2:5], v86 offset:34816
	v_mfma_f32_16x16x32_bf16 v[10:13], v[54:57], v[38:41], v[10:13]
	v_mfma_f32_16x16x32_bf16 v[106:109], v[54:57], v[46:49], v[26:29]
	s_waitcnt lgkmcnt(0)
	v_mfma_f32_16x16x32_bf16 v[46:49], v[2:5], v[6:9], v[70:73]
	v_mfma_f32_16x16x32_bf16 v[42:45], v[2:5], v[114:117], v[78:81]
	s_nop 1
	v_mov_b32_e32 v70, 0
	v_mfma_f32_16x16x32_bf16 v[38:41], v[2:5], v[118:121], v[90:93]
	v_mfma_f32_16x16x32_bf16 v[34:37], v[2:5], v[122:125], v[34:37]
	ds_read_b128 v[2:5], v86 offset:36864
	v_mfma_f32_16x16x32_bf16 v[62:65], v[18:21], v[6:9], v[14:17]
	v_mfma_f32_16x16x32_bf16 v[58:61], v[18:21], v[114:117], v[22:25]
	v_mfma_f32_16x16x32_bf16 v[54:57], v[18:21], v[118:121], v[30:33]
	s_waitcnt lgkmcnt(0)
	v_mfma_f32_16x16x32_bf16 v[30:33], v[2:5], v[6:9], v[66:69]
	v_mfma_f32_16x16x32_bf16 v[26:29], v[2:5], v[114:117], v[94:97]
	s_nop 1
	v_lshl_or_b32 v66, v85, 2, v0
	v_mov_b32_e32 v0, v187
	v_cmp_gt_i32_e32 vcc, s60, v66
	v_mfma_f32_16x16x32_bf16 v[22:25], v[2:5], v[118:121], v[98:101]
	v_ashrrev_i32_e32 v67, 31, v66
	v_mov_b32_e32 v69, 0
	v_mfma_f32_16x16x32_bf16 v[18:21], v[2:5], v[122:125], v[74:77]
	ds_read_b128 v[2:5], v86 offset:38912
	s_waitcnt lgkmcnt(0)
	v_mfma_f32_16x16x32_bf16 v[14:17], v[2:5], v[6:9], v[10:13]
	s_barrier
	v_mfma_f32_16x16x32_bf16 v[10:13], v[2:5], v[114:117], v[102:105]
	v_mfma_f32_16x16x32_bf16 v[6:9], v[2:5], v[118:121], v[106:109]
	v_mfma_f32_16x16x32_bf16 v[2:5], v[2:5], v[122:125], v[110:113]
	s_and_saveexec_b64 s[0:1], vcc
	s_cbranch_execz .LBB0_1281
	v_lshl_add_u64 v[68:69], v[66:67], 2, v[162:163]
	global_load_dword v69, v[68:69], off
.LBB0_1281:
	s_or_b64 exec, exec, s[0:1]
	v_lshl_or_b32 v68, v83, 6, v82
	s_waitcnt vmcnt(0) lgkmcnt(0)
	v_mul_f32_e32 v62, v62, v69
	v_mul_lo_u32 v69, v66, s22
	v_lshlrev_b32_e32 v71, 1, v68
	v_cvt_pk_bf16_f32 v62, v62, s0
	v_lshl_add_u32 v71, v69, 1, v71
	ds_write_b16 v71, v62
	v_or_b32_e32 v62, 1, v66
	v_cmp_gt_i32_e64 s[38:39], s60, v62
	v_mov_b32_e32 v71, 0
	s_and_saveexec_b64 s[0:1], s[38:39]
	s_cbranch_execz .LBB0_1283
	v_lshl_add_u64 v[72:73], v[66:67], 2, v[162:163]
	global_load_dword v71, v[72:73], off offset:4
.LBB0_1283:
	s_or_b64 exec, exec, s[0:1]
	s_waitcnt vmcnt(0) lgkmcnt(0)
	v_mul_f32_e32 v63, v63, v71
	v_cvt_pk_bf16_f32 v71, v63, s0
	v_mul_lo_u32 v63, v62, s23
	v_lshl_add_u32 v62, v68, 1, v63
	ds_write_b16 v62, v71
	v_or_b32_e32 v71, 2, v66
	v_cmp_gt_i32_e64 s[40:41], s60, v71
	s_and_saveexec_b64 s[0:1], s[40:41]
	s_cbranch_execz .LBB0_1285
	v_lshl_add_u64 v[70:71], v[66:67], 2, v[162:163]
	global_load_dword v70, v[70:71], off offset:8
.LBB0_1285:
	s_or_b64 exec, exec, s[0:1]
	s_waitcnt vmcnt(0) lgkmcnt(0)
	v_mul_f32_e32 v64, v64, v70
	v_add_u32_e32 v63, 0x110, v63
	v_cvt_pk_bf16_f32 v64, v64, s0
	v_lshl_add_u32 v63, v68, 1, v63
	ds_write_b16 v63, v64
	v_or_b32_e32 v64, 3, v66
	v_cmp_gt_i32_e64 s[42:43], s60, v64
	v_mov_b32_e32 v64, 0
	v_mov_b32_e32 v70, 0
	s_and_saveexec_b64 s[0:1], s[42:43]
	s_cbranch_execz .LBB0_1287
	v_lshl_add_u64 v[70:71], v[66:67], 2, v[162:163]
	global_load_dword v70, v[70:71], off offset:12
.LBB0_1287:
	s_or_b64 exec, exec, s[0:1]
	s_waitcnt vmcnt(0) lgkmcnt(0)
	v_mul_f32_e32 v65, v65, v70
	v_cvt_pk_bf16_f32 v65, v65, s0
	ds_write_b16 v63, v65 offset:272
	s_and_saveexec_b64 s[0:1], vcc
	s_cbranch_execz .LBB0_1289
	v_lshl_add_u64 v[64:65], v[66:67], 2, v[162:163]
	global_load_dword v64, v[64:65], off
.LBB0_1289:
	s_or_b64 exec, exec, s[0:1]
	s_waitcnt vmcnt(0) lgkmcnt(0)
	v_mul_f32_e32 v58, v58, v64
	v_lshlrev_b32_e32 v64, 1, v69
	v_cvt_pk_bf16_f32 v58, v58, s0
	v_lshl_add_u32 v64, v68, 1, v64
	ds_write_b16 v64, v58 offset:32
	v_mov_b32_e32 v58, 0
	v_mov_b32_e32 v65, 0
	s_and_saveexec_b64 s[0:1], s[38:39]
	s_cbranch_execz .LBB0_1291
	v_lshl_add_u64 v[70:71], v[66:67], 2, v[162:163]
	global_load_dword v65, v[70:71], off offset:4
; __device__ __forceinline__ u16 f2bf(float f) { return (u16)(pack2(f, 0.f) & 0xffffu); }
; __device__ __forceinline__ int tid_() { int t = threadIdx.x; asm volatile("" : "+v"(t)); return t; }
; template <int NT, class VF, class RP>
; __device__ __forceinline__ void epi_staged_bf16(f32x4 (&acc)[4][NT], int r0, int c0, unsigned char* smem, VF vf, RP rowptr) {
;   constexpr int BN = NT * 32, PITCH = BN + 8, CPR = BN / 8;
;   u16* Ts = (u16*)smem;
;   const int t = tid_();
;   __syncthreads();
; #pragma unroll
;   for (int mi = 0; mi < 4; ++mi)
; #pragma unroll
;     for (int ni = 0; ni < NT; ++ni)
; #pragma unroll
;       for (int j = 0; j < 4; ++j) {
;         const int r = r0 + mi * 16 + j, c = c0 + ni * 16;
;         Ts[r * PITCH + c] = f2bf(vf(r, c, acc[mi][ni][j]));
; __device__ __forceinline__ void phase_moe_down(const Params& p, int l, bool last, unsigned char* smem) {
;     ...
;     auto epi = [&](f32x4(&acc)[4][4], int r0, int c0) {
;       auto vf = [&](int r, int, float v) { return (r < mvalid ? gate[r] : 0.f) * v; };
;       auto rp = [&](int r) -> u16* { return r < mvalid ? yb + (size_t)r * 1024 : nullptr; };
;       epi_staged_bf16<4>(acc, r0, c0, smem, vf, rp);
.LBB0_1291:
	s_or_b64 exec, exec, s[0:1]
	s_waitcnt vmcnt(0) lgkmcnt(0)
	v_mul_f32_e32 v59, v59, v65
	v_cvt_pk_bf16_f32 v59, v59, s0
	ds_write_b16 v62, v59 offset:32
	s_and_saveexec_b64 s[0:1], s[40:41]
	s_cbranch_execz .LBB0_1293
	v_lshl_add_u64 v[58:59], v[66:67], 2, v[162:163]
	global_load_dword v58, v[58:59], off offset:8
.LBB0_1293:
	s_or_b64 exec, exec, s[0:1]
	s_waitcnt vmcnt(0) lgkmcnt(0)
	v_mul_f32_e32 v58, v60, v58
	v_cvt_pk_bf16_f32 v58, v58, s0
	v_mov_b32_e32 v59, 0
	v_mov_b32_e32 v60, 0
	ds_write_b16 v63, v58 offset:32
	s_and_saveexec_b64 s[0:1], s[42:43]
	s_cbranch_execz .LBB0_1295
	v_lshl_add_u64 v[70:71], v[66:67], 2, v[162:163]
	global_load_dword v60, v[70:71], off offset:12
.LBB0_1295:
	s_or_b64 exec, exec, s[0:1]
	s_waitcnt vmcnt(0) lgkmcnt(0)
	v_mul_f32_e32 v60, v61, v60
	v_add_u32_e32 v58, 0x110, v63
	v_cvt_pk_bf16_f32 v60, v60, s0
	ds_write_b16 v58, v60 offset:32
	s_and_saveexec_b64 s[0:1], vcc
	s_cbranch_execz .LBB0_1297
	v_lshl_add_u64 v[60:61], v[66:67], 2, v[162:163]
	global_load_dword v59, v[60:61], off
.LBB0_1297:
	s_or_b64 exec, exec, s[0:1]
	s_waitcnt vmcnt(0) lgkmcnt(0)
	v_mul_f32_e32 v54, v54, v59
	v_cvt_pk_bf16_f32 v54, v54, s0
	ds_write_b16 v64, v54 offset:64
	v_mov_b32_e32 v54, 0
	v_mov_b32_e32 v59, 0
	s_and_saveexec_b64 s[0:1], s[38:39]
	s_cbranch_execz .LBB0_1299
	v_lshl_add_u64 v[60:61], v[66:67], 2, v[162:163]
	global_load_dword v59, v[60:61], off offset:4
.LBB0_1299:
	s_or_b64 exec, exec, s[0:1]
	s_waitcnt vmcnt(0) lgkmcnt(0)
	v_mul_f32_e32 v55, v55, v59
	v_cvt_pk_bf16_f32 v55, v55, s0
	ds_write_b16 v62, v55 offset:64
	s_and_saveexec_b64 s[0:1], s[40:41]
	s_cbranch_execz .LBB0_1301
	v_lshl_add_u64 v[54:55], v[66:67], 2, v[162:163]
	global_load_dword v54, v[54:55], off offset:8
.LBB0_1301:
	s_or_b64 exec, exec, s[0:1]
	s_waitcnt vmcnt(0) lgkmcnt(0)
	v_mul_f32_e32 v54, v56, v54
	v_cvt_pk_bf16_f32 v54, v54, s0
	ds_write_b16 v63, v54 offset:64
	v_mov_b32_e32 v54, 0
	v_mov_b32_e32 v55, 0
	s_and_saveexec_b64 s[0:1], s[42:43]
	s_cbranch_execz .LBB0_1303
	v_lshl_add_u64 v[60:61], v[66:67], 2, v[162:163]
	global_load_dword v55, v[60:61], off offset:12
.LBB0_1303:
	s_or_b64 exec, exec, s[0:1]
	s_waitcnt vmcnt(0) lgkmcnt(0)
	v_mul_f32_e32 v55, v57, v55
	v_cvt_pk_bf16_f32 v55, v55, s0
	ds_write_b16 v58, v55 offset:64
	s_and_saveexec_b64 s[0:1], vcc
	s_cbranch_execz .LBB0_1305
	v_lshl_add_u64 v[54:55], v[66:67], 2, v[162:163]
	global_load_dword v54, v[54:55], off
.LBB0_1305:
	s_or_b64 exec, exec, s[0:1]
	s_waitcnt vmcnt(0) lgkmcnt(0)
	v_mul_f32_e32 v50, v50, v54
	v_cvt_pk_bf16_f32 v50, v50, s0
	ds_write_b16 v64, v50 offset:96
	v_mov_b32_e32 v50, 0
	v_mov_b32_e32 v54, 0
	s_and_saveexec_b64 s[0:1], s[38:39]
	s_cbranch_execz .LBB0_1307
	v_lshl_add_u64 v[54:55], v[66:67], 2, v[162:163]
	global_load_dword v54, v[54:55], off offset:4
.LBB0_1307:
	s_or_b64 exec, exec, s[0:1]
	s_waitcnt vmcnt(0) lgkmcnt(0)
	v_mul_f32_e32 v51, v51, v54
	v_cvt_pk_bf16_f32 v51, v51, s0
	ds_write_b16 v62, v51 offset:96
	s_and_saveexec_b64 s[0:1], s[40:41]
	s_cbranch_execz .LBB0_1309
	v_lshl_add_u64 v[50:51], v[66:67], 2, v[162:163]
	global_load_dword v50, v[50:51], off offset:8
.LBB0_1309:
	s_or_b64 exec, exec, s[0:1]
	s_waitcnt vmcnt(0) lgkmcnt(0)
	v_mul_f32_e32 v50, v52, v50
	v_cvt_pk_bf16_f32 v50, v50, s0
	ds_write_b16 v63, v50 offset:96
	v_mov_b32_e32 v50, 0
	v_mov_b32_e32 v51, 0
	s_and_saveexec_b64 s[0:1], s[42:43]
	s_cbranch_execz .LBB0_1311
	v_lshl_add_u64 v[54:55], v[66:67], 2, v[162:163]
	global_load_dword v51, v[54:55], off offset:12
.LBB0_1311:
	s_or_b64 exec, exec, s[0:1]
	s_waitcnt vmcnt(0) lgkmcnt(0)
	v_mul_f32_e32 v51, v53, v51
	v_cvt_pk_bf16_f32 v51, v51, s0
	ds_write_b16 v58, v51 offset:96
	v_or_b32_e32 v51, 16, v66
	v_cmp_gt_i32_e32 vcc, s60, v51
	s_and_saveexec_b64 s[0:1], vcc
	s_cbranch_execz .LBB0_1313
	v_lshl_add_u64 v[52:53], v[66:67], 2, v[162:163]
	global_load_dword v50, v[52:53], off offset:64
.LBB0_1313:
	s_or_b64 exec, exec, s[0:1]
	s_waitcnt vmcnt(0) lgkmcnt(0)
	v_mul_f32_e32 v46, v46, v50
	v_mul_lo_u32 v51, v51, s23
	v_cvt_pk_bf16_f32 v50, v46, s0
	v_lshl_add_u32 v46, v68, 1, v51
	ds_write_b16 v46, v50
	v_or_b32_e32 v50, 17, v66
	v_cmp_gt_i32_e64 s[38:39], s60, v50
	v_mov_b32_e32 v50, 0
	v_mov_b32_e32 v52, 0
	s_and_saveexec_b64 s[0:1], s[38:39]
	s_cbranch_execz .LBB0_1315
	v_lshl_add_u64 v[52:53], v[66:67], 2, v[162:163]
	global_load_dword v52, v[52:53], off offset:68
.LBB0_1315:
	s_or_b64 exec, exec, s[0:1]
	s_waitcnt vmcnt(0) lgkmcnt(0)
	v_mul_f32_e32 v47, v47, v52
	v_add_u32_e32 v51, 0x110, v51
	v_cvt_pk_bf16_f32 v52, v47, s0
	v_lshl_add_u32 v47, v68, 1, v51
	ds_write_b16 v47, v52
	v_or_b32_e32 v52, 18, v66
	v_cmp_gt_i32_e64 s[40:41], s60, v52
	s_and_saveexec_b64 s[0:1], s[40:41]
	s_cbranch_execz .LBB0_1317
	v_lshl_add_u64 v[52:53], v[66:67], 2, v[162:163]
	global_load_dword v50, v[52:53], off offset:72
.LBB0_1317:
	s_or_b64 exec, exec, s[0:1]
	s_waitcnt vmcnt(0) lgkmcnt(0)
	v_mul_f32_e32 v48, v48, v50
	v_cvt_pk_bf16_f32 v50, v48, s0
	v_add_u32_e32 v48, 0x110, v51
	v_lshl_add_u32 v48, v68, 1, v48
	ds_write_b16 v48, v50
	v_or_b32_e32 v50, 19, v66
	v_cmp_gt_i32_e64 s[42:43], s60, v50
	v_mov_b32_e32 v50, 0
	v_mov_b32_e32 v51, 0
	s_and_saveexec_b64 s[0:1], s[42:43]
	s_cbranch_execz .LBB0_1319
	v_lshl_add_u64 v[52:53], v[66:67], 2, v[162:163]
	global_load_dword v51, v[52:53], off offset:76
.LBB0_1319:
	s_or_b64 exec, exec, s[0:1]
	s_waitcnt vmcnt(0) lgkmcnt(0)
	v_mul_f32_e32 v49, v49, v51
	v_cvt_pk_bf16_f32 v49, v49, s0
	ds_write_b16 v48, v49 offset:272
	s_and_saveexec_b64 s[0:1], vcc
	s_cbranch_execz .LBB0_1321
	v_lshl_add_u64 v[50:51], v[66:67], 2, v[162:163]
	global_load_dword v50, v[50:51], off offset:64
; __device__ __forceinline__ u16 f2bf(float f) { return (u16)(pack2(f, 0.f) & 0xffffu); }
; __device__ __forceinline__ int tid_() { int t = threadIdx.x; asm volatile("" : "+v"(t)); return t; }
; template <int NT, class VF, class RP>
; __device__ __forceinline__ void epi_staged_bf16(f32x4 (&acc)[4][NT], int r0, int c0, unsigned char* smem, VF vf, RP rowptr) {
;   constexpr int BN = NT * 32, PITCH = BN + 8, CPR = BN / 8;
;   u16* Ts = (u16*)smem;
;   const int t = tid_();
;   __syncthreads();
; #pragma unroll
;   for (int mi = 0; mi < 4; ++mi)
; #pragma unroll
;     for (int ni = 0; ni < NT; ++ni)
; #pragma unroll
;       for (int j = 0; j < 4; ++j) {
;         const int r = r0 + mi * 16 + j, c = c0 + ni * 16;
;         Ts[r * PITCH + c] = f2bf(vf(r, c, acc[mi][ni][j]));
; __device__ __forceinline__ void phase_moe_down(const Params& p, int l, bool last, unsigned char* smem) {
;     ...
;     auto epi = [&](f32x4(&acc)[4][4], int r0, int c0) {
;       auto vf = [&](int r, int, float v) { return (r < mvalid ? gate[r] : 0.f) * v; };
;       auto rp = [&](int r) -> u16* { return r < mvalid ? yb + (size_t)r * 1024 : nullptr; };
;       epi_staged_bf16<4>(acc, r0, c0, smem, vf, rp);
.LBB0_1321:
	s_or_b64 exec, exec, s[0:1]
	s_waitcnt vmcnt(0) lgkmcnt(0)
	v_mul_f32_e32 v42, v42, v50
	v_cvt_pk_bf16_f32 v42, v42, s0
	ds_write_b16 v46, v42 offset:32
	v_mov_b32_e32 v42, 0
	v_mov_b32_e32 v49, 0
	s_and_saveexec_b64 s[0:1], s[38:39]
	s_cbranch_execz .LBB0_1323
	v_lshl_add_u64 v[50:51], v[66:67], 2, v[162:163]
	global_load_dword v49, v[50:51], off offset:68
.LBB0_1323:
	s_or_b64 exec, exec, s[0:1]
	s_waitcnt vmcnt(0) lgkmcnt(0)
	v_mul_f32_e32 v43, v43, v49
	v_cvt_pk_bf16_f32 v43, v43, s0
	ds_write_b16 v47, v43 offset:32
	s_and_saveexec_b64 s[0:1], s[40:41]
	s_cbranch_execz .LBB0_1325
	v_lshl_add_u64 v[42:43], v[66:67], 2, v[162:163]
	global_load_dword v42, v[42:43], off offset:72
.LBB0_1325:
	s_or_b64 exec, exec, s[0:1]
	s_waitcnt vmcnt(0) lgkmcnt(0)
	v_mul_f32_e32 v42, v44, v42
	v_cvt_pk_bf16_f32 v42, v42, s0
	v_mov_b32_e32 v43, 0
	v_mov_b32_e32 v44, 0
	ds_write_b16 v48, v42 offset:32
	s_and_saveexec_b64 s[0:1], s[42:43]
	s_cbranch_execz .LBB0_1327
	v_lshl_add_u64 v[50:51], v[66:67], 2, v[162:163]
	global_load_dword v44, v[50:51], off offset:76
.LBB0_1327:
	s_or_b64 exec, exec, s[0:1]
	s_waitcnt vmcnt(0) lgkmcnt(0)
	v_mul_f32_e32 v44, v45, v44
	v_add_u32_e32 v42, 0x110, v48
	v_cvt_pk_bf16_f32 v44, v44, s0
	ds_write_b16 v42, v44 offset:32
	s_and_saveexec_b64 s[0:1], vcc
	s_cbranch_execz .LBB0_1329
	v_lshl_add_u64 v[44:45], v[66:67], 2, v[162:163]
	global_load_dword v43, v[44:45], off offset:64
.LBB0_1329:
	s_or_b64 exec, exec, s[0:1]
	s_waitcnt vmcnt(0) lgkmcnt(0)
	v_mul_f32_e32 v38, v38, v43
	v_cvt_pk_bf16_f32 v38, v38, s0
	ds_write_b16 v46, v38 offset:64
	v_mov_b32_e32 v38, 0
	v_mov_b32_e32 v43, 0
	s_and_saveexec_b64 s[0:1], s[38:39]
	s_cbranch_execz .LBB0_1331
	v_lshl_add_u64 v[44:45], v[66:67], 2, v[162:163]
	global_load_dword v43, v[44:45], off offset:68
.LBB0_1331:
	s_or_b64 exec, exec, s[0:1]
	s_waitcnt vmcnt(0) lgkmcnt(0)
	v_mul_f32_e32 v39, v39, v43
	v_cvt_pk_bf16_f32 v39, v39, s0
	ds_write_b16 v47, v39 offset:64
	s_and_saveexec_b64 s[0:1], s[40:41]
	s_cbranch_execz .LBB0_1333
	v_lshl_add_u64 v[38:39], v[66:67], 2, v[162:163]
	global_load_dword v38, v[38:39], off offset:72
.LBB0_1333:
	s_or_b64 exec, exec, s[0:1]
	s_waitcnt vmcnt(0) lgkmcnt(0)
	v_mul_f32_e32 v38, v40, v38
	v_cvt_pk_bf16_f32 v38, v38, s0
	ds_write_b16 v48, v38 offset:64
	v_mov_b32_e32 v38, 0
	v_mov_b32_e32 v39, 0
	s_and_saveexec_b64 s[0:1], s[42:43]
	s_cbranch_execz .LBB0_1335
	v_lshl_add_u64 v[44:45], v[66:67], 2, v[162:163]
	global_load_dword v39, v[44:45], off offset:76
.LBB0_1335:
	s_or_b64 exec, exec, s[0:1]
	s_waitcnt vmcnt(0) lgkmcnt(0)
	v_mul_f32_e32 v39, v41, v39
	v_cvt_pk_bf16_f32 v39, v39, s0
	ds_write_b16 v42, v39 offset:64
	s_and_saveexec_b64 s[0:1], vcc
	s_cbranch_execz .LBB0_1337
	v_lshl_add_u64 v[38:39], v[66:67], 2, v[162:163]
	global_load_dword v38, v[38:39], off offset:64
.LBB0_1337:
	s_or_b64 exec, exec, s[0:1]
	s_waitcnt vmcnt(0) lgkmcnt(0)
	v_mul_f32_e32 v34, v34, v38
	v_cvt_pk_bf16_f32 v34, v34, s0
	ds_write_b16 v46, v34 offset:96
	v_mov_b32_e32 v34, 0
	v_mov_b32_e32 v38, 0
	s_and_saveexec_b64 s[0:1], s[38:39]
	s_cbranch_execz .LBB0_1339
	v_lshl_add_u64 v[38:39], v[66:67], 2, v[162:163]
	global_load_dword v38, v[38:39], off offset:68
.LBB0_1339:
	s_or_b64 exec, exec, s[0:1]
	s_waitcnt vmcnt(0) lgkmcnt(0)
	v_mul_f32_e32 v35, v35, v38
	v_cvt_pk_bf16_f32 v35, v35, s0
	ds_write_b16 v47, v35 offset:96
	s_and_saveexec_b64 s[0:1], s[40:41]
	s_cbranch_execz .LBB0_1341
	v_lshl_add_u64 v[34:35], v[66:67], 2, v[162:163]
	global_load_dword v34, v[34:35], off offset:72
.LBB0_1341:
	s_or_b64 exec, exec, s[0:1]
	s_waitcnt vmcnt(0) lgkmcnt(0)
	v_mul_f32_e32 v34, v36, v34
	v_cvt_pk_bf16_f32 v34, v34, s0
	ds_write_b16 v48, v34 offset:96
	v_mov_b32_e32 v34, 0
	v_mov_b32_e32 v35, 0
	s_and_saveexec_b64 s[0:1], s[42:43]
	s_cbranch_execz .LBB0_1343
	v_lshl_add_u64 v[38:39], v[66:67], 2, v[162:163]
	global_load_dword v35, v[38:39], off offset:76
.LBB0_1343:
	s_or_b64 exec, exec, s[0:1]
	s_waitcnt vmcnt(0) lgkmcnt(0)
	v_mul_f32_e32 v35, v37, v35
	v_cvt_pk_bf16_f32 v35, v35, s0
	ds_write_b16 v42, v35 offset:96
	v_or_b32_e32 v35, 32, v66
	v_cmp_gt_i32_e32 vcc, s60, v35
	s_and_saveexec_b64 s[0:1], vcc
	s_cbranch_execz .LBB0_1345
	v_lshl_add_u64 v[36:37], v[66:67], 2, v[162:163]
	global_load_dword v34, v[36:37], off offset:128
.LBB0_1345:
	s_or_b64 exec, exec, s[0:1]
	s_waitcnt vmcnt(0) lgkmcnt(0)
	v_mul_f32_e32 v30, v30, v34
	v_mul_lo_u32 v35, v35, s23
	v_cvt_pk_bf16_f32 v34, v30, s0
	v_lshl_add_u32 v30, v68, 1, v35
	ds_write_b16 v30, v34
	v_or_b32_e32 v34, 33, v66
	v_cmp_gt_i32_e64 s[38:39], s60, v34
	v_mov_b32_e32 v34, 0
	v_mov_b32_e32 v36, 0
	s_and_saveexec_b64 s[0:1], s[38:39]
	s_cbranch_execz .LBB0_1347
	v_lshl_add_u64 v[36:37], v[66:67], 2, v[162:163]
	global_load_dword v36, v[36:37], off offset:132
.LBB0_1347:
	s_or_b64 exec, exec, s[0:1]
	s_waitcnt vmcnt(0) lgkmcnt(0)
	v_mul_f32_e32 v31, v31, v36
	v_add_u32_e32 v35, 0x110, v35
	v_cvt_pk_bf16_f32 v36, v31, s0
	v_lshl_add_u32 v31, v68, 1, v35
	ds_write_b16 v31, v36
	v_or_b32_e32 v36, 34, v66
	v_cmp_gt_i32_e64 s[40:41], s60, v36
	s_and_saveexec_b64 s[0:1], s[40:41]
	s_cbranch_execz .LBB0_1349
	v_lshl_add_u64 v[36:37], v[66:67], 2, v[162:163]
	global_load_dword v34, v[36:37], off offset:136
.LBB0_1349:
	s_or_b64 exec, exec, s[0:1]
	s_waitcnt vmcnt(0) lgkmcnt(0)
	v_mul_f32_e32 v32, v32, v34
	v_cvt_pk_bf16_f32 v34, v32, s0
	v_add_u32_e32 v32, 0x110, v35
	v_lshl_add_u32 v32, v68, 1, v32
	ds_write_b16 v32, v34
	v_or_b32_e32 v34, 35, v66
	v_cmp_gt_i32_e64 s[42:43], s60, v34
	v_mov_b32_e32 v34, 0
	v_mov_b32_e32 v35, 0
	s_and_saveexec_b64 s[0:1], s[42:43]
	s_cbranch_execz .LBB0_1351
	v_lshl_add_u64 v[36:37], v[66:67], 2, v[162:163]
	global_load_dword v35, v[36:37], off offset:140
; __device__ __forceinline__ u16 f2bf(float f) { return (u16)(pack2(f, 0.f) & 0xffffu); }
; __device__ __forceinline__ int tid_() { int t = threadIdx.x; asm volatile("" : "+v"(t)); return t; }
; template <int NT, class VF, class RP>
; __device__ __forceinline__ void epi_staged_bf16(f32x4 (&acc)[4][NT], int r0, int c0, unsigned char* smem, VF vf, RP rowptr) {
;   constexpr int BN = NT * 32, PITCH = BN + 8, CPR = BN / 8;
;   u16* Ts = (u16*)smem;
;   const int t = tid_();
;   __syncthreads();
; #pragma unroll
;   for (int mi = 0; mi < 4; ++mi)
; #pragma unroll
;     for (int ni = 0; ni < NT; ++ni)
; #pragma unroll
;       for (int j = 0; j < 4; ++j) {
;         const int r = r0 + mi * 16 + j, c = c0 + ni * 16;
;         Ts[r * PITCH + c] = f2bf(vf(r, c, acc[mi][ni][j]));
; __device__ __forceinline__ void phase_moe_down(const Params& p, int l, bool last, unsigned char* smem) {
;     ...
;     auto epi = [&](f32x4(&acc)[4][4], int r0, int c0) {
;       auto vf = [&](int r, int, float v) { return (r < mvalid ? gate[r] : 0.f) * v; };
;       auto rp = [&](int r) -> u16* { return r < mvalid ? yb + (size_t)r * 1024 : nullptr; };
;       epi_staged_bf16<4>(acc, r0, c0, smem, vf, rp);
.LBB0_1351:
	s_or_b64 exec, exec, s[0:1]
	s_waitcnt vmcnt(0) lgkmcnt(0)
	v_mul_f32_e32 v33, v33, v35
	v_cvt_pk_bf16_f32 v33, v33, s0
	ds_write_b16 v32, v33 offset:272
	s_and_saveexec_b64 s[0:1], vcc
	s_cbranch_execz .LBB0_1353
	v_lshl_add_u64 v[34:35], v[66:67], 2, v[162:163]
	global_load_dword v34, v[34:35], off offset:128
.LBB0_1353:
	s_or_b64 exec, exec, s[0:1]
	s_waitcnt vmcnt(0) lgkmcnt(0)
	v_mul_f32_e32 v26, v26, v34
	v_cvt_pk_bf16_f32 v26, v26, s0
	ds_write_b16 v30, v26 offset:32
	v_mov_b32_e32 v26, 0
	v_mov_b32_e32 v33, 0
	s_and_saveexec_b64 s[0:1], s[38:39]
	s_cbranch_execz .LBB0_1355
	v_lshl_add_u64 v[34:35], v[66:67], 2, v[162:163]
	global_load_dword v33, v[34:35], off offset:132
.LBB0_1355:
	s_or_b64 exec, exec, s[0:1]
	s_waitcnt vmcnt(0) lgkmcnt(0)
	v_mul_f32_e32 v27, v27, v33
	v_cvt_pk_bf16_f32 v27, v27, s0
	ds_write_b16 v31, v27 offset:32
	s_and_saveexec_b64 s[0:1], s[40:41]
	s_cbranch_execz .LBB0_1357
	v_lshl_add_u64 v[26:27], v[66:67], 2, v[162:163]
	global_load_dword v26, v[26:27], off offset:136
.LBB0_1357:
	s_or_b64 exec, exec, s[0:1]
	s_waitcnt vmcnt(0) lgkmcnt(0)
	v_mul_f32_e32 v26, v28, v26
	v_cvt_pk_bf16_f32 v26, v26, s0
	v_mov_b32_e32 v27, 0
	v_mov_b32_e32 v28, 0
	ds_write_b16 v32, v26 offset:32
	s_and_saveexec_b64 s[0:1], s[42:43]
	s_cbranch_execz .LBB0_1359
	v_lshl_add_u64 v[34:35], v[66:67], 2, v[162:163]
	global_load_dword v28, v[34:35], off offset:140
.LBB0_1359:
	s_or_b64 exec, exec, s[0:1]
	s_waitcnt vmcnt(0) lgkmcnt(0)
	v_mul_f32_e32 v28, v29, v28
	v_add_u32_e32 v26, 0x110, v32
	v_cvt_pk_bf16_f32 v28, v28, s0
	ds_write_b16 v26, v28 offset:32
	s_and_saveexec_b64 s[0:1], vcc
	s_cbranch_execz .LBB0_1361
	v_lshl_add_u64 v[28:29], v[66:67], 2, v[162:163]
	global_load_dword v27, v[28:29], off offset:128
.LBB0_1361:
	s_or_b64 exec, exec, s[0:1]
	s_waitcnt vmcnt(0) lgkmcnt(0)
	v_mul_f32_e32 v22, v22, v27
	v_cvt_pk_bf16_f32 v22, v22, s0
	ds_write_b16 v30, v22 offset:64
	v_mov_b32_e32 v22, 0
	v_mov_b32_e32 v27, 0
	s_and_saveexec_b64 s[0:1], s[38:39]
	s_cbranch_execz .LBB0_1363
	v_lshl_add_u64 v[28:29], v[66:67], 2, v[162:163]
	global_load_dword v27, v[28:29], off offset:132
.LBB0_1363:
	s_or_b64 exec, exec, s[0:1]
	s_waitcnt vmcnt(0) lgkmcnt(0)
	v_mul_f32_e32 v23, v23, v27
	v_cvt_pk_bf16_f32 v23, v23, s0
	ds_write_b16 v31, v23 offset:64
	s_and_saveexec_b64 s[0:1], s[40:41]
	s_cbranch_execz .LBB0_1365
	v_lshl_add_u64 v[22:23], v[66:67], 2, v[162:163]
	global_load_dword v22, v[22:23], off offset:136
.LBB0_1365:
	s_or_b64 exec, exec, s[0:1]
	s_waitcnt vmcnt(0) lgkmcnt(0)
	v_mul_f32_e32 v22, v24, v22
	v_cvt_pk_bf16_f32 v22, v22, s0
	ds_write_b16 v32, v22 offset:64
	v_mov_b32_e32 v22, 0
	v_mov_b32_e32 v23, 0
	s_and_saveexec_b64 s[0:1], s[42:43]
	s_cbranch_execz .LBB0_1367
	v_lshl_add_u64 v[28:29], v[66:67], 2, v[162:163]
	global_load_dword v23, v[28:29], off offset:140
.LBB0_1367:
	s_or_b64 exec, exec, s[0:1]
	s_waitcnt vmcnt(0) lgkmcnt(0)
	v_mul_f32_e32 v23, v25, v23
	v_cvt_pk_bf16_f32 v23, v23, s0
	ds_write_b16 v26, v23 offset:64
	s_and_saveexec_b64 s[0:1], vcc
	s_cbranch_execz .LBB0_1369
	v_lshl_add_u64 v[22:23], v[66:67], 2, v[162:163]
	global_load_dword v22, v[22:23], off offset:128
.LBB0_1369:
	s_or_b64 exec, exec, s[0:1]
	s_waitcnt vmcnt(0) lgkmcnt(0)
	v_mul_f32_e32 v18, v18, v22
	v_cvt_pk_bf16_f32 v18, v18, s0
	ds_write_b16 v30, v18 offset:96
	v_mov_b32_e32 v18, 0
	v_mov_b32_e32 v22, 0
	s_and_saveexec_b64 s[0:1], s[38:39]
	s_cbranch_execz .LBB0_1371
	v_lshl_add_u64 v[22:23], v[66:67], 2, v[162:163]
	global_load_dword v22, v[22:23], off offset:132
.LBB0_1371:
	s_or_b64 exec, exec, s[0:1]
	s_waitcnt vmcnt(0) lgkmcnt(0)
	v_mul_f32_e32 v19, v19, v22
	v_cvt_pk_bf16_f32 v19, v19, s0
	ds_write_b16 v31, v19 offset:96
	s_and_saveexec_b64 s[0:1], s[40:41]
	s_cbranch_execz .LBB0_1373
	v_lshl_add_u64 v[18:19], v[66:67], 2, v[162:163]
	global_load_dword v18, v[18:19], off offset:136
.LBB0_1373:
	s_or_b64 exec, exec, s[0:1]
	s_waitcnt vmcnt(0) lgkmcnt(0)
	v_mul_f32_e32 v18, v20, v18
	v_cvt_pk_bf16_f32 v18, v18, s0
	ds_write_b16 v32, v18 offset:96
	v_mov_b32_e32 v18, 0
	v_mov_b32_e32 v19, 0
	s_and_saveexec_b64 s[0:1], s[42:43]
	s_cbranch_execz .LBB0_1375
	v_lshl_add_u64 v[22:23], v[66:67], 2, v[162:163]
	global_load_dword v19, v[22:23], off offset:140
.LBB0_1375:
	s_or_b64 exec, exec, s[0:1]
	s_waitcnt vmcnt(0) lgkmcnt(0)
	v_mul_f32_e32 v19, v21, v19
	v_cvt_pk_bf16_f32 v19, v19, s0
	ds_write_b16 v26, v19 offset:96
	v_or_b32_e32 v19, 48, v66
	v_cmp_gt_i32_e32 vcc, s60, v19
	s_and_saveexec_b64 s[0:1], vcc
	s_cbranch_execz .LBB0_1377
	v_lshl_add_u64 v[20:21], v[66:67], 2, v[162:163]
	global_load_dword v18, v[20:21], off offset:192
.LBB0_1377:
	s_or_b64 exec, exec, s[0:1]
	s_waitcnt vmcnt(0) lgkmcnt(0)
	v_mul_f32_e32 v14, v14, v18
	v_mul_lo_u32 v19, v19, s23
	v_cvt_pk_bf16_f32 v18, v14, s0
	v_lshl_add_u32 v14, v68, 1, v19
	ds_write_b16 v14, v18
	v_or_b32_e32 v18, 49, v66
	v_cmp_gt_i32_e64 s[38:39], s60, v18
	v_mov_b32_e32 v18, 0
	v_mov_b32_e32 v20, 0
	s_and_saveexec_b64 s[0:1], s[38:39]
	s_cbranch_execz .LBB0_1379
	v_lshl_add_u64 v[20:21], v[66:67], 2, v[162:163]
	global_load_dword v20, v[20:21], off offset:196
.LBB0_1379:
	s_or_b64 exec, exec, s[0:1]
	s_waitcnt vmcnt(0) lgkmcnt(0)
	v_mul_f32_e32 v15, v15, v20
	v_add_u32_e32 v19, 0x110, v19
	v_cvt_pk_bf16_f32 v20, v15, s0
	v_lshl_add_u32 v15, v68, 1, v19
	ds_write_b16 v15, v20
	v_or_b32_e32 v20, 50, v66
	v_cmp_gt_i32_e64 s[40:41], s60, v20
	s_and_saveexec_b64 s[0:1], s[40:41]
	s_cbranch_execz .LBB0_1381
	v_lshl_add_u64 v[20:21], v[66:67], 2, v[162:163]
	global_load_dword v18, v[20:21], off offset:200
; __device__ __forceinline__ u16 f2bf(float f) { return (u16)(pack2(f, 0.f) & 0xffffu); }
; __device__ __forceinline__ int tid_() { int t = threadIdx.x; asm volatile("" : "+v"(t)); return t; }
; template <int NT, class VF, class RP>
; __device__ __forceinline__ void epi_staged_bf16(f32x4 (&acc)[4][NT], int r0, int c0, unsigned char* smem, VF vf, RP rowptr) {
;   constexpr int BN = NT * 32, PITCH = BN + 8, CPR = BN / 8;
;   u16* Ts = (u16*)smem;
;   const int t = tid_();
;   __syncthreads();
; #pragma unroll
;   for (int mi = 0; mi < 4; ++mi)
; #pragma unroll
;     for (int ni = 0; ni < NT; ++ni)
; #pragma unroll
;       for (int j = 0; j < 4; ++j) {
;         const int r = r0 + mi * 16 + j, c = c0 + ni * 16;
;         Ts[r * PITCH + c] = f2bf(vf(r, c, acc[mi][ni][j]));
; __device__ __forceinline__ void phase_moe_down(const Params& p, int l, bool last, unsigned char* smem) {
;     ...
;     auto epi = [&](f32x4(&acc)[4][4], int r0, int c0) {
;       auto vf = [&](int r, int, float v) { return (r < mvalid ? gate[r] : 0.f) * v; };
;       auto rp = [&](int r) -> u16* { return r < mvalid ? yb + (size_t)r * 1024 : nullptr; };
;       epi_staged_bf16<4>(acc, r0, c0, smem, vf, rp);
.LBB0_1381:
	s_or_b64 exec, exec, s[0:1]
	s_waitcnt vmcnt(0) lgkmcnt(0)
	v_mul_f32_e32 v16, v16, v18
	v_cvt_pk_bf16_f32 v18, v16, s0
	v_add_u32_e32 v16, 0x110, v19
	v_lshl_add_u32 v16, v68, 1, v16
	ds_write_b16 v16, v18
	v_or_b32_e32 v18, 51, v66
	v_cmp_gt_i32_e64 s[42:43], s60, v18
	v_mov_b32_e32 v18, 0
	v_mov_b32_e32 v19, 0
	s_and_saveexec_b64 s[0:1], s[42:43]
	s_cbranch_execz .LBB0_1383
	v_lshl_add_u64 v[20:21], v[66:67], 2, v[162:163]
	global_load_dword v19, v[20:21], off offset:204
.LBB0_1383:
	s_or_b64 exec, exec, s[0:1]
	s_waitcnt vmcnt(0) lgkmcnt(0)
	v_mul_f32_e32 v17, v17, v19
	v_cvt_pk_bf16_f32 v17, v17, s0
	ds_write_b16 v16, v17 offset:272
	s_and_saveexec_b64 s[0:1], vcc
	s_cbranch_execz .LBB0_1385
	v_lshl_add_u64 v[18:19], v[66:67], 2, v[162:163]
	global_load_dword v18, v[18:19], off offset:192
.LBB0_1385:
	s_or_b64 exec, exec, s[0:1]
	s_waitcnt vmcnt(0) lgkmcnt(0)
	v_mul_f32_e32 v10, v10, v18
	v_cvt_pk_bf16_f32 v10, v10, s0
	ds_write_b16 v14, v10 offset:32
	v_mov_b32_e32 v10, 0
	v_mov_b32_e32 v17, 0
	s_and_saveexec_b64 s[0:1], s[38:39]
	s_cbranch_execz .LBB0_1387
	v_lshl_add_u64 v[18:19], v[66:67], 2, v[162:163]
	global_load_dword v17, v[18:19], off offset:196
.LBB0_1387:
	s_or_b64 exec, exec, s[0:1]
	s_waitcnt vmcnt(0) lgkmcnt(0)
	v_mul_f32_e32 v11, v11, v17
	v_cvt_pk_bf16_f32 v11, v11, s0
	ds_write_b16 v15, v11 offset:32
	s_and_saveexec_b64 s[0:1], s[40:41]
	s_cbranch_execz .LBB0_1389
	v_lshl_add_u64 v[10:11], v[66:67], 2, v[162:163]
	global_load_dword v10, v[10:11], off offset:200
.LBB0_1389:
	s_or_b64 exec, exec, s[0:1]
	s_waitcnt vmcnt(0) lgkmcnt(0)
	v_mul_f32_e32 v10, v12, v10
	v_cvt_pk_bf16_f32 v10, v10, s0
	v_mov_b32_e32 v11, 0
	v_mov_b32_e32 v12, 0
	ds_write_b16 v16, v10 offset:32
	s_and_saveexec_b64 s[0:1], s[42:43]
	s_cbranch_execz .LBB0_1391
	v_lshl_add_u64 v[18:19], v[66:67], 2, v[162:163]
	global_load_dword v12, v[18:19], off offset:204
.LBB0_1391:
	s_or_b64 exec, exec, s[0:1]
	s_waitcnt vmcnt(0) lgkmcnt(0)
	v_mul_f32_e32 v12, v13, v12
	v_add_u32_e32 v10, 0x110, v16
	v_cvt_pk_bf16_f32 v12, v12, s0
	ds_write_b16 v10, v12 offset:32
	s_and_saveexec_b64 s[0:1], vcc
	s_cbranch_execz .LBB0_1393
	v_lshl_add_u64 v[12:13], v[66:67], 2, v[162:163]
	global_load_dword v11, v[12:13], off offset:192
.LBB0_1393:
	s_or_b64 exec, exec, s[0:1]
	s_waitcnt vmcnt(0) lgkmcnt(0)
	v_mul_f32_e32 v6, v6, v11
	v_cvt_pk_bf16_f32 v6, v6, s0
	ds_write_b16 v14, v6 offset:64
	v_mov_b32_e32 v6, 0
	v_mov_b32_e32 v11, 0
	s_and_saveexec_b64 s[0:1], s[38:39]
	s_cbranch_execz .LBB0_1395
	v_lshl_add_u64 v[12:13], v[66:67], 2, v[162:163]
	global_load_dword v11, v[12:13], off offset:196
.LBB0_1395:
	s_or_b64 exec, exec, s[0:1]
	s_waitcnt vmcnt(0) lgkmcnt(0)
	v_mul_f32_e32 v7, v7, v11
	v_cvt_pk_bf16_f32 v7, v7, s0
	ds_write_b16 v15, v7 offset:64
	s_and_saveexec_b64 s[0:1], s[40:41]
	s_cbranch_execz .LBB0_1397
	v_lshl_add_u64 v[6:7], v[66:67], 2, v[162:163]
	global_load_dword v6, v[6:7], off offset:200
.LBB0_1397:
	s_or_b64 exec, exec, s[0:1]
	s_waitcnt vmcnt(0) lgkmcnt(0)
	v_mul_f32_e32 v6, v8, v6
	v_cvt_pk_bf16_f32 v6, v6, s0
	ds_write_b16 v16, v6 offset:64
	v_mov_b32_e32 v6, 0
	v_mov_b32_e32 v7, 0
	s_and_saveexec_b64 s[0:1], s[42:43]
	s_cbranch_execz .LBB0_1399
	v_lshl_add_u64 v[12:13], v[66:67], 2, v[162:163]
	global_load_dword v7, v[12:13], off offset:204
.LBB0_1399:
	s_or_b64 exec, exec, s[0:1]
	s_waitcnt vmcnt(0) lgkmcnt(0)
	v_mul_f32_e32 v7, v9, v7
	v_cvt_pk_bf16_f32 v7, v7, s0
	ds_write_b16 v10, v7 offset:64
	s_and_saveexec_b64 s[0:1], vcc
	s_cbranch_execz .LBB0_1401
	v_lshl_add_u64 v[6:7], v[66:67], 2, v[162:163]
	global_load_dword v6, v[6:7], off offset:192
.LBB0_1401:
	s_or_b64 exec, exec, s[0:1]
	s_waitcnt vmcnt(0) lgkmcnt(0)
	v_mul_f32_e32 v2, v2, v6
	v_cvt_pk_bf16_f32 v2, v2, s0
	ds_write_b16 v14, v2 offset:96
	v_mov_b32_e32 v2, 0
	v_mov_b32_e32 v6, 0
	s_and_saveexec_b64 s[0:1], s[38:39]
	s_cbranch_execz .LBB0_1403
	v_lshl_add_u64 v[6:7], v[66:67], 2, v[162:163]
	global_load_dword v6, v[6:7], off offset:196
.LBB0_1403:
	s_or_b64 exec, exec, s[0:1]
	s_waitcnt vmcnt(0) lgkmcnt(0)
	v_mul_f32_e32 v3, v3, v6
	v_cvt_pk_bf16_f32 v3, v3, s0
	ds_write_b16 v15, v3 offset:96
	s_and_saveexec_b64 s[0:1], s[40:41]
	s_cbranch_execz .LBB0_1405
	v_lshl_add_u64 v[2:3], v[66:67], 2, v[162:163]
	global_load_dword v2, v[2:3], off offset:200
.LBB0_1405:
	s_or_b64 exec, exec, s[0:1]
	s_waitcnt vmcnt(0) lgkmcnt(0)
	v_mul_f32_e32 v2, v4, v2
	v_cvt_pk_bf16_f32 v2, v2, s0
	ds_write_b16 v16, v2 offset:96
	v_mov_b32_e32 v2, 0
	s_and_saveexec_b64 s[0:1], s[42:43]
	s_cbranch_execz .LBB0_1407
	v_lshl_add_u64 v[2:3], v[66:67], 2, v[162:163]
	global_load_dword v2, v[2:3], off offset:204
; __device__ __forceinline__ u16 f2bf(float f) { return (u16)(pack2(f, 0.f) & 0xffffu); }
; __device__ __forceinline__ int tid_() { int t = threadIdx.x; asm volatile("" : "+v"(t)); return t; }
; template <int NT, class VF, class RP>
; __device__ __forceinline__ void epi_staged_bf16(f32x4 (&acc)[4][NT], int r0, int c0, unsigned char* smem, VF vf, RP rowptr) {
;   constexpr int BN = NT * 32, PITCH = BN + 8, CPR = BN / 8;
;   u16* Ts = (u16*)smem;
;   const int t = tid_();
;   __syncthreads();
; #pragma unroll
;   for (int mi = 0; mi < 4; ++mi)
; #pragma unroll
;     for (int ni = 0; ni < NT; ++ni)
; #pragma unroll
;       for (int j = 0; j < 4; ++j) {
;         const int r = r0 + mi * 16 + j, c = c0 + ni * 16;
;         Ts[r * PITCH + c] = f2bf(vf(r, c, acc[mi][ni][j]));
;       }
;   __syncthreads();
; #pragma unroll
;   for (int i = 0; i < CPR / 2; ++i) {
;     const int c = t + 256 * i, row = c / CPR, ch = c % CPR;
;     u16* d = rowptr(row);
;     if (d) *(u32x4*)(d + ch * 8) = *(const u32x4*)(Ts + row * PITCH + ch * 8);
;   }
; __device__ __forceinline__ void phase_moe_down(const Params& p, int l, bool last, unsigned char* smem) {
;     ...
;     auto epi = [&](f32x4(&acc)[4][4], int r0, int c0) {
;       auto vf = [&](int r, int, float v) { return (r < mvalid ? gate[r] : 0.f) * v; };
;       auto rp = [&](int r) -> u16* { return r < mvalid ? yb + (size_t)r * 1024 : nullptr; };
;       epi_staged_bf16<4>(acc, r0, c0, smem, vf, rp);
.LBB0_1407:
	s_or_b64 exec, exec, s[0:1]
	s_waitcnt vmcnt(0) lgkmcnt(0)
	v_mul_f32_e32 v2, v5, v2
	v_cvt_pk_bf16_f32 v2, v2, s0
	ds_write_b16 v10, v2 offset:96
	v_ashrrev_i32_e32 v2, 31, v0
	v_lshrrev_b32_e32 v2, 28, v2
	v_add_u32_e32 v2, v0, v2
	v_ashrrev_i32_e32 v2, 4, v2
	v_cmp_gt_i32_e64 s[38:39], s60, v2
	v_cmp_ne_u64_e64 s[40:41], 0, v[164:165]
	v_cmp_eq_u64_e32 vcc, 0, v[164:165]
	s_and_b64 s[8:9], s[38:39], s[40:41]
	s_waitcnt lgkmcnt(0)
	s_barrier
	s_and_saveexec_b64 s[0:1], s[8:9]
	s_cbranch_execz .LBB0_1409
	v_ashrrev_i32_e32 v3, 31, v2
	v_lshlrev_b64 v[6:7], 11, v[2:3]
	v_lshlrev_b32_e32 v3, 4, v2
	v_sub_u32_e32 v8, v0, v3
	v_mul_lo_u32 v2, v2, s23
	v_lshl_add_u32 v2, v8, 4, v2
	ds_read_b128 v[2:5], v2
	v_lshlrev_b32_e32 v8, 3, v8
	v_lshl_add_u64 v[6:7], v[160:161], 0, v[6:7]
	v_ashrrev_i32_e32 v9, 31, v8
	v_lshl_add_u64 v[6:7], v[8:9], 1, v[6:7]
	s_waitcnt lgkmcnt(0)
	global_store_dwordx4 v[6:7], v[2:5], off
.LBB0_1409:
	s_or_b64 exec, exec, s[0:1]
	s_nop 0
	v_add_u32_e32 v4, 0x100, v0
	v_ashrrev_i32_e32 v2, 31, v4
	v_lshrrev_b32_e32 v2, 28, v2
	v_add_u32_e32 v2, v4, v2
	v_ashrrev_i32_e32 v2, 4, v2
	v_cmp_gt_i32_e64 s[38:39], s60, v2
	s_xor_b64 s[0:1], vcc, -1
	s_and_b64 s[36:37], s[38:39], s[0:1]
	s_and_saveexec_b64 s[8:9], s[36:37]
	s_cbranch_execz .LBB0_1411
	v_ashrrev_i32_e32 v3, 31, v2
	v_lshlrev_b64 v[6:7], 11, v[2:3]
	v_lshlrev_b32_e32 v3, 4, v2
	v_sub_u32_e32 v8, v4, v3
	v_mul_lo_u32 v2, v2, s23
	v_lshl_add_u32 v2, v8, 4, v2
	ds_read_b128 v[2:5], v2
	v_lshlrev_b32_e32 v8, 3, v8
	v_lshl_add_u64 v[6:7], v[160:161], 0, v[6:7]
	v_ashrrev_i32_e32 v9, 31, v8
	v_lshl_add_u64 v[6:7], v[8:9], 1, v[6:7]
	s_waitcnt lgkmcnt(0)
	global_store_dwordx4 v[6:7], v[2:5], off
.LBB0_1411:
	s_or_b64 exec, exec, s[8:9]
	s_nop 0
	v_add_u32_e32 v4, 0x200, v0
	v_ashrrev_i32_e32 v2, 31, v4
	v_lshrrev_b32_e32 v2, 28, v2
	v_add_u32_e32 v2, v4, v2
	v_ashrrev_i32_e32 v2, 4, v2
	v_cmp_gt_i32_e32 vcc, s60, v2
	s_and_b64 s[36:37], vcc, s[0:1]
	s_and_saveexec_b64 s[8:9], s[36:37]
	s_cbranch_execz .LBB0_1413
	v_ashrrev_i32_e32 v3, 31, v2
	v_lshlrev_b64 v[6:7], 11, v[2:3]
	v_lshlrev_b32_e32 v3, 4, v2
	v_sub_u32_e32 v8, v4, v3
	v_mul_lo_u32 v2, v2, s23
	v_lshl_add_u32 v2, v8, 4, v2
	ds_read_b128 v[2:5], v2
	v_lshlrev_b32_e32 v8, 3, v8
	v_lshl_add_u64 v[6:7], v[160:161], 0, v[6:7]
	v_ashrrev_i32_e32 v9, 31, v8
	v_lshl_add_u64 v[6:7], v[8:9], 1, v[6:7]
	s_waitcnt lgkmcnt(0)
	global_store_dwordx4 v[6:7], v[2:5], off
.LBB0_1413:
	s_or_b64 exec, exec, s[8:9]
	s_nop 0
	v_add_u32_e32 v4, 0x300, v0
	v_ashrrev_i32_e32 v2, 31, v4
	v_lshrrev_b32_e32 v2, 28, v2
	v_add_u32_e32 v2, v4, v2
	v_ashrrev_i32_e32 v2, 4, v2
	v_cmp_gt_i32_e32 vcc, s60, v2
	s_and_b64 s[36:37], vcc, s[0:1]
	s_and_saveexec_b64 s[8:9], s[36:37]
	s_cbranch_execz .LBB0_1415
	v_ashrrev_i32_e32 v3, 31, v2
	v_lshlrev_b64 v[6:7], 11, v[2:3]
	v_lshlrev_b32_e32 v3, 4, v2
	v_sub_u32_e32 v8, v4, v3
	v_mul_lo_u32 v2, v2, s23
	v_lshl_add_u32 v2, v8, 4, v2
	ds_read_b128 v[2:5], v2
	v_lshlrev_b32_e32 v8, 3, v8
	v_lshl_add_u64 v[6:7], v[160:161], 0, v[6:7]
	v_ashrrev_i32_e32 v9, 31, v8
	v_lshl_add_u64 v[6:7], v[8:9], 1, v[6:7]
	s_waitcnt lgkmcnt(0)
	global_store_dwordx4 v[6:7], v[2:5], off
.LBB0_1415:
	s_or_b64 exec, exec, s[8:9]
	s_nop 0
	v_add_u32_e32 v4, 0x400, v0
	v_ashrrev_i32_e32 v2, 31, v4
	v_lshrrev_b32_e32 v2, 28, v2
	v_add_u32_e32 v2, v4, v2
	v_ashrrev_i32_e32 v2, 4, v2
	v_cmp_gt_i32_e32 vcc, s60, v2
	s_and_b64 s[36:37], vcc, s[0:1]
	s_and_saveexec_b64 s[8:9], s[36:37]
	s_cbranch_execz .LBB0_1417
	v_ashrrev_i32_e32 v3, 31, v2
	v_lshlrev_b64 v[6:7], 11, v[2:3]
	v_lshlrev_b32_e32 v3, 4, v2
	v_sub_u32_e32 v8, v4, v3
	v_mul_lo_u32 v2, v2, s23
	v_lshl_add_u32 v2, v8, 4, v2
	ds_read_b128 v[2:5], v2
	v_lshlrev_b32_e32 v8, 3, v8
	v_lshl_add_u64 v[6:7], v[160:161], 0, v[6:7]
	v_ashrrev_i32_e32 v9, 31, v8
	v_lshl_add_u64 v[6:7], v[8:9], 1, v[6:7]
	s_waitcnt lgkmcnt(0)
	global_store_dwordx4 v[6:7], v[2:5], off
.LBB0_1417:
	s_or_b64 exec, exec, s[8:9]
	s_nop 0
	v_add_u32_e32 v4, 0x500, v0
	v_ashrrev_i32_e32 v2, 31, v4
	v_lshrrev_b32_e32 v2, 28, v2
	v_add_u32_e32 v2, v4, v2
	v_ashrrev_i32_e32 v2, 4, v2
	v_cmp_gt_i32_e32 vcc, s60, v2
	s_and_b64 s[36:37], vcc, s[0:1]
	s_and_saveexec_b64 s[8:9], s[36:37]
	s_cbranch_execz .LBB0_1419
	v_ashrrev_i32_e32 v3, 31, v2
	v_lshlrev_b64 v[6:7], 11, v[2:3]
	v_lshlrev_b32_e32 v3, 4, v2
	v_sub_u32_e32 v8, v4, v3
	v_mul_lo_u32 v2, v2, s23
	v_lshl_add_u32 v2, v8, 4, v2
	ds_read_b128 v[2:5], v2
	v_lshlrev_b32_e32 v8, 3, v8
	v_lshl_add_u64 v[6:7], v[160:161], 0, v[6:7]
	v_ashrrev_i32_e32 v9, 31, v8
	v_lshl_add_u64 v[6:7], v[8:9], 1, v[6:7]
	s_waitcnt lgkmcnt(0)
	global_store_dwordx4 v[6:7], v[2:5], off
.LBB0_1419:
	s_or_b64 exec, exec, s[8:9]
	s_nop 0
	v_add_u32_e32 v4, 0x600, v0
	v_ashrrev_i32_e32 v2, 31, v4
	v_lshrrev_b32_e32 v2, 28, v2
	v_add_u32_e32 v2, v4, v2
	v_ashrrev_i32_e32 v2, 4, v2
	v_cmp_gt_i32_e32 vcc, s60, v2
	s_and_b64 s[36:37], vcc, s[0:1]
	s_and_saveexec_b64 s[8:9], s[36:37]
	s_cbranch_execz .LBB0_1421
	v_ashrrev_i32_e32 v3, 31, v2
	v_lshlrev_b64 v[6:7], 11, v[2:3]
	v_lshlrev_b32_e32 v3, 4, v2
	v_sub_u32_e32 v8, v4, v3
	v_mul_lo_u32 v2, v2, s23
	v_lshl_add_u32 v2, v8, 4, v2
	ds_read_b128 v[2:5], v2
	v_lshlrev_b32_e32 v8, 3, v8
	v_lshl_add_u64 v[6:7], v[160:161], 0, v[6:7]
	v_ashrrev_i32_e32 v9, 31, v8
	v_lshl_add_u64 v[6:7], v[8:9], 1, v[6:7]
	s_waitcnt lgkmcnt(0)
	global_store_dwordx4 v[6:7], v[2:5], off

.LBB0_1432:
	v_cndmask_b32_e64 v131, 0, v131, s[40:41]
	v_cndmask_b32_e64 v130, 0, v130, s[40:41]
	v_cndmask_b32_e64 v129, 0, v129, s[40:41]
	v_cndmask_b32_e64 v128, 0, v128, s[40:41]
	v_cndmask_b32_e64 v123, 0, v123, s[42:43]
	v_cndmask_b32_e64 v122, 0, v122, s[42:43]
	v_cndmask_b32_e64 v121, 0, v121, s[42:43]
	v_cndmask_b32_e64 v120, 0, v120, s[42:43]
	v_cndmask_b32_e64 v127, 0, v127, s[44:45]
	v_cndmask_b32_e64 v126, 0, v126, s[44:45]
	v_cndmask_b32_e64 v125, 0, v125, s[44:45]
	v_cndmask_b32_e64 v124, 0, v124, s[44:45]
	v_cndmask_b32_e64 v111, 0, v111, s[38:39]
	v_cndmask_b32_e64 v110, 0, v110, s[38:39]
	v_cndmask_b32_e64 v109, 0, v109, s[38:39]
	v_cndmask_b32_e64 v108, 0, v108, s[38:39]
	ds_write_b128 v191, v[128:131] offset:32768
	ds_write_b128 v191, v[120:123] offset:36864
	ds_write_b128 v191, v[124:127] offset:40960
	ds_write_b128 v191, v[108:111] offset:45056
	ds_write_b128 v191, v[100:103] offset:49152
	ds_write_b128 v191, v[104:107] offset:53248
	ds_write_b128 v191, v[112:115] offset:57344
	ds_write_b128 v191, v[116:119] offset:61440
	global_load_dwordx4 v[132:135], v[170:171], off offset:384
	global_load_dwordx4 v[124:127], v[172:173], off offset:384
	global_load_dwordx4 v[120:123], v[174:175], off offset:384
	global_load_dwordx4 v[116:119], v[176:177], off offset:384
	global_load_dwordx4 v[100:103], v[178:179], off offset:384
	global_load_dwordx4 v[104:107], v[180:181], off offset:384
	global_load_dwordx4 v[108:111], v[182:183], off offset:384
	global_load_dwordx4 v[112:115], v[184:185], off offset:384
	s_waitcnt lgkmcnt(0)
	s_barrier
	ds_read_b128 v[156:159], v192 offset:34816
	ds_read_b128 v[152:155], v192 offset:36864
	ds_read_b128 v[128:131], v192 offset:38912
	ds_read_b128 v[136:139], v193 offset:49152
	ds_read_b128 v[140:143], v193 offset:51200
	ds_read_b128 v[144:147], v193 offset:53248
	ds_read_b128 v[148:151], v193 offset:55296
	s_and_b64 vcc, exec, s[46:47]
	s_cbranch_vccnz .LBB0_1434
	ds_read_b128 v[194:197], v192 offset:32768
	s_waitcnt lgkmcnt(0)
	v_mfma_f32_16x16x32_bf16 v[64:67], v[194:197], v[136:139], v[64:67]
	v_mfma_f32_16x16x32_bf16 v[60:63], v[194:197], v[140:143], v[60:63]
	v_mfma_f32_16x16x32_bf16 v[56:59], v[194:197], v[144:147], v[56:59]
	v_mfma_f32_16x16x32_bf16 v[52:55], v[194:197], v[148:151], v[52:55]

.LBB0_1444:
	s_waitcnt vmcnt(0)
	v_cndmask_b32_e64 v91, 0, v91, s[40:41]
	v_cndmask_b32_e64 v90, 0, v90, s[40:41]
	v_cndmask_b32_e64 v89, 0, v89, s[40:41]
	v_cndmask_b32_e64 v88, 0, v88, s[40:41]
	v_cndmask_b32_e64 v95, 0, v95, s[42:43]
	v_cndmask_b32_e64 v94, 0, v94, s[42:43]
	v_cndmask_b32_e64 v93, 0, v93, s[42:43]
	v_cndmask_b32_e64 v92, 0, v92, s[42:43]
	v_cndmask_b32_e64 v79, 0, v79, s[44:45]
	v_cndmask_b32_e64 v78, 0, v78, s[44:45]
	v_cndmask_b32_e64 v77, 0, v77, s[44:45]
	v_cndmask_b32_e64 v76, 0, v76, s[44:45]
	v_cndmask_b32_e64 v71, 0, v71, s[38:39]
	v_cndmask_b32_e64 v70, 0, v70, s[38:39]
	v_cndmask_b32_e64 v69, 0, v69, s[38:39]
	v_cndmask_b32_e64 v68, 0, v68, s[38:39]
	ds_write_b128 v191, v[88:91]
	ds_write_b128 v191, v[92:95] offset:4096
	ds_write_b128 v191, v[76:79] offset:8192
	ds_write_b128 v191, v[68:71] offset:12288
	ds_write_b128 v191, v[72:75] offset:16384
	ds_write_b128 v191, v[80:83] offset:20480
	ds_write_b128 v191, v[84:87] offset:24576
	ds_write_b128 v191, v[96:99] offset:28672
	s_waitcnt lgkmcnt(11)
	global_load_dwordx4 v[136:139], v[170:171], off offset:512
	global_load_dwordx4 v[128:131], v[172:173], off offset:512
	global_load_dwordx4 v[88:91], v[174:175], off offset:512
	global_load_dwordx4 v[84:87], v[176:177], off offset:512
	global_load_dwordx4 v[68:71], v[178:179], off offset:512
	global_load_dwordx4 v[72:75], v[180:181], off offset:512
	global_load_dwordx4 v[76:79], v[182:183], off offset:512
	global_load_dwordx4 v[80:83], v[184:185], off offset:512
	s_waitcnt lgkmcnt(0)
	s_barrier
	ds_read_b128 v[156:159], v192 offset:2048
	ds_read_b128 v[152:155], v192 offset:4096
	ds_read_b128 v[92:95], v192 offset:6144
	ds_read_b128 v[96:99], v193 offset:16384
	ds_read_b128 v[140:143], v193 offset:18432
	ds_read_b128 v[144:147], v193 offset:20480
	ds_read_b128 v[148:151], v193 offset:22528
	s_and_b64 vcc, exec, s[46:47]
	s_cbranch_vccnz .LBB0_1446
	ds_read_b128 v[194:197], v192
	s_waitcnt lgkmcnt(0)
	v_mfma_f32_16x16x32_bf16 v[64:67], v[194:197], v[96:99], v[64:67]
	v_mfma_f32_16x16x32_bf16 v[60:63], v[194:197], v[140:143], v[60:63]
	v_mfma_f32_16x16x32_bf16 v[56:59], v[194:197], v[144:147], v[56:59]
	v_mfma_f32_16x16x32_bf16 v[52:55], v[194:197], v[148:151], v[52:55]

.LBB0_1456:
	s_waitcnt lgkmcnt(0)
	v_cndmask_b32_e64 v95, 0, v135, s[40:41]
	v_cndmask_b32_e64 v94, 0, v134, s[40:41]
	v_cndmask_b32_e64 v93, 0, v133, s[40:41]
	v_cndmask_b32_e64 v92, 0, v132, s[40:41]
	v_cndmask_b32_e64 v99, 0, v127, s[42:43]
	v_cndmask_b32_e64 v98, 0, v126, s[42:43]
	v_cndmask_b32_e64 v97, 0, v125, s[42:43]
	v_cndmask_b32_e64 v96, 0, v124, s[42:43]
	v_cndmask_b32_e64 v123, 0, v123, s[44:45]
	v_cndmask_b32_e64 v122, 0, v122, s[44:45]
	v_cndmask_b32_e64 v121, 0, v121, s[44:45]
	v_cndmask_b32_e64 v120, 0, v120, s[44:45]
	v_cndmask_b32_e64 v119, 0, v119, s[38:39]
	v_cndmask_b32_e64 v118, 0, v118, s[38:39]
	v_cndmask_b32_e64 v117, 0, v117, s[38:39]
	v_cndmask_b32_e64 v116, 0, v116, s[38:39]
	ds_write_b128 v191, v[92:95] offset:32768
	ds_write_b128 v191, v[96:99] offset:36864
	ds_write_b128 v191, v[120:123] offset:40960
	ds_write_b128 v191, v[116:119] offset:45056
	ds_write_b128 v191, v[100:103] offset:49152
	ds_write_b128 v191, v[104:107] offset:53248
	ds_write_b128 v191, v[108:111] offset:57344
	ds_write_b128 v191, v[112:115] offset:61440
	global_load_dwordx4 v[132:135], v[170:171], off offset:640
	global_load_dwordx4 v[124:127], v[172:173], off offset:640
	global_load_dwordx4 v[116:119], v[174:175], off offset:640
	global_load_dwordx4 v[112:115], v[176:177], off offset:640
	global_load_dwordx4 v[92:95], v[178:179], off offset:640
	global_load_dwordx4 v[96:99], v[180:181], off offset:640
	global_load_dwordx4 v[100:103], v[182:183], off offset:640
	global_load_dwordx4 v[104:107], v[184:185], off offset:640
	s_waitcnt lgkmcnt(0)
	s_barrier
	ds_read_b128 v[156:159], v192 offset:34816
	ds_read_b128 v[152:155], v192 offset:36864
	ds_read_b128 v[108:111], v192 offset:38912
	ds_read_b128 v[120:123], v193 offset:49152
	ds_read_b128 v[140:143], v193 offset:51200
	ds_read_b128 v[144:147], v193 offset:53248
	ds_read_b128 v[148:151], v193 offset:55296
	s_and_b64 vcc, exec, s[46:47]
	s_cbranch_vccnz .LBB0_1458
	ds_read_b128 v[194:197], v192 offset:32768
	s_waitcnt lgkmcnt(0)
	v_mfma_f32_16x16x32_bf16 v[64:67], v[194:197], v[120:123], v[64:67]
	v_mfma_f32_16x16x32_bf16 v[60:63], v[194:197], v[140:143], v[60:63]
	v_mfma_f32_16x16x32_bf16 v[56:59], v[194:197], v[144:147], v[56:59]
	v_mfma_f32_16x16x32_bf16 v[52:55], v[194:197], v[148:151], v[52:55]

.LBB0_1468:
	s_waitcnt vmcnt(0) lgkmcnt(0)
	v_cndmask_b32_e64 v111, 0, v139, s[40:41]
	v_cndmask_b32_e64 v110, 0, v138, s[40:41]
	v_cndmask_b32_e64 v109, 0, v137, s[40:41]
	v_cndmask_b32_e64 v108, 0, v136, s[40:41]
	v_cndmask_b32_e64 v123, 0, v131, s[42:43]
	v_cndmask_b32_e64 v122, 0, v130, s[42:43]
	v_cndmask_b32_e64 v121, 0, v129, s[42:43]
	v_cndmask_b32_e64 v120, 0, v128, s[42:43]
	v_cndmask_b32_e64 v91, 0, v91, s[44:45]
	v_cndmask_b32_e64 v90, 0, v90, s[44:45]
	v_cndmask_b32_e64 v89, 0, v89, s[44:45]
	v_cndmask_b32_e64 v88, 0, v88, s[44:45]
	v_cndmask_b32_e64 v87, 0, v87, s[38:39]
	v_cndmask_b32_e64 v86, 0, v86, s[38:39]
	v_cndmask_b32_e64 v85, 0, v85, s[38:39]
	v_cndmask_b32_e64 v84, 0, v84, s[38:39]
	ds_write_b128 v191, v[108:111]
	ds_write_b128 v191, v[120:123] offset:4096
	ds_write_b128 v191, v[88:91] offset:8192
	ds_write_b128 v191, v[84:87] offset:12288
	ds_write_b128 v191, v[68:71] offset:16384
	ds_write_b128 v191, v[72:75] offset:20480
	ds_write_b128 v191, v[76:79] offset:24576
	ds_write_b128 v191, v[80:83] offset:28672
	global_load_dwordx4 v[120:123], v[170:171], off offset:768
	global_load_dwordx4 v[108:111], v[172:173], off offset:768
	global_load_dwordx4 v[88:91], v[174:175], off offset:768
	global_load_dwordx4 v[84:87], v[176:177], off offset:768
	global_load_dwordx4 v[68:71], v[178:179], off offset:768
	global_load_dwordx4 v[72:75], v[180:181], off offset:768
	global_load_dwordx4 v[76:79], v[182:183], off offset:768
	global_load_dwordx4 v[80:83], v[184:185], off offset:768
	s_waitcnt lgkmcnt(0)
	s_barrier
	ds_read_b128 v[156:159], v192 offset:2048
	ds_read_b128 v[152:155], v192 offset:4096
	ds_read_b128 v[128:131], v192 offset:6144
	ds_read_b128 v[136:139], v193 offset:16384
	ds_read_b128 v[140:143], v193 offset:18432
	ds_read_b128 v[144:147], v193 offset:20480
	ds_read_b128 v[148:151], v193 offset:22528
	s_and_b64 vcc, exec, s[46:47]
	s_cbranch_vccnz .LBB0_1470
	ds_read_b128 v[194:197], v192
	s_waitcnt lgkmcnt(0)
	v_mfma_f32_16x16x32_bf16 v[64:67], v[194:197], v[136:139], v[64:67]
	v_mfma_f32_16x16x32_bf16 v[60:63], v[194:197], v[140:143], v[60:63]
	v_mfma_f32_16x16x32_bf16 v[56:59], v[194:197], v[144:147], v[56:59]
	v_mfma_f32_16x16x32_bf16 v[52:55], v[194:197], v[148:151], v[52:55]

.LBB0_1480:
	s_waitcnt lgkmcnt(0)
	v_cndmask_b32_e64 v131, 0, v135, s[40:41]
	v_cndmask_b32_e64 v130, 0, v134, s[40:41]
	v_cndmask_b32_e64 v129, 0, v133, s[40:41]
	v_cndmask_b32_e64 v128, 0, v132, s[40:41]
	v_cndmask_b32_e64 v127, 0, v127, s[42:43]
	v_cndmask_b32_e64 v126, 0, v126, s[42:43]
	v_cndmask_b32_e64 v125, 0, v125, s[42:43]
	v_cndmask_b32_e64 v124, 0, v124, s[42:43]
	v_cndmask_b32_e64 v119, 0, v119, s[44:45]
	v_cndmask_b32_e64 v118, 0, v118, s[44:45]
	v_cndmask_b32_e64 v117, 0, v117, s[44:45]
	v_cndmask_b32_e64 v116, 0, v116, s[44:45]
	v_cndmask_b32_e64 v115, 0, v115, s[38:39]
	v_cndmask_b32_e64 v114, 0, v114, s[38:39]
	v_cndmask_b32_e64 v113, 0, v113, s[38:39]
	v_cndmask_b32_e64 v112, 0, v112, s[38:39]
	ds_write_b128 v191, v[128:131] offset:32768
	ds_write_b128 v191, v[124:127] offset:36864
	ds_write_b128 v191, v[116:119] offset:40960
	ds_write_b128 v191, v[112:115] offset:45056
	ds_write_b128 v191, v[92:95] offset:49152
	ds_write_b128 v191, v[96:99] offset:53248
	ds_write_b128 v191, v[100:103] offset:57344
	ds_write_b128 v191, v[104:107] offset:61440
	global_load_dwordx4 v[128:131], v[170:171], off offset:896
	global_load_dwordx4 v[124:127], v[172:173], off offset:896
	global_load_dwordx4 v[116:119], v[174:175], off offset:896
	global_load_dwordx4 v[112:115], v[176:177], off offset:896
	global_load_dwordx4 v[92:95], v[178:179], off offset:896
	global_load_dwordx4 v[96:99], v[180:181], off offset:896
	global_load_dwordx4 v[100:103], v[182:183], off offset:896
	global_load_dwordx4 v[104:107], v[184:185], off offset:896
	s_waitcnt lgkmcnt(0)
	s_barrier
	ds_read_b128 v[156:159], v192 offset:34816
	ds_read_b128 v[152:155], v192 offset:36864
	ds_read_b128 v[132:135], v192 offset:38912
	ds_read_b128 v[136:139], v193 offset:49152
	ds_read_b128 v[140:143], v193 offset:51200
	ds_read_b128 v[144:147], v193 offset:53248
	ds_read_b128 v[148:151], v193 offset:55296
	s_and_b64 vcc, exec, s[46:47]
	s_cbranch_vccnz .LBB0_1482
	ds_read_b128 v[170:173], v192 offset:32768
	s_waitcnt lgkmcnt(0)
	v_mfma_f32_16x16x32_bf16 v[64:67], v[170:173], v[136:139], v[64:67]
	v_mfma_f32_16x16x32_bf16 v[60:63], v[170:173], v[140:143], v[60:63]
	v_mfma_f32_16x16x32_bf16 v[56:59], v[170:173], v[144:147], v[56:59]
	v_mfma_f32_16x16x32_bf16 v[52:55], v[170:173], v[148:151], v[52:55]

; __device__ __forceinline__ u16 f2bf(float f) { return (u16)(pack2(f, 0.f) & 0xffffu); }
; __device__ __forceinline__ int tid_() { int t = threadIdx.x; asm volatile("" : "+v"(t)); return t; }
; template <int NT, class VF, class RP>
; __device__ __forceinline__ void epi_staged_bf16(f32x4 (&acc)[4][NT], int r0, int c0, unsigned char* smem, VF vf, RP rowptr) {
;   constexpr int BN = NT * 32, PITCH = BN + 8, CPR = BN / 8;
;   u16* Ts = (u16*)smem;
;   const int t = tid_();
;   __syncthreads();
; #pragma unroll
;   for (int mi = 0; mi < 4; ++mi)
; #pragma unroll
;     for (int ni = 0; ni < NT; ++ni)
; #pragma unroll
;       for (int j = 0; j < 4; ++j) {
;         const int r = r0 + mi * 16 + j, c = c0 + ni * 16;
;         Ts[r * PITCH + c] = f2bf(vf(r, c, acc[mi][ni][j]));
; __device__ __forceinline__ void phase_moe_down(const Params& p, int l, bool last, unsigned char* smem) {
;     ...
;     auto epi = [&](f32x4(&acc)[4][4], int r0, int c0) {
;       auto vf = [&](int r, int, float v) { return (r < mvalid ? gate[r] : 0.f) * v; };
;       auto rp = [&](int r) -> u16* { return r < mvalid ? yb + (size_t)r * 1024 : nullptr; };
;       epi_staged_bf16<4>(acc, r0, c0, smem, vf, rp);
.LBB0_1516:
	v_lshl_or_b32 v2, v0, 2, v190
	v_mov_b32_e32 v0, v187
	v_cmp_gt_i32_e32 vcc, s60, v2
	s_waitcnt lgkmcnt(4)
	v_mov_b32_e32 v70, 0
	v_ashrrev_i32_e32 v3, 31, v2
	v_mov_b32_e32 v69, 0
	s_waitcnt lgkmcnt(0)
	s_barrier
	s_and_saveexec_b64 s[0:1], vcc
	s_xor_b64 s[0:1], exec, s[0:1]
	s_cbranch_execz .LBB0_1518
	v_lshl_add_u64 v[68:69], v[2:3], 2, v[162:163]
	global_load_dword v69, v[68:69], off
.LBB0_1518:
	s_or_b64 exec, exec, s[0:1]
	v_lshl_or_b32 v68, v188, 6, v189
	s_waitcnt vmcnt(0) lgkmcnt(0)
	v_mul_f32_e32 v64, v64, v69
	v_mul_lo_u32 v69, v2, s22
	v_lshlrev_b32_e32 v71, 1, v68
	v_cvt_pk_bf16_f32 v64, v64, s0
	v_lshl_add_u32 v71, v69, 1, v71
	ds_write_b16 v71, v64
	v_or_b32_e32 v64, 1, v2
	v_cmp_gt_i32_e64 s[38:39], s60, v64
	s_and_saveexec_b64 s[0:1], s[38:39]
	s_cbranch_execz .LBB0_1520
	v_lshl_add_u64 v[70:71], v[2:3], 2, v[162:163]
	global_load_dword v70, v[70:71], off offset:4
.LBB0_1520:
	s_or_b64 exec, exec, s[0:1]
	s_waitcnt vmcnt(0) lgkmcnt(0)
	v_mul_f32_e32 v65, v65, v70
	v_cvt_pk_bf16_f32 v70, v65, s0
	v_mul_lo_u32 v65, v64, s23
	v_lshl_add_u32 v64, v68, 1, v65
	ds_write_b16 v64, v70
	v_or_b32_e32 v70, 2, v2
	v_cmp_gt_i32_e64 s[40:41], s60, v70
	v_mov_b32_e32 v70, 0
	v_mov_b32_e32 v71, 0
	s_and_saveexec_b64 s[0:1], s[40:41]
	s_cbranch_execz .LBB0_1522
	v_lshl_add_u64 v[72:73], v[2:3], 2, v[162:163]
	global_load_dword v71, v[72:73], off offset:8
.LBB0_1522:
	s_or_b64 exec, exec, s[0:1]
	s_waitcnt vmcnt(0) lgkmcnt(0)
	v_mul_f32_e32 v66, v66, v71
	v_add_u32_e32 v65, 0x110, v65
	v_cvt_pk_bf16_f32 v66, v66, s0
	v_lshl_add_u32 v65, v68, 1, v65
	ds_write_b16 v65, v66
	v_or_b32_e32 v66, 3, v2
	v_cmp_gt_i32_e64 s[42:43], s60, v66
	s_and_saveexec_b64 s[0:1], s[42:43]
	s_cbranch_execz .LBB0_1524
	v_lshl_add_u64 v[70:71], v[2:3], 2, v[162:163]
	global_load_dword v70, v[70:71], off offset:12
.LBB0_1524:
	s_or_b64 exec, exec, s[0:1]
	s_waitcnt vmcnt(0) lgkmcnt(0)
	v_mul_f32_e32 v66, v67, v70
	v_cvt_pk_bf16_f32 v66, v66, s0
	ds_write_b16 v65, v66 offset:272
	v_mov_b32_e32 v67, 0
	v_mov_b32_e32 v66, 0
	s_and_saveexec_b64 s[0:1], vcc
	s_cbranch_execz .LBB0_1526
	v_lshl_add_u64 v[70:71], v[2:3], 2, v[162:163]
	global_load_dword v66, v[70:71], off
.LBB0_1526:
	s_or_b64 exec, exec, s[0:1]
	s_waitcnt vmcnt(0) lgkmcnt(0)
	v_mul_f32_e32 v60, v60, v66
	v_lshlrev_b32_e32 v66, 1, v69
	v_cvt_pk_bf16_f32 v60, v60, s0
	v_lshl_add_u32 v66, v68, 1, v66
	ds_write_b16 v66, v60 offset:32
	s_and_saveexec_b64 s[0:1], s[38:39]
	s_cbranch_execz .LBB0_1528
	v_lshl_add_u64 v[70:71], v[2:3], 2, v[162:163]
	global_load_dword v67, v[70:71], off offset:4
.LBB0_1528:
	s_or_b64 exec, exec, s[0:1]
	s_waitcnt vmcnt(0) lgkmcnt(0)
	v_mul_f32_e32 v60, v61, v67
	v_cvt_pk_bf16_f32 v60, v60, s0
	ds_write_b16 v64, v60 offset:32
	v_mov_b32_e32 v61, 0
	v_mov_b32_e32 v60, 0
	s_and_saveexec_b64 s[0:1], s[40:41]
	s_cbranch_execz .LBB0_1530
	v_lshl_add_u64 v[70:71], v[2:3], 2, v[162:163]
	global_load_dword v60, v[70:71], off offset:8
.LBB0_1530:
	s_or_b64 exec, exec, s[0:1]
	s_waitcnt vmcnt(0) lgkmcnt(0)
	v_mul_f32_e32 v60, v62, v60
	v_cvt_pk_bf16_f32 v60, v60, s0
	ds_write_b16 v65, v60 offset:32
	s_and_saveexec_b64 s[0:1], s[42:43]
	s_cbranch_execz .LBB0_1532
	v_lshl_add_u64 v[60:61], v[2:3], 2, v[162:163]
	global_load_dword v61, v[60:61], off offset:12
.LBB0_1532:
	s_or_b64 exec, exec, s[0:1]
	s_waitcnt vmcnt(0) lgkmcnt(0)
	v_mul_f32_e32 v61, v63, v61
	v_add_u32_e32 v60, 0x110, v65
	v_cvt_pk_bf16_f32 v61, v61, s0
	ds_write_b16 v60, v61 offset:32
	v_mov_b32_e32 v61, 0
	v_mov_b32_e32 v62, 0
	s_and_saveexec_b64 s[0:1], vcc
	s_cbranch_execz .LBB0_1534
	v_lshl_add_u64 v[62:63], v[2:3], 2, v[162:163]
	global_load_dword v62, v[62:63], off
.LBB0_1534:
	s_or_b64 exec, exec, s[0:1]
	s_waitcnt vmcnt(0) lgkmcnt(0)
	v_mul_f32_e32 v56, v56, v62
	v_cvt_pk_bf16_f32 v56, v56, s0
	ds_write_b16 v66, v56 offset:64
	s_and_saveexec_b64 s[0:1], s[38:39]
	s_cbranch_execz .LBB0_1536
	v_lshl_add_u64 v[62:63], v[2:3], 2, v[162:163]
	global_load_dword v61, v[62:63], off offset:4
.LBB0_1536:
	s_or_b64 exec, exec, s[0:1]
	s_waitcnt vmcnt(0) lgkmcnt(0)
	v_mul_f32_e32 v56, v57, v61
	v_cvt_pk_bf16_f32 v56, v56, s0
	ds_write_b16 v64, v56 offset:64
	v_mov_b32_e32 v56, 0
	v_mov_b32_e32 v57, 0
	s_and_saveexec_b64 s[0:1], s[40:41]
	s_cbranch_execz .LBB0_1538
	v_lshl_add_u64 v[62:63], v[2:3], 2, v[162:163]
	global_load_dword v57, v[62:63], off offset:8
.LBB0_1538:
	s_or_b64 exec, exec, s[0:1]
	s_waitcnt vmcnt(0) lgkmcnt(0)
	v_mul_f32_e32 v57, v58, v57
	v_cvt_pk_bf16_f32 v57, v57, s0
	ds_write_b16 v65, v57 offset:64
	s_and_saveexec_b64 s[0:1], s[42:43]
	s_cbranch_execz .LBB0_1540
	v_lshl_add_u64 v[56:57], v[2:3], 2, v[162:163]
	global_load_dword v56, v[56:57], off offset:12
.LBB0_1540:
	s_or_b64 exec, exec, s[0:1]
	s_waitcnt vmcnt(0) lgkmcnt(0)
	v_mul_f32_e32 v56, v59, v56
	v_cvt_pk_bf16_f32 v56, v56, s0
	ds_write_b16 v60, v56 offset:64
	v_mov_b32_e32 v56, 0
	v_mov_b32_e32 v57, 0
	s_and_saveexec_b64 s[0:1], vcc
	s_cbranch_execz .LBB0_1542
	v_lshl_add_u64 v[58:59], v[2:3], 2, v[162:163]
	global_load_dword v57, v[58:59], off
.LBB0_1542:
	s_or_b64 exec, exec, s[0:1]
	s_waitcnt vmcnt(0) lgkmcnt(0)
	v_mul_f32_e32 v52, v52, v57
	v_cvt_pk_bf16_f32 v52, v52, s0
	ds_write_b16 v66, v52 offset:96
	s_and_saveexec_b64 s[0:1], s[38:39]
	s_cbranch_execz .LBB0_1544
	v_lshl_add_u64 v[56:57], v[2:3], 2, v[162:163]
	global_load_dword v56, v[56:57], off offset:4
.LBB0_1544:
	s_or_b64 exec, exec, s[0:1]
	s_waitcnt vmcnt(0) lgkmcnt(0)
	v_mul_f32_e32 v52, v53, v56
	v_cvt_pk_bf16_f32 v52, v52, s0
	ds_write_b16 v64, v52 offset:96
	v_mov_b32_e32 v52, 0
	v_mov_b32_e32 v53, 0
	s_and_saveexec_b64 s[0:1], s[40:41]
	s_cbranch_execz .LBB0_1546
	v_lshl_add_u64 v[56:57], v[2:3], 2, v[162:163]
	global_load_dword v53, v[56:57], off offset:8
; __device__ __forceinline__ u16 f2bf(float f) { return (u16)(pack2(f, 0.f) & 0xffffu); }
; __device__ __forceinline__ int tid_() { int t = threadIdx.x; asm volatile("" : "+v"(t)); return t; }
; template <int NT, class VF, class RP>
; __device__ __forceinline__ void epi_staged_bf16(f32x4 (&acc)[4][NT], int r0, int c0, unsigned char* smem, VF vf, RP rowptr) {
;   constexpr int BN = NT * 32, PITCH = BN + 8, CPR = BN / 8;
;   u16* Ts = (u16*)smem;
;   const int t = tid_();
;   __syncthreads();
; #pragma unroll
;   for (int mi = 0; mi < 4; ++mi)
; #pragma unroll
;     for (int ni = 0; ni < NT; ++ni)
; #pragma unroll
;       for (int j = 0; j < 4; ++j) {
;         const int r = r0 + mi * 16 + j, c = c0 + ni * 16;
;         Ts[r * PITCH + c] = f2bf(vf(r, c, acc[mi][ni][j]));
; __device__ __forceinline__ void phase_moe_down(const Params& p, int l, bool last, unsigned char* smem) {
;     ...
;     auto epi = [&](f32x4(&acc)[4][4], int r0, int c0) {
;       auto vf = [&](int r, int, float v) { return (r < mvalid ? gate[r] : 0.f) * v; };
;       auto rp = [&](int r) -> u16* { return r < mvalid ? yb + (size_t)r * 1024 : nullptr; };
;       epi_staged_bf16<4>(acc, r0, c0, smem, vf, rp);
.LBB0_1546:
	s_or_b64 exec, exec, s[0:1]
	s_waitcnt vmcnt(0) lgkmcnt(0)
	v_mul_f32_e32 v53, v54, v53
	v_cvt_pk_bf16_f32 v53, v53, s0
	ds_write_b16 v65, v53 offset:96
	s_and_saveexec_b64 s[0:1], s[42:43]
	s_cbranch_execz .LBB0_1548
	v_lshl_add_u64 v[52:53], v[2:3], 2, v[162:163]
	global_load_dword v52, v[52:53], off offset:12
.LBB0_1548:
	s_or_b64 exec, exec, s[0:1]
	s_waitcnt vmcnt(0) lgkmcnt(0)
	v_mul_f32_e32 v52, v55, v52
	v_cvt_pk_bf16_f32 v52, v52, s0
	v_or_b32_e32 v53, 16, v2
	ds_write_b16 v60, v52 offset:96
	v_cmp_gt_i32_e32 vcc, s60, v53
	v_mov_b32_e32 v52, 0
	v_mov_b32_e32 v54, 0
	s_and_saveexec_b64 s[0:1], vcc
	s_cbranch_execz .LBB0_1550
	v_lshl_add_u64 v[54:55], v[2:3], 2, v[162:163]
	global_load_dword v54, v[54:55], off offset:64
.LBB0_1550:
	s_or_b64 exec, exec, s[0:1]
	s_waitcnt vmcnt(0) lgkmcnt(0)
	v_mul_f32_e32 v48, v48, v54
	v_mul_lo_u32 v53, v53, s23
	v_cvt_pk_bf16_f32 v54, v48, s0
	v_lshl_add_u32 v48, v68, 1, v53
	ds_write_b16 v48, v54
	v_or_b32_e32 v54, 17, v2
	v_cmp_gt_i32_e64 s[38:39], s60, v54
	s_and_saveexec_b64 s[0:1], s[38:39]
	s_cbranch_execz .LBB0_1552
	v_lshl_add_u64 v[54:55], v[2:3], 2, v[162:163]
	global_load_dword v52, v[54:55], off offset:68
.LBB0_1552:
	s_or_b64 exec, exec, s[0:1]
	s_waitcnt vmcnt(0) lgkmcnt(0)
	v_mul_f32_e32 v49, v49, v52
	v_add_u32_e32 v53, 0x110, v53
	v_cvt_pk_bf16_f32 v52, v49, s0
	v_lshl_add_u32 v49, v68, 1, v53
	ds_write_b16 v49, v52
	v_or_b32_e32 v52, 18, v2
	v_cmp_gt_i32_e64 s[40:41], s60, v52
	v_mov_b32_e32 v52, 0
	v_mov_b32_e32 v54, 0
	s_and_saveexec_b64 s[0:1], s[40:41]
	s_cbranch_execz .LBB0_1554
	v_lshl_add_u64 v[54:55], v[2:3], 2, v[162:163]
	global_load_dword v54, v[54:55], off offset:72
.LBB0_1554:
	s_or_b64 exec, exec, s[0:1]
	s_waitcnt vmcnt(0) lgkmcnt(0)
	v_mul_f32_e32 v50, v50, v54
	v_cvt_pk_bf16_f32 v54, v50, s0
	v_add_u32_e32 v50, 0x110, v53
	v_or_b32_e32 v53, 19, v2
	v_lshl_add_u32 v50, v68, 1, v50
	v_cmp_gt_i32_e64 s[42:43], s60, v53
	ds_write_b16 v50, v54
	s_and_saveexec_b64 s[0:1], s[42:43]
	s_cbranch_execz .LBB0_1556
	v_lshl_add_u64 v[52:53], v[2:3], 2, v[162:163]
	global_load_dword v52, v[52:53], off offset:76
.LBB0_1556:
	s_or_b64 exec, exec, s[0:1]
	s_waitcnt vmcnt(0) lgkmcnt(0)
	v_mul_f32_e32 v51, v51, v52
	v_cvt_pk_bf16_f32 v51, v51, s0
	ds_write_b16 v50, v51 offset:272
	v_mov_b32_e32 v51, 0
	v_mov_b32_e32 v52, 0
	s_and_saveexec_b64 s[0:1], vcc
	s_cbranch_execz .LBB0_1558
	v_lshl_add_u64 v[52:53], v[2:3], 2, v[162:163]
	global_load_dword v52, v[52:53], off offset:64
.LBB0_1558:
	s_or_b64 exec, exec, s[0:1]
	s_waitcnt vmcnt(0) lgkmcnt(0)
	v_mul_f32_e32 v44, v44, v52
	v_cvt_pk_bf16_f32 v44, v44, s0
	ds_write_b16 v48, v44 offset:32
	s_and_saveexec_b64 s[0:1], s[38:39]
	s_cbranch_execz .LBB0_1560
	v_lshl_add_u64 v[52:53], v[2:3], 2, v[162:163]
	global_load_dword v51, v[52:53], off offset:68
.LBB0_1560:
	s_or_b64 exec, exec, s[0:1]
	s_waitcnt vmcnt(0) lgkmcnt(0)
	v_mul_f32_e32 v44, v45, v51
	v_cvt_pk_bf16_f32 v44, v44, s0
	ds_write_b16 v49, v44 offset:32
	v_mov_b32_e32 v45, 0
	v_mov_b32_e32 v44, 0
	s_and_saveexec_b64 s[0:1], s[40:41]
	s_cbranch_execz .LBB0_1562
	v_lshl_add_u64 v[52:53], v[2:3], 2, v[162:163]
	global_load_dword v44, v[52:53], off offset:72
.LBB0_1562:
	s_or_b64 exec, exec, s[0:1]
	s_waitcnt vmcnt(0) lgkmcnt(0)
	v_mul_f32_e32 v44, v46, v44
	v_cvt_pk_bf16_f32 v44, v44, s0
	ds_write_b16 v50, v44 offset:32
	s_and_saveexec_b64 s[0:1], s[42:43]
	s_cbranch_execz .LBB0_1564
	v_lshl_add_u64 v[44:45], v[2:3], 2, v[162:163]
	global_load_dword v45, v[44:45], off offset:76
.LBB0_1564:
	s_or_b64 exec, exec, s[0:1]
	s_waitcnt vmcnt(0) lgkmcnt(0)
	v_mul_f32_e32 v45, v47, v45
	v_add_u32_e32 v44, 0x110, v50
	v_cvt_pk_bf16_f32 v45, v45, s0
	ds_write_b16 v44, v45 offset:32
	v_mov_b32_e32 v45, 0
	v_mov_b32_e32 v46, 0
	s_and_saveexec_b64 s[0:1], vcc
	s_cbranch_execz .LBB0_1566
	v_lshl_add_u64 v[46:47], v[2:3], 2, v[162:163]
	global_load_dword v46, v[46:47], off offset:64
.LBB0_1566:
	s_or_b64 exec, exec, s[0:1]
	s_waitcnt vmcnt(0) lgkmcnt(0)
	v_mul_f32_e32 v40, v40, v46
	v_cvt_pk_bf16_f32 v40, v40, s0
	ds_write_b16 v48, v40 offset:64
	s_and_saveexec_b64 s[0:1], s[38:39]
	s_cbranch_execz .LBB0_1568
	v_lshl_add_u64 v[46:47], v[2:3], 2, v[162:163]
	global_load_dword v45, v[46:47], off offset:68
.LBB0_1568:
	s_or_b64 exec, exec, s[0:1]
	s_waitcnt vmcnt(0) lgkmcnt(0)
	v_mul_f32_e32 v40, v41, v45
	v_cvt_pk_bf16_f32 v40, v40, s0
	ds_write_b16 v49, v40 offset:64
	v_mov_b32_e32 v40, 0
	v_mov_b32_e32 v41, 0
	s_and_saveexec_b64 s[0:1], s[40:41]
	s_cbranch_execz .LBB0_1570
	v_lshl_add_u64 v[46:47], v[2:3], 2, v[162:163]
	global_load_dword v41, v[46:47], off offset:72
.LBB0_1570:
	s_or_b64 exec, exec, s[0:1]
	s_waitcnt vmcnt(0) lgkmcnt(0)
	v_mul_f32_e32 v41, v42, v41
	v_cvt_pk_bf16_f32 v41, v41, s0
	ds_write_b16 v50, v41 offset:64
	s_and_saveexec_b64 s[0:1], s[42:43]
	s_cbranch_execz .LBB0_1572
	v_lshl_add_u64 v[40:41], v[2:3], 2, v[162:163]
	global_load_dword v40, v[40:41], off offset:76
.LBB0_1572:
	s_or_b64 exec, exec, s[0:1]
	s_waitcnt vmcnt(0) lgkmcnt(0)
	v_mul_f32_e32 v40, v43, v40
	v_cvt_pk_bf16_f32 v40, v40, s0
	ds_write_b16 v44, v40 offset:64
	v_mov_b32_e32 v40, 0
	v_mov_b32_e32 v41, 0
	s_and_saveexec_b64 s[0:1], vcc
	s_cbranch_execz .LBB0_1574
	v_lshl_add_u64 v[42:43], v[2:3], 2, v[162:163]
	global_load_dword v41, v[42:43], off offset:64
.LBB0_1574:
	s_or_b64 exec, exec, s[0:1]
	s_waitcnt vmcnt(0) lgkmcnt(0)
	v_mul_f32_e32 v36, v36, v41
	v_cvt_pk_bf16_f32 v36, v36, s0
	ds_write_b16 v48, v36 offset:96
	s_and_saveexec_b64 s[0:1], s[38:39]
	s_cbranch_execz .LBB0_1576
	v_lshl_add_u64 v[40:41], v[2:3], 2, v[162:163]
	global_load_dword v40, v[40:41], off offset:68
; __device__ __forceinline__ u16 f2bf(float f) { return (u16)(pack2(f, 0.f) & 0xffffu); }
; __device__ __forceinline__ int tid_() { int t = threadIdx.x; asm volatile("" : "+v"(t)); return t; }
; template <int NT, class VF, class RP>
; __device__ __forceinline__ void epi_staged_bf16(f32x4 (&acc)[4][NT], int r0, int c0, unsigned char* smem, VF vf, RP rowptr) {
;   constexpr int BN = NT * 32, PITCH = BN + 8, CPR = BN / 8;
;   u16* Ts = (u16*)smem;
;   const int t = tid_();
;   __syncthreads();
; #pragma unroll
;   for (int mi = 0; mi < 4; ++mi)
; #pragma unroll
;     for (int ni = 0; ni < NT; ++ni)
; #pragma unroll
;       for (int j = 0; j < 4; ++j) {
;         const int r = r0 + mi * 16 + j, c = c0 + ni * 16;
;         Ts[r * PITCH + c] = f2bf(vf(r, c, acc[mi][ni][j]));
; __device__ __forceinline__ void phase_moe_down(const Params& p, int l, bool last, unsigned char* smem) {
;     ...
;     auto epi = [&](f32x4(&acc)[4][4], int r0, int c0) {
;       auto vf = [&](int r, int, float v) { return (r < mvalid ? gate[r] : 0.f) * v; };
;       auto rp = [&](int r) -> u16* { return r < mvalid ? yb + (size_t)r * 1024 : nullptr; };
;       epi_staged_bf16<4>(acc, r0, c0, smem, vf, rp);
.LBB0_1576:
	s_or_b64 exec, exec, s[0:1]
	s_waitcnt vmcnt(0) lgkmcnt(0)
	v_mul_f32_e32 v36, v37, v40
	v_cvt_pk_bf16_f32 v36, v36, s0
	ds_write_b16 v49, v36 offset:96
	v_mov_b32_e32 v36, 0
	v_mov_b32_e32 v37, 0
	s_and_saveexec_b64 s[0:1], s[40:41]
	s_cbranch_execz .LBB0_1578
	v_lshl_add_u64 v[40:41], v[2:3], 2, v[162:163]
	global_load_dword v37, v[40:41], off offset:72
.LBB0_1578:
	s_or_b64 exec, exec, s[0:1]
	s_waitcnt vmcnt(0) lgkmcnt(0)
	v_mul_f32_e32 v37, v38, v37
	v_cvt_pk_bf16_f32 v37, v37, s0
	ds_write_b16 v50, v37 offset:96
	s_and_saveexec_b64 s[0:1], s[42:43]
	s_cbranch_execz .LBB0_1580
	v_lshl_add_u64 v[36:37], v[2:3], 2, v[162:163]
	global_load_dword v36, v[36:37], off offset:76
.LBB0_1580:
	s_or_b64 exec, exec, s[0:1]
	s_waitcnt vmcnt(0) lgkmcnt(0)
	v_mul_f32_e32 v36, v39, v36
	v_cvt_pk_bf16_f32 v36, v36, s0
	v_or_b32_e32 v37, 32, v2
	ds_write_b16 v44, v36 offset:96
	v_cmp_gt_i32_e32 vcc, s60, v37
	v_mov_b32_e32 v36, 0
	v_mov_b32_e32 v38, 0
	s_and_saveexec_b64 s[0:1], vcc
	s_cbranch_execz .LBB0_1582
	v_lshl_add_u64 v[38:39], v[2:3], 2, v[162:163]
	global_load_dword v38, v[38:39], off offset:128
.LBB0_1582:
	s_or_b64 exec, exec, s[0:1]
	s_waitcnt vmcnt(0) lgkmcnt(0)
	v_mul_f32_e32 v32, v32, v38
	v_mul_lo_u32 v37, v37, s23
	v_cvt_pk_bf16_f32 v38, v32, s0
	v_lshl_add_u32 v32, v68, 1, v37
	ds_write_b16 v32, v38
	v_or_b32_e32 v38, 33, v2
	v_cmp_gt_i32_e64 s[38:39], s60, v38
	s_and_saveexec_b64 s[0:1], s[38:39]
	s_cbranch_execz .LBB0_1584
	v_lshl_add_u64 v[38:39], v[2:3], 2, v[162:163]
	global_load_dword v36, v[38:39], off offset:132
.LBB0_1584:
	s_or_b64 exec, exec, s[0:1]
	s_waitcnt vmcnt(0) lgkmcnt(0)
	v_mul_f32_e32 v33, v33, v36
	v_add_u32_e32 v37, 0x110, v37
	v_cvt_pk_bf16_f32 v36, v33, s0
	v_lshl_add_u32 v33, v68, 1, v37
	ds_write_b16 v33, v36
	v_or_b32_e32 v36, 34, v2
	v_cmp_gt_i32_e64 s[40:41], s60, v36
	v_mov_b32_e32 v36, 0
	v_mov_b32_e32 v38, 0
	s_and_saveexec_b64 s[0:1], s[40:41]
	s_cbranch_execz .LBB0_1586
	v_lshl_add_u64 v[38:39], v[2:3], 2, v[162:163]
	global_load_dword v38, v[38:39], off offset:136
.LBB0_1586:
	s_or_b64 exec, exec, s[0:1]
	s_waitcnt vmcnt(0) lgkmcnt(0)
	v_mul_f32_e32 v34, v34, v38
	v_cvt_pk_bf16_f32 v38, v34, s0
	v_add_u32_e32 v34, 0x110, v37
	v_or_b32_e32 v37, 35, v2
	v_lshl_add_u32 v34, v68, 1, v34
	v_cmp_gt_i32_e64 s[42:43], s60, v37
	ds_write_b16 v34, v38
	s_and_saveexec_b64 s[0:1], s[42:43]
	s_cbranch_execz .LBB0_1588
	v_lshl_add_u64 v[36:37], v[2:3], 2, v[162:163]
	global_load_dword v36, v[36:37], off offset:140
.LBB0_1588:
	s_or_b64 exec, exec, s[0:1]
	s_waitcnt vmcnt(0) lgkmcnt(0)
	v_mul_f32_e32 v35, v35, v36
	v_cvt_pk_bf16_f32 v35, v35, s0
	ds_write_b16 v34, v35 offset:272
	v_mov_b32_e32 v35, 0
	v_mov_b32_e32 v36, 0
	s_and_saveexec_b64 s[0:1], vcc
	s_cbranch_execz .LBB0_1590
	v_lshl_add_u64 v[36:37], v[2:3], 2, v[162:163]
	global_load_dword v36, v[36:37], off offset:128
.LBB0_1590:
	s_or_b64 exec, exec, s[0:1]
	s_waitcnt vmcnt(0) lgkmcnt(0)
	v_mul_f32_e32 v28, v28, v36
	v_cvt_pk_bf16_f32 v28, v28, s0
	ds_write_b16 v32, v28 offset:32
	s_and_saveexec_b64 s[0:1], s[38:39]
	s_cbranch_execz .LBB0_1592
	v_lshl_add_u64 v[36:37], v[2:3], 2, v[162:163]
	global_load_dword v35, v[36:37], off offset:132
.LBB0_1592:
	s_or_b64 exec, exec, s[0:1]
	s_waitcnt vmcnt(0) lgkmcnt(0)
	v_mul_f32_e32 v28, v29, v35
	v_cvt_pk_bf16_f32 v28, v28, s0
	ds_write_b16 v33, v28 offset:32
	v_mov_b32_e32 v29, 0
	v_mov_b32_e32 v28, 0
	s_and_saveexec_b64 s[0:1], s[40:41]
	s_cbranch_execz .LBB0_1594
	v_lshl_add_u64 v[36:37], v[2:3], 2, v[162:163]
	global_load_dword v28, v[36:37], off offset:136
.LBB0_1594:
	s_or_b64 exec, exec, s[0:1]
	s_waitcnt vmcnt(0) lgkmcnt(0)
	v_mul_f32_e32 v28, v30, v28
	v_cvt_pk_bf16_f32 v28, v28, s0
	ds_write_b16 v34, v28 offset:32
	s_and_saveexec_b64 s[0:1], s[42:43]
	s_cbranch_execz .LBB0_1596
	v_lshl_add_u64 v[28:29], v[2:3], 2, v[162:163]
	global_load_dword v29, v[28:29], off offset:140
.LBB0_1596:
	s_or_b64 exec, exec, s[0:1]
	s_waitcnt vmcnt(0) lgkmcnt(0)
	v_mul_f32_e32 v29, v31, v29
	v_add_u32_e32 v28, 0x110, v34
	v_cvt_pk_bf16_f32 v29, v29, s0
	ds_write_b16 v28, v29 offset:32
	v_mov_b32_e32 v29, 0
	v_mov_b32_e32 v30, 0
	s_and_saveexec_b64 s[0:1], vcc
	s_cbranch_execz .LBB0_1598
	v_lshl_add_u64 v[30:31], v[2:3], 2, v[162:163]
	global_load_dword v30, v[30:31], off offset:128
.LBB0_1598:
	s_or_b64 exec, exec, s[0:1]
	s_waitcnt vmcnt(0) lgkmcnt(0)
	v_mul_f32_e32 v24, v24, v30
	v_cvt_pk_bf16_f32 v24, v24, s0
	ds_write_b16 v32, v24 offset:64
	s_and_saveexec_b64 s[0:1], s[38:39]
	s_cbranch_execz .LBB0_1600
	v_lshl_add_u64 v[30:31], v[2:3], 2, v[162:163]
	global_load_dword v29, v[30:31], off offset:132
.LBB0_1600:
	s_or_b64 exec, exec, s[0:1]
	s_waitcnt vmcnt(0) lgkmcnt(0)
	v_mul_f32_e32 v24, v25, v29
	v_cvt_pk_bf16_f32 v24, v24, s0
	ds_write_b16 v33, v24 offset:64
	v_mov_b32_e32 v24, 0
	v_mov_b32_e32 v25, 0
	s_and_saveexec_b64 s[0:1], s[40:41]
	s_cbranch_execz .LBB0_1602
	v_lshl_add_u64 v[30:31], v[2:3], 2, v[162:163]
	global_load_dword v25, v[30:31], off offset:136
.LBB0_1602:
	s_or_b64 exec, exec, s[0:1]
	s_waitcnt vmcnt(0) lgkmcnt(0)
	v_mul_f32_e32 v25, v26, v25
	v_cvt_pk_bf16_f32 v25, v25, s0
	ds_write_b16 v34, v25 offset:64
	s_and_saveexec_b64 s[0:1], s[42:43]
	s_cbranch_execz .LBB0_1604
	v_lshl_add_u64 v[24:25], v[2:3], 2, v[162:163]
	global_load_dword v24, v[24:25], off offset:140
.LBB0_1604:
	s_or_b64 exec, exec, s[0:1]
	s_waitcnt vmcnt(0) lgkmcnt(0)
	v_mul_f32_e32 v24, v27, v24
	v_cvt_pk_bf16_f32 v24, v24, s0
	ds_write_b16 v28, v24 offset:64
	v_mov_b32_e32 v24, 0
	v_mov_b32_e32 v25, 0
	s_and_saveexec_b64 s[0:1], vcc
	s_cbranch_execz .LBB0_1606
	v_lshl_add_u64 v[26:27], v[2:3], 2, v[162:163]
	global_load_dword v25, v[26:27], off offset:128
; __device__ __forceinline__ u16 f2bf(float f) { return (u16)(pack2(f, 0.f) & 0xffffu); }
; __device__ __forceinline__ int tid_() { int t = threadIdx.x; asm volatile("" : "+v"(t)); return t; }
; template <int NT, class VF, class RP>
; __device__ __forceinline__ void epi_staged_bf16(f32x4 (&acc)[4][NT], int r0, int c0, unsigned char* smem, VF vf, RP rowptr) {
;   constexpr int BN = NT * 32, PITCH = BN + 8, CPR = BN / 8;
;   u16* Ts = (u16*)smem;
;   const int t = tid_();
;   __syncthreads();
; #pragma unroll
;   for (int mi = 0; mi < 4; ++mi)
; #pragma unroll
;     for (int ni = 0; ni < NT; ++ni)
; #pragma unroll
;       for (int j = 0; j < 4; ++j) {
;         const int r = r0 + mi * 16 + j, c = c0 + ni * 16;
;         Ts[r * PITCH + c] = f2bf(vf(r, c, acc[mi][ni][j]));
; __device__ __forceinline__ void phase_moe_down(const Params& p, int l, bool last, unsigned char* smem) {
;     ...
;     auto epi = [&](f32x4(&acc)[4][4], int r0, int c0) {
;       auto vf = [&](int r, int, float v) { return (r < mvalid ? gate[r] : 0.f) * v; };
;       auto rp = [&](int r) -> u16* { return r < mvalid ? yb + (size_t)r * 1024 : nullptr; };
;       epi_staged_bf16<4>(acc, r0, c0, smem, vf, rp);
.LBB0_1606:
	s_or_b64 exec, exec, s[0:1]
	s_waitcnt vmcnt(0) lgkmcnt(0)
	v_mul_f32_e32 v20, v20, v25
	v_cvt_pk_bf16_f32 v20, v20, s0
	ds_write_b16 v32, v20 offset:96
	s_and_saveexec_b64 s[0:1], s[38:39]
	s_cbranch_execz .LBB0_1608
	v_lshl_add_u64 v[24:25], v[2:3], 2, v[162:163]
	global_load_dword v24, v[24:25], off offset:132
.LBB0_1608:
	s_or_b64 exec, exec, s[0:1]
	s_waitcnt vmcnt(0) lgkmcnt(0)
	v_mul_f32_e32 v20, v21, v24
	v_cvt_pk_bf16_f32 v20, v20, s0
	ds_write_b16 v33, v20 offset:96
	v_mov_b32_e32 v20, 0
	v_mov_b32_e32 v21, 0
	s_and_saveexec_b64 s[0:1], s[40:41]
	s_cbranch_execz .LBB0_1610
	v_lshl_add_u64 v[24:25], v[2:3], 2, v[162:163]
	global_load_dword v21, v[24:25], off offset:136
.LBB0_1610:
	s_or_b64 exec, exec, s[0:1]
	s_waitcnt vmcnt(0) lgkmcnt(0)
	v_mul_f32_e32 v21, v22, v21
	v_cvt_pk_bf16_f32 v21, v21, s0
	ds_write_b16 v34, v21 offset:96
	s_and_saveexec_b64 s[0:1], s[42:43]
	s_cbranch_execz .LBB0_1612
	v_lshl_add_u64 v[20:21], v[2:3], 2, v[162:163]
	global_load_dword v20, v[20:21], off offset:140
.LBB0_1612:
	s_or_b64 exec, exec, s[0:1]
	s_waitcnt vmcnt(0) lgkmcnt(0)
	v_mul_f32_e32 v20, v23, v20
	v_cvt_pk_bf16_f32 v20, v20, s0
	v_or_b32_e32 v21, 48, v2
	ds_write_b16 v28, v20 offset:96
	v_cmp_gt_i32_e32 vcc, s60, v21
	v_mov_b32_e32 v20, 0
	v_mov_b32_e32 v22, 0
	s_and_saveexec_b64 s[0:1], vcc
	s_cbranch_execz .LBB0_1614
	v_lshl_add_u64 v[22:23], v[2:3], 2, v[162:163]
	global_load_dword v22, v[22:23], off offset:192
.LBB0_1614:
	s_or_b64 exec, exec, s[0:1]
	s_waitcnt vmcnt(0) lgkmcnt(0)
	v_mul_f32_e32 v16, v16, v22
	v_mul_lo_u32 v21, v21, s23
	v_cvt_pk_bf16_f32 v22, v16, s0
	v_lshl_add_u32 v16, v68, 1, v21
	ds_write_b16 v16, v22
	v_or_b32_e32 v22, 49, v2
	v_cmp_gt_i32_e64 s[38:39], s60, v22
	s_and_saveexec_b64 s[0:1], s[38:39]
	s_cbranch_execz .LBB0_1616
	v_lshl_add_u64 v[22:23], v[2:3], 2, v[162:163]
	global_load_dword v20, v[22:23], off offset:196
.LBB0_1616:
	s_or_b64 exec, exec, s[0:1]
	s_waitcnt vmcnt(0) lgkmcnt(0)
	v_mul_f32_e32 v17, v17, v20
	v_add_u32_e32 v21, 0x110, v21
	v_cvt_pk_bf16_f32 v20, v17, s0
	v_lshl_add_u32 v17, v68, 1, v21
	ds_write_b16 v17, v20
	v_or_b32_e32 v20, 50, v2
	v_cmp_gt_i32_e64 s[40:41], s60, v20
	v_mov_b32_e32 v20, 0
	v_mov_b32_e32 v22, 0
	s_and_saveexec_b64 s[0:1], s[40:41]
	s_cbranch_execz .LBB0_1618
	v_lshl_add_u64 v[22:23], v[2:3], 2, v[162:163]
	global_load_dword v22, v[22:23], off offset:200
.LBB0_1618:
	s_or_b64 exec, exec, s[0:1]
	s_waitcnt vmcnt(0) lgkmcnt(0)
	v_mul_f32_e32 v18, v18, v22
	v_cvt_pk_bf16_f32 v22, v18, s0
	v_add_u32_e32 v18, 0x110, v21
	v_or_b32_e32 v21, 51, v2
	v_lshl_add_u32 v18, v68, 1, v18
	v_cmp_gt_i32_e64 s[42:43], s60, v21
	ds_write_b16 v18, v22
	s_and_saveexec_b64 s[0:1], s[42:43]
	s_cbranch_execz .LBB0_1620
	v_lshl_add_u64 v[20:21], v[2:3], 2, v[162:163]
	global_load_dword v20, v[20:21], off offset:204
.LBB0_1620:
	s_or_b64 exec, exec, s[0:1]
	s_waitcnt vmcnt(0) lgkmcnt(0)
	v_mul_f32_e32 v19, v19, v20
	v_cvt_pk_bf16_f32 v19, v19, s0
	ds_write_b16 v18, v19 offset:272
	v_mov_b32_e32 v19, 0
	v_mov_b32_e32 v20, 0
	s_and_saveexec_b64 s[0:1], vcc
	s_cbranch_execz .LBB0_1622
	v_lshl_add_u64 v[20:21], v[2:3], 2, v[162:163]
	global_load_dword v20, v[20:21], off offset:192
.LBB0_1622:
	s_or_b64 exec, exec, s[0:1]
	s_waitcnt vmcnt(0) lgkmcnt(0)
	v_mul_f32_e32 v12, v12, v20
	v_cvt_pk_bf16_f32 v12, v12, s0
	ds_write_b16 v16, v12 offset:32
	s_and_saveexec_b64 s[0:1], s[38:39]
	s_cbranch_execz .LBB0_1624
	v_lshl_add_u64 v[20:21], v[2:3], 2, v[162:163]
	global_load_dword v19, v[20:21], off offset:196
.LBB0_1624:
	s_or_b64 exec, exec, s[0:1]
	s_waitcnt vmcnt(0) lgkmcnt(0)
	v_mul_f32_e32 v12, v13, v19
	v_cvt_pk_bf16_f32 v12, v12, s0
	ds_write_b16 v17, v12 offset:32
	v_mov_b32_e32 v13, 0
	v_mov_b32_e32 v12, 0
	s_and_saveexec_b64 s[0:1], s[40:41]
	s_cbranch_execz .LBB0_1626
	v_lshl_add_u64 v[20:21], v[2:3], 2, v[162:163]
	global_load_dword v12, v[20:21], off offset:200
; __device__ __forceinline__ u16 f2bf(float f) { return (u16)(pack2(f, 0.f) & 0xffffu); }
; __device__ __forceinline__ int tid_() { int t = threadIdx.x; asm volatile("" : "+v"(t)); return t; }
; template <int NT, class VF, class RP>
; __device__ __forceinline__ void epi_staged_bf16(f32x4 (&acc)[4][NT], int r0, int c0, unsigned char* smem, VF vf, RP rowptr) {
;   constexpr int BN = NT * 32, PITCH = BN + 8, CPR = BN / 8;
;   u16* Ts = (u16*)smem;
;   const int t = tid_();
;   __syncthreads();
; #pragma unroll
;   for (int mi = 0; mi < 4; ++mi)
; #pragma unroll
;     for (int ni = 0; ni < NT; ++ni)
; #pragma unroll
;       for (int j = 0; j < 4; ++j) {
;         const int r = r0 + mi * 16 + j, c = c0 + ni * 16;
;         Ts[r * PITCH + c] = f2bf(vf(r, c, acc[mi][ni][j]));
;       }
;   __syncthreads();
; #pragma unroll
;   for (int i = 0; i < CPR / 2; ++i) {
;     const int c = t + 256 * i, row = c / CPR, ch = c % CPR;
;     u16* d = rowptr(row);
;     if (d) *(u32x4*)(d + ch * 8) = *(const u32x4*)(Ts + row * PITCH + ch * 8);
;   }
; __device__ __forceinline__ void phase_moe_down(const Params& p, int l, bool last, unsigned char* smem) {
;     ...
;     auto epi = [&](f32x4(&acc)[4][4], int r0, int c0) {
;       auto vf = [&](int r, int, float v) { return (r < mvalid ? gate[r] : 0.f) * v; };
;       auto rp = [&](int r) -> u16* { return r < mvalid ? yb + (size_t)r * 1024 : nullptr; };
;       epi_staged_bf16<4>(acc, r0, c0, smem, vf, rp);
.LBB0_1626:
	s_or_b64 exec, exec, s[0:1]
	s_waitcnt vmcnt(0) lgkmcnt(0)
	v_mul_f32_e32 v12, v14, v12
	v_cvt_pk_bf16_f32 v12, v12, s0
	ds_write_b16 v18, v12 offset:32
	s_and_saveexec_b64 s[0:1], s[42:43]
	s_cbranch_execz .LBB0_1628
	v_lshl_add_u64 v[12:13], v[2:3], 2, v[162:163]
	global_load_dword v13, v[12:13], off offset:204
.LBB0_1628:
	s_or_b64 exec, exec, s[0:1]
	s_waitcnt vmcnt(0) lgkmcnt(0)
	v_mul_f32_e32 v13, v15, v13
	v_add_u32_e32 v12, 0x110, v18
	v_cvt_pk_bf16_f32 v13, v13, s0
	ds_write_b16 v12, v13 offset:32
	v_mov_b32_e32 v13, 0
	v_mov_b32_e32 v14, 0
	s_and_saveexec_b64 s[0:1], vcc
	s_cbranch_execz .LBB0_1630
	v_lshl_add_u64 v[14:15], v[2:3], 2, v[162:163]
	global_load_dword v14, v[14:15], off offset:192
.LBB0_1630:
	s_or_b64 exec, exec, s[0:1]
	s_waitcnt vmcnt(0) lgkmcnt(0)
	v_mul_f32_e32 v8, v8, v14
	v_cvt_pk_bf16_f32 v8, v8, s0
	ds_write_b16 v16, v8 offset:64
	s_and_saveexec_b64 s[0:1], s[38:39]
	s_cbranch_execz .LBB0_1632
	v_lshl_add_u64 v[14:15], v[2:3], 2, v[162:163]
	global_load_dword v13, v[14:15], off offset:196
.LBB0_1632:
	s_or_b64 exec, exec, s[0:1]
	s_waitcnt vmcnt(0) lgkmcnt(0)
	v_mul_f32_e32 v8, v9, v13
	v_cvt_pk_bf16_f32 v8, v8, s0
	ds_write_b16 v17, v8 offset:64
	v_mov_b32_e32 v8, 0
	v_mov_b32_e32 v9, 0
	s_and_saveexec_b64 s[0:1], s[40:41]
	s_cbranch_execz .LBB0_1634
	v_lshl_add_u64 v[14:15], v[2:3], 2, v[162:163]
	global_load_dword v9, v[14:15], off offset:200
.LBB0_1634:
	s_or_b64 exec, exec, s[0:1]
	s_waitcnt vmcnt(0) lgkmcnt(0)
	v_mul_f32_e32 v9, v10, v9
	v_cvt_pk_bf16_f32 v9, v9, s0
	ds_write_b16 v18, v9 offset:64
	s_and_saveexec_b64 s[0:1], s[42:43]
	s_cbranch_execz .LBB0_1636
	v_lshl_add_u64 v[8:9], v[2:3], 2, v[162:163]
	global_load_dword v8, v[8:9], off offset:204
.LBB0_1636:
	s_or_b64 exec, exec, s[0:1]
	s_waitcnt vmcnt(0) lgkmcnt(0)
	v_mul_f32_e32 v8, v11, v8
	v_cvt_pk_bf16_f32 v8, v8, s0
	ds_write_b16 v12, v8 offset:64
	v_mov_b32_e32 v8, 0
	v_mov_b32_e32 v9, 0
	s_and_saveexec_b64 s[0:1], vcc
	s_cbranch_execz .LBB0_1638
	v_lshl_add_u64 v[10:11], v[2:3], 2, v[162:163]
	global_load_dword v9, v[10:11], off offset:192
.LBB0_1638:
	s_or_b64 exec, exec, s[0:1]
	s_waitcnt vmcnt(0) lgkmcnt(0)
	v_mul_f32_e32 v4, v4, v9
	v_cvt_pk_bf16_f32 v4, v4, s0
	ds_write_b16 v16, v4 offset:96
	s_and_saveexec_b64 s[0:1], s[38:39]
	s_cbranch_execz .LBB0_1640
	v_lshl_add_u64 v[8:9], v[2:3], 2, v[162:163]
	global_load_dword v8, v[8:9], off offset:196
.LBB0_1640:
	s_or_b64 exec, exec, s[0:1]
	s_waitcnt vmcnt(0) lgkmcnt(0)
	v_mul_f32_e32 v4, v5, v8
	v_cvt_pk_bf16_f32 v4, v4, s0
	ds_write_b16 v17, v4 offset:96
	v_mov_b32_e32 v4, 0
	v_mov_b32_e32 v5, 0
	s_and_saveexec_b64 s[0:1], s[40:41]
	s_cbranch_execz .LBB0_1642
	v_lshl_add_u64 v[8:9], v[2:3], 2, v[162:163]
	global_load_dword v5, v[8:9], off offset:200
.LBB0_1642:
	s_or_b64 exec, exec, s[0:1]
	s_waitcnt vmcnt(0) lgkmcnt(0)
	v_mul_f32_e32 v5, v6, v5
	v_cvt_pk_bf16_f32 v5, v5, s0
	ds_write_b16 v18, v5 offset:96
	s_and_saveexec_b64 s[0:1], s[42:43]
	s_cbranch_execz .LBB0_1644
	v_lshl_add_u64 v[2:3], v[2:3], 2, v[162:163]
	global_load_dword v4, v[2:3], off offset:204
.LBB0_1644:
	s_or_b64 exec, exec, s[0:1]
	s_waitcnt vmcnt(0) lgkmcnt(0)
	v_mul_f32_e32 v2, v7, v4
	v_cvt_pk_bf16_f32 v2, v2, s0
	ds_write_b16 v12, v2 offset:96
	v_ashrrev_i32_e32 v2, 31, v0
	v_lshrrev_b32_e32 v2, 28, v2
	v_add_u32_e32 v2, v0, v2
	v_ashrrev_i32_e32 v2, 4, v2
	v_cmp_gt_i32_e64 s[38:39], s60, v2
	v_cmp_ne_u64_e64 s[40:41], 0, v[164:165]
	v_cmp_eq_u64_e32 vcc, 0, v[164:165]
	s_and_b64 s[8:9], s[38:39], s[40:41]
	s_waitcnt lgkmcnt(0)
	s_barrier
	s_and_saveexec_b64 s[0:1], s[8:9]
	s_cbranch_execz .LBB0_1646
	v_ashrrev_i32_e32 v3, 31, v2
	v_lshlrev_b64 v[6:7], 11, v[2:3]
	v_lshlrev_b32_e32 v3, 4, v2
	v_sub_u32_e32 v8, v0, v3
	v_mul_lo_u32 v2, v2, s23
	v_lshl_add_u32 v2, v8, 4, v2
	ds_read_b128 v[2:5], v2
	v_lshlrev_b32_e32 v8, 3, v8
	v_lshl_add_u64 v[6:7], v[160:161], 0, v[6:7]
	v_ashrrev_i32_e32 v9, 31, v8
	v_lshl_add_u64 v[6:7], v[8:9], 1, v[6:7]
	s_waitcnt lgkmcnt(0)
	global_store_dwordx4 v[6:7], v[2:5], off

; template <int NT, class VF, class RP>
; __device__ __forceinline__ void epi_staged_bf16(f32x4 (&acc)[4][NT], int r0, int c0, unsigned char* smem, VF vf, RP rowptr) {
;     ...
; #pragma unroll
;   for (int i = 0; i < CPR / 2; ++i) {
;     const int c = t + 256 * i, row = c / CPR, ch = c % CPR;
;     u16* d = rowptr(row);
;     if (d) *(u32x4*)(d + ch * 8) = *(const u32x4*)(Ts + row * PITCH + ch * 8);
;   }
.LBB0_1660:
	v_ashrrev_i32_e32 v3, 31, v2
	v_lshlrev_b64 v[4:5], 11, v[2:3]
	v_ashrrev_i32_e32 v3, 31, v0
	v_lshrrev_b32_e32 v3, 28, v3
	v_add_u32_e32 v3, v0, v3
	v_and_b32_e32 v3, -16, v3
	v_sub_u32_e32 v0, v0, v3
	v_mul_lo_u32 v2, v2, s23
	v_lshlrev_b32_e32 v8, 3, v0
	v_lshl_add_u32 v0, v0, 4, v2
	v_lshl_add_u64 v[6:7], v[160:161], 0, v[4:5]
	ds_read_b128 v[2:5], v0
	v_ashrrev_i32_e32 v9, 31, v8
	v_lshl_add_u64 v[6:7], v[8:9], 1, v[6:7]
	s_waitcnt lgkmcnt(0)
	global_store_dwordx4 v[6:7], v[2:5], off
	s_branch .LBB0_1267

; template <bool COMBINE, bool MOD>
; __device__ __forceinline__ void phase_combine_modulate(const Params& p, int lprev, int lnext, const float* xlat, const float* xctx,
;                                                        float* olat, float* octx, int nrows) {
;     ...
;       const int myinv = p.INV[(size_t)row0 * 16 + (lane & 31)];
;       const float* g2 = p.mada + (size_t)(lprev * 3 + cond) * 6144 + 5 * 1024;
;       float* orow = lat ? olat + (size_t)row0 * DM : octx + (size_t)(row0 - T_LAT) * DM;
; #pragma unroll
;       for (int r = 0; r < R; ++r) {
;         float4 s[4];
; #pragma unroll
;         for (int i = 0; i < 4; ++i) s[i] = make_float4(0.f, 0.f, 0.f, 0.f);
;         unsigned mask = (unsigned)((__ballot(myinv >= 0) >> (16 * r)) & 0xFFFFull);
;         while (mask) {
;           const int e0 = __builtin_ctz(mask);
;           mask &= mask - 1;
;           const bool two = mask != 0u;
;           const int e1 = two ? __builtin_ctz(mask) : e0;
;           mask &= mask - 1;
;           const int s0 = __shfl(myinv, 16 * r + e0), s1 = __shfl(myinv, 16 * r + e1);
;           const size_t y0 = lat ? (size_t)(b * 16 + e0) * 1024 + s0 : (size_t)32768 + (size_t)(b * 16 + e0) * 128 + s0;
;           const size_t y1 = lat ? (size_t)(b * 16 + e1) * 1024 + s1 : (size_t)32768 + (size_t)(b * 16 + e1) * 128 + s1;
;           u32x2 a0[4], a1[4];
; #pragma unroll
;           for (int i = 0; i < 4; ++i) { a0[i] = *(const u32x2*)(p.YB + y0 * 1024 + lane * 4 + i * 256); a1[i] = *(const u32x2*)(p.YB + y1 * 1024 + lane * 4 + i * 256); }
;           const float w1 = two ? 1.f : 0.f;
; #pragma unroll
;           for (int i = 0; i < 4; ++i) {
;             s[i].x += bf2f((u16)(a0[i].x & 0xffffu)); s[i].y += bf2f((u16)(a0[i].x >> 16));
;             s[i].z += bf2f((u16)(a0[i].y & 0xffffu)); s[i].w += bf2f((u16)(a0[i].y >> 16));
;             s[i].x += w1 * bf2f((u16)(a1[i].x & 0xffffu)); s[i].y += w1 * bf2f((u16)(a1[i].x >> 16));
;             s[i].z += w1 * bf2f((u16)(a1[i].y & 0xffffu)); s[i].w += w1 * bf2f((u16)(a1[i].y >> 16));
;           }
;         }
; #pragma unroll
;         for (int i = 0; i < 4; ++i) {
;           const int col = i * 256 + lane * 4;
;           const float4 g4 = *(const float4*)(g2 + col);
;           v[r][i].x += g4.x * s[i].x; v[r][i].y += g4.y * s[i].y; v[r][i].z += g4.z * s[i].z; v[r][i].w += g4.w * s[i].w;
.LBB0_1744:
	global_load_dwordx4 v[16:19], v[58:59], off
	v_lshl_add_u64 v[58:59], v[62:63], 0, s[6:7]
	v_mov_b32_e32 v43, v35
	v_lshl_add_u64 v[62:63], v[58:59], 0, v[42:43]
	v_mov_b32_e32 v47, v35
	v_mov_b32_e32 v51, v35
	v_readlane_b32 s10, v254, 54
	v_mov_b32_e32 v55, v35
	v_readlane_b32 s11, v254, 55
	v_add_u32_e32 v32, s10, v32
	v_cmp_lt_i32_e32 vcc, s8, v32
	s_or_b64 s[2:3], vcc, s[2:3]
	s_waitcnt vmcnt(0) lgkmcnt(0)
	v_pk_fma_f32 v[12:13], v[72:73], v[16:17], v[12:13]
	v_pk_fma_f32 v[14:15], v[74:75], v[18:19], v[14:15]
	global_store_dwordx4 v[62:63], v[12:15], off
	global_load_dwordx4 v[12:15], v[60:61], off
	v_lshl_add_u64 v[16:17], v[58:59], 0, v[46:47]
	s_waitcnt vmcnt(0) lgkmcnt(0)
	v_pk_fma_f32 v[8:9], v[70:71], v[12:13], v[8:9]
	v_pk_fma_f32 v[10:11], v[68:69], v[14:15], v[10:11]
	global_store_dwordx4 v[16:17], v[8:11], off
	global_load_dwordx4 v[8:11], v[28:29], off
	v_lshl_add_u64 v[12:13], v[58:59], 0, v[50:51]
	s_waitcnt vmcnt(0) lgkmcnt(0)
	v_pk_fma_f32 v[4:5], v[30:31], v[8:9], v[4:5]
	v_pk_fma_f32 v[6:7], v[26:27], v[10:11], v[6:7]
	global_store_dwordx4 v[12:13], v[4:7], off
	global_load_dwordx4 v[4:7], v[24:25], off
	v_lshl_add_u64 v[8:9], v[58:59], 0, v[54:55]
	s_waitcnt vmcnt(0) lgkmcnt(0)
	v_pk_fma_f32 v[0:1], v[22:23], v[4:5], v[0:1]
	v_pk_fma_f32 v[2:3], v[20:21], v[6:7], v[2:3]
	global_store_dwordx4 v[8:9], v[0:3], off
	s_andn2_b64 exec, exec, s[2:3]
	s_cbranch_execz .LBB0_1751
.LBB0_1745:
	global_load_dwordx2 v[0:1], v[38:39], off offset:416
	global_load_dwordx2 v[58:59], v[38:39], off offset:184
	v_ashrrev_i32_e32 v33, 31, v32
	v_lshlrev_b64 v[60:61], 12, v[32:33]
	v_lshlrev_b64 v[2:3], 6, v[32:33]
	v_lshl_add_u64 v[4:5], v[36:37], 0, v[60:61]
	v_add_co_u32_e32 v62, vcc, 0x1000, v4
	global_load_dwordx4 v[28:31], v[4:5], off
	global_load_dwordx4 v[24:27], v[4:5], off offset:1024
	global_load_dwordx4 v[20:23], v[4:5], off offset:2048
	global_load_dwordx4 v[16:19], v[4:5], off offset:3072
	v_addc_co_u32_e32 v63, vcc, 0, v5, vcc
	v_ashrrev_i32_e32 v47, 13, v32
	v_mov_b32_e32 v65, v35
	v_mov_b32_e32 v64, v35
	v_mov_b32_e32 v67, v35
	v_mov_b32_e32 v66, v35
	v_mov_b32_e32 v69, v35
	v_mov_b32_e32 v68, v35
	v_mov_b32_e32 v71, v35
	v_mov_b32_e32 v70, v35
	v_mov_b32_e32 v73, v35
	v_mov_b32_e32 v72, v35
	v_mov_b32_e32 v75, v35
	v_mov_b32_e32 v74, v35
	v_mov_b32_e32 v77, v35
	v_mov_b32_e32 v76, v35
	v_lshlrev_b32_e32 v43, 4, v47
	v_mov_b32_e32 v79, v35
	v_mov_b32_e32 v78, v35
	s_waitcnt vmcnt(0) lgkmcnt(0)
	v_lshl_add_u64 v[0:1], v[0:1], 0, v[2:3]
	v_lshl_add_u64 v[0:1], v[0:1], 0, v[40:41]
	global_load_dword v33, v[0:1], off
	global_load_dwordx4 v[12:15], v[62:63], off
	global_load_dwordx4 v[8:11], v[62:63], off offset:1024
	global_load_dwordx4 v[4:7], v[62:63], off offset:2048
	s_nop 0
	global_load_dwordx4 v[0:3], v[62:63], off offset:3072
	s_waitcnt vmcnt(0) lgkmcnt(0)
	v_cmp_lt_i32_e32 vcc, -1, v33
	s_and_b32 s9, vcc_lo, 0xffff
	s_cmp_eq_u32 s9, 0
	s_cbranch_scc1 .LBB0_1748
	global_load_dwordx2 v[62:63], v[38:39], off offset:424
	v_mov_b32_e32 v78, 0
	v_mov_b32_e32 v79, v78
	v_mov_b32_e32 v76, v78
	v_mov_b32_e32 v77, v78
	v_mov_b32_e32 v74, v78
	v_mov_b32_e32 v75, v78
	v_mov_b32_e32 v72, v78
	v_mov_b32_e32 v73, v78
	v_mov_b32_e32 v70, v78
	v_mov_b32_e32 v71, v78
	v_mov_b32_e32 v68, v78
	v_mov_b32_e32 v69, v78
	v_mov_b32_e32 v66, v78
	v_mov_b32_e32 v67, v78
	v_mov_b32_e32 v64, v78
	v_mov_b32_e32 v65, v78
.LBB0_1747:
	s_add_i32 s10, s9, -1
	s_ff1_i32_b32 s12, s9
	s_and_b32 s9, s10, s9
	v_or_b32_e32 v51, s12, v214
	v_sub_co_u32_e64 v55, s[10:11], s9, 1
	s_ff1_i32_b32 s13, s9
	v_lshlrev_b32_e32 v51, 2, v51
	v_cndmask_b32_e64 v84, 1.0, 0, s[10:11]
	s_and_b64 s[10:11], s[10:11], exec
	ds_bpermute_b32 v86, v51, v33
	s_cselect_b32 s10, s12, s13
	v_or_b32_e32 v51, s10, v214
	v_lshlrev_b32_e32 v51, 2, v51
	v_add_u32_e32 v82, s12, v43
	ds_bpermute_b32 v90, v51, v33
	v_ashrrev_i32_e32 v83, 31, v82
	v_lshlrev_b64 v[82:83], 21, v[82:83]
	s_waitcnt lgkmcnt(0)
	v_ashrrev_i32_e32 v87, 31, v86
	s_waitcnt vmcnt(0)
	v_lshl_add_u64 v[82:83], v[62:63], 0, v[82:83]
	v_add_u32_e32 v88, s10, v43
	v_lshlrev_b64 v[86:87], 11, v[86:87]
	v_ashrrev_i32_e32 v89, 31, v88
	v_lshl_add_u64 v[82:83], v[82:83], 0, v[86:87]
	v_lshlrev_b64 v[88:89], 21, v[88:89]
	v_lshl_add_u64 v[82:83], v[82:83], 0, v[34:35]
	v_ashrrev_i32_e32 v91, 31, v90
	v_lshl_add_u64 v[88:89], v[62:63], 0, v[88:89]
	global_load_dwordx2 v[86:87], v[82:83], off
	global_load_dwordx2 v[92:93], v[82:83], off offset:512
	global_load_dwordx2 v[94:95], v[82:83], off offset:1024
	global_load_dwordx2 v[96:97], v[82:83], off offset:1536
	v_lshlrev_b64 v[82:83], 11, v[90:91]
	v_lshl_add_u64 v[82:83], v[88:89], 0, v[82:83]
	v_lshl_add_u64 v[82:83], v[82:83], 0, v[34:35]
	global_load_dwordx2 v[88:89], v[82:83], off
	global_load_dwordx2 v[90:91], v[82:83], off offset:512
	global_load_dwordx2 v[98:99], v[82:83], off offset:1024
	global_load_dwordx2 v[100:101], v[82:83], off offset:1536
	v_readfirstlane_b32 s10, v55
	s_and_b32 s9, s10, s9
	s_cmp_eq_u32 s9, 0
	s_waitcnt vmcnt(0) lgkmcnt(0)
; __device__ __forceinline__ float bf2f(u16 b) { return __uint_as_float(((unsigned)b) << 16); }
; template <bool COMBINE, bool MOD>
; __device__ __forceinline__ void phase_combine_modulate(const Params& p, int lprev, int lnext, const float* xlat, const float* xctx,
;                                                        float* olat, float* octx, int nrows) {
;     ...
;         unsigned mask = (unsigned)((__ballot(myinv >= 0) >> (16 * r)) & 0xFFFFull);
;         while (mask) {
;           const int e0 = __builtin_ctz(mask);
;           mask &= mask - 1;
;           const bool two = mask != 0u;
;           const int e1 = two ? __builtin_ctz(mask) : e0;
;           mask &= mask - 1;
;           const int s0 = __shfl(myinv, 16 * r + e0), s1 = __shfl(myinv, 16 * r + e1);
;           const size_t y0 = lat ? (size_t)(b * 16 + e0) * 1024 + s0 : (size_t)32768 + (size_t)(b * 16 + e0) * 128 + s0;
;           const size_t y1 = lat ? (size_t)(b * 16 + e1) * 1024 + s1 : (size_t)32768 + (size_t)(b * 16 + e1) * 128 + s1;
;           u32x2 a0[4], a1[4];
; #pragma unroll
;           for (int i = 0; i < 4; ++i) { a0[i] = *(const u32x2*)(p.YB + y0 * 1024 + lane * 4 + i * 256); a1[i] = *(const u32x2*)(p.YB + y1 * 1024 + lane * 4 + i * 256); }
;           const float w1 = two ? 1.f : 0.f;
; #pragma unroll
;           for (int i = 0; i < 4; ++i) {
;             s[i].x += bf2f((u16)(a0[i].x & 0xffffu)); s[i].y += bf2f((u16)(a0[i].x >> 16));
;             s[i].z += bf2f((u16)(a0[i].y & 0xffffu)); s[i].w += bf2f((u16)(a0[i].y >> 16));
;             s[i].x += w1 * bf2f((u16)(a1[i].x & 0xffffu)); s[i].y += w1 * bf2f((u16)(a1[i].x >> 16));
;             s[i].z += w1 * bf2f((u16)(a1[i].y & 0xffffu)); s[i].w += w1 * bf2f((u16)(a1[i].y >> 16));
;           }
;         }
; #pragma unroll
;         for (int i = 0; i < 4; ++i) {
;           const int col = i * 256 + lane * 4;
;           const float4 g4 = *(const float4*)(g2 + col);
;           v[r][i].x += g4.x * s[i].x; v[r][i].y += g4.y * s[i].y; v[r][i].z += g4.z * s[i].z; v[r][i].w += g4.w * s[i].w;
;           *(float4*)(orow + (size_t)r * DM + col) = v[r][i];
	v_and_b32_e32 v83, 0xffff0000, v86
	v_lshlrev_b32_e32 v82, 16, v86
	v_and_b32_e32 v103, 0xffff0000, v87
	v_lshlrev_b32_e32 v102, 16, v87
	v_and_b32_e32 v87, 0xffff0000, v92
	v_lshlrev_b32_e32 v86, 16, v92
	v_and_b32_e32 v105, 0xffff0000, v93
	v_lshlrev_b32_e32 v104, 16, v93
	v_and_b32_e32 v93, 0xffff0000, v94
	v_lshlrev_b32_e32 v92, 16, v94
	v_and_b32_e32 v107, 0xffff0000, v95
	v_lshlrev_b32_e32 v106, 16, v95
	v_and_b32_e32 v95, 0xffff0000, v96
	v_lshlrev_b32_e32 v94, 16, v96
	v_and_b32_e32 v109, 0xffff0000, v97
	v_lshlrev_b32_e32 v108, 16, v97
	v_pk_add_f32 v[78:79], v[78:79], v[82:83]
	v_pk_add_f32 v[76:77], v[76:77], v[102:103]
	v_pk_add_f32 v[74:75], v[74:75], v[86:87]
	v_pk_add_f32 v[72:73], v[72:73], v[104:105]
	v_pk_add_f32 v[70:71], v[70:71], v[92:93]
	v_pk_add_f32 v[68:69], v[68:69], v[106:107]
	v_pk_add_f32 v[66:67], v[66:67], v[94:95]
	v_pk_add_f32 v[64:65], v[64:65], v[108:109]
	v_and_b32_e32 v83, 0xffff0000, v88
	v_lshlrev_b32_e32 v82, 16, v88
	v_and_b32_e32 v87, 0xffff0000, v89
	v_lshlrev_b32_e32 v86, 16, v89
	v_and_b32_e32 v89, 0xffff0000, v90
	v_lshlrev_b32_e32 v88, 16, v90
	v_and_b32_e32 v93, 0xffff0000, v91
	v_lshlrev_b32_e32 v92, 16, v91
	v_and_b32_e32 v91, 0xffff0000, v98
	v_lshlrev_b32_e32 v90, 16, v98
	v_and_b32_e32 v95, 0xffff0000, v99
	v_lshlrev_b32_e32 v94, 16, v99
	v_and_b32_e32 v97, 0xffff0000, v100
	v_lshlrev_b32_e32 v96, 16, v100
	v_and_b32_e32 v99, 0xffff0000, v101
	v_lshlrev_b32_e32 v98, 16, v101
	v_pk_fma_f32 v[78:79], v[84:85], v[82:83], v[78:79] op_sel_hi:[0,1,1]
	v_pk_fma_f32 v[76:77], v[84:85], v[86:87], v[76:77] op_sel_hi:[0,1,1]
	v_pk_fma_f32 v[74:75], v[84:85], v[88:89], v[74:75] op_sel_hi:[0,1,1]
	v_pk_fma_f32 v[72:73], v[84:85], v[92:93], v[72:73] op_sel_hi:[0,1,1]
	v_pk_fma_f32 v[70:71], v[84:85], v[90:91], v[70:71] op_sel_hi:[0,1,1]
	v_pk_fma_f32 v[68:69], v[84:85], v[94:95], v[68:69] op_sel_hi:[0,1,1]
	v_pk_fma_f32 v[66:67], v[84:85], v[96:97], v[66:67] op_sel_hi:[0,1,1]
	v_pk_fma_f32 v[64:65], v[84:85], v[98:99], v[64:65] op_sel_hi:[0,1,1]
	s_cbranch_scc0 .LBB0_1747
.LBB0_1748:
	v_add_u32_e32 v47, 3, v47
	v_mul_hi_i32_i24_e32 v63, 0x6000, v47
	v_mul_i32_i24_e32 v62, 0x6000, v47
	v_lshl_add_u64 v[58:59], v[58:59], 0, v[62:63]
	v_lshl_add_u64 v[86:87], v[58:59], 0, s[4:5]
	v_lshl_add_u64 v[58:59], v[86:87], 0, v[44:45]
	global_load_dwordx4 v[82:85], v[58:59], off
	v_lshl_add_u64 v[62:63], s[0:1], 0, v[60:61]
	v_lshl_add_u64 v[88:89], v[62:63], 0, v[44:45]
	v_lshl_add_u64 v[60:61], v[86:87], 0, v[48:49]
	s_waitcnt vmcnt(0) lgkmcnt(0)
	v_pk_fma_f32 v[28:29], v[78:79], v[82:83], v[28:29]
	v_pk_fma_f32 v[30:31], v[76:77], v[84:85], v[30:31]
	global_store_dwordx4 v[88:89], v[28:31], off
	global_load_dwordx4 v[76:79], v[60:61], off
	s_waitcnt vmcnt(0) lgkmcnt(0)
	v_pk_fma_f32 v[24:25], v[74:75], v[76:77], v[24:25]
	v_pk_fma_f32 v[26:27], v[72:73], v[78:79], v[26:27]
	v_lshl_add_u64 v[28:29], v[86:87], 0, v[52:53]
	global_store_dwordx4 v[88:89], v[24:27], off offset:1024
	global_load_dwordx4 v[72:75], v[28:29], off
	s_waitcnt vmcnt(0) lgkmcnt(0)
	v_pk_fma_f32 v[20:21], v[70:71], v[72:73], v[20:21]
	v_pk_fma_f32 v[22:23], v[68:69], v[74:75], v[22:23]
	v_lshl_add_u64 v[24:25], v[86:87], 0, v[56:57]
	global_store_dwordx4 v[88:89], v[20:23], off offset:2048
	global_load_dwordx4 v[76:79], v[24:25], off
	s_waitcnt vmcnt(0) lgkmcnt(0)
	v_pk_fma_f32 v[16:17], v[66:67], v[76:77], v[16:17]
	v_cndmask_b32_e64 v20, 0, 1, vcc
	v_mov_b32_e32 v21, 0
	v_cmp_ne_u32_e32 vcc, 0, v20
	v_mov_b32_e32 v20, v21
	v_mov_b32_e32 v23, v21
	v_mov_b32_e32 v22, v21
	v_mov_b32_e32 v27, v21
	v_mov_b32_e32 v26, v21
	v_mov_b32_e32 v31, v21
	v_mov_b32_e32 v30, v21
	v_mov_b32_e32 v69, v21
	v_mov_b32_e32 v68, v21
	v_mov_b32_e32 v71, v21
	v_mov_b32_e32 v70, v21
	v_mov_b32_e32 v75, v21
	v_mov_b32_e32 v74, v21
	v_mov_b32_e32 v73, v21
	s_cmpk_gt_u32 vcc_lo, 0xffff
	v_pk_fma_f32 v[18:19], v[64:65], v[78:79], v[18:19]
	v_mov_b32_e32 v72, v21
	global_store_dwordx4 v[88:89], v[16:19], off offset:3072
	s_cbranch_scc0 .LBB0_1744
	global_load_dwordx2 v[16:17], v[38:39], off offset:424
	v_mov_b32_e32 v72, 0
	s_lshr_b32 s9, vcc_lo, 16
	v_mov_b32_e32 v73, v72
	v_mov_b32_e32 v74, v72
	v_mov_b32_e32 v75, v72
	v_mov_b32_e32 v70, v72
	v_mov_b32_e32 v71, v72
	v_mov_b32_e32 v68, v72
	v_mov_b32_e32 v69, v72
	v_mov_b32_e32 v30, v72
	v_mov_b32_e32 v31, v72
	v_mov_b32_e32 v26, v72
	v_mov_b32_e32 v27, v72
	v_mov_b32_e32 v22, v72
	v_mov_b32_e32 v23, v72
	v_mov_b32_e32 v20, v72
	v_mov_b32_e32 v21, v72
; __device__ __forceinline__ float bf2f(u16 b) { return __uint_as_float(((unsigned)b) << 16); }
; template <bool COMBINE, bool MOD>
; __device__ __forceinline__ void phase_combine_modulate(const Params& p, int lprev, int lnext, const float* xlat, const float* xctx,
;                                                        float* olat, float* octx, int nrows) {
;     ...
;         while (mask) {
;           const int e0 = __builtin_ctz(mask);
;           mask &= mask - 1;
;           const bool two = mask != 0u;
;           const int e1 = two ? __builtin_ctz(mask) : e0;
;           mask &= mask - 1;
;           const int s0 = __shfl(myinv, 16 * r + e0), s1 = __shfl(myinv, 16 * r + e1);
;           const size_t y0 = lat ? (size_t)(b * 16 + e0) * 1024 + s0 : (size_t)32768 + (size_t)(b * 16 + e0) * 128 + s0;
;           const size_t y1 = lat ? (size_t)(b * 16 + e1) * 1024 + s1 : (size_t)32768 + (size_t)(b * 16 + e1) * 128 + s1;
;           u32x2 a0[4], a1[4];
; #pragma unroll
;           for (int i = 0; i < 4; ++i) { a0[i] = *(const u32x2*)(p.YB + y0 * 1024 + lane * 4 + i * 256); a1[i] = *(const u32x2*)(p.YB + y1 * 1024 + lane * 4 + i * 256); }
;           const float w1 = two ? 1.f : 0.f;
; #pragma unroll
;           for (int i = 0; i < 4; ++i) {
;             s[i].x += bf2f((u16)(a0[i].x & 0xffffu)); s[i].y += bf2f((u16)(a0[i].x >> 16));
;             s[i].z += bf2f((u16)(a0[i].y & 0xffffu)); s[i].w += bf2f((u16)(a0[i].y >> 16));
;             s[i].x += w1 * bf2f((u16)(a1[i].x & 0xffffu)); s[i].y += w1 * bf2f((u16)(a1[i].x >> 16));
;             s[i].z += w1 * bf2f((u16)(a1[i].y & 0xffffu)); s[i].w += w1 * bf2f((u16)(a1[i].y >> 16));
;           }
.LBB0_1750:
	s_add_i32 s10, s9, -1
	s_ff1_i32_b32 s12, s9
	s_and_b32 s9, s10, s9
	v_add_lshl_u32 v19, s12, v80, 2
	v_sub_co_u32_e64 v47, s[10:11], s9, 1
	s_ff1_i32_b32 s13, s9
	ds_bpermute_b32 v64, v19, v33
	v_cndmask_b32_e64 v66, 1.0, 0, s[10:11]
	s_and_b64 s[10:11], s[10:11], exec
	s_cselect_b32 s10, s12, s13
	v_add_lshl_u32 v51, s10, v80, 2
	v_add_u32_e32 v18, s12, v43
	ds_bpermute_b32 v78, v51, v33
	v_ashrrev_i32_e32 v19, 31, v18
	v_lshlrev_b64 v[18:19], 21, v[18:19]
	s_waitcnt lgkmcnt(0)
	v_ashrrev_i32_e32 v65, 31, v64
	s_waitcnt vmcnt(0)
	v_lshl_add_u64 v[18:19], v[16:17], 0, v[18:19]
	v_add_u32_e32 v76, s10, v43
	v_lshlrev_b64 v[64:65], 11, v[64:65]
	v_ashrrev_i32_e32 v77, 31, v76
	v_lshl_add_u64 v[18:19], v[18:19], 0, v[64:65]
	v_lshlrev_b64 v[76:77], 21, v[76:77]
	v_lshl_add_u64 v[18:19], v[18:19], 0, v[34:35]
	v_ashrrev_i32_e32 v79, 31, v78
	v_lshl_add_u64 v[76:77], v[16:17], 0, v[76:77]
	global_load_dwordx2 v[64:65], v[18:19], off
	global_load_dwordx2 v[82:83], v[18:19], off offset:512
	global_load_dwordx2 v[84:85], v[18:19], off offset:1024
	global_load_dwordx2 v[86:87], v[18:19], off offset:1536
	v_lshlrev_b64 v[18:19], 11, v[78:79]
	v_lshl_add_u64 v[18:19], v[76:77], 0, v[18:19]
	v_lshl_add_u64 v[18:19], v[18:19], 0, v[34:35]
	global_load_dwordx2 v[76:77], v[18:19], off
	global_load_dwordx2 v[78:79], v[18:19], off offset:512
	global_load_dwordx2 v[88:89], v[18:19], off offset:1024
	global_load_dwordx2 v[90:91], v[18:19], off offset:1536
	v_readfirstlane_b32 s10, v47
	s_and_b32 s9, s10, s9
	s_cmp_lg_u32 s9, 0
	s_waitcnt vmcnt(0) lgkmcnt(0)
	v_and_b32_e32 v19, 0xffff0000, v64
	v_lshlrev_b32_e32 v18, 16, v64
	v_and_b32_e32 v93, 0xffff0000, v65
	v_lshlrev_b32_e32 v92, 16, v65
	v_and_b32_e32 v65, 0xffff0000, v82
	v_lshlrev_b32_e32 v64, 16, v82
	v_and_b32_e32 v95, 0xffff0000, v83
	v_lshlrev_b32_e32 v94, 16, v83
	v_and_b32_e32 v83, 0xffff0000, v84
	v_lshlrev_b32_e32 v82, 16, v84
	v_and_b32_e32 v97, 0xffff0000, v85
	v_lshlrev_b32_e32 v96, 16, v85
	v_and_b32_e32 v85, 0xffff0000, v86
	v_lshlrev_b32_e32 v84, 16, v86
	v_and_b32_e32 v99, 0xffff0000, v87
	v_lshlrev_b32_e32 v98, 16, v87
	v_pk_add_f32 v[18:19], v[72:73], v[18:19]
	v_pk_add_f32 v[74:75], v[74:75], v[92:93]
	v_pk_add_f32 v[64:65], v[70:71], v[64:65]
	v_pk_add_f32 v[68:69], v[68:69], v[94:95]
	v_pk_add_f32 v[30:31], v[30:31], v[82:83]
	v_pk_add_f32 v[26:27], v[26:27], v[96:97]
	v_pk_add_f32 v[22:23], v[22:23], v[84:85]
	v_pk_add_f32 v[20:21], v[20:21], v[98:99]
	v_and_b32_e32 v71, 0xffff0000, v76
	v_lshlrev_b32_e32 v70, 16, v76
	v_and_b32_e32 v83, 0xffff0000, v77
	v_lshlrev_b32_e32 v82, 16, v77
	v_and_b32_e32 v77, 0xffff0000, v78
	v_lshlrev_b32_e32 v76, 16, v78
	v_and_b32_e32 v85, 0xffff0000, v79
	v_lshlrev_b32_e32 v84, 16, v79
	v_and_b32_e32 v79, 0xffff0000, v88
	v_lshlrev_b32_e32 v78, 16, v88
	v_and_b32_e32 v87, 0xffff0000, v89
	v_lshlrev_b32_e32 v86, 16, v89
	v_and_b32_e32 v89, 0xffff0000, v90
	v_lshlrev_b32_e32 v88, 16, v90
	v_and_b32_e32 v93, 0xffff0000, v91
	v_lshlrev_b32_e32 v92, 16, v91
	v_pk_fma_f32 v[72:73], v[66:67], v[70:71], v[18:19] op_sel_hi:[0,1,1]
	v_pk_fma_f32 v[74:75], v[66:67], v[82:83], v[74:75] op_sel_hi:[0,1,1]
	v_pk_fma_f32 v[70:71], v[66:67], v[76:77], v[64:65] op_sel_hi:[0,1,1]
	v_pk_fma_f32 v[68:69], v[66:67], v[84:85], v[68:69] op_sel_hi:[0,1,1]
	v_pk_fma_f32 v[30:31], v[66:67], v[78:79], v[30:31] op_sel_hi:[0,1,1]
	v_pk_fma_f32 v[26:27], v[66:67], v[86:87], v[26:27] op_sel_hi:[0,1,1]
	v_pk_fma_f32 v[22:23], v[66:67], v[88:89], v[22:23] op_sel_hi:[0,1,1]
	v_pk_fma_f32 v[20:21], v[66:67], v[92:93], v[20:21] op_sel_hi:[0,1,1]
	s_cbranch_scc1 .LBB0_1750
	s_branch .LBB0_1744
